# all generic-pointer (flat) memory instructions rewritten as global ones so LDS waits no longer cover global traffic
# speedup vs baseline: 1.0221x; 1.0016x over previous
_Z10hybrid_fwd6Params:
	s_mov_b64 s[64:65], s[0:1]
	s_add_u32 s14, s64, 0x100
	v_and_b32_e32 v247, 0x3ff, v0
	s_mov_b32 s88, s2
	s_addc_u32 s15, s65, 0
	v_cmp_eq_u32_e64 s[62:63], 0, v247
	s_and_saveexec_b64 s[2:3], s[62:63]
	v_mov_b32_e32 v2, 0
	v_mov_b32_e32 v3, v2
	v_mov_b32_e32 v4, v2
	v_mov_b32_e32 v5, v2
	ds_write_b128 v2, v[2:5]
	s_or_b64 exec, exec, s[2:3]
	s_load_dwordx2 s[0:1], s[64:65], 0x100
	v_mov_b32_e32 v1, s64
	v_mov_b32_e32 v2, s65
	s_waitcnt lgkmcnt(0)
	s_barrier
	v_writelane_b32 v253, s0, 0
	s_nop 1
	v_writelane_b32 v253, s1, 1
	v_readfirstlane_b32 s0, v1
	v_readfirstlane_b32 s1, v2
	s_nop 0
	v_mov_b32_e32 v2, s0
	v_mov_b32_e32 v3, s1
	global_load_dwordx2 v[2:3], v[2:3], off offset:248
	s_waitcnt vmcnt(0) lgkmcnt(0)
	v_mov_b32_e32 v1, v3
	s_getreg_b32 s2, hwreg(HW_REG_XCC_ID, 0, 4)
	v_readfirstlane_b32 s0, v2
	v_readfirstlane_b32 s1, v1
	s_add_u32 s33, s0, 0x20965200
	s_addc_u32 s36, s1, 0
	s_and_b32 s37, s2, 15
	s_and_saveexec_b64 s[2:3], s[62:63]
	s_cbranch_execz .LBB0_4
	s_lshl_b32 s4, s37, 8
	s_add_u32 s4, s33, s4
	s_addc_u32 s5, s36, 0
	v_mov_b32_e32 v1, 1
	v_mov_b64_e32 v[2:3], s[4:5]
	global_atomic_add v[2:3], v1, off offset:1024

.LBB0_6:
	s_or_b64 exec, exec, s[8:9]
	global_load_dword v6, v[8:9], off
	v_add_u32_e32 v9, 0x200, v3
	v_cmp_lt_i32_e32 vcc, s11, v3
	v_lshl_add_u64 v[4:5], v[4:5], 0, s[6:7]
	s_or_b64 s[4:5], vcc, s[4:5]
	s_waitcnt vmcnt(0) lgkmcnt(0)
	v_mul_f32_e32 v8, 0xbfb8aa3b, v6
	v_exp_f32_e32 v8, v8
	s_nop 0
	v_add_f32_e32 v8, 1.0, v8
	v_rcp_f32_e32 v8, v8
	s_nop 0
	v_mul_f32_e32 v3, v6, v8
	ds_write_b32 v1, v3
	v_add_u32_e32 v1, 0x800, v1
	v_mov_b32_e32 v3, v9
	s_andn2_b64 exec, exec, s[4:5]
	s_cbranch_execz .LBB0_11
.LBB0_7:
	v_cmp_lt_i32_e32 vcc, s10, v3
	s_and_saveexec_b64 s[8:9], vcc
	s_xor_b64 s[8:9], exec, s[8:9]
	s_cbranch_execz .LBB0_9
	v_mov_b32_e32 v6, s64
	v_mov_b32_e32 v8, s65
	s_nop 0
	v_readfirstlane_b32 s12, v6
	v_readfirstlane_b32 s13, v8
	v_and_b32_e32 v6, 0x3ff, v3
	v_mov_b32_e32 v8, s12
	v_mov_b32_e32 v9, s13
	global_load_dwordx2 v[8:9], v[8:9], off offset:24
	s_waitcnt vmcnt(0) lgkmcnt(0)
	v_lshlrev_b32_e32 v6, 2, v6
	v_readfirstlane_b32 s12, v8
	v_readfirstlane_b32 s13, v9
	s_nop 1
	v_lshl_add_u64 v[8:9], s[12:13], 0, v[6:7]
.LBB0_9:
	s_andn2_saveexec_b64 s[8:9], s[8:9]
	s_cbranch_execz .LBB0_6
	v_mov_b32_e32 v6, s64
	v_mov_b32_e32 v8, s65
	s_nop 0
	v_readfirstlane_b32 s12, v6
	v_readfirstlane_b32 s13, v8
	s_nop 0
	v_mov_b32_e32 v8, s12
	v_mov_b32_e32 v9, s13
	global_load_dwordx2 v[8:9], v[8:9], off offset:8
	s_waitcnt vmcnt(0) lgkmcnt(0)
	v_mov_b32_e32 v6, v9
	s_nop 0
	v_readfirstlane_b32 s12, v8
	v_readfirstlane_b32 s13, v6
	s_nop 1
	v_lshl_add_u64 v[8:9], s[12:13], 0, v[4:5]
	s_branch .LBB0_6
.LBB0_11:
	s_or_b64 exec, exec, s[2:3]
	v_mov_b32_e32 v1, s64
	v_mov_b32_e32 v3, s65
	s_waitcnt lgkmcnt(0)
	s_barrier
	s_nop 0
	v_readfirstlane_b32 s2, v1
	v_readfirstlane_b32 s3, v3
	v_mov_b32_e32 v1, s88
	v_mov_b32_e32 v4, s2
	v_mov_b32_e32 v5, s3
	global_load_dwordx2 v[4:5], v[4:5], off offset:248
	s_waitcnt vmcnt(0) lgkmcnt(0)
	v_mov_b32_e32 v3, v5
	s_nop 0
	v_readfirstlane_b32 s10, v1
	v_readfirstlane_b32 s2, v4
	s_cmpk_gt_i32 s10, 0x23f
	v_readfirstlane_b32 s3, v3
	s_cbranch_scc1 .LBB0_19
	v_and_b32_e32 v1, 63, v2
	v_lshlrev_b32_e32 v6, 2, v1
	v_ashrrev_i32_e32 v7, 6, v2
	v_add_u32_e32 v8, 16, v6
	s_movk_i32 s4, 0x900
	v_lshlrev_b32_e32 v4, 7, v7
	v_lshl_add_u32 v3, v7, 9, 16
	v_mad_u64_u32 v[10:11], s[4:5], v7, s4, v[8:9]
	v_mov_b32_e32 v7, 0
	s_movk_i32 s4, 0x240
	v_lshl_add_u64 v[12:13], s[2:3], 0, v[6:7]
	s_mov_b64 s[2:3], 0x20700000
	v_ashrrev_i32_e32 v5, 31, v4
	v_cmp_gt_i32_e32 vcc, s4, v2
	v_lshl_add_u64 v[12:13], v[12:13], 0, s[2:3]
	v_mov_b32_e32 v6, s64
	v_mov_b32_e32 v9, s65
	s_mov_b32 s11, 0x9000
	s_mov_b32 s12, 0x12000
	s_mov_b32 s13, 0x1b000
	s_branch .LBB0_14

.LBB0_14:
	v_mov_b32_e32 v11, v9
	v_mov_b32_e32 v14, v6
	s_mov_b64 s[8:9], 0
	v_readfirstlane_b32 s2, v14
	v_readfirstlane_b32 s3, v11
	v_mov_b32_e32 v11, v3
	v_mov_b32_e32 v14, s2
	v_mov_b32_e32 v15, s3
	global_load_dwordx2 v[22:23], v[14:15], off offset:32
	s_mul_hi_i32 s2, s10, 0x38e38e39
	s_lshr_b32 s3, s2, 31
	s_ashr_i32 s2, s2, 5
	s_add_i32 s6, s2, s3
	s_ashr_i32 s7, s6, 31
	s_mul_i32 s2, s6, 0x90
	s_lshl_b64 s[4:5], s[6:7], 10
	s_sub_i32 s2, s10, s2
	v_lshl_add_u64 v[26:27], s[4:5], 0, v[4:5]
	s_lshl_b32 s2, s2, 6
	v_or_b32_e32 v28, s2, v1
	v_ashrrev_i32_e32 v29, 31, v28
	v_mov_b32_e32 v24, 0
	v_mov_b32_e32 v14, 0
	v_mov_b32_e32 v15, v7
	v_mov_b32_e32 v16, 0
	v_mov_b32_e32 v17, v7
	v_mov_b32_e32 v18, 0
	v_mov_b32_e32 v19, v7
	v_mov_b32_e32 v20, 0
	s_waitcnt vmcnt(0) lgkmcnt(0)
	v_mov_b32_e32 v21, v22
	s_nop 0
	v_readfirstlane_b32 s3, v21
	v_readfirstlane_b32 s4, v23
	v_mov_b32_e32 v21, v7
	v_mov_b32_e32 v22, s3
	v_mov_b32_e32 v23, s4
	v_mad_u64_u32 v[22:23], s[4:5], v26, s11, v[22:23]
	v_mad_i32_i24 v23, v27, s11, v23
	v_lshl_add_u64 v[22:23], v[28:29], 2, v[22:23]
.LBB0_15:
	v_lshl_add_u64 v[26:27], v[22:23], 0, s[8:9]
	v_add_co_u32_e64 v28, s[4:5], s11, v26
	global_load_dword v62, v[26:27], off
	s_nop 0
	v_addc_co_u32_e64 v29, s[4:5], 0, v27, s[4:5]
	v_add_co_u32_e64 v30, s[4:5], s12, v26
	s_add_u32 s8, s8, 0x24000
	s_nop 0
	v_addc_co_u32_e64 v31, s[4:5], 0, v27, s[4:5]
	v_add_co_u32_e64 v26, s[4:5], s13, v26
	s_addc_u32 s9, s9, 0
	s_nop 0
	v_addc_co_u32_e64 v27, s[4:5], 0, v27, s[4:5]
	global_load_dword v64, v[28:29], off
	global_load_dword v66, v[30:31], off
	global_load_dword v68, v[26:27], off
	ds_read_b128 v[26:29], v11 offset:4096
	ds_read_b128 v[30:33], v11 offset:8192
	ds_read_b128 v[34:37], v11 offset:12288
	ds_read_b128 v[38:41], v11 offset:16384
	ds_read_b128 v[42:45], v11 offset:20480
	ds_read_b128 v[46:49], v11 offset:24576
	ds_read_b128 v[50:53], v11 offset:28672
	ds_read_b128 v[54:57], v11
	ds_read_b128 v[58:61], v11 offset:32768
	s_waitcnt lgkmcnt(0)
	v_mov_b32_e32 v70, v34
	v_mov_b32_e32 v71, v30
	v_mov_b32_e32 v30, v35
	v_mov_b32_e32 v34, v36
	v_mov_b32_e32 v35, v32
	v_mov_b32_e32 v32, v37
	v_mov_b32_e32 v36, v42
	v_mov_b32_e32 v37, v38
	v_mov_b32_e32 v38, v43
	v_mov_b32_e32 v42, v44
	v_mov_b32_e32 v43, v40
	v_mov_b32_e32 v40, v45
	v_mov_b32_e32 v44, v50
	v_mov_b32_e32 v45, v46
	v_mov_b32_e32 v46, v51
	v_mov_b32_e32 v50, v52
	v_mov_b32_e32 v51, v48
	v_mov_b32_e32 v48, v53
	v_mov_b32_e32 v52, v54
	v_mov_b32_e32 v53, v58
	v_mov_b32_e32 v58, v55
	v_mov_b32_e32 v54, v56
	v_mov_b32_e32 v55, v60
	v_mov_b32_e32 v60, v57
	v_add_u32_e32 v11, 16, v11
	s_cmp_eq_u32 s8, 0x480000
	s_waitcnt vmcnt(0)
	v_fmac_f32_e32 v24, v62, v26
	v_pk_fma_f32 v[20:21], v[62:63], v[70:71], v[20:21] op_sel_hi:[0,1,1]
	v_pk_fma_f32 v[18:19], v[62:63], v[36:37], v[18:19] op_sel_hi:[0,1,1]
	v_pk_fma_f32 v[16:17], v[62:63], v[44:45], v[16:17] op_sel_hi:[0,1,1]
	v_pk_fma_f32 v[14:15], v[62:63], v[52:53], v[14:15] op_sel_hi:[0,1,1]
	v_fmac_f32_e32 v24, v64, v27
	v_pk_fma_f32 v[20:21], v[64:65], v[30:31], v[20:21] op_sel_hi:[0,1,1]
	v_pk_fma_f32 v[18:19], v[64:65], v[38:39], v[18:19] op_sel_hi:[0,1,1]
	v_pk_fma_f32 v[16:17], v[64:65], v[46:47], v[16:17] op_sel_hi:[0,1,1]
	v_pk_fma_f32 v[14:15], v[64:65], v[58:59], v[14:15] op_sel_hi:[0,1,1]
	v_fmac_f32_e32 v24, v66, v28
	v_pk_fma_f32 v[20:21], v[66:67], v[34:35], v[20:21] op_sel_hi:[0,1,1]
	v_pk_fma_f32 v[18:19], v[66:67], v[42:43], v[18:19] op_sel_hi:[0,1,1]
	v_pk_fma_f32 v[16:17], v[66:67], v[50:51], v[16:17] op_sel_hi:[0,1,1]
	v_pk_fma_f32 v[14:15], v[66:67], v[54:55], v[14:15] op_sel_hi:[0,1,1]
	v_fmac_f32_e32 v24, v68, v29
	v_pk_fma_f32 v[20:21], v[68:69], v[32:33], v[20:21] op_sel_hi:[0,1,1]
	v_pk_fma_f32 v[18:19], v[68:69], v[40:41], v[18:19] op_sel_hi:[0,1,1]
	v_pk_fma_f32 v[16:17], v[68:69], v[48:49], v[16:17] op_sel_hi:[0,1,1]
	v_pk_fma_f32 v[14:15], v[68:69], v[60:61], v[14:15] op_sel_hi:[0,1,1]
	s_cbranch_scc0 .LBB0_15
	ds_write2st64_b32 v10, v14, v24 offset0:144 offset1:145
	ds_write2st64_b32 v10, v21, v20 offset0:146 offset1:147
	ds_write2st64_b32 v10, v19, v18 offset0:148 offset1:149
	ds_write2st64_b32 v10, v17, v16 offset0:150 offset1:151
	ds_write_b32 v10, v15 offset:38912
	s_waitcnt lgkmcnt(0)
	s_barrier
	s_and_saveexec_b64 s[8:9], vcc
	s_cbranch_execz .LBB0_13
	s_mul_i32 s3, s6, 0x2400
	s_add_i32 s4, s3, s2
	s_ashr_i32 s3, s2, 31
	v_or_b32_e32 v14, s4, v1
	s_mul_i32 s6, s6, 9
	v_ashrrev_i32_e32 v15, 31, v14
	v_lshl_add_u64 v[16:17], s[2:3], 2, v[12:13]
	s_mov_b64 s[2:3], 0
	v_mov_b32_e32 v11, v2
.LBB0_18:
	v_ashrrev_i32_e32 v28, 6, v11
	v_mov_b32_e32 v26, s64
	v_mov_b32_e32 v27, s65
	v_lshl_add_u32 v24, v28, 8, v8
	ds_read2st64_b32 v[18:19], v24 offset0:144 offset1:153
	ds_read2st64_b32 v[20:21], v24 offset0:162 offset1:171
	ds_read2st64_b32 v[22:23], v24 offset0:180 offset1:189
	ds_read2st64_b32 v[24:25], v24 offset0:198 offset1:207
	s_waitcnt lgkmcnt(0)
	v_add_f32_e32 v18, 0, v18
	v_readfirstlane_b32 s4, v26
	v_readfirstlane_b32 s5, v27
	v_add_f32_e32 v18, v18, v19
	v_mov_b32_e32 v26, s4
	v_mov_b32_e32 v27, s5
	global_load_dwordx2 v[26:27], v[26:27], off offset:40
	s_waitcnt vmcnt(0) lgkmcnt(0)
	v_add_f32_e32 v18, v18, v20
	v_readfirstlane_b32 s4, v26
	v_readfirstlane_b32 s5, v27
	v_add_f32_e32 v18, v18, v21
	v_mov_b32_e32 v26, s4
	v_mov_b32_e32 v27, s5
	v_lshl_add_u64 v[26:27], v[14:15], 2, v[26:27]
	global_load_dword v29, v[26:27], off
	v_add_f32_e32 v18, v18, v22
	v_add_f32_e32 v18, v18, v23
	v_add_f32_e32 v18, v18, v24
	v_add_u32_e32 v26, 0x200, v11
	v_cmp_lt_i32_e64 s[4:5], 63, v11
	v_add_u32_e32 v27, s6, v28
	v_add_f32_e32 v18, v18, v25
	s_or_b64 s[2:3], s[4:5], s[2:3]
	v_mov_b32_e32 v11, v26
	v_mad_i64_i32 v[26:27], s[4:5], v27, s11, v[16:17]
	s_waitcnt vmcnt(0) lgkmcnt(0)
	v_add_f32_e32 v18, v18, v29
	global_store_dword v[26:27], v18, off
	s_andn2_b64 exec, exec, s[2:3]
	s_cbranch_execnz .LBB0_18
	s_branch .LBB0_13
.LBB0_19:
	v_mov_b32_e32 v2, s65
	v_mov_b32_e32 v3, s64
	v_mov_b32_e32 v4, s65
	v_readfirstlane_b32 s2, v3
	v_readfirstlane_b32 s3, v2
	v_mov_b32_e32 v5, s64
	v_mov_b32_e32 v2, s2
	v_mov_b32_e32 v3, s3
	global_load_dwordx2 v[2:3], v[2:3], off offset:248
	s_waitcnt vmcnt(0) lgkmcnt(0)
	v_mov_b32_e32 v1, s64
	v_readfirstlane_b32 s2, v5
	v_readfirstlane_b32 s3, v4
	v_mov_b32_e32 v6, s65
	v_mov_b32_e32 v4, s2
	v_mov_b32_e32 v5, s3
	global_load_dwordx2 v[4:5], v[4:5], off
	v_readfirstlane_b32 s6, v2
	s_mov_b32 s13, 0
	v_readfirstlane_b32 s7, v3
	s_waitcnt vmcnt(0) lgkmcnt(0)
	v_mov_b32_e32 v8, v4
	v_mov_b32_e32 v4, v247
	v_readfirstlane_b32 s2, v1
	v_readfirstlane_b32 s3, v6
	v_mov_b32_e32 v1, s88
	v_mov_b32_e32 v6, s2
	v_mov_b32_e32 v7, s3
	global_load_dwordx2 v[6:7], v[6:7], off offset:16
	s_load_dwordx2 s[2:3], s[64:65], 0x100
	s_waitcnt lgkmcnt(0)
	v_readfirstlane_b32 s3, v5
	s_mov_b32 s12, s2
	s_lshl_b64 s[60:61], s[12:13], 9
	v_readfirstlane_b32 s2, v8
	s_waitcnt vmcnt(0)
	v_mov_b32_e32 v2, v6
	s_nop 0
	v_readfirstlane_b32 s8, v1
	s_ashr_i32 s9, s8, 31
	v_ashrrev_i32_e32 v5, 31, v4
	s_lshl_b64 s[4:5], s[8:9], 9
	v_readfirstlane_b32 s10, v2
	v_lshl_add_u64 v[2:3], s[4:5], 0, v[4:5]
	s_mov_b64 s[4:5], 0x480000
	v_readfirstlane_b32 s11, v7
	v_cmp_gt_u64_e32 vcc, s[4:5], v[2:3]
	s_and_saveexec_b64 s[4:5], vcc
	s_cbranch_execz .LBB0_22
	s_add_u32 s6, s6, 0x3300000
	s_addc_u32 s7, s7, 0
	s_lshl_b64 s[8:9], s[8:9], 13
	v_lshl_add_u64 v[4:5], v[4:5], 4, s[8:9]
	s_lshl_b64 s[8:9], s[12:13], 13
	s_add_u32 s10, s10, 0xfc000000
	s_addc_u32 s11, s11, -1
	s_mov_b64 s[16:17], 0
	s_mov_b64 s[18:19], 0x400000
	s_mov_b64 s[20:21], 0x47ffff
.LBB0_21:
	v_lshl_add_u64 v[6:7], s[2:3], 0, v[4:5]
	v_lshl_add_u64 v[8:9], s[10:11], 0, v[4:5]
	v_cmp_gt_u64_e32 vcc, s[18:19], v[2:3]
	v_lshl_add_u64 v[2:3], v[2:3], 0, s[60:61]
	v_lshl_add_u64 v[10:11], s[6:7], 0, v[4:5]
	v_cndmask_b32_e32 v7, v9, v7, vcc
	v_cndmask_b32_e32 v6, v8, v6, vcc
	global_load_dwordx4 v[6:9], v[6:7], off
	v_cmp_lt_u64_e32 vcc, s[20:21], v[2:3]
	v_lshl_add_u64 v[4:5], v[4:5], 0, s[8:9]
	s_or_b64 s[16:17], vcc, s[16:17]
	s_waitcnt vmcnt(0) lgkmcnt(0)
	global_store_dwordx4 v[10:11], v[6:9], off
	s_andn2_b64 exec, exec, s[16:17]
	s_cbranch_execnz .LBB0_21
.LBB0_22:
	s_or_b64 exec, exec, s[4:5]
	v_mov_b32_e32 v1, s64
	v_mov_b32_e32 v2, s65
	v_mov_b32_e32 v4, v247
	v_readfirstlane_b32 s2, v1
	v_readfirstlane_b32 s3, v2
	v_mov_b32_e32 v1, s88
	v_mov_b32_e32 v2, s2
	v_mov_b32_e32 v3, s3
	global_load_dwordx2 v[2:3], v[2:3], off offset:248
	s_waitcnt vmcnt(0) lgkmcnt(0)
	s_nop 0
	v_readfirstlane_b32 s2, v1
	s_ashr_i32 s3, s2, 31
	v_ashrrev_i32_e32 v5, 31, v4
	s_lshl_b64 s[2:3], s[2:3], 9
	v_readfirstlane_b32 s4, v2
	v_readfirstlane_b32 s5, v3
	v_lshl_add_u64 v[2:3], s[2:3], 0, v[4:5]
	s_mov_b64 s[2:3], 0x10000
	v_cmp_gt_u64_e32 vcc, s[2:3], v[2:3]
	s_and_saveexec_b64 s[2:3], vcc
	s_cbranch_execz .LBB0_33
	v_and_b32_e32 v1, 15, v4
	v_cvt_f32_ubyte0_e32 v1, v1
	v_mul_f32_e32 v5, 0xbf549a78, v1
	s_mov_b32 s6, 0xc2fc0000
	v_mov_b32_e32 v6, 0x42800000
	v_cmp_gt_f32_e32 vcc, s6, v5
	v_and_b32_e32 v4, 31, v4
	v_lshlrev_b32_e32 v4, 2, v4
	v_cndmask_b32_e32 v5, 0, v6, vcc
	v_fmac_f32_e32 v5, 0xbf549a78, v1
	v_exp_f32_e32 v5, v5
	v_not_b32_e32 v1, 63
	v_cndmask_b32_e32 v6, 0, v1, vcc
	s_mov_b64 s[16:17], 0
	v_ldexp_f32 v10, v5, v6
	v_mov_b32_e32 v5, 0
	v_lshl_add_u64 v[6:7], s[4:5], 0, v[4:5]
	s_mov_b64 s[4:5], 0x21b69200
	v_lshl_add_u64 v[6:7], v[6:7], 0, s[4:5]
	s_brev_b32 s22, 18
	s_mov_b32 s23, 0xfe5163ab
	s_mov_b32 s24, 0x3c439041
	s_mov_b32 s25, 0xdb629599
	s_mov_b32 s26, 0xf534ddc0
	s_mov_b32 s27, 0xfc2757d1
	s_mov_b32 s28, 0x4e441529
	s_mov_b32 s29, 0xa2f9836e
	s_mov_b32 s30, 0x3fc90fda
	v_mov_b32_e32 v11, 0x3c0881c4
	v_mov_b32_e32 v12, 0xbab64f3b
	s_brev_b32 s31, 1
	s_mov_b32 s34, 0x7f800000
	s_mov_b64 s[18:19], 0xffff
	v_not_b32_e32 v13, 31
	v_mov_b32_e32 v14, 0x7fc00000
	s_branch .LBB0_25
.LBB0_24:
	s_or_b64 exec, exec, s[6:7]
	v_mul_f32_e32 v4, v15, v15
	v_fmamk_f32 v16, v4, 0xb94c1982, v11
	v_fmaak_f32 v16, v4, v16, 0xbe2aaa9d
	v_mul_f32_e32 v16, v4, v16
	v_fmac_f32_e32 v15, v15, v16
	v_fmamk_f32 v16, v4, 0x37d75334, v12
	v_fmaak_f32 v16, v4, v16, 0x3d2aabf7
	v_fmaak_f32 v16, v4, v16, 0xbf000004
	v_fma_f32 v4, v4, v16, 1.0
	v_and_b32_e32 v16, 1, v18
	v_cmp_eq_u32_e32 vcc, 0, v16
	v_lshl_add_u64 v[2:3], v[2:3], 0, s[60:61]
	s_nop 0
	v_cndmask_b32_e32 v4, v4, v15, vcc
	v_lshlrev_b32_e32 v15, 30, v18
	v_bitop3_b32 v4, v15, v4, s31 bitop3:0x6c
	v_cmp_lt_u64_e32 vcc, s[18:19], v[2:3]
	v_cndmask_b32_e64 v4, v14, v4, s[4:5]
	s_or_b64 s[16:17], vcc, s[16:17]
	global_store_dword v[8:9], v4, off offset:128
	s_andn2_b64 exec, exec, s[16:17]
	s_cbranch_execz .LBB0_33

.LBB0_27:
	s_or_saveexec_b64 s[4:5], s[20:21]
	v_mul_f32_e32 v4, 0x3f22f983, v15
	v_rndne_f32_e32 v4, v4
	s_xor_b64 exec, exec, s[4:5]
	v_cvt_i32_f32_e32 v8, v4
	v_fmamk_f32 v9, v4, 0xbfc90fda, v15
	v_fmac_f32_e32 v9, 0xb3a22168, v4
	v_fmac_f32_e32 v9, 0xa7c234c4, v4
	s_or_b64 exec, exec, s[4:5]
	v_mul_f32_e32 v20, v9, v9
	v_fmamk_f32 v21, v20, 0xb94c1982, v11
	v_fmaak_f32 v21, v20, v21, 0xbe2aaa9d
	v_mul_f32_e32 v21, v20, v21
	v_fmac_f32_e32 v9, v9, v21
	v_fmamk_f32 v21, v20, 0x37d75334, v12
	v_fmaak_f32 v21, v20, v21, 0x3d2aabf7
	v_fmaak_f32 v21, v20, v21, 0xbf000004
	v_fma_f32 v20, v20, v21, 1.0
	v_and_b32_e32 v21, 1, v8
	v_cmp_eq_u32_e64 s[4:5], 0, v21
	v_lshlrev_b32_e32 v8, 30, v8
	v_lshrrev_b64 v[18:19], 5, v[2:3]
	v_cndmask_b32_e64 v9, -v9, v20, s[4:5]
	v_bitop3_b32 v8, v8, v9, s31 bitop3:0x6c
	v_cmp_lg_f32_e64 s[4:5], s34, v15
	s_nop 1
	v_cndmask_b32_e64 v20, v14, v8, s[4:5]
	v_lshlrev_b64 v[8:9], 8, v[18:19]
	v_lshl_add_u64 v[8:9], v[6:7], 0, v[8:9]
	global_store_dword v[8:9], v20, off
	s_and_saveexec_b64 s[6:7], vcc
	s_xor_b64 s[20:21], exec, s[6:7]
	s_cbranch_execz .LBB0_31
	v_cmp_lt_u32_e32 vcc, 63, v17
	v_mad_u64_u32 v[18:19], s[10:11], v16, s23, 0
	s_nop 0
	v_cndmask_b32_e32 v4, 0, v1, vcc
	v_add_u32_e32 v4, v4, v17
	v_cmp_lt_u32_e64 s[6:7], 31, v4
	s_nop 1
	v_cndmask_b32_e64 v15, 0, v13, s[6:7]
	v_add_u32_e32 v4, v15, v4
	v_cmp_lt_u32_e64 s[8:9], 31, v4
	s_nop 1
	v_cndmask_b32_e64 v15, 0, v13, s[8:9]
	v_add_u32_e32 v15, v15, v4
	v_mov_b32_e32 v4, v19
	v_mad_u64_u32 v[20:21], s[10:11], v16, s24, v[4:5]
	v_mov_b32_e32 v4, v21
	v_mad_u64_u32 v[22:23], s[10:11], v16, s25, v[4:5]
	v_mov_b32_e32 v4, v23
	v_mad_u64_u32 v[24:25], s[10:11], v16, s26, v[4:5]
	v_mov_b32_e32 v4, v25
	v_mad_u64_u32 v[26:27], s[10:11], v16, s27, v[4:5]
	v_mov_b32_e32 v4, v27
	v_mad_u64_u32 v[28:29], s[10:11], v16, s28, v[4:5]
	v_mov_b32_e32 v4, v29
	v_mad_u64_u32 v[16:17], s[10:11], v16, s29, v[4:5]
	v_cndmask_b32_e32 v19, v28, v24, vcc
	v_cndmask_b32_e32 v4, v16, v26, vcc
	v_cndmask_b32_e32 v17, v17, v28, vcc
	v_cndmask_b32_e64 v16, v4, v19, s[6:7]
	v_cndmask_b32_e64 v4, v17, v4, s[6:7]
	v_cndmask_b32_e32 v17, v26, v22, vcc
	v_cndmask_b32_e64 v19, v19, v17, s[6:7]
	v_sub_u32_e32 v21, 32, v15
	v_cmp_eq_u32_e64 s[10:11], 0, v15
	v_cndmask_b32_e32 v15, v24, v20, vcc
	v_cndmask_b32_e64 v4, v4, v16, s[8:9]
	v_cndmask_b32_e64 v16, v16, v19, s[8:9]
	v_cndmask_b32_e64 v17, v17, v15, s[6:7]
	v_alignbit_b32 v23, v4, v16, v21
	v_cndmask_b32_e64 v19, v19, v17, s[8:9]
	v_cndmask_b32_e64 v4, v23, v4, s[10:11]
	v_alignbit_b32 v20, v16, v19, v21
	v_cndmask_b32_e32 v18, v22, v18, vcc
	v_cndmask_b32_e64 v16, v20, v16, s[10:11]
	v_bfe_u32 v24, v4, 29, 1
	v_cndmask_b32_e64 v15, v15, v18, s[6:7]
	v_alignbit_b32 v20, v4, v16, 30
	v_sub_u32_e32 v25, 0, v24
	v_cndmask_b32_e64 v15, v17, v15, s[8:9]
	v_xor_b32_e32 v20, v20, v25
	v_alignbit_b32 v17, v19, v15, v21
	v_cndmask_b32_e64 v17, v17, v19, s[10:11]
	v_ffbh_u32_e32 v18, v20
	v_alignbit_b32 v16, v16, v17, 30
	v_min_u32_e32 v18, 32, v18
	v_alignbit_b32 v15, v17, v15, 30
	v_xor_b32_e32 v16, v16, v25
	v_sub_u32_e32 v19, 31, v18
	v_xor_b32_e32 v15, v15, v25
	v_alignbit_b32 v20, v20, v16, v19
	v_alignbit_b32 v15, v16, v15, v19
	v_alignbit_b32 v16, v20, v15, 9
	v_ffbh_u32_e32 v17, v16
	v_min_u32_e32 v17, 32, v17
	v_lshrrev_b32_e32 v23, 29, v4
	v_not_b32_e32 v19, v17
	v_alignbit_b32 v15, v16, v15, v19
	v_lshlrev_b32_e32 v16, 31, v23
	v_or_b32_e32 v19, 0x33000000, v16
	v_add_lshl_u32 v17, v17, v18, 23
	v_lshrrev_b32_e32 v15, 9, v15
	v_sub_u32_e32 v17, v19, v17
	v_or_b32_e32 v16, 0.5, v16
	v_lshlrev_b32_e32 v18, 23, v18
	v_or_b32_e32 v15, v17, v15
	v_lshrrev_b32_e32 v17, 9, v20
	v_sub_u32_e32 v16, v16, v18
	v_or_b32_e32 v16, v17, v16
	v_mul_f32_e32 v17, 0x3fc90fda, v16
	v_fma_f32 v18, v16, s30, -v17
	v_fmac_f32_e32 v18, 0x33a22168, v16
	v_fmac_f32_e32 v18, 0x3fc90fda, v15
	v_lshrrev_b32_e32 v4, 30, v4
	v_add_f32_e32 v15, v17, v18
	v_add_u32_e32 v18, v24, v4

.LBB0_33:
	s_or_b64 exec, exec, s[2:3]
	v_mov_b32_e32 v1, s64
	v_mov_b32_e32 v2, s65
	v_writelane_b32 v253, s64, 2
	v_readfirstlane_b32 s2, v1
	v_readfirstlane_b32 s3, v2
	v_mov_b32_e32 v1, s88
	v_mov_b32_e32 v2, s2
	v_mov_b32_e32 v3, s3
	global_load_dwordx2 v[2:3], v[2:3], off offset:248
	v_writelane_b32 v253, s65, 3
	s_waitcnt vmcnt(0) lgkmcnt(0)
	v_writelane_b32 v253, s60, 4
	v_readfirstlane_b32 s39, v1
	v_readfirstlane_b32 s38, v2
	s_cmpk_gt_u32 s39, 0x65f
	v_readfirstlane_b32 s40, v3
	v_writelane_b32 v253, s61, 5
	s_cbranch_scc1 .LBB0_345
	s_add_u32 s41, s38, 0x2d80000
	s_addc_u32 s42, s40, 0
	s_add_u32 s43, s38, 0x2280000
	s_addc_u32 s44, s40, 0
	s_add_u32 s45, s38, 0x2080000
	s_addc_u32 s46, s40, 0
	s_add_u32 s47, s38, 0x1e80000
	s_addc_u32 s48, s40, 0
	s_add_u32 s49, s38, 0x1080000
	s_addc_u32 s50, s40, 0
	s_add_u32 s51, s38, 0xb00000
	v_readlane_b32 s2, v253, 0
	s_mov_b64 s[90:91], s[62:63]
	s_addc_u32 s52, s40, 0
	s_lshl_b32 s53, s39, 8
	s_lshl_b32 s54, s2, 8
	s_lshl_b32 s55, s39, 4
	s_lshl_b32 s56, s2, 4
	s_movk_i32 s57, 0x4ff
	s_mov_b32 s5, 0
	v_mov_b32_e32 v35, 0
	s_movk_i32 s58, 0x104
	s_movk_i32 s59, 0x400
	s_movk_i32 s60, 0x1600
	s_movk_i32 s61, 0x2c00
	s_movk_i32 s62, 0xb00
	s_movk_i32 s63, 0x1f00
	s_movk_i32 s64, 0x6c20
	s_movk_i32 s65, 0x1b09
	s_movk_i32 s66, 0x1b08
	s_movk_i32 s67, 0x17f
	s_movk_i32 s68, 0x1ff
	s_movk_i32 s69, 0x2ff
	s_movk_i32 s70, 0x3ff
	s_movk_i32 s71, 0x5ff
	s_movk_i32 s72, 0x67f
	s_movk_i32 s73, 0x6ff
	s_movk_i32 s74, 0x7ff
	s_movk_i32 s75, 0x8ff
	s_movk_i32 s76, 0x9ff
	s_movk_i32 s77, 0xaff
	s_movk_i32 s78, 0xb07
	v_readlane_b32 s3, v253, 1
	s_branch .LBB0_37

.LBB0_37:
	s_cmpk_gt_i32 s39, 0xaf
	s_mov_b64 s[2:3], -1
	s_cbranch_scc0 .LBB0_334
	s_cmpk_gt_u32 s39, 0x15f
	s_cbranch_scc0 .LBB0_323
	s_cmpk_gt_u32 s39, 0x20f
	s_cbranch_scc0 .LBB0_312
	s_cmpk_gt_u32 s39, 0x3cf
	s_cbranch_scc0 .LBB0_97
	s_cmpk_gt_u32 s39, 0x40f
	s_cbranch_scc0 .LBB0_86
	s_cmpk_gt_u32 s39, 0x44f
	s_cbranch_scc0 .LBB0_75
	s_cmpk_gt_u32 s39, 0x4ff
	s_cbranch_scc0 .LBB0_64
	s_cmpk_gt_u32 s39, 0x5af
	s_cbranch_scc0 .LBB0_54
	v_readlane_b32 s2, v253, 2
	v_readlane_b32 s3, v253, 3
	v_mov_b32_e32 v4, v247
	v_mov_b32_e32 v1, s2
	v_mov_b32_e32 v2, s3
	s_and_b32 s6, s53, 0x300
	v_readfirstlane_b32 s2, v1
	v_readfirstlane_b32 s3, v2
	s_lshl_b32 s4, s6, 2
	v_mov_b32_e32 v2, s2
	v_mov_b32_e32 v3, s3
	global_load_dwordx2 v[2:3], v[2:3], off offset:224
	s_and_b32 s2, s55, 0x7fffffc0
	s_addk_i32 s2, 0xa500
	s_mov_b32 s3, s5
	s_waitcnt vmcnt(0) lgkmcnt(0)
	v_mov_b32_e32 v1, v3
	s_nop 0
	v_readfirstlane_b32 s8, v2
	v_readfirstlane_b32 s9, v1
	v_ashrrev_i32_e32 v1, 3, v4
	v_lshlrev_b32_e32 v2, 3, v4
	v_and_b32_e32 v5, 56, v2
	v_add_u32_e32 v2, s2, v1
	v_ashrrev_i32_e32 v3, 31, v2
	v_lshlrev_b64 v[2:3], 12, v[2:3]
	v_lshlrev_b32_e32 v34, 2, v5
	v_lshl_add_u64 v[2:3], s[8:9], 0, v[2:3]
	v_lshl_add_u64 v[2:3], v[2:3], 0, v[34:35]
	v_lshl_add_u64 v[2:3], v[2:3], 0, s[4:5]
	global_load_dwordx4 v[6:9], v[2:3], off
	global_load_dwordx4 v[10:13], v[2:3], off offset:16
	global_load_dwordx4 v[14:17], v[2:3], off offset:256
	global_load_dwordx4 v[18:21], v[2:3], off offset:272
	global_load_dwordx4 v[22:25], v[2:3], off offset:512
	global_load_dwordx4 v[26:29], v[2:3], off offset:528
	global_load_dwordx4 v[30:33], v[2:3], off offset:768
	global_load_dwordx4 v[36:39], v[2:3], off offset:784
	s_lshl_b64 s[2:3], s[2:3], 1
	v_mul_lo_u32 v2, v1, s58
	s_add_u32 s2, s41, s2
	v_lshlrev_b32_e32 v3, 8, v1
	v_add_u32_e32 v2, 16, v2
	s_addc_u32 s3, s42, s3
	v_add_u32_e32 v4, s6, v1
	v_mul_u32_u24_e32 v40, 0x104, v5
	v_add_u32_e32 v41, v2, v34
	v_sub_u32_e32 v42, v2, v3
	v_lshlrev_b32_e32 v34, 1, v5
	v_cmp_gt_u32_e32 vcc, s59, v4
	v_lshl_add_u64 v[2:3], s[2:3], 0, v[34:35]
	v_add_u32_e32 v5, v42, v40
	v_add_u32_e32 v43, 0x4100, v41
	v_add_u32_e32 v44, 0x4108, v41
	v_add_u32_e32 v45, 0x4110, v41
	v_add_u32_e32 v46, 0x4118, v41
	v_add_u32_e32 v47, 0x8200, v41
	v_add_u32_e32 v48, 0x8208, v41
	v_add_u32_e32 v49, 0x8210, v41
	v_add_u32_e32 v50, 0x8218, v41
	v_add_u32_e32 v51, 0xc300, v41
	v_add_u32_e32 v52, 0xc308, v41
	v_add_u32_e32 v53, 0xc310, v41
	v_add_u32_e32 v54, 0xc318, v41
	s_waitcnt vmcnt(0) lgkmcnt(0)
	ds_write2_b32 v41, v6, v7 offset1:1
	ds_write2_b32 v41, v8, v9 offset0:2 offset1:3
	ds_write2_b32 v41, v10, v11 offset0:4 offset1:5
	ds_write2_b32 v41, v12, v13 offset0:6 offset1:7
	ds_write2_b32 v43, v14, v15 offset1:1
	ds_write2_b32 v44, v16, v17 offset1:1
	ds_write2_b32 v45, v18, v19 offset1:1
	ds_write2_b32 v46, v20, v21 offset1:1
	ds_write2_b32 v47, v22, v23 offset1:1
	ds_write2_b32 v48, v24, v25 offset1:1
	ds_write2_b32 v49, v26, v27 offset1:1
	ds_write2_b32 v50, v28, v29 offset1:1
	ds_write2_b32 v51, v30, v31 offset1:1
	ds_write2_b32 v52, v32, v33 offset1:1
	ds_write2_b32 v53, v36, v37 offset1:1
	ds_write2_b32 v54, v38, v39 offset1:1
	s_waitcnt lgkmcnt(0)
	s_barrier
	s_and_saveexec_b64 s[2:3], vcc
	s_cbranch_execz .LBB0_47
	v_add_u32_e32 v8, 0x400, v5
	ds_read2_b32 v[6:7], v8 offset0:134 offset1:199
	ds_read2_b32 v[10:11], v8 offset0:4 offset1:69
	ds_read2_b32 v[12:13], v5 offset0:130 offset1:195
	ds_read2_b32 v[14:15], v5 offset1:65
	v_mul_lo_u32 v34, v4, s60
	s_waitcnt lgkmcnt(3)
	v_cvt_pk_bf16_f32 v9, v6, v7
	s_waitcnt lgkmcnt(2)
	v_cvt_pk_bf16_f32 v8, v10, v11
	s_waitcnt lgkmcnt(1)
	v_cvt_pk_bf16_f32 v7, v12, v13
	s_waitcnt lgkmcnt(0)
	v_cvt_pk_bf16_f32 v6, v14, v15
	v_lshl_add_u64 v[10:11], v[2:3], 0, v[34:35]
	global_store_dwordx4 v[10:11], v[6:9], off
.LBB0_47:
	s_or_b64 exec, exec, s[2:3]
	v_add3_u32 v1, v1, s6, 64
	v_cmp_gt_u32_e32 vcc, s59, v1
	s_and_saveexec_b64 s[2:3], vcc
	s_cbranch_execz .LBB0_49
	v_add_u32_e32 v8, 0x4400, v5
	ds_read2_b32 v[10:11], v8 offset0:68 offset1:133
	v_add_u32_e32 v8, 0x4200, v5
	v_add_u32_e32 v6, 0x4600, v5
	ds_read2_b32 v[12:13], v8 offset0:66 offset1:131
	v_add_u32_e32 v8, 0x4000, v5
	ds_read2_b32 v[6:7], v6 offset0:70 offset1:135
	ds_read2_b32 v[14:15], v8 offset0:64 offset1:129
	v_mul_lo_u32 v34, v1, s60
	s_waitcnt lgkmcnt(0)
	v_cvt_pk_bf16_f32 v8, v10, v11
	v_lshl_add_u64 v[10:11], v[2:3], 0, v[34:35]
	v_cvt_pk_bf16_f32 v9, v6, v7
	v_cvt_pk_bf16_f32 v7, v12, v13
	v_cvt_pk_bf16_f32 v6, v14, v15
	global_store_dwordx4 v[10:11], v[6:9], off
.LBB0_49:
	s_or_b64 exec, exec, s[2:3]
	v_add_u32_e32 v1, 0x80, v4
	v_cmp_gt_u32_e32 vcc, s59, v1
	s_and_saveexec_b64 s[2:3], vcc
	s_cbranch_execz .LBB0_51
	v_add_u32_e32 v6, 0x8800, v5
	v_add_u32_e32 v8, 0x8400, v5
	ds_read2_b32 v[6:7], v6 offset0:6 offset1:71
	ds_read2_b32 v[10:11], v8 offset0:132 offset1:197
	ds_read2_b32 v[12:13], v8 offset0:2 offset1:67
	v_add_u32_e32 v8, 0x8000, v5
	ds_read2_b32 v[14:15], v8 offset0:128 offset1:193
	v_mul_lo_u32 v34, v1, s60
	s_waitcnt lgkmcnt(0)
	v_cvt_pk_bf16_f32 v9, v6, v7
	v_cvt_pk_bf16_f32 v8, v10, v11
	v_cvt_pk_bf16_f32 v7, v12, v13
	v_cvt_pk_bf16_f32 v6, v14, v15
	v_lshl_add_u64 v[10:11], v[2:3], 0, v[34:35]
	global_store_dwordx4 v[10:11], v[6:9], off
.LBB0_51:
	s_or_b64 exec, exec, s[2:3]
	v_add_u32_e32 v1, 0xc0, v4
	v_cmp_gt_u32_e32 vcc, s59, v1
	s_and_saveexec_b64 s[2:3], vcc
	s_cbranch_execz .LBB0_53
	v_add_u32_e32 v4, 0xc800, v5
	ds_read2_b32 v[6:7], v4 offset0:70 offset1:135
	v_add_u32_e32 v4, 0xc600, v5
	ds_read2_b32 v[8:9], v4 offset0:68 offset1:133
	v_add_u32_e32 v4, 0xc400, v5
	ds_read2_b32 v[10:11], v4 offset0:66 offset1:131
	v_add_u32_e32 v4, 0xc200, v5
	ds_read2_b32 v[12:13], v4 offset0:64 offset1:129
	v_mul_lo_u32 v34, v1, s60
	s_waitcnt lgkmcnt(0)
	v_cvt_pk_bf16_f32 v7, v6, v7
	v_cvt_pk_bf16_f32 v6, v8, v9
	v_cvt_pk_bf16_f32 v5, v10, v11
	v_cvt_pk_bf16_f32 v4, v12, v13
	v_lshl_add_u64 v[2:3], v[2:3], 0, v[34:35]
	global_store_dwordx4 v[2:3], v[4:7], off

.LBB0_54:
	s_and_b64 vcc, exec, s[2:3]
	s_cbranch_vccz .LBB0_343
	v_readlane_b32 s2, v253, 2
	v_readlane_b32 s3, v253, 3
	s_nop 0
	v_mov_b32_e32 v1, s2
	v_mov_b32_e32 v2, s3
	s_nop 0
	v_readfirstlane_b32 s2, v1
	v_readfirstlane_b32 s3, v2
	v_mov_b32_e32 v1, v247
	v_mov_b32_e32 v2, s2
	s_and_b32 s2, s39, 0xff
	s_mulk_i32 s2, 0x75
	s_lshr_b32 s2, s2, 8
	v_mov_b32_e32 v3, s3
	s_sub_i32 s3, s39, s2
	s_bfe_u32 s3, s3, 0x70001
	s_add_i32 s3, s3, s2
	s_bfe_u32 s6, s3, 0x50003
	s_mul_i32 s2, s6, 11
	s_sub_i32 s2, s39, s2
	global_load_dwordx2 v[2:3], v[2:3], off offset:216
	s_lshl_b32 s2, s2, 2
	s_and_b32 s7, s2, 0xfc
	s_waitcnt vmcnt(0) lgkmcnt(0)
	s_lshl_b32 s4, s7, 8
	v_readfirstlane_b32 s2, v2
	v_readfirstlane_b32 s3, v3
	v_ashrrev_i32_e32 v4, 3, v1
	v_lshlrev_b32_e32 v5, 3, v1
	v_mov_b32_e32 v2, s2
	v_mov_b32_e32 v3, s3
	v_and_b32_e32 v40, 56, v5
	v_lshl_add_u32 v5, s6, 6, v4
	v_mad_i64_i32 v[2:3], s[2:3], v5, s61, v[2:3]
	v_lshlrev_b32_e32 v34, 2, v40
	v_lshl_add_u64 v[2:3], v[2:3], 0, v[34:35]
	v_lshl_add_u64 v[2:3], v[2:3], 0, s[4:5]
	global_load_dwordx4 v[6:9], v[2:3], off
	global_load_dwordx4 v[10:13], v[2:3], off offset:16
	global_load_dwordx4 v[14:17], v[2:3], off offset:256
	global_load_dwordx4 v[18:21], v[2:3], off offset:272
	global_load_dwordx4 v[22:25], v[2:3], off offset:512
	global_load_dwordx4 v[26:29], v[2:3], off offset:528
	global_load_dwordx4 v[30:33], v[2:3], off offset:768
	global_load_dwordx4 v[36:39], v[2:3], off offset:784
	s_lshl_b32 s2, s6, 7
	s_lshl_b32 s4, s7, 6
	v_mul_lo_u32 v2, v4, s58
	s_add_u32 s2, s43, s2
	v_lshlrev_b32_e32 v3, 8, v4
	v_add_u32_e32 v2, 16, v2
	s_addc_u32 s3, s44, 0
	v_bfe_u32 v5, v1, 3, 7
	v_add_u32_e32 v1, s4, v4
	v_mul_u32_u24_e32 v41, 0x104, v40
	v_add_u32_e32 v42, v2, v34
	v_sub_u32_e32 v43, v2, v3
	v_lshlrev_b32_e32 v34, 1, v40
	v_cmp_gt_u32_e32 vcc, s62, v1
	v_add_u32_e32 v40, 0x4100, v42
	v_add_u32_e32 v44, 0x4108, v42
	v_add_u32_e32 v45, 0x4110, v42
	v_add_u32_e32 v46, 0x4118, v42
	v_add_u32_e32 v47, 0x8200, v42
	v_add_u32_e32 v48, 0x8208, v42
	v_add_u32_e32 v49, 0x8210, v42
	v_add_u32_e32 v50, 0x8218, v42
	v_add_u32_e32 v51, 0xc300, v42
	v_add_u32_e32 v52, 0xc308, v42
	v_add_u32_e32 v53, 0xc310, v42
	v_add_u32_e32 v54, 0xc318, v42
	v_lshl_add_u64 v[2:3], s[2:3], 0, v[34:35]
	s_waitcnt vmcnt(0) lgkmcnt(0)
	ds_write2_b32 v42, v6, v7 offset1:1
	ds_write2_b32 v42, v8, v9 offset0:2 offset1:3
	ds_write2_b32 v42, v10, v11 offset0:4 offset1:5
	ds_write2_b32 v42, v12, v13 offset0:6 offset1:7
	ds_write2_b32 v40, v14, v15 offset1:1
	ds_write2_b32 v44, v16, v17 offset1:1
	ds_write2_b32 v45, v18, v19 offset1:1
	ds_write2_b32 v46, v20, v21 offset1:1
	ds_write2_b32 v47, v22, v23 offset1:1
	ds_write2_b32 v48, v24, v25 offset1:1
	ds_write2_b32 v49, v26, v27 offset1:1
	ds_write2_b32 v50, v28, v29 offset1:1
	ds_write2_b32 v51, v30, v31 offset1:1
	ds_write2_b32 v52, v32, v33 offset1:1
	ds_write2_b32 v53, v36, v37 offset1:1
	ds_write2_b32 v54, v38, v39 offset1:1
	v_add_u32_e32 v6, v43, v41
	s_waitcnt lgkmcnt(0)
	s_barrier
	s_and_saveexec_b64 s[2:3], vcc
	s_cbranch_execz .LBB0_57
	v_add_u32_e32 v10, 0x400, v6
	v_lshlrev_b32_e32 v7, 1, v1
	ds_read2_b32 v[8:9], v10 offset0:134 offset1:199
	ds_read2_b32 v[12:13], v10 offset0:4 offset1:69
	ds_read2_b32 v[14:15], v6 offset0:130 offset1:195
	ds_read2_b32 v[16:17], v6 offset1:65
	v_and_or_b32 v7, v7, s63, v5
	v_lshlrev_b32_e32 v34, 11, v7
	s_waitcnt lgkmcnt(2)
	v_cvt_pk_bf16_f32 v10, v12, v13
	v_lshl_add_u64 v[12:13], v[2:3], 0, v[34:35]
	v_add_co_u32_e32 v12, vcc, 0x40000, v12
	v_cvt_pk_bf16_f32 v11, v8, v9
	s_waitcnt lgkmcnt(1)
	v_cvt_pk_bf16_f32 v9, v14, v15
	s_waitcnt lgkmcnt(0)
	v_cvt_pk_bf16_f32 v8, v16, v17
	v_addc_co_u32_e32 v13, vcc, 0, v13, vcc
	global_store_dwordx4 v[12:13], v[8:11], off
.LBB0_57:
	s_or_b64 exec, exec, s[2:3]
	v_add3_u32 v4, v4, s4, 64
	v_cmp_gt_u32_e32 vcc, s62, v4
	s_and_saveexec_b64 s[2:3], vcc
	s_cbranch_execz .LBB0_59
	v_add_u32_e32 v10, 0x4400, v6
	ds_read2_b32 v[12:13], v10 offset0:68 offset1:133
	v_add_u32_e32 v10, 0x4200, v6
	v_add_u32_e32 v8, 0x4600, v6
	ds_read2_b32 v[14:15], v10 offset0:66 offset1:131
	v_add_u32_e32 v10, 0x4000, v6
	v_lshlrev_b32_e32 v7, 1, v4
	v_and_b32_e32 v4, 0x7f, v4
	ds_read2_b32 v[8:9], v8 offset0:70 offset1:135
	ds_read2_b32 v[16:17], v10 offset0:64 offset1:129
	v_and_or_b32 v4, v7, s63, v4
	v_lshlrev_b32_e32 v34, 11, v4
	s_waitcnt lgkmcnt(0)
	v_cvt_pk_bf16_f32 v10, v12, v13
	v_lshl_add_u64 v[12:13], v[2:3], 0, v[34:35]
	v_add_co_u32_e32 v12, vcc, 0x40000, v12
	v_cvt_pk_bf16_f32 v11, v8, v9
	v_cvt_pk_bf16_f32 v9, v14, v15
	v_cvt_pk_bf16_f32 v8, v16, v17
	v_addc_co_u32_e32 v13, vcc, 0, v13, vcc
	global_store_dwordx4 v[12:13], v[8:11], off
.LBB0_59:
	s_or_b64 exec, exec, s[2:3]
	v_add_u32_e32 v4, 0x80, v1
	v_cmp_gt_u32_e32 vcc, s62, v4
	s_and_saveexec_b64 s[2:3], vcc
	s_cbranch_execz .LBB0_61
	v_add_u32_e32 v7, 0x8800, v6
	ds_read2_b32 v[8:9], v7 offset0:6 offset1:71
	v_add_u32_e32 v7, 0x8400, v6
	ds_read2_b32 v[12:13], v7 offset0:132 offset1:197
	ds_read2_b32 v[14:15], v7 offset0:2 offset1:67
	v_add_u32_e32 v7, 0x8000, v6
	v_lshlrev_b32_e32 v4, 1, v4
	ds_read2_b32 v[16:17], v7 offset0:128 offset1:193
	v_and_or_b32 v4, v4, s63, v5
	v_lshlrev_b32_e32 v34, 11, v4
	v_lshl_add_u64 v[4:5], v[2:3], 0, v[34:35]
	v_add_co_u32_e32 v4, vcc, 0x40000, v4
	s_waitcnt lgkmcnt(0)
	v_cvt_pk_bf16_f32 v11, v8, v9
	v_cvt_pk_bf16_f32 v10, v12, v13
	v_cvt_pk_bf16_f32 v9, v14, v15
	v_cvt_pk_bf16_f32 v8, v16, v17
	v_addc_co_u32_e32 v5, vcc, 0, v5, vcc
	global_store_dwordx4 v[4:5], v[8:11], off
.LBB0_61:
	s_or_b64 exec, exec, s[2:3]
	v_add_u32_e32 v1, 0xc0, v1
	v_cmp_gt_u32_e32 vcc, s62, v1
	s_and_saveexec_b64 s[2:3], vcc
	s_cbranch_execz .LBB0_63
	v_add_u32_e32 v4, 0xc800, v6
	v_add_u32_e32 v8, 0xc600, v6
	v_add_u32_e32 v10, 0xc400, v6
	v_add_u32_e32 v6, 0xc200, v6
	v_lshlrev_b32_e32 v7, 1, v1
	v_and_b32_e32 v1, 0x7f, v1
	ds_read2_b32 v[4:5], v4 offset0:70 offset1:135
	ds_read2_b32 v[8:9], v8 offset0:68 offset1:133
	ds_read2_b32 v[10:11], v10 offset0:66 offset1:131
	ds_read2_b32 v[12:13], v6 offset0:64 offset1:129
	v_and_or_b32 v1, v7, s63, v1
	v_lshlrev_b32_e32 v34, 11, v1
	v_lshl_add_u64 v[2:3], v[2:3], 0, v[34:35]
	v_add_co_u32_e32 v2, vcc, 0x40000, v2
	s_waitcnt lgkmcnt(0)
	v_cvt_pk_bf16_f32 v7, v4, v5
	v_cvt_pk_bf16_f32 v6, v8, v9
	v_cvt_pk_bf16_f32 v5, v10, v11
	v_cvt_pk_bf16_f32 v4, v12, v13
	v_addc_co_u32_e32 v3, vcc, 0, v3, vcc
	global_store_dwordx4 v[2:3], v[4:7], off

.LBB0_65:
	v_readlane_b32 s2, v253, 2
	v_readlane_b32 s3, v253, 3
	s_nop 0
	v_mov_b32_e32 v1, s2
	v_mov_b32_e32 v2, s3
	s_nop 0
	v_readfirstlane_b32 s2, v1
	v_readfirstlane_b32 s3, v2
	v_mov_b32_e32 v1, v247
	v_mov_b32_e32 v2, s2
	s_add_i32 s2, s39, 0xffb0
	v_mov_b32_e32 v3, s3
	s_and_b32 s3, s2, 0xff
	s_mulk_i32 s3, 0x75
	s_lshr_b32 s4, s3, 8
	s_sub_i32 s4, s2, s4
	s_bfe_u32 s3, s3, 0x80008
	s_bfe_u32 s4, s4, 0x70001
	s_add_i32 s4, s4, s3
	s_bfe_u32 s6, s4, 0x50003
	s_mul_i32 s3, s6, 11
	s_sub_i32 s2, s2, s3
	global_load_dwordx2 v[2:3], v[2:3], off offset:208
	s_lshl_b32 s2, s2, 2
	s_and_b32 s7, s2, 0xfc
	s_waitcnt vmcnt(0) lgkmcnt(0)
	s_lshl_b32 s4, s7, 8
	v_readfirstlane_b32 s2, v2
	v_readfirstlane_b32 s3, v3
	v_ashrrev_i32_e32 v4, 3, v1
	v_lshlrev_b32_e32 v5, 3, v1
	v_mov_b32_e32 v2, s2
	v_mov_b32_e32 v3, s3
	v_and_b32_e32 v40, 56, v5
	v_lshl_add_u32 v5, s6, 6, v4
	v_mad_i64_i32 v[2:3], s[2:3], v5, s61, v[2:3]
	v_lshlrev_b32_e32 v34, 2, v40
	v_lshl_add_u64 v[2:3], v[2:3], 0, v[34:35]
	v_lshl_add_u64 v[2:3], v[2:3], 0, s[4:5]
	global_load_dwordx4 v[6:9], v[2:3], off
	global_load_dwordx4 v[10:13], v[2:3], off offset:16
	global_load_dwordx4 v[14:17], v[2:3], off offset:256
	global_load_dwordx4 v[18:21], v[2:3], off offset:272
	global_load_dwordx4 v[22:25], v[2:3], off offset:512
	global_load_dwordx4 v[26:29], v[2:3], off offset:528
	global_load_dwordx4 v[30:33], v[2:3], off offset:768
	global_load_dwordx4 v[36:39], v[2:3], off offset:784
	s_lshl_b32 s2, s6, 7
	s_lshl_b32 s4, s7, 6
	v_mul_lo_u32 v2, v4, s58
	s_add_u32 s2, s43, s2
	v_lshlrev_b32_e32 v3, 8, v4
	v_add_u32_e32 v2, 16, v2
	s_addc_u32 s3, s44, 0
	v_bfe_u32 v5, v1, 3, 7
	v_add_u32_e32 v1, s4, v4
	v_mul_u32_u24_e32 v41, 0x104, v40
	v_add_u32_e32 v42, v2, v34
	v_sub_u32_e32 v43, v2, v3
	v_lshlrev_b32_e32 v34, 1, v40
	v_cmp_gt_u32_e32 vcc, s62, v1
	v_add_u32_e32 v40, 0x4100, v42
	v_add_u32_e32 v44, 0x4108, v42
	v_add_u32_e32 v45, 0x4110, v42
	v_add_u32_e32 v46, 0x4118, v42
	v_add_u32_e32 v47, 0x8200, v42
	v_add_u32_e32 v48, 0x8208, v42
	v_add_u32_e32 v49, 0x8210, v42
	v_add_u32_e32 v50, 0x8218, v42
	v_add_u32_e32 v51, 0xc300, v42
	v_add_u32_e32 v52, 0xc308, v42
	v_add_u32_e32 v53, 0xc310, v42
	v_add_u32_e32 v54, 0xc318, v42
	v_lshl_add_u64 v[2:3], s[2:3], 0, v[34:35]
	s_waitcnt vmcnt(0) lgkmcnt(0)
	ds_write2_b32 v42, v6, v7 offset1:1
	ds_write2_b32 v42, v8, v9 offset0:2 offset1:3
	ds_write2_b32 v42, v10, v11 offset0:4 offset1:5
	ds_write2_b32 v42, v12, v13 offset0:6 offset1:7
	ds_write2_b32 v40, v14, v15 offset1:1
	ds_write2_b32 v44, v16, v17 offset1:1
	ds_write2_b32 v45, v18, v19 offset1:1
	ds_write2_b32 v46, v20, v21 offset1:1
	ds_write2_b32 v47, v22, v23 offset1:1
	ds_write2_b32 v48, v24, v25 offset1:1
	ds_write2_b32 v49, v26, v27 offset1:1
	ds_write2_b32 v50, v28, v29 offset1:1
	ds_write2_b32 v51, v30, v31 offset1:1
	ds_write2_b32 v52, v32, v33 offset1:1
	ds_write2_b32 v53, v36, v37 offset1:1
	ds_write2_b32 v54, v38, v39 offset1:1
	v_add_u32_e32 v6, v43, v41
	s_waitcnt lgkmcnt(0)
	s_barrier
	s_and_saveexec_b64 s[2:3], vcc
	s_cbranch_execz .LBB0_67
	v_add_u32_e32 v10, 0x400, v6
	ds_read2_b32 v[8:9], v10 offset0:134 offset1:199
	ds_read2_b32 v[12:13], v10 offset0:4 offset1:69
	ds_read2_b32 v[14:15], v6 offset0:130 offset1:195
	ds_read2_b32 v[16:17], v6 offset1:65
	v_lshlrev_b32_e32 v7, 1, v1
	v_and_or_b32 v7, v7, s63, v5
	v_lshlrev_b32_e32 v34, 11, v7
	s_waitcnt lgkmcnt(3)
	v_cvt_pk_bf16_f32 v11, v8, v9
	s_waitcnt lgkmcnt(2)
	v_cvt_pk_bf16_f32 v10, v12, v13
	s_waitcnt lgkmcnt(1)
	v_cvt_pk_bf16_f32 v9, v14, v15
	s_waitcnt lgkmcnt(0)
	v_cvt_pk_bf16_f32 v8, v16, v17
	v_lshl_add_u64 v[12:13], v[2:3], 0, v[34:35]
	global_store_dwordx4 v[12:13], v[8:11], off
.LBB0_67:
	s_or_b64 exec, exec, s[2:3]
	v_add3_u32 v4, v4, s4, 64
	v_cmp_gt_u32_e32 vcc, s62, v4
	s_and_saveexec_b64 s[2:3], vcc
	s_cbranch_execz .LBB0_69
	v_add_u32_e32 v10, 0x4400, v6
	ds_read2_b32 v[12:13], v10 offset0:68 offset1:133
	v_add_u32_e32 v10, 0x4200, v6
	v_add_u32_e32 v8, 0x4600, v6
	ds_read2_b32 v[14:15], v10 offset0:66 offset1:131
	v_add_u32_e32 v10, 0x4000, v6
	ds_read2_b32 v[8:9], v8 offset0:70 offset1:135
	ds_read2_b32 v[16:17], v10 offset0:64 offset1:129
	v_lshlrev_b32_e32 v7, 1, v4
	v_and_b32_e32 v4, 0x7f, v4
	v_and_or_b32 v4, v7, s63, v4
	v_lshlrev_b32_e32 v34, 11, v4
	s_waitcnt lgkmcnt(0)
	v_cvt_pk_bf16_f32 v11, v8, v9
	v_cvt_pk_bf16_f32 v10, v12, v13
	v_cvt_pk_bf16_f32 v9, v14, v15
	v_cvt_pk_bf16_f32 v8, v16, v17
	v_lshl_add_u64 v[12:13], v[2:3], 0, v[34:35]
	global_store_dwordx4 v[12:13], v[8:11], off
.LBB0_69:
	s_or_b64 exec, exec, s[2:3]
	v_add_u32_e32 v4, 0x80, v1
	v_cmp_gt_u32_e32 vcc, s62, v4
	s_and_saveexec_b64 s[2:3], vcc
	s_cbranch_execz .LBB0_71
	v_add_u32_e32 v7, 0x8800, v6
	ds_read2_b32 v[8:9], v7 offset0:6 offset1:71
	v_add_u32_e32 v7, 0x8400, v6
	ds_read2_b32 v[12:13], v7 offset0:132 offset1:197
	ds_read2_b32 v[14:15], v7 offset0:2 offset1:67
	v_add_u32_e32 v7, 0x8000, v6
	ds_read2_b32 v[16:17], v7 offset0:128 offset1:193
	v_lshlrev_b32_e32 v4, 1, v4
	v_and_or_b32 v4, v4, s63, v5
	v_lshlrev_b32_e32 v34, 11, v4
	s_waitcnt lgkmcnt(0)
	v_cvt_pk_bf16_f32 v11, v8, v9
	v_cvt_pk_bf16_f32 v10, v12, v13
	v_cvt_pk_bf16_f32 v9, v14, v15
	v_cvt_pk_bf16_f32 v8, v16, v17
	v_lshl_add_u64 v[4:5], v[2:3], 0, v[34:35]
	global_store_dwordx4 v[4:5], v[8:11], off
.LBB0_71:
	s_or_b64 exec, exec, s[2:3]
	v_add_u32_e32 v1, 0xc0, v1
	v_cmp_gt_u32_e32 vcc, s62, v1
	s_and_saveexec_b64 s[2:3], vcc
	s_cbranch_execz .LBB0_73
	v_add_u32_e32 v4, 0xc800, v6
	v_add_u32_e32 v8, 0xc600, v6
	v_add_u32_e32 v10, 0xc400, v6
	v_add_u32_e32 v6, 0xc200, v6
	ds_read2_b32 v[4:5], v4 offset0:70 offset1:135
	ds_read2_b32 v[8:9], v8 offset0:68 offset1:133
	ds_read2_b32 v[10:11], v10 offset0:66 offset1:131
	ds_read2_b32 v[12:13], v6 offset0:64 offset1:129
	v_lshlrev_b32_e32 v7, 1, v1
	v_and_b32_e32 v1, 0x7f, v1
	v_and_or_b32 v1, v7, s63, v1
	v_lshlrev_b32_e32 v34, 11, v1
	s_waitcnt lgkmcnt(0)
	v_cvt_pk_bf16_f32 v7, v4, v5
	v_cvt_pk_bf16_f32 v6, v8, v9
	v_cvt_pk_bf16_f32 v5, v10, v11
	v_cvt_pk_bf16_f32 v4, v12, v13
	v_lshl_add_u64 v[2:3], v[2:3], 0, v[34:35]
	global_store_dwordx4 v[2:3], v[4:7], off

.LBB0_75:
	s_andn2_b64 vcc, exec, s[2:3]
	s_cbranch_vccnz .LBB0_85
	v_readlane_b32 s2, v253, 2
	v_readlane_b32 s3, v253, 3
	v_mov_b32_e32 v4, v247
	v_mov_b32_e32 v1, s2
	v_mov_b32_e32 v2, s3
	s_and_b32 s6, s53, 0x300
	v_readfirstlane_b32 s2, v1
	v_readfirstlane_b32 s3, v2
	s_lshl_b32 s4, s6, 2
	v_mov_b32_e32 v2, s2
	v_mov_b32_e32 v3, s3
	global_load_dwordx2 v[2:3], v[2:3], off offset:192
	s_and_b32 s2, s55, 0x7fc0
	s_addk_i32 s2, 0xbf00
	s_mov_b32 s3, s5
	s_waitcnt vmcnt(0) lgkmcnt(0)
	v_mov_b32_e32 v1, v2
	s_nop 0
	v_readfirstlane_b32 s8, v1
	v_ashrrev_i32_e32 v1, 3, v4
	v_lshlrev_b32_e32 v2, 3, v4
	v_and_b32_e32 v5, 56, v2
	v_add_u32_e32 v2, s2, v1
	v_readfirstlane_b32 s9, v3
	v_ashrrev_i32_e32 v3, 31, v2
	v_lshlrev_b64 v[2:3], 12, v[2:3]
	v_lshlrev_b32_e32 v34, 2, v5
	v_lshl_add_u64 v[2:3], s[8:9], 0, v[2:3]
	v_lshl_add_u64 v[2:3], v[2:3], 0, v[34:35]
	v_lshl_add_u64 v[2:3], v[2:3], 0, s[4:5]
	global_load_dwordx4 v[6:9], v[2:3], off
	global_load_dwordx4 v[10:13], v[2:3], off offset:16
	global_load_dwordx4 v[14:17], v[2:3], off offset:256
	global_load_dwordx4 v[18:21], v[2:3], off offset:272
	global_load_dwordx4 v[22:25], v[2:3], off offset:512
	global_load_dwordx4 v[26:29], v[2:3], off offset:528
	global_load_dwordx4 v[30:33], v[2:3], off offset:768
	global_load_dwordx4 v[36:39], v[2:3], off offset:784
	s_lshl_b64 s[2:3], s[2:3], 1
	v_mul_lo_u32 v2, v1, s58
	s_add_u32 s2, s45, s2
	v_lshlrev_b32_e32 v3, 8, v1
	v_add_u32_e32 v2, 16, v2
	s_addc_u32 s3, s46, s3
	v_add_u32_e32 v4, s6, v1
	v_mul_u32_u24_e32 v40, 0x104, v5
	v_add_u32_e32 v41, v2, v34
	v_sub_u32_e32 v42, v2, v3
	v_lshlrev_b32_e32 v34, 1, v5
	v_cmp_gt_u32_e32 vcc, s59, v4
	v_lshl_add_u64 v[2:3], s[2:3], 0, v[34:35]
	v_add_u32_e32 v5, v42, v40
	v_add_u32_e32 v43, 0x4100, v41
	v_add_u32_e32 v44, 0x4108, v41
	v_add_u32_e32 v45, 0x4110, v41
	v_add_u32_e32 v46, 0x4118, v41
	v_add_u32_e32 v47, 0x8200, v41
	v_add_u32_e32 v48, 0x8208, v41
	v_add_u32_e32 v49, 0x8210, v41
	v_add_u32_e32 v50, 0x8218, v41
	v_add_u32_e32 v51, 0xc300, v41
	v_add_u32_e32 v52, 0xc308, v41
	v_add_u32_e32 v53, 0xc310, v41
	v_add_u32_e32 v54, 0xc318, v41
	s_waitcnt vmcnt(0) lgkmcnt(0)
	ds_write2_b32 v41, v6, v7 offset1:1
	ds_write2_b32 v41, v8, v9 offset0:2 offset1:3
	ds_write2_b32 v41, v10, v11 offset0:4 offset1:5
	ds_write2_b32 v41, v12, v13 offset0:6 offset1:7
	ds_write2_b32 v43, v14, v15 offset1:1
	ds_write2_b32 v44, v16, v17 offset1:1
	ds_write2_b32 v45, v18, v19 offset1:1
	ds_write2_b32 v46, v20, v21 offset1:1
	ds_write2_b32 v47, v22, v23 offset1:1
	ds_write2_b32 v48, v24, v25 offset1:1
	ds_write2_b32 v49, v26, v27 offset1:1
	ds_write2_b32 v50, v28, v29 offset1:1
	ds_write2_b32 v51, v30, v31 offset1:1
	ds_write2_b32 v52, v32, v33 offset1:1
	ds_write2_b32 v53, v36, v37 offset1:1
	ds_write2_b32 v54, v38, v39 offset1:1
	s_waitcnt lgkmcnt(0)
	s_barrier
	s_and_saveexec_b64 s[2:3], vcc
	s_cbranch_execz .LBB0_78
	v_add_u32_e32 v8, 0x400, v5
	ds_read2_b32 v[6:7], v8 offset0:134 offset1:199
	ds_read2_b32 v[10:11], v8 offset0:4 offset1:69
	ds_read2_b32 v[12:13], v5 offset0:130 offset1:195
	ds_read2_b32 v[14:15], v5 offset1:65
	v_lshlrev_b32_e32 v34, 11, v4
	s_waitcnt lgkmcnt(3)
	v_cvt_pk_bf16_f32 v9, v6, v7
	s_waitcnt lgkmcnt(2)
	v_cvt_pk_bf16_f32 v8, v10, v11
	s_waitcnt lgkmcnt(1)
	v_cvt_pk_bf16_f32 v7, v12, v13
	s_waitcnt lgkmcnt(0)
	v_cvt_pk_bf16_f32 v6, v14, v15
	v_lshl_add_u64 v[10:11], v[2:3], 0, v[34:35]
	global_store_dwordx4 v[10:11], v[6:9], off
.LBB0_78:
	s_or_b64 exec, exec, s[2:3]
	v_add3_u32 v1, v1, s6, 64
	v_cmp_gt_u32_e32 vcc, s59, v1
	s_and_saveexec_b64 s[2:3], vcc
	s_cbranch_execz .LBB0_80
	v_add_u32_e32 v8, 0x4400, v5
	ds_read2_b32 v[10:11], v8 offset0:68 offset1:133
	v_add_u32_e32 v8, 0x4200, v5
	v_add_u32_e32 v6, 0x4600, v5
	ds_read2_b32 v[12:13], v8 offset0:66 offset1:131
	v_add_u32_e32 v8, 0x4000, v5
	ds_read2_b32 v[6:7], v6 offset0:70 offset1:135
	ds_read2_b32 v[14:15], v8 offset0:64 offset1:129
	v_lshlrev_b32_e32 v34, 11, v1
	s_waitcnt lgkmcnt(0)
	v_cvt_pk_bf16_f32 v8, v10, v11
	v_lshl_add_u64 v[10:11], v[2:3], 0, v[34:35]
	v_cvt_pk_bf16_f32 v9, v6, v7
	v_cvt_pk_bf16_f32 v7, v12, v13
	v_cvt_pk_bf16_f32 v6, v14, v15
	global_store_dwordx4 v[10:11], v[6:9], off
.LBB0_80:
	s_or_b64 exec, exec, s[2:3]
	v_add_u32_e32 v1, 0x80, v4
	v_cmp_gt_u32_e32 vcc, s59, v1
	s_and_saveexec_b64 s[2:3], vcc
	s_cbranch_execz .LBB0_82
	v_add_u32_e32 v6, 0x8800, v5
	v_add_u32_e32 v8, 0x8400, v5
	ds_read2_b32 v[6:7], v6 offset0:6 offset1:71
	ds_read2_b32 v[10:11], v8 offset0:132 offset1:197
	ds_read2_b32 v[12:13], v8 offset0:2 offset1:67
	v_add_u32_e32 v8, 0x8000, v5
	ds_read2_b32 v[14:15], v8 offset0:128 offset1:193
	v_lshlrev_b32_e32 v34, 11, v1
	s_waitcnt lgkmcnt(0)
	v_cvt_pk_bf16_f32 v9, v6, v7
	v_cvt_pk_bf16_f32 v8, v10, v11
	v_cvt_pk_bf16_f32 v7, v12, v13
	v_cvt_pk_bf16_f32 v6, v14, v15
	v_lshl_add_u64 v[10:11], v[2:3], 0, v[34:35]
	global_store_dwordx4 v[10:11], v[6:9], off
.LBB0_82:
	s_or_b64 exec, exec, s[2:3]
	v_add_u32_e32 v1, 0xc0, v4
	v_cmp_gt_u32_e32 vcc, s59, v1
	s_and_saveexec_b64 s[2:3], vcc
	s_cbranch_execz .LBB0_84
	v_add_u32_e32 v4, 0xc800, v5
	ds_read2_b32 v[6:7], v4 offset0:70 offset1:135
	v_add_u32_e32 v4, 0xc600, v5
	ds_read2_b32 v[8:9], v4 offset0:68 offset1:133
	v_add_u32_e32 v4, 0xc400, v5
	ds_read2_b32 v[10:11], v4 offset0:66 offset1:131
	v_add_u32_e32 v4, 0xc200, v5
	ds_read2_b32 v[12:13], v4 offset0:64 offset1:129
	v_lshlrev_b32_e32 v34, 11, v1
	s_waitcnt lgkmcnt(0)
	v_cvt_pk_bf16_f32 v7, v6, v7
	v_cvt_pk_bf16_f32 v6, v8, v9
	v_cvt_pk_bf16_f32 v5, v10, v11
	v_cvt_pk_bf16_f32 v4, v12, v13
	v_lshl_add_u64 v[2:3], v[2:3], 0, v[34:35]
	global_store_dwordx4 v[2:3], v[4:7], off

.LBB0_86:
	s_andn2_b64 vcc, exec, s[2:3]
	s_cbranch_vccnz .LBB0_96
	v_readlane_b32 s2, v253, 2
	v_readlane_b32 s3, v253, 3
	v_mov_b32_e32 v4, v247
	v_mov_b32_e32 v1, s2
	v_mov_b32_e32 v2, s3
	s_nop 0
	v_readfirstlane_b32 s2, v1
	v_readfirstlane_b32 s3, v2
	s_nop 0
	v_mov_b32_e32 v2, s2
	v_mov_b32_e32 v3, s3
	global_load_dwordx2 v[2:3], v[2:3], off offset:184
	s_add_i32 s2, s39, 0xfffffc30
	s_lshr_b32 s4, s2, 4
	s_lshl_b64 s[2:3], s[4:5], 20
	s_waitcnt vmcnt(0) lgkmcnt(0)
	v_mov_b32_e32 v1, v3
	s_nop 0
	v_readfirstlane_b32 s6, v2
	v_readfirstlane_b32 s7, v1
	s_add_u32 s2, s6, s2
	s_addc_u32 s3, s7, s3
	s_and_b32 s6, s53, 0x300
	s_lshl_b64 s[8:9], s[4:5], 9
	s_add_u32 s7, s47, s8
	v_ashrrev_i32_e32 v1, 3, v4
	v_lshlrev_b32_e32 v2, 3, v4
	s_addc_u32 s8, s48, s9
	s_and_b32 s9, s55, 0xc0
	v_and_b32_e32 v5, 56, v2
	v_add_u32_e32 v2, s9, v1
	v_ashrrev_i32_e32 v3, 31, v2
	v_lshlrev_b64 v[2:3], 12, v[2:3]
	v_lshlrev_b32_e32 v34, 2, v5
	v_lshl_add_u64 v[2:3], s[2:3], 0, v[2:3]
	s_lshl_b32 s4, s6, 2
	v_lshl_add_u64 v[2:3], v[2:3], 0, v[34:35]
	v_lshl_add_u64 v[2:3], v[2:3], 0, s[4:5]
	global_load_dwordx4 v[6:9], v[2:3], off
	global_load_dwordx4 v[10:13], v[2:3], off offset:16
	global_load_dwordx4 v[14:17], v[2:3], off offset:256
	global_load_dwordx4 v[18:21], v[2:3], off offset:272
	global_load_dwordx4 v[22:25], v[2:3], off offset:512
	global_load_dwordx4 v[26:29], v[2:3], off offset:528
	global_load_dwordx4 v[30:33], v[2:3], off offset:768
	global_load_dwordx4 v[36:39], v[2:3], off offset:784
	v_mul_lo_u32 v2, v1, s58
	s_lshl_b32 s2, s9, 1
	v_lshlrev_b32_e32 v3, 8, v1
	v_add_u32_e32 v2, 16, v2
	s_add_u32 s2, s7, s2
	v_mul_u32_u24_e32 v40, 0x104, v5
	v_add_u32_e32 v41, v2, v34
	v_sub_u32_e32 v42, v2, v3
	v_add_u32_e32 v4, s6, v1
	s_addc_u32 s3, s8, 0
	v_lshlrev_b32_e32 v34, 1, v5
	v_cmp_gt_u32_e32 vcc, s59, v4
	v_lshl_add_u64 v[2:3], s[2:3], 0, v[34:35]
	v_add_u32_e32 v5, v42, v40
	v_add_u32_e32 v43, 0x4100, v41
	v_add_u32_e32 v44, 0x4108, v41
	v_add_u32_e32 v45, 0x4110, v41
	v_add_u32_e32 v46, 0x4118, v41
	v_add_u32_e32 v47, 0x8200, v41
	v_add_u32_e32 v48, 0x8208, v41
	v_add_u32_e32 v49, 0x8210, v41
	v_add_u32_e32 v50, 0x8218, v41
	v_add_u32_e32 v51, 0xc300, v41
	v_add_u32_e32 v52, 0xc308, v41
	v_add_u32_e32 v53, 0xc310, v41
	v_add_u32_e32 v54, 0xc318, v41
	s_waitcnt vmcnt(0) lgkmcnt(0)
	ds_write2_b32 v41, v6, v7 offset1:1
	ds_write2_b32 v41, v8, v9 offset0:2 offset1:3
	ds_write2_b32 v41, v10, v11 offset0:4 offset1:5
	ds_write2_b32 v41, v12, v13 offset0:6 offset1:7
	ds_write2_b32 v43, v14, v15 offset1:1
	ds_write2_b32 v44, v16, v17 offset1:1
	ds_write2_b32 v45, v18, v19 offset1:1
	ds_write2_b32 v46, v20, v21 offset1:1
	ds_write2_b32 v47, v22, v23 offset1:1
	ds_write2_b32 v48, v24, v25 offset1:1
	ds_write2_b32 v49, v26, v27 offset1:1
	ds_write2_b32 v50, v28, v29 offset1:1
	ds_write2_b32 v51, v30, v31 offset1:1
	ds_write2_b32 v52, v32, v33 offset1:1
	ds_write2_b32 v53, v36, v37 offset1:1
	ds_write2_b32 v54, v38, v39 offset1:1
	s_waitcnt lgkmcnt(0)
	s_barrier
	s_and_saveexec_b64 s[2:3], vcc
	s_cbranch_execz .LBB0_89
	v_add_u32_e32 v8, 0x400, v5
	ds_read2_b32 v[6:7], v8 offset0:134 offset1:199
	ds_read2_b32 v[10:11], v8 offset0:4 offset1:69
	ds_read2_b32 v[12:13], v5 offset0:130 offset1:195
	ds_read2_b32 v[14:15], v5 offset1:65
	v_lshlrev_b32_e32 v34, 11, v4
	s_waitcnt lgkmcnt(3)
	v_cvt_pk_bf16_f32 v9, v6, v7
	s_waitcnt lgkmcnt(2)
	v_cvt_pk_bf16_f32 v8, v10, v11
	s_waitcnt lgkmcnt(1)
	v_cvt_pk_bf16_f32 v7, v12, v13
	s_waitcnt lgkmcnt(0)
	v_cvt_pk_bf16_f32 v6, v14, v15
	v_lshl_add_u64 v[10:11], v[2:3], 0, v[34:35]
	global_store_dwordx4 v[10:11], v[6:9], off

.LBB0_97:
	s_andn2_b64 vcc, exec, s[2:3]
	s_cbranch_vccnz .LBB0_311
	v_readlane_b32 s2, v253, 2
	v_readlane_b32 s3, v253, 3
	v_mov_b32_e32 v6, 0
	v_mov_b32_e32 v1, s2
	v_mov_b32_e32 v2, s3
	v_mov_b32_e32 v7, 0
	v_readfirstlane_b32 s2, v1
	v_readfirstlane_b32 s3, v2
	v_mov_b32_e32 v8, 0
	v_mov_b32_e32 v2, s2
	v_mov_b32_e32 v3, s3
	global_load_dwordx2 v[4:5], v[2:3], off offset:88
	s_add_i32 s2, s39, 0xfdf0
	s_bfe_u32 s3, s2, 0xe0002
	s_mulk_i32 s3, 0x4925
	s_lshr_b32 s3, s3, 17
	v_mov_b32_e32 v3, v247
	s_mul_i32 s4, s3, 28
	s_sub_i32 s6, s2, s4
	s_lshl_b32 s9, s3, 6
	s_lshl_b32 s2, s6, 2
	s_and_b32 s10, s2, 0xfffc
	s_lshl_b32 s8, s10, 6
	v_mov_b32_e32 v2, 0
	v_mov_b32_e32 v9, 0
	v_mov_b32_e32 v10, 0
	v_mov_b32_e32 v11, 0
	v_mov_b32_e32 v12, 0
	v_mov_b32_e32 v13, 0
	s_waitcnt vmcnt(0) lgkmcnt(0)
	v_mov_b32_e32 v1, v5
	s_nop 0
	v_readfirstlane_b32 s3, v1
	v_ashrrev_i32_e32 v1, 3, v3
	v_lshlrev_b32_e32 v3, 3, v3
	v_readfirstlane_b32 s2, v4
	v_and_b32_e32 v38, 56, v3
	v_mov_b32_e32 v5, s3
	v_mov_b32_e32 v4, s2
	v_add_u32_e32 v3, s9, v1
	v_add_u32_e32 v19, 8, v38
	v_mad_i64_i32 v[4:5], s[2:3], v3, s64, v[4:5]
	v_lshlrev_b32_e32 v34, 2, v38
	v_or_b32_e32 v3, s8, v19
	v_lshl_add_u64 v[36:37], v[4:5], 0, v[34:35]
	v_cmp_gt_u32_e32 vcc, s65, v3
	s_and_saveexec_b64 s[2:3], vcc
	s_cbranch_execz .LBB0_100
	s_lshl_b32 s4, s8, 2
	v_lshl_add_u64 v[4:5], v[36:37], 0, s[4:5]
	global_load_dwordx4 v[6:9], v[4:5], off
	global_load_dwordx4 v[10:13], v[4:5], off offset:16
.LBB0_100:
	s_or_b64 exec, exec, s[2:3]
	s_or_b32 s83, s10, 1
	s_lshl_b32 s84, s83, 6
	s_and_b32 s4, 0xffff, s6
	s_cmp_gt_u32 s4, 26
	s_cselect_b64 s[2:3], -1, 0
	s_cmp_lt_u32 s4, 27
	v_add_u32_e32 v3, s84, v19
	s_cselect_b64 s[6:7], -1, 0
	v_cmp_gt_u32_e32 vcc, s65, v3
	s_and_b64 s[16:17], s[6:7], vcc
	v_mov_b32_e32 v3, 0
	v_mov_b32_e32 v4, 0
	v_mov_b32_e32 v5, 0
	v_mov_b32_e32 v14, 0
	v_mov_b32_e32 v15, 0
	v_mov_b32_e32 v16, 0
	v_mov_b32_e32 v17, 0
	s_and_saveexec_b64 s[6:7], s[16:17]
	s_cbranch_execz .LBB0_102
	s_lshl_b32 s4, s84, 2
	v_lshl_add_u64 v[14:15], v[36:37], 0, s[4:5]
	global_load_dwordx4 v[2:5], v[14:15], off
	s_nop 0
	global_load_dwordx4 v[14:17], v[14:15], off offset:16
.LBB0_102:
	s_or_b64 exec, exec, s[6:7]
	s_or_b32 s81, s10, 2
	s_lshl_b32 s82, s81, 6
	v_or_b32_e32 v18, s82, v19
	v_cmp_gt_u32_e32 vcc, s65, v18
	s_xor_b64 s[2:3], s[2:3], -1
	s_and_b64 s[6:7], s[2:3], vcc
	v_mov_b32_e32 v18, 0
	v_mov_b32_e32 v22, 0
	v_mov_b32_e32 v23, 0
	v_mov_b32_e32 v24, 0
	v_mov_b32_e32 v25, 0
	v_mov_b32_e32 v26, 0
	v_mov_b32_e32 v27, 0
	v_mov_b32_e32 v28, 0
	v_mov_b32_e32 v29, 0
	s_and_saveexec_b64 s[2:3], s[6:7]
	s_cbranch_execz .LBB0_104
	s_lshl_b32 s4, s82, 2
	v_lshl_add_u64 v[20:21], v[36:37], 0, s[4:5]
	global_load_dwordx4 v[22:25], v[20:21], off
	global_load_dwordx4 v[26:29], v[20:21], off offset:16
.LBB0_104:
	s_or_b64 exec, exec, s[2:3]
	s_or_b32 s79, s10, 3
	s_lshl_b32 s80, s79, 6
	s_cmpk_lt_u32 s79, 0x6d
	v_add_u32_e32 v19, s80, v19
	s_cselect_b64 s[2:3], -1, 0
	v_cmp_gt_u32_e32 vcc, s65, v19
	s_and_b64 s[6:7], s[2:3], vcc
	v_mov_b32_e32 v19, 0
	v_mov_b32_e32 v20, 0
	v_mov_b32_e32 v21, 0
	v_mov_b32_e32 v30, 0
	v_mov_b32_e32 v31, 0
	v_mov_b32_e32 v32, 0
	v_mov_b32_e32 v33, 0
	s_and_saveexec_b64 s[2:3], s[6:7]
	s_cbranch_execz .LBB0_106
	s_lshl_b32 s4, s80, 2
	v_lshl_add_u64 v[30:31], v[36:37], 0, s[4:5]
	global_load_dwordx4 v[18:21], v[30:31], off
	s_nop 0
	global_load_dwordx4 v[30:33], v[30:31], off offset:16

.LBB0_153:
	s_or_b64 exec, exec, s[6:7]
	s_waitcnt lgkmcnt(3)
	v_cvt_pk_bf16_f32 v2, v2, v3
	s_waitcnt lgkmcnt(2)
	v_cvt_pk_bf16_f32 v3, v4, v5
	s_waitcnt lgkmcnt(1)
	v_cvt_pk_bf16_f32 v4, v8, v9
	s_waitcnt lgkmcnt(0)
	v_cvt_pk_bf16_f32 v5, v10, v11
	v_cmp_lt_i32_e32 vcc, -1, v34
	s_and_saveexec_b64 s[6:7], vcc
	s_cbranch_execz .LBB0_155
	v_lshlrev_b64 v[8:9], 11, v[34:35]
	v_lshl_add_u64 v[8:9], v[6:7], 0, v[8:9]
	global_store_dwordx4 v[8:9], v[2:5], off
.LBB0_155:
	s_or_b64 exec, exec, s[6:7]
	v_cmp_lt_i32_e32 vcc, -1, v13
	s_and_b64 exec, exec, vcc
	s_cbranch_execz .LBB0_157
	v_add_u32_e32 v34, 0x1800, v13
	v_lshlrev_b64 v[8:9], 11, v[34:35]
	v_lshl_add_u64 v[8:9], v[6:7], 0, v[8:9]
	global_store_dwordx4 v[8:9], v[2:5], off

.LBB0_204:
	s_or_b64 exec, exec, s[6:7]
	s_waitcnt lgkmcnt(0)
	v_cvt_pk_bf16_f32 v2, v2, v3
	v_cvt_pk_bf16_f32 v3, v4, v5
	v_cvt_pk_bf16_f32 v4, v8, v9
	v_cvt_pk_bf16_f32 v5, v10, v11
	v_cmp_lt_i32_e32 vcc, -1, v34
	s_and_saveexec_b64 s[6:7], vcc
	s_cbranch_execz .LBB0_206
	v_lshlrev_b64 v[8:9], 11, v[34:35]
	v_lshl_add_u64 v[8:9], v[6:7], 0, v[8:9]
	global_store_dwordx4 v[8:9], v[2:5], off

.LBB0_308:
	s_or_b64 exec, exec, s[6:7]
	v_cmp_lt_i32_e32 vcc, -1, v1
	s_and_b64 exec, exec, vcc
	s_cbranch_execz .LBB0_310
	v_add_u32_e32 v34, 0x1800, v1
	v_lshlrev_b64 v[8:9], 11, v[34:35]
	v_lshl_add_u64 v[6:7], v[6:7], 0, v[8:9]
	global_store_dwordx4 v[6:7], v[2:5], off

.LBB0_312:
	s_andn2_b64 vcc, exec, s[2:3]
	s_cbranch_vccnz .LBB0_322
	v_readlane_b32 s2, v253, 2
	v_readlane_b32 s3, v253, 3
	v_mov_b32_e32 v4, v247
	v_mov_b32_e32 v1, s2
	v_mov_b32_e32 v2, s3
	s_and_b32 s6, s53, 0x300
	v_readfirstlane_b32 s2, v1
	v_readfirstlane_b32 s3, v2
	s_lshl_b32 s4, s6, 2
	v_mov_b32_e32 v2, s2
	v_mov_b32_e32 v3, s3
	global_load_dwordx2 v[2:3], v[2:3], off offset:72
	s_and_b32 s2, s55, 0x3fc0
	s_addk_i32 s2, 0xea00
	s_mov_b32 s3, s5
	s_waitcnt vmcnt(0) lgkmcnt(0)
	v_mov_b32_e32 v1, v3
	s_nop 0
	v_readfirstlane_b32 s8, v2
	v_readfirstlane_b32 s9, v1
	v_ashrrev_i32_e32 v1, 3, v4
	v_lshlrev_b32_e32 v2, 3, v4
	v_and_b32_e32 v5, 56, v2
	v_add_u32_e32 v2, s2, v1
	v_ashrrev_i32_e32 v3, 31, v2
	v_lshlrev_b64 v[2:3], 12, v[2:3]
	v_lshlrev_b32_e32 v34, 2, v5
	v_lshl_add_u64 v[2:3], s[8:9], 0, v[2:3]
	v_lshl_add_u64 v[2:3], v[2:3], 0, v[34:35]
	v_lshl_add_u64 v[2:3], v[2:3], 0, s[4:5]
	global_load_dwordx4 v[6:9], v[2:3], off
	global_load_dwordx4 v[10:13], v[2:3], off offset:16
	global_load_dwordx4 v[14:17], v[2:3], off offset:256
	global_load_dwordx4 v[18:21], v[2:3], off offset:272
	global_load_dwordx4 v[22:25], v[2:3], off offset:512
	global_load_dwordx4 v[26:29], v[2:3], off offset:528
	global_load_dwordx4 v[30:33], v[2:3], off offset:768
	global_load_dwordx4 v[36:39], v[2:3], off offset:784
	s_lshl_b64 s[2:3], s[2:3], 1
	v_mul_lo_u32 v2, v1, s58
	s_add_u32 s2, s51, s2
	v_lshlrev_b32_e32 v3, 8, v1
	v_add_u32_e32 v2, 16, v2
	s_addc_u32 s3, s52, s3
	v_add_u32_e32 v4, s6, v1
	v_mul_u32_u24_e32 v40, 0x104, v5
	v_add_u32_e32 v41, v2, v34
	v_sub_u32_e32 v42, v2, v3
	v_lshlrev_b32_e32 v34, 1, v5
	v_cmp_gt_u32_e32 vcc, s59, v4
	v_lshl_add_u64 v[2:3], s[2:3], 0, v[34:35]
	v_add_u32_e32 v5, v42, v40
	v_add_u32_e32 v43, 0x4100, v41
	v_add_u32_e32 v44, 0x4108, v41
	v_add_u32_e32 v45, 0x4110, v41
	v_add_u32_e32 v46, 0x4118, v41
	v_add_u32_e32 v47, 0x8200, v41
	v_add_u32_e32 v48, 0x8208, v41
	v_add_u32_e32 v49, 0x8210, v41
	v_add_u32_e32 v50, 0x8218, v41
	v_add_u32_e32 v51, 0xc300, v41
	v_add_u32_e32 v52, 0xc308, v41
	v_add_u32_e32 v53, 0xc310, v41
	v_add_u32_e32 v54, 0xc318, v41
	s_waitcnt vmcnt(0) lgkmcnt(0)
	ds_write2_b32 v41, v6, v7 offset1:1
	ds_write2_b32 v41, v8, v9 offset0:2 offset1:3
	ds_write2_b32 v41, v10, v11 offset0:4 offset1:5
	ds_write2_b32 v41, v12, v13 offset0:6 offset1:7
	ds_write2_b32 v43, v14, v15 offset1:1
	ds_write2_b32 v44, v16, v17 offset1:1
	ds_write2_b32 v45, v18, v19 offset1:1
	ds_write2_b32 v46, v20, v21 offset1:1
	ds_write2_b32 v47, v22, v23 offset1:1
	ds_write2_b32 v48, v24, v25 offset1:1
	ds_write2_b32 v49, v26, v27 offset1:1
	ds_write2_b32 v50, v28, v29 offset1:1
	ds_write2_b32 v51, v30, v31 offset1:1
	ds_write2_b32 v52, v32, v33 offset1:1
	ds_write2_b32 v53, v36, v37 offset1:1
	ds_write2_b32 v54, v38, v39 offset1:1
	s_waitcnt lgkmcnt(0)
	s_barrier
	s_and_saveexec_b64 s[2:3], vcc
	s_cbranch_execz .LBB0_315
	v_add_u32_e32 v8, 0x400, v5
	ds_read2_b32 v[6:7], v8 offset0:134 offset1:199
	ds_read2_b32 v[10:11], v8 offset0:4 offset1:69
	ds_read2_b32 v[12:13], v5 offset0:130 offset1:195
	ds_read2_b32 v[14:15], v5 offset1:65
	v_mul_lo_u32 v34, v4, s60
	s_waitcnt lgkmcnt(3)
	v_cvt_pk_bf16_f32 v9, v6, v7
	s_waitcnt lgkmcnt(2)
	v_cvt_pk_bf16_f32 v8, v10, v11
	s_waitcnt lgkmcnt(1)
	v_cvt_pk_bf16_f32 v7, v12, v13
	s_waitcnt lgkmcnt(0)
	v_cvt_pk_bf16_f32 v6, v14, v15
	v_lshl_add_u64 v[10:11], v[2:3], 0, v[34:35]
	global_store_dwordx4 v[10:11], v[6:9], off

.LBB0_323:
	s_andn2_b64 vcc, exec, s[2:3]
	s_cbranch_vccnz .LBB0_333
	v_readlane_b32 s2, v253, 2
	v_readlane_b32 s3, v253, 3
	s_nop 0
	v_mov_b32_e32 v1, s2
	v_mov_b32_e32 v2, s3
	s_nop 0
	v_readfirstlane_b32 s2, v1
	v_readfirstlane_b32 s3, v2
	v_mov_b32_e32 v1, v247
	v_mov_b32_e32 v2, s2
	s_add_i32 s2, s39, 0x50
	v_mov_b32_e32 v3, s3
	s_and_b32 s3, s2, 0xff
	s_mulk_i32 s3, 0x75
	s_lshr_b32 s4, s3, 8
	s_sub_i32 s4, s2, s4
	s_bfe_u32 s3, s3, 0x80008
	s_bfe_u32 s4, s4, 0x70001
	s_add_i32 s4, s4, s3
	s_bfe_u32 s6, s4, 0x50003
	s_mul_i32 s3, s6, 11
	s_sub_i32 s2, s2, s3
	global_load_dwordx2 v[2:3], v[2:3], off offset:64
	s_lshl_b32 s2, s2, 2
	s_and_b32 s7, s2, 0xfc
	s_waitcnt vmcnt(0) lgkmcnt(0)
	s_lshl_b32 s4, s7, 8
	v_readfirstlane_b32 s2, v2
	v_readfirstlane_b32 s3, v3
	v_ashrrev_i32_e32 v4, 3, v1
	v_lshlrev_b32_e32 v5, 3, v1
	v_mov_b32_e32 v2, s2
	v_mov_b32_e32 v3, s3
	v_and_b32_e32 v40, 56, v5
	v_lshl_add_u32 v5, s6, 6, v4
	v_mad_i64_i32 v[2:3], s[2:3], v5, s61, v[2:3]
	v_lshlrev_b32_e32 v34, 2, v40
	v_lshl_add_u64 v[2:3], v[2:3], 0, v[34:35]
	v_lshl_add_u64 v[2:3], v[2:3], 0, s[4:5]
	global_load_dwordx4 v[6:9], v[2:3], off
	global_load_dwordx4 v[10:13], v[2:3], off offset:16
	global_load_dwordx4 v[14:17], v[2:3], off offset:256
	global_load_dwordx4 v[18:21], v[2:3], off offset:272
	global_load_dwordx4 v[22:25], v[2:3], off offset:512
	global_load_dwordx4 v[26:29], v[2:3], off offset:528
	global_load_dwordx4 v[30:33], v[2:3], off offset:768
	global_load_dwordx4 v[36:39], v[2:3], off offset:784
	s_lshl_b32 s2, s6, 7
	s_lshl_b32 s4, s7, 6
	v_mul_lo_u32 v2, v4, s58
	s_add_u32 s2, s38, s2
	v_lshlrev_b32_e32 v3, 8, v4
	v_add_u32_e32 v2, 16, v2
	s_addc_u32 s3, s40, 0
	v_bfe_u32 v5, v1, 3, 7
	v_add_u32_e32 v1, s4, v4
	v_mul_u32_u24_e32 v41, 0x104, v40
	v_add_u32_e32 v42, v2, v34
	v_sub_u32_e32 v43, v2, v3
	v_lshlrev_b32_e32 v34, 1, v40
	v_cmp_gt_u32_e32 vcc, s62, v1
	v_add_u32_e32 v40, 0x4100, v42
	v_add_u32_e32 v44, 0x4108, v42
	v_add_u32_e32 v45, 0x4110, v42
	v_add_u32_e32 v46, 0x4118, v42
	v_add_u32_e32 v47, 0x8200, v42
	v_add_u32_e32 v48, 0x8208, v42
	v_add_u32_e32 v49, 0x8210, v42
	v_add_u32_e32 v50, 0x8218, v42
	v_add_u32_e32 v51, 0xc300, v42
	v_add_u32_e32 v52, 0xc308, v42
	v_add_u32_e32 v53, 0xc310, v42
	v_add_u32_e32 v54, 0xc318, v42
	v_lshl_add_u64 v[2:3], s[2:3], 0, v[34:35]
	s_waitcnt vmcnt(0) lgkmcnt(0)
	ds_write2_b32 v42, v6, v7 offset1:1
	ds_write2_b32 v42, v8, v9 offset0:2 offset1:3
	ds_write2_b32 v42, v10, v11 offset0:4 offset1:5
	ds_write2_b32 v42, v12, v13 offset0:6 offset1:7
	ds_write2_b32 v40, v14, v15 offset1:1
	ds_write2_b32 v44, v16, v17 offset1:1
	ds_write2_b32 v45, v18, v19 offset1:1
	ds_write2_b32 v46, v20, v21 offset1:1
	ds_write2_b32 v47, v22, v23 offset1:1
	ds_write2_b32 v48, v24, v25 offset1:1
	ds_write2_b32 v49, v26, v27 offset1:1
	ds_write2_b32 v50, v28, v29 offset1:1
	ds_write2_b32 v51, v30, v31 offset1:1
	ds_write2_b32 v52, v32, v33 offset1:1
	ds_write2_b32 v53, v36, v37 offset1:1
	ds_write2_b32 v54, v38, v39 offset1:1
	v_add_u32_e32 v6, v43, v41
	s_waitcnt lgkmcnt(0)
	s_barrier
	s_and_saveexec_b64 s[2:3], vcc
	s_cbranch_execz .LBB0_326
	v_add_u32_e32 v10, 0x400, v6
	v_lshlrev_b32_e32 v7, 1, v1
	ds_read2_b32 v[8:9], v10 offset0:134 offset1:199
	ds_read2_b32 v[12:13], v10 offset0:4 offset1:69
	ds_read2_b32 v[14:15], v6 offset0:130 offset1:195
	ds_read2_b32 v[16:17], v6 offset1:65
	v_and_or_b32 v7, v7, s63, v5
	v_lshlrev_b32_e32 v34, 11, v7
	s_waitcnt lgkmcnt(2)
	v_cvt_pk_bf16_f32 v10, v12, v13
	v_lshl_add_u64 v[12:13], v[2:3], 0, v[34:35]
	v_add_co_u32_e32 v12, vcc, 0x40000, v12
	v_cvt_pk_bf16_f32 v11, v8, v9
	s_waitcnt lgkmcnt(1)
	v_cvt_pk_bf16_f32 v9, v14, v15
	s_waitcnt lgkmcnt(0)
	v_cvt_pk_bf16_f32 v8, v16, v17
	v_addc_co_u32_e32 v13, vcc, 0, v13, vcc
	global_store_dwordx4 v[12:13], v[8:11], off

.LBB0_334:
	s_andn2_b64 vcc, exec, s[2:3]
	s_cbranch_vccnz .LBB0_36
	v_readlane_b32 s2, v253, 2
	v_readlane_b32 s3, v253, 3
	s_nop 0
	v_mov_b32_e32 v1, s2
	v_mov_b32_e32 v2, s3
	s_nop 0
	v_readfirstlane_b32 s2, v1
	v_readfirstlane_b32 s3, v2
	v_mov_b32_e32 v1, v247
	v_mov_b32_e32 v2, s2
	s_mul_hi_i32 s2, s39, 0x2e8ba2e9
	v_mov_b32_e32 v3, s3
	s_lshr_b32 s3, s2, 31
	s_ashr_i32 s2, s2, 1
	s_add_i32 s3, s2, s3
	global_load_dwordx2 v[2:3], v[2:3], off offset:56
	s_mul_i32 s4, s3, 0xfffff500
	s_lshl_b32 s2, s3, 6
	s_add_i32 s6, s53, s4
	s_waitcnt vmcnt(0) lgkmcnt(0)
	s_ashr_i32 s7, s6, 31
	v_readfirstlane_b32 s4, v2
	v_readfirstlane_b32 s8, v3
	v_ashrrev_i32_e32 v5, 3, v1
	v_lshlrev_b32_e32 v4, 3, v1
	v_mov_b32_e32 v2, s4
	v_mov_b32_e32 v3, s8
	v_and_b32_e32 v40, 56, v4
	v_add_u32_e32 v4, s2, v5
	v_mad_i64_i32 v[2:3], s[8:9], v4, s61, v[2:3]
	v_lshlrev_b32_e32 v34, 2, v40
	v_lshl_add_u64 v[2:3], v[2:3], 0, v[34:35]
	v_lshl_add_u64 v[2:3], s[6:7], 2, v[2:3]
	global_load_dwordx4 v[6:9], v[2:3], off
	global_load_dwordx4 v[10:13], v[2:3], off offset:16
	global_load_dwordx4 v[14:17], v[2:3], off offset:256
	global_load_dwordx4 v[18:21], v[2:3], off offset:272
	global_load_dwordx4 v[22:25], v[2:3], off offset:512
	global_load_dwordx4 v[26:29], v[2:3], off offset:528
	global_load_dwordx4 v[30:33], v[2:3], off offset:768
	global_load_dwordx4 v[36:39], v[2:3], off offset:784
	s_mul_i32 s4, s3, 0xb00
	s_ashr_i32 s3, s2, 31
	s_lshl_b64 s[2:3], s[2:3], 1
	v_bfe_u32 v4, v1, 3, 7
	v_mul_lo_u32 v1, v5, s58
	s_add_u32 s2, s38, s2
	v_lshlrev_b32_e32 v2, 8, v5
	v_subrev_u32_e32 v3, s4, v5
	v_add_u32_e32 v5, 16, v1
	s_addc_u32 s3, s40, s3
	v_mul_u32_u24_e32 v41, 0x104, v40
	v_add_u32_e32 v1, s53, v3
	v_add_u32_e32 v42, v5, v34
	v_sub_u32_e32 v5, v5, v2
	v_lshlrev_b32_e32 v34, 1, v40
	v_cmp_gt_u32_e32 vcc, s62, v1
	v_lshl_add_u64 v[2:3], s[2:3], 0, v[34:35]
	v_add_u32_e32 v5, v5, v41
	v_add_u32_e32 v40, 0x4100, v42
	v_add_u32_e32 v43, 0x4108, v42
	v_add_u32_e32 v44, 0x4110, v42
	v_add_u32_e32 v45, 0x4118, v42
	v_add_u32_e32 v46, 0x8200, v42
	v_add_u32_e32 v47, 0x8208, v42
	v_add_u32_e32 v48, 0x8210, v42
	v_add_u32_e32 v49, 0x8218, v42
	v_add_u32_e32 v50, 0xc300, v42
	v_add_u32_e32 v51, 0xc308, v42
	v_add_u32_e32 v52, 0xc310, v42
	v_add_u32_e32 v53, 0xc318, v42
	s_waitcnt vmcnt(0) lgkmcnt(0)
	ds_write2_b32 v42, v6, v7 offset1:1
	ds_write2_b32 v42, v8, v9 offset0:2 offset1:3
	ds_write2_b32 v42, v10, v11 offset0:4 offset1:5
	ds_write2_b32 v42, v12, v13 offset0:6 offset1:7
	ds_write2_b32 v40, v14, v15 offset1:1
	ds_write2_b32 v43, v16, v17 offset1:1
	ds_write2_b32 v44, v18, v19 offset1:1
	ds_write2_b32 v45, v20, v21 offset1:1
	ds_write2_b32 v46, v22, v23 offset1:1
	ds_write2_b32 v47, v24, v25 offset1:1
	ds_write2_b32 v48, v26, v27 offset1:1
	ds_write2_b32 v49, v28, v29 offset1:1
	ds_write2_b32 v50, v30, v31 offset1:1
	ds_write2_b32 v51, v32, v33 offset1:1
	ds_write2_b32 v52, v36, v37 offset1:1
	ds_write2_b32 v53, v38, v39 offset1:1
	s_waitcnt lgkmcnt(0)
	s_barrier
	s_and_saveexec_b64 s[2:3], vcc
	s_cbranch_execz .LBB0_337
	v_add_u32_e32 v9, 0x400, v5
	ds_read2_b32 v[6:7], v9 offset0:134 offset1:199
	ds_read2_b32 v[10:11], v9 offset0:4 offset1:69
	ds_read2_b32 v[12:13], v5 offset0:130 offset1:195
	ds_read2_b32 v[14:15], v5 offset1:65
	v_lshlrev_b32_e32 v8, 1, v1
	v_and_or_b32 v16, v8, s63, v4
	v_lshlrev_b32_e32 v34, 11, v16
	s_waitcnt lgkmcnt(3)
	v_cvt_pk_bf16_f32 v9, v6, v7
	s_waitcnt lgkmcnt(2)
	v_cvt_pk_bf16_f32 v8, v10, v11
	s_waitcnt lgkmcnt(1)
	v_cvt_pk_bf16_f32 v7, v12, v13
	s_waitcnt lgkmcnt(0)
	v_cvt_pk_bf16_f32 v6, v14, v15
	v_lshl_add_u64 v[10:11], v[2:3], 0, v[34:35]
	global_store_dwordx4 v[10:11], v[6:9], off
.LBB0_337:
	s_or_b64 exec, exec, s[2:3]
	s_nop 0
	v_add_u32_e32 v6, 64, v1
	v_cmp_gt_u32_e32 vcc, s62, v6
	s_and_saveexec_b64 s[2:3], vcc
	s_cbranch_execz .LBB0_339
	v_lshlrev_b32_e32 v8, 1, v6
	v_and_b32_e32 v9, 0x7f, v6
	v_add_u32_e32 v6, 0x4600, v5
	v_add_u32_e32 v10, 0x4400, v5
	v_add_u32_e32 v12, 0x4200, v5
	v_add_u32_e32 v14, 0x4000, v5
	ds_read2_b32 v[6:7], v6 offset0:70 offset1:135
	ds_read2_b32 v[10:11], v10 offset0:68 offset1:133
	ds_read2_b32 v[12:13], v12 offset0:66 offset1:131
	ds_read2_b32 v[14:15], v14 offset0:64 offset1:129
	v_and_or_b32 v16, v8, s63, v9
	v_lshlrev_b32_e32 v34, 11, v16
	s_waitcnt lgkmcnt(0)
	v_cvt_pk_bf16_f32 v9, v6, v7
	v_cvt_pk_bf16_f32 v8, v10, v11
	v_cvt_pk_bf16_f32 v7, v12, v13
	v_cvt_pk_bf16_f32 v6, v14, v15
	v_lshl_add_u64 v[10:11], v[2:3], 0, v[34:35]
	global_store_dwordx4 v[10:11], v[6:9], off
.LBB0_339:
	s_or_b64 exec, exec, s[2:3]
	s_nop 0
	v_add_u32_e32 v6, 0x80, v1
	v_cmp_gt_u32_e32 vcc, s62, v6
	s_and_saveexec_b64 s[2:3], vcc
	s_cbranch_execz .LBB0_341
	v_lshlrev_b32_e32 v8, 1, v6
	v_add_u32_e32 v6, 0x8800, v5
	v_add_u32_e32 v9, 0x8400, v5
	ds_read2_b32 v[6:7], v6 offset0:6 offset1:71
	ds_read2_b32 v[10:11], v9 offset0:132 offset1:197
	ds_read2_b32 v[12:13], v9 offset0:2 offset1:67
	v_add_u32_e32 v9, 0x8000, v5
	ds_read2_b32 v[14:15], v9 offset0:128 offset1:193
	v_and_or_b32 v4, v8, s63, v4
	v_lshlrev_b32_e32 v34, 11, v4
	s_waitcnt lgkmcnt(0)
	v_cvt_pk_bf16_f32 v9, v6, v7
	v_cvt_pk_bf16_f32 v8, v10, v11
	v_cvt_pk_bf16_f32 v7, v12, v13
	v_cvt_pk_bf16_f32 v6, v14, v15
	v_lshl_add_u64 v[10:11], v[2:3], 0, v[34:35]
	global_store_dwordx4 v[10:11], v[6:9], off
.LBB0_341:
	s_or_b64 exec, exec, s[2:3]
	v_add_u32_e32 v1, 0xc0, v1
	v_cmp_gt_u32_e32 vcc, s62, v1
	s_and_saveexec_b64 s[2:3], vcc
	s_cbranch_execz .LBB0_35
	v_add_u32_e32 v6, 0xc800, v5
	v_add_u32_e32 v8, 0xc600, v5
	v_add_u32_e32 v10, 0xc400, v5
	v_add_u32_e32 v5, 0xc200, v5
	ds_read2_b32 v[6:7], v6 offset0:70 offset1:135
	ds_read2_b32 v[8:9], v8 offset0:68 offset1:133
	ds_read2_b32 v[10:11], v10 offset0:66 offset1:131
	ds_read2_b32 v[12:13], v5 offset0:64 offset1:129
	v_lshlrev_b32_e32 v4, 1, v1
	v_and_b32_e32 v1, 0x7f, v1
	v_and_or_b32 v1, v4, s63, v1
	v_lshlrev_b32_e32 v34, 11, v1
	s_waitcnt lgkmcnt(0)
	v_cvt_pk_bf16_f32 v7, v6, v7
	v_cvt_pk_bf16_f32 v6, v8, v9
	v_cvt_pk_bf16_f32 v5, v10, v11
	v_cvt_pk_bf16_f32 v4, v12, v13
	v_lshl_add_u64 v[2:3], v[2:3], 0, v[34:35]
	global_store_dwordx4 v[2:3], v[4:7], off
	s_branch .LBB0_35

.LBB0_358:
	s_or_b64 exec, exec, s[8:9]
	v_readlane_b32 s0, v254, 11
	v_readlane_b32 s1, v254, 12
	s_waitcnt vmcnt(0) lgkmcnt(0)
	buffer_inv sc1
	v_mov_b64_e32 v[2:3], s[0:1]
	global_atomic_add v[2:3], v166, off
	s_waitcnt vmcnt(0)

.LBB0_361:
	v_mov_b32_e32 v0, s0
	v_mov_b32_e32 v2, v218
	v_mov_b32_e32 v3, v252
	v_writelane_b32 v255, s0, 7
	s_nop 0
	v_readfirstlane_b32 s0, v3
	v_readfirstlane_b32 s1, v2
	v_readfirstlane_b32 s87, v0
	v_mov_b32_e32 v2, s0
	v_mov_b32_e32 v3, s1
	global_load_dwordx2 v[2:3], v[2:3], off offset:248
	s_cmp_eq_u32 s87, 0
	s_cselect_b64 s[0:1], -1, 0
	v_writelane_b32 v255, s0, 8
	s_cmp_lg_u32 s87, 0
	s_waitcnt vmcnt(0) lgkmcnt(0)
	v_mov_b32_e32 v0, v2
	v_writelane_b32 v255, s1, 9
	s_nop 0
	v_readfirstlane_b32 s10, v0
	v_readfirstlane_b32 s11, v3
	s_cbranch_scc0 .LBB0_371
	s_cmp_lt_i32 s87, 4
	s_mov_b32 s79, 0x3300000
	s_cbranch_scc1 .LBB0_372
	s_cmp_gt_i32 s87, 5
	s_cbranch_scc0 .LBB0_382
	s_mov_b64 s[6:7], 0
	s_cmp_eq_u32 s87, 6
	s_mov_b64 s[8:9], 0
	s_cbranch_scc0 .LBB0_383
	v_mov_b32_e32 v0, v218
	v_mov_b32_e32 v2, v252
	v_mov_b32_e32 v4, v252
	v_readfirstlane_b32 s0, v2
	v_readfirstlane_b32 s1, v0
	v_mov_b32_e32 v0, v218
	v_mov_b32_e32 v2, s0
	v_mov_b32_e32 v3, s1
	global_load_dwordx2 v[2:3], v[2:3], off offset:200
	s_waitcnt vmcnt(0) lgkmcnt(0)
	v_mov_b32_e32 v24, v247
	v_readfirstlane_b32 s0, v4
	v_readfirstlane_b32 s1, v0
	v_mov_b32_e32 v0, s88
	v_mov_b32_e32 v4, s0
	v_mov_b32_e32 v5, s1
	global_load_dwordx2 v[4:5], v[4:5], off offset:248
	v_readfirstlane_b32 s0, v2
	v_readfirstlane_b32 s1, v3
	s_waitcnt vmcnt(0) lgkmcnt(0)
	v_mov_b32_e32 v2, v4
	s_nop 0
	v_readfirstlane_b32 s4, v0
	v_ashrrev_i32_e32 v22, 6, v24
	s_lshl_b32 s22, s4, 3
	v_add_u32_e32 v32, s22, v22
	s_movk_i32 s4, 0x2400
	v_readfirstlane_b32 s8, v2
	v_readfirstlane_b32 s9, v5
	v_cmp_gt_i32_e32 vcc, s4, v32
	s_and_saveexec_b64 s[12:13], vcc
	s_mov_b32 s21, 0x800000
	s_mov_b64 s[24:25], 0x7000
	s_mov_b64 s[26:27], 0x6000
	s_cbranch_execz .LBB0_368
	v_readlane_b32 s4, v254, 39
	v_readlane_b32 s5, v254, 40
	s_lshl_b64 s[4:5], s[4:5], 2
	v_lshlrev_b32_e32 v0, 2, v24
	s_add_u32 s0, s0, s4
	v_and_b32_e32 v26, 0xfc, v0
	s_addc_u32 s1, s1, s5
	v_lshlrev_b32_e32 v0, 2, v26
	v_lshl_add_u64 v[14:15], s[0:1], 0, v[0:1]
	global_load_dwordx4 v[2:5], v[14:15], off
	global_load_dwordx4 v[6:9], v[14:15], off offset:1024
	global_load_dwordx4 v[10:13], v[14:15], off offset:2048
	s_nop 0
	global_load_dwordx4 v[14:17], v[14:15], off offset:3072
	v_lshl_add_u64 v[18:19], s[8:9], 0, v[0:1]
	v_xor_b32_e32 v0, 1, v219
	v_cmp_lt_i32_e32 vcc, v0, v220
	v_readlane_b32 s0, v254, 42
	s_add_u32 s0, s8, s0
	v_cndmask_b32_e32 v0, v219, v0, vcc
	v_lshlrev_b32_e32 v33, 2, v0
	v_xor_b32_e32 v0, 2, v219
	v_cmp_lt_i32_e32 vcc, v0, v220
	v_readlane_b32 s1, v254, 41
	s_addc_u32 s1, s9, s1
	v_cndmask_b32_e32 v0, v219, v0, vcc
	v_lshlrev_b32_e32 v34, 2, v0
	v_xor_b32_e32 v0, 4, v219
	v_cmp_lt_i32_e32 vcc, v0, v220
	s_add_u32 s14, s0, 0x20700000
	s_addc_u32 s15, s1, 0
	v_cndmask_b32_e32 v0, v219, v0, vcc
	v_lshlrev_b32_e32 v35, 2, v0
	v_xor_b32_e32 v0, 8, v219
	v_cmp_lt_i32_e32 vcc, v0, v220
	v_ashrrev_i32_e32 v23, 31, v22
	s_ashr_i32 s23, s22, 31
	v_cndmask_b32_e32 v0, v219, v0, vcc
	v_cmp_lt_i32_e32 vcc, v222, v220
	v_lshlrev_b32_e32 v36, 2, v0
	s_mov_b64 s[0:1], 0x3300000
	v_cndmask_b32_e32 v0, v219, v222, vcc
	v_cmp_lt_i32_e32 vcc, v221, v220
	v_lshlrev_b32_e32 v37, 2, v0
	v_lshl_add_u64 v[28:29], v[22:23], 0, s[22:23]
	v_cndmask_b32_e32 v0, v219, v221, vcc
	v_lshlrev_b32_e32 v38, 2, v0
	v_lshlrev_b32_e32 v0, 1, v26
	v_lshl_add_u64 v[18:19], v[18:19], 0, s[0:1]
	v_lshl_add_u64 v[20:21], s[8:9], 0, v[0:1]
	s_mov_b64 s[0:1], 0x7b00000
	v_lshlrev_b64 v[22:23], 11, v[28:29]
	v_and_b32_e32 v0, 63, v24
	v_lshlrev_b64 v[24:25], 12, v[28:29]
	v_lshl_add_u64 v[20:21], v[20:21], 0, s[0:1]
	v_lshl_or_b32 v22, v0, 3, v22
	v_lshl_or_b32 v24, v0, 4, v24
	s_mov_b64 s[22:23], 0
	v_lshlrev_b32_e32 v0, 2, v26
.LBB0_367:
	v_lshl_add_u64 v[28:29], s[8:9], 0, v[24:25]
	v_add_co_u32_e32 v52, vcc, s79, v28
	v_ashrrev_i32_e32 v27, 11, v32
	v_add_u32_e32 v26, 0x2400, v32
	v_lshl_add_u64 v[30:31], s[8:9], 0, v[22:23]
	v_addc_co_u32_e32 v53, vcc, 0, v29, vcc
	v_mul_i32_i24_e32 v56, 0x2400, v27
	v_ashrrev_i32_e32 v27, 31, v26
	v_add_co_u32_e32 v28, vcc, s43, v30
	global_load_dwordx4 v[40:43], v[52:53], off
	global_load_dwordx4 v[44:47], v[52:53], off offset:1024
	global_load_dwordx4 v[48:51], v[52:53], off offset:2048
	s_nop 0
	global_load_dwordx4 v[52:55], v[52:53], off offset:3072
	v_addc_co_u32_e32 v29, vcc, 0, v31, vcc
	v_lshlrev_b64 v[30:31], 12, v[26:27]
	v_ashrrev_i32_e32 v57, 31, v56
	v_lshl_add_u64 v[30:31], v[18:19], 0, v[30:31]
	v_lshl_add_u64 v[64:65], v[56:57], 2, s[14:15]
	global_load_dwordx4 v[56:59], v[30:31], off
	global_load_dwordx4 v[60:63], v[30:31], off offset:1024
	v_lshl_add_u64 v[74:75], v[64:65], 0, v[0:1]
	global_load_dwordx4 v[64:67], v[30:31], off offset:2048
	global_load_dwordx4 v[68:71], v[30:31], off offset:3072
	v_add_u32_e32 v32, s78, v32
	v_min_i32_e32 v39, 0x4000, v26
	v_cmp_lt_i32_e32 vcc, s42, v32
	v_ashrrev_i32_e32 v39, 11, v39
	s_or_b64 s[22:23], vcc, s[22:23]
	v_mul_i32_i24_e32 v72, 0x2400, v39
	v_add_co_u32_e32 v76, vcc, s18, v74
	v_ashrrev_i32_e32 v73, 31, v72
	s_nop 0
	v_addc_co_u32_e32 v77, vcc, 0, v75, vcc
	v_lshl_add_u64 v[72:73], v[72:73], 2, s[14:15]
	v_add_co_u32_e32 v78, vcc, s20, v74
	v_lshl_add_u64 v[104:105], v[72:73], 0, v[0:1]
	s_nop 0
	v_addc_co_u32_e32 v79, vcc, 0, v75, vcc
	v_add_co_u32_e32 v106, vcc, s18, v104
	v_lshl_add_u64 v[30:31], v[74:75], 0, s[24:25]
	s_nop 0
	v_addc_co_u32_e32 v107, vcc, 0, v105, vcc
	v_add_co_u32_e32 v124, vcc, s20, v104
	v_lshl_add_u64 v[100:101], v[74:75], 0, s[26:27]
	v_lshl_add_u64 v[132:133], v[104:105], 0, s[26:27]
	v_addc_co_u32_e32 v125, vcc, 0, v105, vcc
	global_load_dwordx4 v[72:75], v[76:77], off
	s_nop 0
	global_load_dwordx4 v[76:79], v[78:79], off
	s_nop 0
	global_load_dwordx4 v[80:83], v[30:31], off offset:1024
	global_load_dwordx4 v[84:87], v[30:31], off offset:2048
	global_load_dwordx4 v[88:91], v[100:101], off offset:1024
	global_load_dwordx4 v[92:95], v[30:31], off offset:3072
	global_load_dwordx4 v[96:99], v[100:101], off offset:2048
	s_nop 0
	global_load_dwordx4 v[100:103], v[100:101], off offset:3072
	v_lshl_add_u64 v[30:31], v[104:105], 0, s[24:25]
	global_load_dwordx4 v[104:107], v[106:107], off
	s_nop 0
	global_load_dwordx4 v[108:111], v[30:31], off offset:1024
	global_load_dwordx4 v[112:115], v[30:31], off offset:2048
	global_load_dwordx4 v[116:119], v[30:31], off offset:3072
	global_load_dwordx4 v[120:123], v[132:133], off offset:1024
	s_nop 0
	global_load_dwordx4 v[124:127], v[124:125], off
	s_nop 0
	global_load_dwordx4 v[128:131], v[132:133], off offset:2048
	s_nop 0
	global_load_dwordx4 v[132:135], v[132:133], off offset:3072
	v_lshl_add_u64 v[22:23], v[22:23], 0, s[84:85]
	v_lshl_add_u64 v[24:25], v[24:25], 0, s[80:81]
	v_lshlrev_b64 v[26:27], 11, v[26:27]
	v_lshl_add_u64 v[26:27], v[20:21], 0, v[26:27]
	s_waitcnt vmcnt(0) lgkmcnt(0)
	v_mov_b32_e32 v142, v41
	v_mov_b32_e32 v143, v45
	v_mov_b32_e32 v150, v49
	v_mov_b32_e32 v151, v53
	v_mov_b32_e32 v138, v40
	v_mov_b32_e32 v139, v44
	v_mov_b32_e32 v148, v48
	v_mov_b32_e32 v149, v52
	v_pk_mul_f32 v[142:143], v[142:143], v[142:143]
	v_pk_mul_f32 v[150:151], v[150:151], v[150:151]
	v_mov_b32_e32 v30, v42
	v_mov_b32_e32 v31, v46
	v_mov_b32_e32 v144, v50
	v_mov_b32_e32 v145, v54
	v_pk_fma_f32 v[138:139], v[138:139], v[138:139], v[142:143]
	v_pk_fma_f32 v[142:143], v[148:149], v[148:149], v[150:151]
	v_mov_b32_e32 v154, v57
	v_mov_b32_e32 v155, v61
	v_mov_b32_e32 v136, v43
	v_mov_b32_e32 v137, v47
	v_mov_b32_e32 v146, v51
	v_mov_b32_e32 v147, v55
	v_mov_b32_e32 v152, v56
	v_mov_b32_e32 v153, v60
	v_pk_fma_f32 v[30:31], v[30:31], v[30:31], v[138:139]
	v_mov_b32_e32 v138, v65
	v_mov_b32_e32 v139, v69
	v_pk_fma_f32 v[142:143], v[144:145], v[144:145], v[142:143]
	v_pk_mul_f32 v[144:145], v[154:155], v[154:155]
	v_mov_b32_e32 v148, v58
	v_mov_b32_e32 v149, v62
	v_mov_b32_e32 v160, v64
	v_mov_b32_e32 v161, v68
	v_pk_mul_f32 v[138:139], v[138:139], v[138:139]
	v_pk_fma_f32 v[30:31], v[136:137], v[136:137], v[30:31]
	v_pk_fma_f32 v[136:137], v[146:147], v[146:147], v[142:143]
	v_pk_fma_f32 v[142:143], v[152:153], v[152:153], v[144:145]
	v_mov_b32_e32 v150, v59
	v_mov_b32_e32 v151, v63
	v_mov_b32_e32 v156, v66
	v_mov_b32_e32 v157, v70
	v_pk_fma_f32 v[138:139], v[160:161], v[160:161], v[138:139]
	v_pk_fma_f32 v[142:143], v[148:149], v[148:149], v[142:143]
	v_mov_b32_e32 v158, v67
	v_mov_b32_e32 v159, v71
	v_pk_fma_f32 v[138:139], v[156:157], v[156:157], v[138:139]
	v_pk_fma_f32 v[142:143], v[150:151], v[150:151], v[142:143]
	v_mov_b32_e32 v145, v30
	v_pk_fma_f32 v[138:139], v[158:159], v[158:159], v[138:139]
	v_mov_b32_e32 v144, v142
	v_mov_b32_e32 v30, v143
	v_mov_b32_e32 v147, v136
	v_mov_b32_e32 v146, v138
	v_pk_add_f32 v[30:31], v[144:145], v[30:31]
	v_mov_b32_e32 v136, v139
	v_pk_add_f32 v[30:31], v[30:31], v[146:147]
	v_pk_add_f32 v[72:73], v[72:73], 1.0 op_sel_hi:[1,0]
	v_pk_add_f32 v[30:31], v[30:31], v[136:137]
	ds_bpermute_b32 v137, v33, v31
	ds_bpermute_b32 v136, v33, v30
	v_pk_add_f32 v[74:75], v[74:75], 1.0 op_sel_hi:[1,0]
	v_pk_add_f32 v[80:81], v[80:81], 1.0 op_sel_hi:[1,0]
	v_pk_add_f32 v[82:83], v[82:83], 1.0 op_sel_hi:[1,0]
	v_pk_add_f32 v[84:85], v[84:85], 1.0 op_sel_hi:[1,0]
	s_waitcnt lgkmcnt(0)
	v_pk_add_f32 v[30:31], v[30:31], v[136:137]
	ds_bpermute_b32 v137, v34, v31
	ds_bpermute_b32 v136, v34, v30
	v_pk_add_f32 v[86:87], v[86:87], 1.0 op_sel_hi:[1,0]
	v_pk_add_f32 v[92:93], v[92:93], 1.0 op_sel_hi:[1,0]
	v_pk_add_f32 v[94:95], v[94:95], 1.0 op_sel_hi:[1,0]
	v_pk_add_f32 v[104:105], v[104:105], 1.0 op_sel_hi:[1,0]
	s_waitcnt lgkmcnt(0)
	v_pk_add_f32 v[30:31], v[30:31], v[136:137]
	ds_bpermute_b32 v137, v35, v31
	ds_bpermute_b32 v136, v35, v30
	v_pk_add_f32 v[106:107], v[106:107], 1.0 op_sel_hi:[1,0]
	v_pk_add_f32 v[108:109], v[108:109], 1.0 op_sel_hi:[1,0]
	v_pk_add_f32 v[110:111], v[110:111], 1.0 op_sel_hi:[1,0]
	v_pk_add_f32 v[112:113], v[112:113], 1.0 op_sel_hi:[1,0]
	s_waitcnt lgkmcnt(0)
	v_pk_add_f32 v[30:31], v[30:31], v[136:137]
	ds_bpermute_b32 v137, v36, v31
	ds_bpermute_b32 v136, v36, v30
	v_pk_add_f32 v[114:115], v[114:115], 1.0 op_sel_hi:[1,0]
	v_pk_add_f32 v[116:117], v[116:117], 1.0 op_sel_hi:[1,0]
	v_pk_add_f32 v[118:119], v[118:119], 1.0 op_sel_hi:[1,0]
	s_waitcnt lgkmcnt(0)
	v_pk_add_f32 v[30:31], v[30:31], v[136:137]
	ds_bpermute_b32 v137, v37, v31
	ds_bpermute_b32 v136, v37, v30
	s_waitcnt lgkmcnt(0)
	v_pk_add_f32 v[30:31], v[30:31], v[136:137]
	ds_bpermute_b32 v137, v38, v31
	ds_bpermute_b32 v136, v38, v30
	s_waitcnt lgkmcnt(0)
	v_pk_add_f32 v[30:31], v[30:31], v[136:137]
	s_nop 0
	v_pk_fma_f32 v[30:31], v[30:31], s[86:87], v[162:163] op_sel_hi:[1,0,0]
	s_nop 0
	v_mul_f32_e32 v39, 0x4b800000, v31
	v_cmp_gt_f32_e64 s[38:39], s21, v31
	v_mul_f32_e32 v136, 0x4b800000, v30
	v_cmp_gt_f32_e32 vcc, s21, v30
	v_cndmask_b32_e64 v31, v31, v39, s[38:39]
	v_rsq_f32_e32 v31, v31
	v_cndmask_b32_e32 v30, v30, v136, vcc
	v_rsq_f32_e32 v39, v30
	v_mul_f32_e32 v30, 0x45800000, v31
	v_cndmask_b32_e64 v30, v31, v30, s[38:39]
	v_mul_f32_e32 v136, 0x45800000, v39
	v_cndmask_b32_e32 v136, v39, v136, vcc
	v_pk_mul_f32 v[40:41], v[40:41], v[30:31] op_sel_hi:[1,0]
	v_pk_mul_f32 v[42:43], v[42:43], v[30:31] op_sel_hi:[1,0]
	v_pk_mul_f32 v[44:45], v[44:45], v[30:31] op_sel_hi:[1,0]
	v_pk_mul_f32 v[46:47], v[46:47], v[30:31] op_sel_hi:[1,0]
	v_pk_mul_f32 v[48:49], v[48:49], v[30:31] op_sel_hi:[1,0]
	v_pk_mul_f32 v[50:51], v[50:51], v[30:31] op_sel_hi:[1,0]
	v_pk_mul_f32 v[52:53], v[52:53], v[30:31] op_sel_hi:[1,0]
	v_pk_mul_f32 v[30:31], v[54:55], v[30:31] op_sel_hi:[1,0]
	v_pk_mul_f32 v[54:55], v[56:57], v[136:137] op_sel_hi:[1,0]
	v_pk_mul_f32 v[56:57], v[58:59], v[136:137] op_sel_hi:[1,0]
	v_pk_mul_f32 v[58:59], v[60:61], v[136:137] op_sel_hi:[1,0]
	v_pk_mul_f32 v[60:61], v[62:63], v[136:137] op_sel_hi:[1,0]
	v_pk_mul_f32 v[62:63], v[64:65], v[136:137] op_sel_hi:[1,0]
	v_pk_mul_f32 v[64:65], v[66:67], v[136:137] op_sel_hi:[1,0]
	v_pk_mul_f32 v[66:67], v[68:69], v[136:137] op_sel_hi:[1,0]
	v_pk_mul_f32 v[68:69], v[70:71], v[136:137] op_sel_hi:[1,0]
	v_pk_mul_f32 v[40:41], v[2:3], v[40:41]
	v_pk_mul_f32 v[42:43], v[4:5], v[42:43]
	v_pk_mul_f32 v[44:45], v[6:7], v[44:45]
	v_pk_mul_f32 v[46:47], v[8:9], v[46:47]
	v_pk_mul_f32 v[48:49], v[10:11], v[48:49]
	v_pk_mul_f32 v[50:51], v[12:13], v[50:51]
	v_pk_mul_f32 v[52:53], v[14:15], v[52:53]
	v_pk_mul_f32 v[30:31], v[16:17], v[30:31]
	v_pk_mul_f32 v[54:55], v[2:3], v[54:55]
	v_pk_mul_f32 v[56:57], v[4:5], v[56:57]
	v_pk_mul_f32 v[58:59], v[6:7], v[58:59]
	v_pk_mul_f32 v[60:61], v[8:9], v[60:61]
	v_pk_mul_f32 v[62:63], v[10:11], v[62:63]
	v_pk_mul_f32 v[64:65], v[12:13], v[64:65]
	v_pk_mul_f32 v[66:67], v[14:15], v[66:67]
	v_pk_mul_f32 v[68:69], v[16:17], v[68:69]
	v_pk_fma_f32 v[40:41], v[72:73], v[40:41], v[76:77]
	v_pk_fma_f32 v[42:43], v[74:75], v[42:43], v[78:79]
	v_pk_fma_f32 v[44:45], v[80:81], v[44:45], v[88:89]
	v_pk_fma_f32 v[46:47], v[82:83], v[46:47], v[90:91]
	v_pk_fma_f32 v[48:49], v[84:85], v[48:49], v[96:97]
	v_pk_fma_f32 v[50:51], v[86:87], v[50:51], v[98:99]
	v_pk_fma_f32 v[52:53], v[92:93], v[52:53], v[100:101]
	v_pk_fma_f32 v[30:31], v[94:95], v[30:31], v[102:103]
	v_pk_fma_f32 v[54:55], v[104:105], v[54:55], v[124:125]
	v_pk_fma_f32 v[56:57], v[106:107], v[56:57], v[126:127]
	v_pk_fma_f32 v[58:59], v[108:109], v[58:59], v[120:121]
	v_pk_fma_f32 v[60:61], v[110:111], v[60:61], v[122:123]
	v_pk_fma_f32 v[62:63], v[112:113], v[62:63], v[128:129]
	v_pk_fma_f32 v[64:65], v[114:115], v[64:65], v[130:131]
	v_pk_fma_f32 v[66:67], v[116:117], v[66:67], v[132:133]
	v_pk_fma_f32 v[68:69], v[118:119], v[68:69], v[134:135]
	v_cvt_pk_bf16_f32 v40, v40, v41
	v_cvt_pk_bf16_f32 v41, v42, v43
	v_cvt_pk_bf16_f32 v42, v44, v45
	v_cvt_pk_bf16_f32 v43, v46, v47
	v_cvt_pk_bf16_f32 v44, v48, v49
	v_cvt_pk_bf16_f32 v45, v50, v51
	v_cvt_pk_bf16_f32 v46, v52, v53
	v_cvt_pk_bf16_f32 v47, v30, v31
	v_cvt_pk_bf16_f32 v30, v54, v55
	v_cvt_pk_bf16_f32 v31, v56, v57
	v_cvt_pk_bf16_f32 v48, v58, v59
	v_cvt_pk_bf16_f32 v49, v60, v61
	v_cvt_pk_bf16_f32 v50, v62, v63
	v_cvt_pk_bf16_f32 v51, v64, v65
	v_cvt_pk_bf16_f32 v52, v66, v67
	v_cvt_pk_bf16_f32 v53, v68, v69
	global_store_dwordx2 v[28:29], v[40:41], off
	global_store_dwordx2 v[28:29], v[42:43], off offset:512
	global_store_dwordx2 v[28:29], v[44:45], off offset:1024
	global_store_dwordx2 v[28:29], v[46:47], off offset:1536
	global_store_dwordx2 v[26:27], v[30:31], off
	global_store_dwordx2 v[26:27], v[48:49], off offset:512
	global_store_dwordx2 v[26:27], v[50:51], off offset:1024
	global_store_dwordx2 v[26:27], v[52:53], off offset:1536
	s_andn2_b64 exec, exec, s[22:23]
	s_cbranch_execnz .LBB0_367

.LBB0_375:
	v_readlane_b32 s4, v253, 9
	v_readlane_b32 s5, v253, 10
	v_readlane_b32 s1, v253, 6
	s_or_b64 s[24:25], s[24:25], exec
	v_mov_b64_e32 v[2:3], s[4:5]
	v_readlane_b32 s4, v253, 11
	v_readlane_b32 s5, v253, 12
	s_waitcnt lgkmcnt(0)
	global_load_dword v0, v[2:3], off sc1
	s_or_b64 s[22:23], s[22:23], exec
	v_mov_b64_e32 v[2:3], s[4:5]
	v_readlane_b32 s4, v253, 13
	v_readlane_b32 s5, v253, 14
	global_load_dword v2, v[2:3], off sc1
	s_waitcnt vmcnt(0) lgkmcnt(0)
	v_add_u32_e32 v6, v2, v0
	v_mov_b64_e32 v[4:5], s[4:5]
	v_readlane_b32 s4, v253, 15
	v_readlane_b32 s5, v253, 16
	global_load_dword v3, v[4:5], off sc1
	s_waitcnt vmcnt(0) lgkmcnt(0)
	v_add_u32_e32 v6, v6, v3
	v_mov_b64_e32 v[4:5], s[4:5]
	global_load_dword v4, v[4:5], off sc1
	v_readlane_b32 s4, v253, 17
	v_readlane_b32 s5, v253, 18
	s_waitcnt vmcnt(0) lgkmcnt(0)
	v_add_u32_e32 v8, v6, v4
	v_mov_b64_e32 v[6:7], s[4:5]
	v_readlane_b32 s4, v253, 19
	v_readlane_b32 s5, v253, 20
	global_load_dword v5, v[6:7], off sc1
	s_waitcnt vmcnt(0) lgkmcnt(0)
	v_add_u32_e32 v8, v8, v5
	v_mov_b64_e32 v[6:7], s[4:5]
	global_load_dword v6, v[6:7], off sc1
	v_readlane_b32 s4, v253, 21
	v_readlane_b32 s5, v253, 22
	s_waitcnt vmcnt(0) lgkmcnt(0)
	v_add_u32_e32 v10, v8, v6
	v_mov_b64_e32 v[8:9], s[4:5]
	v_readlane_b32 s4, v253, 23
	v_readlane_b32 s5, v253, 24
	global_load_dword v7, v[8:9], off sc1
	s_waitcnt vmcnt(0) lgkmcnt(0)
	v_add_u32_e32 v10, v10, v7
	v_mov_b64_e32 v[8:9], s[4:5]
	global_load_dword v8, v[8:9], off sc1
	v_readlane_b32 s4, v253, 25
	v_readlane_b32 s5, v253, 26
	s_waitcnt vmcnt(0) lgkmcnt(0)
	v_add_u32_e32 v12, v10, v8
	v_mov_b64_e32 v[10:11], s[4:5]
	v_readlane_b32 s4, v253, 27
	v_readlane_b32 s5, v253, 28
	global_load_dword v9, v[10:11], off sc1
	s_waitcnt vmcnt(0) lgkmcnt(0)
	v_add_u32_e32 v12, v12, v9
	v_mov_b64_e32 v[10:11], s[4:5]
	global_load_dword v10, v[10:11], off sc1
	v_readlane_b32 s4, v253, 29
	v_readlane_b32 s5, v253, 30
	s_waitcnt vmcnt(0) lgkmcnt(0)
	v_add_u32_e32 v14, v12, v10
	v_mov_b64_e32 v[12:13], s[4:5]
	v_readlane_b32 s4, v253, 31
	v_readlane_b32 s5, v253, 32
	global_load_dword v11, v[12:13], off sc1
	s_waitcnt vmcnt(0) lgkmcnt(0)
	v_add_u32_e32 v14, v14, v11
	v_mov_b64_e32 v[12:13], s[4:5]
	global_load_dword v12, v[12:13], off sc1
	v_readlane_b32 s4, v253, 33
	v_readlane_b32 s5, v253, 34
	s_waitcnt vmcnt(0) lgkmcnt(0)
	v_add_u32_e32 v16, v14, v12
	v_mov_b64_e32 v[14:15], s[4:5]
	v_readlane_b32 s4, v253, 35
	v_readlane_b32 s5, v253, 36
	global_load_dword v13, v[14:15], off sc1
	s_waitcnt vmcnt(0) lgkmcnt(0)
	v_add_u32_e32 v16, v16, v13
	v_mov_b64_e32 v[14:15], s[4:5]
	global_load_dword v14, v[14:15], off sc1
	v_readlane_b32 s4, v253, 37
	v_readlane_b32 s5, v253, 38
	s_waitcnt vmcnt(0) lgkmcnt(0)
	v_add_u32_e32 v18, v16, v14
	v_mov_b64_e32 v[16:17], s[4:5]
	v_readlane_b32 s4, v253, 39
	v_readlane_b32 s5, v253, 40
	global_load_dword v15, v[16:17], off sc1
	s_waitcnt vmcnt(0) lgkmcnt(0)
	v_add_u32_e32 v18, v18, v15
	v_mov_b64_e32 v[16:17], s[4:5]
	global_load_dword v16, v[16:17], off sc1
	s_waitcnt vmcnt(0) lgkmcnt(0)
	v_add_u32_e32 v17, v18, v16
	v_cmp_ne_u32_e32 vcc, s1, v17
	s_and_saveexec_b64 s[26:27], vcc
	s_cbranch_execz .LBB0_374
	s_and_b32 s1, s0, 0xff
	s_mov_b64 s[28:29], -1
	s_cmp_eq_u32 s1, 0
	s_mov_b64 s[38:39], -1
	s_mov_b64 s[30:31], -1
	s_sleep 1
	s_cbranch_scc1 .LBB0_378
	s_and_saveexec_b64 s[40:41], s[38:39]
	s_cbranch_execz .LBB0_373
	s_branch .LBB0_381
.LBB0_378:
	v_readlane_b32 s4, v253, 7
	v_readlane_b32 s5, v253, 8
	s_mov_b64 s[38:39], 0
	s_nop 0
	v_mov_b64_e32 v[18:19], s[4:5]
	global_load_dword v17, v[18:19], off sc1
	s_waitcnt vmcnt(0) lgkmcnt(0)
	v_cmp_eq_u32_e32 vcc, 0, v17
	s_and_saveexec_b64 s[40:41], vcc
	s_cmp_lt_u32 s0, 0x40001
	s_cselect_b64 s[4:5], -1, 0
	s_xor_b64 s[30:31], exec, -1
	s_and_b64 s[38:39], s[4:5], exec
	s_or_b64 exec, exec, s[40:41]
	s_and_saveexec_b64 s[40:41], s[38:39]
	s_cbranch_execz .LBB0_373

.LBB0_384:
	s_cmp_eq_u32 s87, 4
	s_cbranch_scc0 .LBB0_496
	v_mov_b32_e32 v2, s64
	v_mov_b32_e32 v3, s65
	v_mov_b32_e32 v10, v247
	v_readfirstlane_b32 s0, v2
	v_readfirstlane_b32 s1, v3
	v_mov_b32_e32 v8, s88
	v_mov_b32_e32 v2, s0
	v_mov_b32_e32 v3, s1
	global_load_dwordx2 v[2:3], v[2:3], off offset:248
	v_mov_b32_e32 v4, s64
	v_mov_b32_e32 v5, s65
	s_waitcnt vmcnt(0) lgkmcnt(0)
	v_mov_b32_e32 v0, s64
	v_readfirstlane_b32 s0, v4
	v_readfirstlane_b32 s1, v5
	v_mov_b32_e32 v6, s65
	v_mov_b32_e32 v4, s0
	v_mov_b32_e32 v5, s1
	global_load_dwordx2 v[4:5], v[4:5], off offset:120
	s_waitcnt vmcnt(0) lgkmcnt(0)
	v_readfirstlane_b32 s8, v8
	v_readfirstlane_b32 s0, v0
	v_readfirstlane_b32 s1, v6
	v_ashrrev_i32_e32 v11, 31, v10
	v_mov_b32_e32 v6, s0
	v_mov_b32_e32 v7, s1
	global_load_dwordx2 v[6:7], v[6:7], off offset:128
	v_readfirstlane_b32 s0, v2
	v_readfirstlane_b32 s1, v3
	s_add_u32 s6, s0, 0x9f00000
	s_addc_u32 s7, s1, 0
	s_ashr_i32 s9, s8, 31
	s_lshl_b64 s[4:5], s[8:9], 9
	s_mov_b64 s[12:13], 0x36000
	v_lshl_add_u64 v[62:63], s[4:5], 0, v[10:11]
	s_mov_b32 s33, 0x800000
	v_readfirstlane_b32 s4, v4
	v_readfirstlane_b32 s5, v5
	v_cmp_gt_u64_e32 vcc, s[12:13], v[62:63]
	s_waitcnt vmcnt(0) lgkmcnt(0)
	v_mov_b32_e32 v0, v7
	s_nop 0
	v_readfirstlane_b32 s18, v6
	v_readfirstlane_b32 s20, v0
	s_and_saveexec_b64 s[12:13], vcc
	s_cbranch_execz .LBB0_402
	s_add_u32 s14, s0, 0x21b69200
	s_addc_u32 s15, s1, 0
	s_mov_b64 s[22:23], 0
	v_mov_b64_e32 v[12:13], v[62:63]
	s_branch .LBB0_389
.LBB0_387:
	s_or_b64 exec, exec, s[26:27]
	v_mov_b32_e32 v4, v81
	v_mov_b32_e32 v5, v78
	v_mov_b32_e32 v6, v79
	v_mov_b32_e32 v7, v76
	v_mov_b32_e32 v8, v77
	v_mov_b32_e32 v9, v74
	v_mov_b32_e32 v0, v75
	v_pk_mov_b32 v[4:5], v[4:5], v[6:7] op_sel:[1,0]
	v_cvt_pk_bf16_f32 v2, v80, v81
	v_cvt_pk_bf16_f32 v3, v4, v5
	v_pk_mov_b32 v[4:5], v[6:7], v[8:9] op_sel:[1,0]
	v_pk_mov_b32 v[6:7], v[8:9], v[0:1] op_sel:[1,0]
	v_cvt_pk_bf16_f32 v4, v4, v5
	v_cvt_pk_bf16_f32 v5, v6, v7
	global_store_dwordx4 v[14:15], v[2:5], off
	s_nop 1
	v_cvt_pk_bf16_f32 v2, v68, v69
	v_cvt_pk_bf16_f32 v3, v34, v35
	v_cvt_pk_bf16_f32 v4, v58, v59
	v_cvt_pk_bf16_f32 v5, v36, v37
	global_store_dwordx4 v[14:15], v[2:5], off offset:16
	s_nop 1
	v_cvt_pk_bf16_f32 v2, v66, v67
	v_cvt_pk_bf16_f32 v3, v70, v71
	v_cvt_pk_bf16_f32 v4, v72, v73
	v_cvt_pk_bf16_f32 v5, v64, v65
	global_store_dwordx4 v[14:15], v[2:5], off offset:32
	s_nop 1
	v_cvt_pk_bf16_f32 v2, v46, v47
	v_cvt_pk_bf16_f32 v3, v26, v27
	v_cvt_pk_bf16_f32 v4, v48, v49
	v_cvt_pk_bf16_f32 v5, v32, v33
	global_store_dwordx4 v[14:15], v[2:5], off offset:48
	s_nop 1
	v_cvt_pk_bf16_f32 v2, v52, v53
	v_cvt_pk_bf16_f32 v3, v24, v25
	v_cvt_pk_bf16_f32 v4, v56, v57
	v_cvt_pk_bf16_f32 v5, v30, v31
	global_store_dwordx4 v[14:15], v[2:5], off offset:64
	s_nop 1
	v_cvt_pk_bf16_f32 v2, v50, v51
	v_cvt_pk_bf16_f32 v3, v18, v19
	v_cvt_pk_bf16_f32 v4, v54, v55
	v_cvt_pk_bf16_f32 v5, v28, v29
	global_store_dwordx4 v[14:15], v[2:5], off offset:80
	s_nop 1
	v_cvt_pk_bf16_f32 v2, v42, v43
	v_cvt_pk_bf16_f32 v3, v16, v17
	v_cvt_pk_bf16_f32 v4, v44, v45
	v_cvt_pk_bf16_f32 v5, v20, v21
	global_store_dwordx4 v[14:15], v[2:5], off offset:96
	s_nop 1
	v_cvt_pk_bf16_f32 v2, v40, v41
	v_cvt_pk_bf16_f32 v3, v22, v23
	v_cvt_pk_bf16_f32 v4, v60, v61
	v_cvt_pk_bf16_f32 v5, v38, v39
	global_store_dwordx4 v[14:15], v[2:5], off offset:112

.LBB0_396:
	s_andn2_saveexec_b64 s[26:27], s[26:27]
	v_lshlrev_b64 v[2:3], 6, v[0:1]
	v_mov_b64_e32 v[6:7], 0
	s_or_b64 exec, exec, s[26:27]
	v_mov_b64_e32 v[4:5], s[6:7]
	v_mad_u64_u32 v[4:5], s[26:27], v82, s2, v[4:5]
	v_lshl_add_u64 v[14:15], v[2:3], 1, v[4:5]
	global_load_dwordx4 v[2:5], v[14:15], off
	global_load_dwordx4 v[16:19], v[14:15], off offset:16
	global_load_dwordx4 v[20:23], v[14:15], off offset:32
	global_load_dwordx4 v[26:29], v[14:15], off offset:48
	global_load_dwordx4 v[38:41], v[14:15], off offset:64
	global_load_dwordx4 v[42:45], v[14:15], off offset:80
	global_load_dwordx4 v[84:87], v[14:15], off offset:96
	global_load_dwordx4 v[88:91], v[14:15], off offset:112
	v_cmp_ne_u64_e64 s[38:39], 0, v[6:7]
	s_waitcnt vmcnt(0) lgkmcnt(0)
	v_lshlrev_b32_e32 v80, 16, v2
	v_and_b32_e32 v81, 0xffff0000, v2
	v_lshlrev_b32_e32 v78, 16, v3
	v_and_b32_e32 v79, 0xffff0000, v3
	v_lshlrev_b32_e32 v76, 16, v4
	v_and_b32_e32 v77, 0xffff0000, v4
	v_lshlrev_b32_e32 v74, 16, v5
	v_and_b32_e32 v75, 0xffff0000, v5
	v_lshlrev_b32_e32 v68, 16, v16
	v_and_b32_e32 v69, 0xffff0000, v16
	v_lshlrev_b32_e32 v34, 16, v17
	v_and_b32_e32 v35, 0xffff0000, v17
	v_lshlrev_b32_e32 v58, 16, v18
	v_and_b32_e32 v59, 0xffff0000, v18
	v_lshlrev_b32_e32 v36, 16, v19
	v_and_b32_e32 v37, 0xffff0000, v19
	v_lshlrev_b32_e32 v66, 16, v20
	v_and_b32_e32 v67, 0xffff0000, v20
	v_lshlrev_b32_e32 v70, 16, v21
	v_and_b32_e32 v71, 0xffff0000, v21
	v_lshlrev_b32_e32 v72, 16, v22
	v_and_b32_e32 v73, 0xffff0000, v22
	v_lshlrev_b32_e32 v64, 16, v23
	v_and_b32_e32 v65, 0xffff0000, v23
	v_lshlrev_b32_e32 v46, 16, v26
	v_and_b32_e32 v47, 0xffff0000, v26
	v_lshlrev_b32_e32 v26, 16, v27
	v_and_b32_e32 v27, 0xffff0000, v27
	v_lshlrev_b32_e32 v48, 16, v28
	v_and_b32_e32 v49, 0xffff0000, v28
	v_lshlrev_b32_e32 v32, 16, v29
	v_and_b32_e32 v33, 0xffff0000, v29
	v_lshlrev_b32_e32 v52, 16, v38
	v_and_b32_e32 v53, 0xffff0000, v38
	v_lshlrev_b32_e32 v24, 16, v39
	v_and_b32_e32 v25, 0xffff0000, v39
	v_lshlrev_b32_e32 v56, 16, v40
	v_and_b32_e32 v57, 0xffff0000, v40
	v_lshlrev_b32_e32 v30, 16, v41
	v_and_b32_e32 v31, 0xffff0000, v41
	v_lshlrev_b32_e32 v50, 16, v42
	v_and_b32_e32 v51, 0xffff0000, v42
	v_lshlrev_b32_e32 v18, 16, v43
	v_and_b32_e32 v19, 0xffff0000, v43
	v_lshlrev_b32_e32 v54, 16, v44
	v_and_b32_e32 v55, 0xffff0000, v44
	v_lshlrev_b32_e32 v28, 16, v45
	v_and_b32_e32 v29, 0xffff0000, v45
	v_lshlrev_b32_e32 v42, 16, v84
	v_and_b32_e32 v43, 0xffff0000, v84
	v_lshlrev_b32_e32 v16, 16, v85
	v_and_b32_e32 v17, 0xffff0000, v85
	v_lshlrev_b32_e32 v44, 16, v86
	v_and_b32_e32 v45, 0xffff0000, v86
	v_lshlrev_b32_e32 v20, 16, v87
	v_and_b32_e32 v21, 0xffff0000, v87
	v_lshlrev_b32_e32 v40, 16, v88
	v_and_b32_e32 v41, 0xffff0000, v88
	v_lshlrev_b32_e32 v22, 16, v89
	v_and_b32_e32 v23, 0xffff0000, v89
	v_lshlrev_b32_e32 v60, 16, v90
	v_and_b32_e32 v61, 0xffff0000, v90
	v_lshlrev_b32_e32 v38, 16, v91
	v_and_b32_e32 v39, 0xffff0000, v91
	s_and_saveexec_b64 s[26:27], s[38:39]
	s_cbranch_execz .LBB0_400
	v_pk_mul_f32 v[2:3], v[80:81], v[80:81]
	v_pk_mul_f32 v[4:5], v[78:79], v[78:79]
	v_add_f32_e32 v0, v2, v3
	v_add_f32_e32 v0, v0, v4
	v_pk_mul_f32 v[8:9], v[76:77], v[76:77]
	v_add_f32_e32 v0, v5, v0
	v_add_f32_e32 v0, v8, v0
	v_pk_mul_f32 v[84:85], v[74:75], v[74:75]
	v_add_f32_e32 v0, v9, v0
	v_add_f32_e32 v0, v84, v0
	v_pk_mul_f32 v[86:87], v[68:69], v[68:69]
	v_add_f32_e32 v0, v85, v0
	v_add_f32_e32 v0, v86, v0
	v_pk_mul_f32 v[88:89], v[34:35], v[34:35]
	v_add_f32_e32 v0, v87, v0
	v_add_f32_e32 v0, v88, v0
	v_pk_mul_f32 v[90:91], v[58:59], v[58:59]
	v_add_f32_e32 v0, v89, v0
	v_add_f32_e32 v0, v90, v0
	v_pk_mul_f32 v[92:93], v[36:37], v[36:37]
	v_add_f32_e32 v0, v91, v0
	v_add_f32_e32 v0, v92, v0
	v_pk_mul_f32 v[94:95], v[66:67], v[66:67]
	v_add_f32_e32 v0, v93, v0
	v_add_f32_e32 v0, v94, v0
	v_pk_mul_f32 v[96:97], v[70:71], v[70:71]
	v_add_f32_e32 v0, v95, v0
	v_add_f32_e32 v0, v96, v0
	v_pk_mul_f32 v[98:99], v[72:73], v[72:73]
	v_add_f32_e32 v0, v97, v0
	v_add_f32_e32 v0, v98, v0
	v_pk_mul_f32 v[100:101], v[64:65], v[64:65]
	v_add_f32_e32 v0, v99, v0
	v_add_f32_e32 v0, v100, v0
	v_pk_mul_f32 v[102:103], v[46:47], v[46:47]
	v_add_f32_e32 v0, v101, v0
	v_add_f32_e32 v0, v102, v0
	v_pk_mul_f32 v[104:105], v[26:27], v[26:27]
	v_add_f32_e32 v0, v103, v0
	v_add_f32_e32 v0, v104, v0
	v_pk_mul_f32 v[106:107], v[48:49], v[48:49]
	v_add_f32_e32 v0, v105, v0
	v_add_f32_e32 v0, v106, v0
	v_pk_mul_f32 v[108:109], v[32:33], v[32:33]
	v_add_f32_e32 v0, v107, v0
	v_add_f32_e32 v0, v108, v0
	v_pk_mul_f32 v[110:111], v[52:53], v[52:53]
	v_add_f32_e32 v0, v109, v0
	v_add_f32_e32 v0, v110, v0
	v_pk_mul_f32 v[112:113], v[24:25], v[24:25]
	v_add_f32_e32 v0, v111, v0
	v_add_f32_e32 v0, v112, v0
	v_pk_mul_f32 v[114:115], v[56:57], v[56:57]
	v_add_f32_e32 v0, v113, v0
	v_add_f32_e32 v0, v114, v0
	v_pk_mul_f32 v[116:117], v[30:31], v[30:31]
	v_add_f32_e32 v0, v115, v0
	v_add_f32_e32 v0, v116, v0
	v_pk_mul_f32 v[118:119], v[50:51], v[50:51]
	v_add_f32_e32 v0, v117, v0
	v_add_f32_e32 v0, v118, v0
	v_pk_mul_f32 v[120:121], v[18:19], v[18:19]
	v_add_f32_e32 v0, v119, v0
	v_add_f32_e32 v0, v120, v0
	v_pk_mul_f32 v[122:123], v[54:55], v[54:55]
	v_add_f32_e32 v0, v121, v0
	v_add_f32_e32 v0, v122, v0
	v_pk_mul_f32 v[124:125], v[28:29], v[28:29]
	v_add_f32_e32 v0, v123, v0
	v_add_f32_e32 v0, v124, v0
	v_pk_mul_f32 v[126:127], v[42:43], v[42:43]
	v_add_f32_e32 v0, v125, v0
	v_add_f32_e32 v0, v126, v0
	v_pk_mul_f32 v[128:129], v[16:17], v[16:17]
	v_add_f32_e32 v0, v127, v0
	v_add_f32_e32 v0, v128, v0
	v_pk_mul_f32 v[130:131], v[44:45], v[44:45]
	v_add_f32_e32 v0, v129, v0
	v_add_f32_e32 v0, v130, v0
	v_pk_mul_f32 v[132:133], v[20:21], v[20:21]
	v_add_f32_e32 v0, v131, v0
	v_add_f32_e32 v0, v132, v0
	v_pk_mul_f32 v[134:135], v[40:41], v[40:41]
	v_add_f32_e32 v0, v133, v0
	v_add_f32_e32 v0, v134, v0
	v_pk_mul_f32 v[136:137], v[22:23], v[22:23]
	v_add_f32_e32 v0, v135, v0
	v_add_f32_e32 v0, v136, v0
	v_pk_mul_f32 v[138:139], v[60:61], v[60:61]
	v_add_f32_e32 v0, v137, v0
	v_add_f32_e32 v0, v138, v0
	v_pk_mul_f32 v[142:143], v[38:39], v[38:39]
	v_add_f32_e32 v0, v139, v0
	v_add_f32_e32 v0, v142, v0
	v_add_f32_e32 v0, v143, v0
	v_fmamk_f32 v0, v0, 0x3c800000, v162
	v_cmp_gt_f32_e64 s[38:39], s33, v0
	v_mul_f32_e32 v2, 0x4b800000, v0
	global_load_dwordx4 v[84:87], v[6:7], off offset:64
	v_cndmask_b32_e64 v0, v0, v2, s[38:39]
	v_rsq_f32_e32 v0, v0
	s_nop 0
	v_mul_f32_e32 v2, 0x45800000, v0
	v_cndmask_b32_e64 v0, v0, v2, s[38:39]
	global_load_dwordx4 v[2:5], v[6:7], off
	v_pk_mul_f32 v[8:9], v[0:1], v[80:81] op_sel_hi:[0,1]
	s_waitcnt vmcnt(0) lgkmcnt(0)
	v_pk_mul_f32 v[80:81], v[8:9], v[2:3]
	v_pk_mul_f32 v[2:3], v[0:1], v[66:67] op_sel_hi:[0,1]
	v_pk_mul_f32 v[66:67], v[2:3], v[84:85]
	v_pk_mul_f32 v[2:3], v[0:1], v[78:79] op_sel_hi:[0,1]
	v_pk_mul_f32 v[78:79], v[2:3], v[4:5]
	v_pk_mul_f32 v[2:3], v[0:1], v[70:71] op_sel_hi:[0,1]
	v_pk_mul_f32 v[70:71], v[2:3], v[86:87]
	global_load_dwordx4 v[2:5], v[6:7], off offset:16
	global_load_dwordx4 v[84:87], v[6:7], off offset:80
	v_pk_mul_f32 v[8:9], v[0:1], v[76:77] op_sel_hi:[0,1]
	s_waitcnt vmcnt(0) lgkmcnt(0)
	v_pk_mul_f32 v[76:77], v[8:9], v[2:3]
	v_pk_mul_f32 v[2:3], v[0:1], v[72:73] op_sel_hi:[0,1]
	v_pk_mul_f32 v[72:73], v[2:3], v[84:85]
	v_pk_mul_f32 v[2:3], v[0:1], v[74:75] op_sel_hi:[0,1]
	v_pk_mul_f32 v[74:75], v[2:3], v[4:5]
	v_pk_mul_f32 v[2:3], v[0:1], v[64:65] op_sel_hi:[0,1]
	v_pk_mul_f32 v[64:65], v[2:3], v[86:87]
	global_load_dwordx4 v[2:5], v[6:7], off offset:32
	global_load_dwordx4 v[84:87], v[6:7], off offset:96
	v_pk_mul_f32 v[8:9], v[0:1], v[68:69] op_sel_hi:[0,1]
	s_waitcnt vmcnt(0) lgkmcnt(0)
	v_pk_mul_f32 v[68:69], v[8:9], v[2:3]
	v_pk_mul_f32 v[2:3], v[0:1], v[46:47] op_sel_hi:[0,1]
	v_pk_mul_f32 v[46:47], v[2:3], v[84:85]
	v_pk_mul_f32 v[2:3], v[0:1], v[34:35] op_sel_hi:[0,1]
	v_pk_mul_f32 v[34:35], v[2:3], v[4:5]
	v_pk_mul_f32 v[2:3], v[0:1], v[26:27] op_sel_hi:[0,1]
	v_pk_mul_f32 v[26:27], v[2:3], v[86:87]
	global_load_dwordx4 v[2:5], v[6:7], off offset:48
	global_load_dwordx4 v[84:87], v[6:7], off offset:112
	v_pk_mul_f32 v[8:9], v[0:1], v[58:59] op_sel_hi:[0,1]
	s_waitcnt vmcnt(0) lgkmcnt(0)
	v_pk_mul_f32 v[58:59], v[8:9], v[2:3]
	v_pk_mul_f32 v[2:3], v[0:1], v[48:49] op_sel_hi:[0,1]
	v_pk_mul_f32 v[48:49], v[2:3], v[84:85]
	v_pk_mul_f32 v[2:3], v[0:1], v[36:37] op_sel_hi:[0,1]
	v_pk_mul_f32 v[36:37], v[2:3], v[4:5]
	v_pk_mul_f32 v[2:3], v[0:1], v[32:33] op_sel_hi:[0,1]
	v_pk_mul_f32 v[32:33], v[2:3], v[86:87]
	global_load_dwordx4 v[2:5], v[6:7], off offset:128
	global_load_dwordx4 v[84:87], v[6:7], off offset:192
	v_pk_mul_f32 v[8:9], v[0:1], v[52:53] op_sel_hi:[0,1]
	s_waitcnt vmcnt(0) lgkmcnt(0)
	v_pk_mul_f32 v[52:53], v[8:9], v[2:3]
	v_pk_mul_f32 v[2:3], v[0:1], v[42:43] op_sel_hi:[0,1]
	v_pk_mul_f32 v[42:43], v[2:3], v[84:85]
	v_pk_mul_f32 v[2:3], v[0:1], v[24:25] op_sel_hi:[0,1]
	v_pk_mul_f32 v[24:25], v[2:3], v[4:5]
	v_pk_mul_f32 v[2:3], v[0:1], v[16:17] op_sel_hi:[0,1]
	v_pk_mul_f32 v[16:17], v[2:3], v[86:87]
	global_load_dwordx4 v[2:5], v[6:7], off offset:144
	global_load_dwordx4 v[84:87], v[6:7], off offset:208
	v_pk_mul_f32 v[8:9], v[0:1], v[56:57] op_sel_hi:[0,1]
	s_waitcnt vmcnt(0) lgkmcnt(0)
	v_pk_mul_f32 v[56:57], v[8:9], v[2:3]
	v_pk_mul_f32 v[2:3], v[0:1], v[44:45] op_sel_hi:[0,1]
	v_pk_mul_f32 v[44:45], v[2:3], v[84:85]
	v_pk_mul_f32 v[2:3], v[0:1], v[30:31] op_sel_hi:[0,1]
	v_pk_mul_f32 v[30:31], v[2:3], v[4:5]
	v_pk_mul_f32 v[2:3], v[0:1], v[20:21] op_sel_hi:[0,1]
	v_pk_mul_f32 v[20:21], v[2:3], v[86:87]
	global_load_dwordx4 v[2:5], v[6:7], off offset:160
	global_load_dwordx4 v[84:87], v[6:7], off offset:224
	v_pk_mul_f32 v[8:9], v[0:1], v[50:51] op_sel_hi:[0,1]
	s_waitcnt vmcnt(0) lgkmcnt(0)
	v_pk_mul_f32 v[50:51], v[8:9], v[2:3]
	v_pk_mul_f32 v[2:3], v[0:1], v[40:41] op_sel_hi:[0,1]
	v_pk_mul_f32 v[40:41], v[2:3], v[84:85]
	v_pk_mul_f32 v[2:3], v[0:1], v[18:19] op_sel_hi:[0,1]
	v_pk_mul_f32 v[18:19], v[2:3], v[4:5]
	v_pk_mul_f32 v[2:3], v[0:1], v[22:23] op_sel_hi:[0,1]
	v_pk_mul_f32 v[22:23], v[2:3], v[86:87]
	global_load_dwordx4 v[2:5], v[6:7], off offset:176
	v_pk_mul_f32 v[8:9], v[0:1], v[54:55] op_sel_hi:[0,1]
	s_waitcnt vmcnt(0) lgkmcnt(0)
	v_pk_mul_f32 v[54:55], v[8:9], v[2:3]
	global_load_dwordx4 v[6:9], v[6:7], off offset:240
	v_pk_mul_f32 v[2:3], v[0:1], v[60:61] op_sel_hi:[0,1]
	s_waitcnt vmcnt(0) lgkmcnt(0)
	v_pk_mul_f32 v[60:61], v[2:3], v[6:7]
	v_pk_mul_f32 v[2:3], v[0:1], v[28:29] op_sel_hi:[0,1]
	v_pk_mul_f32 v[28:29], v[2:3], v[4:5]
	v_pk_mul_f32 v[2:3], v[0:1], v[38:39] op_sel_hi:[0,1]
	v_pk_mul_f32 v[38:39], v[2:3], v[8:9]
.LBB0_400:
	s_or_b64 exec, exec, s[26:27]
	s_and_saveexec_b64 s[26:27], vcc
	s_cbranch_execz .LBB0_387
	v_lshlrev_b32_e32 v0, 8, v82
	v_and_b32_e32 v0, 0x7ff00, v0
	v_lshl_add_u64 v[6:7], s[14:15], 0, v[0:1]
	global_load_dwordx4 v[2:5], v[6:7], off
	global_load_dwordx4 v[88:91], v[6:7], off offset:128
	v_pk_mov_b32 v[94:95], v[66:67], v[70:71] op_sel:[1,0]
	v_pk_mov_b32 v[92:93], v[80:81], v[78:79] op_sel:[1,0]
	v_pk_mov_b32 v[84:85], v[78:79], v[76:77] op_sel:[1,0]
	v_pk_mov_b32 v[86:87], v[76:77], v[74:75] op_sel:[1,0]
	v_pk_mov_b32 v[8:9], v[74:75], v[68:69] op_sel:[1,0]
	v_mov_b32_e32 v104, v80
	v_mov_b32_e32 v105, v69
	s_waitcnt vmcnt(0) lgkmcnt(0)
	v_pk_mov_b32 v[82:83], v[2:3], v[4:5] op_sel:[1,0]
	v_pk_mov_b32 v[96:97], v[88:89], v[90:91] op_sel:[1,0]
	v_pk_mul_f32 v[78:79], v[78:79], v[90:91]
	v_pk_mul_f32 v[94:95], v[94:95], v[96:97]
	v_pk_fma_f32 v[78:79], v[70:71], v[4:5], v[78:79]
	v_pk_fma_f32 v[82:83], v[92:93], v[82:83], v[94:95] neg_lo:[0,0,1] neg_hi:[0,0,1]
	global_load_dwordx4 v[92:95], v[6:7], off offset:16
	global_load_dwordx4 v[96:99], v[6:7], off offset:144
	v_pk_mov_b32 v[70:71], v[70:71], v[72:73] op_sel:[1,0]
	v_pk_mul_f32 v[80:81], v[80:81], v[88:89]
	s_waitcnt vmcnt(0) lgkmcnt(0)
	v_pk_mov_b32 v[4:5], v[4:5], v[92:93] op_sel:[1,0]
	v_pk_mov_b32 v[90:91], v[90:91], v[96:97] op_sel:[1,0]
	v_pk_fma_f32 v[80:81], v[66:67], v[2:3], v[80:81]
	v_pk_mul_f32 v[70:71], v[70:71], v[90:91]
	v_mov_b32_e32 v67, v47
	v_pk_fma_f32 v[84:85], v[84:85], v[4:5], v[70:71] neg_lo:[0,0,1] neg_hi:[0,0,1]
	v_pk_mul_f32 v[4:5], v[76:77], v[96:97]
	v_pk_mov_b32 v[70:71], v[72:73], v[64:65] op_sel:[1,0]
	v_pk_fma_f32 v[76:77], v[72:73], v[92:93], v[4:5]
	v_pk_mov_b32 v[72:73], v[96:97], v[98:99] op_sel:[1,0]
	v_pk_mov_b32 v[4:5], v[92:93], v[94:95] op_sel:[1,0]
	v_pk_mul_f32 v[70:71], v[70:71], v[72:73]
	s_nop 0
	v_pk_fma_f32 v[86:87], v[86:87], v[4:5], v[70:71] neg_lo:[0,0,1] neg_hi:[0,0,1]
	global_load_dwordx4 v[70:73], v[6:7], off offset:32
	global_load_dwordx4 v[100:103], v[6:7], off offset:160
	v_pk_mul_f32 v[4:5], v[74:75], v[98:99]
	s_waitcnt vmcnt(0) lgkmcnt(0)
	v_mov_b32_e32 v3, v71
	v_pk_fma_f32 v[74:75], v[64:65], v[94:95], v[4:5]
	v_pk_mov_b32 v[64:65], v[64:65], v[46:47] op_sel:[1,0]
	v_pk_mov_b32 v[90:91], v[98:99], v[100:101] op_sel:[1,0]
	v_pk_mov_b32 v[4:5], v[94:95], v[70:71] op_sel:[1,0]
	v_pk_mul_f32 v[64:65], v[64:65], v[90:91]
	v_mov_b32_e32 v89, v101
	v_pk_fma_f32 v[90:91], v[8:9], v[4:5], v[64:65] neg_lo:[0,0,1] neg_hi:[0,0,1]
	v_pk_mul_f32 v[4:5], v[68:69], v[100:101]
	v_pk_mul_f32 v[8:9], v[66:67], v[88:89]
	v_pk_fma_f32 v[46:47], v[46:47], v[70:71], v[4:5]
	v_pk_fma_f32 v[88:89], v[104:105], v[2:3], v[8:9] neg_lo:[0,0,1] neg_hi:[0,0,1]
	v_pk_mul_f32 v[2:3], v[34:35], v[102:103]
	v_pk_mul_f32 v[4:5], v[26:27], v[102:103]
	v_pk_fma_f32 v[26:27], v[26:27], v[72:73], v[2:3]
	v_pk_fma_f32 v[34:35], v[34:35], v[72:73], v[4:5] neg_lo:[0,0,1] neg_hi:[0,0,1]
	global_load_dwordx4 v[2:5], v[6:7], off offset:48
	global_load_dwordx4 v[64:67], v[6:7], off offset:176
	v_mov_b64_e32 v[70:71], v[78:79]
	v_mov_b64_e32 v[72:73], v[76:77]
	v_mov_b32_e32 v68, v91
	v_mov_b32_e32 v77, v86
	v_mov_b32_e32 v79, v84
	v_mov_b32_e32 v76, v85
	v_mov_b32_e32 v78, v83
	v_mov_b32_e32 v69, v89
	s_waitcnt vmcnt(0) lgkmcnt(0)
	v_pk_mul_f32 v[8:9], v[58:59], v[64:65]
	v_pk_mul_f32 v[64:65], v[48:49], v[64:65]
	v_pk_fma_f32 v[48:49], v[48:49], v[2:3], v[8:9]
	v_pk_fma_f32 v[58:59], v[58:59], v[2:3], v[64:65] neg_lo:[0,0,1] neg_hi:[0,0,1]
	v_pk_mul_f32 v[2:3], v[36:37], v[66:67]
	v_pk_mul_f32 v[8:9], v[32:33], v[66:67]
	v_pk_fma_f32 v[32:33], v[32:33], v[4:5], v[2:3]
	v_pk_fma_f32 v[36:37], v[36:37], v[4:5], v[8:9] neg_lo:[0,0,1] neg_hi:[0,0,1]
	global_load_dwordx4 v[2:5], v[6:7], off offset:64
	global_load_dwordx4 v[64:67], v[6:7], off offset:192
	s_waitcnt vmcnt(0) lgkmcnt(0)
	v_pk_mul_f32 v[8:9], v[52:53], v[64:65]
	v_pk_mul_f32 v[64:65], v[42:43], v[64:65]
	v_pk_fma_f32 v[42:43], v[42:43], v[2:3], v[8:9]
	v_pk_fma_f32 v[52:53], v[52:53], v[2:3], v[64:65] neg_lo:[0,0,1] neg_hi:[0,0,1]
	v_pk_mul_f32 v[2:3], v[24:25], v[66:67]
	v_pk_mul_f32 v[8:9], v[16:17], v[66:67]
	v_pk_fma_f32 v[16:17], v[16:17], v[4:5], v[2:3]
	v_pk_fma_f32 v[24:25], v[24:25], v[4:5], v[8:9] neg_lo:[0,0,1] neg_hi:[0,0,1]
	global_load_dwordx4 v[2:5], v[6:7], off offset:80
	global_load_dwordx4 v[64:67], v[6:7], off offset:208
	s_waitcnt vmcnt(0) lgkmcnt(0)
	v_pk_mul_f32 v[8:9], v[56:57], v[64:65]
	v_pk_mul_f32 v[64:65], v[44:45], v[64:65]
	v_pk_fma_f32 v[44:45], v[44:45], v[2:3], v[8:9]
	v_pk_fma_f32 v[56:57], v[56:57], v[2:3], v[64:65] neg_lo:[0,0,1] neg_hi:[0,0,1]
	v_pk_mul_f32 v[2:3], v[30:31], v[66:67]
	v_pk_mul_f32 v[8:9], v[20:21], v[66:67]
	v_pk_fma_f32 v[20:21], v[20:21], v[4:5], v[2:3]
	v_pk_fma_f32 v[30:31], v[30:31], v[4:5], v[8:9] neg_lo:[0,0,1] neg_hi:[0,0,1]
	global_load_dwordx4 v[2:5], v[6:7], off offset:96
	global_load_dwordx4 v[64:67], v[6:7], off offset:224
	s_waitcnt vmcnt(0) lgkmcnt(0)
	v_pk_mul_f32 v[8:9], v[50:51], v[64:65]
	v_pk_mul_f32 v[64:65], v[40:41], v[64:65]
	v_pk_fma_f32 v[40:41], v[40:41], v[2:3], v[8:9]
	v_pk_fma_f32 v[50:51], v[50:51], v[2:3], v[64:65] neg_lo:[0,0,1] neg_hi:[0,0,1]
	v_pk_mul_f32 v[2:3], v[18:19], v[66:67]
	v_pk_mul_f32 v[8:9], v[22:23], v[66:67]
	v_pk_fma_f32 v[22:23], v[22:23], v[4:5], v[2:3]
	v_pk_fma_f32 v[18:19], v[18:19], v[4:5], v[8:9] neg_lo:[0,0,1] neg_hi:[0,0,1]
	global_load_dwordx4 v[2:5], v[6:7], off offset:112
	s_nop 0
	global_load_dwordx4 v[6:9], v[6:7], off offset:240
	v_mov_b64_e32 v[66:67], v[80:81]
	v_mov_b32_e32 v81, v82
	v_mov_b32_e32 v80, v88
	s_waitcnt vmcnt(0) lgkmcnt(0)
	v_pk_mul_f32 v[64:65], v[54:55], v[6:7]
	v_pk_mul_f32 v[6:7], v[60:61], v[6:7]
	v_pk_fma_f32 v[60:61], v[60:61], v[2:3], v[64:65]
	v_pk_fma_f32 v[54:55], v[54:55], v[2:3], v[6:7] neg_lo:[0,0,1] neg_hi:[0,0,1]
	v_pk_mul_f32 v[2:3], v[28:29], v[8:9]
	v_pk_mul_f32 v[6:7], v[38:39], v[8:9]
	v_pk_fma_f32 v[38:39], v[38:39], v[4:5], v[2:3]
	v_pk_fma_f32 v[28:29], v[28:29], v[4:5], v[6:7] neg_lo:[0,0,1] neg_hi:[0,0,1]
	v_mov_b64_e32 v[64:65], v[74:75]
	v_mov_b32_e32 v75, v90
	v_mov_b32_e32 v74, v87
	s_branch .LBB0_387
.LBB0_402:
	s_or_b64 exec, exec, s[12:13]
	v_mov_b32_e32 v2, s64
	v_mov_b32_e32 v3, s65
	v_mov_b32_e32 v0, s64
	v_readfirstlane_b32 s4, v2
	v_readfirstlane_b32 s5, v3
	v_mov_b32_e32 v4, s65
	v_mov_b32_e32 v2, s4
	v_mov_b32_e32 v3, s5
	global_load_dwordx2 v[2:3], v[2:3], off offset:136
	s_waitcnt vmcnt(0) lgkmcnt(0)
	v_readlane_b32 s14, v254, 46
	v_readfirstlane_b32 s4, v0
	v_readfirstlane_b32 s5, v4
	v_readfirstlane_b32 s12, v2
	v_mov_b32_e32 v4, s4
	v_mov_b32_e32 v5, s5
	global_load_dwordx2 v[4:5], v[4:5], off offset:144
	v_readfirstlane_b32 s13, v3
	s_add_u32 s12, s12, s14
	v_readlane_b32 s14, v254, 45
	s_addc_u32 s13, s13, s14
	v_readlane_b32 s18, v254, 48
	s_mov_b64 s[4:5], 0x120000
	v_cmp_gt_u64_e32 vcc, s[4:5], v[62:63]
	s_waitcnt vmcnt(0) lgkmcnt(0)
	v_mov_b32_e32 v0, v5
	s_nop 0
	v_readfirstlane_b32 s14, v4
	v_readfirstlane_b32 s15, v0
	s_add_u32 s14, s14, s18
	v_readlane_b32 s18, v254, 47
	s_addc_u32 s15, s15, s18
	s_and_saveexec_b64 s[22:23], vcc
	s_cbranch_execz .LBB0_415
	s_add_u32 s24, s0, 0x19b00000
	s_addc_u32 s25, s1, 0
	s_add_u32 s26, s12, 0x1000
	s_addc_u32 s27, s13, 0
	s_add_u32 s28, s12, 0x1c00
	s_addc_u32 s29, s13, 0
	s_add_u32 s30, s12, 0x2800
	s_addc_u32 s31, s13, 0
	s_add_u32 s40, s12, 0x3400
	s_addc_u32 s41, s13, 0
	s_lshl_b64 s[4:5], s[8:9], 12
	v_lshl_add_u64 v[64:65], v[10:11], 3, s[4:5]
	s_mov_b64 s[8:9], 0
	v_mov_b64_e32 v[66:67], v[62:63]
	s_branch .LBB0_405
.LBB0_404:
	s_or_b64 exec, exec, s[38:39]
	v_lshlrev_b32_e32 v0, 2, v22
	v_lshl_add_u64 v[22:23], s[12:13], 0, v[0:1]
	v_lshl_add_u64 v[24:25], s[14:15], 0, v[0:1]
	global_load_dwordx4 v[26:29], v[22:23], off offset:1024
	global_load_dwordx4 v[30:33], v[24:25], off offset:1024
	global_load_dwordx4 v[46:49], v[24:25], off offset:1040
	global_load_dwordx4 v[54:57], v[22:23], off offset:1040
	v_lshl_add_u64 v[22:23], s[26:27], 0, v[0:1]
	global_load_dwordx4 v[50:53], v[22:23], off
	v_lshl_add_u64 v[34:35], s[28:29], 0, v[0:1]
	global_load_dwordx4 v[22:25], v[22:23], off offset:16
	s_nop 0
	global_load_dwordx4 v[58:61], v[34:35], off
	v_lshl_add_u64 v[38:39], s[30:31], 0, v[0:1]
	global_load_dwordx4 v[34:37], v[34:35], off offset:16
	s_nop 0
	global_load_dwordx4 v[72:75], v[38:39], off
	v_lshl_add_u64 v[42:43], s[40:41], 0, v[0:1]
	global_load_dwordx4 v[38:41], v[38:39], off offset:16
	s_nop 0
	global_load_dwordx4 v[76:79], v[42:43], off
	s_nop 0
	global_load_dwordx4 v[42:45], v[42:43], off offset:16
	s_waitcnt vmcnt(0) lgkmcnt(0)
	v_lshlrev_b32_e32 v80, 16, v10
	v_and_b32_e32 v81, 0xffff0000, v10
	v_lshlrev_b32_e32 v82, 16, v11
	v_and_b32_e32 v83, 0xffff0000, v11
	v_lshlrev_b32_e32 v84, 16, v12
	v_and_b32_e32 v85, 0xffff0000, v12
	v_lshlrev_b32_e32 v86, 16, v14
	v_and_b32_e32 v87, 0xffff0000, v14
	v_lshlrev_b32_e32 v14, 16, v15
	v_and_b32_e32 v15, 0xffff0000, v15
	v_lshlrev_b32_e32 v88, 16, v16
	v_and_b32_e32 v89, 0xffff0000, v16
	v_lshlrev_b32_e32 v10, 16, v17
	v_and_b32_e32 v11, 0xffff0000, v17
	v_lshlrev_b32_e32 v16, 16, v6
	v_and_b32_e32 v17, 0xffff0000, v6
	v_lshlrev_b32_e32 v90, 16, v7
	v_and_b32_e32 v91, 0xffff0000, v7
	v_lshlrev_b32_e32 v92, 16, v8
	v_and_b32_e32 v93, 0xffff0000, v8
	v_lshlrev_b32_e32 v94, 16, v18
	v_and_b32_e32 v95, 0xffff0000, v18
	v_lshlrev_b32_e32 v18, 16, v19
	v_and_b32_e32 v19, 0xffff0000, v19
	v_lshlrev_b32_e32 v6, 16, v9
	v_and_b32_e32 v7, 0xffff0000, v9
	v_lshlrev_b32_e32 v96, 16, v20
	v_and_b32_e32 v97, 0xffff0000, v20
	v_lshlrev_b32_e32 v8, 16, v21
	v_and_b32_e32 v9, 0xffff0000, v21
	v_lshlrev_b32_e32 v20, 16, v2
	v_and_b32_e32 v21, 0xffff0000, v2
	v_lshlrev_b32_e32 v2, 16, v3
	v_and_b32_e32 v3, 0xffff0000, v3
	v_lshlrev_b32_e32 v98, 16, v4
	v_and_b32_e32 v99, 0xffff0000, v4
	v_lshlrev_b32_e32 v12, 16, v13
	v_and_b32_e32 v13, 0xffff0000, v13
	v_lshl_add_u64 v[66:67], v[66:67], 0, s[60:61]
	s_mov_b64 s[4:5], 0x11ffff
	v_cmp_lt_u64_e32 vcc, s[4:5], v[66:67]
	v_readlane_b32 s4, v254, 22
	v_mov_b32_e32 v71, v1
	v_readlane_b32 s5, v254, 23
	s_or_b64 s[8:9], vcc, s[8:9]
	v_pk_fma_f32 v[26:27], v[26:27], v[80:81], v[30:31]
	v_pk_fma_f32 v[28:29], v[28:29], v[82:83], v[32:33]
	v_pk_fma_f32 v[30:31], v[54:55], v[84:85], v[46:47]
	v_pk_fma_f32 v[12:13], v[56:57], v[12:13], v[48:49]
	v_pk_fma_f32 v[26:27], v[50:51], v[86:87], v[26:27]
	v_pk_fma_f32 v[14:15], v[52:53], v[14:15], v[28:29]
	v_pk_fma_f32 v[22:23], v[22:23], v[88:89], v[30:31]
	v_pk_fma_f32 v[16:17], v[58:59], v[16:17], v[26:27]
	v_pk_fma_f32 v[14:15], v[60:61], v[90:91], v[14:15]
	v_pk_fma_f32 v[22:23], v[34:35], v[92:93], v[22:23]
	v_pk_fma_f32 v[16:17], v[72:73], v[94:95], v[16:17]
	v_pk_fma_f32 v[14:15], v[74:75], v[18:19], v[14:15]
	v_pk_fma_f32 v[18:19], v[38:39], v[96:97], v[22:23]
	v_pk_fma_f32 v[16:17], v[76:77], v[20:21], v[16:17]
	v_pk_fma_f32 v[2:3], v[78:79], v[2:3], v[14:15]
	v_pk_fma_f32 v[14:15], v[42:43], v[98:99], v[18:19]
	v_mul_f32_e32 v0, 0xbfb8aa3b, v16
	v_mul_f32_e32 v4, 0xbfb8aa3b, v17
	v_mul_f32_e32 v18, 0xbfb8aa3b, v2
	v_mul_f32_e32 v19, 0xbfb8aa3b, v3
	v_mul_f32_e32 v20, 0xbfb8aa3b, v14
	v_exp_f32_e32 v0, v0
	v_exp_f32_e32 v4, v4
	v_exp_f32_e32 v18, v18
	v_exp_f32_e32 v19, v19
	v_exp_f32_e32 v20, v20
	v_mul_f32_e32 v21, 0xbfb8aa3b, v15
	v_exp_f32_e32 v22, v21
	v_add_f32_e32 v0, 1.0, v0
	v_add_f32_e32 v4, 1.0, v4
	v_add_f32_e32 v21, 1.0, v18
	v_add_f32_e32 v23, 1.0, v19
	v_add_f32_e32 v26, 1.0, v20
	v_rcp_f32_e32 v18, v0
	v_rcp_f32_e32 v19, v4
	v_rcp_f32_e32 v20, v21
	v_rcp_f32_e32 v21, v23
	v_pk_fma_f32 v[10:11], v[24:25], v[10:11], v[12:13]
	v_pk_mul_f32 v[16:17], v[16:17], v[18:19]
	v_pk_fma_f32 v[6:7], v[36:37], v[6:7], v[10:11]
	v_pk_mul_f32 v[18:19], v[2:3], v[20:21]
	v_pk_fma_f32 v[6:7], v[40:41], v[8:9], v[6:7]
	v_lshlrev_b32_e32 v8, 16, v5
	v_and_b32_e32 v9, 0xffff0000, v5
	v_pk_fma_f32 v[6:7], v[44:45], v[8:9], v[6:7]
	v_add_f32_e32 v0, 1.0, v22
	v_mul_f32_e32 v3, 0xbfb8aa3b, v6
	v_exp_f32_e32 v3, v3
	v_mul_f32_e32 v5, 0xbfb8aa3b, v7
	v_exp_f32_e32 v9, v5
	v_rcp_f32_e32 v5, v0
	v_add_f32_e32 v0, 1.0, v3
	v_rcp_f32_e32 v8, v0
	v_add_f32_e32 v0, 1.0, v9
	v_rcp_f32_e32 v4, v26
	v_rcp_f32_e32 v9, v0
	v_cvt_pk_bf16_f32 v2, v16, v17
	v_cvt_pk_bf16_f32 v3, v18, v19
	v_pk_mul_f32 v[4:5], v[14:15], v[4:5]
	v_pk_mul_f32 v[6:7], v[6:7], v[8:9]
	v_cvt_pk_bf16_f32 v4, v4, v5
	v_cvt_pk_bf16_f32 v5, v6, v7
	v_lshlrev_b64 v[6:7], 10, v[68:69]
	v_lshl_add_u64 v[6:7], s[24:25], 0, v[6:7]
	v_lshl_add_u64 v[6:7], v[6:7], 0, v[70:71]
	v_lshl_add_u64 v[64:65], v[64:65], 0, s[4:5]
	global_store_dwordx4 v[6:7], v[2:5], off
	s_andn2_b64 exec, exec, s[8:9]
	s_cbranch_execz .LBB0_415
.LBB0_405:
	s_mov_b64 s[4:5], 0x100000
	v_mov_b32_e32 v2, 0xff
	v_mov_b32_e32 v3, 0x7ff
	v_cmp_gt_u64_e32 vcc, s[4:5], v[66:67]
	v_alignbit_b32 v0, v67, v66, 6
	v_lshrrev_b64 v[68:69], 6, v[66:67]
	v_cndmask_b32_e32 v2, v2, v3, vcc
	v_and_b32_e32 v3, v2, v0
	v_bfrev_b32_e32 v0, 4.0
	v_mov_b32_e32 v2, 0x802
	v_cndmask_b32_e32 v4, v0, v2, vcc
	v_and_b32_e32 v22, 0x1f8, v64
	v_cmp_lt_u32_e32 vcc, 1, v3
	v_cmp_lt_u32_e64 s[38:39], v3, v4
	s_movk_i32 s18, 0x1800
	s_and_b64 s[4:5], vcc, s[38:39]
	v_mov_b32_e32 v6, 0
	v_mul_lo_u32 v0, v68, s18
	v_lshlrev_b32_e32 v70, 1, v22
	v_mov_b32_e32 v10, 0
	v_mov_b32_e32 v11, 0
	v_mov_b32_e32 v12, 0
	v_mov_b32_e32 v13, 0
	s_and_saveexec_b64 s[38:39], s[4:5]
	s_cbranch_execz .LBB0_407
	v_lshl_add_u64 v[8:9], v[0:1], 1, s[6:7]
	v_mov_b32_e32 v71, v1
	v_lshl_add_u64 v[8:9], v[8:9], 0, v[70:71]
	v_add_co_u32_e32 v8, vcc, 0xffffac00, v8
	s_nop 1
	v_addc_co_u32_e32 v9, vcc, -1, v9, vcc
	global_load_dwordx4 v[10:13], v[8:9], off
.LBB0_407:
	s_or_b64 exec, exec, s[38:39]
	v_add_u32_e32 v2, 1, v3
	v_cmp_ne_u32_e32 vcc, 0, v3
	v_cmp_lt_u32_e64 s[38:39], v2, v4
	s_and_b64 s[4:5], vcc, s[38:39]
	v_mov_b32_e32 v14, 0
	v_mov_b32_e32 v15, 0
	v_mov_b32_e32 v16, 0
	v_mov_b32_e32 v17, 0
	s_and_saveexec_b64 s[38:39], s[4:5]
	s_cbranch_execz .LBB0_409
	v_add_u32_e32 v8, 0x1800, v0
	v_mov_b32_e32 v9, v1
	v_lshl_add_u64 v[8:9], v[8:9], 1, s[6:7]
	v_mov_b32_e32 v71, v1
	v_lshl_add_u64 v[8:9], v[8:9], 0, v[70:71]
	v_add_co_u32_e32 v8, vcc, 0xffffac00, v8
	s_nop 1
	v_addc_co_u32_e32 v9, vcc, -1, v9, vcc
	global_load_dwordx4 v[14:17], v[8:9], off
.LBB0_409:
	s_or_b64 exec, exec, s[38:39]
	v_add_u32_e32 v2, 2, v3
	v_cmp_lt_u32_e32 vcc, v2, v4
	v_mov_b32_e32 v7, 0
	v_mov_b32_e32 v8, 0
	v_mov_b32_e32 v9, 0
	s_and_saveexec_b64 s[38:39], vcc
	s_cbranch_execz .LBB0_411
	v_add_u32_e32 v6, 0x3000, v0
	v_mov_b32_e32 v7, v1
	v_lshl_add_u64 v[6:7], v[6:7], 1, s[6:7]
	v_mov_b32_e32 v71, v1
	v_lshl_add_u64 v[6:7], v[6:7], 0, v[70:71]
	v_add_co_u32_e32 v6, vcc, 0xffffac00, v6
	s_nop 1
	v_addc_co_u32_e32 v7, vcc, -1, v7, vcc
	global_load_dwordx4 v[6:9], v[6:7], off
.LBB0_411:
	s_or_b64 exec, exec, s[38:39]
	v_add_u32_e32 v2, 3, v3
	v_cmp_lt_u32_e32 vcc, v2, v4
	v_mov_b32_e32 v2, 0
	v_mov_b32_e32 v18, 0
	v_mov_b32_e32 v19, 0
	v_mov_b32_e32 v20, 0
	v_mov_b32_e32 v21, 0
	s_and_saveexec_b64 s[38:39], vcc
	s_cbranch_execz .LBB0_413
	v_add_u32_e32 v18, 0x4800, v0
	v_mov_b32_e32 v19, v1
	v_lshl_add_u64 v[18:19], v[18:19], 1, s[6:7]
	v_mov_b32_e32 v71, v1
	v_lshl_add_u64 v[18:19], v[18:19], 0, v[70:71]
	v_add_co_u32_e32 v18, vcc, 0xffffac00, v18
	s_nop 1
	v_addc_co_u32_e32 v19, vcc, -1, v19, vcc
	global_load_dwordx4 v[18:21], v[18:19], off
.LBB0_413:
	s_or_b64 exec, exec, s[38:39]
	v_add_u32_e32 v3, 4, v3
	v_cmp_lt_u32_e32 vcc, v3, v4
	v_mov_b32_e32 v3, 0
	v_mov_b32_e32 v4, 0
	v_mov_b32_e32 v5, 0
	s_and_saveexec_b64 s[38:39], vcc
	s_cbranch_execz .LBB0_404
	v_add_u32_e32 v0, 0x6000, v0
	v_lshl_add_u64 v[2:3], v[0:1], 1, s[6:7]
	v_mov_b32_e32 v71, v1
	v_lshl_add_u64 v[2:3], v[2:3], 0, v[70:71]
	v_add_co_u32_e32 v2, vcc, 0xffffac00, v2
	s_nop 1
	v_addc_co_u32_e32 v3, vcc, -1, v3, vcc
	global_load_dwordx4 v[2:5], v[2:3], off
	s_branch .LBB0_404

.LBB0_417:
	s_or_b64 exec, exec, s[26:27]
	v_lshlrev_b32_e32 v0, 2, v19
	v_lshl_add_u64 v[14:15], s[12:13], 0, v[0:1]
	v_lshl_add_u64 v[20:21], s[14:15], 0, v[0:1]
	global_load_dword v0, v[20:21], off
	global_load_dword v10, v[14:15], off
	global_load_dword v12, v[14:15], off offset:3072
	v_add_co_u32_e32 v20, vcc, s83, v14
	s_movk_i32 s0, 0x2000
	s_nop 0
	v_addc_co_u32_e32 v21, vcc, 0, v15, vcc
	global_load_dword v16, v[20:21], off offset:2048
	v_add_co_u32_e32 v20, vcc, s0, v14
	s_waitcnt vmcnt(0) lgkmcnt(0)
	v_lshlrev_b32_e32 v32, 16, v8
	v_addc_co_u32_e32 v21, vcc, 0, v15, vcc
	v_add_co_u32_e32 v14, vcc, s2, v14
	global_load_dword v18, v[20:21], off offset:1024
	s_nop 0
	v_addc_co_u32_e32 v15, vcc, 0, v15, vcc
	global_load_dword v20, v[14:15], off
	v_and_b32_e32 v33, 0xffff0000, v8
	v_and_b32_e32 v8, 0xffff0000, v4
	v_lshlrev_b32_e32 v36, 16, v6
	v_and_b32_e32 v37, 0xffff0000, v6
	v_lshlrev_b32_e32 v30, 16, v7
	v_and_b32_e32 v31, 0xffff0000, v7
	v_lshlrev_b32_e32 v28, 16, v9
	v_and_b32_e32 v29, 0xffff0000, v9
	v_and_b32_e32 v9, 16, v5
	v_lshlrev_b32_e32 v7, 16, v5
	v_mov_b32_e32 v6, v8
	v_pk_mov_b32 v[34:35], v[6:7], v[8:9] op_sel:[1,0]
	v_lshlrev_b32_e32 v24, 16, v2
	v_and_b32_e32 v25, 0xffff0000, v2
	v_lshlrev_b32_e32 v22, 16, v3
	v_and_b32_e32 v23, 0xffff0000, v3
	v_lshlrev_b32_e32 v2, 16, v4
	v_pk_mov_b32 v[38:39], v[26:27], v[36:37] op_sel:[1,0]
	v_pk_mov_b32 v[40:41], v[36:37], v[30:31] op_sel:[1,0]
	v_mov_b32_e32 v3, v35
	v_and_b32_e32 v35, 0xffff0000, v5
	v_pk_mov_b32 v[42:43], v[30:31], v[32:33] op_sel:[1,0]
	v_pk_mov_b32 v[44:45], v[32:33], v[28:29] op_sel:[1,0]
	v_pk_mov_b32 v[46:47], v[28:29], v[24:25] op_sel:[1,0]
	v_mul_hi_u32_u24_e32 v15, 0x9000, v19
	v_mul_u32_u24_e32 v14, 0x9000, v19
	v_lshl_add_u64 v[62:63], v[62:63], 0, s[60:61]
	s_mov_b64 s[0:1], 0x8ffff
	v_cmp_lt_u64_e32 vcc, s[0:1], v[62:63]
	s_or_b64 s[24:25], vcc, s[24:25]
	v_pk_fma_f32 v[4:5], v[26:27], v[10:11], v[0:1] op_sel_hi:[1,0,0]
	v_pk_fma_f32 v[26:27], v[10:11], v[36:37], v[0:1] op_sel_hi:[0,1,0]
	v_pk_fma_f32 v[48:49], v[10:11], v[30:31], v[0:1] op_sel_hi:[0,1,0]
	v_pk_fma_f32 v[50:51], v[10:11], v[32:33], v[0:1] op_sel_hi:[0,1,0]
	v_pk_fma_f32 v[26:27], v[12:13], v[40:41], v[26:27] op_sel_hi:[0,1,1]
	v_pk_fma_f32 v[4:5], v[38:39], v[12:13], v[4:5] op_sel_hi:[1,0,1]
	v_pk_fma_f32 v[38:39], v[12:13], v[42:43], v[48:49] op_sel_hi:[0,1,1]
	v_pk_fma_f32 v[48:49], v[12:13], v[44:45], v[50:51] op_sel_hi:[0,1,1]
	v_pk_fma_f32 v[26:27], v[16:17], v[30:31], v[26:27] op_sel_hi:[0,1,1]
	v_pk_fma_f32 v[4:5], v[16:17], v[36:37], v[4:5] op_sel_hi:[0,1,1]
	v_pk_fma_f32 v[36:37], v[16:17], v[32:33], v[38:39] op_sel_hi:[0,1,1]
	v_pk_fma_f32 v[38:39], v[16:17], v[28:29], v[48:49] op_sel_hi:[0,1,1]
	s_waitcnt vmcnt(0) lgkmcnt(0)
	v_pk_fma_f32 v[26:27], v[18:19], v[42:43], v[26:27] op_sel_hi:[0,1,1]
	v_pk_fma_f32 v[4:5], v[18:19], v[40:41], v[4:5] op_sel_hi:[0,1,1]
	v_pk_fma_f32 v[36:37], v[18:19], v[44:45], v[36:37] op_sel_hi:[0,1,1]
	v_pk_fma_f32 v[38:39], v[18:19], v[46:47], v[38:39] op_sel_hi:[0,1,1]
	v_pk_fma_f32 v[26:27], v[20:21], v[32:33], v[26:27] op_sel_hi:[0,1,1]
	v_pk_fma_f32 v[4:5], v[20:21], v[30:31], v[4:5] op_sel_hi:[0,1,1]
	v_pk_fma_f32 v[30:31], v[20:21], v[28:29], v[36:37] op_sel_hi:[0,1,1]
	v_pk_fma_f32 v[32:33], v[20:21], v[24:25], v[38:39] op_sel_hi:[0,1,1]
	v_mul_f32_e32 v21, 0xbfb8aa3b, v26
	v_mul_f32_e32 v36, 0xbfb8aa3b, v27
	v_mul_f32_e32 v38, 0xbfb8aa3b, v31
	v_exp_f32_e32 v21, v21
	v_exp_f32_e32 v36, v36
	v_exp_f32_e32 v38, v38
	v_mul_f32_e32 v9, 0xbfb8aa3b, v4
	v_mul_f32_e32 v19, 0xbfb8aa3b, v5
	v_mul_f32_e32 v37, 0xbfb8aa3b, v30
	v_mul_f32_e32 v39, 0xbfb8aa3b, v32
	v_exp_f32_e32 v9, v9
	v_exp_f32_e32 v19, v19
	v_exp_f32_e32 v37, v37
	v_exp_f32_e32 v43, v39
	v_add_f32_e32 v21, 1.0, v21
	v_add_f32_e32 v39, 1.0, v36
	v_add_f32_e32 v41, 1.0, v38
	v_rcp_f32_e32 v38, v21
	v_rcp_f32_e32 v39, v39
	v_mul_f32_e32 v42, 0xbfb8aa3b, v33
	v_add_f32_e32 v9, 1.0, v9
	v_add_f32_e32 v19, 1.0, v19
	v_pk_fma_f32 v[28:29], v[10:11], v[28:29], v[0:1] op_sel_hi:[0,1,0]
	v_add_f32_e32 v40, 1.0, v37
	v_rcp_f32_e32 v36, v9
	v_rcp_f32_e32 v37, v19
	v_exp_f32_e32 v9, v42
	v_pk_fma_f32 v[28:29], v[12:13], v[46:47], v[28:29] op_sel_hi:[0,1,1]
	v_pk_mul_f32 v[26:27], v[26:27], v[38:39]
	v_add_f32_e32 v19, 1.0, v43
	v_pk_fma_f32 v[28:29], v[16:17], v[24:25], v[28:29] op_sel_hi:[0,1,1]
	v_pk_mov_b32 v[38:39], v[24:25], v[22:23] op_sel:[1,0]
	v_pk_mul_f32 v[4:5], v[4:5], v[36:37]
	v_pk_fma_f32 v[28:29], v[18:19], v[38:39], v[28:29] op_sel_hi:[0,1,1]
	v_pk_fma_f32 v[28:29], v[20:21], v[22:23], v[28:29] op_sel_hi:[0,1,1]
	v_rcp_f32_e32 v36, v19
	v_add_f32_e32 v9, 1.0, v9
	v_mul_f32_e32 v19, 0xbfb8aa3b, v29
	v_rcp_f32_e32 v40, v40
	v_rcp_f32_e32 v41, v41
	v_rcp_f32_e32 v37, v9
	v_mul_f32_e32 v9, 0xbfb8aa3b, v28
	v_exp_f32_e32 v19, v19
	v_exp_f32_e32 v9, v9
	v_pk_fma_f32 v[24:25], v[10:11], v[24:25], v[0:1] op_sel_hi:[0,1,0]
	v_pk_fma_f32 v[24:25], v[12:13], v[38:39], v[24:25] op_sel_hi:[0,1,1]
	v_pk_fma_f32 v[24:25], v[16:17], v[22:23], v[24:25] op_sel_hi:[0,1,1]
	v_pk_mov_b32 v[38:39], v[22:23], v[2:3] op_sel:[1,0]
	v_pk_mul_f32 v[30:31], v[30:31], v[40:41]
	v_pk_fma_f32 v[24:25], v[18:19], v[38:39], v[24:25] op_sel_hi:[0,1,1]
	v_mov_b32_e32 v40, v2
	v_mov_b32_e32 v41, v8
	v_add_f32_e32 v9, 1.0, v9
	v_pk_fma_f32 v[24:25], v[20:21], v[40:41], v[24:25] op_sel_hi:[0,1,1]
	v_pk_mul_f32 v[32:33], v[32:33], v[36:37]
	v_rcp_f32_e32 v36, v9
	v_add_f32_e32 v9, 1.0, v19
	v_mul_f32_e32 v19, 0xbfb8aa3b, v24
	v_exp_f32_e32 v19, v19
	v_mul_f32_e32 v21, 0xbfb8aa3b, v25
	v_exp_f32_e32 v21, v21
	v_pk_fma_f32 v[22:23], v[10:11], v[22:23], v[0:1] op_sel_hi:[0,1,0]
	v_rcp_f32_e32 v37, v9
	v_add_f32_e32 v9, 1.0, v19
	v_pk_fma_f32 v[22:23], v[12:13], v[38:39], v[22:23] op_sel_hi:[0,1,1]
	v_rcp_f32_e32 v42, v9
	v_add_f32_e32 v19, 1.0, v21
	v_pk_fma_f32 v[22:23], v[16:17], v[40:41], v[22:23] op_sel_hi:[0,1,1]
	v_mov_b32_e32 v9, v34
	v_pk_fma_f32 v[8:9], v[18:19], v[8:9], v[22:23] op_sel_hi:[0,1,1]
	v_pk_fma_f32 v[8:9], v[20:21], v[34:35], v[8:9] op_sel_hi:[0,1,1]
	v_mul_f32_e32 v21, 0xbfb8aa3b, v8
	v_exp_f32_e32 v21, v21
	v_mul_f32_e32 v22, 0xbfb8aa3b, v9
	v_exp_f32_e32 v23, v22
	v_pk_fma_f32 v[2:3], v[10:11], v[2:3], v[0:1] op_sel_hi:[0,1,0]
	v_rcp_f32_e32 v43, v19
	v_add_f32_e32 v19, 1.0, v21
	v_pk_fma_f32 v[2:3], v[12:13], v[6:7], v[2:3] op_sel_hi:[0,1,1]
	v_rcp_f32_e32 v22, v19
	v_add_f32_e32 v19, 1.0, v23
	v_pk_fma_f32 v[2:3], v[16:17], v[34:35], v[2:3] op_sel_hi:[0,1,1]
	v_mov_b32_e32 v10, v35
	v_pk_fma_f32 v[2:3], v[18:19], v[10:11], v[2:3] op_sel_hi:[0,1,1]
	v_mov_b32_e32 v12, v11
	v_pk_fma_f32 v[2:3], v[12:13], v[20:21], v[2:3] op_sel_hi:[1,0,1]
	v_rcp_f32_e32 v23, v19
	v_mul_f32_e32 v0, 0xbfb8aa3b, v2
	v_exp_f32_e32 v0, v0
	v_mul_f32_e32 v6, 0xbfb8aa3b, v3
	v_exp_f32_e32 v7, v6
	v_pk_mul_f32 v[10:11], v[28:29], v[36:37]
	v_add_f32_e32 v0, 1.0, v0
	v_rcp_f32_e32 v6, v0
	v_add_f32_e32 v0, 1.0, v7
	v_rcp_f32_e32 v7, v0
	v_pk_mul_f32 v[12:13], v[24:25], v[42:43]
	v_pk_mul_f32 v[8:9], v[8:9], v[22:23]
	v_lshlrev_b32_e32 v0, 1, v17
	v_pk_mul_f32 v[18:19], v[2:3], v[6:7]
	v_cvt_pk_bf16_f32 v6, v10, v11
	v_lshl_add_u64 v[10:11], s[8:9], 0, v[14:15]
	v_cvt_pk_bf16_f32 v2, v4, v5
	v_cvt_pk_bf16_f32 v3, v26, v27
	v_cvt_pk_bf16_f32 v4, v30, v31
	v_cvt_pk_bf16_f32 v5, v32, v33
	v_cvt_pk_bf16_f32 v7, v12, v13
	v_cvt_pk_bf16_f32 v8, v8, v9
	v_cvt_pk_bf16_f32 v9, v18, v19
	v_lshl_add_u64 v[10:11], v[10:11], 0, v[0:1]
	global_store_dwordx4 v[10:11], v[2:5], off
	global_store_dwordx4 v[10:11], v[6:9], off offset:16
	s_andn2_b64 exec, exec, s[24:25]
	s_cbranch_execz .LBB0_424
.LBB0_418:
	s_mov_b32 s0, 0x38e38e39
	v_mul_hi_u32 v0, v62, s0
	v_lshrrev_b32_e32 v19, 8, v0
	v_mul_u32_u24_e32 v0, 0x480, v19
	v_sub_u32_e32 v10, v62, v0
	v_mov_b64_e32 v[2:3], s[22:23]
	s_mov_b32 s0, 0x9000
	v_mad_u64_u32 v[2:3], s[0:1], v19, s0, v[2:3]
	v_lshlrev_b32_e32 v0, 5, v10
	v_lshl_add_u64 v[14:15], v[2:3], 0, v[0:1]
	global_load_dwordx4 v[6:9], v[14:15], off
	global_load_dwordx4 v[2:5], v[14:15], off offset:16
	s_movk_i32 s0, 0x400
	v_mov_b32_e32 v0, 0xf0
	v_mov_b32_e32 v11, 0x7f0
	v_cmp_gt_u32_e32 vcc, s0, v10
	v_lshlrev_b32_e32 v17, 4, v10
	v_mov_b32_e32 v26, 0
	v_cndmask_b32_e32 v0, v0, v11, vcc
	v_and_b32_e32 v0, v0, v17
	v_cmp_ne_u32_e64 s[38:39], 0, v0
	v_mov_b32_e32 v11, 0
	v_mov_b32_e32 v27, 0
	s_and_saveexec_b64 s[26:27], s[38:39]
	s_cbranch_execz .LBB0_420
	v_add_co_u32_e64 v12, s[38:39], -4, v14
	s_nop 1
	v_addc_co_u32_e64 v13, s[38:39], -1, v15, s[38:39]
	global_load_dword v10, v[12:13], off
	s_waitcnt vmcnt(0) lgkmcnt(0)
	v_and_b32_e32 v27, 0xffff0000, v10
	v_lshlrev_b32_e32 v26, 16, v10
.LBB0_420:
	s_or_b64 exec, exec, s[26:27]
	v_mov_b32_e32 v10, 0x100
	v_cndmask_b32_e32 v10, v10, v163, vcc
	v_add_u32_e32 v12, 16, v0
	v_cmp_lt_u32_e32 vcc, v12, v10
	s_and_saveexec_b64 s[26:27], vcc
	s_cbranch_execz .LBB0_422
	global_load_ushort v11, v[14:15], off offset:32
	s_waitcnt vmcnt(0) lgkmcnt(0)
	v_lshlrev_b32_e32 v11, 16, v11
.LBB0_422:
	s_or_b64 exec, exec, s[26:27]
	v_add_u32_e32 v0, 17, v0
	v_cmp_lt_u32_e32 vcc, v0, v10
	v_mov_b32_e32 v13, 0
	s_and_saveexec_b64 s[26:27], vcc
	s_cbranch_execz .LBB0_417
	global_load_ushort v0, v[14:15], off offset:34
	s_waitcnt vmcnt(0) lgkmcnt(0)
	v_lshlrev_b32_e32 v13, 16, v0
	s_branch .LBB0_417

.LBB0_429:
	v_readlane_b32 s4, v253, 9
	v_readlane_b32 s5, v253, 10
	v_readlane_b32 s1, v253, 6
	s_or_b64 s[22:23], s[22:23], exec
	v_mov_b64_e32 v[2:3], s[4:5]
	v_readlane_b32 s4, v253, 11
	v_readlane_b32 s5, v253, 12
	s_waitcnt lgkmcnt(0)
	global_load_dword v0, v[2:3], off sc1
	s_or_b64 s[14:15], s[14:15], exec
	v_mov_b64_e32 v[2:3], s[4:5]
	v_readlane_b32 s4, v253, 13
	v_readlane_b32 s5, v253, 14
	global_load_dword v2, v[2:3], off sc1
	s_nop 0
	v_mov_b64_e32 v[4:5], s[4:5]
	v_readlane_b32 s4, v253, 15
	v_readlane_b32 s5, v253, 16
	global_load_dword v3, v[4:5], off sc1
	s_nop 0
	v_mov_b64_e32 v[4:5], s[4:5]
	v_readlane_b32 s4, v253, 17
	v_readlane_b32 s5, v253, 18
	global_load_dword v4, v[4:5], off sc1
	s_nop 0
	v_mov_b64_e32 v[6:7], s[4:5]
	v_readlane_b32 s4, v253, 19
	v_readlane_b32 s5, v253, 20
	global_load_dword v5, v[6:7], off sc1
	s_nop 0
	v_mov_b64_e32 v[6:7], s[4:5]
	v_readlane_b32 s4, v253, 21
	v_readlane_b32 s5, v253, 22
	global_load_dword v6, v[6:7], off sc1
	s_nop 0
	v_mov_b64_e32 v[8:9], s[4:5]
	v_readlane_b32 s4, v253, 23
	v_readlane_b32 s5, v253, 24
	global_load_dword v7, v[8:9], off sc1
	s_nop 0
	v_mov_b64_e32 v[8:9], s[4:5]
	v_readlane_b32 s4, v253, 25
	v_readlane_b32 s5, v253, 26
	global_load_dword v8, v[8:9], off sc1
	s_nop 0
	v_mov_b64_e32 v[10:11], s[4:5]
	v_readlane_b32 s4, v253, 27
	v_readlane_b32 s5, v253, 28
	global_load_dword v9, v[10:11], off sc1
	s_nop 0
	v_mov_b64_e32 v[10:11], s[4:5]
	v_readlane_b32 s4, v253, 29
	v_readlane_b32 s5, v253, 30
	global_load_dword v10, v[10:11], off sc1
	s_nop 0
	v_mov_b64_e32 v[12:13], s[4:5]
	v_readlane_b32 s4, v253, 31
	v_readlane_b32 s5, v253, 32
	global_load_dword v11, v[12:13], off sc1
	s_nop 0
	v_mov_b64_e32 v[12:13], s[4:5]
	v_readlane_b32 s4, v253, 33
	v_readlane_b32 s5, v253, 34
	global_load_dword v12, v[12:13], off sc1
	s_nop 0
	v_mov_b64_e32 v[14:15], s[4:5]
	v_readlane_b32 s4, v253, 35
	v_readlane_b32 s5, v253, 36
	global_load_dword v13, v[14:15], off sc1
	s_nop 0
	v_mov_b64_e32 v[14:15], s[4:5]
	v_readlane_b32 s4, v253, 37
	v_readlane_b32 s5, v253, 38
	global_load_dword v14, v[14:15], off sc1
	s_nop 0
	v_mov_b64_e32 v[16:17], s[4:5]
	v_readlane_b32 s4, v253, 39
	v_readlane_b32 s5, v253, 40
	global_load_dword v15, v[16:17], off sc1
	s_nop 0
	v_mov_b64_e32 v[16:17], s[4:5]
	global_load_dword v16, v[16:17], off sc1
	s_waitcnt vmcnt(0) lgkmcnt(0)
	v_add_u32_e32 v17, v2, v0
	v_add_u32_e32 v17, v17, v3
	v_add_u32_e32 v17, v17, v4
	v_add_u32_e32 v17, v17, v5
	v_add_u32_e32 v17, v17, v6
	v_add_u32_e32 v17, v17, v7
	v_add_u32_e32 v17, v17, v8
	v_add_u32_e32 v17, v17, v9
	v_add_u32_e32 v17, v17, v10
	v_add_u32_e32 v17, v17, v11
	v_add_u32_e32 v17, v17, v12
	v_add_u32_e32 v17, v17, v13
	v_add_u32_e32 v17, v17, v14
	v_add_u32_e32 v17, v17, v15
	v_add_u32_e32 v17, v17, v16
	v_cmp_ne_u32_e32 vcc, s1, v17
	s_and_saveexec_b64 s[24:25], vcc
	s_cbranch_execz .LBB0_428
	s_and_b32 s1, s0, 0xff
	s_mov_b64 s[26:27], -1
	s_cmp_eq_u32 s1, 0
	s_mov_b64 s[30:31], -1
	s_mov_b64 s[28:29], -1
	s_sleep 1
	s_cbranch_scc1 .LBB0_432
	s_and_saveexec_b64 s[38:39], s[30:31]
	s_cbranch_execz .LBB0_427
	s_branch .LBB0_435
.LBB0_432:
	v_readlane_b32 s4, v253, 7
	v_readlane_b32 s5, v253, 8
	s_mov_b64 s[30:31], 0
	s_nop 0
	v_mov_b64_e32 v[18:19], s[4:5]
	global_load_dword v17, v[18:19], off sc1
	s_waitcnt vmcnt(0) lgkmcnt(0)
	v_cmp_eq_u32_e32 vcc, 0, v17
	s_and_saveexec_b64 s[38:39], vcc
	s_cmp_lt_u32 s0, 0x40001
	s_cselect_b64 s[4:5], -1, 0
	s_xor_b64 s[28:29], exec, -1
	s_and_b64 s[30:31], s[4:5], exec
	s_or_b64 exec, exec, s[38:39]
	s_and_saveexec_b64 s[38:39], s[30:31]
	s_cbranch_execz .LBB0_427

.LBB0_436:
	s_or_b64 exec, exec, s[12:13]
	s_xor_b64 s[0:1], s[14:15], -1
	s_and_saveexec_b64 s[4:5], s[0:1]
	s_xor_b64 s[12:13], exec, s[4:5]
	s_cbranch_execz .LBB0_438
	v_readlane_b32 s0, v253, 7
	v_readlane_b32 s1, v253, 8
	s_nop 1
	v_mov_b64_e32 v[18:19], s[0:1]
	global_atomic_add v[18:19], v166, off

.LBB0_439:
	v_readlane_b32 s0, v254, 9
	v_readlane_b32 s1, v254, 10
	v_cvt_f32_u32_e32 v3, v2
	v_rcp_iflag_f32_e32 v3, v3
	v_mov_b64_e32 v[4:5], s[0:1]
	global_atomic_add v4, v[4:5], v166, off sc0
	v_sub_u32_e32 v5, 0, v2
	v_mul_f32_e32 v3, 0x4f7ffffe, v3
	v_cvt_u32_f32_e32 v3, v3
	v_mul_lo_u32 v5, v5, v3
	v_mul_hi_u32 v5, v3, v5
	v_add_u32_e32 v3, v3, v5
	s_waitcnt vmcnt(0) lgkmcnt(0)
	v_mul_hi_u32 v3, v4, v3
	v_mul_lo_u32 v5, v3, v2
	v_sub_u32_e32 v5, v4, v5
	v_cmp_ge_u32_e32 vcc, v5, v2
	v_add_u32_e32 v6, 1, v3
	s_nop 0
	v_cndmask_b32_e32 v3, v3, v6, vcc
	v_sub_u32_e32 v6, v5, v2
	v_cndmask_b32_e32 v5, v5, v6, vcc
	v_cmp_ge_u32_e32 vcc, v5, v2
	v_add_u32_e32 v5, 1, v3
	v_add_u32_e32 v6, 1, v4
	v_cndmask_b32_e32 v3, v3, v5, vcc
	v_mad_u64_u32 v[4:5], s[0:1], v2, v3, v[2:3]
	v_cmp_ne_u32_e32 vcc, v6, v4
	s_and_saveexec_b64 s[0:1], vcc
	s_xor_b64 s[12:13], exec, s[0:1]
	s_cbranch_execz .LBB0_465
	v_readlane_b32 s0, v254, 11
	v_readlane_b32 s1, v254, 12
	s_nop 1
	v_mov_b64_e32 v[4:5], s[0:1]
	global_load_dword v0, v[4:5], off sc1
	s_waitcnt vmcnt(0) lgkmcnt(0)
	v_cmp_eq_u32_e32 vcc, v0, v3
	s_and_saveexec_b64 s[14:15], vcc
	s_cbranch_execz .LBB0_464
	s_mov_b32 s0, 1
	s_mov_b64 s[22:23], 0
	s_branch .LBB0_443

.LBB0_443:
	s_and_b32 s1, s0, 0xff
	s_mov_b64 s[28:29], -1
	s_cmp_lg_u32 s1, 0
	s_mov_b64 s[30:31], -1
	s_sleep 1
	s_cbranch_scc1 .LBB0_447
	v_readlane_b32 s4, v253, 7
	v_readlane_b32 s5, v253, 8
	s_mov_b64 s[30:31], 0
	s_mov_b64 s[38:39], -1
	v_mov_b64_e32 v[4:5], s[4:5]
	global_load_dword v0, v[4:5], off sc1
	s_waitcnt vmcnt(0) lgkmcnt(0)
	v_cmp_eq_u32_e32 vcc, 0, v0
	s_and_saveexec_b64 s[40:41], vcc
	s_cmp_lt_u32 s0, 0x40001
	s_cselect_b64 s[4:5], -1, 0
	s_xor_b64 s[38:39], exec, -1
	s_and_b64 s[30:31], s[4:5], exec
	s_or_b64 exec, exec, s[40:41]
.LBB0_447:
	s_andn2_b64 s[4:5], s[26:27], exec
	s_and_b64 s[20:21], s[38:39], exec
	s_or_b64 s[26:27], s[4:5], s[20:21]
	s_and_saveexec_b64 s[38:39], s[30:31]
	s_cbranch_execz .LBB0_442
	v_readlane_b32 s4, v254, 11
	v_readlane_b32 s5, v254, 12
	s_add_i32 s0, s0, 1
	s_or_b64 s[26:27], s[26:27], exec
	v_mov_b64_e32 v[4:5], s[4:5]
	global_load_dword v0, v[4:5], off sc1
	s_waitcnt vmcnt(0) lgkmcnt(0)
	v_cmp_ne_u32_e32 vcc, v0, v3
	s_orn2_b64 s[28:29], vcc, exec
	s_branch .LBB0_442
.LBB0_449:
	s_or_b64 exec, exec, s[8:9]
	s_xor_b64 s[0:1], s[12:13], -1
	s_and_saveexec_b64 s[4:5], s[0:1]
	s_xor_b64 s[8:9], exec, s[4:5]
	s_cbranch_execz .LBB0_451
	v_readlane_b32 s0, v253, 7
	v_readlane_b32 s1, v253, 8
	s_nop 1
	v_mov_b64_e32 v[18:19], s[0:1]
	global_atomic_add v[18:19], v166, off

.LBB0_452:
	v_readlane_b32 s0, v254, 9
	v_readlane_b32 s1, v254, 10
	s_nop 1
	v_mov_b64_e32 v[4:5], s[0:1]
	global_atomic_add v3, v[4:5], v166, off sc0
	v_cvt_f32_u32_e32 v4, v2
	v_sub_u32_e32 v5, 0, v2
	v_rcp_iflag_f32_e32 v4, v4
	s_nop 0
	v_mul_f32_e32 v4, 0x4f7ffffe, v4
	v_cvt_u32_f32_e32 v4, v4
	v_mul_lo_u32 v5, v5, v4
	v_mul_hi_u32 v5, v4, v5
	v_add_u32_e32 v4, v4, v5
	s_waitcnt vmcnt(0) lgkmcnt(0)
	v_mul_hi_u32 v4, v3, v4
	v_mul_lo_u32 v5, v4, v2
	v_add_u32_e32 v6, 1, v3
	v_sub_u32_e32 v3, v3, v5
	v_add_u32_e32 v7, 1, v4
	v_cmp_ge_u32_e32 vcc, v3, v2
	v_sub_u32_e32 v5, v3, v2
	s_nop 0
	v_cndmask_b32_e32 v4, v4, v7, vcc
	v_cndmask_b32_e32 v3, v3, v5, vcc
	v_add_u32_e32 v5, 1, v4
	v_cmp_ge_u32_e32 vcc, v3, v2
	s_nop 1
	v_cndmask_b32_e32 v3, v4, v5, vcc
	v_mad_u64_u32 v[4:5], s[0:1], v2, v3, v[2:3]
	v_cmp_ne_u32_e32 vcc, v6, v4
	s_and_saveexec_b64 s[0:1], vcc
	s_xor_b64 s[8:9], exec, s[0:1]
	s_cbranch_execz .LBB0_479
	v_readlane_b32 s0, v254, 11
	v_readlane_b32 s1, v254, 12
	s_nop 1
	v_mov_b64_e32 v[4:5], s[0:1]
	global_load_dword v0, v[4:5], off sc1
	s_waitcnt vmcnt(0) lgkmcnt(0)
	v_cmp_eq_u32_e32 vcc, v0, v3
	s_and_saveexec_b64 s[12:13], vcc
	s_cbranch_execz .LBB0_478
	s_mov_b32 s0, 1
	s_mov_b64 s[14:15], 0
	s_branch .LBB0_456

.LBB0_456:
	s_and_b32 s1, s0, 0xff
	s_mov_b64 s[26:27], -1
	s_cmp_lg_u32 s1, 0
	s_mov_b64 s[28:29], -1
	s_sleep 1
	s_cbranch_scc1 .LBB0_460
	v_readlane_b32 s4, v253, 7
	v_readlane_b32 s5, v253, 8
	s_mov_b64 s[28:29], 0
	s_mov_b64 s[30:31], -1
	v_mov_b64_e32 v[4:5], s[4:5]
	global_load_dword v0, v[4:5], off sc1
	s_waitcnt vmcnt(0) lgkmcnt(0)
	v_cmp_eq_u32_e32 vcc, 0, v0
	s_and_saveexec_b64 s[38:39], vcc
	s_cmp_lt_u32 s0, 0x40001
	s_cselect_b64 s[4:5], -1, 0
	s_xor_b64 s[30:31], exec, -1
	s_and_b64 s[28:29], s[4:5], exec
	s_or_b64 exec, exec, s[38:39]
.LBB0_460:
	s_andn2_b64 s[4:5], s[24:25], exec
	s_and_b64 s[20:21], s[30:31], exec
	s_or_b64 s[24:25], s[4:5], s[20:21]
	s_and_saveexec_b64 s[30:31], s[28:29]
	s_cbranch_execz .LBB0_455
	v_readlane_b32 s4, v254, 11
	v_readlane_b32 s5, v254, 12
	s_add_i32 s0, s0, 1
	s_or_b64 s[24:25], s[24:25], exec
	v_mov_b64_e32 v[4:5], s[4:5]
	global_load_dword v0, v[4:5], off sc1
	s_waitcnt vmcnt(0) lgkmcnt(0)
	v_cmp_ne_u32_e32 vcc, v0, v3
	s_orn2_b64 s[26:27], vcc, exec
	s_branch .LBB0_455
.LBB0_462:
	s_or_b64 exec, exec, s[22:23]
	s_xor_b64 s[0:1], s[24:25], -1
	s_and_saveexec_b64 s[4:5], s[0:1]
	s_xor_b64 s[4:5], exec, s[4:5]
	s_cbranch_execz .LBB0_464
	v_readlane_b32 s0, v253, 7
	v_readlane_b32 s1, v253, 8
	s_nop 1
	v_mov_b64_e32 v[2:3], s[0:1]
	global_atomic_add v[2:3], v166, off

.LBB0_465:
	s_andn2_saveexec_b64 s[0:1], s[12:13]
	s_cbranch_execz .LBB0_495
	v_readlane_b32 s0, v254, 13
	v_readlane_b32 s1, v254, 14
	buffer_wbl2 sc1
	s_waitcnt vmcnt(0)
	v_sub_u32_e32 v4, 0, v0
	v_mov_b64_e32 v[2:3], s[0:1]
	global_atomic_add v2, v[2:3], v166, off sc0
	v_cvt_f32_u32_e32 v3, v0
	s_mov_b64 s[14:15], -1
	v_rcp_iflag_f32_e32 v3, v3
	s_nop 0
	v_mul_f32_e32 v3, 0x4f7ffffe, v3
	v_cvt_u32_f32_e32 v3, v3
	v_mul_lo_u32 v4, v4, v3
	v_mul_hi_u32 v4, v3, v4
	v_add_u32_e32 v3, v3, v4
	s_waitcnt vmcnt(0) lgkmcnt(0)
	v_mul_hi_u32 v3, v2, v3
	v_mul_lo_u32 v4, v3, v0
	v_sub_u32_e32 v4, v2, v4
	v_cmp_ge_u32_e32 vcc, v4, v0
	v_add_u32_e32 v5, 1, v3
	s_nop 0
	v_cndmask_b32_e32 v3, v3, v5, vcc
	v_sub_u32_e32 v5, v4, v0
	v_cndmask_b32_e32 v4, v4, v5, vcc
	v_cmp_ge_u32_e32 vcc, v4, v0
	v_add_u32_e32 v4, 1, v3
	v_add_u32_e32 v5, 1, v2
	v_cndmask_b32_e32 v4, v3, v4, vcc
	v_mad_u64_u32 v[2:3], s[0:1], v0, v4, v[0:1]
	v_readlane_b32 s0, v254, 15
	v_readlane_b32 s1, v254, 16
	v_cmp_ne_u32_e32 vcc, v5, v2
	s_nop 0
	v_mov_b64_e32 v[2:3], s[0:1]
	s_and_saveexec_b64 s[12:13], vcc
	s_cbranch_execz .LBB0_492
	v_readlane_b32 s0, v254, 15
	v_readlane_b32 s1, v254, 16
	s_mov_b64 s[22:23], 0
	s_nop 0
	v_mov_b64_e32 v[2:3], s[0:1]
	global_load_dword v0, v[2:3], off sc1
	s_waitcnt vmcnt(0) lgkmcnt(0)
	v_cmp_eq_u32_e32 vcc, v0, v4
	s_and_saveexec_b64 s[14:15], vcc
	s_cbranch_execz .LBB0_491
	s_mov_b32 s0, 1
	s_branch .LBB0_470

.LBB0_472:
	v_readlane_b32 s4, v253, 7
	v_readlane_b32 s5, v253, 8
	s_mov_b64 s[30:31], 0
	s_mov_b64 s[28:29], -1
	v_mov_b64_e32 v[2:3], s[4:5]
	global_load_dword v0, v[2:3], off sc1
	s_waitcnt vmcnt(0) lgkmcnt(0)
	v_cmp_eq_u32_e32 vcc, 0, v0
	s_and_saveexec_b64 s[38:39], vcc
	s_cmp_lt_u32 s0, 0x40001
	s_cselect_b64 s[4:5], -1, 0
	s_xor_b64 s[28:29], exec, -1
	s_and_b64 s[30:31], s[4:5], exec
	s_or_b64 exec, exec, s[38:39]
	s_and_saveexec_b64 s[38:39], s[30:31]
	s_cbranch_execz .LBB0_469
.LBB0_475:
	v_readlane_b32 s4, v254, 15
	v_readlane_b32 s5, v254, 16
	s_add_i32 s0, s0, 1
	s_or_b64 s[28:29], s[28:29], exec
	v_mov_b64_e32 v[2:3], s[4:5]
	global_load_dword v0, v[2:3], off sc1
	s_waitcnt vmcnt(0) lgkmcnt(0)
	v_cmp_ne_u32_e32 vcc, v0, v4
	s_orn2_b64 s[26:27], vcc, exec
	s_branch .LBB0_469
.LBB0_476:
	s_or_b64 exec, exec, s[14:15]
	s_xor_b64 s[0:1], s[22:23], -1
	s_and_saveexec_b64 s[4:5], s[0:1]
	s_xor_b64 s[4:5], exec, s[4:5]
	s_cbranch_execz .LBB0_478
	v_readlane_b32 s0, v253, 7
	v_readlane_b32 s1, v253, 8
	s_nop 1
	v_mov_b64_e32 v[2:3], s[0:1]
	global_atomic_add v[2:3], v166, off

.LBB0_479:
	s_andn2_saveexec_b64 s[0:1], s[8:9]
	s_cbranch_execz .LBB0_502
	v_readlane_b32 s0, v254, 13
	v_readlane_b32 s1, v254, 14
	buffer_wbl2 sc1
	s_waitcnt vmcnt(0)
	v_sub_u32_e32 v4, 0, v0
	v_mov_b64_e32 v[2:3], s[0:1]
	global_atomic_add v2, v[2:3], v166, off sc0
	v_cvt_f32_u32_e32 v3, v0
	s_mov_b64 s[12:13], -1
	v_rcp_iflag_f32_e32 v3, v3
	s_nop 0
	v_mul_f32_e32 v3, 0x4f7ffffe, v3
	v_cvt_u32_f32_e32 v3, v3
	v_mul_lo_u32 v4, v4, v3
	v_mul_hi_u32 v4, v3, v4
	v_add_u32_e32 v3, v3, v4
	s_waitcnt vmcnt(0) lgkmcnt(0)
	v_mul_hi_u32 v3, v2, v3
	v_mul_lo_u32 v4, v3, v0
	v_add_u32_e32 v5, 1, v2
	v_sub_u32_e32 v2, v2, v4
	v_add_u32_e32 v6, 1, v3
	v_cmp_ge_u32_e32 vcc, v2, v0
	v_sub_u32_e32 v4, v2, v0
	s_nop 0
	v_cndmask_b32_e32 v3, v3, v6, vcc
	v_cndmask_b32_e32 v2, v2, v4, vcc
	v_add_u32_e32 v4, 1, v3
	v_cmp_ge_u32_e32 vcc, v2, v0
	s_nop 1
	v_cndmask_b32_e32 v4, v3, v4, vcc
	v_mad_u64_u32 v[2:3], s[0:1], v0, v4, v[0:1]
	v_readlane_b32 s0, v254, 15
	v_readlane_b32 s1, v254, 16
	v_cmp_ne_u32_e32 vcc, v5, v2
	s_nop 0
	v_mov_b64_e32 v[2:3], s[0:1]
	s_and_saveexec_b64 s[8:9], vcc
	s_cbranch_execz .LBB0_499
	v_readlane_b32 s0, v254, 15
	v_readlane_b32 s1, v254, 16
	s_mov_b64 s[14:15], 0
	s_nop 0
	v_mov_b64_e32 v[2:3], s[0:1]
	global_load_dword v0, v[2:3], off sc1
	s_waitcnt vmcnt(0) lgkmcnt(0)
	v_cmp_eq_u32_e32 vcc, v0, v4
	s_and_saveexec_b64 s[12:13], vcc
	s_cbranch_execz .LBB0_498
	s_mov_b32 s0, 1
	s_branch .LBB0_484

.LBB0_486:
	v_readlane_b32 s4, v253, 7
	v_readlane_b32 s5, v253, 8
	s_mov_b64 s[28:29], 0
	s_mov_b64 s[26:27], -1
	v_mov_b64_e32 v[2:3], s[4:5]
	global_load_dword v0, v[2:3], off sc1
	s_waitcnt vmcnt(0) lgkmcnt(0)
	v_cmp_eq_u32_e32 vcc, 0, v0
	s_and_saveexec_b64 s[30:31], vcc
	s_cmp_lt_u32 s0, 0x40001
	s_cselect_b64 s[4:5], -1, 0
	s_xor_b64 s[26:27], exec, -1
	s_and_b64 s[28:29], s[4:5], exec
	s_or_b64 exec, exec, s[30:31]
	s_and_saveexec_b64 s[30:31], s[28:29]
	s_cbranch_execz .LBB0_483
.LBB0_489:
	v_readlane_b32 s4, v254, 15
	v_readlane_b32 s5, v254, 16
	s_add_i32 s0, s0, 1
	s_or_b64 s[26:27], s[26:27], exec
	v_mov_b64_e32 v[2:3], s[4:5]
	global_load_dword v0, v[2:3], off sc1
	s_waitcnt vmcnt(0) lgkmcnt(0)
	v_cmp_ne_u32_e32 vcc, v0, v4
	s_orn2_b64 s[24:25], vcc, exec
	s_branch .LBB0_483

.LBB0_492:
	s_or_b64 exec, exec, s[12:13]
	s_and_saveexec_b64 s[12:13], s[14:15]
	s_cbranch_execz .LBB0_494
	global_atomic_add v[2:3], v166, off
.LBB0_494:
	s_or_b64 exec, exec, s[12:13]
	v_readlane_b32 s0, v254, 11
	v_readlane_b32 s1, v254, 12
	s_waitcnt vmcnt(0) lgkmcnt(0)
	buffer_inv sc1
	v_mov_b64_e32 v[2:3], s[0:1]
	global_atomic_add v[2:3], v166, off
	s_waitcnt vmcnt(0)

.LBB0_499:
	s_or_b64 exec, exec, s[8:9]
	s_and_saveexec_b64 s[8:9], s[12:13]
	s_cbranch_execz .LBB0_501
	global_atomic_add v[2:3], v166, off

.LBB0_506:
	s_cmpk_gt_i32 s6, 0x8f
	s_mov_b64 s[8:9], -1
	s_cbranch_scc0 .LBB0_600
	s_cmpk_gt_u32 s6, 0x28f
	s_cbranch_scc0 .LBB0_571
	s_cmpk_gt_u32 s6, 0x48f
	s_cbranch_scc0 .LBB0_528
	v_readlane_b32 s8, v254, 49
	v_readlane_b32 s9, v254, 50
	s_andn2_b64 vcc, exec, s[8:9]
	s_cbranch_vccnz .LBB0_527
	v_mov_b32_e32 v2, s64
	v_mov_b32_e32 v3, s65
	v_mov_b32_e32 v4, s64
	v_readfirstlane_b32 s7, v2
	v_readfirstlane_b32 s8, v3
	v_mov_b32_e32 v5, s65
	v_mov_b32_e32 v2, s7
	v_mov_b32_e32 v3, s8
	global_load_dwordx2 v[2:3], v[2:3], off offset:248
	s_waitcnt vmcnt(0) lgkmcnt(0)
	v_mov_b32_e32 v0, s64
	v_readfirstlane_b32 s7, v4
	v_readfirstlane_b32 s8, v5
	v_mov_b32_e32 v6, s65
	v_mov_b32_e32 v4, s7
	v_mov_b32_e32 v5, s8
	global_load_dwordx2 v[4:5], v[4:5], off offset:248
	s_waitcnt vmcnt(0) lgkmcnt(0)
	s_add_i32 s15, s6, 0xfffffb70
	v_readfirstlane_b32 s7, v0
	v_readfirstlane_b32 s8, v6
	s_lshr_b32 s18, s15, 1
	v_mov_b32_e32 v6, s7
	v_mov_b32_e32 v7, s8
	global_load_dwordx2 v[6:7], v[6:7], off offset:248
	s_bfe_u32 s7, s15, 0x20001
	s_lshr_b32 s21, s15, 6
	s_cmp_lt_u32 s15, 64
	v_mov_b32_e32 v18, v247
	s_cselect_b64 s[40:41], -1, 0
	s_cmp_gt_u32 s15, 63
	v_readfirstlane_b32 s26, v2
	v_readfirstlane_b32 s27, v3
	v_readfirstlane_b32 s12, v4
	v_readfirstlane_b32 s13, v5
	s_mov_b64 s[24:25], -1
	s_waitcnt vmcnt(0) lgkmcnt(0)
	v_mov_b32_e32 v0, v7
	s_nop 0
	v_readfirstlane_b32 s8, v6
	v_readfirstlane_b32 s9, v0
	s_cbranch_scc0 .LBB0_516
	s_lshl_b32 s28, s7, 6
	s_cmp_lg_u32 s21, 1
	s_cbranch_scc0 .LBB0_513
	s_lshl_b32 s14, s18, 5
	s_and_b32 s23, s14, 64
	s_add_i32 s22, s28, 0x380
	s_or_b32 s14, s23, 0x480
	s_or_b32 s23, s23, 0x180
	s_mov_b64 s[24:25], 0

.LBB0_518:
	s_lshl_b32 s18, s15, 5
	s_and_b32 s18, s18, 0x700
	s_lshl_b32 s15, s15, 7
	s_bfe_u32 s25, s0, 0x30008
	s_and_b32 s15, s15, 0x80
	s_or_b32 s30, s18, 0x4000
	s_lshl_b32 s24, s25, 9
	s_or_b32 s18, s30, s15
	v_ashrrev_i32_e32 v0, 2, v18
	s_add_u32 s28, s26, 0x9f00000
	v_and_b32_e32 v2, -16, v0
	s_addc_u32 s29, s27, 0
	v_ashrrev_i32_e32 v19, 3, v18
	v_ashrrev_i32_e32 v3, 31, v2
	v_mov_b64_e32 v[10:11], s[28:29]
	v_add_u32_e32 v0, s30, v19
	s_mov_b32 s15, s19
	v_lshlrev_b32_e32 v22, 3, v18
	v_add_u32_e32 v23, s23, v19
	v_mov_b64_e32 v[4:5], s[12:13]
	s_mov_b32 s31, 0x9000
	v_lshl_add_u64 v[50:51], v[2:3], 0, s[18:19]
	v_mad_i64_i32 v[2:3], s[28:29], v0, s2, v[10:11]
	s_lshl_b64 s[14:15], s[14:15], 1
	v_and_b32_e32 v53, 56, v22
	v_mad_i64_i32 v[4:5], s[28:29], v23, s31, v[4:5]
	s_lshl_b32 s18, s30, 1
	v_lshl_add_u64 v[2:3], v[2:3], 0, s[14:15]
	v_lshlrev_b32_e32 v20, 1, v53
	v_mov_b32_e32 v21, v1
	v_lshl_add_u64 v[4:5], v[4:5], 0, s[18:19]
	v_lshl_add_u64 v[2:3], v[2:3], 0, v[20:21]
	v_lshl_add_u64 v[4:5], v[4:5], 0, v[20:21]
	s_mov_b32 s18, 0x17700000
	v_and_b32_e32 v21, 15, v18
	v_add_co_u32_e32 v4, vcc, s18, v4
	v_or_b32_e32 v50, v50, v21
	v_lshrrev_b32_e32 v0, 1, v18
	v_addc_co_u32_e32 v5, vcc, 0, v5, vcc
	v_mad_i64_i32 v[10:11], s[28:29], v50, s2, v[10:11]
	s_mov_b32 s23, s19
	v_and_b32_e32 v52, 24, v0
	global_load_dwordx4 v[6:9], v[4:5], off
	s_nop 0
	global_load_dwordx4 v[2:5], v[2:3], off
	v_lshl_add_u64 v[10:11], s[22:23], 1, v[10:11]
	v_lshlrev_b32_e32 v0, 1, v52
	v_lshl_add_u64 v[14:15], v[10:11], 0, v[0:1]
	global_load_dwordx4 v[10:13], v[14:15], off
	s_nop 0
	global_load_dwordx4 v[14:17], v[14:15], off offset:64
	v_lshlrev_b32_e32 v24, 4, v18
	v_lshlrev_b32_e32 v18, 1, v18
	s_movk_i32 s22, 0x90
	v_and_b32_e32 v27, 32, v22
	v_and_b32_e32 v28, 16, v24
	v_and_b32_e32 v29, 4, v18
	v_mul_lo_u32 v30, v19, s22
	v_cmp_lt_i32_e32 vcc, v222, v220
	v_mul_u32_u24_e32 v60, 0x90, v21
	v_and_b32_e32 v21, 0x70, v24
	v_mad_i64_i32 v[18:19], s[22:23], v19, s2, 0
	v_mad_i64_i32 v[22:23], s[22:23], v23, s31, 0
	v_or3_b32 v61, v27, v28, v29
	v_add_u32_e32 v62, 16, v30
	v_mov_b32_e32 v24, 0x300000
	v_cndmask_b32_e32 v25, v219, v222, vcc
	v_mad_u64_u32 v[18:19], s[22:23], s25, v24, v[18:19]
	v_add_u32_e32 v24, v62, v20
	v_lshl_add_u32 v20, v61, 1, v62
	v_or3_b32 v22, v22, s24, v21
	v_lshlrev_b32_e32 v58, 2, v25
	v_or_b32_e32 v18, v18, v21
	v_add_u32_e32 v25, 0x2000, v20
	v_lshl_add_u64 v[20:21], s[12:13], 0, v[22:23]
	s_mov_b64 s[12:13], 0x17708080
	v_lshl_add_u64 v[54:55], v[20:21], 0, s[12:13]
	s_add_u32 s12, s26, s14
	v_cmp_lt_i32_e32 vcc, v221, v220
	s_addc_u32 s13, s27, s15
	v_lshl_add_u64 v[18:19], s[12:13], 0, v[18:19]
	v_cndmask_b32_e32 v26, v219, v221, vcc
	s_mov_b64 s[12:13], 0x15fc0000
	v_mov_b32_e32 v20, v1
	v_mov_b32_e32 v21, v1
	v_lshlrev_b32_e32 v59, 2, v26
	v_lshl_add_u64 v[56:57], v[18:19], 0, s[12:13]
	s_waitcnt vmcnt(0) lgkmcnt(0)
	ds_write2_b64 v25, v[6:7], v[8:9] offset0:128 offset1:130
	ds_write_b128 v24, v[2:5]
	v_mov_b32_e32 v18, v1
	v_mov_b32_e32 v19, v1
	v_mov_b64_e32 v[24:25], v[20:21]
	v_mov_b64_e32 v[28:29], v[20:21]
	v_mov_b64_e32 v[32:33], v[20:21]
	s_mov_b32 s18, 0
	v_mov_b32_e32 v64, 0xf149f2ca
	v_mov_b32_e32 v63, 0
	v_mov_b64_e32 v[22:23], v[18:19]
	v_mov_b64_e32 v[26:27], v[18:19]
	v_mov_b64_e32 v[30:31], v[18:19]
	s_waitcnt lgkmcnt(0)
	s_barrier
	s_branch .LBB0_520

.LBB0_520:
	s_cmp_lg_u32 s18, 3
	s_cselect_b64 s[12:13], -1, 0
	s_cmp_eq_u32 s18, 3
	s_cbranch_scc1 .LBB0_522
	s_waitcnt vmcnt(0)
	global_load_dwordx4 v[2:5], v[56:57], off
	global_load_dwordx4 v[6:9], v[54:55], off

.LBB0_526:
	v_mov_b32_e32 v0, s64
	s_waitcnt vmcnt(0)
	v_mov_b32_e32 v2, s65
	v_mov_b32_e32 v53, v1
	v_readfirstlane_b32 s12, v0
	v_readfirstlane_b32 s13, v2
	s_nop 0
	v_mov_b32_e32 v2, s12
	v_mov_b32_e32 v3, s13
	global_load_dwordx2 v[2:3], v[2:3], off offset:104
	v_readlane_b32 s12, v254, 51
	s_or_b32 s12, s7, s12
	s_ashr_i32 s13, s12, 31
	s_lshl_b64 s[12:13], s[12:13], 2
	s_waitcnt vmcnt(0) lgkmcnt(0)
	v_mov_b32_e32 v0, v2
	s_nop 0
	v_readfirstlane_b32 s14, v0
	v_readfirstlane_b32 s15, v3
	s_add_u32 s12, s14, s12
	s_addc_u32 s13, s15, s13
	v_mov_b64_e32 v[2:3], s[12:13]
	global_load_dword v0, v[2:3], off
	ds_bpermute_b32 v2, v58, v63
	s_lshl_b32 s18, s21, 9
	s_waitcnt lgkmcnt(0)
	v_add_f32_e32 v4, v63, v2
	v_lshlrev_b64 v[2:3], 11, v[50:51]
	v_lshl_add_u64 v[2:3], s[8:9], 0, v[2:3]
	ds_bpermute_b32 v5, v59, v4
	v_lshl_add_u64 v[2:3], v[2:3], 0, s[18:19]
	s_lshl_b32 s18, s7, 7
	s_mov_b32 s7, 0x3fb8aa3b
	v_lshl_add_u64 v[2:3], v[2:3], 0, s[18:19]
	s_waitcnt lgkmcnt(0)
	v_add_f32_e32 v6, v4, v5
	v_lshl_add_u64 v[2:3], v[2:3], 0, v[52:53]
	s_mov_b64 s[8:9], 0x1e300000
	v_lshl_add_u64 v[4:5], v[2:3], 0, s[8:9]
	s_waitcnt vmcnt(0)
	v_fma_f32 v0, v0, s7, -v64
	v_exp_f32_e32 v0, v0
	s_mov_b32 s7, 0x1e300000
	v_add_co_u32_e32 v2, vcc, s7, v2
	v_add_f32_e32 v0, v0, v6
	v_cndmask_b32_e64 v0, v6, v0, s[40:41]
	v_div_scale_f32 v6, s[8:9], v0, v0, 1.0
	v_rcp_f32_e32 v7, v6
	v_addc_co_u32_e32 v3, vcc, 0, v3, vcc
	v_div_scale_f32 v8, vcc, 1.0, v0, 1.0
	v_fma_f32 v9, -v6, v7, 1.0
	v_fmac_f32_e32 v7, v9, v7
	v_mul_f32_e32 v9, v8, v7
	v_fma_f32 v10, -v6, v9, v8
	v_fmac_f32_e32 v9, v10, v7
	v_fma_f32 v6, -v6, v9, v8
	v_div_fmas_f32 v6, v6, v7, v9
	v_div_fixup_f32 v0, v6, v0, 1.0
	v_pk_mul_f32 v[6:7], v[30:31], v[0:1] op_sel_hi:[1,0]
	v_pk_mul_f32 v[8:9], v[32:33], v[0:1] op_sel_hi:[1,0]
	v_pk_mul_f32 v[10:11], v[26:27], v[0:1] op_sel_hi:[1,0]
	v_pk_mul_f32 v[12:13], v[28:29], v[0:1] op_sel_hi:[1,0]
	v_pk_mul_f32 v[14:15], v[22:23], v[0:1] op_sel_hi:[1,0]
	v_pk_mul_f32 v[16:17], v[24:25], v[0:1] op_sel_hi:[1,0]
	v_pk_mul_f32 v[18:19], v[18:19], v[0:1] op_sel_hi:[1,0]
	v_pk_mul_f32 v[20:21], v[20:21], v[0:1] op_sel_hi:[1,0]
	v_cvt_pk_bf16_f32 v6, v6, v7
	v_cvt_pk_bf16_f32 v7, v8, v9
	v_cvt_pk_bf16_f32 v8, v10, v11
	v_cvt_pk_bf16_f32 v9, v12, v13
	v_cvt_pk_bf16_f32 v10, v14, v15
	v_cvt_pk_bf16_f32 v11, v16, v17
	v_cvt_pk_bf16_f32 v12, v18, v19
	v_cvt_pk_bf16_f32 v13, v20, v21
	global_store_dwordx2 v[2:3], v[6:7], off
	global_store_dwordx2 v[4:5], v[8:9], off offset:32
	global_store_dwordx2 v[4:5], v[10:11], off offset:64
	global_store_dwordx2 v[4:5], v[12:13], off offset:96

.LBB0_528:
	s_andn2_b64 vcc, exec, s[8:9]
	s_cbranch_vccnz .LBB0_570
	v_mov_b32_e32 v2, s64
	v_mov_b32_e32 v3, s65
	v_mov_b32_e32 v4, s64
	v_readfirstlane_b32 s7, v2
	v_readfirstlane_b32 s8, v3
	v_mov_b32_e32 v5, s65
	v_mov_b32_e32 v2, s7
	v_mov_b32_e32 v3, s8
	global_load_dwordx2 v[2:3], v[2:3], off offset:248
	s_waitcnt vmcnt(0) lgkmcnt(0)
	v_mov_b32_e32 v21, v247
	v_readfirstlane_b32 s7, v4
	v_readfirstlane_b32 s8, v5
	v_readfirstlane_b32 s12, v3
	v_mov_b32_e32 v4, s7
	v_mov_b32_e32 v5, s8
	global_load_dwordx2 v[12:13], v[4:5], off offset:248
	v_mov_b32_e32 v4, s64
	v_mov_b32_e32 v5, s65
	s_waitcnt vmcnt(0) lgkmcnt(0)
	s_mov_b32 s9, s19
	v_readfirstlane_b32 s7, v4
	v_readfirstlane_b32 s8, v5
	v_mov_b32_e32 v71, v1
	v_mov_b32_e32 v4, s7
	v_mov_b32_e32 v5, s8
	global_load_dwordx2 v[28:29], v[4:5], off offset:248
	s_add_i32 s7, s6, 0xfffffd70
	v_readfirstlane_b32 s8, v2
	s_add_u32 s22, s8, 0x9f00000
	s_addc_u32 s23, s12, 0
	s_bfe_u32 s21, s7, 0x20004
	s_lshr_b32 s14, s7, 6
	s_lshl_b32 s7, s7, 1
	s_and_b32 s24, s7, 30
	s_lshl_b32 s8, s14, 11
	v_mov_b64_e32 v[2:3], s[22:23]
	s_lshl_b32 s18, s21, 7
	v_mov_b32_e32 v0, s64
	v_mov_b32_e32 v14, s65
	v_readfirstlane_b32 s15, v13
	v_sub_u32_e64 v32, s24, 3 clamp
	s_waitcnt vmcnt(0) lgkmcnt(0)
	v_mov_b32_e32 v20, v29
	v_mov_b32_e32 v13, s15
	v_ashrrev_i32_e32 v22, 8, v21
	v_lshrrev_b32_e32 v4, 1, v21
	v_add_u32_e32 v25, s24, v22
	v_and_b32_e32 v5, 24, v4
	v_lshlrev_b32_e32 v4, 6, v25
	v_lshrrev_b32_e32 v26, 2, v21
	v_lshlrev_b32_e32 v70, 1, v5
	v_ashrrev_i32_e32 v5, 31, v4
	v_and_b32_e32 v23, 15, v21
	v_and_b32_e32 v24, 48, v26
	v_lshl_add_u64 v[68:69], v[4:5], 0, s[8:9]
	v_or3_b32 v68, v68, v24, v23
	v_mad_u64_u32 v[4:5], s[12:13], v68, s2, v[2:3]
	v_mad_i32_i24 v5, v69, s2, v5
	v_lshl_add_u64 v[4:5], v[4:5], 0, s[18:19]
	v_lshl_add_u64 v[8:9], v[4:5], 0, v[70:71]
	global_load_dwordx4 v[4:7], v[8:9], off offset:768
	s_nop 0
	global_load_dwordx4 v[8:11], v[8:9], off offset:832
	v_ashrrev_i32_e32 v72, 3, v21
	v_readfirstlane_b32 s7, v0
	v_readfirstlane_b32 s9, v14
	s_mov_b32 s13, s19
	v_mov_b32_e32 v14, s7
	v_mov_b32_e32 v15, s9
	global_load_dwordx2 v[30:31], v[14:15], off offset:112
	s_lshl_b32 s7, s21, 6
	s_lshl_b32 s9, s14, 8
	s_add_i32 s14, s7, 0x80
	s_add_i32 s12, s9, 0x4000
	v_readfirstlane_b32 s9, v12
	v_ashrrev_i32_e32 v73, 31, v72
	v_add_u32_e32 v16, s14, v72
	v_mov_b32_e32 v12, s9
	v_lshl_add_u64 v[14:15], v[72:73], 0, s[12:13]
	s_mov_b32 s9, 0x9000
	v_mad_i64_i32 v[12:13], s[14:15], v16, s9, v[12:13]
	v_mad_u64_u32 v[16:17], s[14:15], v14, s2, v[2:3]
	v_lshlrev_b32_e32 v27, 3, v21
	s_mov_b64 s[14:15], 0x17700000
	v_mad_i32_i24 v17, v15, s2, v17
	v_and_b32_e32 v71, 56, v27
	v_lshl_add_u64 v[2:3], v[12:13], 0, s[14:15]
	v_lshl_add_u64 v[12:13], v[16:17], 0, s[18:19]
	s_lshl_b32 s18, s12, 1
	v_lshlrev_b32_e32 v0, 1, v71
	v_lshl_add_u64 v[14:15], v[2:3], 0, s[18:19]
	v_lshl_add_u64 v[12:13], v[12:13], 0, v[0:1]
	v_lshl_add_u64 v[16:17], v[14:15], 0, v[0:1]
	v_readfirstlane_b32 s12, v32
	s_min_u32 s12, s12, 24
	v_readfirstlane_b32 s13, v20
	v_lshlrev_b32_e32 v20, 4, v21
	s_movk_i32 s18, 0x90
	v_and_b32_e32 v27, 32, v27
	v_and_b32_e32 v20, 16, v20
	s_mov_b64 s[14:15], -1
	v_and_b32_e32 v98, 12, v26
	s_waitcnt vmcnt(0) lgkmcnt(0)
	v_mov_b32_e32 v29, v30
	global_load_dwordx4 v[12:15], v[12:13], off offset:1280
	s_nop 0
	global_load_dwordx4 v[16:19], v[16:17], off
	v_sub_u32_e64 v30, s24, 4 clamp
	v_readfirstlane_b32 s24, v31
	v_readfirstlane_b32 s9, v30
	s_min_u32 s9, s9, 24
	s_sub_i32 s9, s12, s9
	v_readfirstlane_b32 s12, v28
	v_lshlrev_b32_e32 v28, 1, v21
	v_and_b32_e32 v28, 4, v28
	v_mul_lo_u32 v30, v72, s18
	s_add_i32 s9, s9, 8
	v_or3_b32 v96, v27, v20, v28
	v_add_u32_e32 v97, 16, v30
	v_add_u32_e32 v20, v97, v0
	v_lshl_add_u32 v27, v96, 1, v97
	s_cmp_gt_i32 s9, -4
	v_readfirstlane_b32 s18, v29
	v_add_u32_e32 v27, 0x2000, v27
	s_waitcnt vmcnt(0) lgkmcnt(0)
	ds_write_b128 v20, v[12:15]
	ds_write2_b64 v27, v[16:17], v[18:19] offset0:128 offset1:130
	s_waitcnt lgkmcnt(0)
	s_barrier
	s_cbranch_scc1 .LBB0_531
	v_and_b32_e32 v20, 12, v26
	s_mov_b64 s[14:15], 0

.LBB0_536:
	v_lshl_add_u64 v[2:3], s[40:41], 0, v[72:73]
	s_waitcnt vmcnt(0)
	v_mad_u64_u32 v[12:13], s[54:55], v2, s2, v[92:93]
	v_mad_i32_i24 v13, v3, s2, v13
	v_lshl_add_u64 v[2:3], s[40:41], 1, v[74:75]
	global_load_dwordx4 v[12:15], v[12:13], off
	s_nop 0
	global_load_dwordx4 v[16:19], v[2:3], off
.LBB0_537:
	s_bitcmp1_b32 s52, 0
	s_cselect_b32 s40, 0x4800, 0
	s_add_i32 s45, s40, 16
	s_cmp_gt_u32 s52, 3
	s_mov_b64 s[40:41], -1
	s_cbranch_scc0 .LBB0_563
	s_add_i32 s40, s21, s52
	v_cmp_ge_i32_e32 vcc, s40, v99
	v_cmp_lt_i32_e64 s[40:41], s40, v100
	v_mov_b64_e32 v[50:51], v[22:23]
	v_mov_b64_e32 v[38:39], v[26:27]
	v_mov_b64_e32 v[42:43], v[30:31]
	v_mov_b64_e32 v[46:47], v[34:35]
	s_and_b64 s[52:53], vcc, s[40:41]
	v_mov_b32_e32 v56, v109
	v_mov_b32_e32 v95, v110
	v_mov_b64_e32 v[48:49], v[20:21]
	v_mov_b64_e32 v[36:37], v[24:25]
	v_mov_b64_e32 v[40:41], v[28:29]
	v_mov_b64_e32 v[44:45], v[32:33]
	s_and_saveexec_b64 s[40:41], s[52:53]
	s_cbranch_execz .LBB0_558
	v_mov_b32_e32 v2, 0xff800000
	v_ashrrev_i32_e32 v95, 31, v94
	v_mov_b32_e32 v0, 0xff800000
	s_and_saveexec_b64 s[52:53], s[22:23]
	s_cbranch_execz .LBB0_541
	v_lshl_add_u64 v[36:37], v[94:95], 0, v[78:79]
	v_lshl_add_u64 v[36:37], v[36:37], 2, s[14:15]
	global_load_dword v0, v[36:37], off offset:868
	s_waitcnt vmcnt(0) lgkmcnt(0)
	v_mul_f32_e32 v0, 0x3fb8aa3b, v0
.LBB0_541:
	s_or_b64 exec, exec, s[52:53]
	s_and_saveexec_b64 s[52:53], s[24:25]
	s_cbranch_execz .LBB0_543
	v_lshl_add_u64 v[2:3], v[94:95], 0, v[76:77]
	v_lshl_add_u64 v[2:3], v[2:3], 2, s[14:15]
	global_load_dword v2, v[2:3], off offset:868
	s_waitcnt vmcnt(0) lgkmcnt(0)
	v_mul_f32_e32 v2, 0x3fb8aa3b, v2
.LBB0_543:
	s_or_b64 exec, exec, s[52:53]
	v_mov_b32_e32 v3, 0xff800000
	v_mov_b32_e32 v112, 0xff800000
	s_and_saveexec_b64 s[52:53], s[26:27]
	s_cbranch_execz .LBB0_545
	v_lshl_add_u64 v[36:37], v[94:95], 0, v[82:83]
	v_lshl_add_u64 v[36:37], v[36:37], 2, s[14:15]
	global_load_dword v36, v[36:37], off offset:868
	s_waitcnt vmcnt(0) lgkmcnt(0)
	v_mul_f32_e32 v112, 0x3fb8aa3b, v36
.LBB0_545:
	s_or_b64 exec, exec, s[52:53]
	s_and_saveexec_b64 s[52:53], s[28:29]
	s_cbranch_execz .LBB0_547
	v_lshl_add_u64 v[36:37], v[94:95], 0, v[80:81]
	v_lshl_add_u64 v[36:37], v[36:37], 2, s[14:15]
	global_load_dword v3, v[36:37], off offset:868
	s_waitcnt vmcnt(0) lgkmcnt(0)
	v_mul_f32_e32 v3, 0x3fb8aa3b, v3
.LBB0_547:
	s_or_b64 exec, exec, s[52:53]
	v_mov_b32_e32 v111, 0xff800000
	v_mov_b32_e32 v113, 0xff800000
	s_and_saveexec_b64 s[52:53], s[30:31]
	s_cbranch_execz .LBB0_549
	v_lshl_add_u64 v[36:37], v[94:95], 0, v[86:87]
	v_lshl_add_u64 v[36:37], v[36:37], 2, s[14:15]
	global_load_dword v36, v[36:37], off offset:868
	s_waitcnt vmcnt(0) lgkmcnt(0)
	v_mul_f32_e32 v113, 0x3fb8aa3b, v36
.LBB0_549:
	s_or_b64 exec, exec, s[52:53]
	s_and_saveexec_b64 s[52:53], s[46:47]
	s_cbranch_execz .LBB0_551
	v_lshl_add_u64 v[36:37], v[94:95], 0, v[84:85]
	v_lshl_add_u64 v[36:37], v[36:37], 2, s[14:15]
	global_load_dword v36, v[36:37], off offset:868
	s_waitcnt vmcnt(0) lgkmcnt(0)
	v_mul_f32_e32 v111, 0x3fb8aa3b, v36
.LBB0_551:
	s_or_b64 exec, exec, s[52:53]
	v_mov_b32_e32 v114, 0xff800000
	v_mov_b32_e32 v115, 0xff800000
	s_and_saveexec_b64 s[52:53], s[42:43]
	s_cbranch_execz .LBB0_553
	v_lshl_add_u64 v[36:37], v[94:95], 0, v[90:91]
	v_lshl_add_u64 v[36:37], v[36:37], 2, s[14:15]
	global_load_dword v36, v[36:37], off offset:868
	s_waitcnt vmcnt(0) lgkmcnt(0)
	v_mul_f32_e32 v115, 0x3fb8aa3b, v36
.LBB0_553:
	s_or_b64 exec, exec, s[52:53]
	s_and_saveexec_b64 s[52:53], s[48:49]
	s_cbranch_execz .LBB0_555
	v_lshl_add_u64 v[36:37], v[94:95], 0, v[88:89]
	v_lshl_add_u64 v[36:37], v[36:37], 2, s[14:15]
	global_load_dword v36, v[36:37], off offset:868
	s_waitcnt vmcnt(0) lgkmcnt(0)
	v_mul_f32_e32 v114, 0x3fb8aa3b, v36

.LBB0_569:
	v_cmp_lt_i32_e32 vcc, v222, v220
	s_lshl_b32 s18, s7, 1
	v_mov_b32_e32 v21, v1
	v_cndmask_b32_e32 v0, v219, v222, vcc
	v_lshlrev_b32_e32 v0, 2, v0
	ds_bpermute_b32 v0, v0, v56
	v_cmp_lt_i32_e32 vcc, v221, v220
	s_mov_b32 s7, 0x1e300000
	s_waitcnt lgkmcnt(0)
	v_add_f32_e32 v0, v56, v0
	v_cndmask_b32_e32 v2, v219, v221, vcc
	v_lshlrev_b32_e32 v2, 2, v2
	ds_bpermute_b32 v4, v2, v0
	v_lshlrev_b64 v[2:3], 11, v[68:69]
	v_lshl_add_u64 v[2:3], s[12:13], 0, v[2:3]
	v_lshl_add_u64 v[2:3], v[2:3], 0, s[18:19]
	v_lshl_add_u64 v[2:3], v[20:21], 1, v[2:3]
	s_waitcnt lgkmcnt(0)
	v_add_f32_e32 v0, v0, v4
	v_div_scale_f32 v4, s[8:9], v0, v0, 1.0
	v_rcp_f32_e32 v5, v4
	v_div_scale_f32 v6, vcc, 1.0, v0, 1.0
	s_mov_b64 s[8:9], 0x1e300200
	v_fma_f32 v7, -v4, v5, 1.0
	v_fmac_f32_e32 v5, v7, v5
	v_mul_f32_e32 v7, v6, v5
	v_fma_f32 v8, -v4, v7, v6
	v_fmac_f32_e32 v7, v8, v5
	v_fma_f32 v4, -v4, v7, v6
	v_div_fmas_f32 v4, v4, v5, v7
	v_div_fixup_f32 v0, v4, v0, 1.0
	v_lshl_add_u64 v[4:5], v[2:3], 0, s[8:9]
	v_pk_mul_f32 v[6:7], v[44:45], v[0:1] op_sel_hi:[1,0]
	v_pk_mul_f32 v[8:9], v[46:47], v[0:1] op_sel_hi:[1,0]
	v_add_co_u32_e32 v2, vcc, s7, v2
	v_cvt_pk_bf16_f32 v6, v6, v7
	v_cvt_pk_bf16_f32 v7, v8, v9
	v_addc_co_u32_e32 v3, vcc, 0, v3, vcc
	global_store_dwordx2 v[2:3], v[6:7], off offset:512
	v_pk_mul_f32 v[2:3], v[40:41], v[0:1] op_sel_hi:[1,0]
	v_pk_mul_f32 v[6:7], v[42:43], v[0:1] op_sel_hi:[1,0]
	v_cvt_pk_bf16_f32 v2, v2, v3
	v_cvt_pk_bf16_f32 v3, v6, v7
	global_store_dwordx2 v[4:5], v[2:3], off offset:32
	v_pk_mul_f32 v[2:3], v[36:37], v[0:1] op_sel_hi:[1,0]
	v_pk_mul_f32 v[6:7], v[38:39], v[0:1] op_sel_hi:[1,0]
	v_cvt_pk_bf16_f32 v2, v2, v3
	v_cvt_pk_bf16_f32 v3, v6, v7
	global_store_dwordx2 v[4:5], v[2:3], off offset:64
	v_pk_mul_f32 v[2:3], v[48:49], v[0:1] op_sel_hi:[1,0]
	v_pk_mul_f32 v[6:7], v[50:51], v[0:1] op_sel_hi:[1,0]
	v_cvt_pk_bf16_f32 v2, v2, v3
	v_cvt_pk_bf16_f32 v3, v6, v7
	global_store_dwordx2 v[4:5], v[2:3], off offset:96

.LBB0_571:
	s_andn2_b64 vcc, exec, s[8:9]
	s_cbranch_vccnz .LBB0_599
	v_mov_b32_e32 v2, s64
	v_mov_b32_e32 v3, s65
	v_mov_b32_e32 v0, s64
	v_readfirstlane_b32 s7, v2
	v_readfirstlane_b32 s8, v3
	v_mov_b32_e32 v8, s65
	v_mov_b32_e32 v2, s7
	v_mov_b32_e32 v3, s8
	global_load_dwordx2 v[4:5], v[2:3], off offset:248
	v_mov_b32_e32 v2, s64
	v_mov_b32_e32 v3, s65
	s_waitcnt vmcnt(0) lgkmcnt(0)
	v_mov_b32_e32 v22, v247
	v_readfirstlane_b32 s7, v2
	v_readfirstlane_b32 s8, v3
	v_readfirstlane_b32 s12, v5
	v_mov_b32_e32 v2, s7
	v_mov_b32_e32 v3, s8
	global_load_dwordx2 v[6:7], v[2:3], off offset:248
	s_waitcnt vmcnt(0) lgkmcnt(0)
	s_mov_b32 s13, s19
	v_readfirstlane_b32 s7, v0
	v_readfirstlane_b32 s8, v8
	v_readfirstlane_b32 s25, v6
	v_mov_b32_e32 v2, s7
	v_mov_b32_e32 v3, s8
	global_load_dwordx2 v[2:3], v[2:3], off offset:248
	s_add_i32 s8, s6, 0xffffff70
	v_readfirstlane_b32 s7, v4
	s_add_u32 s22, s7, 0x9f00000
	s_addc_u32 s23, s12, 0
	s_lshr_b32 s18, s8, 6
	s_lshl_b32 s12, s8, 7
	s_lshl_b32 s24, s8, 1
	s_and_b32 s21, s12, 0x780
	s_lshl_b32 s12, s18, 8
	s_lshl_b64 s[14:15], s[18:19], 11
	s_and_b32 s24, s24, 64
	s_add_i32 s18, s12, 0x4000
	v_readfirstlane_b32 s26, v7
	v_mov_b64_e32 v[4:5], s[22:23]
	s_lshl_b32 s12, s24, 1
	v_mov_b32_e32 v6, s25
	v_mov_b32_e32 v7, s26
	s_bfe_u32 s7, s8, 0x20004
	s_mov_b32 s9, s19
	s_lshl_b32 s8, s7, 7
	v_mov_b32_e32 v69, v1
	s_movk_i32 s26, 0x90
	s_waitcnt vmcnt(0) lgkmcnt(0)
	v_mov_b32_e32 v25, v3
	s_nop 0
	v_ashrrev_i32_e32 v0, 2, v22
	v_ashrrev_i32_e32 v70, 3, v22
	v_lshrrev_b32_e32 v8, 1, v22
	v_and_b32_e32 v23, -16, v0
	v_ashrrev_i32_e32 v71, 31, v70
	v_and_b32_e32 v3, 15, v22
	v_and_b32_e32 v0, 24, v8
	v_add_u32_e32 v10, s24, v70
	v_add_u32_e32 v24, s21, v23
	v_lshl_add_u64 v[8:9], v[70:71], 0, s[18:19]
	s_mov_b32 s24, 0x9000
	v_mad_i64_i32 v[6:7], s[24:25], v10, s24, v[6:7]
	v_or_b32_e32 v10, v24, v3
	v_mad_u64_u32 v[12:13], s[24:25], v8, s2, v[4:5]
	v_lshlrev_b32_e32 v26, 3, v22
	s_mov_b64 s[24:25], 0x17700000
	v_ashrrev_i32_e32 v11, 31, v10
	v_and_b32_e32 v78, 56, v26
	s_lshl_b32 s18, s18, 1
	v_lshl_add_u64 v[20:21], v[6:7], 0, s[24:25]
	v_lshl_add_u64 v[72:73], s[14:15], 0, v[10:11]
	v_lshlrev_b32_e32 v68, 1, v0
	v_lshlrev_b32_e32 v0, 1, v78
	v_mad_i32_i24 v13, v9, s2, v13
	v_lshl_add_u64 v[6:7], v[20:21], 0, s[18:19]
	v_mad_u64_u32 v[4:5], s[24:25], v72, s2, v[4:5]
	v_lshl_add_u64 v[8:9], v[12:13], 0, s[12:13]
	v_lshl_add_u64 v[6:7], v[6:7], 0, v[0:1]
	v_mad_i32_i24 v5, v73, s2, v5
	v_lshl_add_u64 v[8:9], v[8:9], 0, v[0:1]
	global_load_dwordx4 v[16:19], v[6:7], off
	global_load_dwordx4 v[12:15], v[8:9], off offset:512
	v_lshl_add_u64 v[4:5], v[4:5], 0, s[8:9]
	v_lshl_add_u64 v[8:9], v[4:5], 0, v[68:69]
	global_load_dwordx4 v[4:7], v[8:9], off
	s_nop 0
	global_load_dwordx4 v[8:11], v[8:9], off offset:64
	s_max_u32 s13, s21, 0x80
	s_min_u32 s8, s21, 0x700
	s_sub_i32 s18, s8, s13
	v_readfirstlane_b32 s8, v2
	v_readfirstlane_b32 s9, v25
	v_lshlrev_b32_e32 v2, 4, v22
	v_lshlrev_b32_e32 v25, 1, v22
	v_and_b32_e32 v26, 32, v26
	v_and_b32_e32 v2, 16, v2
	v_and_b32_e32 v25, 4, v25
	v_mul_lo_u32 v27, v70, s26
	v_or3_b32 v69, v26, v2, v25
	v_add_u32_e32 v79, 16, v27
	v_lshl_add_u32 v25, v69, 1, v79
	s_addk_i32 s18, 0x180
	v_add_u32_e32 v2, v79, v0
	v_add_u32_e32 v25, 0x2000, v25
	s_ashr_i32 s21, s18, 6
	s_mov_b64 s[24:25], -1
	s_cmp_gt_i32 s21, -4
	s_waitcnt vmcnt(0) lgkmcnt(0)
	ds_write2_b64 v25, v[16:17], v[18:19] offset0:128 offset1:130
	ds_write_b128 v2, v[12:15]
	v_lshrrev_b32_e32 v2, 2, v22
	v_and_b32_e32 v80, 12, v2
	s_waitcnt lgkmcnt(0)
	s_barrier
	s_cbranch_scc1 .LBB0_574
	v_and_b32_e32 v22, 12, v2
	s_mov_b64 s[24:25], 0

.LBB0_576:
	s_add_i32 s26, s14, 1
	s_cmp_lt_i32 s26, s21
	s_cselect_b64 s[12:13], -1, 0
	s_cmp_ge_i32 s26, s21
	s_cbranch_scc1 .LBB0_578
	s_add_i32 s15, s23, s18
	s_add_i32 s27, s18, 0xffffff40
	s_add_u32 s27, s24, s27
	s_addc_u32 s28, s25, 0
	s_cmp_lt_u32 s14, 3
	s_cselect_b32 s29, 0, s28
	s_cselect_b32 s28, s15, s27
	v_lshl_add_u64 v[2:3], s[28:29], 0, v[70:71]
	s_waitcnt vmcnt(0)
	v_mad_u64_u32 v[12:13], s[30:31], v2, s2, v[76:77]
	v_mad_i32_i24 v13, v3, s2, v13
	v_lshl_add_u64 v[2:3], s[28:29], 1, v[74:75]
	global_load_dwordx4 v[12:15], v[12:13], off
	s_nop 0
	global_load_dwordx4 v[16:19], v[2:3], off

.LBB0_598:
	v_mov_b32_e32 v0, s64
	v_mov_b32_e32 v2, s65
	s_lshl_b32 s12, s7, 6
	v_readfirstlane_b32 s13, v0
	v_readfirstlane_b32 s14, v2
	v_cmp_lt_i32_e32 vcc, v222, v220
	v_mov_b32_e32 v2, s13
	v_mov_b32_e32 v3, s14
	global_load_dwordx2 v[2:3], v[2:3], off offset:104
	v_readlane_b32 s13, v254, 51
	s_or_b32 s14, s7, s13
	s_ashr_i32 s15, s14, 31
	s_lshl_b64 s[14:15], s[14:15], 2
	v_mov_b32_e32 v23, v1
	s_waitcnt vmcnt(0) lgkmcnt(0)
	v_mov_b32_e32 v0, v3
	s_nop 0
	v_readfirstlane_b32 s7, v2
	v_readfirstlane_b32 s13, v0
	s_add_u32 s14, s7, s14
	s_addc_u32 s15, s13, s15
	v_mov_b64_e32 v[2:3], s[14:15]
	global_load_dword v0, v[2:3], off
	v_cndmask_b32_e32 v2, v219, v222, vcc
	v_lshlrev_b32_e32 v2, 2, v2
	ds_bpermute_b32 v2, v2, v88
	v_cmp_lt_i32_e32 vcc, v221, v220
	s_mov_b32 s7, 0x3fb8aa3b
	s_lshl_b32 s18, s12, 1
	v_cndmask_b32_e32 v3, v219, v221, vcc
	v_lshlrev_b32_e32 v3, 2, v3
	s_waitcnt lgkmcnt(0)
	v_add_f32_e32 v4, v88, v2
	ds_bpermute_b32 v5, v3, v4
	v_lshlrev_b64 v[2:3], 11, v[72:73]
	v_lshl_add_u64 v[2:3], s[8:9], 0, v[2:3]
	v_lshl_add_u64 v[2:3], v[2:3], 0, s[18:19]
	v_lshl_add_u64 v[2:3], v[22:23], 1, v[2:3]
	s_waitcnt lgkmcnt(0)
	v_add_f32_e32 v6, v4, v5
	s_mov_b64 s[8:9], 0x1e300000
	v_lshl_add_u64 v[4:5], v[2:3], 0, s[8:9]
	s_waitcnt vmcnt(0)
	v_fma_f32 v0, v0, s7, -v87
	v_exp_f32_e32 v0, v0
	s_mov_b32 s7, 0x1e300000
	v_add_co_u32_e32 v2, vcc, s7, v2
	v_add_f32_e32 v0, v0, v6
	v_div_scale_f32 v6, s[8:9], v0, v0, 1.0
	v_rcp_f32_e32 v7, v6
	v_addc_co_u32_e32 v3, vcc, 0, v3, vcc
	v_div_scale_f32 v8, vcc, 1.0, v0, 1.0
	v_fma_f32 v9, -v6, v7, 1.0
	v_fmac_f32_e32 v7, v9, v7
	v_mul_f32_e32 v9, v8, v7
	v_fma_f32 v10, -v6, v9, v8
	v_fmac_f32_e32 v9, v10, v7
	v_fma_f32 v6, -v6, v9, v8
	v_div_fmas_f32 v6, v6, v7, v9
	v_div_fixup_f32 v0, v6, v0, 1.0
	v_pk_mul_f32 v[6:7], v[44:45], v[0:1] op_sel_hi:[1,0]
	v_pk_mul_f32 v[8:9], v[46:47], v[0:1] op_sel_hi:[1,0]
	v_pk_mul_f32 v[10:11], v[40:41], v[0:1] op_sel_hi:[1,0]
	v_pk_mul_f32 v[12:13], v[42:43], v[0:1] op_sel_hi:[1,0]
	v_pk_mul_f32 v[14:15], v[36:37], v[0:1] op_sel_hi:[1,0]
	v_pk_mul_f32 v[16:17], v[38:39], v[0:1] op_sel_hi:[1,0]
	v_pk_mul_f32 v[18:19], v[48:49], v[0:1] op_sel_hi:[1,0]
	v_pk_mul_f32 v[20:21], v[50:51], v[0:1] op_sel_hi:[1,0]
	v_cvt_pk_bf16_f32 v6, v6, v7
	v_cvt_pk_bf16_f32 v7, v8, v9
	v_cvt_pk_bf16_f32 v8, v10, v11
	v_cvt_pk_bf16_f32 v9, v12, v13
	v_cvt_pk_bf16_f32 v10, v14, v15
	v_cvt_pk_bf16_f32 v11, v16, v17
	v_cvt_pk_bf16_f32 v12, v18, v19
	v_cvt_pk_bf16_f32 v13, v20, v21
	global_store_dwordx2 v[2:3], v[6:7], off
	global_store_dwordx2 v[4:5], v[8:9], off offset:32
	global_store_dwordx2 v[4:5], v[10:11], off offset:64
	global_store_dwordx2 v[4:5], v[12:13], off offset:96

.LBB0_600:
	s_andn2_b64 vcc, exec, s[8:9]
	s_cbranch_vccnz .LBB0_505
	v_mov_b32_e32 v0, s64
	v_mov_b32_e32 v2, s65
	v_mov_b32_e32 v9, v247
	v_readfirstlane_b32 s7, v0
	v_readfirstlane_b32 s8, v2
	s_mov_b64 s[22:23], -1
	v_mov_b32_e32 v2, s7
	v_mov_b32_e32 v3, s8
	global_load_dwordx2 v[2:3], v[2:3], off offset:248
	s_mul_hi_i32 s7, s6, 0x38e38e39
	s_lshr_b32 s8, s7, 31
	s_ashr_i32 s7, s7, 2
	s_add_i32 s14, s7, s8
	s_mul_i32 s7, s14, 18
	s_sub_i32 s7, s6, s7
	s_cmp_gt_i32 s7, 1
	s_waitcnt vmcnt(0) lgkmcnt(0)
	v_mov_b32_e32 v0, v3
	s_nop 0
	v_readfirstlane_b32 s8, v2
	v_readfirstlane_b32 s9, v0
	s_cbranch_scc0 .LBB0_603
	s_ashr_i32 s15, s14, 31
	s_lshl_b64 s[12:13], s[14:15], 11
	s_lshl_b32 s15, s7, 7
	s_addk_i32 s15, 0xff00
	s_add_u32 s12, s12, s15
	s_addc_u32 s13, s13, 0
	s_mov_b64 s[22:23], 0

.LBB0_605:
	v_mov_b32_e32 v0, s64
	v_mov_b32_e32 v2, s65
	v_and_b32_e32 v19, 64, v219
	v_readfirstlane_b32 s7, v0
	v_readfirstlane_b32 s14, v2
	v_and_b32_e32 v0, 63, v9
	v_mov_b32_e32 v2, s7
	v_mov_b32_e32 v3, s14
	global_load_dwordx2 v[4:5], v[2:3], off offset:160
	v_ashrrev_i32_e32 v2, 6, v9
	v_lshl_add_u64 v[6:7], s[12:13], 0, v[0:1]
	v_ashrrev_i32_e32 v3, 31, v2
	v_lshl_add_u64 v[6:7], v[6:7], 3, v[2:3]
	v_readlane_b32 s7, v254, 52
	v_lshl_add_u64 v[6:7], v[6:7], 2, s[8:9]
	s_mov_b64 s[14:15], 0x20844000
	v_add_u32_e32 v10, s7, v2
	v_lshl_add_u64 v[12:13], v[6:7], 0, s[14:15]
	s_waitcnt vmcnt(0) lgkmcnt(0)
	v_ashrrev_i32_e32 v11, 31, v10
	v_readfirstlane_b32 s7, v4
	v_readfirstlane_b32 s14, v5
	v_cmp_eq_u32_e64 s[40:41], 0, v0
	v_mov_b32_e32 v4, s7
	v_mov_b32_e32 v5, s14
	v_lshl_add_u64 v[4:5], v[10:11], 2, v[4:5]
	global_load_dword v8, v[4:5], off
	s_mov_b32 s7, 0x20844000
	v_add_co_u32_e32 v4, vcc, s7, v6
	v_add_u32_e32 v10, -1, v219
	s_nop 0
	v_addc_co_u32_e32 v5, vcc, 0, v7, vcc
	global_load_dword v4, v[4:5], off
	s_nop 0
	global_load_dword v5, v[12:13], off offset:2048
	v_cmp_lt_i32_e32 vcc, v10, v19
	v_add_u32_e32 v12, -2, v219
	v_add_u32_e32 v13, -4, v219
	v_cndmask_b32_e32 v10, v10, v219, vcc
	v_lshlrev_b32_e32 v17, 2, v10
	v_cmp_lt_i32_e32 vcc, v12, v19
	v_add_u32_e32 v14, -8, v219
	v_add_u32_e32 v15, -16, v219
	v_cndmask_b32_e32 v12, v12, v219, vcc
	v_lshlrev_b32_e32 v12, 2, v12
	v_cmp_lt_i32_e32 vcc, v13, v19
	v_subrev_u32_e32 v16, 32, v219
	s_mov_b64 s[14:15], 0x208d4000
	v_cndmask_b32_e32 v13, v13, v219, vcc
	v_cmp_gt_u32_e32 vcc, 2, v0
	v_lshlrev_b32_e32 v13, 2, v13
	s_movk_i32 s7, 0x100
	s_waitcnt vmcnt(0) lgkmcnt(0)
	v_mul_f32_e32 v8, 0x3fb8aa3b, v8
	v_exp_f32_e32 v8, v8
	s_nop 0
	v_pk_mul_f32 v[10:11], v[4:5], v[8:9] op_sel_hi:[1,0] neg_lo:[0,1] neg_hi:[0,1]
	ds_bpermute_b32 v18, v17, v10
	ds_bpermute_b32 v17, v17, v11
	s_waitcnt lgkmcnt(1)
	v_add_f32_e32 v18, v10, v18
	s_waitcnt lgkmcnt(0)
	v_add_f32_e32 v17, v11, v17
	v_cndmask_b32_e64 v10, v18, v10, s[40:41]
	v_cndmask_b32_e64 v11, v17, v11, s[40:41]
	ds_bpermute_b32 v17, v12, v10
	ds_bpermute_b32 v12, v12, v11
	s_waitcnt lgkmcnt(1)
	v_add_f32_e32 v17, v10, v17
	s_waitcnt lgkmcnt(0)
	v_add_f32_e32 v12, v11, v12
	v_cndmask_b32_e32 v10, v17, v10, vcc
	v_cndmask_b32_e32 v11, v12, v11, vcc
	ds_bpermute_b32 v12, v13, v10
	ds_bpermute_b32 v13, v13, v11
	v_cmp_lt_i32_e32 vcc, v14, v19
	s_waitcnt lgkmcnt(1)
	v_add_f32_e32 v12, v10, v12
	v_cndmask_b32_e32 v14, v14, v219, vcc
	v_cmp_gt_u32_e32 vcc, 4, v0
	v_lshlrev_b32_e32 v14, 2, v14
	s_waitcnt lgkmcnt(0)
	v_add_f32_e32 v13, v11, v13
	v_cndmask_b32_e32 v10, v12, v10, vcc
	v_cndmask_b32_e32 v11, v13, v11, vcc
	ds_bpermute_b32 v12, v14, v10
	ds_bpermute_b32 v13, v14, v11
	v_cmp_lt_i32_e32 vcc, v15, v19
	s_waitcnt lgkmcnt(1)
	v_add_f32_e32 v12, v10, v12
	v_cndmask_b32_e32 v14, v15, v219, vcc
	v_cmp_gt_u32_e32 vcc, 8, v0
	v_lshlrev_b32_e32 v14, 2, v14
	s_waitcnt lgkmcnt(0)
	v_add_f32_e32 v13, v11, v13
	v_cndmask_b32_e32 v10, v12, v10, vcc
	v_cndmask_b32_e32 v11, v13, v11, vcc
	ds_bpermute_b32 v12, v14, v10
	ds_bpermute_b32 v13, v14, v11
	v_cmp_lt_i32_e32 vcc, v16, v19
	s_waitcnt lgkmcnt(1)
	v_add_f32_e32 v12, v10, v12
	v_cndmask_b32_e32 v14, v16, v219, vcc
	v_cmp_gt_u32_e32 vcc, 16, v0
	v_lshlrev_b32_e32 v14, 2, v14
	s_waitcnt lgkmcnt(0)
	v_add_f32_e32 v13, v11, v13
	v_cndmask_b32_e32 v12, v12, v10, vcc
	v_cndmask_b32_e32 v13, v13, v11, vcc
	ds_bpermute_b32 v15, v14, v12
	ds_bpermute_b32 v14, v14, v13
	v_bfrev_b32_e32 v10, 0.5
	v_cmp_gt_u32_e32 vcc, 32, v0
	v_lshl_or_b32 v16, v219, 2, v10
	s_waitcnt lgkmcnt(1)
	v_add_f32_e32 v15, v12, v15
	s_waitcnt lgkmcnt(0)
	v_add_f32_e32 v14, v13, v14
	v_cndmask_b32_e32 v12, v15, v12, vcc
	v_cndmask_b32_e32 v13, v14, v13, vcc
	ds_bpermute_b32 v17, v16, v12
	ds_bpermute_b32 v16, v16, v13
	v_add_co_u32_e32 v14, vcc, 0x208d4000, v6
	v_lshl_add_u64 v[10:11], v[6:7], 0, s[14:15]
	s_waitcnt lgkmcnt(1)
	v_add_f32_e32 v13, v13, v17
	v_addc_co_u32_e32 v15, vcc, 0, v7, vcc
	s_waitcnt lgkmcnt(0)
	v_add_f32_e32 v6, v17, v16
	v_pk_fma_f32 v[16:17], v[4:5], v[8:9], v[12:13] op_sel_hi:[1,0,1] neg_lo:[1,1,0] neg_hi:[1,1,0]
	v_cmp_gt_u32_e32 vcc, s7, v9
	v_pk_add_f32 v[16:17], v[6:7], v[16:17] op_sel_hi:[0,1] neg_lo:[0,1] neg_hi:[0,1]
	s_ashr_i32 s7, s6, 31
	v_cndmask_b32_e32 v7, v17, v13, vcc
	v_cndmask_b32_e32 v8, v16, v12, vcc
	global_store_dword v[14:15], v8, off
	global_store_dword v[10:11], v7, off offset:2048
	s_and_saveexec_b64 s[14:15], s[40:41]
	s_cbranch_execz .LBB0_607
	s_lshl_b64 s[22:23], s[6:7], 5
	s_add_u32 s22, s8, s22
	s_addc_u32 s23, s9, s23
	v_lshl_add_u64 v[10:11], v[2:3], 2, s[22:23]
	v_add_co_u32_e32 v10, vcc, 0x20964000, v10
	s_nop 1
	v_addc_co_u32_e32 v11, vcc, 0, v11, vcc
	global_store_dword v[10:11], v6, off

.LBB0_609:
	v_lshl_add_u64 v[78:79], v[84:85], 0, s[12:13]
	v_add_co_u32_e32 v66, vcc, s66, v78
	s_nop 1
	v_addc_co_u32_e32 v67, vcc, 0, v79, vcc
	global_load_dwordx4 v[66:69], v[66:67], off
	v_add_co_u32_e32 v70, vcc, s67, v78
	s_nop 1
	v_addc_co_u32_e32 v71, vcc, 0, v79, vcc
	global_load_dwordx4 v[70:73], v[70:71], off
	v_add_co_u32_e32 v74, vcc, s68, v78
	s_waitcnt vmcnt(0) lgkmcnt(0)
	v_and_b32_e32 v95, 0xffff0000, v66
	v_addc_co_u32_e32 v75, vcc, 0, v79, vcc
	global_load_dwordx4 v[74:77], v[74:75], off
	v_add_co_u32_e32 v78, vcc, s69, v78
	v_lshlrev_b32_e32 v94, 16, v66
	s_nop 0
	v_addc_co_u32_e32 v79, vcc, 0, v79, vcc
	global_load_dwordx4 v[78:81], v[78:79], off
	ds_read_b128 v[116:119], v0
	ds_read_b128 v[120:123], v0 offset:16
	v_add_u32_e32 v0, 0x80, v0
	s_waitcnt lgkmcnt(0)
	v_pk_mul_f32 v[94:95], v[116:117], v[94:95]
	s_nop 0
	v_cvt_pk_bf16_f32 v66, v94, v95
	v_and_b32_e32 v95, 0xffff0000, v70
	v_lshlrev_b32_e32 v94, 16, v70
	v_pk_mul_f32 v[94:95], v[116:117], v[94:95]
	s_nop 0
	v_cvt_pk_bf16_f32 v70, v94, v95
	s_waitcnt vmcnt(0)
	v_and_b32_e32 v95, 0xffff0000, v74
	v_lshlrev_b32_e32 v94, 16, v74
	v_pk_mul_f32 v[94:95], v[116:117], v[94:95]
	s_nop 0
	v_cvt_pk_bf16_f32 v74, v94, v95
	v_and_b32_e32 v95, 0xffff0000, v78
	v_lshlrev_b32_e32 v94, 16, v78
	v_pk_mul_f32 v[94:95], v[116:117], v[94:95]
	s_nop 0
	v_cvt_pk_bf16_f32 v78, v94, v95
	v_and_b32_e32 v95, 0xffff0000, v67
	v_lshlrev_b32_e32 v94, 16, v67
	v_pk_mul_f32 v[94:95], v[118:119], v[94:95]
	s_nop 0
	v_cvt_pk_bf16_f32 v67, v94, v95
	v_and_b32_e32 v95, 0xffff0000, v71
	v_lshlrev_b32_e32 v94, 16, v71
	v_pk_mul_f32 v[94:95], v[118:119], v[94:95]
	s_nop 0
	v_cvt_pk_bf16_f32 v71, v94, v95
	v_and_b32_e32 v95, 0xffff0000, v75
	v_lshlrev_b32_e32 v94, 16, v75
	v_pk_mul_f32 v[94:95], v[118:119], v[94:95]
	s_nop 0
	v_cvt_pk_bf16_f32 v75, v94, v95
	v_and_b32_e32 v95, 0xffff0000, v79
	v_lshlrev_b32_e32 v94, 16, v79
	v_pk_mul_f32 v[94:95], v[118:119], v[94:95]
	s_nop 0
	v_cvt_pk_bf16_f32 v79, v94, v95
	v_and_b32_e32 v95, 0xffff0000, v68
	v_lshlrev_b32_e32 v94, 16, v68
	v_pk_mul_f32 v[94:95], v[120:121], v[94:95]
	s_nop 0
	v_cvt_pk_bf16_f32 v68, v94, v95
	v_and_b32_e32 v95, 0xffff0000, v72
	v_lshlrev_b32_e32 v94, 16, v72
	v_pk_mul_f32 v[94:95], v[120:121], v[94:95]
	s_nop 0
	v_cvt_pk_bf16_f32 v72, v94, v95
	v_and_b32_e32 v95, 0xffff0000, v76
	v_lshlrev_b32_e32 v94, 16, v76
	v_pk_mul_f32 v[94:95], v[120:121], v[94:95]
	s_nop 0
	v_cvt_pk_bf16_f32 v76, v94, v95
	v_and_b32_e32 v95, 0xffff0000, v80
	v_lshlrev_b32_e32 v94, 16, v80
	v_pk_mul_f32 v[94:95], v[120:121], v[94:95]
	s_nop 0
	v_cvt_pk_bf16_f32 v80, v94, v95
	v_and_b32_e32 v95, 0xffff0000, v69
	v_lshlrev_b32_e32 v94, 16, v69
	v_pk_mul_f32 v[94:95], v[122:123], v[94:95]
	s_nop 0
	v_cvt_pk_bf16_f32 v69, v94, v95
	v_and_b32_e32 v95, 0xffff0000, v73
	v_lshlrev_b32_e32 v94, 16, v73
	v_pk_mul_f32 v[94:95], v[122:123], v[94:95]
	s_nop 0
	v_cvt_pk_bf16_f32 v73, v94, v95
	v_and_b32_e32 v95, 0xffff0000, v77
	v_lshlrev_b32_e32 v94, 16, v77
	v_pk_mul_f32 v[94:95], v[122:123], v[94:95]
	s_nop 0
	v_cvt_pk_bf16_f32 v77, v94, v95
	v_and_b32_e32 v95, 0xffff0000, v81
	v_lshlrev_b32_e32 v94, 16, v81
	v_pk_mul_f32 v[94:95], v[122:123], v[94:95]
	s_nop 0
	v_cvt_pk_bf16_f32 v81, v94, v95
	v_lshl_add_u64 v[94:95], v[92:93], 0, s[12:13]
	v_add_co_u32_e32 v116, vcc, s70, v94
	s_nop 1
	v_addc_co_u32_e32 v117, vcc, 0, v95, vcc
	global_load_dwordx4 v[116:119], v[116:117], off
	s_waitcnt vmcnt(0) lgkmcnt(0)
	v_mfma_f32_16x16x32_bf16 v[62:65], v[66:69], v[116:119], v[62:65]
	v_mfma_f32_16x16x32_bf16 v[46:49], v[70:73], v[116:119], v[46:49]
	v_mfma_f32_16x16x32_bf16 v[30:33], v[74:77], v[116:119], v[30:33]
	v_mfma_f32_16x16x32_bf16 v[14:17], v[78:81], v[116:119], v[14:17]
	v_add_co_u32_e32 v116, vcc, s71, v94
	s_nop 1
	v_addc_co_u32_e32 v117, vcc, 0, v95, vcc
	global_load_dwordx4 v[116:119], v[116:117], off
	v_add_co_u32_e32 v94, vcc, s72, v94
	s_waitcnt vmcnt(0) lgkmcnt(0)
	v_mfma_f32_16x16x32_bf16 v[58:61], v[66:69], v[116:119], v[58:61]
	v_addc_co_u32_e32 v95, vcc, 0, v95, vcc
	v_mfma_f32_16x16x32_bf16 v[42:45], v[70:73], v[116:119], v[42:45]
	v_mfma_f32_16x16x32_bf16 v[26:29], v[74:77], v[116:119], v[26:29]
	v_mfma_f32_16x16x32_bf16 v[10:13], v[78:81], v[116:119], v[10:13]
	global_load_dwordx4 v[116:119], v[94:95], off
	v_lshl_add_u64 v[94:95], v[90:91], 0, s[12:13]
	s_add_u32 s12, s12, 64
	s_waitcnt vmcnt(0) lgkmcnt(0)
	v_mfma_f32_16x16x32_bf16 v[54:57], v[66:69], v[116:119], v[54:57]
	s_addc_u32 s13, s13, 0
	s_cmpk_eq_i32 s12, 0x100
	v_mfma_f32_16x16x32_bf16 v[38:41], v[70:73], v[116:119], v[38:41]
	v_mfma_f32_16x16x32_bf16 v[22:25], v[74:77], v[116:119], v[22:25]
	v_mfma_f32_16x16x32_bf16 v[6:9], v[78:81], v[116:119], v[6:9]
	global_load_dwordx4 v[116:119], v[94:95], off
	s_waitcnt vmcnt(0) lgkmcnt(0)
	v_mfma_f32_16x16x32_bf16 v[50:53], v[66:69], v[116:119], v[50:53]
	v_mfma_f32_16x16x32_bf16 v[34:37], v[70:73], v[116:119], v[34:37]
	v_mfma_f32_16x16x32_bf16 v[18:21], v[74:77], v[116:119], v[18:21]
	v_mfma_f32_16x16x32_bf16 v[2:5], v[78:81], v[116:119], v[2:5]
	s_cbranch_scc0 .LBB0_609
	v_or_b32_e32 v0, v114, v97
	v_lshl_add_u64 v[66:67], v[0:1], 2, v[82:83]
	v_add_u32_e32 v0, v114, v97
	global_store_dword v[66:67], v62, off
	v_lshl_add_u64 v[66:67], v[0:1], 2, v[82:83]
	v_add_u32_e32 v0, v114, v98
	global_store_dword v[66:67], v63, off offset:512
	global_store_dword v[66:67], v64, off offset:1024
	global_store_dword v[66:67], v65, off offset:1536
	global_store_dword v[66:67], v58, off offset:64
	v_lshl_add_u64 v[62:63], v[0:1], 2, v[82:83]
	v_add_u32_e32 v0, v114, v99
	global_store_dword v[62:63], v59, off offset:64
	v_lshl_add_u64 v[58:59], v[0:1], 2, v[82:83]
	v_add_u32_e32 v0, v114, v100
	v_lshl_add_u64 v[64:65], v[0:1], 2, v[82:83]
	v_or_b32_e32 v0, v114, v101
	global_store_dword v[58:59], v60, off offset:64
	global_store_dword v[64:65], v61, off offset:64
	global_store_dword v[66:67], v54, off offset:128
	global_store_dword v[62:63], v55, off offset:128
	global_store_dword v[58:59], v56, off offset:128
	global_store_dword v[64:65], v57, off offset:128
	global_store_dword v[66:67], v50, off offset:192
	global_store_dword v[62:63], v51, off offset:192
	global_store_dword v[58:59], v52, off offset:192
	global_store_dword v[64:65], v53, off offset:192
	v_lshl_add_u64 v[50:51], v[0:1], 2, v[82:83]
	v_or_b32_e32 v0, v114, v102
	global_store_dword v[50:51], v46, off
	v_lshl_add_u64 v[50:51], v[0:1], 2, v[82:83]
	v_or_b32_e32 v0, v114, v103
	global_store_dword v[50:51], v47, off
	v_lshl_add_u64 v[46:47], v[0:1], 2, v[82:83]
	v_or_b32_e32 v0, v114, v104
	global_store_dword v[46:47], v48, off
	v_lshl_add_u64 v[46:47], v[0:1], 2, v[82:83]
	v_add_u32_e32 v0, v114, v101
	global_store_dword v[46:47], v49, off
	v_lshl_add_u64 v[46:47], v[0:1], 2, v[82:83]
	v_add_u32_e32 v0, v114, v102
	v_lshl_add_u64 v[48:49], v[0:1], 2, v[82:83]
	v_add_u32_e32 v0, v114, v103
	global_store_dword v[46:47], v42, off offset:64
	global_store_dword v[48:49], v43, off offset:64
	v_lshl_add_u64 v[42:43], v[0:1], 2, v[82:83]
	v_add_u32_e32 v0, v114, v104
	v_lshl_add_u64 v[50:51], v[0:1], 2, v[82:83]
	v_or_b32_e32 v0, v114, v105
	global_store_dword v[42:43], v44, off offset:64
	global_store_dword v[50:51], v45, off offset:64
	global_store_dword v[46:47], v38, off offset:128
	global_store_dword v[48:49], v39, off offset:128
	global_store_dword v[42:43], v40, off offset:128
	global_store_dword v[50:51], v41, off offset:128
	global_store_dword v[46:47], v34, off offset:192
	global_store_dword v[48:49], v35, off offset:192
	global_store_dword v[42:43], v36, off offset:192
	global_store_dword v[50:51], v37, off offset:192
	v_lshl_add_u64 v[34:35], v[0:1], 2, v[82:83]
	v_or_b32_e32 v0, v114, v106
	global_store_dword v[34:35], v30, off
	v_lshl_add_u64 v[34:35], v[0:1], 2, v[82:83]
	v_or_b32_e32 v0, v114, v107
	global_store_dword v[34:35], v31, off
	v_lshl_add_u64 v[30:31], v[0:1], 2, v[82:83]
	v_or_b32_e32 v0, v114, v108
	global_store_dword v[30:31], v32, off
	v_lshl_add_u64 v[30:31], v[0:1], 2, v[82:83]
	v_add_u32_e32 v0, v114, v105
	global_store_dword v[30:31], v33, off
	v_lshl_add_u64 v[30:31], v[0:1], 2, v[82:83]
	v_add_u32_e32 v0, v114, v106
	v_lshl_add_u64 v[32:33], v[0:1], 2, v[82:83]
	v_add_u32_e32 v0, v114, v107
	global_store_dword v[30:31], v26, off offset:64
	global_store_dword v[32:33], v27, off offset:64
	v_lshl_add_u64 v[26:27], v[0:1], 2, v[82:83]
	v_add_u32_e32 v0, v114, v108
	v_lshl_add_u64 v[34:35], v[0:1], 2, v[82:83]
	v_or_b32_e32 v0, v114, v109
	global_store_dword v[26:27], v28, off offset:64
	global_store_dword v[34:35], v29, off offset:64
	global_store_dword v[30:31], v22, off offset:128
	global_store_dword v[32:33], v23, off offset:128
	global_store_dword v[26:27], v24, off offset:128
	global_store_dword v[34:35], v25, off offset:128
	global_store_dword v[30:31], v18, off offset:192
	global_store_dword v[32:33], v19, off offset:192
	global_store_dword v[26:27], v20, off offset:192
	global_store_dword v[34:35], v21, off offset:192
	v_lshl_add_u64 v[18:19], v[0:1], 2, v[82:83]
	v_or_b32_e32 v0, v114, v110
	global_store_dword v[18:19], v14, off
	v_lshl_add_u64 v[18:19], v[0:1], 2, v[82:83]
	v_or_b32_e32 v0, v114, v111
	global_store_dword v[18:19], v15, off
	v_lshl_add_u64 v[14:15], v[0:1], 2, v[82:83]
	v_or_b32_e32 v0, v114, v112
	global_store_dword v[14:15], v16, off
	v_lshl_add_u64 v[14:15], v[0:1], 2, v[82:83]
	v_add_u32_e32 v0, v114, v109
	global_store_dword v[14:15], v17, off
	v_lshl_add_u64 v[14:15], v[0:1], 2, v[82:83]
	v_add_u32_e32 v0, v114, v110
	v_lshl_add_u64 v[16:17], v[0:1], 2, v[82:83]
	v_add_u32_e32 v0, v114, v111
	global_store_dword v[14:15], v10, off offset:64
	global_store_dword v[16:17], v11, off offset:64
	v_lshl_add_u64 v[10:11], v[0:1], 2, v[82:83]
	v_add_u32_e32 v0, v114, v112
	v_lshl_add_u64 v[18:19], v[0:1], 2, v[82:83]
	s_mov_b32 s7, 64
	s_mov_b64 s[12:13], 0
	s_and_b64 vcc, exec, s[8:9]
	global_store_dword v[10:11], v12, off offset:64
	global_store_dword v[18:19], v13, off offset:64
	global_store_dword v[14:15], v6, off offset:128
	global_store_dword v[16:17], v7, off offset:128
	global_store_dword v[10:11], v8, off offset:128
	global_store_dword v[18:19], v9, off offset:128
	global_store_dword v[14:15], v2, off offset:192
	global_store_dword v[16:17], v3, off offset:192
	global_store_dword v[10:11], v4, off offset:192
	global_store_dword v[18:19], v5, off offset:192
	s_cbranch_vccz .LBB0_608
	s_waitcnt lgkmcnt(0)
	s_barrier
	s_branch .LBB0_505

.LBB0_613:
	s_andn2_b64 vcc, exec, s[6:7]
	s_cbranch_vccnz .LBB0_727
	s_cmpk_gt_i32 s44, 0x8f
	s_cbranch_scc1 .LBB0_626
	v_mov_b32_e32 v0, s64
	v_mov_b32_e32 v2, s65
	v_mov_b32_e32 v9, v247
	v_readfirstlane_b32 s0, v0
	v_readfirstlane_b32 s1, v2
	s_mov_b64 s[14:15], -1
	v_mov_b32_e32 v2, s0
	v_mov_b32_e32 v3, s1
	global_load_dwordx2 v[2:3], v[2:3], off offset:248
	s_mul_hi_i32 s0, s44, 0x38e38e39
	s_lshr_b32 s1, s0, 31
	s_ashr_i32 s0, s0, 2
	s_add_i32 s12, s0, s1
	s_mul_i32 s0, s12, 18
	s_sub_i32 s0, s44, s0
	s_cmp_gt_i32 s0, 1
	s_waitcnt vmcnt(0) lgkmcnt(0)
	v_mov_b32_e32 v0, v3
	s_nop 0
	v_readfirstlane_b32 s6, v2
	v_readfirstlane_b32 s7, v0
	s_cbranch_scc0 .LBB0_617
	s_ashr_i32 s13, s12, 31
	s_lshl_b32 s1, s0, 7
	s_lshl_b64 s[4:5], s[12:13], 11
	s_addk_i32 s1, 0xff00
	s_add_u32 s8, s4, s1
	s_addc_u32 s9, s5, 0
	s_mov_b64 s[14:15], 0

.LBB0_619:
	v_mov_b32_e32 v0, s64
	v_mov_b32_e32 v2, s65
	v_and_b32_e32 v19, 64, v219
	v_readfirstlane_b32 s0, v0
	v_readfirstlane_b32 s1, v2
	v_and_b32_e32 v0, 63, v9
	v_mov_b32_e32 v2, s0
	v_mov_b32_e32 v3, s1
	global_load_dwordx2 v[4:5], v[2:3], off offset:160
	v_ashrrev_i32_e32 v2, 6, v9
	v_lshl_add_u64 v[6:7], s[8:9], 0, v[0:1]
	v_ashrrev_i32_e32 v3, 31, v2
	v_readlane_b32 s0, v254, 52
	v_lshl_add_u64 v[6:7], v[6:7], 3, v[2:3]
	v_lshl_add_u64 v[6:7], v[6:7], 2, s[6:7]
	v_add_u32_e32 v10, s0, v2
	s_mov_b64 s[0:1], 0x20844000
	v_lshl_add_u64 v[12:13], v[6:7], 0, s[0:1]
	s_waitcnt vmcnt(0) lgkmcnt(0)
	v_ashrrev_i32_e32 v11, 31, v10
	v_readfirstlane_b32 s0, v4
	v_readfirstlane_b32 s1, v5
	v_cmp_eq_u32_e64 s[40:41], 0, v0
	v_mov_b32_e32 v4, s0
	v_mov_b32_e32 v5, s1
	v_lshl_add_u64 v[4:5], v[10:11], 2, v[4:5]
	global_load_dword v8, v[4:5], off
	s_mov_b32 s0, 0x20844000
	v_add_co_u32_e32 v4, vcc, s0, v6
	v_add_u32_e32 v10, -1, v219
	s_nop 0
	v_addc_co_u32_e32 v5, vcc, 0, v7, vcc
	global_load_dword v4, v[4:5], off
	s_nop 0
	global_load_dword v5, v[12:13], off offset:2048
	v_cmp_lt_i32_e32 vcc, v10, v19
	v_add_u32_e32 v12, -2, v219
	v_add_u32_e32 v13, -4, v219
	v_cndmask_b32_e32 v10, v10, v219, vcc
	v_lshlrev_b32_e32 v17, 2, v10
	v_cmp_lt_i32_e32 vcc, v12, v19
	v_add_u32_e32 v14, -8, v219
	v_add_u32_e32 v15, -16, v219
	v_cndmask_b32_e32 v12, v12, v219, vcc
	v_lshlrev_b32_e32 v12, 2, v12
	v_cmp_lt_i32_e32 vcc, v13, v19
	v_subrev_u32_e32 v16, 32, v219
	s_mov_b64 s[0:1], 0x208d4000
	v_cndmask_b32_e32 v13, v13, v219, vcc
	v_cmp_gt_u32_e32 vcc, 2, v0
	v_lshlrev_b32_e32 v13, 2, v13
	s_ashr_i32 s45, s44, 31
	s_waitcnt vmcnt(0) lgkmcnt(0)
	v_mul_f32_e32 v8, 0x3fb8aa3b, v8
	v_exp_f32_e32 v8, v8
	s_nop 0
	v_pk_mul_f32 v[10:11], v[4:5], v[8:9] op_sel_hi:[1,0] neg_lo:[0,1] neg_hi:[0,1]
	ds_bpermute_b32 v18, v17, v10
	ds_bpermute_b32 v17, v17, v11
	s_waitcnt lgkmcnt(1)
	v_add_f32_e32 v18, v10, v18
	s_waitcnt lgkmcnt(0)
	v_add_f32_e32 v17, v11, v17
	v_cndmask_b32_e64 v10, v18, v10, s[40:41]
	v_cndmask_b32_e64 v11, v17, v11, s[40:41]
	ds_bpermute_b32 v17, v12, v10
	ds_bpermute_b32 v12, v12, v11
	s_waitcnt lgkmcnt(1)
	v_add_f32_e32 v17, v10, v17
	s_waitcnt lgkmcnt(0)
	v_add_f32_e32 v12, v11, v12
	v_cndmask_b32_e32 v10, v17, v10, vcc
	v_cndmask_b32_e32 v11, v12, v11, vcc
	ds_bpermute_b32 v12, v13, v10
	ds_bpermute_b32 v13, v13, v11
	v_cmp_lt_i32_e32 vcc, v14, v19
	s_waitcnt lgkmcnt(1)
	v_add_f32_e32 v12, v10, v12
	v_cndmask_b32_e32 v14, v14, v219, vcc
	v_cmp_gt_u32_e32 vcc, 4, v0
	v_lshlrev_b32_e32 v14, 2, v14
	s_waitcnt lgkmcnt(0)
	v_add_f32_e32 v13, v11, v13
	v_cndmask_b32_e32 v10, v12, v10, vcc
	v_cndmask_b32_e32 v11, v13, v11, vcc
	ds_bpermute_b32 v12, v14, v10
	ds_bpermute_b32 v13, v14, v11
	v_cmp_lt_i32_e32 vcc, v15, v19
	s_waitcnt lgkmcnt(1)
	v_add_f32_e32 v12, v10, v12
	v_cndmask_b32_e32 v14, v15, v219, vcc
	v_cmp_gt_u32_e32 vcc, 8, v0
	v_lshlrev_b32_e32 v14, 2, v14
	s_waitcnt lgkmcnt(0)
	v_add_f32_e32 v13, v11, v13
	v_cndmask_b32_e32 v10, v12, v10, vcc
	v_cndmask_b32_e32 v11, v13, v11, vcc
	ds_bpermute_b32 v12, v14, v10
	ds_bpermute_b32 v13, v14, v11
	v_cmp_lt_i32_e32 vcc, v16, v19
	s_waitcnt lgkmcnt(1)
	v_add_f32_e32 v12, v10, v12
	v_cndmask_b32_e32 v14, v16, v219, vcc
	v_cmp_gt_u32_e32 vcc, 16, v0
	v_lshlrev_b32_e32 v14, 2, v14
	s_waitcnt lgkmcnt(0)
	v_add_f32_e32 v13, v11, v13
	v_cndmask_b32_e32 v12, v12, v10, vcc
	v_cndmask_b32_e32 v13, v13, v11, vcc
	ds_bpermute_b32 v15, v14, v12
	ds_bpermute_b32 v14, v14, v13
	v_bfrev_b32_e32 v10, 0.5
	v_cmp_gt_u32_e32 vcc, 32, v0
	v_lshl_or_b32 v16, v219, 2, v10
	s_waitcnt lgkmcnt(1)
	v_add_f32_e32 v15, v12, v15
	s_waitcnt lgkmcnt(0)
	v_add_f32_e32 v14, v13, v14
	v_cndmask_b32_e32 v12, v15, v12, vcc
	v_cndmask_b32_e32 v13, v14, v13, vcc
	ds_bpermute_b32 v17, v16, v12
	ds_bpermute_b32 v16, v16, v13
	v_add_co_u32_e32 v14, vcc, 0x208d4000, v6
	v_lshl_add_u64 v[10:11], v[6:7], 0, s[0:1]
	s_waitcnt lgkmcnt(1)
	v_add_f32_e32 v13, v13, v17
	v_addc_co_u32_e32 v15, vcc, 0, v7, vcc
	s_waitcnt lgkmcnt(0)
	v_add_f32_e32 v6, v17, v16
	v_pk_fma_f32 v[16:17], v[4:5], v[8:9], v[12:13] op_sel_hi:[1,0,1] neg_lo:[1,1,0] neg_hi:[1,1,0]
	s_movk_i32 s0, 0x100
	v_pk_add_f32 v[16:17], v[6:7], v[16:17] op_sel_hi:[0,1] neg_lo:[0,1] neg_hi:[0,1]
	v_cmp_gt_u32_e32 vcc, s0, v9
	s_nop 1
	v_cndmask_b32_e32 v7, v17, v13, vcc
	v_cndmask_b32_e32 v8, v16, v12, vcc
	global_store_dword v[14:15], v8, off
	global_store_dword v[10:11], v7, off offset:2048
	s_and_saveexec_b64 s[12:13], s[40:41]
	s_cbranch_execz .LBB0_621
	s_lshl_b64 s[0:1], s[44:45], 5
	s_add_u32 s0, s6, s0
	s_addc_u32 s1, s7, s1
	v_lshl_add_u64 v[10:11], v[2:3], 2, s[0:1]
	v_add_co_u32_e32 v10, vcc, 0x20964000, v10
	s_nop 1
	v_addc_co_u32_e32 v11, vcc, 0, v11, vcc
	global_store_dword v[10:11], v6, off

.LBB0_623:
	v_lshl_add_u64 v[78:79], v[84:85], 0, s[8:9]
	v_add_co_u32_e32 v66, vcc, s66, v78
	s_nop 1
	v_addc_co_u32_e32 v67, vcc, 0, v79, vcc
	global_load_dwordx4 v[66:69], v[66:67], off
	v_add_co_u32_e32 v70, vcc, s67, v78
	s_nop 1
	v_addc_co_u32_e32 v71, vcc, 0, v79, vcc
	global_load_dwordx4 v[70:73], v[70:71], off
	v_add_co_u32_e32 v74, vcc, s68, v78
	s_waitcnt vmcnt(0) lgkmcnt(0)
	v_and_b32_e32 v95, 0xffff0000, v66
	v_addc_co_u32_e32 v75, vcc, 0, v79, vcc
	global_load_dwordx4 v[74:77], v[74:75], off
	v_add_co_u32_e32 v78, vcc, s69, v78
	v_lshlrev_b32_e32 v94, 16, v66
	s_nop 0
	v_addc_co_u32_e32 v79, vcc, 0, v79, vcc
	global_load_dwordx4 v[78:81], v[78:79], off
	ds_read_b128 v[116:119], v0
	ds_read_b128 v[120:123], v0 offset:16
	v_add_u32_e32 v0, 0x80, v0
	s_waitcnt lgkmcnt(0)
	v_pk_mul_f32 v[94:95], v[116:117], v[94:95]
	s_nop 0
	v_cvt_pk_bf16_f32 v66, v94, v95
	v_and_b32_e32 v95, 0xffff0000, v70
	v_lshlrev_b32_e32 v94, 16, v70
	v_pk_mul_f32 v[94:95], v[116:117], v[94:95]
	s_nop 0
	v_cvt_pk_bf16_f32 v70, v94, v95
	s_waitcnt vmcnt(0)
	v_and_b32_e32 v95, 0xffff0000, v74
	v_lshlrev_b32_e32 v94, 16, v74
	v_pk_mul_f32 v[94:95], v[116:117], v[94:95]
	s_nop 0
	v_cvt_pk_bf16_f32 v74, v94, v95
	v_and_b32_e32 v95, 0xffff0000, v78
	v_lshlrev_b32_e32 v94, 16, v78
	v_pk_mul_f32 v[94:95], v[116:117], v[94:95]
	s_nop 0
	v_cvt_pk_bf16_f32 v78, v94, v95
	v_and_b32_e32 v95, 0xffff0000, v67
	v_lshlrev_b32_e32 v94, 16, v67
	v_pk_mul_f32 v[94:95], v[118:119], v[94:95]
	s_nop 0
	v_cvt_pk_bf16_f32 v67, v94, v95
	v_and_b32_e32 v95, 0xffff0000, v71
	v_lshlrev_b32_e32 v94, 16, v71
	v_pk_mul_f32 v[94:95], v[118:119], v[94:95]
	s_nop 0
	v_cvt_pk_bf16_f32 v71, v94, v95
	v_and_b32_e32 v95, 0xffff0000, v75
	v_lshlrev_b32_e32 v94, 16, v75
	v_pk_mul_f32 v[94:95], v[118:119], v[94:95]
	s_nop 0
	v_cvt_pk_bf16_f32 v75, v94, v95
	v_and_b32_e32 v95, 0xffff0000, v79
	v_lshlrev_b32_e32 v94, 16, v79
	v_pk_mul_f32 v[94:95], v[118:119], v[94:95]
	s_nop 0
	v_cvt_pk_bf16_f32 v79, v94, v95
	v_and_b32_e32 v95, 0xffff0000, v68
	v_lshlrev_b32_e32 v94, 16, v68
	v_pk_mul_f32 v[94:95], v[120:121], v[94:95]
	s_nop 0
	v_cvt_pk_bf16_f32 v68, v94, v95
	v_and_b32_e32 v95, 0xffff0000, v72
	v_lshlrev_b32_e32 v94, 16, v72
	v_pk_mul_f32 v[94:95], v[120:121], v[94:95]
	s_nop 0
	v_cvt_pk_bf16_f32 v72, v94, v95
	v_and_b32_e32 v95, 0xffff0000, v76
	v_lshlrev_b32_e32 v94, 16, v76
	v_pk_mul_f32 v[94:95], v[120:121], v[94:95]
	s_nop 0
	v_cvt_pk_bf16_f32 v76, v94, v95
	v_and_b32_e32 v95, 0xffff0000, v80
	v_lshlrev_b32_e32 v94, 16, v80
	v_pk_mul_f32 v[94:95], v[120:121], v[94:95]
	s_nop 0
	v_cvt_pk_bf16_f32 v80, v94, v95
	v_and_b32_e32 v95, 0xffff0000, v69
	v_lshlrev_b32_e32 v94, 16, v69
	v_pk_mul_f32 v[94:95], v[122:123], v[94:95]
	s_nop 0
	v_cvt_pk_bf16_f32 v69, v94, v95
	v_and_b32_e32 v95, 0xffff0000, v73
	v_lshlrev_b32_e32 v94, 16, v73
	v_pk_mul_f32 v[94:95], v[122:123], v[94:95]
	s_nop 0
	v_cvt_pk_bf16_f32 v73, v94, v95
	v_and_b32_e32 v95, 0xffff0000, v77
	v_lshlrev_b32_e32 v94, 16, v77
	v_pk_mul_f32 v[94:95], v[122:123], v[94:95]
	s_nop 0
	v_cvt_pk_bf16_f32 v77, v94, v95
	v_and_b32_e32 v95, 0xffff0000, v81
	v_lshlrev_b32_e32 v94, 16, v81
	v_pk_mul_f32 v[94:95], v[122:123], v[94:95]
	s_nop 0
	v_cvt_pk_bf16_f32 v81, v94, v95
	v_lshl_add_u64 v[94:95], v[92:93], 0, s[8:9]
	v_add_co_u32_e32 v116, vcc, s70, v94
	s_nop 1
	v_addc_co_u32_e32 v117, vcc, 0, v95, vcc
	global_load_dwordx4 v[116:119], v[116:117], off
	s_waitcnt vmcnt(0) lgkmcnt(0)
	v_mfma_f32_16x16x32_bf16 v[62:65], v[66:69], v[116:119], v[62:65]
	v_mfma_f32_16x16x32_bf16 v[46:49], v[70:73], v[116:119], v[46:49]
	v_mfma_f32_16x16x32_bf16 v[30:33], v[74:77], v[116:119], v[30:33]
	v_mfma_f32_16x16x32_bf16 v[14:17], v[78:81], v[116:119], v[14:17]
	v_add_co_u32_e32 v116, vcc, s71, v94
	s_nop 1
	v_addc_co_u32_e32 v117, vcc, 0, v95, vcc
	global_load_dwordx4 v[116:119], v[116:117], off
	v_add_co_u32_e32 v94, vcc, s72, v94
	s_waitcnt vmcnt(0) lgkmcnt(0)
	v_mfma_f32_16x16x32_bf16 v[58:61], v[66:69], v[116:119], v[58:61]
	v_addc_co_u32_e32 v95, vcc, 0, v95, vcc
	v_mfma_f32_16x16x32_bf16 v[42:45], v[70:73], v[116:119], v[42:45]
	v_mfma_f32_16x16x32_bf16 v[26:29], v[74:77], v[116:119], v[26:29]
	v_mfma_f32_16x16x32_bf16 v[10:13], v[78:81], v[116:119], v[10:13]
	global_load_dwordx4 v[116:119], v[94:95], off
	v_lshl_add_u64 v[94:95], v[90:91], 0, s[8:9]
	s_add_u32 s8, s8, 64
	s_waitcnt vmcnt(0) lgkmcnt(0)
	v_mfma_f32_16x16x32_bf16 v[54:57], v[66:69], v[116:119], v[54:57]
	s_addc_u32 s9, s9, 0
	s_cmpk_eq_i32 s8, 0x100
	v_mfma_f32_16x16x32_bf16 v[38:41], v[70:73], v[116:119], v[38:41]
	v_mfma_f32_16x16x32_bf16 v[22:25], v[74:77], v[116:119], v[22:25]
	v_mfma_f32_16x16x32_bf16 v[6:9], v[78:81], v[116:119], v[6:9]
	global_load_dwordx4 v[116:119], v[94:95], off
	s_waitcnt vmcnt(0) lgkmcnt(0)
	v_mfma_f32_16x16x32_bf16 v[50:53], v[66:69], v[116:119], v[50:53]
	v_mfma_f32_16x16x32_bf16 v[34:37], v[70:73], v[116:119], v[34:37]
	v_mfma_f32_16x16x32_bf16 v[18:21], v[74:77], v[116:119], v[18:21]
	v_mfma_f32_16x16x32_bf16 v[2:5], v[78:81], v[116:119], v[2:5]
	s_cbranch_scc0 .LBB0_623
	v_or_b32_e32 v0, v114, v97
	v_lshl_add_u64 v[66:67], v[0:1], 2, v[82:83]
	v_add_u32_e32 v0, v114, v97
	global_store_dword v[66:67], v62, off
	v_lshl_add_u64 v[66:67], v[0:1], 2, v[82:83]
	v_add_u32_e32 v0, v114, v98
	global_store_dword v[66:67], v63, off offset:512
	global_store_dword v[66:67], v64, off offset:1024
	global_store_dword v[66:67], v65, off offset:1536
	global_store_dword v[66:67], v58, off offset:64
	v_lshl_add_u64 v[62:63], v[0:1], 2, v[82:83]
	v_add_u32_e32 v0, v114, v99
	global_store_dword v[62:63], v59, off offset:64
	v_lshl_add_u64 v[58:59], v[0:1], 2, v[82:83]
	v_add_u32_e32 v0, v114, v100
	v_lshl_add_u64 v[64:65], v[0:1], 2, v[82:83]
	v_or_b32_e32 v0, v114, v101
	global_store_dword v[58:59], v60, off offset:64
	global_store_dword v[64:65], v61, off offset:64
	global_store_dword v[66:67], v54, off offset:128
	global_store_dword v[62:63], v55, off offset:128
	global_store_dword v[58:59], v56, off offset:128
	global_store_dword v[64:65], v57, off offset:128
	global_store_dword v[66:67], v50, off offset:192
	global_store_dword v[62:63], v51, off offset:192
	global_store_dword v[58:59], v52, off offset:192
	global_store_dword v[64:65], v53, off offset:192
	v_lshl_add_u64 v[50:51], v[0:1], 2, v[82:83]
	v_or_b32_e32 v0, v114, v102
	global_store_dword v[50:51], v46, off
	v_lshl_add_u64 v[50:51], v[0:1], 2, v[82:83]
	v_or_b32_e32 v0, v114, v103
	global_store_dword v[50:51], v47, off
	v_lshl_add_u64 v[46:47], v[0:1], 2, v[82:83]
	v_or_b32_e32 v0, v114, v104
	global_store_dword v[46:47], v48, off
	v_lshl_add_u64 v[46:47], v[0:1], 2, v[82:83]
	v_add_u32_e32 v0, v114, v101
	global_store_dword v[46:47], v49, off
	v_lshl_add_u64 v[46:47], v[0:1], 2, v[82:83]
	v_add_u32_e32 v0, v114, v102
	v_lshl_add_u64 v[48:49], v[0:1], 2, v[82:83]
	v_add_u32_e32 v0, v114, v103
	global_store_dword v[46:47], v42, off offset:64
	global_store_dword v[48:49], v43, off offset:64
	v_lshl_add_u64 v[42:43], v[0:1], 2, v[82:83]
	v_add_u32_e32 v0, v114, v104
	v_lshl_add_u64 v[50:51], v[0:1], 2, v[82:83]
	v_or_b32_e32 v0, v114, v105
	global_store_dword v[42:43], v44, off offset:64
	global_store_dword v[50:51], v45, off offset:64
	global_store_dword v[46:47], v38, off offset:128
	global_store_dword v[48:49], v39, off offset:128
	global_store_dword v[42:43], v40, off offset:128
	global_store_dword v[50:51], v41, off offset:128
	global_store_dword v[46:47], v34, off offset:192
	global_store_dword v[48:49], v35, off offset:192
	global_store_dword v[42:43], v36, off offset:192
	global_store_dword v[50:51], v37, off offset:192
	v_lshl_add_u64 v[34:35], v[0:1], 2, v[82:83]
	v_or_b32_e32 v0, v114, v106
	global_store_dword v[34:35], v30, off
	v_lshl_add_u64 v[34:35], v[0:1], 2, v[82:83]
	v_or_b32_e32 v0, v114, v107
	global_store_dword v[34:35], v31, off
	v_lshl_add_u64 v[30:31], v[0:1], 2, v[82:83]
	v_or_b32_e32 v0, v114, v108
	global_store_dword v[30:31], v32, off
	v_lshl_add_u64 v[30:31], v[0:1], 2, v[82:83]
	v_add_u32_e32 v0, v114, v105
	global_store_dword v[30:31], v33, off
	v_lshl_add_u64 v[30:31], v[0:1], 2, v[82:83]
	v_add_u32_e32 v0, v114, v106
	v_lshl_add_u64 v[32:33], v[0:1], 2, v[82:83]
	v_add_u32_e32 v0, v114, v107
	global_store_dword v[30:31], v26, off offset:64
	global_store_dword v[32:33], v27, off offset:64
	v_lshl_add_u64 v[26:27], v[0:1], 2, v[82:83]
	v_add_u32_e32 v0, v114, v108
	v_lshl_add_u64 v[34:35], v[0:1], 2, v[82:83]
	v_or_b32_e32 v0, v114, v109
	global_store_dword v[26:27], v28, off offset:64
	global_store_dword v[34:35], v29, off offset:64
	global_store_dword v[30:31], v22, off offset:128
	global_store_dword v[32:33], v23, off offset:128
	global_store_dword v[26:27], v24, off offset:128
	global_store_dword v[34:35], v25, off offset:128
	global_store_dword v[30:31], v18, off offset:192
	global_store_dword v[32:33], v19, off offset:192
	global_store_dword v[26:27], v20, off offset:192
	global_store_dword v[34:35], v21, off offset:192
	v_lshl_add_u64 v[18:19], v[0:1], 2, v[82:83]
	v_or_b32_e32 v0, v114, v110
	global_store_dword v[18:19], v14, off
	v_lshl_add_u64 v[18:19], v[0:1], 2, v[82:83]
	v_or_b32_e32 v0, v114, v111
	global_store_dword v[18:19], v15, off
	v_lshl_add_u64 v[14:15], v[0:1], 2, v[82:83]
	v_or_b32_e32 v0, v114, v112
	global_store_dword v[14:15], v16, off
	v_lshl_add_u64 v[14:15], v[0:1], 2, v[82:83]
	v_add_u32_e32 v0, v114, v109
	global_store_dword v[14:15], v17, off
	v_lshl_add_u64 v[14:15], v[0:1], 2, v[82:83]
	v_add_u32_e32 v0, v114, v110
	v_lshl_add_u64 v[16:17], v[0:1], 2, v[82:83]
	v_add_u32_e32 v0, v114, v111
	global_store_dword v[14:15], v10, off offset:64
	global_store_dword v[16:17], v11, off offset:64
	v_lshl_add_u64 v[10:11], v[0:1], 2, v[82:83]
	v_add_u32_e32 v0, v114, v112
	v_lshl_add_u64 v[18:19], v[0:1], 2, v[82:83]
	s_mov_b32 s0, 64
	s_mov_b64 s[8:9], 0
	s_and_b64 vcc, exec, s[6:7]
	global_store_dword v[10:11], v12, off offset:64
	global_store_dword v[18:19], v13, off offset:64
	global_store_dword v[14:15], v6, off offset:128
	global_store_dword v[16:17], v7, off offset:128
	global_store_dword v[10:11], v8, off offset:128
	global_store_dword v[18:19], v9, off offset:128
	global_store_dword v[14:15], v2, off offset:192
	global_store_dword v[16:17], v3, off offset:192
	global_store_dword v[10:11], v4, off offset:192
	global_store_dword v[18:19], v5, off offset:192
	s_cbranch_vccz .LBB0_622
	s_movk_i32 s4, 0x2a0
	s_movk_i32 s0, 0x4c0
	s_movk_i32 s1, 0x90
	s_waitcnt lgkmcnt(0)
	s_barrier
	s_add_i32 s4, s44, s4
	s_cmp_ge_i32 s4, s0
	s_cbranch_scc0 .LBB0_627
	s_branch .LBB0_727

.LBB0_629:
	s_cmpk_gt_i32 s4, 0x1ff
	s_cbranch_scc0 .LBB0_648
	s_cmpk_gt_u32 s4, 0x3ff
	s_cbranch_scc0 .LBB0_649
	v_readlane_b32 s8, v254, 49
	v_readlane_b32 s9, v254, 50
	s_mov_b64 s[6:7], 0
	s_and_b64 vcc, exec, s[8:9]
	s_mov_b64 s[8:9], 0
	s_cbranch_vccz .LBB0_650
	v_mov_b32_e32 v2, s64
	v_mov_b32_e32 v3, s65
	v_mov_b32_e32 v4, s64
	v_readfirstlane_b32 s8, v2
	v_readfirstlane_b32 s9, v3
	v_mov_b32_e32 v5, s65
	v_mov_b32_e32 v2, s8
	v_mov_b32_e32 v3, s9
	global_load_dwordx2 v[2:3], v[2:3], off offset:248
	s_waitcnt vmcnt(0) lgkmcnt(0)
	v_mov_b32_e32 v0, s64
	v_readfirstlane_b32 s8, v4
	v_readfirstlane_b32 s9, v5
	v_mov_b32_e32 v6, s65
	v_mov_b32_e32 v4, s8
	v_mov_b32_e32 v5, s9
	global_load_dwordx2 v[4:5], v[4:5], off offset:248
	s_waitcnt vmcnt(0) lgkmcnt(0)
	s_add_i32 s15, s4, 0xfffffc00
	v_readfirstlane_b32 s8, v0
	v_readfirstlane_b32 s9, v6
	s_lshr_b32 s18, s15, 1
	v_mov_b32_e32 v6, s8
	v_mov_b32_e32 v7, s9
	global_load_dwordx2 v[6:7], v[6:7], off offset:248
	s_bfe_u32 s26, s15, 0x20001
	s_lshr_b32 s27, s15, 6
	s_cmp_lt_u32 s15, 64
	v_mov_b32_e32 v56, v247
	s_cselect_b64 s[40:41], -1, 0
	s_cmp_gt_u32 s15, 63
	v_readfirstlane_b32 s28, v2
	v_readfirstlane_b32 s29, v3
	v_readfirstlane_b32 s12, v4
	v_readfirstlane_b32 s13, v5
	s_mov_b64 s[24:25], -1
	s_waitcnt vmcnt(0) lgkmcnt(0)
	v_mov_b32_e32 v0, v7
	s_nop 0
	v_readfirstlane_b32 s8, v6
	v_readfirstlane_b32 s9, v0
	s_cbranch_scc0 .LBB0_638
	s_lshl_b32 s30, s26, 6
	s_cmp_lg_u32 s27, 1
	s_cbranch_scc0 .LBB0_635
	s_lshl_b32 s14, s18, 5
	s_and_b32 s23, s14, 64
	s_add_i32 s22, s30, 0x380
	s_or_b32 s14, s23, 0x480
	s_or_b32 s23, s23, 0x180
	s_mov_b64 s[24:25], 0

.LBB0_640:
	s_lshl_b32 s18, s15, 5
	s_and_b32 s18, s18, 0x700
	s_lshl_b32 s15, s15, 7
	s_bfe_u32 s25, s5, 0x30008
	s_and_b32 s15, s15, 0x80
	s_or_b32 s42, s18, 0x4000
	s_lshl_b32 s24, s25, 9
	s_or_b32 s18, s42, s15
	v_ashrrev_i32_e32 v0, 2, v56
	v_and_b32_e32 v2, -16, v0
	s_add_u32 s30, s28, 0x9f00000
	v_ashrrev_i32_e32 v12, 3, v56
	v_ashrrev_i32_e32 v3, 31, v2
	s_addc_u32 s31, s29, 0
	v_lshlrev_b32_e32 v13, 3, v56
	v_add_u32_e32 v14, s23, v12
	v_mov_b64_e32 v[10:11], s[12:13]
	s_mov_b32 s44, 0x9000
	v_lshl_add_u64 v[2:3], v[2:3], 0, s[18:19]
	v_mov_b64_e32 v[4:5], s[30:31]
	v_and_b32_e32 v57, 56, v13
	v_mad_i64_i32 v[10:11], s[30:31], v14, s44, v[10:11]
	s_lshl_b32 s18, s42, 1
	v_add_u32_e32 v0, s42, v12
	s_mov_b32 s15, s19
	v_lshlrev_b32_e32 v8, 1, v57
	v_mov_b32_e32 v9, v1
	v_lshl_add_u64 v[10:11], v[10:11], 0, s[18:19]
	v_mad_i64_i32 v[6:7], s[30:31], v0, s2, v[4:5]
	s_lshl_b64 s[14:15], s[14:15], 1
	v_lshl_add_u64 v[10:11], v[10:11], 0, v[8:9]
	s_mov_b32 s18, 0x17700000
	v_lshl_add_u64 v[6:7], v[6:7], 0, s[14:15]
	v_add_co_u32_e32 v10, vcc, s18, v10
	v_lshl_add_u64 v[6:7], v[6:7], 0, v[8:9]
	s_nop 0
	v_addc_co_u32_e32 v11, vcc, 0, v11, vcc
	global_load_dwordx4 v[24:27], v[10:11], off
	global_load_dwordx4 v[20:23], v[6:7], off
	v_and_b32_e32 v6, 15, v56
	v_or_b32_e32 v2, v2, v6
	v_lshrrev_b32_e32 v0, 1, v56
	v_mad_i64_i32 v[4:5], s[30:31], v2, s2, v[4:5]
	s_mov_b32 s23, s19
	v_and_b32_e32 v0, 24, v0
	v_lshl_add_u64 v[4:5], s[22:23], 1, v[4:5]
	v_lshlrev_b32_e32 v0, 1, v0
	v_lshl_add_u64 v[4:5], v[4:5], 0, v[0:1]
	global_load_dwordx4 v[28:31], v[4:5], off
	global_load_dwordx4 v[32:35], v[4:5], off offset:64
	v_cmp_lt_i32_e32 vcc, v222, v220
	v_lshlrev_b32_e32 v4, 4, v56
	s_movk_i32 s22, 0x90
	v_cndmask_b32_e32 v7, v219, v222, vcc
	v_cmp_lt_i32_e32 vcc, v221, v220
	v_lshlrev_b32_e32 v5, 1, v56
	v_mul_lo_u32 v15, v12, s22
	v_cndmask_b32_e32 v9, v219, v221, vcc
	v_lshlrev_b32_e32 v58, 2, v7
	v_lshlrev_b32_e32 v59, 2, v9
	v_mul_u32_u24_e32 v60, 0x90, v6
	v_and_b32_e32 v9, 0x70, v4
	v_mad_i64_i32 v[6:7], s[22:23], v14, s44, 0
	v_and_b32_e32 v10, 32, v13
	v_and_b32_e32 v11, 16, v4
	v_and_b32_e32 v13, 4, v5
	v_or3_b32 v6, v6, s24, v9
	v_mad_i64_i32 v[4:5], s[22:23], v12, s2, 0
	v_or3_b32 v61, v10, v11, v13
	v_mov_b32_e32 v10, 0x300000
	v_lshl_add_u64 v[6:7], s[12:13], 0, v[6:7]
	s_mov_b64 s[12:13], 0x17708080
	v_add_u32_e32 v62, 16, v15
	v_mad_u64_u32 v[4:5], s[22:23], s25, v10, v[4:5]
	v_lshl_add_u64 v[52:53], v[6:7], 0, s[12:13]
	s_add_u32 s12, s28, s14
	v_lshl_add_u32 v10, v61, 1, v62
	v_or_b32_e32 v4, v4, v9
	s_addc_u32 s13, s29, s15
	v_add_u32_e32 v8, v62, v8
	v_add_u32_e32 v9, 0x2000, v10
	v_lshl_add_u64 v[4:5], s[12:13], 0, v[4:5]
	s_mov_b64 s[12:13], 0x15fc0000
	v_mov_b32_e32 v16, v1
	v_mov_b32_e32 v17, v1
	v_lshl_add_u64 v[54:55], v[4:5], 0, s[12:13]
	s_waitcnt vmcnt(0) lgkmcnt(0)
	ds_write2_b64 v9, v[24:25], v[26:27] offset0:128 offset1:130
	ds_write_b128 v8, v[20:23]
	v_mov_b32_e32 v18, v1
	v_mov_b32_e32 v19, v1
	v_mov_b64_e32 v[4:5], v[16:17]
	v_mov_b64_e32 v[8:9], v[16:17]
	v_mov_b64_e32 v[12:13], v[16:17]
	s_mov_b32 s18, 0
	v_mov_b32_e32 v64, 0xf149f2ca
	v_mov_b32_e32 v63, 0
	v_mov_b64_e32 v[6:7], v[18:19]
	v_mov_b64_e32 v[10:11], v[18:19]
	v_mov_b64_e32 v[14:15], v[18:19]
	s_movk_i32 s42, 0x23ff
	s_waitcnt lgkmcnt(0)
	s_barrier
	s_branch .LBB0_642

.LBB0_642:
	s_cmp_lg_u32 s18, 3
	s_cselect_b64 s[12:13], -1, 0
	s_cmp_eq_u32 s18, 3
	s_cbranch_scc1 .LBB0_644
	s_waitcnt vmcnt(0)
	global_load_dwordx4 v[20:23], v[54:55], off
	global_load_dwordx4 v[24:27], v[52:53], off

.LBB0_651:
	v_mov_b32_e32 v2, s64
	v_mov_b32_e32 v3, s65
	v_mov_b32_e32 v4, s64
	v_readfirstlane_b32 s6, v2
	v_readfirstlane_b32 s7, v3
	v_mov_b32_e32 v5, s65
	v_mov_b32_e32 v2, s6
	v_mov_b32_e32 v3, s7
	global_load_dwordx2 v[2:3], v[2:3], off offset:248
	s_waitcnt vmcnt(0) lgkmcnt(0)
	v_mov_b32_e32 v71, v1
	v_readfirstlane_b32 s6, v4
	v_readfirstlane_b32 s7, v5
	v_readfirstlane_b32 s8, v2
	v_mov_b32_e32 v4, s6
	v_mov_b32_e32 v5, s7
	global_load_dwordx2 v[10:11], v[4:5], off offset:248
	v_mov_b32_e32 v4, s64
	v_mov_b32_e32 v5, s65
	s_waitcnt vmcnt(0) lgkmcnt(0)
	v_readfirstlane_b32 s9, v3
	v_readfirstlane_b32 s6, v4
	v_readfirstlane_b32 s7, v5
	v_mov_b32_e32 v0, s64
	v_mov_b32_e32 v4, s6
	s_add_i32 s6, s4, 0xfffffe00
	v_mov_b32_e32 v5, s7
	s_add_u32 s14, s8, 0x9f00000
	global_load_dwordx2 v[12:13], v[4:5], off offset:248
	v_mov_b32_e32 v4, v247
	s_addc_u32 s15, s9, 0
	s_lshr_b32 s12, s6, 6
	s_lshl_b32 s6, s6, 1
	s_and_b32 s23, s6, 30
	s_waitcnt vmcnt(0) lgkmcnt(0)
	s_mov_b32 s7, s19
	v_ashrrev_i32_e32 v5, 8, v4
	v_lshrrev_b32_e32 v14, 1, v4
	v_add_u32_e32 v8, s23, v5
	v_and_b32_e32 v15, 24, v14
	v_lshlrev_b32_e32 v14, 6, v8
	s_lshl_b32 s6, s12, 11
	v_lshrrev_b32_e32 v9, 2, v4
	v_lshlrev_b32_e32 v70, 1, v15
	v_ashrrev_i32_e32 v15, 31, v14
	v_and_b32_e32 v6, 15, v4
	v_and_b32_e32 v7, 48, v9
	v_lshl_add_u64 v[68:69], v[14:15], 0, s[6:7]
	v_mov_b64_e32 v[2:3], s[14:15]
	v_or3_b32 v68, v68, v7, v6
	s_bfe_u32 s22, s4, 0x20004
	v_mad_u64_u32 v[14:15], s[8:9], v68, s2, v[2:3]
	s_lshl_b32 s18, s22, 7
	v_mad_i32_i24 v15, v69, s2, v15
	v_lshl_add_u64 v[14:15], v[14:15], 0, s[18:19]
	v_mov_b32_e32 v16, s65
	v_lshl_add_u64 v[14:15], v[14:15], 0, v[70:71]
	global_load_dwordx4 v[20:23], v[14:15], off offset:768
	global_load_dwordx4 v[24:27], v[14:15], off offset:832
	v_ashrrev_i32_e32 v72, 3, v4
	v_readfirstlane_b32 s7, v0
	v_readfirstlane_b32 s8, v16
	s_mov_b32 s9, s19
	v_mov_b32_e32 v14, s7
	v_mov_b32_e32 v15, s8
	s_lshl_b32 s7, s22, 6
	s_lshl_b32 s8, s12, 8
	s_add_i32 s12, s7, 0x80
	s_addk_i32 s8, 0x4000
	v_readfirstlane_b32 s13, v10
	v_readfirstlane_b32 s24, v11
	v_ashrrev_i32_e32 v73, 31, v72
	v_mov_b32_e32 v10, s13
	v_mov_b32_e32 v11, s24
	v_add_u32_e32 v18, s12, v72
	v_lshl_add_u64 v[16:17], v[72:73], 0, s[8:9]
	s_mov_b32 s9, 0x9000
	v_lshlrev_b32_e32 v36, 3, v4
	v_mad_i64_i32 v[10:11], s[12:13], v18, s9, v[10:11]
	v_mad_u64_u32 v[18:19], s[12:13], v16, s2, v[2:3]
	v_and_b32_e32 v71, 56, v36
	s_mov_b64 s[12:13], 0x17700000
	v_mad_i32_i24 v19, v17, s2, v19
	v_lshlrev_b32_e32 v0, 1, v71
	v_lshl_add_u64 v[2:3], v[10:11], 0, s[12:13]
	v_lshl_add_u64 v[10:11], v[18:19], 0, s[18:19]
	s_lshl_b32 s18, s8, 1
	global_load_dwordx2 v[14:15], v[14:15], off offset:112
	v_lshl_add_u64 v[10:11], v[10:11], 0, v[0:1]
	v_lshl_add_u64 v[16:17], v[2:3], 0, s[18:19]
	v_lshl_add_u64 v[16:17], v[16:17], 0, v[0:1]
	s_waitcnt vmcnt(0) lgkmcnt(0)
	global_load_dwordx4 v[28:31], v[10:11], off offset:1280
	global_load_dwordx4 v[32:35], v[16:17], off
	v_sub_u32_e64 v10, s23, 4 clamp
	v_sub_u32_e64 v11, s23, 3 clamp
	v_readfirstlane_b32 s8, v10
	v_readfirstlane_b32 s9, v11
	s_min_u32 s8, s8, 24
	s_min_u32 s9, s9, 24
	v_lshlrev_b32_e32 v10, 4, v4
	v_lshlrev_b32_e32 v11, 1, v4
	s_movk_i32 s18, 0x90
	s_sub_i32 s51, s9, s8
	v_readfirstlane_b32 s8, v12
	v_readfirstlane_b32 s9, v13
	v_and_b32_e32 v12, 32, v36
	v_and_b32_e32 v10, 16, v10
	v_and_b32_e32 v11, 4, v11
	v_mul_lo_u32 v13, v72, s18
	s_add_i32 s51, s51, 8
	v_or3_b32 v96, v12, v10, v11
	v_add_u32_e32 v97, 16, v13
	s_mov_b64 s[12:13], -1
	v_add_u32_e32 v10, v97, v0
	v_lshl_add_u32 v11, v96, 1, v97
	s_cmp_gt_i32 s51, -4
	v_readfirstlane_b32 s18, v14
	v_readfirstlane_b32 s23, v15
	v_and_b32_e32 v98, 12, v9
	v_add_u32_e32 v11, 0x2000, v11
	s_waitcnt vmcnt(0) lgkmcnt(0)
	ds_write_b128 v10, v[28:31]
	ds_write2_b64 v11, v[32:33], v[34:35] offset0:128 offset1:130
	s_waitcnt lgkmcnt(0)
	s_barrier
	s_cbranch_scc1 .LBB0_653
	v_and_b32_e32 v36, 12, v9
	s_mov_b64 s[12:13], 0

.LBB0_658:
	v_lshl_add_u64 v[2:3], s[40:41], 0, v[72:73]
	v_mad_u64_u32 v[4:5], s[56:57], v2, s2, v[92:93]
	v_mad_i32_i24 v5, v3, s2, v5
	v_lshl_add_u64 v[2:3], s[40:41], 1, v[74:75]
	s_waitcnt vmcnt(0)
	global_load_dwordx4 v[28:31], v[4:5], off
	global_load_dwordx4 v[32:35], v[2:3], off
.LBB0_659:
	s_bitcmp1_b32 s48, 0
	s_cselect_b32 s40, 0x4800, 0
	s_add_i32 s56, s40, 16
	s_cmp_gt_u32 s48, 3
	s_mov_b64 s[40:41], -1
	s_cbranch_scc0 .LBB0_685
	s_add_i32 s40, s52, s48
	v_cmp_ge_i32_e32 vcc, s40, v99
	v_cmp_lt_i32_e64 s[40:41], s40, v100
	v_mov_b64_e32 v[16:17], v[36:37]
	v_mov_b64_e32 v[4:5], v[40:41]
	v_mov_b64_e32 v[8:9], v[44:45]
	v_mov_b64_e32 v[12:13], v[48:49]
	s_and_b64 s[48:49], vcc, s[40:41]
	v_mov_b32_e32 v56, v109
	v_mov_b32_e32 v95, v110
	v_mov_b64_e32 v[18:19], v[38:39]
	v_mov_b64_e32 v[6:7], v[42:43]
	v_mov_b64_e32 v[10:11], v[46:47]
	v_mov_b64_e32 v[14:15], v[50:51]
	s_and_saveexec_b64 s[40:41], s[48:49]
	s_cbranch_execz .LBB0_680
	v_mov_b32_e32 v14, 0xff800000
	v_ashrrev_i32_e32 v95, 31, v94
	v_mov_b32_e32 v0, 0xff800000
	s_and_saveexec_b64 s[48:49], s[14:15]
	s_cbranch_execz .LBB0_663
	v_lshl_add_u64 v[2:3], v[94:95], 0, v[78:79]
	v_lshl_add_u64 v[2:3], v[2:3], 2, s[12:13]
	global_load_dword v0, v[2:3], off offset:868
	s_waitcnt vmcnt(0) lgkmcnt(0)
	v_mul_f32_e32 v0, 0x3fb8aa3b, v0
.LBB0_663:
	s_or_b64 exec, exec, s[48:49]
	s_and_saveexec_b64 s[48:49], s[22:23]
	s_cbranch_execz .LBB0_665
	v_lshl_add_u64 v[2:3], v[94:95], 0, v[76:77]
	v_lshl_add_u64 v[2:3], v[2:3], 2, s[12:13]
	global_load_dword v2, v[2:3], off offset:868
	s_waitcnt vmcnt(0) lgkmcnt(0)
	v_mul_f32_e32 v14, 0x3fb8aa3b, v2
.LBB0_665:
	s_or_b64 exec, exec, s[48:49]
	v_mov_b32_e32 v15, 0xff800000
	v_mov_b32_e32 v112, 0xff800000
	s_and_saveexec_b64 s[48:49], s[24:25]
	s_cbranch_execz .LBB0_667
	v_lshl_add_u64 v[2:3], v[94:95], 0, v[82:83]
	v_lshl_add_u64 v[2:3], v[2:3], 2, s[12:13]
	global_load_dword v2, v[2:3], off offset:868
	s_waitcnt vmcnt(0) lgkmcnt(0)
	v_mul_f32_e32 v112, 0x3fb8aa3b, v2
.LBB0_667:
	s_or_b64 exec, exec, s[48:49]
	s_and_saveexec_b64 s[48:49], s[26:27]
	s_cbranch_execz .LBB0_669
	v_lshl_add_u64 v[2:3], v[94:95], 0, v[80:81]
	v_lshl_add_u64 v[2:3], v[2:3], 2, s[12:13]
	global_load_dword v2, v[2:3], off offset:868
	s_waitcnt vmcnt(0) lgkmcnt(0)
	v_mul_f32_e32 v15, 0x3fb8aa3b, v2
.LBB0_669:
	s_or_b64 exec, exec, s[48:49]
	v_mov_b32_e32 v111, 0xff800000
	v_mov_b32_e32 v113, 0xff800000
	s_and_saveexec_b64 s[48:49], s[28:29]
	s_cbranch_execz .LBB0_671
	v_lshl_add_u64 v[2:3], v[94:95], 0, v[86:87]
	v_lshl_add_u64 v[2:3], v[2:3], 2, s[12:13]
	global_load_dword v2, v[2:3], off offset:868
	s_waitcnt vmcnt(0) lgkmcnt(0)
	v_mul_f32_e32 v113, 0x3fb8aa3b, v2
.LBB0_671:
	s_or_b64 exec, exec, s[48:49]
	s_and_saveexec_b64 s[48:49], s[30:31]
	s_cbranch_execz .LBB0_673
	v_lshl_add_u64 v[2:3], v[94:95], 0, v[84:85]
	v_lshl_add_u64 v[2:3], v[2:3], 2, s[12:13]
	global_load_dword v2, v[2:3], off offset:868
	s_waitcnt vmcnt(0) lgkmcnt(0)
	v_mul_f32_e32 v111, 0x3fb8aa3b, v2
.LBB0_673:
	s_or_b64 exec, exec, s[48:49]
	v_mov_b32_e32 v114, 0xff800000
	v_mov_b32_e32 v115, 0xff800000
	s_and_saveexec_b64 s[48:49], s[42:43]
	s_cbranch_execz .LBB0_675
	v_lshl_add_u64 v[2:3], v[94:95], 0, v[90:91]
	v_lshl_add_u64 v[2:3], v[2:3], 2, s[12:13]
	global_load_dword v2, v[2:3], off offset:868
	s_waitcnt vmcnt(0) lgkmcnt(0)
	v_mul_f32_e32 v115, 0x3fb8aa3b, v2
.LBB0_675:
	s_or_b64 exec, exec, s[48:49]
	s_and_saveexec_b64 s[48:49], s[44:45]
	s_cbranch_execz .LBB0_677
	v_lshl_add_u64 v[2:3], v[94:95], 0, v[88:89]
	v_lshl_add_u64 v[2:3], v[2:3], 2, s[12:13]
	global_load_dword v2, v[2:3], off offset:868
	s_waitcnt vmcnt(0) lgkmcnt(0)
	v_mul_f32_e32 v114, 0x3fb8aa3b, v2

.LBB0_689:
	v_mov_b32_e32 v0, s64
	s_waitcnt vmcnt(0)
	v_mov_b32_e32 v20, s65
	v_lshlrev_b64 v[2:3], 11, v[2:3]
	v_readfirstlane_b32 s12, v0
	v_readfirstlane_b32 s13, v20
	v_lshl_add_u64 v[2:3], s[8:9], 0, v[2:3]
	v_mov_b32_e32 v20, s12
	v_mov_b32_e32 v21, s13
	global_load_dwordx2 v[20:21], v[20:21], off offset:104
	v_readlane_b32 s12, v254, 51
	s_or_b32 s12, s26, s12
	s_ashr_i32 s13, s12, 31
	s_lshl_b64 s[12:13], s[12:13], 2
	s_mov_b32 s8, 0x3fb8aa3b
	v_lshrrev_b32_e32 v22, 2, v56
	v_and_b32_e32 v36, 12, v22
	s_waitcnt vmcnt(0) lgkmcnt(0)
	v_mov_b32_e32 v0, v21
	s_nop 0
	v_readfirstlane_b32 s14, v20
	v_readfirstlane_b32 s15, v0
	s_add_u32 s12, s14, s12
	s_addc_u32 s13, s15, s13
	v_mov_b64_e32 v[20:21], s[12:13]
	global_load_dword v0, v[20:21], off
	ds_bpermute_b32 v20, v58, v63
	s_lshl_b32 s18, s27, 9
	v_lshl_add_u64 v[2:3], v[2:3], 0, s[18:19]
	s_lshl_b32 s18, s26, 7
	v_lshl_add_u64 v[2:3], v[2:3], 0, s[18:19]
	s_waitcnt lgkmcnt(0)
	v_add_f32_e32 v20, v63, v20
	ds_bpermute_b32 v21, v59, v20
	s_waitcnt lgkmcnt(0)
	v_add_f32_e32 v20, v20, v21
	s_waitcnt vmcnt(0)
	v_fma_f32 v0, v0, s8, -v64
	v_exp_f32_e32 v0, v0
	s_mov_b64 s[8:9], 0x1e300000
	v_lshl_add_u64 v[2:3], v[2:3], 0, s[8:9]
	s_mov_b64 s[8:9], -1
	v_add_f32_e32 v0, v0, v20
	v_cndmask_b32_e64 v0, v20, v0, s[40:41]
	s_and_b64 vcc, exec, s[6:7]
	s_cbranch_vccnz .LBB0_651
	s_branch .LBB0_693

.LBB0_694:
	v_mov_b32_e32 v2, s64
	v_mov_b32_e32 v3, s65
	v_mov_b32_e32 v4, s64
	v_readfirstlane_b32 s6, v2
	v_readfirstlane_b32 s7, v3
	v_mov_b32_e32 v5, s65
	v_mov_b32_e32 v2, s6
	v_mov_b32_e32 v3, s7
	global_load_dwordx2 v[2:3], v[2:3], off offset:248
	s_waitcnt vmcnt(0) lgkmcnt(0)
	v_mov_b32_e32 v0, s64
	v_readfirstlane_b32 s6, v4
	v_readfirstlane_b32 s7, v5
	v_mov_b32_e32 v6, s65
	v_mov_b32_e32 v4, s6
	v_mov_b32_e32 v5, s7
	global_load_dwordx2 v[4:5], v[4:5], off offset:248
	s_waitcnt vmcnt(0) lgkmcnt(0)
	v_mov_b32_e32 v71, v1
	v_readfirstlane_b32 s6, v0
	v_readfirstlane_b32 s7, v6
	v_readfirstlane_b32 s15, v4
	v_mov_b32_e32 v6, s6
	v_readfirstlane_b32 s6, v2
	v_mov_b32_e32 v7, s7
	v_readfirstlane_b32 s7, v3
	s_add_u32 s8, s6, 0x9f00000
	s_addc_u32 s9, s7, 0
	s_ashr_i32 s6, s4, 6
	s_lshl_b32 s7, s4, 7
	s_lshl_b32 s12, s4, 1
	s_and_b32 s14, s7, 0x780
	s_ashr_i32 s7, s6, 31
	s_and_b32 s26, s12, 64
	s_lshl_b32 s23, s6, 8
	s_lshl_b64 s[12:13], s[6:7], 11
	s_max_u32 s27, s14, 0x80
	s_min_u32 s6, s14, 0x700
	s_bfe_u32 s22, s4, 0x20004
	s_sub_i32 s25, s6, s27
	global_load_dwordx2 v[8:9], v[6:7], off offset:248
	v_mov_b32_e32 v7, v247
	s_lshl_b32 s18, s22, 7
	s_ashr_i32 s24, s23, 31
	s_addk_i32 s25, 0x180
	s_add_u32 s6, s23, 0x4000
	s_waitcnt vmcnt(0) lgkmcnt(0)
	s_addc_u32 s7, s24, 0
	v_ashrrev_i32_e32 v0, 2, v7
	v_ashrrev_i32_e32 v72, 3, v7
	v_readfirstlane_b32 s28, v5
	v_and_b32_e32 v5, -16, v0
	v_ashrrev_i32_e32 v73, 31, v72
	v_mov_b64_e32 v[10:11], s[8:9]
	v_mov_b32_e32 v2, s15
	v_mov_b32_e32 v3, s28
	v_and_b32_e32 v4, 15, v7
	v_add_u32_e32 v14, s26, v72
	v_add_u32_e32 v6, s14, v5
	v_lshl_add_u64 v[12:13], s[6:7], 0, v[72:73]
	s_mov_b32 s14, 0x9000
	v_mad_i64_i32 v[2:3], s[14:15], v14, s14, v[2:3]
	v_or_b32_e32 v14, v6, v4
	v_mad_u64_u32 v[16:17], s[14:15], v12, s2, v[10:11]
	s_mov_b64 s[14:15], 0x17700000
	v_ashrrev_i32_e32 v15, 31, v14
	v_lshlrev_b32_e32 v19, 3, v7
	v_lshl_add_u64 v[2:3], v[2:3], 0, s[14:15]
	v_lshl_add_u64 v[68:69], s[12:13], 0, v[14:15]
	v_and_b32_e32 v78, 56, v19
	v_mad_i32_i24 v17, v13, s2, v17
	v_lshl_add_u64 v[12:13], s[6:7], 1, v[2:3]
	v_mad_u64_u32 v[10:11], s[6:7], v68, s2, v[10:11]
	v_lshlrev_b32_e32 v0, 1, v78
	v_mad_i32_i24 v11, v69, s2, v11
	v_lshl_add_u64 v[12:13], v[12:13], 0, v[0:1]
	v_lshl_add_u64 v[10:11], v[10:11], 0, s[18:19]
	s_lshl_b32 s18, s26, 1
	global_load_dwordx4 v[28:31], v[12:13], off
	v_lshl_add_u64 v[12:13], v[16:17], 0, s[18:19]
	v_lshrrev_b32_e32 v18, 1, v7
	v_lshl_add_u64 v[12:13], v[12:13], 0, v[0:1]
	global_load_dwordx4 v[32:35], v[12:13], off offset:512
	v_and_b32_e32 v12, 24, v18
	v_lshlrev_b32_e32 v70, 1, v12
	v_lshl_add_u64 v[10:11], v[10:11], 0, v[70:71]
	global_load_dwordx4 v[20:23], v[10:11], off
	global_load_dwordx4 v[24:27], v[10:11], off offset:64
	v_readfirstlane_b32 s6, v8
	v_readfirstlane_b32 s7, v9
	v_lshlrev_b32_e32 v8, 4, v7
	v_lshlrev_b32_e32 v9, 1, v7
	s_movk_i32 s28, 0x90
	v_and_b32_e32 v10, 32, v19
	v_and_b32_e32 v8, 16, v8
	v_and_b32_e32 v9, 4, v9
	v_mul_lo_u32 v11, v72, s28
	v_or3_b32 v71, v10, v8, v9
	v_add_u32_e32 v79, 16, v11
	s_ashr_i32 s26, s25, 6
	v_lshrrev_b32_e32 v7, 2, v7
	v_lshl_add_u32 v9, v71, 1, v79
	s_mov_b64 s[14:15], -1
	v_add_u32_e32 v9, 0x2000, v9
	s_cmp_gt_i32 s26, -4
	v_and_b32_e32 v80, 12, v7
	v_add_u32_e32 v8, v79, v0
	s_waitcnt vmcnt(0) lgkmcnt(0)
	ds_write2_b64 v9, v[28:29], v[30:31] offset0:128 offset1:130
	ds_write_b128 v8, v[32:35]
	s_waitcnt lgkmcnt(0)
	s_barrier
	s_cbranch_scc1 .LBB0_696
	v_and_b32_e32 v36, 12, v7
	s_mov_b64 s[14:15], 0

.LBB0_703:
	v_lshl_add_u64 v[2:3], s[12:13], 0, v[72:73]
	v_mad_u64_u32 v[4:5], s[14:15], v2, s2, v[76:77]
	v_mov_b32_e32 v0, v5
	v_mad_u64_u32 v[2:3], s[14:15], v3, s2, v[0:1]
	v_mov_b32_e32 v5, v2
	v_lshl_add_u64 v[2:3], s[12:13], 1, v[74:75]
	s_waitcnt vmcnt(0)
	global_load_dwordx4 v[32:35], v[4:5], off
	global_load_dwordx4 v[28:31], v[2:3], off

.LBB0_724:
	v_mov_b32_e32 v0, s64
	v_mov_b32_e32 v2, s65
	s_lshl_b32 s8, s22, 6
	v_readfirstlane_b32 s9, v0
	v_readfirstlane_b32 s12, v2
	v_cmp_lt_i32_e32 vcc, v222, v220
	v_mov_b32_e32 v2, s9
	v_mov_b32_e32 v3, s12
	global_load_dwordx2 v[2:3], v[2:3], off offset:104
	v_readlane_b32 s9, v254, 51
	s_or_b32 s12, s22, s9
	s_ashr_i32 s13, s12, 31
	s_lshl_b64 s[12:13], s[12:13], 2
	s_waitcnt vmcnt(0) lgkmcnt(0)
	v_mov_b32_e32 v0, v2
	s_nop 0
	v_readfirstlane_b32 s9, v0
	v_readfirstlane_b32 s14, v3
	s_add_u32 s12, s9, s12
	s_addc_u32 s13, s14, s13
	v_mov_b64_e32 v[2:3], s[12:13]
	global_load_dword v0, v[2:3], off
	v_cndmask_b32_e32 v2, v219, v222, vcc
	v_lshlrev_b32_e32 v2, 2, v2
	ds_bpermute_b32 v2, v2, v88
	v_cmp_lt_i32_e32 vcc, v221, v220
	s_lshl_b32 s18, s8, 1
	s_mov_b64 s[8:9], -1
	v_cndmask_b32_e32 v3, v219, v221, vcc
	v_lshlrev_b32_e32 v3, 2, v3
	s_waitcnt lgkmcnt(0)
	v_add_f32_e32 v20, v88, v2
	ds_bpermute_b32 v21, v3, v20
	v_lshlrev_b64 v[2:3], 11, v[68:69]
	v_lshl_add_u64 v[2:3], s[6:7], 0, v[2:3]
	s_mov_b32 s6, 0x3fb8aa3b
	v_lshl_add_u64 v[2:3], v[2:3], 0, s[18:19]
	s_waitcnt lgkmcnt(0)
	v_add_f32_e32 v20, v20, v21
	s_waitcnt vmcnt(0)
	v_fma_f32 v0, v0, s6, -v87
	v_exp_f32_e32 v0, v0
	s_mov_b64 s[6:7], 0x1e300000
	v_lshl_add_u64 v[2:3], v[2:3], 0, s[6:7]
	v_add_f32_e32 v0, v0, v20
.LBB0_725:
	s_and_b64 vcc, exec, s[8:9]
	s_cbranch_vccz .LBB0_628
	v_div_scale_f32 v20, s[6:7], v0, v0, 1.0
	v_rcp_f32_e32 v21, v20
	v_div_scale_f32 v22, vcc, 1.0, v0, 1.0
	v_mov_b32_e32 v37, v1
	v_fma_f32 v23, -v20, v21, 1.0
	v_fmac_f32_e32 v21, v23, v21
	v_mul_f32_e32 v23, v22, v21
	v_fma_f32 v24, -v20, v23, v22
	v_fmac_f32_e32 v23, v24, v21
	v_fma_f32 v20, -v20, v23, v22
	v_div_fmas_f32 v20, v20, v21, v23
	v_div_fixup_f32 v0, v20, v0, 1.0
	v_pk_mul_f32 v[4:5], v[4:5], v[0:1] op_sel_hi:[1,0]
	v_pk_mul_f32 v[6:7], v[6:7], v[0:1] op_sel_hi:[1,0]
	v_lshl_add_u64 v[2:3], v[36:37], 1, v[2:3]
	v_cvt_pk_bf16_f32 v4, v4, v5
	v_cvt_pk_bf16_f32 v5, v6, v7
	s_waitcnt vmcnt(0)
	v_pk_mul_f32 v[12:13], v[12:13], v[0:1] op_sel_hi:[1,0]
	v_pk_mul_f32 v[14:15], v[14:15], v[0:1] op_sel_hi:[1,0]
	v_pk_mul_f32 v[8:9], v[8:9], v[0:1] op_sel_hi:[1,0]
	v_pk_mul_f32 v[10:11], v[10:11], v[0:1] op_sel_hi:[1,0]
	global_store_dwordx2 v[2:3], v[4:5], off offset:64
	v_pk_mul_f32 v[4:5], v[16:17], v[0:1] op_sel_hi:[1,0]
	v_pk_mul_f32 v[6:7], v[18:19], v[0:1] op_sel_hi:[1,0]
	v_cvt_pk_bf16_f32 v12, v12, v13
	v_cvt_pk_bf16_f32 v13, v14, v15
	v_cvt_pk_bf16_f32 v8, v8, v9
	v_cvt_pk_bf16_f32 v9, v10, v11
	v_cvt_pk_bf16_f32 v4, v4, v5
	v_cvt_pk_bf16_f32 v5, v6, v7
	global_store_dwordx2 v[2:3], v[12:13], off
	global_store_dwordx2 v[2:3], v[8:9], off offset:32
	global_store_dwordx2 v[2:3], v[4:5], off offset:96
	s_branch .LBB0_628

.LBB0_732:
	v_readlane_b32 s4, v253, 9
	v_readlane_b32 s5, v253, 10
	v_readlane_b32 s1, v253, 6
	s_or_b64 s[22:23], s[22:23], exec
	v_mov_b64_e32 v[2:3], s[4:5]
	v_readlane_b32 s4, v253, 11
	v_readlane_b32 s5, v253, 12
	s_waitcnt lgkmcnt(0)
	global_load_dword v0, v[2:3], off sc1
	s_or_b64 s[14:15], s[14:15], exec
	v_mov_b64_e32 v[2:3], s[4:5]
	v_readlane_b32 s4, v253, 13
	v_readlane_b32 s5, v253, 14
	global_load_dword v2, v[2:3], off sc1
	s_nop 0
	v_mov_b64_e32 v[4:5], s[4:5]
	v_readlane_b32 s4, v253, 15
	v_readlane_b32 s5, v253, 16
	global_load_dword v3, v[4:5], off sc1
	s_nop 0
	v_mov_b64_e32 v[4:5], s[4:5]
	v_readlane_b32 s4, v253, 17
	v_readlane_b32 s5, v253, 18
	global_load_dword v4, v[4:5], off sc1
	s_nop 0
	v_mov_b64_e32 v[6:7], s[4:5]
	v_readlane_b32 s4, v253, 19
	v_readlane_b32 s5, v253, 20
	global_load_dword v5, v[6:7], off sc1
	s_nop 0
	v_mov_b64_e32 v[6:7], s[4:5]
	v_readlane_b32 s4, v253, 21
	v_readlane_b32 s5, v253, 22
	global_load_dword v6, v[6:7], off sc1
	s_nop 0
	v_mov_b64_e32 v[8:9], s[4:5]
	v_readlane_b32 s4, v253, 23
	v_readlane_b32 s5, v253, 24
	global_load_dword v7, v[8:9], off sc1
	s_nop 0
	v_mov_b64_e32 v[8:9], s[4:5]
	v_readlane_b32 s4, v253, 25
	v_readlane_b32 s5, v253, 26
	global_load_dword v8, v[8:9], off sc1
	s_nop 0
	v_mov_b64_e32 v[10:11], s[4:5]
	v_readlane_b32 s4, v253, 27
	v_readlane_b32 s5, v253, 28
	global_load_dword v9, v[10:11], off sc1
	s_nop 0
	v_mov_b64_e32 v[10:11], s[4:5]
	v_readlane_b32 s4, v253, 29
	v_readlane_b32 s5, v253, 30
	global_load_dword v10, v[10:11], off sc1
	s_nop 0
	v_mov_b64_e32 v[12:13], s[4:5]
	v_readlane_b32 s4, v253, 31
	v_readlane_b32 s5, v253, 32
	global_load_dword v11, v[12:13], off sc1
	s_nop 0
	v_mov_b64_e32 v[12:13], s[4:5]
	v_readlane_b32 s4, v253, 33
	v_readlane_b32 s5, v253, 34
	global_load_dword v12, v[12:13], off sc1
	s_nop 0
	v_mov_b64_e32 v[14:15], s[4:5]
	v_readlane_b32 s4, v253, 35
	v_readlane_b32 s5, v253, 36
	global_load_dword v13, v[14:15], off sc1
	s_nop 0
	v_mov_b64_e32 v[14:15], s[4:5]
	v_readlane_b32 s4, v253, 37
	v_readlane_b32 s5, v253, 38
	global_load_dword v14, v[14:15], off sc1
	s_nop 0
	v_mov_b64_e32 v[16:17], s[4:5]
	v_readlane_b32 s4, v253, 39
	v_readlane_b32 s5, v253, 40
	global_load_dword v15, v[16:17], off sc1
	s_nop 0
	v_mov_b64_e32 v[16:17], s[4:5]
	global_load_dword v16, v[16:17], off sc1
	s_waitcnt vmcnt(0) lgkmcnt(0)
	v_add_u32_e32 v17, v2, v0
	v_add_u32_e32 v17, v17, v3
	v_add_u32_e32 v17, v17, v4
	v_add_u32_e32 v17, v17, v5
	v_add_u32_e32 v17, v17, v6
	v_add_u32_e32 v17, v17, v7
	v_add_u32_e32 v17, v17, v8
	v_add_u32_e32 v17, v17, v9
	v_add_u32_e32 v17, v17, v10
	v_add_u32_e32 v17, v17, v11
	v_add_u32_e32 v17, v17, v12
	v_add_u32_e32 v17, v17, v13
	v_add_u32_e32 v17, v17, v14
	v_add_u32_e32 v17, v17, v15
	v_add_u32_e32 v17, v17, v16
	v_cmp_ne_u32_e32 vcc, s1, v17
	s_and_saveexec_b64 s[24:25], vcc
	s_cbranch_execz .LBB0_731
	s_and_b32 s1, s0, 0xff
	s_mov_b64 s[26:27], -1
	s_cmp_eq_u32 s1, 0
	s_mov_b64 s[30:31], -1
	s_mov_b64 s[28:29], -1
	s_sleep 1
	s_cbranch_scc1 .LBB0_735
	s_and_saveexec_b64 s[40:41], s[30:31]
	s_cbranch_execz .LBB0_730
	s_branch .LBB0_738
.LBB0_735:
	v_readlane_b32 s4, v253, 7
	v_readlane_b32 s5, v253, 8
	s_mov_b64 s[30:31], 0
	s_nop 0
	v_mov_b64_e32 v[18:19], s[4:5]
	global_load_dword v17, v[18:19], off sc1
	s_waitcnt vmcnt(0) lgkmcnt(0)
	v_cmp_eq_u32_e32 vcc, 0, v17
	s_and_saveexec_b64 s[40:41], vcc
	s_cmp_lt_u32 s0, 0x40001
	s_cselect_b64 s[4:5], -1, 0
	s_xor_b64 s[28:29], exec, -1
	s_and_b64 s[30:31], s[4:5], exec
	s_or_b64 exec, exec, s[40:41]
	s_and_saveexec_b64 s[40:41], s[30:31]
	s_cbranch_execz .LBB0_730

.LBB0_746:
	s_and_b32 s1, s0, 0xff
	s_mov_b64 s[26:27], -1
	s_cmp_lg_u32 s1, 0
	s_mov_b64 s[28:29], -1
	s_sleep 1
	s_cbranch_scc1 .LBB0_750
	v_readlane_b32 s4, v253, 7
	v_readlane_b32 s5, v253, 8
	s_mov_b64 s[28:29], 0
	s_mov_b64 s[30:31], -1
	v_mov_b64_e32 v[4:5], s[4:5]
	global_load_dword v0, v[4:5], off sc1
	s_waitcnt vmcnt(0) lgkmcnt(0)
	v_cmp_eq_u32_e32 vcc, 0, v0
	s_and_saveexec_b64 s[40:41], vcc
	s_cmp_lt_u32 s0, 0x40001
	s_cselect_b64 s[4:5], -1, 0
	s_xor_b64 s[30:31], exec, -1
	s_and_b64 s[28:29], s[4:5], exec
	s_or_b64 exec, exec, s[40:41]

.LBB0_771:
	s_or_b64 exec, exec, s[6:7]
	v_mov_b32_e32 v0, s64
	v_mov_b32_e32 v2, s65
	s_waitcnt lgkmcnt(0)
	s_barrier
	v_mov_b32_e32 v4, v247
	v_readfirstlane_b32 s0, v0
	v_readfirstlane_b32 s1, v2
	v_mov_b32_e32 v0, s88
	v_mov_b32_e32 v2, s0
	v_mov_b32_e32 v3, s1
	global_load_dwordx2 v[2:3], v[2:3], off offset:248
	s_waitcnt vmcnt(0) lgkmcnt(0)
	s_nop 0
	v_readfirstlane_b32 s4, v0
	s_ashr_i32 s5, s4, 31
	v_ashrrev_i32_e32 v5, 31, v4
	s_lshl_b64 s[4:5], s[4:5], 9
	v_readfirstlane_b32 s0, v2
	v_readfirstlane_b32 s1, v3
	v_lshl_add_u64 v[2:3], s[4:5], 0, v[4:5]
	s_mov_b64 s[4:5], 0x20000
	v_cmp_gt_u64_e32 vcc, s[4:5], v[2:3]
	s_and_saveexec_b64 s[6:7], vcc
	s_cbranch_execz .LBB0_776
	s_add_u32 s8, s0, 0x1bf00000
	s_addc_u32 s9, s1, 0
	s_add_u32 s12, s0, 0x20964000
	s_addc_u32 s13, s1, 0
	s_add_u32 s14, s0, 0x20969200
	s_addc_u32 s15, s1, 0
	s_mov_b64 s[22:23], 0

.LBB0_774:
	s_cmp_eq_u32 s0, 0
	s_cselect_b32 s4, 1, 19
	s_add_i32 s18, s1, 2
	s_add_i32 s20, s0, 17
	s_add_i32 s21, s1, 3
	s_add_i32 s24, s0, 16
	s_add_i32 s25, s1, 4
	s_add_i32 s26, s0, 15
	s_add_i32 s27, s1, 5
	s_add_i32 s28, s0, 14
	s_add_i32 s4, s4, s0
	v_mov_b32_e32 v0, s1
	v_mov_b32_e32 v14, s20
	v_mov_b32_e32 v16, s18
	v_mov_b32_e32 v18, s24
	v_mov_b32_e32 v20, s21
	v_mov_b32_e32 v22, s26
	v_mov_b32_e32 v23, s25
	v_mov_b32_e32 v24, s28
	v_mov_b32_e32 v25, s27
	v_mov_b32_e32 v26, s4
	s_or_b32 s5, s1, 1
	s_add_i32 s4, s4, -1
	v_cndmask_b32_e32 v14, v14, v16, vcc
	v_cndmask_b32_e32 v16, v18, v20, vcc
	v_cndmask_b32_e32 v18, v22, v23, vcc
	v_cndmask_b32_e32 v20, v24, v25, vcc
	v_cndmask_b32_e32 v22, v26, v0, vcc
	v_mov_b32_e32 v15, v1
	v_mov_b32_e32 v17, v1
	v_mov_b32_e32 v21, s5
	v_mov_b32_e32 v23, s4
	v_add_u32_e32 v0, v14, v5
	v_add_u32_e32 v14, v16, v5
	v_add_u32_e32 v16, v18, v5
	v_add_u32_e32 v18, v20, v5
	v_add_u32_e32 v20, v22, v5
	v_mov_b32_e32 v19, v1
	v_cndmask_b32_e32 v22, v23, v21, vcc
	v_lshlrev_b64 v[24:25], 3, v[0:1]
	v_lshlrev_b64 v[26:27], 3, v[14:15]
	v_lshlrev_b64 v[28:29], 3, v[16:17]
	v_ashrrev_i32_e32 v21, 31, v20
	v_lshlrev_b64 v[30:31], 3, v[18:19]
	v_add_u32_e32 v22, v22, v5
	v_or_b32_e32 v24, v24, v4
	v_or_b32_e32 v26, v26, v4
	v_or_b32_e32 v28, v28, v4
	v_lshlrev_b64 v[32:33], 3, v[20:21]
	v_or_b32_e32 v30, v30, v4
	v_ashrrev_i32_e32 v23, 31, v22
	v_lshlrev_b64 v[34:35], 15, v[24:25]
	v_lshl_add_u64 v[24:25], v[24:25], 2, s[12:13]
	v_lshlrev_b64 v[36:37], 15, v[26:27]
	v_lshl_add_u64 v[26:27], v[26:27], 2, s[12:13]
	v_lshlrev_b64 v[38:39], 15, v[28:29]
	v_lshl_add_u64 v[28:29], v[28:29], 2, s[12:13]
	v_or_b32_e32 v32, v32, v4
	v_lshlrev_b64 v[40:41], 15, v[30:31]
	v_lshl_add_u64 v[30:31], v[30:31], 2, s[12:13]
	v_lshlrev_b64 v[42:43], 3, v[22:23]
	v_lshl_add_u64 v[34:35], v[6:7], 0, v[34:35]
	global_load_dword v52, v[24:25], off
	global_load_dword v53, v[26:27], off
	global_load_dword v54, v[28:29], off
	global_load_dword v55, v[30:31], off
	v_lshl_add_u64 v[46:47], v[32:33], 2, s[12:13]
	v_lshl_add_u64 v[36:37], v[6:7], 0, v[36:37]
	v_lshl_add_u64 v[38:39], v[6:7], 0, v[38:39]
	v_lshl_add_u64 v[44:45], v[6:7], 0, v[40:41]
	v_lshlrev_b64 v[40:41], 15, v[32:33]
	v_or_b32_e32 v42, v42, v4
	global_load_dwordx4 v[24:27], v[34:35], off
	global_load_dwordx4 v[28:31], v[36:37], off
	s_nop 0
	global_load_dwordx4 v[32:35], v[38:39], off
	global_load_dword v56, v[46:47], off
	v_lshl_add_u64 v[36:37], v[6:7], 0, v[40:41]
	v_lshl_add_u64 v[38:39], v[42:43], 2, s[12:13]
	global_load_dword v57, v[38:39], off
	s_nop 0
	global_load_dwordx4 v[36:39], v[36:37], off
	v_lshlrev_b64 v[40:41], 15, v[42:43]
	v_lshl_add_u64 v[40:41], v[6:7], 0, v[40:41]
	global_load_dwordx4 v[40:43], v[40:41], off
	s_nop 0
	global_load_dwordx4 v[44:47], v[44:45], off
	v_lshlrev_b64 v[20:21], 17, v[20:21]
	v_cvt_pk_bf16_f32 v48, v12, v13
	v_cvt_pk_bf16_f32 v49, v10, v11
	v_lshl_add_u64 v[20:21], v[8:9], 0, v[20:21]
	global_store_dwordx2 v[20:21], v[48:49], off
	v_lshlrev_b64 v[50:51], 17, v[0:1]
	v_lshlrev_b64 v[22:23], 17, v[22:23]
	v_lshl_add_u64 v[22:23], v[8:9], 0, v[22:23]
	v_lshlrev_b64 v[14:15], 17, v[14:15]
	s_add_i32 s4, s1, 6
	s_add_i32 s0, s0, -6
	v_lshlrev_b64 v[16:17], 17, v[16:17]
	v_lshlrev_b64 v[18:19], 17, v[18:19]
	v_lshl_add_u64 v[14:15], v[8:9], 0, v[14:15]
	s_cmp_gt_u32 s1, 11
	s_mov_b32 s1, s4
	v_lshl_add_u64 v[50:51], v[8:9], 0, v[50:51]
	v_lshl_add_u64 v[16:17], v[8:9], 0, v[16:17]
	v_lshl_add_u64 v[18:19], v[8:9], 0, v[18:19]
	s_waitcnt vmcnt(0) lgkmcnt(0)
	v_mul_f32_e32 v0, 0x3fb8aa3b, v52
	v_mul_f32_e32 v20, 0x3fb8aa3b, v53
	v_mul_f32_e32 v21, 0x3fb8aa3b, v54
	v_exp_f32_e32 v48, v21
	v_exp_f32_e32 v0, v0
	v_exp_f32_e32 v20, v20
	v_mul_f32_e32 v49, 0x3fb8aa3b, v55
	v_exp_f32_e32 v52, v49
	v_mul_f32_e32 v21, 0x3fb8aa3b, v56
	v_exp_f32_e32 v54, v21
	v_mul_f32_e32 v21, 0x3fb8aa3b, v57
	v_exp_f32_e32 v56, v21
	v_pk_fma_f32 v[12:13], v[12:13], v[54:55], v[36:37] op_sel_hi:[1,0,1]
	v_pk_fma_f32 v[10:11], v[10:11], v[54:55], v[38:39] op_sel_hi:[1,0,1]
	v_cvt_pk_bf16_f32 v36, v12, v13
	v_pk_fma_f32 v[12:13], v[12:13], v[56:57], v[40:41] op_sel_hi:[1,0,1]
	v_cvt_pk_bf16_f32 v37, v10, v11
	v_pk_fma_f32 v[10:11], v[10:11], v[56:57], v[42:43] op_sel_hi:[1,0,1]
	v_cvt_pk_bf16_f32 v38, v12, v13
	v_pk_fma_f32 v[12:13], v[12:13], v[0:1], v[24:25] op_sel_hi:[1,0,1]
	v_cvt_pk_bf16_f32 v39, v10, v11
	v_pk_fma_f32 v[10:11], v[10:11], v[0:1], v[26:27] op_sel_hi:[1,0,1]
	global_store_dwordx2 v[22:23], v[36:37], off
	v_cvt_pk_bf16_f32 v22, v12, v13
	v_pk_fma_f32 v[12:13], v[12:13], v[20:21], v[28:29] op_sel_hi:[1,0,1]
	v_cvt_pk_bf16_f32 v23, v10, v11
	v_pk_fma_f32 v[10:11], v[10:11], v[20:21], v[30:31] op_sel_hi:[1,0,1]
	v_cvt_pk_bf16_f32 v20, v12, v13
	v_pk_fma_f32 v[12:13], v[12:13], v[48:49], v[32:33] op_sel_hi:[1,0,1]
	v_cvt_pk_bf16_f32 v21, v10, v11
	v_pk_fma_f32 v[10:11], v[10:11], v[48:49], v[34:35] op_sel_hi:[1,0,1]
	global_store_dwordx2 v[14:15], v[22:23], off
	v_cvt_pk_bf16_f32 v14, v12, v13
	v_pk_fma_f32 v[12:13], v[12:13], v[52:53], v[44:45] op_sel_hi:[1,0,1]
	v_cvt_pk_bf16_f32 v15, v10, v11
	v_pk_fma_f32 v[10:11], v[10:11], v[52:53], v[46:47] op_sel_hi:[1,0,1]
	global_store_dwordx2 v[50:51], v[38:39], off
	global_store_dwordx2 v[16:17], v[20:21], off
	global_store_dwordx2 v[18:19], v[14:15], off
	s_cbranch_scc0 .LBB0_774
	v_lshl_add_u64 v[2:3], v[2:3], 0, s[60:61]
	s_mov_b64 s[0:1], 0x1ffff
	v_cmp_lt_u64_e32 vcc, s[0:1], v[2:3]
	s_or_b64 s[22:23], vcc, s[22:23]
	s_andn2_b64 exec, exec, s[22:23]
	s_cbranch_execnz .LBB0_773

.LBB0_824:
	s_cmpk_gt_i32 s8, 0x8f
	s_mov_b64 s[6:7], -1
	s_cbranch_scc0 .LBB0_834
	v_mov_b32_e32 v2, s64
	v_mov_b32_e32 v3, s65
	v_mov_b32_e32 v4, s64
	v_readfirstlane_b32 s0, v2
	v_readfirstlane_b32 s1, v3
	v_mov_b32_e32 v5, s65
	v_mov_b32_e32 v2, s0
	v_mov_b32_e32 v3, s1
	global_load_dwordx2 v[2:3], v[2:3], off offset:248
	s_waitcnt vmcnt(0) lgkmcnt(0)
	v_mov_b32_e32 v0, s64
	v_readfirstlane_b32 s0, v4
	v_readfirstlane_b32 s1, v5
	v_mov_b32_e32 v6, s65
	v_mov_b32_e32 v4, s0
	v_mov_b32_e32 v5, s1
	global_load_dwordx2 v[4:5], v[4:5], off offset:248
	v_readfirstlane_b32 s4, v3
	v_mov_b32_e32 v32, v247
	s_mov_b32 s23, s19
	s_mov_b32 s13, s19
	v_mov_b32_e32 v31, v1
	v_cmp_lt_i32_e32 vcc, v222, v220
	v_mov_b32_e32 v68, 0xf149f2ca
	v_mov_b32_e32 v62, 0
	s_waitcnt vmcnt(0) lgkmcnt(0)
	v_mov_b32_e32 v8, v5
	s_nop 0
	v_readfirstlane_b32 s0, v0
	v_readfirstlane_b32 s1, v6
	v_readfirstlane_b32 s9, v4
	v_mov_b32_e32 v6, s0
	v_mov_b32_e32 v7, s1
	s_add_i32 s0, s8, 0xffffff70
	v_readfirstlane_b32 s1, v2
	s_add_u32 s14, s1, 0x9f00000
	global_load_dwordx2 v[50:51], v[6:7], off offset:248
	s_addc_u32 s15, s4, 0
	s_lshl_b32 s1, s0, 7
	s_bfe_u32 s4, s0, 0x20004
	s_lshr_b32 s18, s0, 6
	s_lshl_b32 s0, s0, 1
	s_and_b32 s1, s1, 0x780
	s_waitcnt vmcnt(0) lgkmcnt(0)
	s_lshl_b64 s[6:7], s[18:19], 11
	v_ashrrev_i32_e32 v0, 2, v32
	v_and_b32_e32 v33, 15, v32
	s_and_b32 s5, s0, 64
	s_lshl_b32 s0, s18, 8
	v_readfirstlane_b32 s20, v8
	v_lshrrev_b32_e32 v4, 1, v32
	v_ashrrev_i32_e32 v54, 3, v32
	v_and_b32_e32 v8, -16, v0
	v_or_b32_e32 v0, s1, v33
	v_mov_b32_e32 v5, s7
	s_add_i32 s18, s0, 0x4000
	v_and_b32_e32 v52, 24, v4
	v_ashrrev_i32_e32 v55, 31, v54
	v_add_u32_e32 v12, s5, v54
	v_ashrrev_i32_e32 v9, 31, v8
	v_or_b32_e32 v4, s6, v0
	v_mov_b64_e32 v[2:3], s[14:15]
	v_mov_b32_e32 v6, s9
	v_mov_b32_e32 v7, s20
	v_lshl_add_u64 v[10:11], s[18:19], 0, v[54:55]
	v_add_u32_e32 v12, 0x180, v12
	v_lshl_add_u64 v[56:57], v[4:5], 0, v[8:9]
	v_lshlrev_b32_e32 v36, 3, v32
	v_mad_u64_u32 v[4:5], s[20:21], v10, s2, v[2:3]
	v_mad_i64_i32 v[6:7], s[20:21], v12, s33, v[6:7]
	v_mad_u64_u32 v[2:3], s[20:21], v56, s2, v[2:3]
	s_lshl_b32 s22, s4, 7
	s_lshl_b32 s12, s5, 1
	v_and_b32_e32 v53, 56, v36
	v_mad_i32_i24 v5, v11, s2, v5
	s_mov_b64 s[20:21], 0x17700000
	v_mad_i32_i24 v3, v57, s2, v3
	v_lshlrev_b32_e32 v0, 1, v52
	v_lshlrev_b32_e32 v30, 1, v53
	v_lshl_add_u64 v[34:35], v[6:7], 0, s[20:21]
	v_lshl_add_u64 v[4:5], v[4:5], 0, s[12:13]
	v_lshl_add_u64 v[2:3], v[2:3], 0, s[22:23]
	v_lshl_add_u64 v[6:7], s[18:19], 1, v[34:35]
	v_lshl_add_u64 v[4:5], v[4:5], 0, v[30:31]
	v_lshl_add_u64 v[2:3], v[2:3], 0, v[0:1]
	v_lshl_add_u64 v[6:7], v[6:7], 0, v[30:31]
	global_load_dwordx4 v[22:25], v[4:5], off offset:2304
	global_load_dwordx4 v[26:29], v[6:7], off
	global_load_dwordx4 v[14:17], v[2:3], off offset:1792
	global_load_dwordx4 v[18:21], v[2:3], off offset:1856
	v_lshlrev_b32_e32 v37, 4, v32
	v_lshlrev_b32_e32 v32, 1, v32
	s_movk_i32 s9, 0x90
	v_cndmask_b32_e32 v6, v219, v222, vcc
	v_cmp_lt_i32_e32 vcc, v221, v220
	v_and_b32_e32 v36, 32, v36
	v_and_b32_e32 v37, 16, v37
	v_and_b32_e32 v32, 4, v32
	v_mul_lo_u32 v38, v54, s9
	v_cndmask_b32_e32 v7, v219, v221, vcc
	v_mov_b32_e32 v4, v1
	v_mov_b32_e32 v5, v1
	v_mul_u32_u24_e32 v65, 0x90, v33
	v_or3_b32 v66, v36, v37, v32
	v_add_u32_e32 v67, 16, v38
	v_lshl_add_u64 v[32:33], s[14:15], 0, v[30:31]
	s_or_b32 s18, s12, 0x900
	v_mov_b32_e32 v2, v1
	v_mov_b32_e32 v3, v1
	v_lshlrev_b32_e32 v64, 2, v6
	v_lshlrev_b32_e32 v63, 2, v7
	v_mov_b64_e32 v[8:9], v[4:5]
	v_mov_b64_e32 v[12:13], v[4:5]
	v_add_u32_e32 v36, v67, v30
	v_lshl_add_u64 v[58:59], v[34:35], 0, v[30:31]
	v_lshl_add_u64 v[60:61], v[32:33], 0, s[18:19]
	v_mov_b64_e32 v[32:33], v[4:5]
	s_mov_b32 s1, 0
	s_movk_i32 s5, 0x4040
	v_mov_b64_e32 v[6:7], v[2:3]
	v_mov_b64_e32 v[10:11], v[2:3]
	s_lshl_b32 s4, s4, 6
	v_lshl_add_u32 v37, v66, 1, v67
	v_mov_b64_e32 v[30:31], v[2:3]
	v_add_u32_e32 v37, 0x2000, v37
	s_waitcnt vmcnt(0) lgkmcnt(0)
	ds_write_b128 v36, v[22:25]
	ds_write2_b64 v37, v[26:27], v[28:29] offset0:128 offset1:130
	s_waitcnt lgkmcnt(0)
	s_barrier
	s_branch .LBB0_827

.LBB0_827:
	s_cmp_lg_u32 s1, 35
	s_cselect_b64 s[12:13], -1, 0
	s_cmp_eq_u32 s1, 35
	s_cbranch_scc1 .LBB0_829
	s_cmp_lt_u32 s1, 3
	s_cselect_b64 s[14:15], -1, 0
	s_add_i32 s9, s5, 0xffffbf00
	s_and_b64 s[14:15], s[14:15], exec
	s_cselect_b32 s9, s5, s9
	s_cselect_b32 s14, s0, s6
	s_cselect_b32 s15, 0, s7
	s_add_u32 s14, s14, s9
	s_addc_u32 s15, s15, 0
	s_waitcnt vmcnt(0)
	v_lshl_add_u64 v[22:23], s[14:15], 0, v[54:55]
	v_mad_u64_u32 v[24:25], s[20:21], v22, s2, v[60:61]
	v_mad_i32_i24 v25, v23, s2, v25
	v_lshl_add_u64 v[26:27], s[14:15], 1, v[58:59]
	global_load_dwordx4 v[22:25], v[24:25], off
	s_nop 0
	global_load_dwordx4 v[26:29], v[26:27], off

.LBB0_833:
	ds_bpermute_b32 v0, v64, v62
	v_readfirstlane_b32 s0, v50
	v_readfirstlane_b32 s1, v51
	v_lshlrev_b64 v[14:15], 11, v[56:57]
	s_lshl_b32 s18, s4, 1
	s_waitcnt lgkmcnt(0)
	v_add_f32_e32 v0, v62, v0
	ds_bpermute_b32 v16, v63, v0
	v_lshl_add_u64 v[14:15], s[0:1], 0, v[14:15]
	v_mov_b32_e32 v53, v1
	v_lshl_add_u64 v[14:15], v[14:15], 0, s[18:19]
	v_lshl_add_u64 v[14:15], v[14:15], 0, v[52:53]
	s_waitcnt lgkmcnt(0)
	v_add_f32_e32 v0, v0, v16
	v_div_scale_f32 v16, s[0:1], v0, v0, 1.0
	v_rcp_f32_e32 v17, v16
	v_div_scale_f32 v18, vcc, 1.0, v0, 1.0
	s_mov_b64 s[0:1], 0x1e300400
	v_fma_f32 v19, -v16, v17, 1.0
	v_fmac_f32_e32 v17, v19, v17
	v_mul_f32_e32 v19, v18, v17
	v_fma_f32 v20, -v16, v19, v18
	v_fmac_f32_e32 v19, v20, v17
	v_fma_f32 v16, -v16, v19, v18
	v_div_fmas_f32 v16, v16, v17, v19
	v_div_fixup_f32 v0, v16, v0, 1.0
	v_lshl_add_u64 v[16:17], v[14:15], 0, s[0:1]
	v_pk_mul_f32 v[18:19], v[30:31], v[0:1] op_sel_hi:[1,0]
	v_pk_mul_f32 v[20:21], v[32:33], v[0:1] op_sel_hi:[1,0]
	v_add_co_u32_e32 v14, vcc, s34, v14
	v_pk_mul_f32 v[10:11], v[10:11], v[0:1] op_sel_hi:[1,0]
	v_pk_mul_f32 v[12:13], v[12:13], v[0:1] op_sel_hi:[1,0]
	v_pk_mul_f32 v[6:7], v[6:7], v[0:1] op_sel_hi:[1,0]
	v_pk_mul_f32 v[8:9], v[8:9], v[0:1] op_sel_hi:[1,0]
	v_pk_mul_f32 v[2:3], v[2:3], v[0:1] op_sel_hi:[1,0]
	v_pk_mul_f32 v[4:5], v[4:5], v[0:1] op_sel_hi:[1,0]
	v_cvt_pk_bf16_f32 v18, v18, v19
	v_cvt_pk_bf16_f32 v19, v20, v21
	v_addc_co_u32_e32 v15, vcc, 0, v15, vcc
	v_cvt_pk_bf16_f32 v10, v10, v11
	v_cvt_pk_bf16_f32 v11, v12, v13
	v_cvt_pk_bf16_f32 v6, v6, v7
	v_cvt_pk_bf16_f32 v7, v8, v9
	v_cvt_pk_bf16_f32 v2, v2, v3
	v_cvt_pk_bf16_f32 v3, v4, v5
	s_mov_b64 s[6:7], 0
	s_mov_b32 s18, 0x800000
	global_store_dwordx2 v[14:15], v[18:19], off offset:1024
	global_store_dwordx2 v[16:17], v[10:11], off offset:32
	global_store_dwordx2 v[16:17], v[6:7], off offset:64
	global_store_dwordx2 v[16:17], v[2:3], off offset:96
.LBB0_834:
	s_and_b64 vcc, exec, s[6:7]
	s_cbranch_vccz .LBB0_823
	s_mul_hi_i32 s0, s8, 0x38e38e39
	s_lshr_b32 s1, s0, 31
	s_ashr_i32 s0, s0, 2
	s_add_i32 s14, s0, s1
	s_mul_i32 s0, s14, 18
	s_sub_i32 s0, s8, s0
	v_readlane_b32 s6, v254, 49
	s_cmp_lt_i32 s0, 2
	v_readlane_b32 s7, v254, 50
	s_cselect_b64 s[4:5], -1, 0
	s_xor_b64 s[6:7], s[6:7], -1
	s_and_b64 s[4:5], s[6:7], s[4:5]
	s_and_b64 vcc, exec, s[4:5]
	s_cbranch_vccnz .LBB0_823
	v_mov_b32_e32 v0, s64
	v_mov_b32_e32 v2, s65
	s_cmp_gt_i32 s0, 1
	v_readfirstlane_b32 s1, v0
	v_readfirstlane_b32 s4, v2
	s_mov_b64 s[22:23], -1
	v_mov_b32_e32 v2, s1
	v_mov_b32_e32 v3, s4
	global_load_dwordx2 v[4:5], v[2:3], off offset:248
	v_mov_b32_e32 v2, v247
	s_waitcnt vmcnt(0) lgkmcnt(0)
	v_mov_b32_e32 v0, v4
	s_nop 0
	v_readfirstlane_b32 s6, v0
	v_readfirstlane_b32 s7, v5
	s_cbranch_scc0 .LBB0_838
	s_ashr_i32 s15, s14, 31
	s_lshl_b32 s1, s0, 7
	s_lshl_b64 s[4:5], s[14:15], 11
	s_addk_i32 s1, 0xff00
	s_add_u32 s12, s4, s1
	s_addc_u32 s13, s5, 0
	s_mov_b64 s[22:23], 0

.LBB0_842:
	v_add_co_u32_e32 v8, vcc, 0x90000, v4
	v_add_u32_e32 v7, 0xfffff000, v6
	s_nop 0
	v_addc_co_u32_e32 v9, vcc, 0, v5, vcc
	global_load_dword v3, v[8:9], off
	v_add_u32_e32 v0, 0x200, v0
	v_cmp_lt_i32_e32 vcc, s4, v0
	s_or_b64 s[22:23], vcc, s[22:23]
	s_waitcnt vmcnt(0) lgkmcnt(0)
	ds_write_b32 v7, v3
	global_load_dword v3, v[4:5], off
	v_lshl_add_u64 v[4:5], v[4:5], 0, s[20:21]
	s_waitcnt vmcnt(0) lgkmcnt(0)
	ds_write_b32 v6, v3
	v_add_u32_e32 v6, 0x800, v6
	s_andn2_b64 exec, exec, s[22:23]
	s_cbranch_execnz .LBB0_842

.LBB0_844:
	v_lshl_or_b32 v0, s0, 13, v69
	v_lshl_add_u64 v[106:107], v[0:1], 1, v[72:73]
	v_or_b32_e32 v38, 0x800, v0
	v_mov_b32_e32 v39, v1
	v_or_b32_e32 v42, 0x1000, v0
	v_mov_b32_e32 v43, v1
	global_load_dwordx4 v[34:37], v[106:107], off
	v_lshlrev_b64 v[122:123], 1, v[38:39]
	v_lshlrev_b64 v[126:127], 1, v[42:43]
	v_or_b32_e32 v46, 0x1800, v0
	v_mov_b32_e32 v47, v1
	v_lshl_add_u64 v[38:39], v[72:73], 0, v[122:123]
	v_lshl_add_u64 v[42:43], v[72:73], 0, v[126:127]
	v_lshlrev_b64 v[130:131], 1, v[46:47]
	global_load_dwordx4 v[38:41], v[38:39], off
	v_lshl_add_u64 v[46:47], v[72:73], 0, v[130:131]
	global_load_dwordx4 v[42:45], v[42:43], off
	s_nop 0
	global_load_dwordx4 v[46:49], v[46:47], off
	s_nop 0
	global_load_dwordx4 v[50:53], v[106:107], off offset:64
	v_lshl_add_u64 v[54:55], v[78:79], 0, v[122:123]
	v_lshl_add_u64 v[58:59], v[78:79], 0, v[126:127]
	global_load_dwordx4 v[54:57], v[54:55], off
	v_lshl_add_u64 v[90:91], v[78:79], 0, v[130:131]
	global_load_dwordx4 v[58:61], v[58:59], off
	v_lshl_add_u64 v[98:99], v[80:81], 0, v[122:123]
	v_lshl_add_u64 v[102:103], v[80:81], 0, v[126:127]
	v_lshl_add_u64 v[114:115], v[80:81], 0, v[130:131]
	global_load_dwordx4 v[90:93], v[90:91], off
	s_nop 0
	global_load_dwordx4 v[94:97], v[106:107], off offset:128
	v_add_u32_e32 v110, 4, v110
	global_load_dwordx4 v[98:101], v[98:99], off
	s_waitcnt vmcnt(0) lgkmcnt(0)
	v_mfma_f32_16x16x32_bf16 v[46:49], v[46:49], v[14:17], 0
	global_load_dwordx4 v[102:105], v[102:103], off
	s_nop 0
	global_load_dwordx4 v[114:117], v[114:115], off
	s_nop 0
	global_load_dwordx4 v[118:121], v[106:107], off offset:192
	v_lshl_add_u64 v[106:107], v[82:83], 0, v[122:123]
	global_load_dwordx4 v[122:125], v[106:107], off
	v_lshl_add_u64 v[106:107], v[82:83], 0, v[126:127]
	global_load_dwordx4 v[126:129], v[106:107], off
	v_lshl_add_u64 v[106:107], v[82:83], 0, v[130:131]
	global_load_dwordx4 v[130:133], v[106:107], off
	v_mfma_f32_16x16x32_bf16 v[34:37], v[34:37], v[14:17], 0
	v_mfma_f32_16x16x32_bf16 v[38:41], v[38:41], v[14:17], 0
	v_mfma_f32_16x16x32_bf16 v[42:45], v[42:45], v[14:17], 0
	v_mfma_f32_16x16x32_bf16 v[46:49], v[90:93], v[10:13], v[46:49]
	v_mfma_f32_16x16x32_bf16 v[34:37], v[50:53], v[10:13], v[34:37]
	v_mul_f32_e32 v50, 0x3fb8aa3b, v88
	v_exp_f32_e32 v50, v50
	v_mfma_f32_16x16x32_bf16 v[38:41], v[54:57], v[10:13], v[38:41]
	v_mfma_f32_16x16x32_bf16 v[42:45], v[58:61], v[10:13], v[42:45]
	s_waitcnt vmcnt(0) lgkmcnt(0)
	v_mfma_f32_16x16x32_bf16 v[46:49], v[114:117], v[6:9], v[46:49]
	v_mfma_f32_16x16x32_bf16 v[34:37], v[94:97], v[6:9], v[34:37]
	v_mfma_f32_16x16x32_bf16 v[38:41], v[98:101], v[6:9], v[38:41]
	v_mfma_f32_16x16x32_bf16 v[42:45], v[102:105], v[6:9], v[42:45]
	v_mfma_f32_16x16x32_bf16 v[46:49], v[130:133], v[2:5], v[46:49]
	v_mfma_f32_16x16x32_bf16 v[34:37], v[118:121], v[2:5], v[34:37]
	v_mfma_f32_16x16x32_bf16 v[38:41], v[122:125], v[2:5], v[38:41]
	s_nop 5
	v_fma_f32 v104, v50, v46, v18
	v_fma_f32 v105, v50, v47, v19
	v_add_u32_e32 v18, 0x8000, v0
	v_mov_b32_e32 v19, v1
	v_mfma_f32_16x16x32_bf16 v[42:45], v[126:129], v[2:5], v[42:45]
	v_lshlrev_b64 v[46:47], 1, v[18:19]
	v_pk_fma_f32 v[92:93], v[50:51], v[34:35], v[30:31] op_sel_hi:[0,1,1]
	v_lshl_add_u64 v[18:19], v[72:73], 0, v[46:47]
	v_lshl_add_u64 v[30:31], v[80:81], 0, v[46:47]
	v_pk_fma_f32 v[90:91], v[50:51], v[36:37], v[32:33] op_sel_hi:[0,1,1]
	global_load_dwordx4 v[114:117], v[18:19], off
	v_pk_fma_f32 v[94:95], v[50:51], v[40:41], v[28:29] op_sel_hi:[0,1,1]
	global_load_dwordx4 v[30:33], v[30:31], off
	v_add_u32_e32 v18, 0x8800, v0
	v_mov_b32_e32 v19, v1
	v_pk_fma_f32 v[96:97], v[50:51], v[38:39], v[26:27] op_sel_hi:[0,1,1]
	v_pk_fma_f32 v[98:99], v[50:51], v[44:45], v[24:25] op_sel_hi:[0,1,1]
	v_pk_fma_f32 v[100:101], v[50:51], v[42:43], v[22:23] op_sel_hi:[0,1,1]
	v_pk_fma_f32 v[102:103], v[50:51], v[48:49], v[20:21] op_sel_hi:[0,1,1]
	v_lshlrev_b64 v[50:51], 1, v[18:19]
	v_lshl_add_u64 v[18:19], v[72:73], 0, v[50:51]
	v_lshl_add_u64 v[34:35], v[80:81], 0, v[50:51]
	global_load_dwordx4 v[118:121], v[18:19], off
	s_waitcnt vmcnt(0) lgkmcnt(0)
	v_mfma_f32_16x16x32_bf16 v[114:117], v[114:117], v[14:17], 0
	global_load_dwordx4 v[34:37], v[34:35], off
	v_add_u32_e32 v18, 0x9000, v0
	v_mov_b32_e32 v19, v1
	v_lshlrev_b64 v[54:55], 1, v[18:19]
	v_add_u32_e32 v0, 0x9800, v0
	v_lshl_add_u64 v[18:19], v[72:73], 0, v[54:55]
	v_lshlrev_b64 v[58:59], 1, v[0:1]
	v_lshl_add_u64 v[22:23], v[78:79], 0, v[54:55]
	global_load_dwordx4 v[122:125], v[18:19], off
	v_lshl_add_u64 v[26:27], v[78:79], 0, v[58:59]
	global_load_dwordx4 v[22:25], v[22:23], off
	v_lshl_add_u64 v[18:19], v[72:73], 0, v[58:59]
	global_load_dwordx4 v[126:129], v[18:19], off
	v_lshl_add_u64 v[38:39], v[80:81], 0, v[54:55]
	global_load_dwordx4 v[26:29], v[26:27], off
	v_lshl_add_u64 v[18:19], v[78:79], 0, v[46:47]
	global_load_dwordx4 v[130:133], v[18:19], off
	v_lshl_add_u64 v[42:43], v[80:81], 0, v[58:59]
	global_load_dwordx4 v[38:41], v[38:39], off
	v_lshl_add_u64 v[18:19], v[78:79], 0, v[50:51]
	global_load_dwordx4 v[18:21], v[18:19], off
	v_lshl_add_u64 v[46:47], v[82:83], 0, v[46:47]
	global_load_dwordx4 v[42:45], v[42:43], off
	v_lshl_add_u64 v[50:51], v[82:83], 0, v[50:51]
	v_lshl_add_u64 v[54:55], v[82:83], 0, v[54:55]
	v_lshl_add_u64 v[58:59], v[82:83], 0, v[58:59]
	global_load_dwordx4 v[46:49], v[46:47], off
	v_mfma_f32_16x16x32_bf16 v[118:121], v[118:121], v[14:17], 0
	global_load_dwordx4 v[50:53], v[50:51], off
	v_mul_f32_e32 v0, 0x3fb8aa3b, v89
	global_load_dwordx4 v[54:57], v[54:55], off
	s_waitcnt vmcnt(0) lgkmcnt(0)
	v_mfma_f32_16x16x32_bf16 v[122:125], v[122:125], v[14:17], 0
	global_load_dwordx4 v[58:61], v[58:59], off
	v_exp_f32_e32 v0, v0
	v_mfma_f32_16x16x32_bf16 v[14:17], v[126:129], v[14:17], 0
	v_mfma_f32_16x16x32_bf16 v[114:117], v[130:133], v[10:13], v[114:117]
	v_mfma_f32_16x16x32_bf16 v[18:21], v[18:21], v[10:13], v[118:121]
	v_mfma_f32_16x16x32_bf16 v[22:25], v[22:25], v[10:13], v[122:125]
	v_mfma_f32_16x16x32_bf16 v[10:13], v[26:29], v[10:13], v[14:17]
	v_mfma_f32_16x16x32_bf16 v[14:17], v[30:33], v[6:9], v[114:117]
	v_mfma_f32_16x16x32_bf16 v[18:21], v[34:37], v[6:9], v[18:21]
	v_mfma_f32_16x16x32_bf16 v[22:25], v[38:41], v[6:9], v[22:25]
	v_mfma_f32_16x16x32_bf16 v[6:9], v[42:45], v[6:9], v[10:13]
	v_mfma_f32_16x16x32_bf16 v[10:13], v[46:49], v[2:5], v[14:17]
	v_mfma_f32_16x16x32_bf16 v[14:17], v[50:53], v[2:5], v[18:21]
	v_mfma_f32_16x16x32_bf16 v[24:27], v[54:57], v[2:5], v[22:25]
	s_waitcnt vmcnt(0) lgkmcnt(0)
	v_mfma_f32_16x16x32_bf16 v[6:9], v[58:61], v[2:5], v[6:9]
	s_nop 3
	v_fma_f32 v4, v0, v12, v90
	v_fma_f32 v5, v0, v13, v91
	v_pk_fma_f32 v[2:3], v[0:1], v[10:11], v[92:93] op_sel_hi:[0,1,1]
	v_pk_fma_f32 v[20:21], v[0:1], v[16:17], v[94:95] op_sel_hi:[0,1,1]
	v_pk_fma_f32 v[22:23], v[0:1], v[14:15], v[96:97] op_sel_hi:[0,1,1]
	v_pk_fma_f32 v[14:15], v[0:1], v[26:27], v[98:99] op_sel_hi:[0,1,1]
	v_pk_fma_f32 v[18:19], v[0:1], v[24:25], v[100:101] op_sel_hi:[0,1,1]
	v_pk_fma_f32 v[8:9], v[0:1], v[8:9], v[102:103] op_sel_hi:[0,1,1]
	v_pk_fma_f32 v[6:7], v[0:1], v[6:7], v[104:105] op_sel_hi:[0,1,1]
	v_mov_b32_e32 v0, s64
	v_mov_b32_e32 v10, s65
	s_nop 0
	v_readfirstlane_b32 s4, v0
	v_readfirstlane_b32 s5, v10
	s_nop 0
	v_mov_b32_e32 v10, s4
	v_mov_b32_e32 v11, s5
	global_load_dwordx2 v[10:11], v[10:11], off offset:168
	v_readlane_b32 s4, v254, 51
	s_add_i32 s4, s0, s4
	s_ashr_i32 s5, s4, 31
	s_lshl_b64 s[4:5], s[4:5], 2
	s_waitcnt vmcnt(0) lgkmcnt(0)
	v_mov_b32_e32 v0, v11
	s_nop 0
	v_readfirstlane_b32 s9, v10
	v_readfirstlane_b32 s14, v0
	s_add_u32 s4, s9, s4
	s_addc_u32 s5, s14, s5
	s_lshl_b32 s18, s1, 1
	v_lshl_add_u64 v[16:17], v[74:75], 0, s[18:19]
	global_load_dwordx2 v[12:13], v[16:17], off
	v_or_b32_e32 v0, s1, v109
	v_mul_lo_u32 v0, v0, s82
	v_mov_b64_e32 v[10:11], s[4:5]
	global_load_dword v10, v[10:11], off
	v_lshl_add_u32 v11, s0, 15, v65
	s_add_i32 s0, s0, 1
	s_add_u32 s12, s12, 64
	s_addc_u32 s13, s13, 0
	s_mov_b64 s[4:5], 0x240000
	v_lshl_add_u64 v[86:87], v[86:87], 0, s[4:5]
	s_cmp_eq_u32 s0, 4
	s_waitcnt vmcnt(0) lgkmcnt(0)
	v_lshlrev_b32_e32 v24, 16, v12
	v_and_b32_e32 v25, 0xffff0000, v12
	v_lshlrev_b32_e32 v26, 16, v13
	v_and_b32_e32 v27, 0xffff0000, v13
	v_lshl_add_u64 v[12:13], v[0:1], 1, v[76:77]
	global_load_ushort v0, v[12:13], off
	v_add_co_u32_e32 v28, vcc, s33, v12
	s_nop 1
	v_addc_co_u32_e32 v29, vcc, 0, v13, vcc
	global_load_ushort v29, v[28:29], off
	v_mul_f32_e32 v28, 0xbfb8aa3b, v24
	v_exp_f32_e32 v28, v28
	s_waitcnt vmcnt(0) lgkmcnt(0)
	v_lshlrev_b32_e32 v30, 16, v0
	v_mul_f32_e32 v0, 0xbfb8aa3b, v25
	v_exp_f32_e32 v0, v0
	v_add_f32_e32 v28, 1.0, v28
	v_rcp_f32_e32 v28, v28
	v_add_f32_e32 v0, 1.0, v0
	v_lshlrev_b32_e32 v31, 16, v29
	v_rcp_f32_e32 v29, v0
	v_pk_fma_f32 v[2:3], v[10:11], v[30:31], v[2:3] op_sel_hi:[0,1,1]
	v_pk_mul_f32 v[24:25], v[28:29], v[24:25]
	s_nop 0
	v_pk_mul_f32 v[2:3], v[2:3], v[24:25]
	v_add_co_u32_e32 v24, vcc, s46, v12
	s_nop 1
	v_addc_co_u32_e32 v25, vcc, 0, v13, vcc
	global_load_ushort v0, v[24:25], off
	v_add_co_u32_e32 v24, vcc, s47, v12
	s_waitcnt vmcnt(0) lgkmcnt(0)
	v_lshlrev_b32_e32 v28, 16, v0
	v_addc_co_u32_e32 v25, vcc, 0, v13, vcc
	global_load_ushort v25, v[24:25], off
	v_mul_f32_e32 v24, 0xbfb8aa3b, v26
	v_mul_f32_e32 v0, 0xbfb8aa3b, v27
	v_exp_f32_e32 v24, v24
	v_exp_f32_e32 v0, v0
	v_add_f32_e32 v24, 1.0, v24
	v_add_f32_e32 v0, 1.0, v0
	v_rcp_f32_e32 v24, v24
	s_waitcnt vmcnt(0) lgkmcnt(0)
	v_lshlrev_b32_e32 v29, 16, v25
	v_rcp_f32_e32 v25, v0
	v_pk_fma_f32 v[4:5], v[10:11], v[28:29], v[4:5] op_sel_hi:[0,1,1]
	v_add_co_u32_e32 v28, vcc, s44, v12
	v_pk_mul_f32 v[24:25], v[24:25], v[26:27]
	s_nop 0
	v_addc_co_u32_e32 v29, vcc, 0, v13, vcc
	v_pk_mul_f32 v[4:5], v[24:25], v[4:5]
	ds_write_b128 v11, v[2:5]
	global_load_dwordx2 v[24:25], v[16:17], off offset:32
	global_load_ushort v0, v[28:29], off
	v_add_co_u32_e32 v28, vcc, s48, v12
	s_waitcnt vmcnt(0) lgkmcnt(0)
	v_lshlrev_b32_e32 v26, 16, v24
	v_addc_co_u32_e32 v29, vcc, 0, v13, vcc
	global_load_ushort v29, v[28:29], off
	v_and_b32_e32 v27, 0xffff0000, v24
	v_mul_f32_e32 v28, 0xbfb8aa3b, v26
	v_lshlrev_b32_e32 v30, 16, v0
	v_mul_f32_e32 v0, 0xbfb8aa3b, v27
	v_exp_f32_e32 v28, v28
	v_exp_f32_e32 v0, v0
	v_lshlrev_b32_e32 v24, 16, v25
	v_and_b32_e32 v25, 0xffff0000, v25
	v_add_f32_e32 v28, 1.0, v28
	v_add_f32_e32 v0, 1.0, v0
	v_rcp_f32_e32 v28, v28
	s_waitcnt vmcnt(0) lgkmcnt(0)
	v_lshlrev_b32_e32 v31, 16, v29
	v_rcp_f32_e32 v29, v0
	v_pk_fma_f32 v[22:23], v[10:11], v[30:31], v[22:23] op_sel_hi:[0,1,1]
	v_pk_mul_f32 v[26:27], v[28:29], v[26:27]
	s_nop 0
	v_pk_mul_f32 v[22:23], v[22:23], v[26:27]
	v_add_co_u32_e32 v26, vcc, s49, v12
	s_nop 1
	v_addc_co_u32_e32 v27, vcc, 0, v13, vcc
	global_load_ushort v0, v[26:27], off
	v_add_co_u32_e32 v26, vcc, s50, v12
	s_waitcnt vmcnt(0) lgkmcnt(0)
	v_lshlrev_b32_e32 v28, 16, v0
	v_addc_co_u32_e32 v27, vcc, 0, v13, vcc
	global_load_ushort v27, v[26:27], off
	v_mul_f32_e32 v26, 0xbfb8aa3b, v24
	v_mul_f32_e32 v0, 0xbfb8aa3b, v25
	v_exp_f32_e32 v26, v26
	v_exp_f32_e32 v0, v0
	v_add_f32_e32 v26, 1.0, v26
	v_add_f32_e32 v0, 1.0, v0
	v_rcp_f32_e32 v26, v26
	s_waitcnt vmcnt(0) lgkmcnt(0)
	v_lshlrev_b32_e32 v29, 16, v27
	v_rcp_f32_e32 v27, v0
	v_pk_fma_f32 v[20:21], v[10:11], v[28:29], v[20:21] op_sel_hi:[0,1,1]
	v_pk_mul_f32 v[24:25], v[26:27], v[24:25]
	s_nop 0
	v_pk_mul_f32 v[24:25], v[24:25], v[20:21]
	v_mov_b32_e32 v20, v2
	v_mov_b32_e32 v2, v3
	v_mov_b32_e32 v3, v23
	v_mov_b32_e32 v21, v22
	v_pk_mul_f32 v[2:3], v[2:3], v[2:3]
	ds_write_b128 v11, v[22:25] offset:1024
	v_pk_fma_f32 v[2:3], v[20:21], v[20:21], v[2:3]
	v_mov_b32_e32 v20, v4
	v_mov_b32_e32 v21, v24
	v_pk_fma_f32 v[2:3], v[20:21], v[20:21], v[2:3]
	v_mov_b32_e32 v4, v5
	v_mov_b32_e32 v5, v25
	v_pk_fma_f32 v[2:3], v[4:5], v[4:5], v[2:3]
	s_nop 0
	v_add_f32_e32 v0, v113, v2
	v_add_f32_e32 v0, v0, v3
	global_load_dwordx2 v[2:3], v[16:17], off offset:64
	s_waitcnt vmcnt(0) lgkmcnt(0)
	v_lshlrev_b32_e32 v20, 16, v2
	v_and_b32_e32 v21, 0xffff0000, v2
	v_add_co_u32_e32 v2, vcc, s35, v12
	v_lshlrev_b32_e32 v4, 16, v3
	v_and_b32_e32 v5, 0xffff0000, v3
	v_addc_co_u32_e32 v3, vcc, 0, v13, vcc
	global_load_ushort v22, v[2:3], off
	v_add_co_u32_e32 v2, vcc, s51, v12
	s_waitcnt vmcnt(0) lgkmcnt(0)
	v_lshlrev_b32_e32 v22, 16, v22
	v_addc_co_u32_e32 v3, vcc, 0, v13, vcc
	global_load_ushort v3, v[2:3], off
	v_mul_f32_e32 v2, 0xbfb8aa3b, v20
	v_exp_f32_e32 v2, v2
	s_waitcnt vmcnt(0) lgkmcnt(0)
	v_lshlrev_b32_e32 v23, 16, v3
	v_mul_f32_e32 v3, 0xbfb8aa3b, v21
	v_exp_f32_e32 v3, v3
	v_add_f32_e32 v2, 1.0, v2
	v_rcp_f32_e32 v2, v2
	v_pk_fma_f32 v[18:19], v[10:11], v[22:23], v[18:19] op_sel_hi:[0,1,1]
	v_add_f32_e32 v3, 1.0, v3
	v_rcp_f32_e32 v3, v3
	s_nop 0
	v_pk_mul_f32 v[2:3], v[2:3], v[20:21]
	s_nop 0
	v_pk_mul_f32 v[2:3], v[18:19], v[2:3]
	v_add_co_u32_e32 v18, vcc, s52, v12
	s_nop 1
	v_addc_co_u32_e32 v19, vcc, 0, v13, vcc
	global_load_ushort v20, v[18:19], off
	v_add_co_u32_e32 v18, vcc, s53, v12
	s_waitcnt vmcnt(0) lgkmcnt(0)
	v_lshlrev_b32_e32 v20, 16, v20
	v_addc_co_u32_e32 v19, vcc, 0, v13, vcc
	global_load_ushort v19, v[18:19], off
	v_mul_f32_e32 v18, 0xbfb8aa3b, v4
	v_exp_f32_e32 v18, v18
	s_waitcnt vmcnt(0) lgkmcnt(0)
	v_lshlrev_b32_e32 v21, 16, v19
	v_mul_f32_e32 v19, 0xbfb8aa3b, v5
	v_exp_f32_e32 v19, v19
	v_add_f32_e32 v18, 1.0, v18
	v_rcp_f32_e32 v18, v18
	v_pk_fma_f32 v[14:15], v[10:11], v[20:21], v[14:15] op_sel_hi:[0,1,1]
	v_add_f32_e32 v19, 1.0, v19
	v_rcp_f32_e32 v19, v19
	s_nop 0
	v_pk_mul_f32 v[4:5], v[18:19], v[4:5]
	s_nop 0
	v_pk_mul_f32 v[4:5], v[4:5], v[14:15]
	v_add_co_u32_e32 v18, vcc, s54, v12
	ds_write_b128 v11, v[2:5] offset:2048
	s_nop 0
	v_addc_co_u32_e32 v19, vcc, 0, v13, vcc
	global_load_ushort v20, v[18:19], off
	v_add_co_u32_e32 v18, vcc, s55, v12
	global_load_dwordx2 v[14:15], v[16:17], off offset:96
	s_nop 0
	v_addc_co_u32_e32 v19, vcc, 0, v13, vcc
	global_load_ushort v19, v[18:19], off
	s_waitcnt vmcnt(0) lgkmcnt(0)
	v_lshlrev_b32_e32 v20, 16, v20
	v_lshlrev_b32_e32 v16, 16, v14
	v_and_b32_e32 v17, 0xffff0000, v14
	v_mul_f32_e32 v18, 0xbfb8aa3b, v16
	v_lshlrev_b32_e32 v21, 16, v19
	v_mul_f32_e32 v19, 0xbfb8aa3b, v17
	v_exp_f32_e32 v18, v18
	v_exp_f32_e32 v19, v19
	v_pk_fma_f32 v[6:7], v[10:11], v[20:21], v[6:7] op_sel_hi:[0,1,1]
	v_lshlrev_b32_e32 v14, 16, v15
	v_add_f32_e32 v18, 1.0, v18
	v_add_f32_e32 v19, 1.0, v19
	v_rcp_f32_e32 v18, v18
	v_rcp_f32_e32 v19, v19
	v_and_b32_e32 v15, 0xffff0000, v15
	v_pk_mul_f32 v[16:17], v[18:19], v[16:17]
	s_nop 0
	v_pk_mul_f32 v[6:7], v[6:7], v[16:17]
	v_add_co_u32_e32 v16, vcc, s56, v12
	s_nop 1
	v_addc_co_u32_e32 v17, vcc, 0, v13, vcc
	v_add_co_u32_e32 v12, vcc, s57, v12
	global_load_ushort v16, v[16:17], off
	s_nop 0
	v_addc_co_u32_e32 v13, vcc, 0, v13, vcc
	global_load_ushort v13, v[12:13], off
	v_mul_f32_e32 v12, 0xbfb8aa3b, v14
	v_exp_f32_e32 v12, v12
	s_waitcnt vmcnt(0) lgkmcnt(0)
	v_lshlrev_b32_e32 v16, 16, v16
	v_add_f32_e32 v12, 1.0, v12
	v_rcp_f32_e32 v12, v12
	v_lshlrev_b32_e32 v17, 16, v13
	v_pk_fma_f32 v[8:9], v[10:11], v[16:17], v[8:9] op_sel_hi:[0,1,1]
	v_mul_f32_e32 v10, 0xbfb8aa3b, v15
	v_exp_f32_e32 v10, v10
	s_nop 0
	v_add_f32_e32 v10, 1.0, v10
	v_rcp_f32_e32 v13, v10
	s_nop 0
	v_pk_mul_f32 v[12:13], v[12:13], v[14:15]
	s_nop 0
	v_pk_mul_f32 v[8:9], v[12:13], v[8:9]
	v_mov_b32_e32 v12, v2
	v_mov_b32_e32 v2, v3
	v_mov_b32_e32 v3, v7
	v_mov_b32_e32 v13, v6
	v_pk_mul_f32 v[2:3], v[2:3], v[2:3]
	ds_write_b128 v11, v[6:9] offset:3072
	v_pk_fma_f32 v[2:3], v[12:13], v[12:13], v[2:3]
	v_mov_b32_e32 v12, v4
	v_mov_b32_e32 v13, v8
	v_pk_fma_f32 v[2:3], v[12:13], v[12:13], v[2:3]
	v_mov_b32_e32 v4, v5
	v_mov_b32_e32 v5, v9
	v_pk_fma_f32 v[2:3], v[4:5], v[4:5], v[2:3]
	s_nop 0
	v_add_f32_e32 v0, v0, v2
	v_add_f32_e32 v113, v0, v3
	s_cbranch_scc1 .LBB0_879
.LBB0_845:
	s_lshl_b32 s1, s0, 7
	s_and_b32 s18, s1, 0xffffff00
	v_lshl_add_u64 v[2:3], v[70:71], 0, s[18:19]
	global_load_dwordx4 v[14:17], v[2:3], off offset:512
	global_load_dwordx4 v[10:13], v[2:3], off offset:576
	global_load_dwordx4 v[6:9], v[2:3], off offset:640
	s_nop 0
	global_load_dwordx4 v[2:5], v[2:3], off offset:704
	v_lshl_add_u32 v0, s0, 2, v108
	ds_read2_b32 v[88:89], v0 offset1:4
	s_lshl_b64 s[4:5], s[12:13], 1
	s_and_b32 s4, s4, 0xffffff00
	v_lshl_add_u64 v[54:55], v[84:85], 0, s[4:5]
	s_lshl_b32 s1, s0, 6
	v_mov_b64_e32 v[56:57], v[86:87]
	v_mov_b32_e32 v0, v111
	s_mov_b32 s4, 0
	v_mov_b32_e32 v30, 0
	v_mov_b32_e32 v31, v112
	v_mov_b32_e32 v32, v112
	v_mov_b32_e32 v33, v112
	v_mov_b32_e32 v26, 0
	v_mov_b32_e32 v27, v112
	v_mov_b32_e32 v28, v112
	v_mov_b32_e32 v29, v112
	v_mov_b32_e32 v22, 0
	v_mov_b32_e32 v23, v112
	v_mov_b32_e32 v24, v112
	v_mov_b32_e32 v25, v112
	v_mov_b32_e32 v18, 0
	v_mov_b32_e32 v19, v112
	v_mov_b32_e32 v20, v112
	v_mov_b32_e32 v21, v112
	s_branch .LBB0_847

.LBB0_847:
	v_lshl_add_u64 v[38:39], s[6:7], 0, v[54:55]
	v_add_co_u32_e32 v40, vcc, s73, v38
	v_lshl_add_u64 v[42:43], s[6:7], 0, v[56:57]
	s_nop 0
	v_addc_co_u32_e32 v41, vcc, 0, v39, vcc
	global_load_dwordx4 v[34:37], v[40:41], off
	global_load_dwordx4 v[50:53], v[40:41], off offset:64
	global_load_dwordx4 v[90:93], v[40:41], off offset:128
	v_add_co_u32_e32 v94, vcc, s66, v42
	global_load_dwordx4 v[104:107], v[40:41], off offset:192
	s_nop 0
	v_addc_co_u32_e32 v95, vcc, 0, v43, vcc
	v_add_co_u32_e32 v98, vcc, s67, v42
	v_mov_b32_e32 v116, 0xff800000
	s_nop 0
	v_addc_co_u32_e32 v99, vcc, 0, v43, vcc
	v_add_co_u32_e32 v102, vcc, s68, v42
	s_waitcnt vmcnt(0) lgkmcnt(0)
	v_mfma_f32_16x16x32_bf16 v[58:61], v[34:37], v[14:17], 0
	v_addc_co_u32_e32 v103, vcc, 0, v43, vcc
	v_add_co_u32_e32 v114, vcc, s69, v42
	v_mfma_f32_16x16x32_bf16 v[50:53], v[50:53], v[10:13], v[58:61]
	s_nop 0
	v_addc_co_u32_e32 v115, vcc, 0, v43, vcc
	v_add_co_u32_e32 v46, vcc, s74, v38
	v_mfma_f32_16x16x32_bf16 v[50:53], v[90:93], v[6:9], v[50:53]
	s_nop 0
	v_addc_co_u32_e32 v47, vcc, 0, v39, vcc
	global_load_dwordx4 v[34:37], v[46:47], off
	global_load_dwordx4 v[38:41], v[46:47], off offset:64
	global_load_dwordx4 v[42:45], v[46:47], off offset:128
	s_nop 0
	global_load_dwordx4 v[46:49], v[46:47], off offset:192
	s_nop 0
	global_load_dwordx2 v[100:101], v[94:95], off
	global_load_dwordx2 v[96:97], v[98:99], off
	global_load_dwordx2 v[58:59], v[98:99], off offset:32
	global_load_dwordx2 v[60:61], v[94:95], off offset:32
	s_nop 0
	global_load_dwordx2 v[98:99], v[102:103], off
	global_load_dwordx2 v[94:95], v[114:115], off
	global_load_dwordx2 v[90:91], v[114:115], off offset:32
	global_load_dwordx2 v[92:93], v[102:103], off offset:32
	v_mfma_f32_16x16x32_bf16 v[50:53], v[104:107], v[2:5], v[50:53]
	v_subrev_u32_e32 v102, 19, v0
	v_cmp_le_i32_e32 vcc, v102, v68
	v_mov_b32_e32 v115, 0xff800000
	v_add_u32_e32 v114, s4, v110
	s_and_saveexec_b64 s[14:15], vcc
	s_cbranch_execz .LBB0_849
	v_add_u32_e32 v103, 0x20000, v114
	ds_read_b32 v103, v103
	s_waitcnt lgkmcnt(0)
	v_sub_f32_e32 v103, v88, v103
	v_mul_f32_e32 v116, 0x3fb8aa3b, v103

.LBB0_879:
	v_mov_b32_e32 v0, s64
	v_mov_b32_e32 v2, s65
	v_cmp_lt_i32_e32 vcc, v222, v220
	v_readfirstlane_b32 s0, v0
	v_readfirstlane_b32 s1, v2
	v_cndmask_b32_e32 v0, v219, v222, vcc
	v_mov_b32_e32 v2, s0
	v_mov_b32_e32 v3, s1
	global_load_dwordx2 v[6:7], v[2:3], off offset:176
	v_lshlrev_b32_e32 v0, 2, v0
	ds_bpermute_b32 v0, v0, v113
	v_cmp_lt_i32_e32 vcc, v221, v220
	s_mov_b32 s18, 0x800000
	v_readlane_b32 s4, v255, 5
	v_cndmask_b32_e32 v2, v219, v221, vcc
	v_lshlrev_b32_e32 v2, 2, v2
	s_waitcnt lgkmcnt(0)
	v_add_f32_e32 v0, v113, v0
	ds_bpermute_b32 v2, v2, v0
	v_readlane_b32 s5, v255, 6
	s_waitcnt lgkmcnt(0)
	v_add_f32_e32 v0, v0, v2
	v_fmamk_f32 v0, v0, 0x3b800000, v162
	v_mul_f32_e32 v2, 0x4b800000, v0
	v_cmp_gt_f32_e32 vcc, s18, v0
	s_nop 1
	v_cndmask_b32_e32 v0, v0, v2, vcc
	v_rsq_f32_e32 v0, v0
	v_lshlrev_b64 v[2:3], 11, v[66:67]
	v_or_b32_e32 v2, v2, v64
	v_lshl_add_u64 v[2:3], s[6:7], 0, v[2:3]
	v_mul_f32_e32 v4, 0x45800000, v0
	v_cndmask_b32_e32 v4, v0, v4, vcc
	v_mov_b32_e32 v5, v4
	s_mov_b64 s[6:7], 0
	s_waitcnt vmcnt(0)
	v_mov_b32_e32 v0, v6
	s_nop 0
	v_readfirstlane_b32 s0, v0
	v_readfirstlane_b32 s1, v7
	s_add_u32 s0, s0, s4
	s_addc_u32 s1, s1, s5
	v_lshl_add_u64 v[6:7], s[0:1], 0, v[62:63]
	s_mov_b64 s[0:1], 0x100
.LBB0_880:
	global_load_dwordx4 v[8:11], v[6:7], off
	ds_read_b128 v[12:15], v65
	v_lshl_add_u64 v[16:17], v[2:3], 0, s[6:7]
	v_add_co_u32_e32 v16, vcc, s34, v16
	s_add_u32 s6, s6, 0x80
	s_waitcnt lgkmcnt(0)
	v_pk_mul_f32 v[12:13], v[4:5], v[12:13]
	v_pk_mul_f32 v[14:15], v[4:5], v[14:15]
	v_addc_co_u32_e32 v17, vcc, 0, v17, vcc
	s_addc_u32 s7, s7, 0
	s_cmpk_lg_i32 s6, 0x200
	s_waitcnt vmcnt(0)
	v_pk_mul_f32 v[8:9], v[8:9], v[12:13]
	v_pk_mul_f32 v[10:11], v[14:15], v[10:11]
	v_cvt_pk_bf16_f32 v8, v8, v9
	v_cvt_pk_bf16_f32 v9, v10, v11
	global_store_dwordx2 v[16:17], v[8:9], off offset:1536
	global_load_dwordx4 v[8:11], v[6:7], off offset:64
	ds_read_b128 v[12:15], v65 offset:1024
	s_waitcnt lgkmcnt(0)
	v_pk_mul_f32 v[12:13], v[4:5], v[12:13]
	v_pk_mul_f32 v[14:15], v[4:5], v[14:15]
	s_waitcnt vmcnt(0)
	v_pk_mul_f32 v[8:9], v[8:9], v[12:13]
	v_pk_mul_f32 v[10:11], v[14:15], v[10:11]
	v_cvt_pk_bf16_f32 v8, v8, v9
	v_cvt_pk_bf16_f32 v9, v10, v11
	global_store_dwordx2 v[16:17], v[8:9], off offset:1568
	global_load_dwordx4 v[8:11], v[6:7], off offset:128
	ds_read_b128 v[12:15], v65 offset:2048
	s_waitcnt lgkmcnt(0)
	v_pk_mul_f32 v[12:13], v[4:5], v[12:13]
	v_pk_mul_f32 v[14:15], v[4:5], v[14:15]
	s_waitcnt vmcnt(0)
	v_pk_mul_f32 v[8:9], v[8:9], v[12:13]
	v_pk_mul_f32 v[10:11], v[14:15], v[10:11]
	v_cvt_pk_bf16_f32 v8, v8, v9
	v_cvt_pk_bf16_f32 v9, v10, v11
	global_store_dwordx2 v[16:17], v[8:9], off offset:1600
	global_load_dwordx4 v[8:11], v[6:7], off offset:192
	ds_read_b128 v[12:15], v65 offset:3072
	v_add_u32_e32 v65, 0x8000, v65
	v_lshl_add_u64 v[6:7], v[6:7], 0, s[0:1]
	s_waitcnt lgkmcnt(0)
	v_pk_mul_f32 v[12:13], v[4:5], v[12:13]
	v_pk_mul_f32 v[14:15], v[4:5], v[14:15]
	s_waitcnt vmcnt(0)
	v_pk_mul_f32 v[8:9], v[8:9], v[12:13]
	v_pk_mul_f32 v[10:11], v[14:15], v[10:11]
	v_cvt_pk_bf16_f32 v8, v8, v9
	v_cvt_pk_bf16_f32 v9, v10, v11
	global_store_dwordx2 v[16:17], v[8:9], off offset:1632
	s_cbranch_scc1 .LBB0_880
	s_waitcnt lgkmcnt(0)
	s_barrier
	s_branch .LBB0_823

.LBB0_883:
	s_andn2_b64 vcc, exec, s[6:7]
	s_cbranch_vccnz .LBB0_979
	s_cmpk_gt_i32 s40, 0x8f
	s_cbranch_scc0 .LBB0_893
	v_mov_b32_e32 v2, s64
	v_mov_b32_e32 v3, s65
	v_mov_b32_e32 v4, s64
	v_readfirstlane_b32 s0, v2
	v_readfirstlane_b32 s1, v3
	v_mov_b32_e32 v5, s65
	v_mov_b32_e32 v2, s0
	v_mov_b32_e32 v3, s1
	global_load_dwordx2 v[2:3], v[2:3], off offset:248
	s_waitcnt vmcnt(0) lgkmcnt(0)
	v_mov_b32_e32 v0, s64
	v_readfirstlane_b32 s0, v4
	v_readfirstlane_b32 s1, v5
	v_mov_b32_e32 v6, s65
	v_mov_b32_e32 v4, s0
	v_mov_b32_e32 v5, s1
	global_load_dwordx2 v[4:5], v[4:5], off offset:248
	v_mov_b32_e32 v32, v247
	s_mov_b32 s15, s19
	s_mov_b32 s9, s19
	v_mov_b32_e32 v31, v1
	v_cmp_lt_i32_e32 vcc, v222, v220
	v_mov_b32_e32 v68, 0xf149f2ca
	v_mov_b32_e32 v64, 0
	s_waitcnt vmcnt(0) lgkmcnt(0)
	v_mov_b32_e32 v8, v5
	s_nop 0
	v_readfirstlane_b32 s0, v0
	v_readfirstlane_b32 s1, v6
	v_readfirstlane_b32 s20, v4
	v_mov_b32_e32 v6, s0
	v_readfirstlane_b32 s0, v2
	v_mov_b32_e32 v7, s1
	v_readfirstlane_b32 s1, v3
	s_add_u32 s12, s0, 0x9f00000
	global_load_dwordx2 v[50:51], v[6:7], off offset:248
	s_addc_u32 s13, s1, 0
	s_lshl_b32 s0, s40, 7
	s_lshr_b32 s18, s40, 6
	s_lshl_b32 s1, s40, 1
	s_and_b32 s0, s0, 0x780
	s_waitcnt vmcnt(0) lgkmcnt(0)
	s_lshl_b64 s[6:7], s[18:19], 11
	v_ashrrev_i32_e32 v0, 2, v32
	v_and_b32_e32 v33, 15, v32
	s_and_b32 s4, s1, 64
	s_lshl_b32 s1, s18, 8
	v_readfirstlane_b32 s21, v8
	v_lshrrev_b32_e32 v4, 1, v32
	v_ashrrev_i32_e32 v54, 3, v32
	v_and_b32_e32 v8, -16, v0
	v_or_b32_e32 v0, s0, v33
	v_mov_b32_e32 v5, s7
	s_add_i32 s18, s1, 0x4000
	v_and_b32_e32 v52, 24, v4
	v_ashrrev_i32_e32 v55, 31, v54
	v_add_u32_e32 v12, s4, v54
	v_ashrrev_i32_e32 v9, 31, v8
	v_or_b32_e32 v4, s6, v0
	v_mov_b64_e32 v[2:3], s[12:13]
	v_mov_b32_e32 v6, s20
	v_mov_b32_e32 v7, s21
	v_lshl_add_u64 v[10:11], s[18:19], 0, v[54:55]
	v_add_u32_e32 v12, 0x180, v12
	v_lshl_add_u64 v[56:57], v[4:5], 0, v[8:9]
	s_bfe_u32 s5, s40, 0x20004
	v_lshlrev_b32_e32 v36, 3, v32
	v_mad_u64_u32 v[4:5], s[20:21], v10, s2, v[2:3]
	v_mad_i64_i32 v[6:7], s[20:21], v12, s33, v[6:7]
	v_mad_u64_u32 v[2:3], s[20:21], v56, s2, v[2:3]
	s_lshl_b32 s14, s5, 7
	s_lshl_b32 s8, s4, 1
	v_and_b32_e32 v53, 56, v36
	v_mad_i32_i24 v5, v11, s2, v5
	s_mov_b64 s[20:21], 0x17700000
	v_mad_i32_i24 v3, v57, s2, v3
	v_lshlrev_b32_e32 v0, 1, v52
	v_lshlrev_b32_e32 v30, 1, v53
	v_lshl_add_u64 v[34:35], v[6:7], 0, s[20:21]
	v_lshl_add_u64 v[4:5], v[4:5], 0, s[8:9]
	v_lshl_add_u64 v[2:3], v[2:3], 0, s[14:15]
	v_lshl_add_u64 v[6:7], s[18:19], 1, v[34:35]
	v_lshl_add_u64 v[4:5], v[4:5], 0, v[30:31]
	v_lshl_add_u64 v[2:3], v[2:3], 0, v[0:1]
	v_lshl_add_u64 v[6:7], v[6:7], 0, v[30:31]
	global_load_dwordx4 v[22:25], v[4:5], off offset:2304
	global_load_dwordx4 v[26:29], v[6:7], off
	global_load_dwordx4 v[14:17], v[2:3], off offset:1792
	global_load_dwordx4 v[18:21], v[2:3], off offset:1856
	v_lshlrev_b32_e32 v37, 4, v32
	v_lshlrev_b32_e32 v32, 1, v32
	s_movk_i32 s9, 0x90
	v_cndmask_b32_e32 v6, v219, v222, vcc
	v_cmp_lt_i32_e32 vcc, v221, v220
	v_and_b32_e32 v36, 32, v36
	v_and_b32_e32 v37, 16, v37
	v_and_b32_e32 v32, 4, v32
	v_mul_lo_u32 v38, v54, s9
	v_cndmask_b32_e32 v7, v219, v221, vcc
	v_mov_b32_e32 v4, v1
	v_mov_b32_e32 v5, v1
	v_mul_u32_u24_e32 v65, 0x90, v33
	v_or3_b32 v66, v36, v37, v32
	v_add_u32_e32 v67, 16, v38
	v_lshl_add_u64 v[32:33], s[12:13], 0, v[30:31]
	s_or_b32 s18, s8, 0x900
	v_mov_b32_e32 v2, v1
	v_mov_b32_e32 v3, v1
	v_lshlrev_b32_e32 v63, 2, v6
	v_lshlrev_b32_e32 v62, 2, v7
	v_mov_b64_e32 v[8:9], v[4:5]
	v_mov_b64_e32 v[12:13], v[4:5]
	v_add_u32_e32 v36, v67, v30
	v_lshl_add_u64 v[58:59], v[34:35], 0, v[30:31]
	v_lshl_add_u64 v[60:61], v[32:33], 0, s[18:19]
	v_mov_b64_e32 v[32:33], v[4:5]
	s_mov_b32 s4, 0
	s_movk_i32 s14, 0x4040
	v_mov_b64_e32 v[6:7], v[2:3]
	v_mov_b64_e32 v[10:11], v[2:3]
	s_lshl_b32 s5, s5, 6
	v_lshl_add_u32 v37, v66, 1, v67
	v_mov_b64_e32 v[30:31], v[2:3]
	v_add_u32_e32 v37, 0x2000, v37
	s_waitcnt vmcnt(0) lgkmcnt(0)
	ds_write_b128 v36, v[22:25]
	ds_write2_b64 v37, v[26:27], v[28:29] offset0:128 offset1:130
	s_waitcnt lgkmcnt(0)
	s_barrier
	s_branch .LBB0_887

.LBB0_887:
	s_cmp_lg_u32 s4, 35
	s_cselect_b64 s[8:9], -1, 0
	s_cmp_eq_u32 s4, 35
	s_cbranch_scc1 .LBB0_889
	s_cmp_lt_u32 s4, 3
	s_cselect_b64 s[12:13], -1, 0
	s_add_i32 s15, s14, 0xffffbf00
	s_and_b64 s[12:13], s[12:13], exec
	s_cselect_b32 s12, s14, s15
	s_cselect_b32 s15, s1, s6
	s_cselect_b32 s13, 0, s7
	s_add_u32 s12, s15, s12
	s_addc_u32 s13, s13, 0
	s_waitcnt vmcnt(0)
	v_lshl_add_u64 v[22:23], s[12:13], 0, v[54:55]
	v_mad_u64_u32 v[24:25], s[20:21], v22, s2, v[60:61]
	v_mad_i32_i24 v25, v23, s2, v25
	v_lshl_add_u64 v[26:27], s[12:13], 1, v[58:59]
	global_load_dwordx4 v[22:25], v[24:25], off
	s_nop 0
	global_load_dwordx4 v[26:29], v[26:27], off

.LBB0_894:
	ds_bpermute_b32 v0, v63, v64
	s_lshl_b32 s18, s5, 1
	v_readfirstlane_b32 s6, v50
	v_readfirstlane_b32 s7, v51
	v_lshlrev_b64 v[14:15], 11, v[56:57]
	s_waitcnt lgkmcnt(0)
	v_add_f32_e32 v0, v64, v0
	ds_bpermute_b32 v16, v62, v0
	v_lshl_add_u64 v[14:15], s[6:7], 0, v[14:15]
	v_mov_b32_e32 v53, v1
	v_lshl_add_u64 v[14:15], v[14:15], 0, s[18:19]
	v_lshl_add_u64 v[14:15], v[14:15], 0, v[52:53]
	s_waitcnt lgkmcnt(0)
	v_add_f32_e32 v0, v0, v16
	v_div_scale_f32 v16, s[4:5], v0, v0, 1.0
	v_rcp_f32_e32 v17, v16
	v_div_scale_f32 v18, vcc, 1.0, v0, 1.0
	s_mov_b64 s[4:5], 0x1e300400
	v_fma_f32 v19, -v16, v17, 1.0
	v_fmac_f32_e32 v17, v19, v17
	v_mul_f32_e32 v19, v18, v17
	v_fma_f32 v20, -v16, v19, v18
	v_fmac_f32_e32 v19, v20, v17
	v_fma_f32 v16, -v16, v19, v18
	v_div_fmas_f32 v16, v16, v17, v19
	v_div_fixup_f32 v0, v16, v0, 1.0
	v_pk_mul_f32 v[2:3], v[2:3], v[0:1] op_sel_hi:[1,0]
	v_pk_mul_f32 v[4:5], v[4:5], v[0:1] op_sel_hi:[1,0]
	v_lshl_add_u64 v[16:17], v[14:15], 0, s[4:5]
	v_pk_mul_f32 v[18:19], v[30:31], v[0:1] op_sel_hi:[1,0]
	v_pk_mul_f32 v[20:21], v[32:33], v[0:1] op_sel_hi:[1,0]
	v_add_co_u32_e32 v14, vcc, s34, v14
	v_pk_mul_f32 v[10:11], v[10:11], v[0:1] op_sel_hi:[1,0]
	v_pk_mul_f32 v[12:13], v[12:13], v[0:1] op_sel_hi:[1,0]
	v_pk_mul_f32 v[6:7], v[6:7], v[0:1] op_sel_hi:[1,0]
	v_pk_mul_f32 v[8:9], v[8:9], v[0:1] op_sel_hi:[1,0]
	v_cvt_pk_bf16_f32 v2, v2, v3
	v_cvt_pk_bf16_f32 v3, v4, v5
	v_cvt_pk_bf16_f32 v18, v18, v19
	v_cvt_pk_bf16_f32 v19, v20, v21
	v_addc_co_u32_e32 v15, vcc, 0, v15, vcc
	v_cvt_pk_bf16_f32 v10, v10, v11
	v_cvt_pk_bf16_f32 v11, v12, v13
	v_cvt_pk_bf16_f32 v6, v6, v7
	v_cvt_pk_bf16_f32 v7, v8, v9
	global_store_dwordx2 v[16:17], v[2:3], off offset:96
	v_mov_b32_e32 v2, s65
	v_mov_b32_e32 v3, s64
	global_store_dwordx2 v[14:15], v[18:19], off offset:1024
	global_store_dwordx2 v[16:17], v[10:11], off offset:32
	global_store_dwordx2 v[16:17], v[6:7], off offset:64
	v_mov_b32_e32 v4, s65
	v_readfirstlane_b32 s1, v3
	v_readfirstlane_b32 s4, v2
	v_mov_b32_e32 v5, s64
	v_mov_b32_e32 v2, s1
	v_mov_b32_e32 v3, s4
	global_load_dwordx2 v[2:3], v[2:3], off offset:248
	s_waitcnt vmcnt(0) lgkmcnt(0)
	v_mov_b32_e32 v0, s64
	v_readfirstlane_b32 s1, v5
	v_readfirstlane_b32 s4, v4
	v_mov_b32_e32 v6, s65
	v_mov_b32_e32 v4, s1
	v_mov_b32_e32 v5, s4
	global_load_dwordx2 v[4:5], v[4:5], off offset:248
	s_waitcnt vmcnt(0) lgkmcnt(0)
	v_mov_b32_e32 v34, v247
	v_readfirstlane_b32 s1, v0
	v_readfirstlane_b32 s4, v6
	v_readfirstlane_b32 s5, v3
	v_mov_b32_e32 v6, s1
	v_mov_b32_e32 v7, s4
	global_load_dwordx2 v[50:51], v[6:7], off offset:248
	s_add_i32 s1, s40, 0x70
	v_readfirstlane_b32 s4, v2
	s_add_u32 s12, s4, 0x9f00000
	s_addc_u32 s13, s5, 0
	s_bfe_u32 s5, s1, 0x20004
	s_lshr_b32 s18, s1, 6
	s_lshl_b32 s1, s1, 1
	s_lshl_b64 s[6:7], s[18:19], 11
	s_and_b32 s4, s1, 64
	s_lshl_b32 s1, s18, 8
	v_mov_b32_e32 v7, s7
	s_add_i32 s18, s1, 0x4000
	v_readfirstlane_b32 s20, v4
	v_readfirstlane_b32 s21, v5
	v_mov_b64_e32 v[2:3], s[12:13]
	v_mov_b32_e32 v4, s20
	v_mov_b32_e32 v5, s21
	s_mov_b32 s15, s19
	s_mov_b32 s9, s19
	s_lshl_b32 s14, s5, 7
	s_lshl_b32 s8, s4, 1
	v_mov_b32_e32 v31, v1
	v_mov_b32_e32 v68, 0xf149f2ca
	v_mov_b32_e32 v64, 0
	s_lshl_b32 s5, s5, 6
	s_waitcnt vmcnt(0) lgkmcnt(0)
	v_mov_b32_e32 v60, v50
	s_nop 0
	v_ashrrev_i32_e32 v0, 2, v34
	v_and_b32_e32 v35, 15, v34
	v_lshrrev_b32_e32 v6, 1, v34
	v_ashrrev_i32_e32 v52, 3, v34
	v_and_b32_e32 v8, -16, v0
	v_or_b32_e32 v0, s0, v35
	v_and_b32_e32 v50, 24, v6
	v_ashrrev_i32_e32 v53, 31, v52
	v_add_u32_e32 v12, s4, v52
	v_ashrrev_i32_e32 v9, 31, v8
	v_or_b32_e32 v6, s6, v0
	v_lshl_add_u64 v[10:11], s[18:19], 0, v[52:53]
	v_add_u32_e32 v12, 0x180, v12
	v_lshl_add_u64 v[54:55], v[6:7], 0, v[8:9]
	v_lshlrev_b32_e32 v36, 3, v34
	v_mad_u64_u32 v[6:7], s[20:21], v10, s2, v[2:3]
	v_mad_i64_i32 v[4:5], s[20:21], v12, s33, v[4:5]
	v_mad_u64_u32 v[2:3], s[20:21], v54, s2, v[2:3]
	v_and_b32_e32 v61, 56, v36
	v_mad_i32_i24 v7, v11, s2, v7
	s_mov_b64 s[20:21], 0x17700000
	v_mad_i32_i24 v3, v55, s2, v3
	v_lshlrev_b32_e32 v0, 1, v50
	v_lshlrev_b32_e32 v30, 1, v61
	v_lshl_add_u64 v[32:33], v[4:5], 0, s[20:21]
	v_lshl_add_u64 v[4:5], v[6:7], 0, s[8:9]
	v_lshl_add_u64 v[2:3], v[2:3], 0, s[14:15]
	v_lshl_add_u64 v[6:7], s[18:19], 1, v[32:33]
	v_lshl_add_u64 v[4:5], v[4:5], 0, v[30:31]
	v_lshl_add_u64 v[2:3], v[2:3], 0, v[0:1]
	v_lshl_add_u64 v[6:7], v[6:7], 0, v[30:31]
	global_load_dwordx4 v[22:25], v[4:5], off offset:2304
	global_load_dwordx4 v[26:29], v[6:7], off
	global_load_dwordx4 v[14:17], v[2:3], off offset:1792
	global_load_dwordx4 v[18:21], v[2:3], off offset:1856
	s_movk_i32 s9, 0x90
	v_lshlrev_b32_e32 v37, 4, v34
	v_lshlrev_b32_e32 v34, 1, v34
	v_mul_lo_u32 v38, v52, s9
	v_mov_b32_e32 v4, v1
	v_mov_b32_e32 v5, v1
	v_and_b32_e32 v36, 32, v36
	v_and_b32_e32 v37, 16, v37
	v_and_b32_e32 v34, 4, v34
	v_add_u32_e32 v67, 16, v38
	v_mov_b32_e32 v2, v1
	v_mov_b32_e32 v3, v1
	v_mov_b64_e32 v[8:9], v[4:5]
	v_mov_b64_e32 v[12:13], v[4:5]
	v_mul_u32_u24_e32 v65, 0x90, v35
	v_or3_b32 v66, v36, v37, v34
	v_add_u32_e32 v36, v67, v30
	v_lshl_add_u64 v[34:35], s[12:13], 0, v[30:31]
	v_lshl_add_u64 v[56:57], v[32:33], 0, v[30:31]
	s_or_b32 s18, s8, 0x900
	v_mov_b64_e32 v[32:33], v[4:5]
	s_mov_b32 s4, 0
	s_movk_i32 s14, 0x4040
	v_mov_b64_e32 v[6:7], v[2:3]
	v_mov_b64_e32 v[10:11], v[2:3]
	v_lshl_add_u32 v37, v66, 1, v67
	v_lshl_add_u64 v[58:59], v[34:35], 0, s[18:19]
	v_mov_b64_e32 v[30:31], v[2:3]
	v_add_u32_e32 v37, 0x2000, v37
	s_waitcnt vmcnt(0) lgkmcnt(0)
	ds_write_b128 v36, v[22:25]
	ds_write2_b64 v37, v[26:27], v[28:29] offset0:128 offset1:130
	s_waitcnt lgkmcnt(0)
	s_barrier
	s_branch .LBB0_896

.LBB0_896:
	s_cmp_lg_u32 s4, 35
	s_cselect_b64 s[8:9], -1, 0
	s_cmp_eq_u32 s4, 35
	s_cbranch_scc1 .LBB0_898
	s_cmp_lt_u32 s4, 3
	s_cselect_b64 s[12:13], -1, 0
	s_add_i32 s15, s14, 0xffffbf00
	s_and_b64 s[12:13], s[12:13], exec
	s_cselect_b32 s12, s14, s15
	s_cselect_b32 s15, s1, s6
	s_cselect_b32 s13, 0, s7
	s_add_u32 s12, s15, s12
	s_addc_u32 s13, s13, 0
	s_waitcnt vmcnt(0)
	v_lshl_add_u64 v[22:23], s[12:13], 0, v[52:53]
	v_mad_u64_u32 v[24:25], s[20:21], v22, s2, v[58:59]
	v_mad_i32_i24 v25, v23, s2, v25
	v_lshl_add_u64 v[26:27], s[12:13], 1, v[56:57]
	global_load_dwordx4 v[22:25], v[24:25], off
	s_nop 0
	global_load_dwordx4 v[26:29], v[26:27], off

.LBB0_902:
	ds_bpermute_b32 v0, v63, v64
	s_lshl_b32 s18, s5, 1
	v_readfirstlane_b32 s6, v60
	v_readfirstlane_b32 s7, v51
	v_lshlrev_b64 v[14:15], 11, v[54:55]
	s_waitcnt lgkmcnt(0)
	v_add_f32_e32 v0, v64, v0
	ds_bpermute_b32 v16, v62, v0
	v_lshl_add_u64 v[14:15], s[6:7], 0, v[14:15]
	v_mov_b32_e32 v51, v1
	v_lshl_add_u64 v[14:15], v[14:15], 0, s[18:19]
	v_lshl_add_u64 v[14:15], v[14:15], 0, v[50:51]
	s_waitcnt lgkmcnt(0)
	v_add_f32_e32 v0, v0, v16
	v_div_scale_f32 v16, s[4:5], v0, v0, 1.0
	v_rcp_f32_e32 v17, v16
	v_div_scale_f32 v18, vcc, 1.0, v0, 1.0
	s_mov_b64 s[4:5], 0x1e300400
	v_fma_f32 v19, -v16, v17, 1.0
	v_fmac_f32_e32 v17, v19, v17
	v_mul_f32_e32 v19, v18, v17
	v_fma_f32 v20, -v16, v19, v18
	v_fmac_f32_e32 v19, v20, v17
	v_fma_f32 v16, -v16, v19, v18
	v_div_fmas_f32 v16, v16, v17, v19
	v_div_fixup_f32 v0, v16, v0, 1.0
	v_pk_mul_f32 v[2:3], v[2:3], v[0:1] op_sel_hi:[1,0]
	v_pk_mul_f32 v[4:5], v[4:5], v[0:1] op_sel_hi:[1,0]
	v_lshl_add_u64 v[16:17], v[14:15], 0, s[4:5]
	v_pk_mul_f32 v[18:19], v[30:31], v[0:1] op_sel_hi:[1,0]
	v_pk_mul_f32 v[20:21], v[32:33], v[0:1] op_sel_hi:[1,0]
	v_add_co_u32_e32 v14, vcc, s34, v14
	v_pk_mul_f32 v[10:11], v[10:11], v[0:1] op_sel_hi:[1,0]
	v_pk_mul_f32 v[12:13], v[12:13], v[0:1] op_sel_hi:[1,0]
	v_pk_mul_f32 v[6:7], v[6:7], v[0:1] op_sel_hi:[1,0]
	v_pk_mul_f32 v[8:9], v[8:9], v[0:1] op_sel_hi:[1,0]
	v_cvt_pk_bf16_f32 v2, v2, v3
	v_cvt_pk_bf16_f32 v3, v4, v5
	v_cvt_pk_bf16_f32 v18, v18, v19
	v_cvt_pk_bf16_f32 v19, v20, v21
	v_addc_co_u32_e32 v15, vcc, 0, v15, vcc
	v_cvt_pk_bf16_f32 v10, v10, v11
	v_cvt_pk_bf16_f32 v11, v12, v13
	v_cvt_pk_bf16_f32 v6, v6, v7
	v_cvt_pk_bf16_f32 v7, v8, v9
	global_store_dwordx2 v[16:17], v[2:3], off offset:96
	v_mov_b32_e32 v2, s64
	v_mov_b32_e32 v3, s65
	global_store_dwordx2 v[14:15], v[18:19], off offset:1024
	global_store_dwordx2 v[16:17], v[10:11], off offset:32
	global_store_dwordx2 v[16:17], v[6:7], off offset:64
	v_mov_b32_e32 v4, s64
	v_readfirstlane_b32 s1, v2
	v_readfirstlane_b32 s4, v3
	v_mov_b32_e32 v5, s65
	v_mov_b32_e32 v2, s1
	v_mov_b32_e32 v3, s4
	global_load_dwordx2 v[2:3], v[2:3], off offset:248
	s_waitcnt vmcnt(0) lgkmcnt(0)
	v_mov_b32_e32 v0, s64
	v_readfirstlane_b32 s1, v4
	v_readfirstlane_b32 s4, v5
	v_mov_b32_e32 v6, s65
	v_mov_b32_e32 v4, s1
	v_mov_b32_e32 v5, s4
	global_load_dwordx2 v[4:5], v[4:5], off offset:248
	v_mov_b32_e32 v34, v247
	v_readfirstlane_b32 s5, v3
	s_mov_b32 s15, s19
	s_mov_b32 s9, s19
	v_mov_b32_e32 v53, v1
	v_mov_b32_e32 v31, v1
	v_mov_b32_e32 v68, 0xf149f2ca
	s_waitcnt vmcnt(0) lgkmcnt(0)
	v_mov_b32_e32 v8, v5
	s_nop 0
	v_readfirstlane_b32 s1, v0
	v_readfirstlane_b32 s4, v6
	v_readfirstlane_b32 s20, v4
	v_mov_b32_e32 v6, s1
	v_mov_b32_e32 v7, s4
	s_add_i32 s1, s40, 0xe0
	v_readfirstlane_b32 s4, v2
	global_load_dwordx2 v[50:51], v[6:7], off offset:248
	s_add_u32 s12, s4, 0x9f00000
	s_addc_u32 s13, s5, 0
	s_bfe_u32 s5, s1, 0x20004
	s_lshr_b32 s18, s1, 6
	s_lshl_b32 s1, s1, 1
	s_waitcnt vmcnt(0) lgkmcnt(0)
	s_lshl_b64 s[6:7], s[18:19], 11
	v_ashrrev_i32_e32 v0, 2, v34
	v_and_b32_e32 v35, 15, v34
	s_and_b32 s4, s1, 64
	s_lshl_b32 s1, s18, 8
	v_readfirstlane_b32 s21, v8
	v_lshrrev_b32_e32 v4, 1, v34
	v_ashrrev_i32_e32 v54, 3, v34
	v_and_b32_e32 v8, -16, v0
	v_or_b32_e32 v10, s0, v35
	v_mov_b32_e32 v5, s7
	s_add_i32 s18, s1, 0x4000
	v_and_b32_e32 v0, 24, v4
	v_ashrrev_i32_e32 v55, 31, v54
	v_add_u32_e32 v12, s4, v54
	v_ashrrev_i32_e32 v9, 31, v8
	v_or_b32_e32 v4, s6, v10
	v_mov_b64_e32 v[2:3], s[12:13]
	v_mov_b32_e32 v6, s20
	v_mov_b32_e32 v7, s21
	v_lshl_add_u64 v[10:11], s[18:19], 0, v[54:55]
	v_add_u32_e32 v12, 0x180, v12
	v_lshl_add_u64 v[56:57], v[4:5], 0, v[8:9]
	v_lshlrev_b32_e32 v36, 3, v34
	v_mad_u64_u32 v[4:5], s[20:21], v10, s2, v[2:3]
	v_mad_i64_i32 v[6:7], s[20:21], v12, s33, v[6:7]
	v_mad_u64_u32 v[2:3], s[20:21], v56, s2, v[2:3]
	s_lshl_b32 s14, s5, 7
	s_lshl_b32 s8, s4, 1
	v_and_b32_e32 v64, 56, v36
	v_mad_i32_i24 v5, v11, s2, v5
	s_mov_b64 s[20:21], 0x17700000
	v_mad_i32_i24 v3, v57, s2, v3
	v_lshlrev_b32_e32 v52, 1, v0
	v_lshlrev_b32_e32 v30, 1, v64
	v_lshl_add_u64 v[32:33], v[6:7], 0, s[20:21]
	v_lshl_add_u64 v[4:5], v[4:5], 0, s[8:9]
	v_lshl_add_u64 v[2:3], v[2:3], 0, s[14:15]
	v_lshl_add_u64 v[6:7], s[18:19], 1, v[32:33]
	v_lshl_add_u64 v[4:5], v[4:5], 0, v[30:31]
	v_lshl_add_u64 v[2:3], v[2:3], 0, v[52:53]
	v_lshl_add_u64 v[6:7], v[6:7], 0, v[30:31]
	global_load_dwordx4 v[22:25], v[4:5], off offset:2304
	global_load_dwordx4 v[26:29], v[6:7], off
	global_load_dwordx4 v[14:17], v[2:3], off offset:1792
	global_load_dwordx4 v[18:21], v[2:3], off offset:1856
	s_movk_i32 s9, 0x90
	v_lshlrev_b32_e32 v37, 4, v34
	v_lshlrev_b32_e32 v34, 1, v34
	v_mul_lo_u32 v38, v54, s9
	v_mov_b32_e32 v4, v1
	v_mov_b32_e32 v5, v1
	v_and_b32_e32 v36, 32, v36
	v_and_b32_e32 v37, 16, v37
	v_and_b32_e32 v34, 4, v34
	v_add_u32_e32 v67, 16, v38
	v_mov_b32_e32 v2, v1
	v_mov_b32_e32 v3, v1
	v_mov_b64_e32 v[8:9], v[4:5]
	v_mov_b64_e32 v[12:13], v[4:5]
	v_mul_u32_u24_e32 v65, 0x90, v35
	v_or3_b32 v66, v36, v37, v34
	v_add_u32_e32 v36, v67, v30
	v_lshl_add_u64 v[34:35], s[12:13], 0, v[30:31]
	v_lshl_add_u64 v[58:59], v[32:33], 0, v[30:31]
	s_or_b32 s18, s8, 0x900
	v_mov_b64_e32 v[32:33], v[4:5]
	s_mov_b32 s4, 0
	v_mov_b32_e32 v53, 0
	s_movk_i32 s14, 0x4040
	v_mov_b64_e32 v[6:7], v[2:3]
	v_mov_b64_e32 v[10:11], v[2:3]
	s_lshl_b32 s5, s5, 6
	v_lshl_add_u32 v37, v66, 1, v67
	v_lshl_add_u64 v[60:61], v[34:35], 0, s[18:19]
	v_mov_b64_e32 v[30:31], v[2:3]
	v_add_u32_e32 v37, 0x2000, v37
	s_waitcnt vmcnt(0) lgkmcnt(0)
	ds_write_b128 v36, v[22:25]
	ds_write2_b64 v37, v[26:27], v[28:29] offset0:128 offset1:130
	s_waitcnt lgkmcnt(0)
	s_barrier
	s_branch .LBB0_904

.LBB0_910:
	ds_bpermute_b32 v14, v63, v53
	s_lshl_b32 s18, s5, 1
	v_readfirstlane_b32 s6, v50
	v_readfirstlane_b32 s7, v51
	s_cmpk_gt_i32 s40, 0xaf
	s_waitcnt lgkmcnt(0)
	v_add_f32_e32 v16, v53, v14
	ds_bpermute_b32 v17, v62, v16
	v_lshlrev_b64 v[14:15], 11, v[56:57]
	v_lshl_add_u64 v[14:15], s[6:7], 0, v[14:15]
	v_lshl_add_u64 v[14:15], v[14:15], 0, s[18:19]
	v_lshl_add_u64 v[14:15], v[14:15], 0, v[0:1]
	s_waitcnt lgkmcnt(0)
	v_add_f32_e32 v16, v16, v17
	v_div_scale_f32 v17, s[4:5], v16, v16, 1.0
	v_rcp_f32_e32 v18, v17
	v_div_scale_f32 v0, vcc, 1.0, v16, 1.0
	s_mov_b64 s[4:5], 0x1e300400
	v_fma_f32 v19, -v17, v18, 1.0
	v_fmac_f32_e32 v18, v19, v18
	v_mul_f32_e32 v19, v0, v18
	v_fma_f32 v20, -v17, v19, v0
	v_fmac_f32_e32 v19, v20, v18
	v_fma_f32 v0, -v17, v19, v0
	v_div_fmas_f32 v0, v0, v18, v19
	v_div_fixup_f32 v0, v0, v16, 1.0
	v_lshl_add_u64 v[16:17], v[14:15], 0, s[4:5]
	v_pk_mul_f32 v[18:19], v[30:31], v[0:1] op_sel_hi:[1,0]
	v_pk_mul_f32 v[20:21], v[32:33], v[0:1] op_sel_hi:[1,0]
	v_add_co_u32_e32 v14, vcc, s34, v14
	v_pk_mul_f32 v[10:11], v[10:11], v[0:1] op_sel_hi:[1,0]
	v_pk_mul_f32 v[12:13], v[12:13], v[0:1] op_sel_hi:[1,0]
	v_pk_mul_f32 v[6:7], v[6:7], v[0:1] op_sel_hi:[1,0]
	v_pk_mul_f32 v[8:9], v[8:9], v[0:1] op_sel_hi:[1,0]
	v_pk_mul_f32 v[2:3], v[2:3], v[0:1] op_sel_hi:[1,0]
	v_pk_mul_f32 v[4:5], v[4:5], v[0:1] op_sel_hi:[1,0]
	v_cvt_pk_bf16_f32 v18, v18, v19
	v_cvt_pk_bf16_f32 v19, v20, v21
	v_addc_co_u32_e32 v15, vcc, 0, v15, vcc
	v_cvt_pk_bf16_f32 v10, v10, v11
	v_cvt_pk_bf16_f32 v11, v12, v13
	v_cvt_pk_bf16_f32 v6, v6, v7
	v_cvt_pk_bf16_f32 v7, v8, v9
	v_cvt_pk_bf16_f32 v2, v2, v3
	v_cvt_pk_bf16_f32 v3, v4, v5
	s_mov_b64 s[6:7], 0
	s_mov_b64 s[8:9], 0
	global_store_dwordx2 v[14:15], v[18:19], off offset:1024
	global_store_dwordx2 v[16:17], v[10:11], off offset:32
	global_store_dwordx2 v[16:17], v[6:7], off offset:64
	global_store_dwordx2 v[16:17], v[2:3], off offset:96
	s_cbranch_scc1 .LBB0_920
	v_mov_b32_e32 v2, s65
	v_mov_b32_e32 v3, s64
	v_mov_b32_e32 v4, s65
	v_readfirstlane_b32 s1, v3
	v_readfirstlane_b32 s4, v2
	v_mov_b32_e32 v5, s64
	v_mov_b32_e32 v2, s1
	v_mov_b32_e32 v3, s4
	global_load_dwordx2 v[2:3], v[2:3], off offset:248
	s_waitcnt vmcnt(0) lgkmcnt(0)
	v_mov_b32_e32 v0, s64
	v_readfirstlane_b32 s1, v5
	v_readfirstlane_b32 s4, v4
	v_mov_b32_e32 v6, s65
	v_mov_b32_e32 v4, s1
	v_mov_b32_e32 v5, s4
	global_load_dwordx2 v[4:5], v[4:5], off offset:248
	s_waitcnt vmcnt(0) lgkmcnt(0)
	v_readfirstlane_b32 s8, v2
	v_readfirstlane_b32 s1, v0
	v_readfirstlane_b32 s4, v6
	v_mov_b32_e32 v60, v247
	v_mov_b32_e32 v6, s1
	v_mov_b32_e32 v7, s4
	global_load_dwordx2 v[50:51], v[6:7], off offset:248
	v_readfirstlane_b32 s9, v3
	s_add_u32 s4, s8, 0x9f00000
	s_addc_u32 s5, s9, 0
	s_waitcnt vmcnt(0) lgkmcnt(0)
	v_mov_b64_e32 v[2:3], s[4:5]
	v_ashrrev_i32_e32 v0, 2, v60
	v_and_b32_e32 v14, 15, v60
	v_lshlrev_b32_e32 v15, 3, v60
	v_readfirstlane_b32 s4, v4
	v_readfirstlane_b32 s5, v5
	v_lshrrev_b32_e32 v7, 1, v60
	v_ashrrev_i32_e32 v54, 3, v60
	v_and_b32_e32 v6, -16, v0
	v_or_b32_e32 v0, s0, v14
	v_and_b32_e32 v61, 56, v15
	v_mov_b32_e32 v11, v1
	v_mov_b32_e32 v4, s4
	v_mov_b32_e32 v5, s5
	v_and_b32_e32 v12, 24, v7
	v_mad_i64_i32 v[8:9], s[4:5], v54, s2, v[2:3]
	v_add_u32_e32 v13, 0x1c0, v54
	v_ashrrev_i32_e32 v7, 31, v6
	v_or_b32_e32 v0, 0x3800, v0
	v_lshlrev_b32_e32 v10, 1, v61
	s_mov_b32 s12, 0xd500000
	s_lshl_b32 s1, s40, 2
	v_mad_i64_i32 v[4:5], s[4:5], v13, s33, v[4:5]
	v_lshl_add_u64 v[52:53], v[0:1], 0, v[6:7]
	v_lshl_add_u64 v[6:7], v[8:9], 0, v[10:11]
	s_add_i32 s1, s1, 64
	v_lshlrev_b32_e32 v0, 1, v12
	v_lshl_add_u64 v[12:13], v[4:5], 0, v[10:11]
	v_add_co_u32_e32 v4, vcc, s12, v6
	s_mov_b32 s13, 0x17708000
	s_and_b32 s1, s1, 0xc0
	v_addc_co_u32_e32 v5, vcc, 0, v7, vcc
	s_lshl_b32 s18, s1, 1
	v_add_co_u32_e32 v6, vcc, s13, v12
	v_mad_i64_i32 v[2:3], s[4:5], v52, s2, v[2:3]
	s_nop 0
	v_addc_co_u32_e32 v7, vcc, 0, v13, vcc
	global_load_dwordx4 v[26:29], v[4:5], off offset:2432
	global_load_dwordx4 v[30:33], v[6:7], off offset:3584
	v_lshl_add_u64 v[2:3], v[2:3], 0, s[18:19]
	v_lshl_add_u64 v[2:3], v[2:3], 0, v[0:1]
	global_load_dwordx4 v[18:21], v[2:3], off offset:1792
	global_load_dwordx4 v[22:25], v[2:3], off offset:1856
	v_lshlrev_b32_e32 v16, 4, v60
	v_lshlrev_b32_e32 v17, 1, v60
	s_movk_i32 s5, 0x90
	v_and_b32_e32 v15, 32, v15
	v_and_b32_e32 v16, 16, v16
	v_and_b32_e32 v17, 4, v17
	v_mul_lo_u32 v34, v54, s5
	v_or3_b32 v66, v15, v16, v17
	v_add_u32_e32 v67, 16, v34
	v_lshl_add_u32 v15, v66, 1, v67
	v_mov_b32_e32 v4, v1
	v_mov_b32_e32 v5, v1
	s_mov_b64 s[12:13], 0x9f00980
	v_mul_u32_u24_e32 v65, 0x90, v14
	v_add_u32_e32 v14, v67, v10
	v_lshl_add_u64 v[10:11], s[8:9], 0, v[10:11]
	v_add_u32_e32 v15, 0x2000, v15
	s_mov_b64 s[8:9], 0x17700000
	v_mov_b32_e32 v2, v1
	v_mov_b32_e32 v3, v1
	v_mov_b64_e32 v[8:9], v[4:5]
	v_lshl_add_u64 v[56:57], v[10:11], 0, s[12:13]
	v_lshl_add_u64 v[58:59], v[12:13], 0, s[8:9]
	s_waitcnt vmcnt(0) lgkmcnt(0)
	ds_write_b128 v14, v[26:29]
	ds_write2_b64 v15, v[30:31], v[32:33] offset0:128 offset1:130
	v_mov_b64_e32 v[12:13], v[4:5]
	v_mov_b64_e32 v[16:17], v[4:5]
	s_mov_b32 s0, 0
	v_mov_b32_e32 v68, 0xf149f2ca
	v_mov_b32_e32 v64, 0
	s_movk_i32 s4, 0x4040
	v_mov_b64_e32 v[6:7], v[2:3]
	v_ashrrev_i32_e32 v55, 31, v54
	v_mov_b64_e32 v[10:11], v[2:3]
	v_mov_b64_e32 v[14:15], v[2:3]
	s_waitcnt lgkmcnt(0)
	s_barrier
	s_branch .LBB0_913

.LBB0_913:
	s_cmp_lg_u32 s0, 35
	s_cselect_b64 s[8:9], -1, 0
	s_cmp_eq_u32 s0, 35
	s_cbranch_scc1 .LBB0_915
	s_add_i32 s5, s4, 0xffffbf00
	s_cmp_lt_u32 s0, 3
	s_movk_i32 s12, 0x3800
	s_cselect_b32 s5, s4, s5
	s_cselect_b32 s12, 0x700, s12
	s_add_i32 s18, s12, s5
	s_waitcnt vmcnt(0)
	v_lshl_add_u64 v[26:27], s[18:19], 0, v[54:55]
	v_mad_u64_u32 v[28:29], s[12:13], v26, s2, v[56:57]
	v_mad_i32_i24 v29, v27, s2, v29
	v_lshl_add_u64 v[30:31], s[18:19], 1, v[58:59]
	global_load_dwordx4 v[26:29], v[28:29], off
	s_nop 0
	global_load_dwordx4 v[30:33], v[30:31], off

.LBB0_921:
	s_mul_hi_i32 s0, s40, 0x38e38e39
	s_lshr_b32 s1, s0, 31
	s_ashr_i32 s0, s0, 2
	s_add_i32 s12, s0, s1
	s_mul_i32 s0, s12, 18
	s_sub_i32 s0, s40, s0
	v_readlane_b32 s6, v254, 49
	s_cmp_lt_i32 s0, 2
	v_readlane_b32 s7, v254, 50
	s_cselect_b64 s[4:5], -1, 0
	s_xor_b64 s[6:7], s[6:7], -1
	s_and_b64 s[4:5], s[6:7], s[4:5]
	s_and_b64 vcc, exec, s[4:5]
	s_cbranch_vccnz .LBB0_968
	v_mov_b32_e32 v0, s64
	v_mov_b32_e32 v2, s65
	s_cmp_gt_i32 s0, 1
	v_readfirstlane_b32 s1, v0
	v_readfirstlane_b32 s4, v2
	s_mov_b64 s[14:15], -1
	v_mov_b32_e32 v2, s1
	v_mov_b32_e32 v3, s4
	global_load_dwordx2 v[4:5], v[2:3], off offset:248
	v_mov_b32_e32 v2, v247
	s_waitcnt vmcnt(0) lgkmcnt(0)
	v_mov_b32_e32 v0, v4
	s_nop 0
	v_readfirstlane_b32 s6, v0
	v_readfirstlane_b32 s7, v5
	s_cbranch_scc0 .LBB0_924
	s_ashr_i32 s13, s12, 31
	s_lshl_b32 s1, s0, 7
	s_lshl_b64 s[4:5], s[12:13], 11
	s_addk_i32 s1, 0xff00
	s_add_u32 s8, s4, s1
	s_addc_u32 s9, s5, 0
	s_mov_b64 s[14:15], 0

.LBB0_928:
	v_add_co_u32_e32 v8, vcc, 0x90000, v4
	v_add_u32_e32 v7, 0xfffff000, v6
	s_nop 0
	v_addc_co_u32_e32 v9, vcc, 0, v5, vcc
	global_load_dword v3, v[8:9], off
	v_add_u32_e32 v0, 0x200, v0
	v_cmp_lt_i32_e32 vcc, s4, v0
	s_or_b64 s[14:15], vcc, s[14:15]
	s_waitcnt vmcnt(0) lgkmcnt(0)
	ds_write_b32 v7, v3
	global_load_dword v3, v[4:5], off
	v_lshl_add_u64 v[4:5], v[4:5], 0, s[20:21]
	s_waitcnt vmcnt(0) lgkmcnt(0)
	ds_write_b32 v6, v3
	v_add_u32_e32 v6, 0x800, v6
	s_andn2_b64 exec, exec, s[14:15]
	s_cbranch_execnz .LBB0_928

.LBB0_930:
	v_lshl_or_b32 v0, s0, 13, v69
	v_lshl_add_u64 v[106:107], v[0:1], 1, v[72:73]
	v_or_b32_e32 v38, 0x800, v0
	v_mov_b32_e32 v39, v1
	v_or_b32_e32 v42, 0x1000, v0
	v_mov_b32_e32 v43, v1
	global_load_dwordx4 v[34:37], v[106:107], off
	v_lshlrev_b64 v[122:123], 1, v[38:39]
	v_lshlrev_b64 v[126:127], 1, v[42:43]
	v_or_b32_e32 v46, 0x1800, v0
	v_mov_b32_e32 v47, v1
	v_lshl_add_u64 v[38:39], v[72:73], 0, v[122:123]
	v_lshl_add_u64 v[42:43], v[72:73], 0, v[126:127]
	v_lshlrev_b64 v[130:131], 1, v[46:47]
	global_load_dwordx4 v[38:41], v[38:39], off
	v_lshl_add_u64 v[46:47], v[72:73], 0, v[130:131]
	global_load_dwordx4 v[42:45], v[42:43], off
	s_nop 0
	global_load_dwordx4 v[46:49], v[46:47], off
	s_nop 0
	global_load_dwordx4 v[50:53], v[106:107], off offset:64
	v_lshl_add_u64 v[54:55], v[78:79], 0, v[122:123]
	v_lshl_add_u64 v[58:59], v[78:79], 0, v[126:127]
	global_load_dwordx4 v[54:57], v[54:55], off
	v_lshl_add_u64 v[90:91], v[78:79], 0, v[130:131]
	global_load_dwordx4 v[58:61], v[58:59], off
	v_lshl_add_u64 v[98:99], v[80:81], 0, v[122:123]
	v_lshl_add_u64 v[102:103], v[80:81], 0, v[126:127]
	v_lshl_add_u64 v[114:115], v[80:81], 0, v[130:131]
	global_load_dwordx4 v[90:93], v[90:91], off
	s_nop 0
	global_load_dwordx4 v[94:97], v[106:107], off offset:128
	v_add_u32_e32 v110, 4, v110
	global_load_dwordx4 v[98:101], v[98:99], off
	s_waitcnt vmcnt(0) lgkmcnt(0)
	v_mfma_f32_16x16x32_bf16 v[46:49], v[46:49], v[14:17], 0
	global_load_dwordx4 v[102:105], v[102:103], off
	s_nop 0
	global_load_dwordx4 v[114:117], v[114:115], off
	s_nop 0
	global_load_dwordx4 v[118:121], v[106:107], off offset:192
	v_lshl_add_u64 v[106:107], v[82:83], 0, v[122:123]
	global_load_dwordx4 v[122:125], v[106:107], off
	v_lshl_add_u64 v[106:107], v[82:83], 0, v[126:127]
	global_load_dwordx4 v[126:129], v[106:107], off
	v_lshl_add_u64 v[106:107], v[82:83], 0, v[130:131]
	global_load_dwordx4 v[130:133], v[106:107], off
	v_mfma_f32_16x16x32_bf16 v[34:37], v[34:37], v[14:17], 0
	v_mfma_f32_16x16x32_bf16 v[38:41], v[38:41], v[14:17], 0
	v_mfma_f32_16x16x32_bf16 v[42:45], v[42:45], v[14:17], 0
	v_mfma_f32_16x16x32_bf16 v[46:49], v[90:93], v[10:13], v[46:49]
	v_mfma_f32_16x16x32_bf16 v[34:37], v[50:53], v[10:13], v[34:37]
	v_mul_f32_e32 v50, 0x3fb8aa3b, v88
	v_exp_f32_e32 v50, v50
	v_mfma_f32_16x16x32_bf16 v[38:41], v[54:57], v[10:13], v[38:41]
	v_mfma_f32_16x16x32_bf16 v[42:45], v[58:61], v[10:13], v[42:45]
	s_waitcnt vmcnt(0) lgkmcnt(0)
	v_mfma_f32_16x16x32_bf16 v[46:49], v[114:117], v[6:9], v[46:49]
	v_mfma_f32_16x16x32_bf16 v[34:37], v[94:97], v[6:9], v[34:37]
	v_mfma_f32_16x16x32_bf16 v[38:41], v[98:101], v[6:9], v[38:41]
	v_mfma_f32_16x16x32_bf16 v[42:45], v[102:105], v[6:9], v[42:45]
	v_mfma_f32_16x16x32_bf16 v[46:49], v[130:133], v[2:5], v[46:49]
	v_mfma_f32_16x16x32_bf16 v[34:37], v[118:121], v[2:5], v[34:37]
	v_mfma_f32_16x16x32_bf16 v[38:41], v[122:125], v[2:5], v[38:41]
	s_nop 5
	v_fma_f32 v104, v50, v46, v18
	v_fma_f32 v105, v50, v47, v19
	v_add_u32_e32 v18, 0x8000, v0
	v_mov_b32_e32 v19, v1
	v_mfma_f32_16x16x32_bf16 v[42:45], v[126:129], v[2:5], v[42:45]
	v_lshlrev_b64 v[46:47], 1, v[18:19]
	v_pk_fma_f32 v[92:93], v[50:51], v[34:35], v[30:31] op_sel_hi:[0,1,1]
	v_lshl_add_u64 v[18:19], v[72:73], 0, v[46:47]
	v_lshl_add_u64 v[30:31], v[80:81], 0, v[46:47]
	v_pk_fma_f32 v[90:91], v[50:51], v[36:37], v[32:33] op_sel_hi:[0,1,1]
	global_load_dwordx4 v[114:117], v[18:19], off
	v_pk_fma_f32 v[94:95], v[50:51], v[40:41], v[28:29] op_sel_hi:[0,1,1]
	global_load_dwordx4 v[30:33], v[30:31], off
	v_add_u32_e32 v18, 0x8800, v0
	v_mov_b32_e32 v19, v1
	v_pk_fma_f32 v[96:97], v[50:51], v[38:39], v[26:27] op_sel_hi:[0,1,1]
	v_pk_fma_f32 v[98:99], v[50:51], v[44:45], v[24:25] op_sel_hi:[0,1,1]
	v_pk_fma_f32 v[100:101], v[50:51], v[42:43], v[22:23] op_sel_hi:[0,1,1]
	v_pk_fma_f32 v[102:103], v[50:51], v[48:49], v[20:21] op_sel_hi:[0,1,1]
	v_lshlrev_b64 v[50:51], 1, v[18:19]
	v_lshl_add_u64 v[18:19], v[72:73], 0, v[50:51]
	v_lshl_add_u64 v[34:35], v[80:81], 0, v[50:51]
	global_load_dwordx4 v[118:121], v[18:19], off
	s_waitcnt vmcnt(0) lgkmcnt(0)
	v_mfma_f32_16x16x32_bf16 v[114:117], v[114:117], v[14:17], 0
	global_load_dwordx4 v[34:37], v[34:35], off
	v_add_u32_e32 v18, 0x9000, v0
	v_mov_b32_e32 v19, v1
	v_lshlrev_b64 v[54:55], 1, v[18:19]
	v_add_u32_e32 v0, 0x9800, v0
	v_lshl_add_u64 v[18:19], v[72:73], 0, v[54:55]
	v_lshlrev_b64 v[58:59], 1, v[0:1]
	v_lshl_add_u64 v[22:23], v[78:79], 0, v[54:55]
	global_load_dwordx4 v[122:125], v[18:19], off
	v_lshl_add_u64 v[26:27], v[78:79], 0, v[58:59]
	global_load_dwordx4 v[22:25], v[22:23], off
	v_lshl_add_u64 v[18:19], v[72:73], 0, v[58:59]
	global_load_dwordx4 v[126:129], v[18:19], off
	v_lshl_add_u64 v[38:39], v[80:81], 0, v[54:55]
	global_load_dwordx4 v[26:29], v[26:27], off
	v_lshl_add_u64 v[18:19], v[78:79], 0, v[46:47]
	global_load_dwordx4 v[130:133], v[18:19], off
	v_lshl_add_u64 v[42:43], v[80:81], 0, v[58:59]
	global_load_dwordx4 v[38:41], v[38:39], off
	v_lshl_add_u64 v[18:19], v[78:79], 0, v[50:51]
	global_load_dwordx4 v[18:21], v[18:19], off
	v_lshl_add_u64 v[46:47], v[82:83], 0, v[46:47]
	global_load_dwordx4 v[42:45], v[42:43], off
	v_lshl_add_u64 v[50:51], v[82:83], 0, v[50:51]
	v_lshl_add_u64 v[54:55], v[82:83], 0, v[54:55]
	v_lshl_add_u64 v[58:59], v[82:83], 0, v[58:59]
	global_load_dwordx4 v[46:49], v[46:47], off
	v_mfma_f32_16x16x32_bf16 v[118:121], v[118:121], v[14:17], 0
	global_load_dwordx4 v[50:53], v[50:51], off
	v_mul_f32_e32 v0, 0x3fb8aa3b, v89
	global_load_dwordx4 v[54:57], v[54:55], off
	s_waitcnt vmcnt(0) lgkmcnt(0)
	v_mfma_f32_16x16x32_bf16 v[122:125], v[122:125], v[14:17], 0
	global_load_dwordx4 v[58:61], v[58:59], off
	v_exp_f32_e32 v0, v0
	v_mfma_f32_16x16x32_bf16 v[14:17], v[126:129], v[14:17], 0
	v_mfma_f32_16x16x32_bf16 v[114:117], v[130:133], v[10:13], v[114:117]
	v_mfma_f32_16x16x32_bf16 v[18:21], v[18:21], v[10:13], v[118:121]
	v_mfma_f32_16x16x32_bf16 v[22:25], v[22:25], v[10:13], v[122:125]
	v_mfma_f32_16x16x32_bf16 v[10:13], v[26:29], v[10:13], v[14:17]
	v_mfma_f32_16x16x32_bf16 v[14:17], v[30:33], v[6:9], v[114:117]
	v_mfma_f32_16x16x32_bf16 v[18:21], v[34:37], v[6:9], v[18:21]
	v_mfma_f32_16x16x32_bf16 v[22:25], v[38:41], v[6:9], v[22:25]
	v_mfma_f32_16x16x32_bf16 v[6:9], v[42:45], v[6:9], v[10:13]
	v_mfma_f32_16x16x32_bf16 v[10:13], v[46:49], v[2:5], v[14:17]
	v_mfma_f32_16x16x32_bf16 v[14:17], v[50:53], v[2:5], v[18:21]
	v_mfma_f32_16x16x32_bf16 v[24:27], v[54:57], v[2:5], v[22:25]
	s_waitcnt vmcnt(0) lgkmcnt(0)
	v_mfma_f32_16x16x32_bf16 v[6:9], v[58:61], v[2:5], v[6:9]
	s_nop 3
	v_fma_f32 v4, v0, v12, v90
	v_fma_f32 v5, v0, v13, v91
	v_pk_fma_f32 v[2:3], v[0:1], v[10:11], v[92:93] op_sel_hi:[0,1,1]
	v_pk_fma_f32 v[20:21], v[0:1], v[16:17], v[94:95] op_sel_hi:[0,1,1]
	v_pk_fma_f32 v[22:23], v[0:1], v[14:15], v[96:97] op_sel_hi:[0,1,1]
	v_pk_fma_f32 v[14:15], v[0:1], v[26:27], v[98:99] op_sel_hi:[0,1,1]
	v_pk_fma_f32 v[18:19], v[0:1], v[24:25], v[100:101] op_sel_hi:[0,1,1]
	v_pk_fma_f32 v[8:9], v[0:1], v[8:9], v[102:103] op_sel_hi:[0,1,1]
	v_pk_fma_f32 v[6:7], v[0:1], v[6:7], v[104:105] op_sel_hi:[0,1,1]
	v_mov_b32_e32 v0, s64
	v_mov_b32_e32 v10, s65
	s_nop 0
	v_readfirstlane_b32 s4, v0
	v_readfirstlane_b32 s5, v10
	s_nop 0
	v_mov_b32_e32 v10, s4
	v_mov_b32_e32 v11, s5
	global_load_dwordx2 v[10:11], v[10:11], off offset:168
	v_readlane_b32 s4, v254, 51
	s_add_i32 s4, s0, s4
	s_ashr_i32 s5, s4, 31
	s_lshl_b64 s[4:5], s[4:5], 2
	s_waitcnt vmcnt(0) lgkmcnt(0)
	v_mov_b32_e32 v0, v11
	s_nop 0
	v_readfirstlane_b32 s12, v10
	v_readfirstlane_b32 s13, v0
	s_add_u32 s4, s12, s4
	s_addc_u32 s5, s13, s5
	s_lshl_b32 s18, s1, 1
	v_lshl_add_u64 v[16:17], v[74:75], 0, s[18:19]
	global_load_dwordx2 v[12:13], v[16:17], off
	v_or_b32_e32 v0, s1, v109
	v_mul_lo_u32 v0, v0, s82
	v_mov_b64_e32 v[10:11], s[4:5]
	global_load_dword v10, v[10:11], off
	v_lshl_add_u32 v11, s0, 15, v65
	s_add_i32 s0, s0, 1
	s_add_u32 s8, s8, 64
	s_addc_u32 s9, s9, 0
	s_mov_b64 s[4:5], 0x240000
	v_lshl_add_u64 v[86:87], v[86:87], 0, s[4:5]
	s_cmp_eq_u32 s0, 4
	s_waitcnt vmcnt(0) lgkmcnt(0)
	v_lshlrev_b32_e32 v24, 16, v12
	v_and_b32_e32 v25, 0xffff0000, v12
	v_lshlrev_b32_e32 v26, 16, v13
	v_and_b32_e32 v27, 0xffff0000, v13
	v_lshl_add_u64 v[12:13], v[0:1], 1, v[76:77]
	global_load_ushort v0, v[12:13], off
	v_add_co_u32_e32 v28, vcc, s33, v12
	s_nop 1
	v_addc_co_u32_e32 v29, vcc, 0, v13, vcc
	global_load_ushort v29, v[28:29], off
	v_mul_f32_e32 v28, 0xbfb8aa3b, v24
	v_exp_f32_e32 v28, v28
	s_waitcnt vmcnt(0) lgkmcnt(0)
	v_lshlrev_b32_e32 v30, 16, v0
	v_mul_f32_e32 v0, 0xbfb8aa3b, v25
	v_exp_f32_e32 v0, v0
	v_add_f32_e32 v28, 1.0, v28
	v_rcp_f32_e32 v28, v28
	v_add_f32_e32 v0, 1.0, v0
	v_lshlrev_b32_e32 v31, 16, v29
	v_rcp_f32_e32 v29, v0
	v_pk_fma_f32 v[2:3], v[10:11], v[30:31], v[2:3] op_sel_hi:[0,1,1]
	v_pk_mul_f32 v[24:25], v[28:29], v[24:25]
	s_nop 0
	v_pk_mul_f32 v[2:3], v[2:3], v[24:25]
	v_add_co_u32_e32 v24, vcc, s46, v12
	s_nop 1
	v_addc_co_u32_e32 v25, vcc, 0, v13, vcc
	global_load_ushort v0, v[24:25], off
	v_add_co_u32_e32 v24, vcc, s47, v12
	s_waitcnt vmcnt(0) lgkmcnt(0)
	v_lshlrev_b32_e32 v28, 16, v0
	v_addc_co_u32_e32 v25, vcc, 0, v13, vcc
	global_load_ushort v25, v[24:25], off
	v_mul_f32_e32 v24, 0xbfb8aa3b, v26
	v_mul_f32_e32 v0, 0xbfb8aa3b, v27
	v_exp_f32_e32 v24, v24
	v_exp_f32_e32 v0, v0
	v_add_f32_e32 v24, 1.0, v24
	v_add_f32_e32 v0, 1.0, v0
	v_rcp_f32_e32 v24, v24
	s_waitcnt vmcnt(0) lgkmcnt(0)
	v_lshlrev_b32_e32 v29, 16, v25
	v_rcp_f32_e32 v25, v0
	v_pk_fma_f32 v[4:5], v[10:11], v[28:29], v[4:5] op_sel_hi:[0,1,1]
	v_add_co_u32_e32 v28, vcc, s44, v12
	v_pk_mul_f32 v[24:25], v[24:25], v[26:27]
	s_nop 0
	v_addc_co_u32_e32 v29, vcc, 0, v13, vcc
	v_pk_mul_f32 v[4:5], v[24:25], v[4:5]
	ds_write_b128 v11, v[2:5]
	global_load_dwordx2 v[24:25], v[16:17], off offset:32
	global_load_ushort v0, v[28:29], off
	v_add_co_u32_e32 v28, vcc, s48, v12
	s_waitcnt vmcnt(0) lgkmcnt(0)
	v_lshlrev_b32_e32 v26, 16, v24
	v_addc_co_u32_e32 v29, vcc, 0, v13, vcc
	global_load_ushort v29, v[28:29], off
	v_and_b32_e32 v27, 0xffff0000, v24
	v_mul_f32_e32 v28, 0xbfb8aa3b, v26
	v_lshlrev_b32_e32 v30, 16, v0
	v_mul_f32_e32 v0, 0xbfb8aa3b, v27
	v_exp_f32_e32 v28, v28
	v_exp_f32_e32 v0, v0
	v_lshlrev_b32_e32 v24, 16, v25
	v_and_b32_e32 v25, 0xffff0000, v25
	v_add_f32_e32 v28, 1.0, v28
	v_add_f32_e32 v0, 1.0, v0
	v_rcp_f32_e32 v28, v28
	s_waitcnt vmcnt(0) lgkmcnt(0)
	v_lshlrev_b32_e32 v31, 16, v29
	v_rcp_f32_e32 v29, v0
	v_pk_fma_f32 v[22:23], v[10:11], v[30:31], v[22:23] op_sel_hi:[0,1,1]
	v_pk_mul_f32 v[26:27], v[28:29], v[26:27]
	s_nop 0
	v_pk_mul_f32 v[22:23], v[22:23], v[26:27]
	v_add_co_u32_e32 v26, vcc, s49, v12
	s_nop 1
	v_addc_co_u32_e32 v27, vcc, 0, v13, vcc
	global_load_ushort v0, v[26:27], off
	v_add_co_u32_e32 v26, vcc, s50, v12
	s_waitcnt vmcnt(0) lgkmcnt(0)
	v_lshlrev_b32_e32 v28, 16, v0
	v_addc_co_u32_e32 v27, vcc, 0, v13, vcc
	global_load_ushort v27, v[26:27], off
	v_mul_f32_e32 v26, 0xbfb8aa3b, v24
	v_mul_f32_e32 v0, 0xbfb8aa3b, v25
	v_exp_f32_e32 v26, v26
	v_exp_f32_e32 v0, v0
	v_add_f32_e32 v26, 1.0, v26
	v_add_f32_e32 v0, 1.0, v0
	v_rcp_f32_e32 v26, v26
	s_waitcnt vmcnt(0) lgkmcnt(0)
	v_lshlrev_b32_e32 v29, 16, v27
	v_rcp_f32_e32 v27, v0
	v_pk_fma_f32 v[20:21], v[10:11], v[28:29], v[20:21] op_sel_hi:[0,1,1]
	v_pk_mul_f32 v[24:25], v[26:27], v[24:25]
	s_nop 0
	v_pk_mul_f32 v[24:25], v[24:25], v[20:21]
	v_mov_b32_e32 v20, v2
	v_mov_b32_e32 v2, v3
	v_mov_b32_e32 v3, v23
	v_mov_b32_e32 v21, v22
	v_pk_mul_f32 v[2:3], v[2:3], v[2:3]
	ds_write_b128 v11, v[22:25] offset:1024
	v_pk_fma_f32 v[2:3], v[20:21], v[20:21], v[2:3]
	v_mov_b32_e32 v20, v4
	v_mov_b32_e32 v21, v24
	v_pk_fma_f32 v[2:3], v[20:21], v[20:21], v[2:3]
	v_mov_b32_e32 v4, v5
	v_mov_b32_e32 v5, v25
	v_pk_fma_f32 v[2:3], v[4:5], v[4:5], v[2:3]
	s_nop 0
	v_add_f32_e32 v0, v113, v2
	v_add_f32_e32 v0, v0, v3
	global_load_dwordx2 v[2:3], v[16:17], off offset:64
	s_waitcnt vmcnt(0) lgkmcnt(0)
	v_lshlrev_b32_e32 v20, 16, v2
	v_and_b32_e32 v21, 0xffff0000, v2
	v_add_co_u32_e32 v2, vcc, s35, v12
	v_lshlrev_b32_e32 v4, 16, v3
	v_and_b32_e32 v5, 0xffff0000, v3
	v_addc_co_u32_e32 v3, vcc, 0, v13, vcc
	global_load_ushort v22, v[2:3], off
	v_add_co_u32_e32 v2, vcc, s51, v12
	s_waitcnt vmcnt(0) lgkmcnt(0)
	v_lshlrev_b32_e32 v22, 16, v22
	v_addc_co_u32_e32 v3, vcc, 0, v13, vcc
	global_load_ushort v3, v[2:3], off
	v_mul_f32_e32 v2, 0xbfb8aa3b, v20
	v_exp_f32_e32 v2, v2
	s_waitcnt vmcnt(0) lgkmcnt(0)
	v_lshlrev_b32_e32 v23, 16, v3
	v_mul_f32_e32 v3, 0xbfb8aa3b, v21
	v_exp_f32_e32 v3, v3
	v_add_f32_e32 v2, 1.0, v2
	v_rcp_f32_e32 v2, v2
	v_pk_fma_f32 v[18:19], v[10:11], v[22:23], v[18:19] op_sel_hi:[0,1,1]
	v_add_f32_e32 v3, 1.0, v3
	v_rcp_f32_e32 v3, v3
	s_nop 0
	v_pk_mul_f32 v[2:3], v[2:3], v[20:21]
	s_nop 0
	v_pk_mul_f32 v[2:3], v[18:19], v[2:3]
	v_add_co_u32_e32 v18, vcc, s52, v12
	s_nop 1
	v_addc_co_u32_e32 v19, vcc, 0, v13, vcc
	global_load_ushort v20, v[18:19], off
	v_add_co_u32_e32 v18, vcc, s53, v12
	s_waitcnt vmcnt(0) lgkmcnt(0)
	v_lshlrev_b32_e32 v20, 16, v20
	v_addc_co_u32_e32 v19, vcc, 0, v13, vcc
	global_load_ushort v19, v[18:19], off
	v_mul_f32_e32 v18, 0xbfb8aa3b, v4
	v_exp_f32_e32 v18, v18
	s_waitcnt vmcnt(0) lgkmcnt(0)
	v_lshlrev_b32_e32 v21, 16, v19
	v_mul_f32_e32 v19, 0xbfb8aa3b, v5
	v_exp_f32_e32 v19, v19
	v_add_f32_e32 v18, 1.0, v18
	v_rcp_f32_e32 v18, v18
	v_pk_fma_f32 v[14:15], v[10:11], v[20:21], v[14:15] op_sel_hi:[0,1,1]
	v_add_f32_e32 v19, 1.0, v19
	v_rcp_f32_e32 v19, v19
	s_nop 0
	v_pk_mul_f32 v[4:5], v[18:19], v[4:5]
	s_nop 0
	v_pk_mul_f32 v[4:5], v[4:5], v[14:15]
	v_add_co_u32_e32 v18, vcc, s54, v12
	ds_write_b128 v11, v[2:5] offset:2048
	s_nop 0
	v_addc_co_u32_e32 v19, vcc, 0, v13, vcc
	global_load_ushort v20, v[18:19], off
	v_add_co_u32_e32 v18, vcc, s55, v12
	global_load_dwordx2 v[14:15], v[16:17], off offset:96
	s_nop 0
	v_addc_co_u32_e32 v19, vcc, 0, v13, vcc
	global_load_ushort v19, v[18:19], off
	s_waitcnt vmcnt(0) lgkmcnt(0)
	v_lshlrev_b32_e32 v20, 16, v20
	v_lshlrev_b32_e32 v16, 16, v14
	v_and_b32_e32 v17, 0xffff0000, v14
	v_mul_f32_e32 v18, 0xbfb8aa3b, v16
	v_lshlrev_b32_e32 v21, 16, v19
	v_mul_f32_e32 v19, 0xbfb8aa3b, v17
	v_exp_f32_e32 v18, v18
	v_exp_f32_e32 v19, v19
	v_pk_fma_f32 v[6:7], v[10:11], v[20:21], v[6:7] op_sel_hi:[0,1,1]
	v_lshlrev_b32_e32 v14, 16, v15
	v_add_f32_e32 v18, 1.0, v18
	v_add_f32_e32 v19, 1.0, v19
	v_rcp_f32_e32 v18, v18
	v_rcp_f32_e32 v19, v19
	v_and_b32_e32 v15, 0xffff0000, v15
	v_pk_mul_f32 v[16:17], v[18:19], v[16:17]
	s_nop 0
	v_pk_mul_f32 v[6:7], v[6:7], v[16:17]
	v_add_co_u32_e32 v16, vcc, s56, v12
	s_nop 1
	v_addc_co_u32_e32 v17, vcc, 0, v13, vcc
	v_add_co_u32_e32 v12, vcc, s57, v12
	global_load_ushort v16, v[16:17], off
	s_nop 0
	v_addc_co_u32_e32 v13, vcc, 0, v13, vcc
	global_load_ushort v13, v[12:13], off
	v_mul_f32_e32 v12, 0xbfb8aa3b, v14
	v_exp_f32_e32 v12, v12
	s_waitcnt vmcnt(0) lgkmcnt(0)
	v_lshlrev_b32_e32 v16, 16, v16
	v_add_f32_e32 v12, 1.0, v12
	v_rcp_f32_e32 v12, v12
	v_lshlrev_b32_e32 v17, 16, v13
	v_pk_fma_f32 v[8:9], v[10:11], v[16:17], v[8:9] op_sel_hi:[0,1,1]
	v_mul_f32_e32 v10, 0xbfb8aa3b, v15
	v_exp_f32_e32 v10, v10
	s_nop 0
	v_add_f32_e32 v10, 1.0, v10
	v_rcp_f32_e32 v13, v10
	s_nop 0
	v_pk_mul_f32 v[12:13], v[12:13], v[14:15]
	s_nop 0
	v_pk_mul_f32 v[8:9], v[12:13], v[8:9]
	v_mov_b32_e32 v12, v2
	v_mov_b32_e32 v2, v3
	v_mov_b32_e32 v3, v7
	v_mov_b32_e32 v13, v6
	v_pk_mul_f32 v[2:3], v[2:3], v[2:3]
	ds_write_b128 v11, v[6:9] offset:3072
	v_pk_fma_f32 v[2:3], v[12:13], v[12:13], v[2:3]
	v_mov_b32_e32 v12, v4
	v_mov_b32_e32 v13, v8
	v_pk_fma_f32 v[2:3], v[12:13], v[12:13], v[2:3]
	v_mov_b32_e32 v4, v5
	v_mov_b32_e32 v5, v9
	v_pk_fma_f32 v[2:3], v[4:5], v[4:5], v[2:3]
	s_nop 0
	v_add_f32_e32 v0, v0, v2
	v_add_f32_e32 v113, v0, v3
	s_cbranch_scc1 .LBB0_965
.LBB0_931:
	s_lshl_b32 s1, s0, 7
	s_and_b32 s18, s1, 0xffffff00
	v_lshl_add_u64 v[2:3], v[70:71], 0, s[18:19]
	global_load_dwordx4 v[14:17], v[2:3], off offset:512
	global_load_dwordx4 v[10:13], v[2:3], off offset:576
	global_load_dwordx4 v[6:9], v[2:3], off offset:640
	s_nop 0
	global_load_dwordx4 v[2:5], v[2:3], off offset:704
	v_lshl_add_u32 v0, s0, 2, v108
	ds_read2_b32 v[88:89], v0 offset1:4
	s_lshl_b64 s[4:5], s[8:9], 1
	s_and_b32 s4, s4, 0xffffff00
	v_lshl_add_u64 v[54:55], v[84:85], 0, s[4:5]
	s_lshl_b32 s1, s0, 6
	v_mov_b64_e32 v[56:57], v[86:87]
	v_mov_b32_e32 v0, v111
	s_mov_b32 s4, 0
	v_mov_b32_e32 v30, 0
	v_mov_b32_e32 v31, v112
	v_mov_b32_e32 v32, v112
	v_mov_b32_e32 v33, v112
	v_mov_b32_e32 v26, 0
	v_mov_b32_e32 v27, v112
	v_mov_b32_e32 v28, v112
	v_mov_b32_e32 v29, v112
	v_mov_b32_e32 v22, 0
	v_mov_b32_e32 v23, v112
	v_mov_b32_e32 v24, v112
	v_mov_b32_e32 v25, v112
	v_mov_b32_e32 v18, 0
	v_mov_b32_e32 v19, v112
	v_mov_b32_e32 v20, v112
	v_mov_b32_e32 v21, v112
	s_branch .LBB0_933

.LBB0_933:
	v_lshl_add_u64 v[38:39], s[6:7], 0, v[54:55]
	v_add_co_u32_e32 v40, vcc, s73, v38
	v_lshl_add_u64 v[42:43], s[6:7], 0, v[56:57]
	s_nop 0
	v_addc_co_u32_e32 v41, vcc, 0, v39, vcc
	global_load_dwordx4 v[34:37], v[40:41], off
	global_load_dwordx4 v[50:53], v[40:41], off offset:64
	global_load_dwordx4 v[90:93], v[40:41], off offset:128
	v_add_co_u32_e32 v94, vcc, s66, v42
	global_load_dwordx4 v[104:107], v[40:41], off offset:192
	s_nop 0
	v_addc_co_u32_e32 v95, vcc, 0, v43, vcc
	v_add_co_u32_e32 v98, vcc, s67, v42
	v_mov_b32_e32 v116, 0xff800000
	s_nop 0
	v_addc_co_u32_e32 v99, vcc, 0, v43, vcc
	v_add_co_u32_e32 v102, vcc, s68, v42
	s_waitcnt vmcnt(0) lgkmcnt(0)
	v_mfma_f32_16x16x32_bf16 v[58:61], v[34:37], v[14:17], 0
	v_addc_co_u32_e32 v103, vcc, 0, v43, vcc
	v_add_co_u32_e32 v114, vcc, s69, v42
	v_mfma_f32_16x16x32_bf16 v[50:53], v[50:53], v[10:13], v[58:61]
	s_nop 0
	v_addc_co_u32_e32 v115, vcc, 0, v43, vcc
	v_add_co_u32_e32 v46, vcc, s74, v38
	v_mfma_f32_16x16x32_bf16 v[50:53], v[90:93], v[6:9], v[50:53]
	s_nop 0
	v_addc_co_u32_e32 v47, vcc, 0, v39, vcc
	global_load_dwordx4 v[34:37], v[46:47], off
	global_load_dwordx4 v[38:41], v[46:47], off offset:64
	global_load_dwordx4 v[42:45], v[46:47], off offset:128
	s_nop 0
	global_load_dwordx4 v[46:49], v[46:47], off offset:192
	s_nop 0
	global_load_dwordx2 v[100:101], v[94:95], off
	global_load_dwordx2 v[96:97], v[98:99], off
	global_load_dwordx2 v[58:59], v[98:99], off offset:32
	global_load_dwordx2 v[60:61], v[94:95], off offset:32
	s_nop 0
	global_load_dwordx2 v[98:99], v[102:103], off
	global_load_dwordx2 v[94:95], v[114:115], off
	global_load_dwordx2 v[90:91], v[114:115], off offset:32
	global_load_dwordx2 v[92:93], v[102:103], off offset:32
	v_mfma_f32_16x16x32_bf16 v[50:53], v[104:107], v[2:5], v[50:53]
	v_subrev_u32_e32 v102, 19, v0
	v_cmp_le_i32_e32 vcc, v102, v68
	v_mov_b32_e32 v115, 0xff800000
	v_add_u32_e32 v114, s4, v110
	s_and_saveexec_b64 s[12:13], vcc
	s_cbranch_execz .LBB0_935
	v_add_u32_e32 v103, 0x20000, v114
	ds_read_b32 v103, v103
	s_waitcnt lgkmcnt(0)
	v_sub_f32_e32 v103, v88, v103
	v_mul_f32_e32 v116, 0x3fb8aa3b, v103

.LBB0_965:
	v_mov_b32_e32 v0, s64
	v_mov_b32_e32 v2, s65
	v_cmp_lt_i32_e32 vcc, v222, v220
	v_readfirstlane_b32 s0, v0
	v_readfirstlane_b32 s1, v2
	v_cndmask_b32_e32 v0, v219, v222, vcc
	v_mov_b32_e32 v2, s0
	v_mov_b32_e32 v3, s1
	global_load_dwordx2 v[6:7], v[2:3], off offset:176
	v_lshlrev_b32_e32 v0, 2, v0
	ds_bpermute_b32 v0, v0, v113
	v_cmp_lt_i32_e32 vcc, v221, v220
	s_mov_b32 s0, 0x800000
	v_readlane_b32 s4, v255, 5
	v_cndmask_b32_e32 v2, v219, v221, vcc
	v_lshlrev_b32_e32 v2, 2, v2
	s_waitcnt lgkmcnt(0)
	v_add_f32_e32 v0, v113, v0
	ds_bpermute_b32 v2, v2, v0
	v_readlane_b32 s5, v255, 6
	s_waitcnt lgkmcnt(0)
	v_add_f32_e32 v0, v0, v2
	v_fmamk_f32 v0, v0, 0x3b800000, v162
	v_mul_f32_e32 v2, 0x4b800000, v0
	v_cmp_gt_f32_e32 vcc, s0, v0
	s_nop 1
	v_cndmask_b32_e32 v0, v0, v2, vcc
	v_rsq_f32_e32 v0, v0
	v_lshlrev_b64 v[2:3], 11, v[66:67]
	v_or_b32_e32 v2, v2, v64
	v_lshl_add_u64 v[2:3], s[6:7], 0, v[2:3]
	v_mul_f32_e32 v4, 0x45800000, v0
	v_cndmask_b32_e32 v4, v0, v4, vcc
	v_mov_b32_e32 v5, v4
	s_mov_b64 s[6:7], 0
	s_waitcnt vmcnt(0)
	v_mov_b32_e32 v0, v6
	s_nop 0
	v_readfirstlane_b32 s0, v0
	v_readfirstlane_b32 s1, v7
	s_add_u32 s0, s0, s4
	s_addc_u32 s1, s1, s5
	v_lshl_add_u64 v[6:7], s[0:1], 0, v[62:63]
.LBB0_966:
	global_load_dwordx4 v[8:11], v[6:7], off
	ds_read_b128 v[12:15], v65
	v_lshl_add_u64 v[16:17], v[2:3], 0, s[6:7]
	v_add_co_u32_e32 v16, vcc, s34, v16
	s_add_u32 s6, s6, 0x80
	s_waitcnt lgkmcnt(0)
	v_pk_mul_f32 v[12:13], v[4:5], v[12:13]
	v_pk_mul_f32 v[14:15], v[4:5], v[14:15]
	v_addc_co_u32_e32 v17, vcc, 0, v17, vcc
	s_addc_u32 s7, s7, 0
	s_cmpk_lg_i32 s6, 0x200
	s_waitcnt vmcnt(0)
	v_pk_mul_f32 v[8:9], v[8:9], v[12:13]
	v_pk_mul_f32 v[10:11], v[14:15], v[10:11]
	v_cvt_pk_bf16_f32 v8, v8, v9
	v_cvt_pk_bf16_f32 v9, v10, v11
	global_store_dwordx2 v[16:17], v[8:9], off offset:1536
	global_load_dwordx4 v[8:11], v[6:7], off offset:64
	ds_read_b128 v[12:15], v65 offset:1024
	s_waitcnt lgkmcnt(0)
	v_pk_mul_f32 v[12:13], v[4:5], v[12:13]
	v_pk_mul_f32 v[14:15], v[4:5], v[14:15]
	s_waitcnt vmcnt(0)
	v_pk_mul_f32 v[8:9], v[8:9], v[12:13]
	v_pk_mul_f32 v[10:11], v[14:15], v[10:11]
	v_cvt_pk_bf16_f32 v8, v8, v9
	v_cvt_pk_bf16_f32 v9, v10, v11
	global_store_dwordx2 v[16:17], v[8:9], off offset:1568
	global_load_dwordx4 v[8:11], v[6:7], off offset:128
	ds_read_b128 v[12:15], v65 offset:2048
	s_waitcnt lgkmcnt(0)
	v_pk_mul_f32 v[12:13], v[4:5], v[12:13]
	v_pk_mul_f32 v[14:15], v[4:5], v[14:15]
	s_waitcnt vmcnt(0)
	v_pk_mul_f32 v[8:9], v[8:9], v[12:13]
	v_pk_mul_f32 v[10:11], v[14:15], v[10:11]
	v_cvt_pk_bf16_f32 v8, v8, v9
	v_cvt_pk_bf16_f32 v9, v10, v11
	global_store_dwordx2 v[16:17], v[8:9], off offset:1600
	global_load_dwordx4 v[8:11], v[6:7], off offset:192
	ds_read_b128 v[12:15], v65 offset:3072
	v_add_u32_e32 v65, 0x8000, v65
	v_lshl_add_u64 v[6:7], v[6:7], 0, s[20:21]
	s_waitcnt lgkmcnt(0)
	v_pk_mul_f32 v[12:13], v[4:5], v[12:13]
	v_pk_mul_f32 v[14:15], v[4:5], v[14:15]
	s_waitcnt vmcnt(0)
	v_pk_mul_f32 v[8:9], v[8:9], v[12:13]
	v_pk_mul_f32 v[10:11], v[14:15], v[10:11]
	v_cvt_pk_bf16_f32 v8, v8, v9
	v_cvt_pk_bf16_f32 v9, v10, v11
	global_store_dwordx2 v[16:17], v[8:9], off offset:1632
	s_cbranch_scc1 .LBB0_966
	s_waitcnt lgkmcnt(0)
	s_barrier
.LBB0_968:
	v_mov_b32_e32 v2, s64
	v_mov_b32_e32 v3, s65
	v_mov_b32_e32 v4, s64
	v_readfirstlane_b32 s0, v2
	v_readfirstlane_b32 s1, v3
	v_mov_b32_e32 v5, s65
	v_mov_b32_e32 v2, s0
	v_mov_b32_e32 v3, s1
	global_load_dwordx2 v[2:3], v[2:3], off offset:248
	s_waitcnt vmcnt(0) lgkmcnt(0)
	v_mov_b32_e32 v0, s64
	v_readfirstlane_b32 s0, v4
	v_readfirstlane_b32 s1, v5
	v_mov_b32_e32 v6, s65
	v_mov_b32_e32 v4, s0
	v_mov_b32_e32 v5, s1
	global_load_dwordx2 v[4:5], v[4:5], off offset:248
	v_mov_b32_e32 v60, v247
	v_mov_b32_e32 v15, v1
	v_cmp_lt_i32_e32 vcc, v222, v220
	v_mov_b32_e32 v68, 0xf149f2ca
	v_mov_b32_e32 v62, 0
	s_waitcnt vmcnt(0) lgkmcnt(0)
	v_mov_b32_e32 v8, v5
	s_nop 0
	v_readfirstlane_b32 s0, v0
	v_readfirstlane_b32 s1, v6
	v_readfirstlane_b32 s13, v8
	v_mov_b32_e32 v6, s0
	v_readfirstlane_b32 s0, v2
	v_mov_b32_e32 v7, s1
	v_readfirstlane_b32 s1, v3
	s_add_u32 s8, s0, 0x9f00000
	global_load_dwordx2 v[50:51], v[6:7], off offset:248
	s_addc_u32 s9, s1, 0
	s_ashr_i32 s4, s40, 6
	s_lshl_b32 s0, s40, 7
	s_lshl_b32 s6, s40, 1
	s_ashr_i32 s5, s4, 31
	s_and_b32 s12, s0, 0x780
	s_waitcnt vmcnt(0) lgkmcnt(0)
	s_and_b32 s14, s6, 64
	v_ashrrev_i32_e32 v0, 2, v60
	v_and_b32_e32 v34, 15, v60
	s_lshl_b64 s[6:7], s[4:5], 11
	v_ashrrev_i32_e32 v52, 3, v60
	v_and_b32_e32 v8, -16, v0
	v_or_b32_e32 v0, s12, v34
	v_mov_b32_e32 v5, s7
	v_readfirstlane_b32 s5, v4
	v_add_u32_e32 v11, s14, v52
	v_ashrrev_i32_e32 v9, 31, v8
	v_or_b32_e32 v4, s6, v0
	v_mov_b64_e32 v[2:3], s[8:9]
	v_mov_b32_e32 v6, s5
	v_mov_b32_e32 v7, s13
	v_add_u32_e32 v0, 0x180, v11
	v_lshl_add_u64 v[54:55], v[4:5], 0, v[8:9]
	s_bfe_u32 s1, s40, 0x20004
	v_mad_i64_i32 v[4:5], s[12:13], v0, s33, v[6:7]
	v_mad_u64_u32 v[6:7], s[12:13], v54, s2, v[2:3]
	s_lshl_b32 s0, s1, 6
	s_lshl_b32 s18, s1, 7
	s_lshl_b32 s1, s4, 8
	s_mov_b64 s[12:13], 0x17700000
	v_mad_i32_i24 v7, v55, s2, v7
	s_ashr_i32 s4, s1, 31
	v_lshl_add_u64 v[16:17], v[4:5], 0, s[12:13]
	v_lshl_add_u64 v[4:5], v[6:7], 0, s[18:19]
	s_lshl_b32 s18, s14, 1
	s_add_u32 s12, s1, 0x4000
	v_ashrrev_i32_e32 v53, 31, v52
	s_addc_u32 s13, s4, 0
	v_lshl_add_u64 v[6:7], s[12:13], 0, v[52:53]
	v_lshlrev_b32_e32 v35, 3, v60
	v_lshl_add_u64 v[8:9], s[12:13], 1, v[16:17]
	v_mad_u64_u32 v[2:3], s[12:13], v6, s2, v[2:3]
	v_lshrrev_b32_e32 v10, 1, v60
	v_and_b32_e32 v61, 56, v35
	v_mad_i32_i24 v3, v7, s2, v3
	v_lshlrev_b32_e32 v14, 1, v61
	v_lshl_add_u64 v[2:3], v[2:3], 0, s[18:19]
	v_and_b32_e32 v0, 24, v10
	v_lshl_add_u64 v[2:3], v[2:3], 0, v[14:15]
	v_lshlrev_b32_e32 v0, 1, v0
	v_lshl_add_u64 v[8:9], v[8:9], 0, v[14:15]
	global_load_dwordx4 v[30:33], v[2:3], off offset:2304
	v_lshl_add_u64 v[2:3], v[4:5], 0, v[0:1]
	global_load_dwordx4 v[26:29], v[8:9], off
	global_load_dwordx4 v[18:21], v[2:3], off offset:1792
	global_load_dwordx4 v[22:25], v[2:3], off offset:1856
	v_lshlrev_b32_e32 v36, 4, v60
	v_lshlrev_b32_e32 v37, 1, v60
	s_movk_i32 s13, 0x90
	v_cndmask_b32_e32 v6, v219, v222, vcc
	v_cmp_lt_i32_e32 vcc, v221, v220
	v_and_b32_e32 v35, 32, v35
	v_and_b32_e32 v36, 16, v36
	v_and_b32_e32 v37, 4, v37
	v_mul_lo_u32 v38, v52, s13
	v_cndmask_b32_e32 v7, v219, v221, vcc
	v_mov_b32_e32 v4, v1
	v_mov_b32_e32 v5, v1
	v_or3_b32 v66, v35, v36, v37
	v_add_u32_e32 v67, 16, v38
	v_mov_b32_e32 v2, v1
	v_mov_b32_e32 v3, v1
	v_lshlrev_b32_e32 v64, 2, v6
	v_lshlrev_b32_e32 v63, 2, v7
	v_mov_b64_e32 v[8:9], v[4:5]
	v_mov_b64_e32 v[12:13], v[4:5]
	v_mul_u32_u24_e32 v65, 0x90, v34
	v_add_u32_e32 v36, v67, v14
	v_lshl_add_u32 v37, v66, 1, v67
	v_lshl_add_u64 v[34:35], s[8:9], 0, v[14:15]
	v_lshl_add_u64 v[56:57], v[16:17], 0, v[14:15]
	s_or_b32 s18, s18, 0x900
	v_mov_b64_e32 v[16:17], v[4:5]
	s_mov_b32 s5, 0
	s_movk_i32 s12, 0x4040
	v_mov_b64_e32 v[6:7], v[2:3]
	v_mov_b64_e32 v[10:11], v[2:3]
	v_add_u32_e32 v37, 0x2000, v37
	v_lshl_add_u64 v[58:59], v[34:35], 0, s[18:19]
	v_mov_b64_e32 v[14:15], v[2:3]
	s_waitcnt vmcnt(0) lgkmcnt(0)
	ds_write2_b64 v37, v[26:27], v[28:29] offset0:128 offset1:130
	ds_write_b128 v36, v[30:33]
	s_waitcnt lgkmcnt(0)
	s_barrier
	s_branch .LBB0_970

.LBB0_970:
	s_cmp_lg_u32 s5, 35
	s_cselect_b64 s[8:9], -1, 0
	s_cmp_eq_u32 s5, 35
	s_cbranch_scc1 .LBB0_972
	s_cmp_lt_u32 s5, 3
	s_cselect_b64 s[14:15], -1, 0
	s_add_i32 s13, s12, 0xffffbf00
	s_and_b64 s[14:15], s[14:15], exec
	s_cselect_b32 s13, s12, s13
	s_cselect_b32 s14, s1, s6
	s_cselect_b32 s15, s4, s7
	s_add_u32 s14, s14, s13
	s_addc_u32 s15, s15, 0
	s_waitcnt vmcnt(0)
	v_lshl_add_u64 v[26:27], s[14:15], 0, v[52:53]
	v_mad_u64_u32 v[28:29], s[20:21], v26, s2, v[58:59]
	v_mad_i32_i24 v29, v27, s2, v29
	v_lshl_add_u64 v[26:27], s[14:15], 1, v[56:57]
	global_load_dwordx4 v[30:33], v[28:29], off
	s_nop 0
	global_load_dwordx4 v[26:29], v[26:27], off

.LBB0_977:
	s_and_b64 vcc, exec, s[8:9]
	s_cbranch_vccz .LBB0_979
	s_waitcnt lgkmcnt(0)
	v_add_f32_e32 v0, v0, v20
	v_div_scale_f32 v20, s[0:1], v0, v0, 1.0
	v_rcp_f32_e32 v21, v20
	s_waitcnt vmcnt(0)
	v_div_scale_f32 v22, vcc, 1.0, v0, 1.0
	v_fma_f32 v23, -v20, v21, 1.0
	v_fmac_f32_e32 v21, v23, v21
	v_mul_f32_e32 v23, v22, v21
	v_fma_f32 v24, -v20, v23, v22
	v_fmac_f32_e32 v23, v24, v21
	v_fma_f32 v20, -v20, v23, v22
	v_div_fmas_f32 v20, v20, v21, v23
	v_div_fixup_f32 v20, v20, v0, 1.0
	v_lshrrev_b32_e32 v0, 1, v60
	v_and_b32_e32 v0, 24, v0
	v_pk_mul_f32 v[14:15], v[14:15], v[20:21] op_sel_hi:[1,0]
	v_pk_mul_f32 v[16:17], v[16:17], v[20:21] op_sel_hi:[1,0]
	v_pk_mul_f32 v[10:11], v[10:11], v[20:21] op_sel_hi:[1,0]
	v_pk_mul_f32 v[12:13], v[12:13], v[20:21] op_sel_hi:[1,0]
	v_pk_mul_f32 v[6:7], v[6:7], v[20:21] op_sel_hi:[1,0]
	v_pk_mul_f32 v[8:9], v[8:9], v[20:21] op_sel_hi:[1,0]
	v_pk_mul_f32 v[2:3], v[2:3], v[20:21] op_sel_hi:[1,0]
	v_pk_mul_f32 v[4:5], v[4:5], v[20:21] op_sel_hi:[1,0]
	v_lshl_add_u64 v[18:19], v[18:19], 0, v[0:1]
	v_cvt_pk_bf16_f32 v14, v14, v15
	v_cvt_pk_bf16_f32 v15, v16, v17
	v_cvt_pk_bf16_f32 v10, v10, v11
	v_cvt_pk_bf16_f32 v11, v12, v13
	v_cvt_pk_bf16_f32 v6, v6, v7
	v_cvt_pk_bf16_f32 v7, v8, v9
	v_cvt_pk_bf16_f32 v2, v2, v3
	v_cvt_pk_bf16_f32 v3, v4, v5
	global_store_dwordx2 v[18:19], v[14:15], off
	global_store_dwordx2 v[18:19], v[10:11], off offset:32
	global_store_dwordx2 v[18:19], v[6:7], off offset:64
	global_store_dwordx2 v[18:19], v[2:3], off offset:96

.LBB0_1024:
	s_cmp_eq_u32 s87, 2
	s_cbranch_scc0 .LBB0_1088
	v_mov_b32_e32 v2, s65
	v_mov_b32_e32 v3, s64
	v_mov_b32_e32 v4, s65
	v_readfirstlane_b32 s0, v3
	v_readfirstlane_b32 s1, v2
	v_mov_b32_e32 v5, s64
	v_mov_b32_e32 v2, s0
	v_mov_b32_e32 v3, s1
	global_load_dwordx2 v[2:3], v[2:3], off offset:80
	s_waitcnt vmcnt(0) lgkmcnt(0)
	v_mov_b32_e32 v0, s64
	v_readfirstlane_b32 s0, v5
	v_readfirstlane_b32 s1, v4
	v_mov_b32_e32 v8, s65
	v_mov_b32_e32 v4, s0
	v_mov_b32_e32 v5, s1
	global_load_dwordx2 v[6:7], v[4:5], off offset:248
	v_mov_b32_e32 v4, v247
	v_mov_b32_e32 v5, s88
	s_waitcnt vmcnt(0) lgkmcnt(0)
	s_movk_i32 s6, 0x2000
	v_readfirstlane_b32 s0, v0
	v_readfirstlane_b32 s1, v8
	v_readfirstlane_b32 s12, v6
	v_mov_b32_e32 v8, s0
	v_mov_b32_e32 v9, s1
	global_load_dwordx2 v[8:9], v[8:9], off offset:88
	v_readfirstlane_b32 s0, v2
	v_readfirstlane_b32 s1, v3
	v_readfirstlane_b32 s13, v7
	v_readfirstlane_b32 s4, v5
	v_cmp_gt_i32_e32 vcc, s6, v4
	s_waitcnt vmcnt(0) lgkmcnt(0)
	v_mov_b32_e32 v0, v8
	s_nop 0
	v_readfirstlane_b32 s5, v0
	v_readfirstlane_b32 s8, v9
	s_and_saveexec_b64 s[6:7], vcc
	s_movk_i32 s20, 0x6c20
	s_cbranch_execz .LBB0_1028
	v_readlane_b32 s9, v254, 62
	s_add_u32 s14, s5, s9
	v_readlane_b32 s5, v254, 53
	v_and_b32_e32 v5, 7, v4
	s_addc_u32 s15, s8, s5
	v_lshlrev_b32_e32 v0, 2, v5
	v_lshl_add_u64 v[2:3], s[14:15], 0, v[0:1]
	s_mov_b64 s[8:9], 0x2c00
	v_lshl_add_u64 v[2:3], v[2:3], 0, s[8:9]
	v_lshl_add_u32 v0, v5, 12, 16
	s_mov_b64 s[8:9], 0
	v_mov_b32_e32 v5, v4
.LBB0_1027:
	v_ashrrev_i32_e32 v8, 3, v5
	v_mad_i64_i32 v[6:7], s[14:15], v8, s20, v[2:3]
	global_load_dword v6, v[6:7], off
	s_movk_i32 s5, 0x1dff
	v_add_u32_e32 v7, 0x200, v5
	v_cmp_lt_i32_e32 vcc, s5, v5
	v_lshl_add_u32 v8, v8, 2, v0
	v_mov_b32_e32 v5, v7
	s_or_b64 s[8:9], vcc, s[8:9]
	s_waitcnt vmcnt(0) lgkmcnt(0)
	ds_write_b32 v8, v6
	s_andn2_b64 exec, exec, s[8:9]
	s_cbranch_execnz .LBB0_1027
.LBB0_1028:
	s_movk_i32 s21, 0x23ff
	s_mov_b32 s20, 0x7b00000
	s_or_b64 exec, exec, s[6:7]
	v_ashrrev_i32_e32 v0, 6, v4
	v_lshl_add_u32 v102, s4, 3, v0
	s_movk_i32 s4, 0x2400
	v_cmp_gt_i32_e32 vcc, s4, v102
	s_waitcnt lgkmcnt(0)
	s_barrier
	s_and_saveexec_b64 s[6:7], vcc
	s_cbranch_execz .LBB0_1043
	v_readlane_b32 s4, v254, 39
	v_readlane_b32 s5, v254, 40
	s_lshl_b64 s[4:5], s[4:5], 2
	s_add_u32 s0, s0, s4
	v_and_b32_e32 v22, 63, v4
	s_addc_u32 s1, s1, s5
	v_lshlrev_b32_e32 v18, 4, v22
	v_mov_b32_e32 v19, v1
	v_lshl_add_u64 v[14:15], s[0:1], 0, v[18:19]
	global_load_dwordx4 v[2:5], v[14:15], off
	global_load_dwordx4 v[6:9], v[14:15], off offset:1024
	global_load_dwordx4 v[10:13], v[14:15], off offset:2048
	s_nop 0
	global_load_dwordx4 v[14:17], v[14:15], off offset:3072
	v_lshl_add_u64 v[20:21], s[12:13], 0, v[18:19]
	v_xor_b32_e32 v19, 1, v219
	v_cmp_lt_i32_e64 s[38:39], v19, v220
	v_readlane_b32 s0, v254, 42
	s_add_u32 s0, s12, s0
	v_cndmask_b32_e64 v19, v219, v19, s[38:39]
	v_lshlrev_b32_e32 v123, 2, v19
	v_xor_b32_e32 v19, 2, v219
	v_cmp_lt_i32_e64 s[38:39], v19, v220
	v_readlane_b32 s1, v254, 41
	s_addc_u32 s1, s13, s1
	v_cndmask_b32_e64 v19, v219, v19, s[38:39]
	v_lshlrev_b32_e32 v124, 2, v19
	v_xor_b32_e32 v19, 4, v219
	v_cmp_lt_i32_e64 s[38:39], v19, v220
	s_add_u32 s8, s0, 0x20700000
	v_lshlrev_b32_e32 v0, 2, v22
	v_cndmask_b32_e64 v19, v219, v19, s[38:39]
	v_lshlrev_b32_e32 v125, 2, v19
	v_xor_b32_e32 v19, 8, v219
	s_addc_u32 s9, s1, 0
	s_mov_b64 s[0:1], 0x3300000
	v_cmp_lt_i32_e64 s[38:39], v19, v220
	v_lshl_add_u64 v[104:105], v[20:21], 0, s[0:1]
	v_lshl_add_u64 v[20:21], s[12:13], 0, v[0:1]
	s_mov_b64 s[4:5], 0x20844000
	v_cndmask_b32_e64 v19, v219, v19, s[38:39]
	v_cmp_lt_i32_e64 s[38:39], v222, v220
	v_readlane_b32 s0, v254, 52
	v_lshl_add_u64 v[108:109], v[20:21], 0, s[4:5]
	v_lshlrev_b32_e32 v126, 2, v19
	v_cndmask_b32_e64 v19, v219, v222, s[38:39]
	v_cmp_lt_i32_e64 s[38:39], v221, v220
	v_lshlrev_b32_e32 v20, 3, v22
	v_mov_b32_e32 v21, v1
	v_cmp_gt_u32_e32 vcc, 8, v22
	v_add_u32_e32 v106, s0, v22
	v_lshlrev_b32_e32 v127, 2, v19
	v_cndmask_b32_e64 v19, v219, v221, s[38:39]
	v_cmp_eq_u32_e64 s[38:39], 1, v22
	v_cmp_eq_u32_e64 s[40:41], 2, v22
	v_cmp_eq_u32_e64 s[42:43], 3, v22
	v_cmp_eq_u32_e64 s[44:45], 4, v22
	v_cmp_eq_u32_e64 s[46:47], 5, v22
	v_cmp_eq_u32_e64 s[48:49], 6, v22
	v_cmp_eq_u32_e64 s[50:51], 7, v22
	v_lshl_add_u64 v[22:23], s[12:13], 0, v[20:21]
	s_mov_b64 s[0:1], 0x7b00000
	v_ashrrev_i32_e32 v103, 31, v102
	v_lshl_add_u64 v[110:111], v[22:23], 0, s[0:1]
	v_lshlrev_b64 v[22:23], 5, v[102:103]
	v_lshl_add_u64 v[22:23], v[22:23], 0, v[0:1]
	v_lshlrev_b64 v[114:115], 11, v[102:103]
	v_lshlrev_b64 v[116:117], 12, v[102:103]
	v_ashrrev_i32_e32 v107, 31, v106
	v_lshlrev_b32_e32 v128, 2, v19
	v_add_u32_e32 v129, 16, v18
	v_lshl_add_u64 v[112:113], v[22:23], 0, s[4:5]
	v_or_b32_e32 v114, v114, v20
	v_or_b32_e32 v116, v116, v18
	s_mov_b64 s[14:15], 0
	v_lshlrev_b32_e32 v0, 2, v0
	s_branch .LBB0_1032
.LBB0_1030:
	s_or_b64 exec, exec, s[24:25]
	v_max_f32_e32 v18, v18, v18
	v_max_f32_e32 v18, 0, v18
	v_add_f32_e32 v20, v18, v19
	v_lshlrev_b64 v[18:19], 5, v[118:119]
	v_lshl_add_u64 v[18:19], v[108:109], 0, v[18:19]
	global_store_dword v[18:19], v20, off

.LBB0_1032:
	v_lshl_add_u64 v[18:19], s[12:13], 0, v[116:117]
	v_add_co_u32_e64 v18, s[54:55], s79, v18
	v_ashrrev_i32_e32 v20, 11, v102
	s_nop 0
	v_addc_co_u32_e64 v19, s[54:55], 0, v19, s[54:55]
	s_waitcnt lgkmcnt(0)
	global_load_dwordx4 v[22:25], v[18:19], off
	global_load_dwordx4 v[82:85], v[18:19], off offset:1024
	global_load_dwordx4 v[70:73], v[18:19], off offset:2048
	global_load_dwordx4 v[66:69], v[18:19], off offset:3072
	v_lshl_add_u64 v[18:19], s[12:13], 0, v[114:115]
	v_mul_i32_i24_e32 v20, 0x2400, v20
	v_add_co_u32_e64 v120, s[54:55], s20, v18
	v_ashrrev_i32_e32 v21, 31, v20
	s_nop 0
	v_addc_co_u32_e64 v121, s[54:55], 0, v19, s[54:55]
	v_lshl_add_u64 v[18:19], v[20:21], 2, s[8:9]
	v_lshl_add_u64 v[38:39], v[18:19], 0, v[0:1]
	s_movk_i32 s0, 0x4000
	v_add_co_u32_e64 v18, s[54:55], s0, v38
	v_add_u32_e32 v118, 0x2400, v102
	s_nop 0
	v_addc_co_u32_e64 v19, s[54:55], 0, v39, s[54:55]
	v_min_i32_e32 v26, 0x4000, v118
	v_add_co_u32_e64 v20, s[54:55], s2, v38
	v_ashrrev_i32_e32 v30, 11, v26
	global_load_dwordx4 v[26:29], v[18:19], off
	v_addc_co_u32_e64 v21, s[54:55], 0, v39, s[54:55]
	global_load_dwordx4 v[34:37], v[20:21], off
	v_mul_i32_i24_e32 v40, 0x2400, v30
	v_ashrrev_i32_e32 v119, 31, v118
	v_lshlrev_b64 v[18:19], 12, v[118:119]
	s_mov_b64 s[4:5], 0x4000
	v_lshl_add_u64 v[18:19], v[104:105], 0, v[18:19]
	s_mov_b64 s[22:23], 0x3000
	v_ashrrev_i32_e32 v41, 31, v40
	v_lshl_add_u64 v[40:41], v[40:41], 2, s[8:9]
	v_lshl_add_u64 v[40:41], v[40:41], 0, v[0:1]
	v_lshl_add_u64 v[130:131], v[40:41], 0, s[22:23]
	s_waitcnt vmcnt(0) lgkmcnt(0)
	v_mov_b32_e32 v42, v23
	v_mov_b32_e32 v43, v83
	v_mov_b32_e32 v32, v22
	v_mov_b32_e32 v33, v82
	v_mov_b32_e32 v50, v71
	v_mov_b32_e32 v51, v67
	v_pk_mul_f32 v[42:43], v[42:43], v[42:43]
	v_mov_b32_e32 v20, v24
	v_mov_b32_e32 v21, v84
	v_mov_b32_e32 v48, v70
	v_mov_b32_e32 v49, v66
	v_pk_mul_f32 v[50:51], v[50:51], v[50:51]
	v_pk_fma_f32 v[32:33], v[32:33], v[32:33], v[42:43]
	v_mov_b32_e32 v30, v25
	v_mov_b32_e32 v31, v85
	v_mov_b32_e32 v44, v72
	v_mov_b32_e32 v45, v68
	v_pk_fma_f32 v[42:43], v[48:49], v[48:49], v[50:51]
	v_pk_fma_f32 v[20:21], v[20:21], v[20:21], v[32:33]
	v_mov_b32_e32 v46, v73
	v_mov_b32_e32 v47, v69
	v_pk_fma_f32 v[32:33], v[44:45], v[44:45], v[42:43]
	v_pk_fma_f32 v[20:21], v[30:31], v[30:31], v[20:21]
	v_pk_fma_f32 v[30:31], v[46:47], v[46:47], v[32:33]
	v_add_f32_e32 v20, v20, v21
	v_add_f32_e32 v20, v20, v30
	v_add_f32_e32 v46, v20, v31
	ds_bpermute_b32 v47, v123, v46
	global_load_dwordx4 v[54:57], v[18:19], off
	global_load_dwordx4 v[42:45], v[18:19], off offset:1024
	global_load_dwordx4 v[30:33], v[18:19], off offset:2048
	s_nop 0
	global_load_dwordx4 v[18:21], v[18:19], off offset:3072
	v_pk_add_f32 v[26:27], v[26:27], 1.0 op_sel_hi:[1,0]
	v_pk_add_f32 v[28:29], v[28:29], 1.0 op_sel_hi:[1,0]
	s_waitcnt lgkmcnt(0)
	v_add_f32_e32 v48, v46, v47
	v_lshl_add_u64 v[46:47], v[38:39], 0, s[4:5]
	v_lshl_add_u64 v[38:39], v[38:39], 0, s[22:23]
	global_load_dwordx4 v[98:101], v[46:47], off offset:1024
	global_load_dwordx4 v[86:89], v[46:47], off offset:2048
	global_load_dwordx4 v[94:97], v[38:39], off offset:1024
	global_load_dwordx4 v[74:77], v[46:47], off offset:3072
	ds_bpermute_b32 v49, v124, v48
	global_load_dwordx4 v[90:93], v[38:39], off offset:2048
	global_load_dwordx4 v[78:81], v[38:39], off offset:3072
	v_lshl_add_u64 v[38:39], v[40:41], 0, s[4:5]
	s_waitcnt lgkmcnt(0)
	v_add_f32_e32 v48, v48, v49
	ds_bpermute_b32 v49, v125, v48
	s_waitcnt lgkmcnt(0)
	v_add_f32_e32 v46, v48, v49
	ds_bpermute_b32 v47, v126, v46
	s_waitcnt lgkmcnt(0)
	v_add_f32_e32 v48, v46, v47
	ds_bpermute_b32 v49, v127, v48
	v_add_co_u32_e64 v46, s[54:55], s0, v40
	s_waitcnt lgkmcnt(0)
	v_add_f32_e32 v48, v48, v49
	ds_bpermute_b32 v49, v128, v48
	v_addc_co_u32_e64 v47, s[54:55], 0, v41, s[54:55]
	v_add_co_u32_e64 v40, s[54:55], s2, v40
	s_waitcnt lgkmcnt(0)
	v_add_f32_e32 v48, v48, v49
	v_addc_co_u32_e64 v41, s[54:55], 0, v41, s[54:55]
	v_fmamk_f32 v48, v48, 0x3a800000, v162
	v_mul_f32_e32 v49, 0x4b800000, v48
	v_cmp_gt_f32_e64 s[54:55], s18, v48
	global_load_dwordx4 v[58:61], v[46:47], off
	global_load_dwordx4 v[62:65], v[40:41], off
	v_cndmask_b32_e64 v48, v48, v49, s[54:55]
	v_rsq_f32_e32 v48, v48
	s_waitcnt vmcnt(0)
	v_pk_add_f32 v[98:99], v[98:99], 1.0 op_sel_hi:[1,0]
	v_mul_f32_e32 v40, 0x45800000, v48
	v_cndmask_b32_e64 v122, v48, v40, s[54:55]
	v_pk_mul_f32 v[22:23], v[22:23], v[122:123] op_sel_hi:[1,0]
	v_pk_mul_f32 v[24:25], v[24:25], v[122:123] op_sel_hi:[1,0]
	v_pk_mul_f32 v[22:23], v[2:3], v[22:23]
	v_pk_mul_f32 v[24:25], v[4:5], v[24:25]
	v_pk_fma_f32 v[142:143], v[26:27], v[22:23], v[34:35]
	v_pk_fma_f32 v[144:145], v[28:29], v[24:25], v[36:37]
	v_cvt_pk_bf16_f32 v132, v142, v143
	v_cvt_pk_bf16_f32 v133, v144, v145
	global_load_dwordx4 v[46:49], v[38:39], off offset:1024
	global_load_dwordx4 v[34:37], v[38:39], off offset:2048
	global_load_dwordx4 v[22:25], v[38:39], off offset:3072
	global_load_dwordx4 v[50:53], v[130:131], off offset:1024
	s_nop 0
	global_load_dwordx4 v[38:41], v[130:131], off offset:2048
	global_load_dwordx4 v[26:29], v[130:131], off offset:3072
	v_pk_mul_f32 v[82:83], v[82:83], v[122:123] op_sel_hi:[1,0]
	global_store_dwordx2 v[120:121], v[132:133], off
	ds_read_b128 v[130:133], v129
	ds_read_b128 v[134:137], v129 offset:4096
	v_pk_mul_f32 v[82:83], v[6:7], v[82:83]
	v_pk_add_f32 v[100:101], v[100:101], 1.0 op_sel_hi:[1,0]
	v_pk_fma_f32 v[98:99], v[98:99], v[82:83], v[94:95]
	s_waitcnt lgkmcnt(0)
	v_mul_f32_e32 v103, v131, v143
	v_fmac_f32_e32 v103, v130, v142
	v_mul_f32_e32 v130, v135, v143
	v_fmac_f32_e32 v130, v134, v142
	v_fmac_f32_e32 v103, v132, v144
	v_fmac_f32_e32 v130, v136, v144
	v_fmac_f32_e32 v103, v133, v145
	v_fmac_f32_e32 v130, v137, v145
	ds_read_b128 v[132:135], v129 offset:8192
	ds_read_b128 v[136:139], v129 offset:12288
	v_pk_mul_f32 v[82:83], v[84:85], v[122:123] op_sel_hi:[1,0]
	v_pk_mul_f32 v[70:71], v[70:71], v[122:123] op_sel_hi:[1,0]
	v_pk_mul_f32 v[82:83], v[8:9], v[82:83]
	s_waitcnt lgkmcnt(0)
	v_mul_f32_e32 v131, v133, v143
	v_mul_f32_e32 v140, v137, v143
	v_fmac_f32_e32 v131, v132, v142
	v_fmac_f32_e32 v140, v136, v142
	v_fmac_f32_e32 v131, v134, v144
	v_fmac_f32_e32 v140, v138, v144
	v_fmac_f32_e32 v131, v135, v145
	v_fmac_f32_e32 v140, v139, v145
	ds_read_b128 v[132:135], v129 offset:16384
	ds_read_b128 v[136:139], v129 offset:20480
	v_pk_fma_f32 v[100:101], v[100:101], v[82:83], v[96:97]
	v_cvt_pk_bf16_f32 v82, v98, v99
	v_cvt_pk_bf16_f32 v83, v100, v101
	s_waitcnt lgkmcnt(0)
	v_mul_f32_e32 v141, v133, v143
	v_mul_f32_e32 v146, v137, v143
	v_fmac_f32_e32 v141, v132, v142
	v_fmac_f32_e32 v146, v136, v142
	v_fmac_f32_e32 v141, v134, v144
	v_fmac_f32_e32 v146, v138, v144
	v_fmac_f32_e32 v141, v135, v145
	v_fmac_f32_e32 v146, v139, v145
	ds_read_b128 v[132:135], v129 offset:24576
	ds_read_b128 v[136:139], v129 offset:28672
	global_store_dwordx2 v[120:121], v[82:83], off offset:512
	ds_read_b128 v[82:85], v129 offset:1024
	ds_read_b128 v[94:97], v129 offset:5120
	v_pk_mul_f32 v[70:71], v[10:11], v[70:71]
	s_waitcnt lgkmcnt(0)
	v_mul_f32_e32 v133, v133, v143
	v_fmac_f32_e32 v133, v132, v142
	v_fmac_f32_e32 v133, v134, v144
	v_fmac_f32_e32 v133, v135, v145
	v_mul_f32_e32 v134, v99, v83
	v_mul_f32_e32 v135, v99, v95
	v_fmac_f32_e32 v134, v98, v82
	v_fmac_f32_e32 v135, v98, v94
	v_fmac_f32_e32 v134, v100, v84
	v_fmac_f32_e32 v135, v100, v96
	v_fmac_f32_e32 v134, v101, v85
	v_fmac_f32_e32 v135, v101, v97
	ds_read_b128 v[82:85], v129 offset:9216
	ds_read_b128 v[94:97], v129 offset:13312
	v_mul_f32_e32 v132, v137, v143
	v_fmac_f32_e32 v132, v136, v142
	v_fmac_f32_e32 v132, v138, v144
	s_waitcnt lgkmcnt(0)
	v_mul_f32_e32 v136, v99, v83
	v_mul_f32_e32 v137, v99, v95
	v_fmac_f32_e32 v136, v98, v82
	v_fmac_f32_e32 v137, v98, v94
	v_fmac_f32_e32 v136, v100, v84
	v_fmac_f32_e32 v137, v100, v96
	v_fmac_f32_e32 v136, v101, v85
	v_fmac_f32_e32 v137, v101, v97
	ds_read_b128 v[82:85], v129 offset:17408
	ds_read_b128 v[94:97], v129 offset:21504
	v_fmac_f32_e32 v132, v139, v145
	v_pk_mul_f32 v[66:67], v[66:67], v[122:123] op_sel_hi:[1,0]
	v_pk_add_f32 v[74:75], v[74:75], 1.0 op_sel_hi:[1,0]
	s_waitcnt lgkmcnt(0)
	v_mul_f32_e32 v138, v99, v83
	v_mul_f32_e32 v139, v99, v95
	v_fmac_f32_e32 v138, v98, v82
	v_fmac_f32_e32 v139, v98, v94
	v_fmac_f32_e32 v138, v100, v84
	v_fmac_f32_e32 v139, v100, v96
	v_fmac_f32_e32 v138, v101, v85
	v_fmac_f32_e32 v139, v101, v97
	ds_read_b128 v[82:85], v129 offset:25600
	ds_read_b128 v[94:97], v129 offset:29696
	v_pk_mul_f32 v[66:67], v[14:15], v[66:67]
	s_waitcnt lgkmcnt(0)
	v_mul_f32_e32 v142, v99, v83
	v_fmac_f32_e32 v142, v98, v82
	v_pk_add_f32 v[82:83], v[86:87], 1.0 op_sel_hi:[1,0]
	v_fmac_f32_e32 v142, v100, v84
	v_pk_fma_f32 v[90:91], v[82:83], v[70:71], v[90:91]
	v_pk_mul_f32 v[70:71], v[72:73], v[122:123] op_sel_hi:[1,0]
	v_fmac_f32_e32 v142, v101, v85
	v_pk_add_f32 v[84:85], v[88:89], 1.0 op_sel_hi:[1,0]
	v_pk_mul_f32 v[70:71], v[12:13], v[70:71]
	v_cvt_pk_bf16_f32 v72, v90, v91
	v_pk_fma_f32 v[70:71], v[84:85], v[70:71], v[92:93]
	v_mul_f32_e32 v95, v99, v95
	v_cvt_pk_bf16_f32 v73, v70, v71
	global_store_dwordx2 v[120:121], v[72:73], off offset:1024
	ds_read_b128 v[82:85], v129 offset:2048
	ds_read_b128 v[86:89], v129 offset:6144
	v_fmac_f32_e32 v95, v98, v94
	v_fmac_f32_e32 v95, v100, v96
	v_fmac_f32_e32 v95, v101, v97
	s_waitcnt lgkmcnt(0)
	v_mul_f32_e32 v92, v91, v83
	v_mul_f32_e32 v93, v91, v87
	v_fmac_f32_e32 v92, v90, v82
	v_fmac_f32_e32 v93, v90, v86
	v_fmac_f32_e32 v92, v70, v84
	v_fmac_f32_e32 v93, v70, v88
	v_fmac_f32_e32 v92, v71, v85
	v_fmac_f32_e32 v93, v71, v89
	ds_read_b128 v[82:85], v129 offset:10240
	ds_read_b128 v[86:89], v129 offset:14336
	v_pk_mul_f32 v[72:73], v[42:43], v[42:43]
	v_pk_fma_f32 v[78:79], v[74:75], v[66:67], v[78:79]
	v_pk_mul_f32 v[66:67], v[68:69], v[122:123] op_sel_hi:[1,0]
	s_waitcnt lgkmcnt(0)
	v_mul_f32_e32 v94, v91, v83
	v_mul_f32_e32 v96, v91, v87
	v_fmac_f32_e32 v94, v90, v82
	v_fmac_f32_e32 v96, v90, v86
	v_fmac_f32_e32 v94, v70, v84
	v_fmac_f32_e32 v96, v70, v88
	v_fmac_f32_e32 v94, v71, v85
	v_fmac_f32_e32 v96, v71, v89
	ds_read_b128 v[82:85], v129 offset:18432
	ds_read_b128 v[86:89], v129 offset:22528
	v_pk_mul_f32 v[66:67], v[16:17], v[66:67]
	v_pk_add_f32 v[68:69], v[76:77], 1.0 op_sel_hi:[1,0]
	v_add_f32_e32 v100, 0, v146
	s_waitcnt lgkmcnt(0)
	v_mul_f32_e32 v97, v91, v83
	v_mul_f32_e32 v98, v91, v87
	v_fmac_f32_e32 v97, v90, v82
	v_fmac_f32_e32 v98, v90, v86
	v_fmac_f32_e32 v97, v70, v84
	v_fmac_f32_e32 v98, v70, v88
	v_fmac_f32_e32 v97, v71, v85
	v_fmac_f32_e32 v98, v71, v89
	ds_read_b128 v[82:85], v129 offset:26624
	ds_read_b128 v[86:89], v129 offset:30720
	v_pk_fma_f32 v[80:81], v[68:69], v[66:67], v[80:81]
	v_cvt_pk_bf16_f32 v66, v78, v79
	v_cvt_pk_bf16_f32 v67, v80, v81
	s_waitcnt lgkmcnt(0)
	v_mul_f32_e32 v83, v91, v83
	v_fmac_f32_e32 v83, v90, v82
	v_add_f32_e32 v82, v72, v73
	v_pk_mul_f32 v[72:73], v[44:45], v[44:45]
	v_fmac_f32_e32 v83, v70, v84
	v_add_f32_e32 v72, v82, v72
	v_add_f32_e32 v82, v72, v73
	v_pk_mul_f32 v[72:73], v[54:55], v[54:55]
	v_fmac_f32_e32 v83, v71, v85
	v_add_f32_e32 v84, v72, v73
	v_pk_mul_f32 v[72:73], v[56:57], v[56:57]
	global_store_dwordx2 v[120:121], v[66:67], off offset:1536
	v_add_f32_e32 v72, v84, v72
	v_add_f32_e32 v84, v72, v73
	v_pk_mul_f32 v[72:73], v[30:31], v[30:31]
	ds_read_b128 v[66:69], v129 offset:3072
	ds_read_b128 v[74:77], v129 offset:7168
	v_add_f32_e32 v85, v72, v73
	v_pk_mul_f32 v[72:73], v[32:33], v[32:33]
	v_mul_f32_e32 v87, v91, v87
	v_add_f32_e32 v72, v85, v72
	v_add_f32_e32 v85, v72, v73
	v_pk_mul_f32 v[72:73], v[18:19], v[18:19]
	s_waitcnt lgkmcnt(0)
	v_mul_f32_e32 v67, v79, v67
	v_add_f32_e32 v99, v72, v73
	v_pk_mul_f32 v[72:73], v[20:21], v[20:21]
	v_fmac_f32_e32 v67, v78, v66
	v_add_f32_e32 v72, v99, v72
	v_add_f32_e32 v72, v72, v73
	v_add_f32_e32 v73, v84, v82
	v_add_f32_e32 v73, v73, v85
	v_add_f32_e32 v72, v73, v72
	ds_bpermute_b32 v73, v123, v72
	v_fmac_f32_e32 v87, v90, v86
	v_fmac_f32_e32 v67, v80, v68
	v_fmac_f32_e32 v87, v70, v88
	v_fmac_f32_e32 v67, v81, v69
	s_waitcnt lgkmcnt(0)
	v_add_f32_e32 v72, v72, v73
	ds_bpermute_b32 v73, v124, v72
	v_fmac_f32_e32 v87, v71, v89
	v_mul_f32_e32 v75, v79, v75
	v_add_f32_e32 v82, 0, v130
	v_fmac_f32_e32 v75, v78, v74
	s_waitcnt lgkmcnt(0)
	v_add_f32_e32 v72, v72, v73
	ds_bpermute_b32 v73, v125, v72
	v_add_f32_e32 v82, v82, v135
	v_fmac_f32_e32 v75, v80, v76
	v_add_f32_e32 v82, v82, v93
	v_fmac_f32_e32 v75, v81, v77
	s_waitcnt lgkmcnt(0)
	v_add_f32_e32 v72, v72, v73
	ds_bpermute_b32 v73, v126, v72
	v_add_f32_e32 v82, v82, v75
	ds_read_b128 v[74:77], v129 offset:15360
	v_add_f32_e32 v84, 0, v131
	v_add_f32_e32 v84, v84, v136
	s_waitcnt lgkmcnt(0)
	v_add_f32_e32 v72, v72, v73
	ds_bpermute_b32 v73, v127, v72
	v_add_f32_e32 v84, v84, v94
	v_mul_f32_e32 v75, v79, v75
	v_add_f32_e32 v85, 0, v140
	v_fmac_f32_e32 v75, v78, v74
	s_waitcnt lgkmcnt(0)
	v_add_f32_e32 v72, v72, v73
	v_add_f32_e32 v73, 0, v103
	v_add_f32_e32 v73, v73, v134
	v_add_f32_e32 v92, v73, v92
	v_add_f32_e32 v71, v92, v67
	ds_read_b128 v[66:69], v129 offset:11264
	v_add_f32_e32 v85, v85, v137
	v_fmac_f32_e32 v75, v80, v76
	v_add_f32_e32 v85, v85, v96
	v_fmac_f32_e32 v75, v81, v77
	s_waitcnt lgkmcnt(0)
	v_mul_f32_e32 v67, v79, v67
	v_fmac_f32_e32 v67, v78, v66
	v_fmac_f32_e32 v67, v80, v68
	v_fmac_f32_e32 v67, v81, v69
	v_add_f32_e32 v84, v84, v67
	ds_read_b128 v[66:69], v129 offset:19456
	v_add_f32_e32 v85, v85, v75
	ds_read_b128 v[74:77], v129 offset:23552
	v_add_f32_e32 v99, 0, v141
	v_add_f32_e32 v99, v99, v138
	s_waitcnt lgkmcnt(0)
	v_mul_f32_e32 v67, v79, v67
	v_fmac_f32_e32 v67, v78, v66
	v_fmac_f32_e32 v67, v80, v68
	v_add_f32_e32 v93, v99, v97
	v_fmac_f32_e32 v67, v81, v69
	v_add_f32_e32 v86, v93, v67
	ds_read_b128 v[66:69], v129 offset:27648
	v_mul_f32_e32 v75, v79, v75
	v_fmac_f32_e32 v75, v78, v74
	v_add_f32_e32 v100, v100, v139
	v_add_f32_e32 v103, 0, v132
	v_fmac_f32_e32 v75, v80, v76
	ds_bpermute_b32 v88, v123, v71
	v_add_f32_e32 v95, v103, v95
	v_add_f32_e32 v94, v100, v98
	v_fmac_f32_e32 v75, v81, v77
	v_add_f32_e32 v70, v95, v87
	v_add_f32_e32 v87, v94, v75
	ds_read_b128 v[74:77], v129 offset:31744
	s_waitcnt lgkmcnt(0)
	v_mul_f32_e32 v67, v79, v67
	v_add_f32_e32 v101, 0, v133
	v_fmac_f32_e32 v67, v78, v66
	v_add_f32_e32 v101, v101, v142
	v_fmac_f32_e32 v67, v80, v68
	v_add_f32_e32 v83, v101, v83
	v_fmac_f32_e32 v67, v81, v69
	v_add_f32_e32 v66, v71, v88
	ds_bpermute_b32 v68, v124, v66
	v_add_f32_e32 v83, v83, v67
	ds_bpermute_b32 v67, v123, v82
	v_mul_f32_e32 v69, v79, v75
	v_fmac_f32_e32 v69, v78, v74
	s_waitcnt lgkmcnt(0)
	v_add_f32_e32 v66, v66, v68
	ds_bpermute_b32 v68, v125, v66
	v_add_f32_e32 v67, v82, v67
	ds_bpermute_b32 v71, v124, v67
	v_fmac_f32_e32 v69, v80, v76
	v_fmac_f32_e32 v69, v81, v77
	s_waitcnt lgkmcnt(0)
	v_add_f32_e32 v66, v66, v68
	v_add_f32_e32 v78, v70, v69
	v_add_f32_e32 v67, v67, v71
	ds_bpermute_b32 v69, v123, v84
	ds_bpermute_b32 v68, v126, v66
	ds_bpermute_b32 v71, v125, v67
	ds_bpermute_b32 v81, v123, v78
	ds_bpermute_b32 v73, v128, v72
	s_waitcnt lgkmcnt(0)
	v_add_f32_e32 v69, v84, v69
	v_add_f32_e32 v66, v66, v68
	v_add_f32_e32 v70, v67, v71
	ds_bpermute_b32 v74, v124, v69
	ds_bpermute_b32 v68, v127, v66
	ds_bpermute_b32 v71, v126, v70
	v_add_f32_e32 v78, v78, v81
	ds_bpermute_b32 v81, v124, v78
	s_waitcnt lgkmcnt(0)
	v_add_f32_e32 v69, v69, v74
	v_add_f32_e32 v66, v66, v68
	v_add_f32_e32 v68, v70, v71
	ds_bpermute_b32 v70, v123, v85
	ds_bpermute_b32 v71, v125, v69
	ds_bpermute_b32 v74, v123, v86
	ds_bpermute_b32 v75, v127, v68
	v_add_f32_e32 v78, v78, v81
	s_waitcnt lgkmcnt(0)
	v_add_f32_e32 v70, v85, v70
	v_add_f32_e32 v69, v69, v71
	v_add_f32_e32 v71, v86, v74
	ds_bpermute_b32 v76, v124, v70
	ds_bpermute_b32 v74, v124, v71
	ds_bpermute_b32 v77, v126, v69
	v_add_f32_e32 v68, v68, v75
	ds_bpermute_b32 v81, v125, v78
	s_waitcnt lgkmcnt(0)
	v_add_f32_e32 v70, v70, v76
	v_add_f32_e32 v71, v71, v74
	ds_bpermute_b32 v76, v125, v70
	ds_bpermute_b32 v74, v125, v71
	v_add_f32_e32 v75, v69, v77
	ds_bpermute_b32 v77, v127, v75
	v_add_f32_e32 v78, v78, v81
	s_waitcnt lgkmcnt(0)
	v_add_f32_e32 v70, v70, v76
	v_add_f32_e32 v71, v71, v74
	ds_bpermute_b32 v76, v126, v70
	ds_bpermute_b32 v74, v126, v71
	ds_bpermute_b32 v81, v126, v78
	ds_bpermute_b32 v67, v128, v66
	ds_bpermute_b32 v69, v128, v68
	s_waitcnt lgkmcnt(0)
	v_add_f32_e32 v76, v70, v76
	v_add_f32_e32 v70, v75, v77
	v_add_f32_e32 v77, v71, v74
	ds_bpermute_b32 v79, v127, v76
	ds_bpermute_b32 v80, v127, v77
	v_add_f32_e32 v84, v78, v81
	ds_bpermute_b32 v85, v127, v84
	ds_bpermute_b32 v71, v128, v70
	s_waitcnt lgkmcnt(0)
	v_add_f32_e32 v74, v76, v79
	ds_bpermute_b32 v79, v123, v87
	v_add_f32_e32 v76, v77, v80
	ds_bpermute_b32 v80, v123, v83
	ds_bpermute_b32 v75, v128, v74
	ds_bpermute_b32 v77, v128, v76
	s_waitcnt lgkmcnt(0)
	v_add_f32_e32 v79, v87, v79
	ds_bpermute_b32 v82, v124, v79
	v_add_f32_e32 v80, v83, v80
	ds_bpermute_b32 v83, v124, v80
	s_waitcnt lgkmcnt(0)
	v_add_f32_e32 v79, v79, v82
	ds_bpermute_b32 v82, v125, v79
	v_add_f32_e32 v80, v80, v83
	ds_bpermute_b32 v83, v125, v80
	s_waitcnt lgkmcnt(0)
	v_add_f32_e32 v79, v79, v82
	ds_bpermute_b32 v82, v126, v79
	v_add_f32_e32 v80, v80, v83
	ds_bpermute_b32 v83, v126, v80
	s_waitcnt lgkmcnt(0)
	v_add_f32_e32 v79, v79, v82
	ds_bpermute_b32 v82, v127, v79
	v_add_f32_e32 v80, v80, v83
	ds_bpermute_b32 v83, v127, v80
	s_waitcnt lgkmcnt(0)
	v_add_f32_e32 v78, v79, v82
	v_add_f32_e32 v82, v84, v85
	v_add_f32_e32 v80, v80, v83
	ds_bpermute_b32 v79, v128, v78
	ds_bpermute_b32 v81, v128, v80
	ds_bpermute_b32 v83, v128, v82
	s_and_saveexec_b64 s[22:23], vcc
	s_cbranch_execz .LBB0_1038
	v_mov_b32_e32 v84, s64
	v_mov_b32_e32 v85, s65
	v_add_f32_e32 v68, v68, v69
	v_readfirstlane_b32 s0, v84
	v_readfirstlane_b32 s1, v85
	v_add_f32_e32 v66, v66, v67
	v_mov_b32_e32 v84, s0
	v_mov_b32_e32 v85, s1
	global_load_dwordx2 v[84:85], v[84:85], off offset:152
	s_waitcnt vmcnt(0) lgkmcnt(0)
	v_add_f32_e32 v70, v70, v71
	v_readfirstlane_b32 s0, v84
	v_readfirstlane_b32 s1, v85
	v_cndmask_b32_e64 v66, v66, v68, s[38:39]
	v_mov_b32_e32 v84, s0
	v_mov_b32_e32 v85, s1
	v_lshl_add_u64 v[84:85], v[106:107], 2, v[84:85]
	global_load_dword v84, v[84:85], off
	v_add_f32_e32 v74, v74, v75
	v_cndmask_b32_e64 v66, v66, v70, s[40:41]
	v_add_f32_e32 v76, v76, v77
	v_cndmask_b32_e64 v66, v66, v74, s[42:43]
	v_add_f32_e32 v78, v78, v79
	v_cndmask_b32_e64 v66, v66, v76, s[44:45]
	v_add_f32_e32 v80, v80, v81
	v_cndmask_b32_e64 v66, v66, v78, s[46:47]
	v_add_f32_e32 v82, v82, v83
	v_cndmask_b32_e64 v66, v66, v80, s[48:49]
	v_cndmask_b32_e64 v66, v66, v82, s[50:51]
	s_mov_b32 s0, 0xbfb8aa3b
	s_waitcnt vmcnt(0) lgkmcnt(0)
	v_add_f32_e32 v66, v66, v84
	v_mul_f32_e64 v67, |v66|, s0
	v_exp_f32_e32 v68, v67
	s_mov_b32 s0, 0x3ca3d70a
	v_cmp_ngt_f32_e64 s[54:55], s0, v68
	s_and_saveexec_b64 s[0:1], s[54:55]
	s_xor_b64 s[24:25], exec, s[0:1]
	s_cbranch_execz .LBB0_1035
	v_add_f32_e32 v67, 1.0, v68
	v_cmp_gt_f32_e64 s[54:55], s18, v67
	s_mov_b32 s0, 0x3f317217
	s_nop 0
	v_cndmask_b32_e64 v68, 0, 32, s[54:55]
	v_ldexp_f32 v67, v67, v68
	v_log_f32_e32 v67, v67
	s_nop 0
	v_mul_f32_e32 v68, 0x3f317217, v67
	v_fma_f32 v68, v67, s0, -v68
	v_fmac_f32_e32 v68, 0x3377d1cf, v67
	s_mov_b32 s0, 0x7f800000
	v_fmac_f32_e32 v68, 0x3f317217, v67
	v_cmp_lt_f32_e64 s[56:57], |v67|, s0
	s_nop 1
	v_cndmask_b32_e64 v67, v67, v68, s[56:57]
	v_cndmask_b32_e64 v68, 0, v167, s[54:55]
	v_sub_f32_e32 v67, v67, v68
.LBB0_1035:
	s_andn2_saveexec_b64 s[24:25], s[24:25]
	s_mov_b32 s0, 0xbeaaaaab
	v_fma_f32 v67, v68, s0, 0.5
	v_fma_f32 v67, -v68, v67, 1.0
	v_mul_f32_e32 v67, v68, v67
	s_or_b64 exec, exec, s[24:25]
	v_max_f32_e32 v66, v66, v66
	v_max_f32_e32 v66, 0, v66
	v_add_f32_e32 v68, v66, v67
	v_lshl_add_u64 v[66:67], s[12:13], 0, v[112:113]
	global_store_dword v[66:67], v68, off
.LBB0_1038:
	s_or_b64 exec, exec, s[22:23]
	v_add_f32_e32 v66, v72, v73
	v_fmamk_f32 v66, v66, 0x3a800000, v162
	v_mul_f32_e32 v67, 0x4b800000, v66
	v_cmp_gt_f32_e64 s[54:55], s18, v66
	v_pk_add_f32 v[68:69], v[58:59], 1.0 op_sel_hi:[1,0]
	s_waitcnt vmcnt(0)
	v_pk_add_f32 v[46:47], v[46:47], 1.0 op_sel_hi:[1,0]
	v_cndmask_b32_e64 v66, v66, v67, s[54:55]
	v_rsq_f32_e32 v70, v66
	v_lshlrev_b64 v[66:67], 11, v[118:119]
	v_pk_add_f32 v[34:35], v[34:35], 1.0 op_sel_hi:[1,0]
	v_pk_add_f32 v[22:23], v[22:23], 1.0 op_sel_hi:[1,0]
	v_mul_f32_e32 v58, 0x45800000, v70
	v_cndmask_b32_e64 v58, v70, v58, s[54:55]
	v_pk_mul_f32 v[54:55], v[54:55], v[58:59] op_sel_hi:[1,0]
	s_nop 0
	v_pk_mul_f32 v[54:55], v[2:3], v[54:55]
	s_nop 0
	v_pk_fma_f32 v[62:63], v[68:69], v[54:55], v[62:63]
	v_pk_mul_f32 v[54:55], v[56:57], v[58:59] op_sel_hi:[1,0]
	v_pk_add_f32 v[56:57], v[60:61], 1.0 op_sel_hi:[1,0]
	v_pk_mul_f32 v[54:55], v[4:5], v[54:55]
	v_cvt_pk_bf16_f32 v60, v62, v63
	v_pk_fma_f32 v[56:57], v[56:57], v[54:55], v[64:65]
	v_lshl_add_u64 v[54:55], v[110:111], 0, v[66:67]
	v_cvt_pk_bf16_f32 v61, v56, v57
	global_store_dwordx2 v[54:55], v[60:61], off
	ds_read_b128 v[64:67], v129
	ds_read_b128 v[68:71], v129 offset:4096
	s_waitcnt lgkmcnt(0)
	v_mul_f32_e32 v59, v63, v65
	v_fmac_f32_e32 v59, v62, v64
	v_fmac_f32_e32 v59, v56, v66
	v_fmac_f32_e32 v59, v57, v67
	ds_read_b128 v[64:67], v129 offset:8192
	v_mul_f32_e32 v60, v63, v69
	v_fmac_f32_e32 v60, v62, v68
	v_fmac_f32_e32 v60, v56, v70
	v_fmac_f32_e32 v60, v57, v71
	ds_read_b128 v[68:71], v129 offset:12288
	v_add_f32_e32 v72, 0, v60
	s_waitcnt lgkmcnt(0)
	v_mul_f32_e32 v60, v63, v65
	v_fmac_f32_e32 v60, v62, v64
	v_fmac_f32_e32 v60, v56, v66
	v_fmac_f32_e32 v60, v57, v67
	ds_read_b128 v[64:67], v129 offset:16384
	v_add_f32_e32 v73, 0, v60
	v_mul_f32_e32 v60, v63, v69
	v_fmac_f32_e32 v60, v62, v68
	v_fmac_f32_e32 v60, v56, v70
	v_fmac_f32_e32 v60, v57, v71
	ds_read_b128 v[68:71], v129 offset:20480
	v_add_f32_e32 v74, 0, v60
	s_waitcnt lgkmcnt(0)
	v_mul_f32_e32 v60, v63, v65
	v_fmac_f32_e32 v60, v62, v64
	v_fmac_f32_e32 v60, v56, v66
	v_fmac_f32_e32 v60, v57, v67
	ds_read_b128 v[64:67], v129 offset:24576
	v_add_f32_e32 v75, 0, v60
	v_mul_f32_e32 v60, v63, v69
	v_fmac_f32_e32 v60, v62, v68
	v_fmac_f32_e32 v60, v56, v70
	v_add_f32_e32 v59, 0, v59
	v_fmac_f32_e32 v60, v57, v71
	ds_read_b128 v[68:71], v129 offset:28672
	v_add_f32_e32 v76, 0, v60
	s_waitcnt lgkmcnt(0)
	v_mul_f32_e32 v60, v63, v65
	v_pk_mul_f32 v[42:43], v[42:43], v[58:59] op_sel_hi:[1,0]
	v_fmac_f32_e32 v60, v62, v64
	v_pk_mul_f32 v[42:43], v[6:7], v[42:43]
	v_fmac_f32_e32 v60, v56, v66
	v_pk_fma_f32 v[46:47], v[46:47], v[42:43], v[50:51]
	v_pk_mul_f32 v[42:43], v[44:45], v[58:59] op_sel_hi:[1,0]
	v_fmac_f32_e32 v60, v57, v67
	v_pk_mul_f32 v[42:43], v[8:9], v[42:43]
	v_pk_add_f32 v[44:45], v[48:49], 1.0 op_sel_hi:[1,0]
	v_add_f32_e32 v64, 0, v60
	v_mul_f32_e32 v60, v63, v69
	v_pk_fma_f32 v[42:43], v[44:45], v[42:43], v[52:53]
	v_fmac_f32_e32 v60, v62, v68
	v_cvt_pk_bf16_f32 v44, v46, v47
	v_cvt_pk_bf16_f32 v45, v42, v43
	global_store_dwordx2 v[54:55], v[44:45], off offset:512
	v_fmac_f32_e32 v60, v56, v70
	ds_read_b128 v[48:51], v129 offset:1024
	v_fmac_f32_e32 v60, v57, v71
	v_add_f32_e32 v44, 0, v60
	ds_read_b128 v[60:63], v129 offset:5120
	s_waitcnt lgkmcnt(0)
	v_mul_f32_e32 v45, v47, v49
	v_fmac_f32_e32 v45, v46, v48
	v_fmac_f32_e32 v45, v42, v50
	v_mul_f32_e32 v52, v47, v61
	v_fmac_f32_e32 v52, v46, v60
	v_fmac_f32_e32 v45, v43, v51
	ds_read_b128 v[48:51], v129 offset:9216
	v_fmac_f32_e32 v52, v42, v62
	v_fmac_f32_e32 v52, v43, v63
	ds_read_b128 v[60:63], v129 offset:13312
	v_add_f32_e32 v45, v59, v45
	s_waitcnt lgkmcnt(0)
	v_mul_f32_e32 v49, v47, v49
	v_fmac_f32_e32 v49, v46, v48
	v_fmac_f32_e32 v49, v42, v50
	v_mul_f32_e32 v56, v47, v61
	v_fmac_f32_e32 v56, v46, v60
	v_fmac_f32_e32 v49, v43, v51
	v_fmac_f32_e32 v56, v42, v62
	v_add_f32_e32 v53, v73, v49
	ds_read_b128 v[48:51], v129 offset:17408
	v_fmac_f32_e32 v56, v43, v63
	ds_read_b128 v[60:63], v129 offset:21504
	v_add_f32_e32 v52, v72, v52
	v_add_f32_e32 v56, v74, v56
	s_waitcnt lgkmcnt(0)
	v_mul_f32_e32 v49, v47, v49
	v_fmac_f32_e32 v49, v46, v48
	v_mul_f32_e32 v59, v47, v61
	v_fmac_f32_e32 v59, v46, v60
	v_fmac_f32_e32 v49, v42, v50
	v_fmac_f32_e32 v59, v42, v62
	v_fmac_f32_e32 v49, v43, v51
	v_fmac_f32_e32 v59, v43, v63
	v_add_f32_e32 v57, v75, v49
	ds_read_b128 v[48:51], v129 offset:25600
	ds_read_b128 v[60:63], v129 offset:29696
	v_add_f32_e32 v59, v76, v59
	v_pk_mul_f32 v[30:31], v[30:31], v[58:59] op_sel_hi:[1,0]
	v_pk_mul_f32 v[18:19], v[18:19], v[58:59] op_sel_hi:[1,0]
	v_pk_mul_f32 v[30:31], v[10:11], v[30:31]
	s_waitcnt lgkmcnt(0)
	v_mul_f32_e32 v49, v47, v49
	v_pk_fma_f32 v[34:35], v[34:35], v[30:31], v[38:39]
	v_pk_mul_f32 v[30:31], v[32:33], v[58:59] op_sel_hi:[1,0]
	v_pk_add_f32 v[32:33], v[36:37], 1.0 op_sel_hi:[1,0]
	v_pk_mul_f32 v[30:31], v[12:13], v[30:31]
	v_mul_f32_e32 v47, v47, v61
	v_pk_fma_f32 v[30:31], v[32:33], v[30:31], v[40:41]
	v_fmac_f32_e32 v49, v46, v48
	v_fmac_f32_e32 v47, v46, v60
	v_cvt_pk_bf16_f32 v32, v34, v35
	v_cvt_pk_bf16_f32 v33, v30, v31
	v_fmac_f32_e32 v49, v42, v50
	global_store_dwordx2 v[54:55], v[32:33], off offset:1024
	v_fmac_f32_e32 v47, v42, v62
	v_fmac_f32_e32 v49, v43, v51
	ds_read_b128 v[36:39], v129 offset:2048
	v_fmac_f32_e32 v47, v43, v63
	ds_read_b128 v[40:43], v129 offset:6144
	v_add_f32_e32 v32, v44, v47
	v_pk_mul_f32 v[18:19], v[14:15], v[18:19]
	s_waitcnt lgkmcnt(0)
	v_mul_f32_e32 v33, v35, v37
	v_fmac_f32_e32 v33, v34, v36
	v_mul_f32_e32 v41, v35, v41
	v_fmac_f32_e32 v41, v34, v40
	v_fmac_f32_e32 v41, v30, v42
	v_fmac_f32_e32 v33, v30, v38
	v_fmac_f32_e32 v41, v31, v43
	v_fmac_f32_e32 v33, v31, v39
	ds_read_b128 v[36:39], v129 offset:10240
	v_add_f32_e32 v44, v52, v41
	ds_read_b128 v[40:43], v129 offset:14336
	v_add_f32_e32 v33, v45, v33
	v_pk_fma_f32 v[22:23], v[22:23], v[18:19], v[26:27]
	s_waitcnt lgkmcnt(0)
	v_mul_f32_e32 v37, v35, v37
	v_fmac_f32_e32 v37, v34, v36
	v_mul_f32_e32 v41, v35, v41
	v_fmac_f32_e32 v41, v34, v40
	v_fmac_f32_e32 v37, v30, v38
	v_fmac_f32_e32 v41, v30, v42
	v_fmac_f32_e32 v37, v31, v39
	v_fmac_f32_e32 v41, v31, v43
	v_add_f32_e32 v45, v53, v37
	ds_read_b128 v[36:39], v129 offset:18432
	v_add_f32_e32 v46, v56, v41
	ds_read_b128 v[40:43], v129 offset:22528
	v_pk_mul_f32 v[18:19], v[20:21], v[58:59] op_sel_hi:[1,0]
	v_add_f32_e32 v48, v64, v49
	s_waitcnt lgkmcnt(0)
	v_mul_f32_e32 v37, v35, v37
	v_fmac_f32_e32 v37, v34, v36
	v_mul_f32_e32 v41, v35, v41
	v_fmac_f32_e32 v41, v34, v40
	v_fmac_f32_e32 v37, v30, v38
	v_fmac_f32_e32 v41, v30, v42
	v_fmac_f32_e32 v37, v31, v39
	v_fmac_f32_e32 v41, v31, v43
	v_add_f32_e32 v47, v57, v37
	ds_read_b128 v[36:39], v129 offset:26624
	v_add_f32_e32 v49, v59, v41
	ds_read_b128 v[40:43], v129 offset:30720
	v_pk_mul_f32 v[18:19], v[16:17], v[18:19]
	v_pk_add_f32 v[20:21], v[24:25], 1.0 op_sel_hi:[1,0]
	s_waitcnt lgkmcnt(0)
	v_mul_f32_e32 v37, v35, v37
	v_pk_fma_f32 v[18:19], v[20:21], v[18:19], v[28:29]
	v_cvt_pk_bf16_f32 v20, v22, v23
	v_cvt_pk_bf16_f32 v21, v18, v19
	global_store_dwordx2 v[54:55], v[20:21], off offset:1536
	ds_read_b128 v[24:27], v129 offset:3072
	v_mul_f32_e32 v35, v35, v41
	v_fmac_f32_e32 v37, v34, v36
	v_fmac_f32_e32 v35, v34, v40
	v_fmac_f32_e32 v37, v30, v38
	v_fmac_f32_e32 v35, v30, v42
	v_fmac_f32_e32 v37, v31, v39
	v_fmac_f32_e32 v35, v31, v43
	ds_read_b128 v[28:31], v129 offset:7168
	s_waitcnt lgkmcnt(0)
	v_mul_f32_e32 v21, v23, v25
	v_fmac_f32_e32 v21, v22, v24
	v_fmac_f32_e32 v21, v18, v26
	v_fmac_f32_e32 v21, v19, v27
	ds_read_b128 v[24:27], v129 offset:11264
	v_mul_f32_e32 v29, v23, v29
	v_fmac_f32_e32 v29, v22, v28
	v_fmac_f32_e32 v29, v18, v30
	v_fmac_f32_e32 v29, v19, v31
	v_add_f32_e32 v20, v32, v35
	v_add_f32_e32 v32, v44, v29
	ds_read_b128 v[28:31], v129 offset:15360
	s_waitcnt lgkmcnt(0)
	v_mul_f32_e32 v25, v23, v25
	v_fmac_f32_e32 v25, v22, v24
	v_fmac_f32_e32 v25, v18, v26
	v_fmac_f32_e32 v25, v19, v27
	v_add_f32_e32 v21, v33, v21
	v_add_f32_e32 v33, v45, v25
	ds_read_b128 v[24:27], v129 offset:19456
	v_mul_f32_e32 v29, v23, v29
	v_fmac_f32_e32 v29, v22, v28
	v_fmac_f32_e32 v29, v18, v30
	v_fmac_f32_e32 v29, v19, v31
	v_add_f32_e32 v34, v46, v29
	ds_read_b128 v[28:31], v129 offset:23552
	s_waitcnt lgkmcnt(0)
	v_mul_f32_e32 v25, v23, v25
	v_fmac_f32_e32 v25, v22, v24
	v_fmac_f32_e32 v25, v18, v26
	v_fmac_f32_e32 v25, v19, v27
	v_add_f32_e32 v35, v47, v25
	ds_read_b128 v[24:27], v129 offset:27648
	v_mul_f32_e32 v29, v23, v29
	v_fmac_f32_e32 v29, v22, v28
	v_fmac_f32_e32 v29, v18, v30
	ds_bpermute_b32 v38, v123, v21
	v_fmac_f32_e32 v29, v19, v31
	v_add_f32_e32 v36, v48, v37
	v_add_f32_e32 v37, v49, v29
	ds_read_b128 v[28:31], v129 offset:31744
	s_waitcnt lgkmcnt(0)
	v_mul_f32_e32 v25, v23, v25
	v_fmac_f32_e32 v25, v22, v24
	v_fmac_f32_e32 v25, v18, v26
	v_fmac_f32_e32 v25, v19, v27
	v_add_f32_e32 v21, v21, v38
	ds_bpermute_b32 v24, v124, v21
	v_add_f32_e32 v36, v36, v25
	ds_bpermute_b32 v25, v123, v32
	v_mul_f32_e32 v23, v23, v29
	v_fmac_f32_e32 v23, v22, v28
	s_waitcnt lgkmcnt(0)
	v_add_f32_e32 v21, v21, v24
	ds_bpermute_b32 v22, v125, v21
	v_add_f32_e32 v24, v32, v25
	ds_bpermute_b32 v25, v124, v24
	v_fmac_f32_e32 v23, v18, v30
	v_fmac_f32_e32 v23, v19, v31
	s_waitcnt lgkmcnt(0)
	v_add_f32_e32 v18, v21, v22
	v_add_f32_e32 v28, v20, v23
	v_add_f32_e32 v21, v24, v25
	ds_bpermute_b32 v22, v125, v21
	ds_bpermute_b32 v20, v123, v33
	ds_bpermute_b32 v24, v123, v35
	ds_bpermute_b32 v30, v123, v36
	ds_bpermute_b32 v31, v123, v28
	s_waitcnt lgkmcnt(0)
	v_add_f32_e32 v21, v21, v22
	ds_bpermute_b32 v22, v126, v21
	v_add_f32_e32 v20, v33, v20
	ds_bpermute_b32 v23, v124, v20
	v_add_f32_e32 v24, v35, v24
	ds_bpermute_b32 v27, v124, v24
	s_waitcnt lgkmcnt(0)
	v_add_f32_e32 v21, v21, v22
	ds_bpermute_b32 v22, v123, v34
	v_add_f32_e32 v20, v20, v23
	ds_bpermute_b32 v23, v125, v20
	ds_bpermute_b32 v25, v127, v21
	v_add_f32_e32 v30, v36, v30
	s_waitcnt lgkmcnt(0)
	v_add_f32_e32 v22, v34, v22
	ds_bpermute_b32 v26, v124, v22
	v_add_f32_e32 v23, v20, v23
	v_add_f32_e32 v20, v21, v25
	v_add_f32_e32 v21, v24, v27
	ds_bpermute_b32 v29, v126, v23
	s_waitcnt lgkmcnt(0)
	v_add_f32_e32 v22, v22, v26
	ds_bpermute_b32 v26, v125, v22
	ds_bpermute_b32 v24, v125, v21
	v_add_f32_e32 v28, v28, v31
	v_add_f32_e32 v23, v23, v29
	ds_bpermute_b32 v33, v124, v30
	s_waitcnt lgkmcnt(0)
	v_add_f32_e32 v22, v22, v26
	ds_bpermute_b32 v25, v126, v22
	v_add_f32_e32 v24, v21, v24
	ds_bpermute_b32 v26, v127, v23
	ds_bpermute_b32 v27, v126, v24
	ds_bpermute_b32 v31, v124, v28
	s_waitcnt lgkmcnt(0)
	v_add_f32_e32 v25, v22, v25
	ds_bpermute_b32 v29, v127, v25
	v_add_f32_e32 v22, v23, v26
	v_add_f32_e32 v26, v24, v27
	v_add_f32_e32 v30, v30, v33
	v_add_f32_e32 v28, v28, v31
	s_waitcnt lgkmcnt(0)
	v_add_f32_e32 v24, v25, v29
	ds_bpermute_b32 v29, v123, v37
	ds_bpermute_b32 v33, v125, v30
	ds_bpermute_b32 v31, v125, v28
	ds_bpermute_b32 v19, v126, v18
	ds_bpermute_b32 v27, v127, v26
	s_waitcnt lgkmcnt(0)
	v_add_f32_e32 v29, v37, v29
	ds_bpermute_b32 v32, v124, v29
	v_add_f32_e32 v30, v30, v33
	v_add_f32_e32 v28, v28, v31
	ds_bpermute_b32 v33, v126, v30
	ds_bpermute_b32 v31, v126, v28
	s_waitcnt lgkmcnt(0)
	v_add_f32_e32 v29, v29, v32
	ds_bpermute_b32 v32, v125, v29
	v_add_f32_e32 v18, v18, v19
	v_add_f32_e32 v30, v30, v33
	v_add_f32_e32 v34, v28, v31
	ds_bpermute_b32 v19, v127, v18
	s_waitcnt lgkmcnt(0)
	v_add_f32_e32 v29, v29, v32
	ds_bpermute_b32 v32, v126, v29
	ds_bpermute_b32 v33, v127, v30
	ds_bpermute_b32 v35, v127, v34
	v_add_f32_e32 v18, v18, v19
	v_add_f32_e32 v26, v26, v27
	s_waitcnt lgkmcnt(0)
	v_add_f32_e32 v29, v29, v32
	ds_bpermute_b32 v32, v127, v29
	v_add_f32_e32 v30, v30, v33
	ds_bpermute_b32 v19, v128, v18
	ds_bpermute_b32 v21, v128, v20
	ds_bpermute_b32 v23, v128, v22
	s_waitcnt lgkmcnt(0)
	v_add_f32_e32 v28, v29, v32
	v_add_f32_e32 v32, v34, v35
	ds_bpermute_b32 v25, v128, v24
	ds_bpermute_b32 v27, v128, v26
	ds_bpermute_b32 v29, v128, v28
	ds_bpermute_b32 v31, v128, v30
	ds_bpermute_b32 v33, v128, v32
	s_and_saveexec_b64 s[22:23], vcc
	s_cbranch_execz .LBB0_1031
	v_mov_b32_e32 v34, s64
	v_mov_b32_e32 v35, s65
	v_add_f32_e32 v20, v20, v21
	v_readfirstlane_b32 s0, v34
	v_readfirstlane_b32 s1, v35
	v_add_f32_e32 v18, v18, v19
	v_mov_b32_e32 v34, s0
	v_mov_b32_e32 v35, s1
	global_load_dwordx2 v[34:35], v[34:35], off offset:152
	s_waitcnt vmcnt(0) lgkmcnt(0)
	v_add_f32_e32 v22, v22, v23
	v_readfirstlane_b32 s0, v34
	v_readfirstlane_b32 s1, v35
	v_cndmask_b32_e64 v18, v18, v20, s[38:39]
	v_mov_b32_e32 v34, s0
	v_mov_b32_e32 v35, s1
	v_lshl_add_u64 v[34:35], v[106:107], 2, v[34:35]
	global_load_dword v34, v[34:35], off
	v_add_f32_e32 v24, v24, v25
	v_cndmask_b32_e64 v18, v18, v22, s[40:41]
	v_add_f32_e32 v26, v26, v27
	v_cndmask_b32_e64 v18, v18, v24, s[42:43]
	v_add_f32_e32 v28, v28, v29
	v_cndmask_b32_e64 v18, v18, v26, s[44:45]
	v_add_f32_e32 v30, v30, v31
	v_cndmask_b32_e64 v18, v18, v28, s[46:47]
	v_add_f32_e32 v32, v32, v33
	v_cndmask_b32_e64 v18, v18, v30, s[48:49]
	v_cndmask_b32_e64 v18, v18, v32, s[50:51]
	s_mov_b32 s0, 0xbfb8aa3b
	s_waitcnt vmcnt(0) lgkmcnt(0)
	v_add_f32_e32 v18, v18, v34
	v_mul_f32_e64 v19, |v18|, s0
	v_exp_f32_e32 v20, v19
	s_mov_b32 s0, 0x3ca3d70a
	v_cmp_ngt_f32_e64 s[54:55], s0, v20
	s_and_saveexec_b64 s[0:1], s[54:55]
	s_xor_b64 s[24:25], exec, s[0:1]
	s_cbranch_execz .LBB0_1041
	v_add_f32_e32 v19, 1.0, v20
	v_cmp_gt_f32_e64 s[54:55], s18, v19
	s_mov_b32 s0, 0x3f317217
	s_nop 0
	v_cndmask_b32_e64 v20, 0, 32, s[54:55]
	v_ldexp_f32 v19, v19, v20
	v_log_f32_e32 v19, v19
	s_nop 0
	v_mul_f32_e32 v20, 0x3f317217, v19
	v_fma_f32 v20, v19, s0, -v20
	v_fmac_f32_e32 v20, 0x3377d1cf, v19
	s_mov_b32 s0, 0x7f800000
	v_fmac_f32_e32 v20, 0x3f317217, v19
	v_cmp_lt_f32_e64 s[56:57], |v19|, s0
	s_nop 1
	v_cndmask_b32_e64 v19, v19, v20, s[56:57]
	v_cndmask_b32_e64 v20, 0, v167, s[54:55]
	v_sub_f32_e32 v19, v19, v20

.LBB0_1089:
	v_mov_b32_e32 v2, s64
	v_mov_b32_e32 v3, s65
	v_mov_b32_e32 v0, s64
	v_readfirstlane_b32 s0, v2
	v_readfirstlane_b32 s1, v3
	v_mov_b32_e32 v4, s65
	v_mov_b32_e32 v2, s0
	v_mov_b32_e32 v3, s1
	global_load_dwordx2 v[2:3], v[2:3], off offset:48
	s_waitcnt vmcnt(0) lgkmcnt(0)
	v_mov_b32_e32 v20, v247
	v_readfirstlane_b32 s0, v0
	v_readfirstlane_b32 s1, v4
	v_mov_b32_e32 v0, s88
	v_mov_b32_e32 v4, s0
	v_mov_b32_e32 v5, s1
	global_load_dwordx2 v[4:5], v[4:5], off offset:248
	v_readfirstlane_b32 s0, v2
	v_readfirstlane_b32 s1, v3
	s_waitcnt vmcnt(0) lgkmcnt(0)
	v_mov_b32_e32 v2, v5
	s_nop 0
	v_readfirstlane_b32 s4, v0
	v_ashrrev_i32_e32 v18, 6, v20
	s_lshl_b32 s14, s4, 3
	v_add_u32_e32 v78, s14, v18
	s_movk_i32 s4, 0x2400
	v_readfirstlane_b32 s6, v4
	v_readfirstlane_b32 s7, v2
	v_cmp_gt_i32_e32 vcc, s4, v78
	s_and_saveexec_b64 s[8:9], vcc
	s_mov_b64 s[20:21], 0x1000
	s_cbranch_execz .LBB0_1092
	v_readlane_b32 s4, v254, 39
	v_readlane_b32 s5, v254, 40
	s_lshl_b64 s[4:5], s[4:5], 2
	v_lshlrev_b32_e32 v0, 2, v20
	s_add_u32 s0, s0, s4
	v_and_b32_e32 v22, 0xfc, v0
	s_addc_u32 s1, s1, s5
	v_lshlrev_b32_e32 v0, 2, v22
	v_lshl_add_u64 v[14:15], s[0:1], 0, v[0:1]
	global_load_dwordx4 v[2:5], v[14:15], off
	global_load_dwordx4 v[6:9], v[14:15], off offset:1024
	global_load_dwordx4 v[10:13], v[14:15], off offset:2048
	s_nop 0
	global_load_dwordx4 v[14:17], v[14:15], off offset:3072
	v_lshl_add_u64 v[24:25], s[6:7], 0, v[0:1]
	v_xor_b32_e32 v0, 1, v219
	v_cmp_lt_i32_e32 vcc, v0, v220
	v_readlane_b32 s0, v254, 42
	s_add_u32 s0, s6, s0
	v_cndmask_b32_e32 v0, v219, v0, vcc
	v_lshlrev_b32_e32 v79, 2, v0
	v_xor_b32_e32 v0, 2, v219
	v_cmp_lt_i32_e32 vcc, v0, v220
	v_readlane_b32 s1, v254, 41
	s_addc_u32 s1, s7, s1
	v_cndmask_b32_e32 v0, v219, v0, vcc
	v_lshlrev_b32_e32 v80, 2, v0
	v_xor_b32_e32 v0, 4, v219
	v_cmp_lt_i32_e32 vcc, v0, v220
	s_add_u32 s12, s0, 0x20700000
	s_addc_u32 s13, s1, 0
	v_cndmask_b32_e32 v0, v219, v0, vcc
	v_lshlrev_b32_e32 v81, 2, v0
	v_xor_b32_e32 v0, 8, v219
	v_cmp_lt_i32_e32 vcc, v0, v220
	v_ashrrev_i32_e32 v19, 31, v18
	s_ashr_i32 s15, s14, 31
	v_cndmask_b32_e32 v0, v219, v0, vcc
	v_cmp_lt_i32_e32 vcc, v222, v220
	v_lshlrev_b32_e32 v82, 2, v0
	s_mov_b64 s[0:1], 0x3300000
	v_cndmask_b32_e32 v0, v219, v222, vcc
	v_cmp_lt_i32_e32 vcc, v221, v220
	v_lshlrev_b32_e32 v83, 2, v0
	v_lshl_add_u64 v[18:19], v[18:19], 0, s[14:15]
	v_cndmask_b32_e32 v0, v219, v221, vcc
	v_lshlrev_b32_e32 v84, 2, v0
	v_lshlrev_b32_e32 v0, 1, v22
	v_lshl_add_u64 v[34:35], v[24:25], 0, s[0:1]
	v_lshl_add_u64 v[24:25], s[6:7], 0, v[0:1]
	s_mov_b64 s[0:1], 0x7b00000
	v_lshlrev_b64 v[38:39], 11, v[18:19]
	v_and_b32_e32 v0, 63, v20
	v_lshlrev_b64 v[40:41], 12, v[18:19]
	v_lshl_add_u64 v[36:37], v[24:25], 0, s[0:1]
	v_lshl_or_b32 v38, v0, 3, v38
	v_lshl_or_b32 v40, v0, 4, v40
	s_mov_b64 s[14:15], 0
	v_lshlrev_b32_e32 v0, 2, v22
.LBB0_1091:
	v_ashrrev_i32_e32 v20, 11, v78
	v_lshl_add_u64 v[18:19], s[6:7], 0, v[40:41]
	v_mul_i32_i24_e32 v42, 0x2400, v20
	v_add_co_u32_e32 v30, vcc, s79, v18
	v_ashrrev_i32_e32 v43, 31, v42
	v_add_u32_e32 v54, 0x2400, v78
	v_addc_co_u32_e32 v31, vcc, 0, v19, vcc
	v_lshl_add_u64 v[42:43], v[42:43], 2, s[12:13]
	v_min_i32_e32 v44, 0x4000, v54
	v_ashrrev_i32_e32 v55, 31, v54
	global_load_dwordx4 v[18:21], v[30:31], off
	global_load_dwordx4 v[22:25], v[30:31], off offset:1024
	global_load_dwordx4 v[26:29], v[30:31], off offset:2048
	s_nop 0
	global_load_dwordx4 v[30:33], v[30:31], off offset:3072
	v_lshl_add_u64 v[76:77], v[42:43], 0, v[0:1]
	v_ashrrev_i32_e32 v46, 11, v44
	v_lshlrev_b64 v[44:45], 12, v[54:55]
	v_add_co_u32_e32 v42, vcc, s83, v76
	v_lshl_add_u64 v[44:45], v[34:35], 0, v[44:45]
	s_nop 0
	v_addc_co_u32_e32 v43, vcc, 0, v77, vcc
	v_mul_i32_i24_e32 v56, 0x2400, v46
	global_load_dwordx4 v[46:49], v[44:45], off
	global_load_dwordx4 v[50:53], v[44:45], off offset:1024
	global_load_dwordx4 v[68:71], v[44:45], off offset:2048
	global_load_dwordx4 v[72:75], v[44:45], off offset:3072
	v_ashrrev_i32_e32 v57, 31, v56
	global_load_dwordx4 v[42:45], v[42:43], off
	v_lshl_add_u64 v[56:57], v[56:57], 2, s[12:13]
	v_lshl_add_u64 v[90:91], v[56:57], 0, v[0:1]
	v_add_co_u32_e32 v56, vcc, s83, v90
	v_lshl_add_u64 v[96:97], v[76:77], 0, s[20:21]
	s_nop 0
	v_addc_co_u32_e32 v57, vcc, 0, v91, vcc
	global_load_dwordx4 v[86:89], v[56:57], off
	v_add_u32_e32 v78, s78, v78
	v_lshl_add_u64 v[40:41], v[40:41], 0, s[80:81]
	v_lshlrev_b64 v[54:55], 11, v[54:55]
	v_lshl_add_u64 v[54:55], v[36:37], 0, v[54:55]
	s_waitcnt vmcnt(0) lgkmcnt(0)
	v_mov_b32_e32 v58, v19
	v_mov_b32_e32 v59, v23
	v_mov_b32_e32 v56, v18
	v_mov_b32_e32 v57, v22
	v_mov_b32_e32 v62, v27
	v_mov_b32_e32 v63, v31
	v_pk_mul_f32 v[58:59], v[58:59], v[58:59]
	v_mov_b32_e32 v60, v26
	v_mov_b32_e32 v61, v30
	v_pk_fma_f32 v[56:57], v[56:57], v[56:57], v[58:59]
	v_mov_b32_e32 v58, v20
	v_mov_b32_e32 v59, v24
	v_pk_mul_f32 v[62:63], v[62:63], v[62:63]
	v_pk_fma_f32 v[56:57], v[58:59], v[58:59], v[56:57]
	v_pk_fma_f32 v[60:61], v[60:61], v[60:61], v[62:63]
	v_mov_b32_e32 v62, v28
	v_mov_b32_e32 v63, v32
	v_mov_b32_e32 v58, v21
	v_mov_b32_e32 v59, v25
	v_pk_fma_f32 v[60:61], v[62:63], v[62:63], v[60:61]
	v_pk_add_f32 v[62:63], v[42:43], 1.0 op_sel_hi:[1,0]
	v_pk_add_f32 v[64:65], v[44:45], 1.0 op_sel_hi:[1,0]
	v_mov_b32_e32 v42, v29
	v_mov_b32_e32 v43, v33
	v_pk_fma_f32 v[44:45], v[58:59], v[58:59], v[56:57]
	v_mov_b32_e32 v58, v47
	v_mov_b32_e32 v59, v51
	v_mov_b32_e32 v56, v46
	v_mov_b32_e32 v57, v50
	v_pk_fma_f32 v[42:43], v[42:43], v[42:43], v[60:61]
	v_pk_mul_f32 v[58:59], v[58:59], v[58:59]
	v_mov_b32_e32 v60, v69
	v_mov_b32_e32 v61, v73
	v_pk_fma_f32 v[56:57], v[56:57], v[56:57], v[58:59]
	v_mov_b32_e32 v58, v68
	v_mov_b32_e32 v59, v72
	v_pk_mul_f32 v[60:61], v[60:61], v[60:61]
	s_nop 0
	v_pk_fma_f32 v[58:59], v[58:59], v[58:59], v[60:61]
	v_mov_b32_e32 v60, v48
	v_mov_b32_e32 v61, v52
	v_pk_fma_f32 v[56:57], v[60:61], v[60:61], v[56:57]
	v_mov_b32_e32 v60, v70
	v_mov_b32_e32 v61, v74
	v_pk_fma_f32 v[58:59], v[60:61], v[60:61], v[58:59]
	v_mov_b32_e32 v60, v49
	v_mov_b32_e32 v61, v53
	v_pk_fma_f32 v[56:57], v[60:61], v[60:61], v[56:57]
	v_mov_b32_e32 v60, v71
	v_mov_b32_e32 v61, v75
	v_pk_fma_f32 v[58:59], v[60:61], v[60:61], v[58:59]
	v_mov_b32_e32 v61, v44
	v_mov_b32_e32 v60, v56
	v_mov_b32_e32 v44, v57
	v_mov_b32_e32 v57, v42
	v_mov_b32_e32 v56, v58
	v_pk_add_f32 v[44:45], v[60:61], v[44:45]
	v_mov_b32_e32 v42, v59
	v_pk_add_f32 v[44:45], v[44:45], v[56:57]
	s_nop 0
	v_pk_add_f32 v[42:43], v[44:45], v[42:43]
	ds_bpermute_b32 v45, v79, v43
	ds_bpermute_b32 v44, v79, v42
	s_waitcnt lgkmcnt(0)
	v_pk_add_f32 v[42:43], v[42:43], v[44:45]
	ds_bpermute_b32 v45, v80, v43
	ds_bpermute_b32 v44, v80, v42
	s_waitcnt lgkmcnt(0)
	v_pk_add_f32 v[42:43], v[42:43], v[44:45]
	ds_bpermute_b32 v45, v81, v43
	ds_bpermute_b32 v44, v81, v42
	s_waitcnt lgkmcnt(0)
	v_pk_add_f32 v[42:43], v[42:43], v[44:45]
	ds_bpermute_b32 v45, v82, v43
	ds_bpermute_b32 v44, v82, v42
	s_waitcnt lgkmcnt(0)
	v_pk_add_f32 v[42:43], v[42:43], v[44:45]
	ds_bpermute_b32 v45, v83, v43
	ds_bpermute_b32 v44, v83, v42
	s_waitcnt lgkmcnt(0)
	v_pk_add_f32 v[42:43], v[42:43], v[44:45]
	ds_bpermute_b32 v45, v84, v43
	ds_bpermute_b32 v44, v84, v42
	s_waitcnt lgkmcnt(0)
	v_pk_add_f32 v[42:43], v[42:43], v[44:45]
	s_nop 0
	v_pk_fma_f32 v[92:93], v[42:43], s[86:87], v[162:163] op_sel_hi:[1,0,0]
	s_nop 0
	v_mul_f32_e32 v42, 0x4b800000, v93
	v_cmp_gt_f32_e32 vcc, s18, v93
	s_nop 1
	v_cndmask_b32_e32 v42, v93, v42, vcc
	v_rsq_f32_e32 v42, v42
	s_nop 0
	v_mul_f32_e32 v43, 0x45800000, v42
	v_cndmask_b32_e32 v94, v42, v43, vcc
	v_pk_mul_f32 v[42:43], v[18:19], v[94:95] op_sel_hi:[1,0]
	v_pk_mul_f32 v[58:59], v[20:21], v[94:95] op_sel_hi:[1,0]
	global_load_dwordx4 v[18:21], v[76:77], off
	v_pk_mul_f32 v[56:57], v[2:3], v[42:43]
	global_load_dwordx4 v[42:45], v[76:77], off offset:1024
	v_pk_mul_f32 v[22:23], v[22:23], v[94:95] op_sel_hi:[1,0]
	v_pk_mul_f32 v[24:25], v[24:25], v[94:95] op_sel_hi:[1,0]
	v_pk_mul_f32 v[22:23], v[6:7], v[22:23]
	v_pk_mul_f32 v[32:33], v[32:33], v[94:95] op_sel_hi:[1,0]
	v_cmp_gt_f32_e32 vcc, s18, v92
	v_pk_mul_f32 v[32:33], v[16:17], v[32:33]
	v_pk_mul_f32 v[30:31], v[30:31], v[94:95] op_sel_hi:[1,0]
	s_waitcnt vmcnt(0) lgkmcnt(0)
	v_pk_fma_f32 v[56:57], v[62:63], v[56:57], v[18:19]
	v_pk_mul_f32 v[18:19], v[4:5], v[58:59]
	v_pk_mul_f32 v[30:31], v[14:15], v[30:31]
	v_pk_fma_f32 v[58:59], v[64:65], v[18:19], v[20:21]
	global_load_dwordx4 v[18:21], v[96:97], off offset:1024
	global_load_dwordx4 v[64:67], v[96:97], off offset:2048
	s_waitcnt vmcnt(0) lgkmcnt(0)
	v_pk_add_f32 v[18:19], v[18:19], 1.0 op_sel_hi:[1,0]
	v_pk_add_f32 v[20:21], v[20:21], 1.0 op_sel_hi:[1,0]
	v_pk_fma_f32 v[60:61], v[18:19], v[22:23], v[42:43]
	v_pk_mul_f32 v[18:19], v[8:9], v[24:25]
	v_pk_add_f32 v[42:43], v[64:65], 1.0 op_sel_hi:[1,0]
	v_pk_fma_f32 v[62:63], v[20:21], v[18:19], v[44:45]
	v_pk_mul_f32 v[18:19], v[26:27], v[94:95] op_sel_hi:[1,0]
	v_pk_mul_f32 v[26:27], v[28:29], v[94:95] op_sel_hi:[1,0]
	v_pk_mul_f32 v[28:29], v[10:11], v[18:19]
	global_load_dwordx4 v[18:21], v[76:77], off offset:2048
	global_load_dwordx4 v[22:25], v[76:77], off offset:3072
	v_pk_add_f32 v[44:45], v[66:67], 1.0 op_sel_hi:[1,0]
	v_pk_add_f32 v[76:77], v[88:89], 1.0 op_sel_hi:[1,0]
	s_waitcnt vmcnt(0) lgkmcnt(0)
	v_pk_fma_f32 v[64:65], v[42:43], v[28:29], v[18:19]
	v_pk_mul_f32 v[18:19], v[12:13], v[26:27]
	s_nop 0
	v_pk_fma_f32 v[66:67], v[44:45], v[18:19], v[20:21]
	global_load_dwordx4 v[18:21], v[96:97], off offset:3072
	s_waitcnt vmcnt(0) lgkmcnt(0)
	v_pk_add_f32 v[26:27], v[18:19], 1.0 op_sel_hi:[1,0]
	v_pk_add_f32 v[28:29], v[20:21], 1.0 op_sel_hi:[1,0]
	global_load_dwordx4 v[18:21], v[90:91], off
	v_pk_fma_f32 v[44:45], v[28:29], v[32:33], v[24:25]
	v_mul_f32_e32 v28, 0x4b800000, v92
	v_cndmask_b32_e32 v28, v92, v28, vcc
	v_rsq_f32_e32 v28, v28
	v_pk_fma_f32 v[42:43], v[26:27], v[30:31], v[22:23]
	v_pk_add_f32 v[22:23], v[86:87], 1.0 op_sel_hi:[1,0]
	v_lshl_add_u64 v[32:33], v[90:91], 0, s[20:21]
	v_mul_f32_e32 v29, 0x45800000, v28
	v_cndmask_b32_e32 v86, v28, v29, vcc
	v_pk_mul_f32 v[28:29], v[46:47], v[86:87] op_sel_hi:[1,0]
	global_load_dwordx4 v[24:27], v[90:91], off offset:1024
	v_pk_mul_f32 v[28:29], v[2:3], v[28:29]
	v_pk_mul_f32 v[48:49], v[48:49], v[86:87] op_sel_hi:[1,0]
	v_pk_mul_f32 v[52:53], v[52:53], v[86:87] op_sel_hi:[1,0]
	v_pk_mul_f32 v[68:69], v[68:69], v[86:87] op_sel_hi:[1,0]
	v_pk_mul_f32 v[70:71], v[70:71], v[86:87] op_sel_hi:[1,0]
	v_pk_mul_f32 v[72:73], v[72:73], v[86:87] op_sel_hi:[1,0]
	v_pk_mul_f32 v[74:75], v[74:75], v[86:87] op_sel_hi:[1,0]
	v_pk_mul_f32 v[68:69], v[10:11], v[68:69]
	v_pk_mul_f32 v[70:71], v[12:13], v[70:71]
	v_pk_mul_f32 v[72:73], v[14:15], v[72:73]
	v_pk_mul_f32 v[74:75], v[16:17], v[74:75]
	s_waitcnt vmcnt(0) lgkmcnt(0)
	v_pk_fma_f32 v[46:47], v[22:23], v[28:29], v[18:19]
	global_load_dwordx4 v[28:31], v[32:33], off offset:1024
	v_pk_mul_f32 v[18:19], v[4:5], v[48:49]
	s_nop 0
	v_pk_fma_f32 v[48:49], v[76:77], v[18:19], v[20:21]
	global_load_dwordx4 v[18:21], v[32:33], off offset:2048
	v_lshl_add_u64 v[76:77], s[6:7], 0, v[38:39]
	v_add_co_u32_e32 v76, vcc, s43, v76
	v_lshl_add_u64 v[38:39], v[38:39], 0, s[84:85]
	s_nop 0
	v_addc_co_u32_e32 v77, vcc, 0, v77, vcc
	v_cmp_lt_i32_e32 vcc, s42, v78
	s_or_b64 s[14:15], vcc, s[14:15]
	s_waitcnt vmcnt(0) lgkmcnt(0)
	v_pk_add_f32 v[22:23], v[28:29], 1.0 op_sel_hi:[1,0]
	v_pk_add_f32 v[28:29], v[30:31], 1.0 op_sel_hi:[1,0]
	v_pk_mul_f32 v[30:31], v[50:51], v[86:87] op_sel_hi:[1,0]
	v_pk_add_f32 v[18:19], v[18:19], 1.0 op_sel_hi:[1,0]
	v_pk_mul_f32 v[30:31], v[6:7], v[30:31]
	v_pk_add_f32 v[20:21], v[20:21], 1.0 op_sel_hi:[1,0]
	v_pk_fma_f32 v[50:51], v[22:23], v[30:31], v[24:25]
	v_pk_mul_f32 v[30:31], v[8:9], v[52:53]
	global_load_dwordx4 v[22:25], v[90:91], off offset:2048
	v_pk_fma_f32 v[52:53], v[28:29], v[30:31], v[26:27]
	global_load_dwordx4 v[30:33], v[32:33], off offset:3072
	s_nop 0
	global_load_dwordx4 v[26:29], v[90:91], off offset:3072
	s_waitcnt vmcnt(0) lgkmcnt(0)
	v_pk_fma_f32 v[18:19], v[18:19], v[68:69], v[22:23]
	v_pk_add_f32 v[30:31], v[30:31], 1.0 op_sel_hi:[1,0]
	v_pk_add_f32 v[32:33], v[32:33], 1.0 op_sel_hi:[1,0]
	v_pk_fma_f32 v[20:21], v[20:21], v[70:71], v[24:25]
	v_pk_fma_f32 v[22:23], v[30:31], v[72:73], v[26:27]
	v_pk_fma_f32 v[24:25], v[32:33], v[74:75], v[28:29]
	v_cvt_pk_bf16_f32 v26, v56, v57
	v_cvt_pk_bf16_f32 v27, v58, v59
	v_cvt_pk_bf16_f32 v28, v60, v61
	v_cvt_pk_bf16_f32 v29, v62, v63
	v_cvt_pk_bf16_f32 v30, v64, v65
	v_cvt_pk_bf16_f32 v31, v66, v67
	v_cvt_pk_bf16_f32 v32, v42, v43
	v_cvt_pk_bf16_f32 v33, v44, v45
	v_cvt_pk_bf16_f32 v42, v46, v47
	v_cvt_pk_bf16_f32 v43, v48, v49
	v_cvt_pk_bf16_f32 v44, v50, v51
	v_cvt_pk_bf16_f32 v45, v52, v53
	v_cvt_pk_bf16_f32 v18, v18, v19
	v_cvt_pk_bf16_f32 v19, v20, v21
	v_cvt_pk_bf16_f32 v20, v22, v23
	v_cvt_pk_bf16_f32 v21, v24, v25
	global_store_dwordx2 v[76:77], v[26:27], off
	global_store_dwordx2 v[76:77], v[28:29], off offset:512
	global_store_dwordx2 v[76:77], v[30:31], off offset:1024
	global_store_dwordx2 v[76:77], v[32:33], off offset:1536
	global_store_dwordx2 v[54:55], v[42:43], off
	global_store_dwordx2 v[54:55], v[44:45], off offset:512
	global_store_dwordx2 v[54:55], v[18:19], off offset:1024
	global_store_dwordx2 v[54:55], v[20:21], off offset:1536
	s_andn2_b64 exec, exec, s[14:15]
	s_cbranch_execnz .LBB0_1091

.LBB0_1139:
	v_mov_b32_e32 v0, s64
	v_mov_b32_e32 v2, s65
	s_add_u32 s40, s10, 0x7b00000
	v_readfirstlane_b32 s0, v0
	v_readfirstlane_b32 s4, v2
	s_addc_u32 s41, s11, 0
	v_mov_b32_e32 v2, s0
	v_mov_b32_e32 v3, s4
	global_load_dwordx2 v[2:3], v[2:3], off offset:96
	v_readlane_b32 s6, v255, 8
	s_add_u32 s42, s10, 0x9f00000
	v_readlane_b32 s7, v255, 9
	s_addc_u32 s43, s11, 0
	s_cmp_lt_i32 s87, 2
	s_waitcnt vmcnt(0) lgkmcnt(0)
	v_mov_b32_e32 v0, v2
	s_nop 0
	v_readfirstlane_b32 s0, v0
	v_cndmask_b32_e64 v0, 0, 1, s[6:7]
	v_readfirstlane_b32 s5, v3
	v_readfirstlane_b32 s80, v0
	s_cbranch_scc1 .LBB0_1142
	s_cmp_gt_i32 s87, 2
	s_cbranch_scc0 .LBB0_1144
	s_cmp_lg_u32 s87, 3
	s_mov_b64 s[8:9], 0
	s_cselect_b64 s[6:7], -1, 0
	s_branch .LBB0_1145

.LBB0_1225:
	s_cmp_eq_u32 s87, 6
	v_readlane_b32 s4, v254, 49
	s_cselect_b64 s[0:1], -1, 0
	v_readlane_b32 s5, v254, 50
	s_and_b64 s[0:1], s[4:5], s[0:1]
	v_readlane_b32 s4, v254, 17
	v_readlane_b32 s5, v254, 18
	v_cndmask_b32_e64 v0, 0, 1, s[0:1]
	s_mov_b64 s[6:7], -1
	s_and_b64 vcc, exec, s[4:5]
	v_cmp_ne_u32_e64 s[38:39], 1, v0
	s_cbranch_vccz .LBB0_1792
	s_and_b64 vcc, exec, s[38:39]
	s_cbranch_vccnz .LBB0_1478
	v_mov_b32_e32 v0, s64
	v_mov_b32_e32 v2, s65
	s_waitcnt vmcnt(0)
	s_barrier
	s_nop 0
	v_readfirstlane_b32 s0, v0
	v_readfirstlane_b32 s1, v2
	v_mov_b32_e32 v0, s88
	v_mov_b32_e32 v2, s0
	v_mov_b32_e32 v3, s1
	global_load_dwordx2 v[2:3], v[2:3], off offset:248
	s_waitcnt vmcnt(0) lgkmcnt(0)
	s_nop 0
	v_readfirstlane_b32 s1, v0
	v_readfirstlane_b32 s0, v2
	s_cmpk_gt_u32 s1, 0x3cf
	v_readfirstlane_b32 s4, v3
	s_cbranch_scc1 .LBB0_1478
	s_add_u32 s5, s0, 0x1080000
	s_addc_u32 s20, s4, 0
	s_add_u32 s21, s0, 0xb00000
	v_readlane_b32 s6, v253, 0
	s_addc_u32 s33, s4, 0
	s_lshl_b32 s34, s1, 8
	s_lshl_b32 s35, s6, 8
	s_lshl_b32 s46, s1, 4
	s_lshl_b32 s47, s6, 4
	v_readlane_b32 s7, v253, 1
	s_branch .LBB0_1231

.LBB0_1231:
	s_cmpk_gt_i32 s1, 0xaf
	s_mov_b64 s[6:7], -1
	s_cbranch_scc0 .LBB0_1468
	s_cmpk_gt_u32 s1, 0x15f
	s_cbranch_scc0 .LBB0_1457
	s_cmpk_gt_u32 s1, 0x20f
	s_cbranch_scc0 .LBB0_1447
	v_mov_b32_e32 v0, s64
	v_mov_b32_e32 v2, s65
	v_readlane_b32 s8, v254, 63
	v_readfirstlane_b32 s6, v0
	v_readfirstlane_b32 s7, v2
	v_mov_b32_e32 v6, 0
	v_mov_b32_e32 v2, s6
	v_mov_b32_e32 v3, s7
	global_load_dwordx2 v[2:3], v[2:3], off offset:88
	v_mov_b32_e32 v7, 0
	v_mov_b32_e32 v8, 0
	v_mov_b32_e32 v9, 0
	v_mov_b32_e32 v10, 0
	v_mov_b32_e32 v11, 0
	v_mov_b32_e32 v12, 0
	v_mov_b32_e32 v13, 0
	s_waitcnt vmcnt(0) lgkmcnt(0)
	v_mov_b32_e32 v0, v3
	s_nop 0
	v_readfirstlane_b32 s6, v2
	v_readfirstlane_b32 s7, v0
	s_add_u32 s6, s6, s8
	v_readlane_b32 s8, v254, 61
	s_addc_u32 s7, s7, s8
	s_add_i32 s8, s1, 0xfdf0
	s_bfe_u32 s9, s8, 0xe0002
	s_mulk_i32 s9, 0x4925
	s_lshr_b32 s9, s9, 17
	s_mul_i32 s10, s9, 28
	v_mov_b32_e32 v0, v247
	s_sub_i32 s8, s8, s10
	s_lshl_b32 s10, s8, 2
	v_ashrrev_i32_e32 v36, 3, v0
	v_lshlrev_b32_e32 v0, 3, v0
	s_lshl_b32 s11, s9, 6
	s_and_b32 s12, s10, 0xfffc
	v_and_b32_e32 v37, 56, v0
	v_add_u32_e32 v0, s11, v36
	v_mov_b64_e32 v[2:3], s[6:7]
	s_movk_i32 s6, 0x6c20
	v_add_u32_e32 v19, 8, v37
	v_mad_i64_i32 v[2:3], s[6:7], v0, s6, v[2:3]
	v_lshlrev_b32_e32 v0, 2, v37
	s_lshl_b32 s10, s12, 6
	v_lshl_add_u64 v[34:35], v[2:3], 0, v[0:1]
	v_or_b32_e32 v0, s10, v19
	s_movk_i32 s6, 0x1b09
	v_cmp_gt_u32_e32 vcc, s6, v0
	v_mov_b32_e32 v2, 0
	s_and_saveexec_b64 s[6:7], vcc
	s_cbranch_execz .LBB0_1236
	s_lshl_b32 s18, s10, 2
	v_lshl_add_u64 v[4:5], v[34:35], 0, s[18:19]
	global_load_dwordx4 v[6:9], v[4:5], off
	global_load_dwordx4 v[10:13], v[4:5], off offset:16
.LBB0_1236:
	s_or_b64 exec, exec, s[6:7]
	s_or_b32 s52, s12, 1
	s_lshl_b32 s53, s52, 6
	s_and_b32 s8, 0xffff, s8
	s_cmp_gt_u32 s8, 26
	s_cselect_b64 s[6:7], -1, 0
	s_cmp_lt_u32 s8, 27
	v_add_u32_e32 v0, s53, v19
	s_movk_i32 s13, 0x1b09
	s_cselect_b64 s[8:9], -1, 0
	v_cmp_gt_u32_e32 vcc, s13, v0
	s_and_b64 s[14:15], s[8:9], vcc
	v_mov_b32_e32 v3, 0
	v_mov_b32_e32 v4, 0
	v_mov_b32_e32 v5, 0
	v_mov_b32_e32 v14, 0
	v_mov_b32_e32 v15, 0
	v_mov_b32_e32 v16, 0
	v_mov_b32_e32 v17, 0
	s_and_saveexec_b64 s[8:9], s[14:15]
	s_cbranch_execz .LBB0_1238
	s_lshl_b32 s18, s53, 2
	v_lshl_add_u64 v[14:15], v[34:35], 0, s[18:19]
	global_load_dwordx4 v[2:5], v[14:15], off
	s_nop 0
	global_load_dwordx4 v[14:17], v[14:15], off offset:16
.LBB0_1238:
	s_or_b64 exec, exec, s[8:9]
	s_or_b32 s50, s12, 2
	s_lshl_b32 s51, s50, 6
	v_or_b32_e32 v0, s51, v19
	s_movk_i32 s8, 0x1b09
	v_cmp_gt_u32_e32 vcc, s8, v0
	s_xor_b64 s[6:7], s[6:7], -1
	s_and_b64 s[8:9], s[6:7], vcc
	v_mov_b32_e32 v18, 0
	v_mov_b32_e32 v22, 0
	v_mov_b32_e32 v23, 0
	v_mov_b32_e32 v24, 0
	v_mov_b32_e32 v25, 0
	v_mov_b32_e32 v26, 0
	v_mov_b32_e32 v27, 0
	v_mov_b32_e32 v28, 0
	v_mov_b32_e32 v29, 0
	s_and_saveexec_b64 s[6:7], s[8:9]
	s_cbranch_execz .LBB0_1240
	s_lshl_b32 s18, s51, 2
	v_lshl_add_u64 v[20:21], v[34:35], 0, s[18:19]
	global_load_dwordx4 v[22:25], v[20:21], off
	global_load_dwordx4 v[26:29], v[20:21], off offset:16
.LBB0_1240:
	s_or_b64 exec, exec, s[6:7]
	s_or_b32 s48, s12, 3
	s_lshl_b32 s49, s48, 6
	s_cmpk_lt_u32 s48, 0x6d
	v_add_u32_e32 v0, s49, v19
	s_movk_i32 s8, 0x1b09
	s_cselect_b64 s[6:7], -1, 0
	v_cmp_gt_u32_e32 vcc, s8, v0
	s_and_b64 s[8:9], s[6:7], vcc
	v_mov_b32_e32 v19, 0
	v_mov_b32_e32 v20, 0
	v_mov_b32_e32 v21, 0
	v_mov_b32_e32 v30, 0
	v_mov_b32_e32 v31, 0
	v_mov_b32_e32 v32, 0
	v_mov_b32_e32 v33, 0
	s_and_saveexec_b64 s[6:7], s[8:9]
	s_cbranch_execz .LBB0_1242
	s_lshl_b32 s18, s49, 2
	v_lshl_add_u64 v[30:31], v[34:35], 0, s[18:19]
	global_load_dwordx4 v[18:21], v[30:31], off
	s_nop 0
	global_load_dwordx4 v[30:33], v[30:31], off offset:16

.LBB0_1289:
	s_or_b64 exec, exec, s[8:9]
	s_waitcnt lgkmcnt(3)
	v_cvt_pk_bf16_f32 v2, v2, v3
	s_waitcnt lgkmcnt(2)
	v_cvt_pk_bf16_f32 v3, v4, v5
	s_waitcnt lgkmcnt(1)
	v_cvt_pk_bf16_f32 v4, v8, v9
	s_waitcnt lgkmcnt(0)
	v_cvt_pk_bf16_f32 v5, v10, v11
	v_cmp_lt_i32_e32 vcc, -1, v0
	s_and_saveexec_b64 s[8:9], vcc
	s_cbranch_execz .LBB0_1291
	v_lshlrev_b64 v[8:9], 11, v[0:1]
	v_lshl_add_u64 v[8:9], v[6:7], 0, v[8:9]
	global_store_dwordx4 v[8:9], v[2:5], off
.LBB0_1291:
	s_or_b64 exec, exec, s[8:9]
	v_cmp_lt_i32_e32 vcc, -1, v13
	s_and_b64 exec, exec, vcc
	s_cbranch_execz .LBB0_1293
	v_add_u32_e32 v0, 0x1800, v13
	v_lshlrev_b64 v[8:9], 11, v[0:1]
	v_lshl_add_u64 v[8:9], v[6:7], 0, v[8:9]
	global_store_dwordx4 v[8:9], v[2:5], off

.LBB0_1340:
	s_or_b64 exec, exec, s[8:9]
	s_waitcnt lgkmcnt(0)
	v_cvt_pk_bf16_f32 v2, v2, v3
	v_cvt_pk_bf16_f32 v3, v4, v5
	v_cvt_pk_bf16_f32 v4, v8, v9
	v_cvt_pk_bf16_f32 v5, v10, v11
	v_cmp_lt_i32_e32 vcc, -1, v0
	s_and_saveexec_b64 s[8:9], vcc
	s_cbranch_execz .LBB0_1342
	v_lshlrev_b64 v[8:9], 11, v[0:1]
	v_lshl_add_u64 v[8:9], v[6:7], 0, v[8:9]
	global_store_dwordx4 v[8:9], v[2:5], off

.LBB0_1444:
	s_or_b64 exec, exec, s[8:9]
	v_cmp_lt_i32_e32 vcc, -1, v12
	s_and_b64 exec, exec, vcc
	s_cbranch_execz .LBB0_1446
	v_add_u32_e32 v0, 0x1800, v12
	v_lshlrev_b64 v[8:9], 11, v[0:1]
	v_lshl_add_u64 v[6:7], v[6:7], 0, v[8:9]
	global_store_dwordx4 v[6:7], v[2:5], off

.LBB0_1447:
	s_and_b64 vcc, exec, s[6:7]
	s_cbranch_vccz .LBB0_1477
	v_mov_b32_e32 v0, s64
	v_mov_b32_e32 v2, s65
	v_readlane_b32 s8, v254, 60
	v_readfirstlane_b32 s6, v0
	v_readfirstlane_b32 s7, v2
	s_nop 0
	v_mov_b32_e32 v2, s6
	v_mov_b32_e32 v3, s7
	global_load_dwordx2 v[2:3], v[2:3], off offset:72
	s_waitcnt vmcnt(0) lgkmcnt(0)
	v_mov_b32_e32 v0, v2
	s_nop 0
	v_readfirstlane_b32 s6, v0
	v_readfirstlane_b32 s7, v3
	s_add_u32 s10, s6, s8
	v_readlane_b32 s6, v254, 58
	s_addc_u32 s11, s7, s6
	v_mov_b32_e32 v0, v247
	s_and_b32 s6, s46, 0x3fc0
	s_addk_i32 s6, 0xea00
	v_ashrrev_i32_e32 v4, 3, v0
	v_add_u32_e32 v2, s6, v4
	v_lshlrev_b32_e32 v0, 3, v0
	v_ashrrev_i32_e32 v3, 31, v2
	v_and_b32_e32 v5, 56, v0
	v_lshlrev_b64 v[2:3], 12, v[2:3]
	s_and_b32 s8, s34, 0x300
	v_lshl_add_u64 v[2:3], s[10:11], 0, v[2:3]
	v_lshlrev_b32_e32 v0, 2, v5
	v_lshl_add_u64 v[2:3], v[2:3], 0, v[0:1]
	s_lshl_b32 s18, s8, 2
	s_movk_i32 s7, 0x104
	v_lshl_add_u64 v[2:3], v[2:3], 0, s[18:19]
	v_mul_lo_u32 v6, v4, s7
	v_add_u32_e32 v10, 16, v6
	global_load_dwordx4 v[6:9], v[2:3], off
	v_add_u32_e32 v0, v10, v0
	v_add_u32_e32 v11, 0x4100, v0
	s_mov_b32 s7, s19
	s_lshl_b64 s[6:7], s[6:7], 1
	s_add_u32 s6, s21, s6
	s_addc_u32 s7, s33, s7
	s_waitcnt vmcnt(0) lgkmcnt(0)
	ds_write2_b32 v0, v6, v7 offset1:1
	ds_write2_b32 v0, v8, v9 offset0:2 offset1:3
	global_load_dwordx4 v[6:9], v[2:3], off offset:16
	s_waitcnt vmcnt(0) lgkmcnt(0)
	ds_write2_b32 v0, v6, v7 offset0:4 offset1:5
	ds_write2_b32 v0, v8, v9 offset0:6 offset1:7
	global_load_dwordx4 v[6:9], v[2:3], off offset:256
	s_waitcnt vmcnt(0) lgkmcnt(0)
	ds_write2_b32 v11, v6, v7 offset1:1
	v_add_u32_e32 v6, 0x4108, v0
	ds_write2_b32 v6, v8, v9 offset1:1
	global_load_dwordx4 v[6:9], v[2:3], off offset:272
	v_add_u32_e32 v11, 0x4110, v0
	s_waitcnt vmcnt(0) lgkmcnt(0)
	ds_write2_b32 v11, v6, v7 offset1:1
	v_add_u32_e32 v6, 0x4118, v0
	ds_write2_b32 v6, v8, v9 offset1:1
	global_load_dwordx4 v[6:9], v[2:3], off offset:512
	v_add_u32_e32 v11, 0x8200, v0
	s_waitcnt vmcnt(0) lgkmcnt(0)
	ds_write2_b32 v11, v6, v7 offset1:1
	v_add_u32_e32 v6, 0x8208, v0
	ds_write2_b32 v6, v8, v9 offset1:1
	global_load_dwordx4 v[6:9], v[2:3], off offset:528
	v_add_u32_e32 v11, 0x8210, v0
	s_waitcnt vmcnt(0) lgkmcnt(0)
	ds_write2_b32 v11, v6, v7 offset1:1
	v_add_u32_e32 v6, 0x8218, v0
	ds_write2_b32 v6, v8, v9 offset1:1
	global_load_dwordx4 v[6:9], v[2:3], off offset:768
	v_add_u32_e32 v11, 0xc300, v0
	s_waitcnt vmcnt(0) lgkmcnt(0)
	ds_write2_b32 v11, v6, v7 offset1:1
	v_add_u32_e32 v6, 0xc308, v0
	ds_write2_b32 v6, v8, v9 offset1:1
	global_load_dwordx4 v[6:9], v[2:3], off offset:784
	v_add_u32_e32 v11, 0xc310, v0
	v_add_u32_e32 v0, 0xc318, v0
	s_waitcnt vmcnt(0) lgkmcnt(0)
	ds_write2_b32 v0, v8, v9 offset1:1
	v_lshlrev_b32_e32 v0, 8, v4
	ds_write2_b32 v11, v6, v7 offset1:1
	v_sub_u32_e32 v6, v10, v0
	v_lshlrev_b32_e32 v0, 1, v5
	v_mul_u32_u24_e32 v7, 0x104, v5
	v_lshl_add_u64 v[2:3], s[6:7], 0, v[0:1]
	v_add_u32_e32 v5, s8, v4
	s_movk_i32 s6, 0x400
	v_cmp_gt_u32_e32 vcc, s6, v5
	v_add_u32_e32 v6, v6, v7
	s_waitcnt lgkmcnt(0)
	s_barrier
	s_and_saveexec_b64 s[6:7], vcc
	s_cbranch_execz .LBB0_1450
	v_add_u32_e32 v0, 0x400, v6
	ds_read2_b32 v[8:9], v0 offset0:134 offset1:199
	ds_read2_b32 v[12:13], v6 offset1:65
	s_movk_i32 s9, 0x1600
	s_waitcnt lgkmcnt(1)
	v_cvt_pk_bf16_f32 v11, v8, v9
	ds_read2_b32 v[8:9], v0 offset0:4 offset1:69
	v_mul_lo_u32 v0, v5, s9
	s_waitcnt lgkmcnt(0)
	v_cvt_pk_bf16_f32 v10, v8, v9
	ds_read2_b32 v[8:9], v6 offset0:130 offset1:195
	s_waitcnt lgkmcnt(0)
	v_cvt_pk_bf16_f32 v9, v8, v9
	v_cvt_pk_bf16_f32 v8, v12, v13
	v_lshl_add_u64 v[12:13], v[2:3], 0, v[0:1]
	global_store_dwordx4 v[12:13], v[8:11], off
.LBB0_1450:
	s_or_b64 exec, exec, s[6:7]
	v_add3_u32 v0, v4, s8, 64
	s_movk_i32 s6, 0x400
	v_cmp_gt_u32_e32 vcc, s6, v0
	s_and_saveexec_b64 s[6:7], vcc
	s_cbranch_execz .LBB0_1452
	v_add_u32_e32 v4, 0x4600, v6
	ds_read2_b32 v[8:9], v4 offset0:70 offset1:135
	v_add_u32_e32 v4, 0x4400, v6
	s_movk_i32 s8, 0x1600
	v_mul_lo_u32 v0, v0, s8
	s_waitcnt lgkmcnt(0)
	v_cvt_pk_bf16_f32 v11, v8, v9
	ds_read2_b32 v[8:9], v4 offset0:68 offset1:133
	v_add_u32_e32 v4, 0x4200, v6
	s_waitcnt lgkmcnt(0)
	v_cvt_pk_bf16_f32 v10, v8, v9
	ds_read2_b32 v[8:9], v4 offset0:66 offset1:131
	v_add_u32_e32 v4, 0x4000, v6
	ds_read2_b32 v[12:13], v4 offset0:64 offset1:129
	s_waitcnt lgkmcnt(0)
	v_cvt_pk_bf16_f32 v9, v8, v9
	v_cvt_pk_bf16_f32 v8, v12, v13
	v_lshl_add_u64 v[12:13], v[2:3], 0, v[0:1]
	global_store_dwordx4 v[12:13], v[8:11], off
.LBB0_1452:
	s_or_b64 exec, exec, s[6:7]
	v_add_u32_e32 v0, 0x80, v5
	s_movk_i32 s6, 0x400
	v_cmp_gt_u32_e32 vcc, s6, v0
	s_and_saveexec_b64 s[6:7], vcc
	s_cbranch_execz .LBB0_1454
	v_add_u32_e32 v4, 0x8800, v6
	ds_read2_b32 v[8:9], v4 offset0:6 offset1:71
	v_add_u32_e32 v4, 0x8400, v6
	s_movk_i32 s8, 0x1600
	v_mul_lo_u32 v0, v0, s8
	s_waitcnt lgkmcnt(0)
	v_cvt_pk_bf16_f32 v11, v8, v9
	ds_read2_b32 v[8:9], v4 offset0:132 offset1:197
	s_waitcnt lgkmcnt(0)
	v_cvt_pk_bf16_f32 v10, v8, v9
	ds_read2_b32 v[8:9], v4 offset0:2 offset1:67
	v_add_u32_e32 v4, 0x8000, v6
	ds_read2_b32 v[12:13], v4 offset0:128 offset1:193
	s_waitcnt lgkmcnt(0)
	v_cvt_pk_bf16_f32 v9, v8, v9
	v_cvt_pk_bf16_f32 v8, v12, v13
	v_lshl_add_u64 v[12:13], v[2:3], 0, v[0:1]
	global_store_dwordx4 v[12:13], v[8:11], off
.LBB0_1454:
	s_or_b64 exec, exec, s[6:7]
	v_add_u32_e32 v0, 0xc0, v5
	s_movk_i32 s6, 0x400
	v_cmp_gt_u32_e32 vcc, s6, v0
	s_and_saveexec_b64 s[6:7], vcc
	s_cbranch_execz .LBB0_1456
	v_add_u32_e32 v4, 0xc800, v6
	ds_read2_b32 v[4:5], v4 offset0:70 offset1:135
	s_movk_i32 s8, 0x1600
	v_mul_lo_u32 v0, v0, s8
	v_lshl_add_u64 v[2:3], v[2:3], 0, v[0:1]
	s_waitcnt lgkmcnt(0)
	v_cvt_pk_bf16_f32 v9, v4, v5
	v_add_u32_e32 v4, 0xc600, v6
	ds_read2_b32 v[4:5], v4 offset0:68 offset1:133
	s_waitcnt lgkmcnt(0)
	v_cvt_pk_bf16_f32 v8, v4, v5
	v_add_u32_e32 v4, 0xc400, v6
	ds_read2_b32 v[4:5], v4 offset0:66 offset1:131
	s_waitcnt lgkmcnt(0)
	v_cvt_pk_bf16_f32 v7, v4, v5
	v_add_u32_e32 v4, 0xc200, v6
	ds_read2_b32 v[4:5], v4 offset0:64 offset1:129
	s_waitcnt lgkmcnt(0)
	v_cvt_pk_bf16_f32 v6, v4, v5
	global_store_dwordx4 v[2:3], v[6:9], off

.LBB0_1458:
	v_mov_b32_e32 v0, s64
	v_mov_b32_e32 v2, s65
	v_readlane_b32 s8, v254, 60
	v_readfirstlane_b32 s6, v0
	v_readfirstlane_b32 s7, v2
	v_mov_b32_e32 v10, v247
	v_mov_b32_e32 v2, s6
	v_mov_b32_e32 v3, s7
	global_load_dwordx2 v[2:3], v[2:3], off offset:64
	s_waitcnt vmcnt(0) lgkmcnt(0)
	v_mov_b32_e32 v0, v3
	s_nop 0
	v_readfirstlane_b32 s6, v2
	v_readfirstlane_b32 s7, v0
	s_add_u32 s6, s6, s8
	v_readlane_b32 s8, v254, 58
	s_addc_u32 s7, s7, s8
	s_add_i32 s8, s1, 0x50
	s_and_b32 s9, s8, 0xff
	s_mulk_i32 s9, 0x75
	s_lshr_b32 s10, s9, 8
	s_sub_i32 s10, s8, s10
	s_bfe_u32 s10, s10, 0x70001
	s_bfe_u32 s9, s9, 0x80008
	s_add_i32 s10, s10, s9
	s_bfe_u32 s9, s10, 0x50003
	s_mul_i32 s10, s9, 11
	s_sub_i32 s8, s8, s10
	v_ashrrev_i32_e32 v4, 3, v10
	v_lshlrev_b32_e32 v0, 3, v10
	s_lshl_b32 s8, s8, 2
	v_and_b32_e32 v5, 56, v0
	v_lshl_add_u32 v0, s9, 6, v4
	v_mov_b64_e32 v[2:3], s[6:7]
	s_movk_i32 s6, 0x2c00
	s_and_b32 s10, s8, 0xfc
	v_mad_i64_i32 v[2:3], s[6:7], v0, s6, v[2:3]
	v_lshlrev_b32_e32 v0, 2, v5
	v_lshl_add_u64 v[2:3], v[2:3], 0, v[0:1]
	s_lshl_b32 s18, s10, 8
	s_movk_i32 s6, 0x104
	v_lshl_add_u64 v[2:3], v[2:3], 0, s[18:19]
	v_mul_lo_u32 v6, v4, s6
	v_add_u32_e32 v11, 16, v6
	global_load_dwordx4 v[6:9], v[2:3], off
	v_add_u32_e32 v0, v11, v0
	v_add_u32_e32 v12, 0x4100, v0
	s_lshl_b32 s8, s10, 6
	s_lshl_b32 s6, s9, 7
	s_add_u32 s6, s0, s6
	s_addc_u32 s7, s4, 0
	s_waitcnt vmcnt(0) lgkmcnt(0)
	ds_write2_b32 v0, v6, v7 offset1:1
	ds_write2_b32 v0, v8, v9 offset0:2 offset1:3
	global_load_dwordx4 v[6:9], v[2:3], off offset:16
	s_waitcnt vmcnt(0) lgkmcnt(0)
	ds_write2_b32 v0, v6, v7 offset0:4 offset1:5
	ds_write2_b32 v0, v8, v9 offset0:6 offset1:7
	global_load_dwordx4 v[6:9], v[2:3], off offset:256
	s_waitcnt vmcnt(0) lgkmcnt(0)
	ds_write2_b32 v12, v6, v7 offset1:1
	v_add_u32_e32 v6, 0x4108, v0
	ds_write2_b32 v6, v8, v9 offset1:1
	global_load_dwordx4 v[6:9], v[2:3], off offset:272
	v_add_u32_e32 v12, 0x4110, v0
	s_waitcnt vmcnt(0) lgkmcnt(0)
	ds_write2_b32 v12, v6, v7 offset1:1
	v_add_u32_e32 v6, 0x4118, v0
	ds_write2_b32 v6, v8, v9 offset1:1
	global_load_dwordx4 v[6:9], v[2:3], off offset:512
	v_add_u32_e32 v12, 0x8200, v0
	s_waitcnt vmcnt(0) lgkmcnt(0)
	ds_write2_b32 v12, v6, v7 offset1:1
	v_add_u32_e32 v6, 0x8208, v0
	ds_write2_b32 v6, v8, v9 offset1:1
	global_load_dwordx4 v[6:9], v[2:3], off offset:528
	v_add_u32_e32 v12, 0x8210, v0
	s_waitcnt vmcnt(0) lgkmcnt(0)
	ds_write2_b32 v12, v6, v7 offset1:1
	v_add_u32_e32 v6, 0x8218, v0
	ds_write2_b32 v6, v8, v9 offset1:1
	global_load_dwordx4 v[6:9], v[2:3], off offset:768
	v_add_u32_e32 v12, 0xc300, v0
	s_waitcnt vmcnt(0) lgkmcnt(0)
	ds_write2_b32 v12, v6, v7 offset1:1
	v_add_u32_e32 v6, 0xc308, v0
	ds_write2_b32 v6, v8, v9 offset1:1
	global_load_dwordx4 v[6:9], v[2:3], off offset:784
	v_add_u32_e32 v12, 0xc310, v0
	v_add_u32_e32 v0, 0xc318, v0
	s_waitcnt vmcnt(0) lgkmcnt(0)
	ds_write2_b32 v0, v8, v9 offset1:1
	v_lshlrev_b32_e32 v0, 8, v4
	ds_write2_b32 v12, v6, v7 offset1:1
	v_sub_u32_e32 v7, v11, v0
	v_lshlrev_b32_e32 v0, 1, v5
	v_mul_u32_u24_e32 v8, 0x104, v5
	v_lshl_add_u64 v[2:3], s[6:7], 0, v[0:1]
	v_add_u32_e32 v5, s8, v4
	s_movk_i32 s6, 0xb00
	v_cmp_gt_u32_e32 vcc, s6, v5
	v_bfe_u32 v6, v10, 3, 7
	v_add_u32_e32 v7, v7, v8
	s_waitcnt lgkmcnt(0)
	s_barrier
	s_and_saveexec_b64 s[6:7], vcc
	s_cbranch_execz .LBB0_1460
	v_add_u32_e32 v10, 0x400, v7
	ds_read2_b32 v[8:9], v10 offset0:134 offset1:199
	ds_read2_b32 v[12:13], v7 offset1:65
	v_lshlrev_b32_e32 v0, 1, v5
	s_movk_i32 s9, 0x1f00
	v_and_or_b32 v0, v0, s9, v6
	s_waitcnt lgkmcnt(1)
	v_cvt_pk_bf16_f32 v11, v8, v9
	ds_read2_b32 v[8:9], v10 offset0:4 offset1:69
	v_lshlrev_b32_e32 v0, 11, v0
	s_waitcnt lgkmcnt(0)
	v_cvt_pk_bf16_f32 v10, v8, v9
	ds_read2_b32 v[8:9], v7 offset0:130 offset1:195
	s_waitcnt lgkmcnt(0)
	v_cvt_pk_bf16_f32 v9, v8, v9
	v_cvt_pk_bf16_f32 v8, v12, v13
	v_lshl_add_u64 v[12:13], v[2:3], 0, v[0:1]
	v_add_co_u32_e32 v12, vcc, 0x40000, v12
	s_nop 1
	v_addc_co_u32_e32 v13, vcc, 0, v13, vcc
	global_store_dwordx4 v[12:13], v[8:11], off
.LBB0_1460:
	s_or_b64 exec, exec, s[6:7]
	v_add3_u32 v0, v4, s8, 64
	s_movk_i32 s10, 0xb00
	v_cmp_gt_u32_e32 vcc, s10, v0
	s_and_saveexec_b64 s[6:7], vcc
	s_cbranch_execz .LBB0_1462
	v_lshlrev_b32_e32 v4, 1, v0
	v_and_b32_e32 v0, 0x7f, v0
	s_movk_i32 s8, 0x1f00
	v_and_or_b32 v0, v4, s8, v0
	v_add_u32_e32 v4, 0x4600, v7
	ds_read2_b32 v[8:9], v4 offset0:70 offset1:135
	v_add_u32_e32 v4, 0x4400, v7
	v_lshlrev_b32_e32 v0, 11, v0
	s_waitcnt lgkmcnt(0)
	v_cvt_pk_bf16_f32 v11, v8, v9
	ds_read2_b32 v[8:9], v4 offset0:68 offset1:133
	v_add_u32_e32 v4, 0x4200, v7
	s_waitcnt lgkmcnt(0)
	v_cvt_pk_bf16_f32 v10, v8, v9
	ds_read2_b32 v[8:9], v4 offset0:66 offset1:131
	v_add_u32_e32 v4, 0x4000, v7
	ds_read2_b32 v[12:13], v4 offset0:64 offset1:129
	s_waitcnt lgkmcnt(0)
	v_cvt_pk_bf16_f32 v9, v8, v9
	v_cvt_pk_bf16_f32 v8, v12, v13
	v_lshl_add_u64 v[12:13], v[2:3], 0, v[0:1]
	v_add_co_u32_e32 v12, vcc, 0x40000, v12
	s_nop 1
	v_addc_co_u32_e32 v13, vcc, 0, v13, vcc
	global_store_dwordx4 v[12:13], v[8:11], off
.LBB0_1462:
	s_or_b64 exec, exec, s[6:7]
	v_add_u32_e32 v0, 0x80, v5
	v_cmp_gt_u32_e32 vcc, s10, v0
	s_and_saveexec_b64 s[6:7], vcc
	s_cbranch_execz .LBB0_1464
	v_add_u32_e32 v4, 0x8800, v7
	ds_read2_b32 v[8:9], v4 offset0:6 offset1:71
	v_add_u32_e32 v4, 0x8400, v7
	v_lshlrev_b32_e32 v0, 1, v0
	s_movk_i32 s8, 0x1f00
	v_and_or_b32 v0, v0, s8, v6
	s_waitcnt lgkmcnt(0)
	v_cvt_pk_bf16_f32 v11, v8, v9
	ds_read2_b32 v[8:9], v4 offset0:132 offset1:197
	v_lshlrev_b32_e32 v0, 11, v0
	s_waitcnt lgkmcnt(0)
	v_cvt_pk_bf16_f32 v10, v8, v9
	ds_read2_b32 v[8:9], v4 offset0:2 offset1:67
	v_add_u32_e32 v4, 0x8000, v7
	ds_read2_b32 v[12:13], v4 offset0:128 offset1:193
	s_waitcnt lgkmcnt(0)
	v_cvt_pk_bf16_f32 v9, v8, v9
	v_cvt_pk_bf16_f32 v8, v12, v13
	v_lshl_add_u64 v[12:13], v[2:3], 0, v[0:1]
	v_add_co_u32_e32 v12, vcc, 0x40000, v12
	s_nop 1
	v_addc_co_u32_e32 v13, vcc, 0, v13, vcc
	global_store_dwordx4 v[12:13], v[8:11], off
.LBB0_1464:
	s_or_b64 exec, exec, s[6:7]
	v_add_u32_e32 v0, 0xc0, v5
	v_cmp_gt_u32_e32 vcc, s10, v0
	s_and_saveexec_b64 s[6:7], vcc
	s_cbranch_execz .LBB0_1466
	v_lshlrev_b32_e32 v4, 1, v0
	v_and_b32_e32 v0, 0x7f, v0
	s_movk_i32 s8, 0x1f00
	v_and_or_b32 v0, v4, s8, v0
	v_add_u32_e32 v4, 0xc800, v7
	ds_read2_b32 v[4:5], v4 offset0:70 offset1:135
	v_lshlrev_b32_e32 v0, 11, v0
	v_lshl_add_u64 v[2:3], v[2:3], 0, v[0:1]
	v_add_co_u32_e32 v2, vcc, 0x40000, v2
	s_waitcnt lgkmcnt(0)
	v_cvt_pk_bf16_f32 v11, v4, v5
	v_add_u32_e32 v4, 0xc600, v7
	ds_read2_b32 v[4:5], v4 offset0:68 offset1:133
	v_addc_co_u32_e32 v3, vcc, 0, v3, vcc
	s_waitcnt lgkmcnt(0)
	v_cvt_pk_bf16_f32 v10, v4, v5
	v_add_u32_e32 v4, 0xc400, v7
	ds_read2_b32 v[4:5], v4 offset0:66 offset1:131
	s_waitcnt lgkmcnt(0)
	v_cvt_pk_bf16_f32 v9, v4, v5
	v_add_u32_e32 v4, 0xc200, v7
	ds_read2_b32 v[4:5], v4 offset0:64 offset1:129
	s_waitcnt lgkmcnt(0)
	v_cvt_pk_bf16_f32 v8, v4, v5
	global_store_dwordx4 v[2:3], v[8:11], off

.LBB0_1468:
	s_andn2_b64 vcc, exec, s[6:7]
	s_cbranch_vccnz .LBB0_1230
	v_mov_b32_e32 v0, s64
	v_mov_b32_e32 v2, s65
	v_readlane_b32 s8, v254, 60
	v_readfirstlane_b32 s6, v0
	v_readfirstlane_b32 s7, v2
	v_mov_b32_e32 v8, v247
	v_mov_b32_e32 v2, s6
	v_mov_b32_e32 v3, s7
	global_load_dwordx2 v[2:3], v[2:3], off offset:56
	s_waitcnt vmcnt(0) lgkmcnt(0)
	v_mov_b32_e32 v0, v2
	s_nop 0
	v_readfirstlane_b32 s6, v0
	v_readfirstlane_b32 s7, v3
	s_add_u32 s12, s6, s8
	v_readlane_b32 s6, v254, 58
	s_addc_u32 s13, s7, s6
	s_mul_hi_i32 s6, s1, 0x2e8ba2e9
	s_lshr_b32 s7, s6, 31
	s_ashr_i32 s10, s6, 1
	s_add_i32 s10, s10, s7
	s_mul_i32 s6, s10, 0xfffff500
	s_add_i32 s8, s34, s6
	v_ashrrev_i32_e32 v9, 3, v8
	v_lshlrev_b32_e32 v0, 3, v8
	s_lshl_b32 s6, s10, 6
	v_and_b32_e32 v10, 56, v0
	v_add_u32_e32 v0, s6, v9
	v_mov_b64_e32 v[2:3], s[12:13]
	s_movk_i32 s7, 0x2c00
	v_mad_i64_i32 v[2:3], s[12:13], v0, s7, v[2:3]
	v_lshlrev_b32_e32 v0, 2, v10
	v_lshl_add_u64 v[2:3], v[2:3], 0, v[0:1]
	s_ashr_i32 s9, s8, 31
	s_movk_i32 s7, 0x104
	v_lshl_add_u64 v[6:7], s[8:9], 2, v[2:3]
	v_mul_lo_u32 v2, v9, s7
	v_add_u32_e32 v11, 16, v2
	global_load_dwordx4 v[2:5], v[6:7], off
	v_add_u32_e32 v0, v11, v0
	v_add_u32_e32 v12, 0x4100, v0
	s_ashr_i32 s7, s6, 31
	s_lshl_b64 s[6:7], s[6:7], 1
	s_add_u32 s6, s0, s6
	s_addc_u32 s7, s4, s7
	s_mulk_i32 s10, 0xb00
	s_waitcnt vmcnt(0) lgkmcnt(0)
	ds_write2_b32 v0, v2, v3 offset1:1
	ds_write2_b32 v0, v4, v5 offset0:2 offset1:3
	global_load_dwordx4 v[2:5], v[6:7], off offset:16
	s_waitcnt vmcnt(0) lgkmcnt(0)
	ds_write2_b32 v0, v2, v3 offset0:4 offset1:5
	ds_write2_b32 v0, v4, v5 offset0:6 offset1:7
	global_load_dwordx4 v[2:5], v[6:7], off offset:256
	s_waitcnt vmcnt(0) lgkmcnt(0)
	ds_write2_b32 v12, v2, v3 offset1:1
	v_add_u32_e32 v2, 0x4108, v0
	ds_write2_b32 v2, v4, v5 offset1:1
	global_load_dwordx4 v[2:5], v[6:7], off offset:272
	v_add_u32_e32 v12, 0x4110, v0
	s_waitcnt vmcnt(0) lgkmcnt(0)
	ds_write2_b32 v12, v2, v3 offset1:1
	v_add_u32_e32 v2, 0x4118, v0
	ds_write2_b32 v2, v4, v5 offset1:1
	global_load_dwordx4 v[2:5], v[6:7], off offset:512
	v_add_u32_e32 v12, 0x8200, v0
	s_waitcnt vmcnt(0) lgkmcnt(0)
	ds_write2_b32 v12, v2, v3 offset1:1
	v_add_u32_e32 v2, 0x8208, v0
	ds_write2_b32 v2, v4, v5 offset1:1
	global_load_dwordx4 v[2:5], v[6:7], off offset:528
	v_add_u32_e32 v12, 0x8210, v0
	s_waitcnt vmcnt(0) lgkmcnt(0)
	ds_write2_b32 v12, v2, v3 offset1:1
	v_add_u32_e32 v2, 0x8218, v0
	ds_write2_b32 v2, v4, v5 offset1:1
	global_load_dwordx4 v[2:5], v[6:7], off offset:768
	v_add_u32_e32 v12, 0xc300, v0
	s_waitcnt vmcnt(0) lgkmcnt(0)
	ds_write2_b32 v12, v2, v3 offset1:1
	v_add_u32_e32 v2, 0xc308, v0
	ds_write2_b32 v2, v4, v5 offset1:1
	global_load_dwordx4 v[2:5], v[6:7], off offset:784
	v_add_u32_e32 v12, 0xc310, v0
	v_add_u32_e32 v0, 0xc318, v0
	v_mul_u32_u24_e32 v7, 0x104, v10
	s_waitcnt vmcnt(0) lgkmcnt(0)
	ds_write2_b32 v0, v4, v5 offset1:1
	v_lshlrev_b32_e32 v0, 8, v9
	v_sub_u32_e32 v6, v11, v0
	v_lshlrev_b32_e32 v0, 1, v10
	ds_write2_b32 v12, v2, v3 offset1:1
	v_lshl_add_u64 v[2:3], s[6:7], 0, v[0:1]
	v_subrev_u32_e32 v0, s10, v9
	v_add_u32_e32 v4, s34, v0
	s_movk_i32 s10, 0xb00
	v_cmp_gt_u32_e32 vcc, s10, v4
	v_bfe_u32 v5, v8, 3, 7
	v_add_u32_e32 v6, v6, v7
	s_waitcnt lgkmcnt(0)
	s_barrier
	s_and_saveexec_b64 s[6:7], vcc
	s_cbranch_execz .LBB0_1471
	v_add_u32_e32 v7, 0x400, v6
	ds_read2_b32 v[8:9], v7 offset0:134 offset1:199
	ds_read2_b32 v[12:13], v6 offset1:65
	v_lshlrev_b32_e32 v0, 1, v4
	s_movk_i32 s8, 0x1f00
	v_and_or_b32 v0, v0, s8, v5
	s_waitcnt lgkmcnt(1)
	v_cvt_pk_bf16_f32 v11, v8, v9
	ds_read2_b32 v[8:9], v7 offset0:4 offset1:69
	v_lshlrev_b32_e32 v0, 11, v0
	s_waitcnt lgkmcnt(0)
	v_cvt_pk_bf16_f32 v10, v8, v9
	ds_read2_b32 v[8:9], v6 offset0:130 offset1:195
	s_waitcnt lgkmcnt(0)
	v_cvt_pk_bf16_f32 v9, v8, v9
	v_cvt_pk_bf16_f32 v8, v12, v13
	v_lshl_add_u64 v[12:13], v[2:3], 0, v[0:1]
	global_store_dwordx4 v[12:13], v[8:11], off
.LBB0_1471:
	s_or_b64 exec, exec, s[6:7]
	v_add_u32_e32 v0, 64, v4
	v_cmp_gt_u32_e32 vcc, s10, v0
	s_and_saveexec_b64 s[6:7], vcc
	s_cbranch_execz .LBB0_1473
	v_lshlrev_b32_e32 v7, 1, v0
	v_and_b32_e32 v0, 0x7f, v0
	s_movk_i32 s8, 0x1f00
	v_and_or_b32 v0, v7, s8, v0
	v_add_u32_e32 v7, 0x4600, v6
	ds_read2_b32 v[8:9], v7 offset0:70 offset1:135
	v_add_u32_e32 v7, 0x4400, v6
	v_lshlrev_b32_e32 v0, 11, v0
	s_waitcnt lgkmcnt(0)
	v_cvt_pk_bf16_f32 v11, v8, v9
	ds_read2_b32 v[8:9], v7 offset0:68 offset1:133
	v_add_u32_e32 v7, 0x4200, v6
	s_waitcnt lgkmcnt(0)
	v_cvt_pk_bf16_f32 v10, v8, v9
	ds_read2_b32 v[8:9], v7 offset0:66 offset1:131
	v_add_u32_e32 v7, 0x4000, v6
	ds_read2_b32 v[12:13], v7 offset0:64 offset1:129
	s_waitcnt lgkmcnt(0)
	v_cvt_pk_bf16_f32 v9, v8, v9
	v_cvt_pk_bf16_f32 v8, v12, v13
	v_lshl_add_u64 v[12:13], v[2:3], 0, v[0:1]
	global_store_dwordx4 v[12:13], v[8:11], off
.LBB0_1473:
	s_or_b64 exec, exec, s[6:7]
	v_add_u32_e32 v0, 0x80, v4
	v_cmp_gt_u32_e32 vcc, s10, v0
	s_and_saveexec_b64 s[6:7], vcc
	s_cbranch_execz .LBB0_1475
	v_lshlrev_b32_e32 v0, 1, v0
	s_movk_i32 s8, 0x1f00
	v_and_or_b32 v0, v0, s8, v5
	v_add_u32_e32 v5, 0x8800, v6
	ds_read2_b32 v[8:9], v5 offset0:6 offset1:71
	v_add_u32_e32 v5, 0x8400, v6
	v_lshlrev_b32_e32 v0, 11, v0
	s_waitcnt lgkmcnt(0)
	v_cvt_pk_bf16_f32 v11, v8, v9
	ds_read2_b32 v[8:9], v5 offset0:132 offset1:197
	s_waitcnt lgkmcnt(0)
	v_cvt_pk_bf16_f32 v10, v8, v9
	ds_read2_b32 v[8:9], v5 offset0:2 offset1:67
	v_add_u32_e32 v5, 0x8000, v6
	ds_read2_b32 v[12:13], v5 offset0:128 offset1:193
	s_waitcnt lgkmcnt(0)
	v_cvt_pk_bf16_f32 v9, v8, v9
	v_cvt_pk_bf16_f32 v8, v12, v13
	v_lshl_add_u64 v[12:13], v[2:3], 0, v[0:1]
	global_store_dwordx4 v[12:13], v[8:11], off
.LBB0_1475:
	s_or_b64 exec, exec, s[6:7]
	v_add_u32_e32 v0, 0xc0, v4
	v_cmp_gt_u32_e32 vcc, s10, v0
	s_and_saveexec_b64 s[6:7], vcc
	s_cbranch_execz .LBB0_1229
	v_lshlrev_b32_e32 v4, 1, v0
	v_and_b32_e32 v0, 0x7f, v0
	s_movk_i32 s8, 0x1f00
	v_and_or_b32 v0, v4, s8, v0
	v_add_u32_e32 v4, 0xc800, v6
	ds_read2_b32 v[4:5], v4 offset0:70 offset1:135
	v_lshlrev_b32_e32 v0, 11, v0
	v_lshl_add_u64 v[2:3], v[2:3], 0, v[0:1]
	s_waitcnt lgkmcnt(0)
	v_cvt_pk_bf16_f32 v9, v4, v5
	v_add_u32_e32 v4, 0xc600, v6
	ds_read2_b32 v[4:5], v4 offset0:68 offset1:133
	s_waitcnt lgkmcnt(0)
	v_cvt_pk_bf16_f32 v8, v4, v5
	v_add_u32_e32 v4, 0xc400, v6
	ds_read2_b32 v[4:5], v4 offset0:66 offset1:131
	s_waitcnt lgkmcnt(0)
	v_cvt_pk_bf16_f32 v7, v4, v5
	v_add_u32_e32 v4, 0xc200, v6
	ds_read2_b32 v[4:5], v4 offset0:64 offset1:129
	s_waitcnt lgkmcnt(0)
	v_cvt_pk_bf16_f32 v6, v4, v5
	global_store_dwordx4 v[2:3], v[6:9], off
	s_branch .LBB0_1229

.LBB0_1478:
	v_readlane_b32 s0, v255, 0
	v_readlane_b32 s4, v255, 8
	v_readlane_b32 s1, v255, 1
	v_readlane_b32 s5, v255, 9
	s_and_b64 s[0:1], s[0:1], s[4:5]
	s_andn2_b64 vcc, exec, s[0:1]
	s_cbranch_vccnz .LBB0_1791
	v_mov_b32_e32 v0, s64
	v_mov_b32_e32 v2, s65
	s_waitcnt vmcnt(0)
	s_barrier
	s_nop 0
	v_readfirstlane_b32 s0, v0
	v_readfirstlane_b32 s1, v2
	v_mov_b32_e32 v0, s88
	v_mov_b32_e32 v2, s0
	v_mov_b32_e32 v3, s1
	global_load_dwordx2 v[2:3], v[2:3], off offset:248
	s_waitcnt vmcnt(0) lgkmcnt(0)
	s_nop 0
	v_readfirstlane_b32 s4, v0
	v_readfirstlane_b32 s0, v2
	s_cmp_lt_i32 s4, 0
	v_readfirstlane_b32 s1, v3
	s_cbranch_scc1 .LBB0_1791
	s_addk_i32 s4, 0x3d0
	s_cmpk_gt_i32 s4, 0x65f
	s_cbranch_scc1 .LBB0_1791
	s_add_u32 s5, s0, 0x2d80000
	s_addc_u32 s20, s1, 0
	s_add_u32 s21, s0, 0x2280000
	s_addc_u32 s33, s1, 0
	s_add_u32 s34, s0, 0x2080000
	s_addc_u32 s35, s1, 0
	s_add_u32 s46, s0, 0x1e80000
	s_addc_u32 s47, s1, 0
	s_add_u32 s48, s0, 0x1080000
	s_addc_u32 s49, s1, 0
	s_add_u32 s50, s0, 0xb00000
	v_readlane_b32 s6, v253, 0
	s_addc_u32 s51, s1, 0
	s_lshl_b32 s52, s4, 8
	s_lshl_b32 s53, s6, 8
	s_lshl_b32 s54, s4, 4
	s_lshl_b32 s55, s6, 4
	v_readlane_b32 s7, v253, 1
	s_branch .LBB0_1484

.LBB0_1484:
	s_cmpk_gt_i32 s4, 0xaf
	s_mov_b64 s[6:7], -1
	s_cbranch_scc0 .LBB0_1781
	s_cmpk_gt_u32 s4, 0x15f
	s_cbranch_scc0 .LBB0_1770
	s_cmpk_gt_u32 s4, 0x20f
	s_cbranch_scc0 .LBB0_1759
	s_cmpk_gt_u32 s4, 0x3cf
	s_cbranch_scc0 .LBB0_1544
	s_cmpk_gt_u32 s4, 0x40f
	s_cbranch_scc0 .LBB0_1533
	s_cmpk_gt_u32 s4, 0x44f
	s_cbranch_scc0 .LBB0_1522
	s_cmpk_gt_u32 s4, 0x4ff
	s_cbranch_scc0 .LBB0_1511
	s_cmpk_gt_u32 s4, 0x5af
	s_cbranch_scc0 .LBB0_1501
	v_mov_b32_e32 v0, s64
	v_mov_b32_e32 v2, s65
	v_readlane_b32 s8, v254, 59
	v_readfirstlane_b32 s6, v0
	v_readfirstlane_b32 s7, v2
	s_nop 0
	v_mov_b32_e32 v2, s6
	v_mov_b32_e32 v3, s7
	global_load_dwordx2 v[2:3], v[2:3], off offset:224
	s_waitcnt vmcnt(0) lgkmcnt(0)
	v_mov_b32_e32 v0, v3
	s_nop 0
	v_readfirstlane_b32 s6, v2
	v_readfirstlane_b32 s7, v0
	s_add_u32 s10, s6, s8
	v_readlane_b32 s6, v255, 2
	s_addc_u32 s11, s7, s6
	v_mov_b32_e32 v0, v247
	s_and_b32 s6, s54, 0xffffffc0
	s_addk_i32 s6, 0xa500
	v_ashrrev_i32_e32 v4, 3, v0
	v_add_u32_e32 v2, s6, v4
	v_lshlrev_b32_e32 v0, 3, v0
	v_ashrrev_i32_e32 v3, 31, v2
	v_and_b32_e32 v5, 56, v0
	v_lshlrev_b64 v[2:3], 12, v[2:3]
	s_and_b32 s8, s52, 0x300
	v_lshl_add_u64 v[2:3], s[10:11], 0, v[2:3]
	v_lshlrev_b32_e32 v0, 2, v5
	v_lshl_add_u64 v[2:3], v[2:3], 0, v[0:1]
	s_lshl_b32 s18, s8, 2
	s_movk_i32 s7, 0x104
	v_lshl_add_u64 v[2:3], v[2:3], 0, s[18:19]
	v_mul_lo_u32 v6, v4, s7
	v_add_u32_e32 v10, 16, v6
	global_load_dwordx4 v[6:9], v[2:3], off
	v_add_u32_e32 v0, v10, v0
	v_add_u32_e32 v11, 0x4100, v0
	s_mov_b32 s7, s19
	s_lshl_b64 s[6:7], s[6:7], 1
	s_add_u32 s6, s5, s6
	s_addc_u32 s7, s20, s7
	s_waitcnt vmcnt(0) lgkmcnt(0)
	ds_write2_b32 v0, v6, v7 offset1:1
	ds_write2_b32 v0, v8, v9 offset0:2 offset1:3
	global_load_dwordx4 v[6:9], v[2:3], off offset:16
	s_waitcnt vmcnt(0) lgkmcnt(0)
	ds_write2_b32 v0, v6, v7 offset0:4 offset1:5
	ds_write2_b32 v0, v8, v9 offset0:6 offset1:7
	global_load_dwordx4 v[6:9], v[2:3], off offset:256
	s_waitcnt vmcnt(0) lgkmcnt(0)
	ds_write2_b32 v11, v6, v7 offset1:1
	v_add_u32_e32 v6, 0x4108, v0
	ds_write2_b32 v6, v8, v9 offset1:1
	global_load_dwordx4 v[6:9], v[2:3], off offset:272
	v_add_u32_e32 v11, 0x4110, v0
	s_waitcnt vmcnt(0) lgkmcnt(0)
	ds_write2_b32 v11, v6, v7 offset1:1
	v_add_u32_e32 v6, 0x4118, v0
	ds_write2_b32 v6, v8, v9 offset1:1
	global_load_dwordx4 v[6:9], v[2:3], off offset:512
	v_add_u32_e32 v11, 0x8200, v0
	s_waitcnt vmcnt(0) lgkmcnt(0)
	ds_write2_b32 v11, v6, v7 offset1:1
	v_add_u32_e32 v6, 0x8208, v0
	ds_write2_b32 v6, v8, v9 offset1:1
	global_load_dwordx4 v[6:9], v[2:3], off offset:528
	v_add_u32_e32 v11, 0x8210, v0
	s_waitcnt vmcnt(0) lgkmcnt(0)
	ds_write2_b32 v11, v6, v7 offset1:1
	v_add_u32_e32 v6, 0x8218, v0
	ds_write2_b32 v6, v8, v9 offset1:1
	global_load_dwordx4 v[6:9], v[2:3], off offset:768
	v_add_u32_e32 v11, 0xc300, v0
	s_waitcnt vmcnt(0) lgkmcnt(0)
	ds_write2_b32 v11, v6, v7 offset1:1
	v_add_u32_e32 v6, 0xc308, v0
	ds_write2_b32 v6, v8, v9 offset1:1
	global_load_dwordx4 v[6:9], v[2:3], off offset:784
	v_add_u32_e32 v11, 0xc310, v0
	v_add_u32_e32 v0, 0xc318, v0
	s_waitcnt vmcnt(0) lgkmcnt(0)
	ds_write2_b32 v0, v8, v9 offset1:1
	v_lshlrev_b32_e32 v0, 8, v4
	ds_write2_b32 v11, v6, v7 offset1:1
	v_sub_u32_e32 v6, v10, v0
	v_lshlrev_b32_e32 v0, 1, v5
	v_mul_u32_u24_e32 v7, 0x104, v5
	v_lshl_add_u64 v[2:3], s[6:7], 0, v[0:1]
	v_add_u32_e32 v5, s8, v4
	s_movk_i32 s6, 0x400
	v_cmp_gt_u32_e32 vcc, s6, v5
	v_add_u32_e32 v6, v6, v7
	s_waitcnt lgkmcnt(0)
	s_barrier
	s_and_saveexec_b64 s[6:7], vcc
	s_cbranch_execz .LBB0_1494
	v_add_u32_e32 v0, 0x400, v6
	ds_read2_b32 v[8:9], v0 offset0:134 offset1:199
	ds_read2_b32 v[12:13], v6 offset1:65
	s_movk_i32 s9, 0x1600
	s_waitcnt lgkmcnt(1)
	v_cvt_pk_bf16_f32 v11, v8, v9
	ds_read2_b32 v[8:9], v0 offset0:4 offset1:69
	v_mul_lo_u32 v0, v5, s9
	s_waitcnt lgkmcnt(0)
	v_cvt_pk_bf16_f32 v10, v8, v9
	ds_read2_b32 v[8:9], v6 offset0:130 offset1:195
	s_waitcnt lgkmcnt(0)
	v_cvt_pk_bf16_f32 v9, v8, v9
	v_cvt_pk_bf16_f32 v8, v12, v13
	v_lshl_add_u64 v[12:13], v[2:3], 0, v[0:1]
	global_store_dwordx4 v[12:13], v[8:11], off

.LBB0_1501:
	s_and_b64 vcc, exec, s[6:7]
	s_cbranch_vccz .LBB0_1790
	v_mov_b32_e32 v0, s64
	v_mov_b32_e32 v2, s65
	v_readlane_b32 s8, v254, 59
	v_readfirstlane_b32 s6, v0
	v_readfirstlane_b32 s7, v2
	v_mov_b32_e32 v10, v247
	v_mov_b32_e32 v2, s6
	v_mov_b32_e32 v3, s7
	global_load_dwordx2 v[2:3], v[2:3], off offset:216
	s_waitcnt vmcnt(0) lgkmcnt(0)
	v_mov_b32_e32 v0, v3
	s_nop 0
	v_readfirstlane_b32 s6, v2
	v_readfirstlane_b32 s7, v0
	s_add_u32 s6, s6, s8
	v_readlane_b32 s8, v255, 2
	s_addc_u32 s7, s7, s8
	s_and_b32 s8, s4, 0xff
	s_mulk_i32 s8, 0x75
	s_lshr_b32 s8, s8, 8
	s_sub_i32 s9, s4, s8
	s_bfe_u32 s9, s9, 0x70001
	s_add_i32 s9, s9, s8
	s_bfe_u32 s9, s9, 0x50003
	s_mul_i32 s8, s9, 11
	s_sub_i32 s8, s4, s8
	v_ashrrev_i32_e32 v4, 3, v10
	v_lshlrev_b32_e32 v0, 3, v10
	s_lshl_b32 s8, s8, 2
	v_and_b32_e32 v5, 56, v0
	v_lshl_add_u32 v0, s9, 6, v4
	v_mov_b64_e32 v[2:3], s[6:7]
	s_movk_i32 s6, 0x2c00
	s_and_b32 s10, s8, 0xfc
	v_mad_i64_i32 v[2:3], s[6:7], v0, s6, v[2:3]
	v_lshlrev_b32_e32 v0, 2, v5
	v_lshl_add_u64 v[2:3], v[2:3], 0, v[0:1]
	s_lshl_b32 s18, s10, 8
	s_movk_i32 s6, 0x104
	v_lshl_add_u64 v[2:3], v[2:3], 0, s[18:19]
	v_mul_lo_u32 v6, v4, s6
	v_add_u32_e32 v11, 16, v6
	global_load_dwordx4 v[6:9], v[2:3], off
	v_add_u32_e32 v0, v11, v0
	v_add_u32_e32 v12, 0x4100, v0
	s_lshl_b32 s8, s10, 6
	s_lshl_b32 s6, s9, 7
	s_add_u32 s6, s21, s6
	s_addc_u32 s7, s33, 0
	s_waitcnt vmcnt(0) lgkmcnt(0)
	ds_write2_b32 v0, v6, v7 offset1:1
	ds_write2_b32 v0, v8, v9 offset0:2 offset1:3
	global_load_dwordx4 v[6:9], v[2:3], off offset:16
	s_waitcnt vmcnt(0) lgkmcnt(0)
	ds_write2_b32 v0, v6, v7 offset0:4 offset1:5
	ds_write2_b32 v0, v8, v9 offset0:6 offset1:7
	global_load_dwordx4 v[6:9], v[2:3], off offset:256
	s_waitcnt vmcnt(0) lgkmcnt(0)
	ds_write2_b32 v12, v6, v7 offset1:1
	v_add_u32_e32 v6, 0x4108, v0
	ds_write2_b32 v6, v8, v9 offset1:1
	global_load_dwordx4 v[6:9], v[2:3], off offset:272
	v_add_u32_e32 v12, 0x4110, v0
	s_waitcnt vmcnt(0) lgkmcnt(0)
	ds_write2_b32 v12, v6, v7 offset1:1
	v_add_u32_e32 v6, 0x4118, v0
	ds_write2_b32 v6, v8, v9 offset1:1
	global_load_dwordx4 v[6:9], v[2:3], off offset:512
	v_add_u32_e32 v12, 0x8200, v0
	s_waitcnt vmcnt(0) lgkmcnt(0)
	ds_write2_b32 v12, v6, v7 offset1:1
	v_add_u32_e32 v6, 0x8208, v0
	ds_write2_b32 v6, v8, v9 offset1:1
	global_load_dwordx4 v[6:9], v[2:3], off offset:528
	v_add_u32_e32 v12, 0x8210, v0
	s_waitcnt vmcnt(0) lgkmcnt(0)
	ds_write2_b32 v12, v6, v7 offset1:1
	v_add_u32_e32 v6, 0x8218, v0
	ds_write2_b32 v6, v8, v9 offset1:1
	global_load_dwordx4 v[6:9], v[2:3], off offset:768
	v_add_u32_e32 v12, 0xc300, v0
	s_waitcnt vmcnt(0) lgkmcnt(0)
	ds_write2_b32 v12, v6, v7 offset1:1
	v_add_u32_e32 v6, 0xc308, v0
	ds_write2_b32 v6, v8, v9 offset1:1
	global_load_dwordx4 v[6:9], v[2:3], off offset:784
	v_add_u32_e32 v12, 0xc310, v0
	v_add_u32_e32 v0, 0xc318, v0
	s_waitcnt vmcnt(0) lgkmcnt(0)
	ds_write2_b32 v0, v8, v9 offset1:1
	v_lshlrev_b32_e32 v0, 8, v4
	ds_write2_b32 v12, v6, v7 offset1:1
	v_sub_u32_e32 v7, v11, v0
	v_lshlrev_b32_e32 v0, 1, v5
	v_mul_u32_u24_e32 v8, 0x104, v5
	v_lshl_add_u64 v[2:3], s[6:7], 0, v[0:1]
	v_add_u32_e32 v5, s8, v4
	s_movk_i32 s6, 0xb00
	v_cmp_gt_u32_e32 vcc, s6, v5
	v_bfe_u32 v6, v10, 3, 7
	v_add_u32_e32 v7, v7, v8
	s_waitcnt lgkmcnt(0)
	s_barrier
	s_and_saveexec_b64 s[6:7], vcc
	s_cbranch_execz .LBB0_1504
	v_add_u32_e32 v10, 0x400, v7
	ds_read2_b32 v[8:9], v10 offset0:134 offset1:199
	ds_read2_b32 v[12:13], v7 offset1:65
	v_lshlrev_b32_e32 v0, 1, v5
	s_movk_i32 s9, 0x1f00
	v_and_or_b32 v0, v0, s9, v6
	s_waitcnt lgkmcnt(1)
	v_cvt_pk_bf16_f32 v11, v8, v9
	ds_read2_b32 v[8:9], v10 offset0:4 offset1:69
	v_lshlrev_b32_e32 v0, 11, v0
	s_waitcnt lgkmcnt(0)
	v_cvt_pk_bf16_f32 v10, v8, v9
	ds_read2_b32 v[8:9], v7 offset0:130 offset1:195
	s_waitcnt lgkmcnt(0)
	v_cvt_pk_bf16_f32 v9, v8, v9
	v_cvt_pk_bf16_f32 v8, v12, v13
	v_lshl_add_u64 v[12:13], v[2:3], 0, v[0:1]
	v_add_co_u32_e32 v12, vcc, 0x40000, v12
	s_nop 1
	v_addc_co_u32_e32 v13, vcc, 0, v13, vcc
	global_store_dwordx4 v[12:13], v[8:11], off

.LBB0_1512:
	v_mov_b32_e32 v0, s64
	v_mov_b32_e32 v2, s65
	v_readlane_b32 s8, v254, 59
	v_readfirstlane_b32 s6, v0
	v_readfirstlane_b32 s7, v2
	v_mov_b32_e32 v10, v247
	v_mov_b32_e32 v2, s6
	v_mov_b32_e32 v3, s7
	global_load_dwordx2 v[2:3], v[2:3], off offset:208
	s_waitcnt vmcnt(0) lgkmcnt(0)
	v_mov_b32_e32 v0, v3
	s_nop 0
	v_readfirstlane_b32 s6, v2
	v_readfirstlane_b32 s7, v0
	s_add_u32 s6, s6, s8
	v_readlane_b32 s8, v255, 2
	s_addc_u32 s7, s7, s8
	s_add_i32 s8, s4, 0xffb0
	s_and_b32 s9, s8, 0xff
	s_mulk_i32 s9, 0x75
	s_lshr_b32 s10, s9, 8
	s_sub_i32 s10, s8, s10
	s_bfe_u32 s10, s10, 0x70001
	s_bfe_u32 s9, s9, 0x80008
	s_add_i32 s10, s10, s9
	s_bfe_u32 s9, s10, 0x50003
	s_mul_i32 s10, s9, 11
	s_sub_i32 s8, s8, s10
	v_ashrrev_i32_e32 v4, 3, v10
	v_lshlrev_b32_e32 v0, 3, v10
	s_lshl_b32 s8, s8, 2
	v_and_b32_e32 v5, 56, v0
	v_lshl_add_u32 v0, s9, 6, v4
	v_mov_b64_e32 v[2:3], s[6:7]
	s_movk_i32 s6, 0x2c00
	s_and_b32 s10, s8, 0xfc
	v_mad_i64_i32 v[2:3], s[6:7], v0, s6, v[2:3]
	v_lshlrev_b32_e32 v0, 2, v5
	v_lshl_add_u64 v[2:3], v[2:3], 0, v[0:1]
	s_lshl_b32 s18, s10, 8
	s_movk_i32 s6, 0x104
	v_lshl_add_u64 v[2:3], v[2:3], 0, s[18:19]
	v_mul_lo_u32 v6, v4, s6
	v_add_u32_e32 v11, 16, v6
	global_load_dwordx4 v[6:9], v[2:3], off
	v_add_u32_e32 v0, v11, v0
	v_add_u32_e32 v12, 0x4100, v0
	s_lshl_b32 s8, s10, 6
	s_lshl_b32 s6, s9, 7
	s_add_u32 s6, s21, s6
	s_addc_u32 s7, s33, 0
	s_waitcnt vmcnt(0) lgkmcnt(0)
	ds_write2_b32 v0, v6, v7 offset1:1
	ds_write2_b32 v0, v8, v9 offset0:2 offset1:3
	global_load_dwordx4 v[6:9], v[2:3], off offset:16
	s_waitcnt vmcnt(0) lgkmcnt(0)
	ds_write2_b32 v0, v6, v7 offset0:4 offset1:5
	ds_write2_b32 v0, v8, v9 offset0:6 offset1:7
	global_load_dwordx4 v[6:9], v[2:3], off offset:256
	s_waitcnt vmcnt(0) lgkmcnt(0)
	ds_write2_b32 v12, v6, v7 offset1:1
	v_add_u32_e32 v6, 0x4108, v0
	ds_write2_b32 v6, v8, v9 offset1:1
	global_load_dwordx4 v[6:9], v[2:3], off offset:272
	v_add_u32_e32 v12, 0x4110, v0
	s_waitcnt vmcnt(0) lgkmcnt(0)
	ds_write2_b32 v12, v6, v7 offset1:1
	v_add_u32_e32 v6, 0x4118, v0
	ds_write2_b32 v6, v8, v9 offset1:1
	global_load_dwordx4 v[6:9], v[2:3], off offset:512
	v_add_u32_e32 v12, 0x8200, v0
	s_waitcnt vmcnt(0) lgkmcnt(0)
	ds_write2_b32 v12, v6, v7 offset1:1
	v_add_u32_e32 v6, 0x8208, v0
	ds_write2_b32 v6, v8, v9 offset1:1
	global_load_dwordx4 v[6:9], v[2:3], off offset:528
	v_add_u32_e32 v12, 0x8210, v0
	s_waitcnt vmcnt(0) lgkmcnt(0)
	ds_write2_b32 v12, v6, v7 offset1:1
	v_add_u32_e32 v6, 0x8218, v0
	ds_write2_b32 v6, v8, v9 offset1:1
	global_load_dwordx4 v[6:9], v[2:3], off offset:768
	v_add_u32_e32 v12, 0xc300, v0
	s_waitcnt vmcnt(0) lgkmcnt(0)
	ds_write2_b32 v12, v6, v7 offset1:1
	v_add_u32_e32 v6, 0xc308, v0
	ds_write2_b32 v6, v8, v9 offset1:1
	global_load_dwordx4 v[6:9], v[2:3], off offset:784
	v_add_u32_e32 v12, 0xc310, v0
	v_add_u32_e32 v0, 0xc318, v0
	s_waitcnt vmcnt(0) lgkmcnt(0)
	ds_write2_b32 v0, v8, v9 offset1:1
	v_lshlrev_b32_e32 v0, 8, v4
	ds_write2_b32 v12, v6, v7 offset1:1
	v_sub_u32_e32 v7, v11, v0
	v_lshlrev_b32_e32 v0, 1, v5
	v_mul_u32_u24_e32 v8, 0x104, v5
	v_lshl_add_u64 v[2:3], s[6:7], 0, v[0:1]
	v_add_u32_e32 v5, s8, v4
	s_movk_i32 s6, 0xb00
	v_cmp_gt_u32_e32 vcc, s6, v5
	v_bfe_u32 v6, v10, 3, 7
	v_add_u32_e32 v7, v7, v8
	s_waitcnt lgkmcnt(0)
	s_barrier
	s_and_saveexec_b64 s[6:7], vcc
	s_cbranch_execz .LBB0_1514
	v_add_u32_e32 v10, 0x400, v7
	ds_read2_b32 v[8:9], v10 offset0:134 offset1:199
	ds_read2_b32 v[12:13], v7 offset1:65
	v_lshlrev_b32_e32 v0, 1, v5
	s_movk_i32 s9, 0x1f00
	v_and_or_b32 v0, v0, s9, v6
	s_waitcnt lgkmcnt(1)
	v_cvt_pk_bf16_f32 v11, v8, v9
	ds_read2_b32 v[8:9], v10 offset0:4 offset1:69
	v_lshlrev_b32_e32 v0, 11, v0
	s_waitcnt lgkmcnt(0)
	v_cvt_pk_bf16_f32 v10, v8, v9
	ds_read2_b32 v[8:9], v7 offset0:130 offset1:195
	s_waitcnt lgkmcnt(0)
	v_cvt_pk_bf16_f32 v9, v8, v9
	v_cvt_pk_bf16_f32 v8, v12, v13
	v_lshl_add_u64 v[12:13], v[2:3], 0, v[0:1]
	global_store_dwordx4 v[12:13], v[8:11], off
.LBB0_1514:
	s_or_b64 exec, exec, s[6:7]
	v_add3_u32 v0, v4, s8, 64
	s_movk_i32 s10, 0xb00
	v_cmp_gt_u32_e32 vcc, s10, v0
	s_and_saveexec_b64 s[6:7], vcc
	s_cbranch_execz .LBB0_1516
	v_lshlrev_b32_e32 v4, 1, v0
	v_and_b32_e32 v0, 0x7f, v0
	s_movk_i32 s8, 0x1f00
	v_and_or_b32 v0, v4, s8, v0
	v_add_u32_e32 v4, 0x4600, v7
	ds_read2_b32 v[8:9], v4 offset0:70 offset1:135
	v_add_u32_e32 v4, 0x4400, v7
	v_lshlrev_b32_e32 v0, 11, v0
	s_waitcnt lgkmcnt(0)
	v_cvt_pk_bf16_f32 v11, v8, v9
	ds_read2_b32 v[8:9], v4 offset0:68 offset1:133
	v_add_u32_e32 v4, 0x4200, v7
	s_waitcnt lgkmcnt(0)
	v_cvt_pk_bf16_f32 v10, v8, v9
	ds_read2_b32 v[8:9], v4 offset0:66 offset1:131
	v_add_u32_e32 v4, 0x4000, v7
	ds_read2_b32 v[12:13], v4 offset0:64 offset1:129
	s_waitcnt lgkmcnt(0)
	v_cvt_pk_bf16_f32 v9, v8, v9
	v_cvt_pk_bf16_f32 v8, v12, v13
	v_lshl_add_u64 v[12:13], v[2:3], 0, v[0:1]
	global_store_dwordx4 v[12:13], v[8:11], off
.LBB0_1516:
	s_or_b64 exec, exec, s[6:7]
	v_add_u32_e32 v0, 0x80, v5
	v_cmp_gt_u32_e32 vcc, s10, v0
	s_and_saveexec_b64 s[6:7], vcc
	s_cbranch_execz .LBB0_1518
	v_add_u32_e32 v4, 0x8800, v7
	ds_read2_b32 v[8:9], v4 offset0:6 offset1:71
	v_add_u32_e32 v4, 0x8400, v7
	v_lshlrev_b32_e32 v0, 1, v0
	s_movk_i32 s8, 0x1f00
	v_and_or_b32 v0, v0, s8, v6
	s_waitcnt lgkmcnt(0)
	v_cvt_pk_bf16_f32 v11, v8, v9
	ds_read2_b32 v[8:9], v4 offset0:132 offset1:197
	v_lshlrev_b32_e32 v0, 11, v0
	s_waitcnt lgkmcnt(0)
	v_cvt_pk_bf16_f32 v10, v8, v9
	ds_read2_b32 v[8:9], v4 offset0:2 offset1:67
	v_add_u32_e32 v4, 0x8000, v7
	ds_read2_b32 v[12:13], v4 offset0:128 offset1:193
	s_waitcnt lgkmcnt(0)
	v_cvt_pk_bf16_f32 v9, v8, v9
	v_cvt_pk_bf16_f32 v8, v12, v13
	v_lshl_add_u64 v[12:13], v[2:3], 0, v[0:1]
	global_store_dwordx4 v[12:13], v[8:11], off
.LBB0_1518:
	s_or_b64 exec, exec, s[6:7]
	v_add_u32_e32 v0, 0xc0, v5
	v_cmp_gt_u32_e32 vcc, s10, v0
	s_and_saveexec_b64 s[6:7], vcc
	s_cbranch_execz .LBB0_1520
	v_lshlrev_b32_e32 v4, 1, v0
	v_and_b32_e32 v0, 0x7f, v0
	s_movk_i32 s8, 0x1f00
	v_and_or_b32 v0, v4, s8, v0
	v_add_u32_e32 v4, 0xc800, v7
	ds_read2_b32 v[4:5], v4 offset0:70 offset1:135
	v_lshlrev_b32_e32 v0, 11, v0
	v_lshl_add_u64 v[2:3], v[2:3], 0, v[0:1]
	s_waitcnt lgkmcnt(0)
	v_cvt_pk_bf16_f32 v11, v4, v5
	v_add_u32_e32 v4, 0xc600, v7
	ds_read2_b32 v[4:5], v4 offset0:68 offset1:133
	s_waitcnt lgkmcnt(0)
	v_cvt_pk_bf16_f32 v10, v4, v5
	v_add_u32_e32 v4, 0xc400, v7
	ds_read2_b32 v[4:5], v4 offset0:66 offset1:131
	s_waitcnt lgkmcnt(0)
	v_cvt_pk_bf16_f32 v9, v4, v5
	v_add_u32_e32 v4, 0xc200, v7
	ds_read2_b32 v[4:5], v4 offset0:64 offset1:129
	s_waitcnt lgkmcnt(0)
	v_cvt_pk_bf16_f32 v8, v4, v5
	global_store_dwordx4 v[2:3], v[8:11], off

.LBB0_1522:
	s_andn2_b64 vcc, exec, s[6:7]
	s_cbranch_vccnz .LBB0_1532
	v_mov_b32_e32 v0, s64
	v_mov_b32_e32 v2, s65
	v_readlane_b32 s8, v255, 3
	v_readfirstlane_b32 s6, v0
	v_readfirstlane_b32 s7, v2
	v_readlane_b32 s9, v255, 4
	v_mov_b32_e32 v2, s6
	v_mov_b32_e32 v3, s7
	global_load_dwordx2 v[2:3], v[2:3], off offset:192
	s_waitcnt vmcnt(0) lgkmcnt(0)
	v_mov_b32_e32 v0, v2
	s_nop 0
	v_readfirstlane_b32 s6, v0
	v_readfirstlane_b32 s7, v3
	s_add_u32 s10, s6, s8
	s_addc_u32 s11, s7, s9
	v_mov_b32_e32 v0, v247
	s_and_b32 s6, s54, 0x7fc0
	s_addk_i32 s6, 0xbf00
	v_ashrrev_i32_e32 v4, 3, v0
	v_add_u32_e32 v2, s6, v4
	v_lshlrev_b32_e32 v0, 3, v0
	v_ashrrev_i32_e32 v3, 31, v2
	v_and_b32_e32 v5, 56, v0
	v_lshlrev_b64 v[2:3], 12, v[2:3]
	s_and_b32 s8, s52, 0x300
	v_lshl_add_u64 v[2:3], s[10:11], 0, v[2:3]
	v_lshlrev_b32_e32 v0, 2, v5
	v_lshl_add_u64 v[2:3], v[2:3], 0, v[0:1]
	s_lshl_b32 s18, s8, 2
	s_movk_i32 s7, 0x104
	v_lshl_add_u64 v[2:3], v[2:3], 0, s[18:19]
	v_mul_lo_u32 v6, v4, s7
	v_add_u32_e32 v10, 16, v6
	global_load_dwordx4 v[6:9], v[2:3], off
	v_add_u32_e32 v0, v10, v0
	v_add_u32_e32 v11, 0x4100, v0
	s_mov_b32 s7, s19
	s_lshl_b64 s[6:7], s[6:7], 1
	s_add_u32 s6, s34, s6
	s_addc_u32 s7, s35, s7
	s_waitcnt vmcnt(0) lgkmcnt(0)
	ds_write2_b32 v0, v6, v7 offset1:1
	ds_write2_b32 v0, v8, v9 offset0:2 offset1:3
	global_load_dwordx4 v[6:9], v[2:3], off offset:16
	s_waitcnt vmcnt(0) lgkmcnt(0)
	ds_write2_b32 v0, v6, v7 offset0:4 offset1:5
	ds_write2_b32 v0, v8, v9 offset0:6 offset1:7
	global_load_dwordx4 v[6:9], v[2:3], off offset:256
	s_waitcnt vmcnt(0) lgkmcnt(0)
	ds_write2_b32 v11, v6, v7 offset1:1
	v_add_u32_e32 v6, 0x4108, v0
	ds_write2_b32 v6, v8, v9 offset1:1
	global_load_dwordx4 v[6:9], v[2:3], off offset:272
	v_add_u32_e32 v11, 0x4110, v0
	s_waitcnt vmcnt(0) lgkmcnt(0)
	ds_write2_b32 v11, v6, v7 offset1:1
	v_add_u32_e32 v6, 0x4118, v0
	ds_write2_b32 v6, v8, v9 offset1:1
	global_load_dwordx4 v[6:9], v[2:3], off offset:512
	v_add_u32_e32 v11, 0x8200, v0
	s_waitcnt vmcnt(0) lgkmcnt(0)
	ds_write2_b32 v11, v6, v7 offset1:1
	v_add_u32_e32 v6, 0x8208, v0
	ds_write2_b32 v6, v8, v9 offset1:1
	global_load_dwordx4 v[6:9], v[2:3], off offset:528
	v_add_u32_e32 v11, 0x8210, v0
	s_waitcnt vmcnt(0) lgkmcnt(0)
	ds_write2_b32 v11, v6, v7 offset1:1
	v_add_u32_e32 v6, 0x8218, v0
	ds_write2_b32 v6, v8, v9 offset1:1
	global_load_dwordx4 v[6:9], v[2:3], off offset:768
	v_add_u32_e32 v11, 0xc300, v0
	s_waitcnt vmcnt(0) lgkmcnt(0)
	ds_write2_b32 v11, v6, v7 offset1:1
	v_add_u32_e32 v6, 0xc308, v0
	ds_write2_b32 v6, v8, v9 offset1:1
	global_load_dwordx4 v[6:9], v[2:3], off offset:784
	v_add_u32_e32 v11, 0xc310, v0
	v_add_u32_e32 v0, 0xc318, v0
	s_waitcnt vmcnt(0) lgkmcnt(0)
	ds_write2_b32 v0, v8, v9 offset1:1
	v_lshlrev_b32_e32 v0, 8, v4
	ds_write2_b32 v11, v6, v7 offset1:1
	v_sub_u32_e32 v6, v10, v0
	v_lshlrev_b32_e32 v0, 1, v5
	v_mul_u32_u24_e32 v7, 0x104, v5
	v_lshl_add_u64 v[2:3], s[6:7], 0, v[0:1]
	v_add_u32_e32 v5, s8, v4
	s_movk_i32 s6, 0x400
	v_cmp_gt_u32_e32 vcc, s6, v5
	v_add_u32_e32 v6, v6, v7
	s_waitcnt lgkmcnt(0)
	s_barrier
	s_and_saveexec_b64 s[6:7], vcc
	s_cbranch_execz .LBB0_1525
	v_add_u32_e32 v0, 0x400, v6
	ds_read2_b32 v[8:9], v0 offset0:134 offset1:199
	ds_read2_b32 v[12:13], v6 offset1:65
	s_waitcnt lgkmcnt(1)
	v_cvt_pk_bf16_f32 v11, v8, v9
	ds_read2_b32 v[8:9], v0 offset0:4 offset1:69
	v_lshlrev_b32_e32 v0, 11, v5
	s_waitcnt lgkmcnt(0)
	v_cvt_pk_bf16_f32 v10, v8, v9
	ds_read2_b32 v[8:9], v6 offset0:130 offset1:195
	s_waitcnt lgkmcnt(0)
	v_cvt_pk_bf16_f32 v9, v8, v9
	v_cvt_pk_bf16_f32 v8, v12, v13
	v_lshl_add_u64 v[12:13], v[2:3], 0, v[0:1]
	global_store_dwordx4 v[12:13], v[8:11], off
.LBB0_1525:
	s_or_b64 exec, exec, s[6:7]
	v_add3_u32 v0, v4, s8, 64
	s_movk_i32 s6, 0x400
	v_cmp_gt_u32_e32 vcc, s6, v0
	s_and_saveexec_b64 s[6:7], vcc
	s_cbranch_execz .LBB0_1527
	v_add_u32_e32 v4, 0x4600, v6
	ds_read2_b32 v[8:9], v4 offset0:70 offset1:135
	v_add_u32_e32 v4, 0x4400, v6
	v_lshlrev_b32_e32 v0, 11, v0
	s_waitcnt lgkmcnt(0)
	v_cvt_pk_bf16_f32 v11, v8, v9
	ds_read2_b32 v[8:9], v4 offset0:68 offset1:133
	v_add_u32_e32 v4, 0x4200, v6
	s_waitcnt lgkmcnt(0)
	v_cvt_pk_bf16_f32 v10, v8, v9
	ds_read2_b32 v[8:9], v4 offset0:66 offset1:131
	v_add_u32_e32 v4, 0x4000, v6
	ds_read2_b32 v[12:13], v4 offset0:64 offset1:129
	s_waitcnt lgkmcnt(0)
	v_cvt_pk_bf16_f32 v9, v8, v9
	v_cvt_pk_bf16_f32 v8, v12, v13
	v_lshl_add_u64 v[12:13], v[2:3], 0, v[0:1]
	global_store_dwordx4 v[12:13], v[8:11], off
.LBB0_1527:
	s_or_b64 exec, exec, s[6:7]
	v_add_u32_e32 v0, 0x80, v5
	s_movk_i32 s6, 0x400
	v_cmp_gt_u32_e32 vcc, s6, v0
	s_and_saveexec_b64 s[6:7], vcc
	s_cbranch_execz .LBB0_1529
	v_add_u32_e32 v4, 0x8800, v6
	ds_read2_b32 v[8:9], v4 offset0:6 offset1:71
	v_add_u32_e32 v4, 0x8400, v6
	v_lshlrev_b32_e32 v0, 11, v0
	s_waitcnt lgkmcnt(0)
	v_cvt_pk_bf16_f32 v11, v8, v9
	ds_read2_b32 v[8:9], v4 offset0:132 offset1:197
	s_waitcnt lgkmcnt(0)
	v_cvt_pk_bf16_f32 v10, v8, v9
	ds_read2_b32 v[8:9], v4 offset0:2 offset1:67
	v_add_u32_e32 v4, 0x8000, v6
	ds_read2_b32 v[12:13], v4 offset0:128 offset1:193
	s_waitcnt lgkmcnt(0)
	v_cvt_pk_bf16_f32 v9, v8, v9
	v_cvt_pk_bf16_f32 v8, v12, v13
	v_lshl_add_u64 v[12:13], v[2:3], 0, v[0:1]
	global_store_dwordx4 v[12:13], v[8:11], off
.LBB0_1529:
	s_or_b64 exec, exec, s[6:7]
	v_add_u32_e32 v0, 0xc0, v5
	s_movk_i32 s6, 0x400
	v_cmp_gt_u32_e32 vcc, s6, v0
	s_and_saveexec_b64 s[6:7], vcc
	s_cbranch_execz .LBB0_1531
	v_add_u32_e32 v4, 0xc800, v6
	ds_read2_b32 v[4:5], v4 offset0:70 offset1:135
	v_lshlrev_b32_e32 v0, 11, v0
	v_lshl_add_u64 v[2:3], v[2:3], 0, v[0:1]
	s_waitcnt lgkmcnt(0)
	v_cvt_pk_bf16_f32 v9, v4, v5
	v_add_u32_e32 v4, 0xc600, v6
	ds_read2_b32 v[4:5], v4 offset0:68 offset1:133
	s_waitcnt lgkmcnt(0)
	v_cvt_pk_bf16_f32 v8, v4, v5
	v_add_u32_e32 v4, 0xc400, v6
	ds_read2_b32 v[4:5], v4 offset0:66 offset1:131
	s_waitcnt lgkmcnt(0)
	v_cvt_pk_bf16_f32 v7, v4, v5
	v_add_u32_e32 v4, 0xc200, v6
	ds_read2_b32 v[4:5], v4 offset0:64 offset1:129
	s_waitcnt lgkmcnt(0)
	v_cvt_pk_bf16_f32 v6, v4, v5
	global_store_dwordx4 v[2:3], v[6:9], off

.LBB0_1533:
	s_andn2_b64 vcc, exec, s[6:7]
	s_cbranch_vccnz .LBB0_1543
	s_add_i32 s6, s4, 0xfffffc30
	v_mov_b32_e32 v0, s64
	v_mov_b32_e32 v2, s65
	s_lshr_b32 s10, s6, 4
	s_mov_b32 s11, s19
	v_readfirstlane_b32 s6, v0
	v_readfirstlane_b32 s7, v2
	s_nop 0
	v_mov_b32_e32 v2, s6
	v_mov_b32_e32 v3, s7
	global_load_dwordx2 v[2:3], v[2:3], off offset:184
	v_readlane_b32 s6, v254, 51
	s_add_i32 s18, s10, s6
	s_lshl_b64 s[6:7], s[18:19], 20
	s_waitcnt vmcnt(0) lgkmcnt(0)
	v_mov_b32_e32 v0, v3
	s_nop 0
	v_readfirstlane_b32 s8, v2
	v_readfirstlane_b32 s9, v0
	s_add_u32 s6, s8, s6
	s_addc_u32 s7, s9, s7
	s_and_b32 s8, s52, 0x300
	s_lshl_b64 s[10:11], s[10:11], 9
	s_add_u32 s9, s46, s10
	v_mov_b32_e32 v0, v247
	s_addc_u32 s10, s47, s11
	s_and_b32 s11, s54, 0xc0
	v_ashrrev_i32_e32 v4, 3, v0
	v_add_u32_e32 v2, s11, v4
	v_lshlrev_b32_e32 v0, 3, v0
	v_ashrrev_i32_e32 v3, 31, v2
	v_and_b32_e32 v5, 56, v0
	v_lshlrev_b64 v[2:3], 12, v[2:3]
	v_lshl_add_u64 v[2:3], s[6:7], 0, v[2:3]
	v_lshlrev_b32_e32 v0, 2, v5
	v_lshl_add_u64 v[2:3], v[2:3], 0, v[0:1]
	s_lshl_b32 s18, s8, 2
	s_movk_i32 s6, 0x104
	v_lshl_add_u64 v[2:3], v[2:3], 0, s[18:19]
	v_mul_lo_u32 v6, v4, s6
	v_add_u32_e32 v10, 16, v6
	global_load_dwordx4 v[6:9], v[2:3], off
	v_add_u32_e32 v0, v10, v0
	v_add_u32_e32 v11, 0x4100, v0
	s_lshl_b32 s6, s11, 1
	s_add_u32 s6, s9, s6
	s_addc_u32 s7, s10, 0
	s_waitcnt vmcnt(0) lgkmcnt(0)
	ds_write2_b32 v0, v6, v7 offset1:1
	ds_write2_b32 v0, v8, v9 offset0:2 offset1:3
	global_load_dwordx4 v[6:9], v[2:3], off offset:16
	s_waitcnt vmcnt(0) lgkmcnt(0)
	ds_write2_b32 v0, v6, v7 offset0:4 offset1:5
	ds_write2_b32 v0, v8, v9 offset0:6 offset1:7
	global_load_dwordx4 v[6:9], v[2:3], off offset:256
	s_waitcnt vmcnt(0) lgkmcnt(0)
	ds_write2_b32 v11, v6, v7 offset1:1
	v_add_u32_e32 v6, 0x4108, v0
	ds_write2_b32 v6, v8, v9 offset1:1
	global_load_dwordx4 v[6:9], v[2:3], off offset:272
	v_add_u32_e32 v11, 0x4110, v0
	s_waitcnt vmcnt(0) lgkmcnt(0)
	ds_write2_b32 v11, v6, v7 offset1:1
	v_add_u32_e32 v6, 0x4118, v0
	ds_write2_b32 v6, v8, v9 offset1:1
	global_load_dwordx4 v[6:9], v[2:3], off offset:512
	v_add_u32_e32 v11, 0x8200, v0
	s_waitcnt vmcnt(0) lgkmcnt(0)
	ds_write2_b32 v11, v6, v7 offset1:1
	v_add_u32_e32 v6, 0x8208, v0
	ds_write2_b32 v6, v8, v9 offset1:1
	global_load_dwordx4 v[6:9], v[2:3], off offset:528
	v_add_u32_e32 v11, 0x8210, v0
	s_waitcnt vmcnt(0) lgkmcnt(0)
	ds_write2_b32 v11, v6, v7 offset1:1
	v_add_u32_e32 v6, 0x8218, v0
	ds_write2_b32 v6, v8, v9 offset1:1
	global_load_dwordx4 v[6:9], v[2:3], off offset:768
	v_add_u32_e32 v11, 0xc300, v0
	s_waitcnt vmcnt(0) lgkmcnt(0)
	ds_write2_b32 v11, v6, v7 offset1:1
	v_add_u32_e32 v6, 0xc308, v0
	ds_write2_b32 v6, v8, v9 offset1:1
	global_load_dwordx4 v[6:9], v[2:3], off offset:784
	v_add_u32_e32 v11, 0xc310, v0
	v_add_u32_e32 v0, 0xc318, v0
	s_waitcnt vmcnt(0) lgkmcnt(0)
	ds_write2_b32 v0, v8, v9 offset1:1
	v_lshlrev_b32_e32 v0, 8, v4
	ds_write2_b32 v11, v6, v7 offset1:1
	v_sub_u32_e32 v6, v10, v0
	v_lshlrev_b32_e32 v0, 1, v5
	v_mul_u32_u24_e32 v7, 0x104, v5
	v_lshl_add_u64 v[2:3], s[6:7], 0, v[0:1]
	v_add_u32_e32 v5, s8, v4
	s_movk_i32 s6, 0x400
	v_cmp_gt_u32_e32 vcc, s6, v5
	v_add_u32_e32 v6, v6, v7
	s_waitcnt lgkmcnt(0)
	s_barrier
	s_and_saveexec_b64 s[6:7], vcc
	s_cbranch_execz .LBB0_1536
	v_add_u32_e32 v0, 0x400, v6
	ds_read2_b32 v[8:9], v0 offset0:134 offset1:199
	ds_read2_b32 v[12:13], v6 offset1:65
	s_waitcnt lgkmcnt(1)
	v_cvt_pk_bf16_f32 v11, v8, v9
	ds_read2_b32 v[8:9], v0 offset0:4 offset1:69
	v_lshlrev_b32_e32 v0, 11, v5
	s_waitcnt lgkmcnt(0)
	v_cvt_pk_bf16_f32 v10, v8, v9
	ds_read2_b32 v[8:9], v6 offset0:130 offset1:195
	s_waitcnt lgkmcnt(0)
	v_cvt_pk_bf16_f32 v9, v8, v9
	v_cvt_pk_bf16_f32 v8, v12, v13
	v_lshl_add_u64 v[12:13], v[2:3], 0, v[0:1]
	global_store_dwordx4 v[12:13], v[8:11], off

.LBB0_1544:
	s_andn2_b64 vcc, exec, s[6:7]
	s_cbranch_vccnz .LBB0_1758
	v_mov_b32_e32 v0, s64
	v_mov_b32_e32 v2, s65
	v_readlane_b32 s8, v254, 62
	v_readfirstlane_b32 s6, v0
	v_readfirstlane_b32 s7, v2
	v_mov_b32_e32 v6, 0
	v_mov_b32_e32 v2, s6
	v_mov_b32_e32 v3, s7
	global_load_dwordx2 v[2:3], v[2:3], off offset:88
	v_mov_b32_e32 v7, 0
	v_mov_b32_e32 v8, 0
	v_mov_b32_e32 v9, 0
	v_mov_b32_e32 v10, 0
	v_mov_b32_e32 v11, 0
	v_mov_b32_e32 v12, 0
	v_mov_b32_e32 v13, 0
	s_waitcnt vmcnt(0) lgkmcnt(0)
	v_mov_b32_e32 v0, v3
	s_nop 0
	v_readfirstlane_b32 s6, v2
	v_readfirstlane_b32 s7, v0
	s_add_u32 s6, s6, s8
	v_readlane_b32 s8, v254, 53
	s_addc_u32 s7, s7, s8
	s_add_i32 s8, s4, 0xfdf0
	s_bfe_u32 s9, s8, 0xe0002
	s_mulk_i32 s9, 0x4925
	s_lshr_b32 s9, s9, 17
	s_mul_i32 s10, s9, 28
	v_mov_b32_e32 v0, v247
	s_sub_i32 s8, s8, s10
	s_lshl_b32 s10, s8, 2
	v_ashrrev_i32_e32 v36, 3, v0
	v_lshlrev_b32_e32 v0, 3, v0
	s_lshl_b32 s11, s9, 6
	s_and_b32 s12, s10, 0xfffc
	v_and_b32_e32 v37, 56, v0
	v_add_u32_e32 v0, s11, v36
	v_mov_b64_e32 v[2:3], s[6:7]
	s_movk_i32 s6, 0x6c20
	v_add_u32_e32 v19, 8, v37
	v_mad_i64_i32 v[2:3], s[6:7], v0, s6, v[2:3]
	v_lshlrev_b32_e32 v0, 2, v37
	s_lshl_b32 s10, s12, 6
	v_lshl_add_u64 v[34:35], v[2:3], 0, v[0:1]
	v_or_b32_e32 v0, s10, v19
	s_movk_i32 s6, 0x1b09
	v_cmp_gt_u32_e32 vcc, s6, v0
	v_mov_b32_e32 v2, 0
	s_and_saveexec_b64 s[6:7], vcc
	s_cbranch_execz .LBB0_1547
	s_lshl_b32 s18, s10, 2
	v_lshl_add_u64 v[4:5], v[34:35], 0, s[18:19]
	global_load_dwordx4 v[6:9], v[4:5], off
	global_load_dwordx4 v[10:13], v[4:5], off offset:16
.LBB0_1547:
	s_or_b64 exec, exec, s[6:7]
	s_or_b32 s60, s12, 1
	s_lshl_b32 s61, s60, 6
	s_and_b32 s8, 0xffff, s8
	s_cmp_gt_u32 s8, 26
	s_cselect_b64 s[6:7], -1, 0
	s_cmp_lt_u32 s8, 27
	v_add_u32_e32 v0, s61, v19
	s_movk_i32 s13, 0x1b09
	s_cselect_b64 s[8:9], -1, 0
	v_cmp_gt_u32_e32 vcc, s13, v0
	s_and_b64 s[14:15], s[8:9], vcc
	v_mov_b32_e32 v3, 0
	v_mov_b32_e32 v4, 0
	v_mov_b32_e32 v5, 0
	v_mov_b32_e32 v14, 0
	v_mov_b32_e32 v15, 0
	v_mov_b32_e32 v16, 0
	v_mov_b32_e32 v17, 0
	s_and_saveexec_b64 s[8:9], s[14:15]
	s_cbranch_execz .LBB0_1549
	s_lshl_b32 s18, s61, 2
	v_lshl_add_u64 v[14:15], v[34:35], 0, s[18:19]
	global_load_dwordx4 v[2:5], v[14:15], off
	s_nop 0
	global_load_dwordx4 v[14:17], v[14:15], off offset:16
.LBB0_1549:
	s_or_b64 exec, exec, s[8:9]
	s_or_b32 s58, s12, 2
	s_lshl_b32 s59, s58, 6
	v_or_b32_e32 v0, s59, v19
	s_movk_i32 s8, 0x1b09
	v_cmp_gt_u32_e32 vcc, s8, v0
	s_xor_b64 s[6:7], s[6:7], -1
	s_and_b64 s[8:9], s[6:7], vcc
	v_mov_b32_e32 v18, 0
	v_mov_b32_e32 v22, 0
	v_mov_b32_e32 v23, 0
	v_mov_b32_e32 v24, 0
	v_mov_b32_e32 v25, 0
	v_mov_b32_e32 v26, 0
	v_mov_b32_e32 v27, 0
	v_mov_b32_e32 v28, 0
	v_mov_b32_e32 v29, 0
	s_and_saveexec_b64 s[6:7], s[8:9]
	s_cbranch_execz .LBB0_1551
	s_lshl_b32 s18, s59, 2
	v_lshl_add_u64 v[20:21], v[34:35], 0, s[18:19]
	global_load_dwordx4 v[22:25], v[20:21], off
	global_load_dwordx4 v[26:29], v[20:21], off offset:16
.LBB0_1551:
	s_or_b64 exec, exec, s[6:7]
	s_or_b32 s56, s12, 3
	s_lshl_b32 s57, s56, 6
	s_cmpk_lt_u32 s56, 0x6d
	v_add_u32_e32 v0, s57, v19
	s_movk_i32 s8, 0x1b09
	s_cselect_b64 s[6:7], -1, 0
	v_cmp_gt_u32_e32 vcc, s8, v0
	s_and_b64 s[8:9], s[6:7], vcc
	v_mov_b32_e32 v19, 0
	v_mov_b32_e32 v20, 0
	v_mov_b32_e32 v21, 0
	v_mov_b32_e32 v30, 0
	v_mov_b32_e32 v31, 0
	v_mov_b32_e32 v32, 0
	v_mov_b32_e32 v33, 0
	s_and_saveexec_b64 s[6:7], s[8:9]
	s_cbranch_execz .LBB0_1553
	s_lshl_b32 s18, s57, 2
	v_lshl_add_u64 v[30:31], v[34:35], 0, s[18:19]
	global_load_dwordx4 v[18:21], v[30:31], off
	s_nop 0
	global_load_dwordx4 v[30:33], v[30:31], off offset:16

.LBB0_1759:
	s_andn2_b64 vcc, exec, s[6:7]
	s_cbranch_vccnz .LBB0_1769
	v_mov_b32_e32 v0, s64
	v_mov_b32_e32 v2, s65
	v_readlane_b32 s8, v254, 59
	v_readfirstlane_b32 s6, v0
	v_readfirstlane_b32 s7, v2
	s_nop 0
	v_mov_b32_e32 v2, s6
	v_mov_b32_e32 v3, s7
	global_load_dwordx2 v[2:3], v[2:3], off offset:72
	s_waitcnt vmcnt(0) lgkmcnt(0)
	v_mov_b32_e32 v0, v3
	s_nop 0
	v_readfirstlane_b32 s6, v2
	v_readfirstlane_b32 s7, v0
	s_add_u32 s10, s6, s8
	v_readlane_b32 s6, v255, 2
	s_addc_u32 s11, s7, s6
	v_mov_b32_e32 v0, v247
	s_and_b32 s6, s54, 0x3fc0
	s_addk_i32 s6, 0xea00
	v_ashrrev_i32_e32 v4, 3, v0
	v_add_u32_e32 v2, s6, v4
	v_lshlrev_b32_e32 v0, 3, v0
	v_ashrrev_i32_e32 v3, 31, v2
	v_and_b32_e32 v5, 56, v0
	v_lshlrev_b64 v[2:3], 12, v[2:3]
	s_and_b32 s8, s52, 0x300
	v_lshl_add_u64 v[2:3], s[10:11], 0, v[2:3]
	v_lshlrev_b32_e32 v0, 2, v5
	v_lshl_add_u64 v[2:3], v[2:3], 0, v[0:1]
	s_lshl_b32 s18, s8, 2
	s_movk_i32 s7, 0x104
	v_lshl_add_u64 v[2:3], v[2:3], 0, s[18:19]
	v_mul_lo_u32 v6, v4, s7
	v_add_u32_e32 v10, 16, v6
	global_load_dwordx4 v[6:9], v[2:3], off
	v_add_u32_e32 v0, v10, v0
	v_add_u32_e32 v11, 0x4100, v0
	s_mov_b32 s7, s19
	s_lshl_b64 s[6:7], s[6:7], 1
	s_add_u32 s6, s50, s6
	s_addc_u32 s7, s51, s7
	s_waitcnt vmcnt(0) lgkmcnt(0)
	ds_write2_b32 v0, v6, v7 offset1:1
	ds_write2_b32 v0, v8, v9 offset0:2 offset1:3
	global_load_dwordx4 v[6:9], v[2:3], off offset:16
	s_waitcnt vmcnt(0) lgkmcnt(0)
	ds_write2_b32 v0, v6, v7 offset0:4 offset1:5
	ds_write2_b32 v0, v8, v9 offset0:6 offset1:7
	global_load_dwordx4 v[6:9], v[2:3], off offset:256
	s_waitcnt vmcnt(0) lgkmcnt(0)
	ds_write2_b32 v11, v6, v7 offset1:1
	v_add_u32_e32 v6, 0x4108, v0
	ds_write2_b32 v6, v8, v9 offset1:1
	global_load_dwordx4 v[6:9], v[2:3], off offset:272
	v_add_u32_e32 v11, 0x4110, v0
	s_waitcnt vmcnt(0) lgkmcnt(0)
	ds_write2_b32 v11, v6, v7 offset1:1
	v_add_u32_e32 v6, 0x4118, v0
	ds_write2_b32 v6, v8, v9 offset1:1
	global_load_dwordx4 v[6:9], v[2:3], off offset:512
	v_add_u32_e32 v11, 0x8200, v0
	s_waitcnt vmcnt(0) lgkmcnt(0)
	ds_write2_b32 v11, v6, v7 offset1:1
	v_add_u32_e32 v6, 0x8208, v0
	ds_write2_b32 v6, v8, v9 offset1:1
	global_load_dwordx4 v[6:9], v[2:3], off offset:528
	v_add_u32_e32 v11, 0x8210, v0
	s_waitcnt vmcnt(0) lgkmcnt(0)
	ds_write2_b32 v11, v6, v7 offset1:1
	v_add_u32_e32 v6, 0x8218, v0
	ds_write2_b32 v6, v8, v9 offset1:1
	global_load_dwordx4 v[6:9], v[2:3], off offset:768
	v_add_u32_e32 v11, 0xc300, v0
	s_waitcnt vmcnt(0) lgkmcnt(0)
	ds_write2_b32 v11, v6, v7 offset1:1
	v_add_u32_e32 v6, 0xc308, v0
	ds_write2_b32 v6, v8, v9 offset1:1
	global_load_dwordx4 v[6:9], v[2:3], off offset:784
	v_add_u32_e32 v11, 0xc310, v0
	v_add_u32_e32 v0, 0xc318, v0
	s_waitcnt vmcnt(0) lgkmcnt(0)
	ds_write2_b32 v0, v8, v9 offset1:1
	v_lshlrev_b32_e32 v0, 8, v4
	ds_write2_b32 v11, v6, v7 offset1:1
	v_sub_u32_e32 v6, v10, v0
	v_lshlrev_b32_e32 v0, 1, v5
	v_mul_u32_u24_e32 v7, 0x104, v5
	v_lshl_add_u64 v[2:3], s[6:7], 0, v[0:1]
	v_add_u32_e32 v5, s8, v4
	s_movk_i32 s6, 0x400
	v_cmp_gt_u32_e32 vcc, s6, v5
	v_add_u32_e32 v6, v6, v7
	s_waitcnt lgkmcnt(0)
	s_barrier
	s_and_saveexec_b64 s[6:7], vcc
	s_cbranch_execz .LBB0_1762
	v_add_u32_e32 v0, 0x400, v6
	ds_read2_b32 v[8:9], v0 offset0:134 offset1:199
	ds_read2_b32 v[12:13], v6 offset1:65
	s_movk_i32 s9, 0x1600
	s_waitcnt lgkmcnt(1)
	v_cvt_pk_bf16_f32 v11, v8, v9
	ds_read2_b32 v[8:9], v0 offset0:4 offset1:69
	v_mul_lo_u32 v0, v5, s9
	s_waitcnt lgkmcnt(0)
	v_cvt_pk_bf16_f32 v10, v8, v9
	ds_read2_b32 v[8:9], v6 offset0:130 offset1:195
	s_waitcnt lgkmcnt(0)
	v_cvt_pk_bf16_f32 v9, v8, v9
	v_cvt_pk_bf16_f32 v8, v12, v13
	v_lshl_add_u64 v[12:13], v[2:3], 0, v[0:1]
	global_store_dwordx4 v[12:13], v[8:11], off

.LBB0_1770:
	s_andn2_b64 vcc, exec, s[6:7]
	s_cbranch_vccnz .LBB0_1780
	v_mov_b32_e32 v0, s64
	v_mov_b32_e32 v2, s65
	v_readlane_b32 s8, v254, 59
	v_readfirstlane_b32 s6, v0
	v_readfirstlane_b32 s7, v2
	v_mov_b32_e32 v10, v247
	v_mov_b32_e32 v2, s6
	v_mov_b32_e32 v3, s7
	global_load_dwordx2 v[2:3], v[2:3], off offset:64
	s_waitcnt vmcnt(0) lgkmcnt(0)
	v_mov_b32_e32 v0, v3
	s_nop 0
	v_readfirstlane_b32 s6, v2
	v_readfirstlane_b32 s7, v0
	s_add_u32 s6, s6, s8
	v_readlane_b32 s8, v255, 2
	s_addc_u32 s7, s7, s8
	s_add_i32 s8, s4, 0x50
	s_and_b32 s9, s8, 0xff
	s_mulk_i32 s9, 0x75
	s_lshr_b32 s10, s9, 8
	s_sub_i32 s10, s8, s10
	s_bfe_u32 s10, s10, 0x70001
	s_bfe_u32 s9, s9, 0x80008
	s_add_i32 s10, s10, s9
	s_bfe_u32 s9, s10, 0x50003
	s_mul_i32 s10, s9, 11
	s_sub_i32 s8, s8, s10
	v_ashrrev_i32_e32 v4, 3, v10
	v_lshlrev_b32_e32 v0, 3, v10
	s_lshl_b32 s8, s8, 2
	v_and_b32_e32 v5, 56, v0
	v_lshl_add_u32 v0, s9, 6, v4
	v_mov_b64_e32 v[2:3], s[6:7]
	s_movk_i32 s6, 0x2c00
	s_and_b32 s10, s8, 0xfc
	v_mad_i64_i32 v[2:3], s[6:7], v0, s6, v[2:3]
	v_lshlrev_b32_e32 v0, 2, v5
	v_lshl_add_u64 v[2:3], v[2:3], 0, v[0:1]
	s_lshl_b32 s18, s10, 8
	s_movk_i32 s6, 0x104
	v_lshl_add_u64 v[2:3], v[2:3], 0, s[18:19]
	v_mul_lo_u32 v6, v4, s6
	v_add_u32_e32 v11, 16, v6
	global_load_dwordx4 v[6:9], v[2:3], off
	v_add_u32_e32 v0, v11, v0
	v_add_u32_e32 v12, 0x4100, v0
	s_lshl_b32 s8, s10, 6
	s_lshl_b32 s6, s9, 7
	s_add_u32 s6, s0, s6
	s_addc_u32 s7, s1, 0
	s_waitcnt vmcnt(0) lgkmcnt(0)
	ds_write2_b32 v0, v6, v7 offset1:1
	ds_write2_b32 v0, v8, v9 offset0:2 offset1:3
	global_load_dwordx4 v[6:9], v[2:3], off offset:16
	s_waitcnt vmcnt(0) lgkmcnt(0)
	ds_write2_b32 v0, v6, v7 offset0:4 offset1:5
	ds_write2_b32 v0, v8, v9 offset0:6 offset1:7
	global_load_dwordx4 v[6:9], v[2:3], off offset:256
	s_waitcnt vmcnt(0) lgkmcnt(0)
	ds_write2_b32 v12, v6, v7 offset1:1
	v_add_u32_e32 v6, 0x4108, v0
	ds_write2_b32 v6, v8, v9 offset1:1
	global_load_dwordx4 v[6:9], v[2:3], off offset:272
	v_add_u32_e32 v12, 0x4110, v0
	s_waitcnt vmcnt(0) lgkmcnt(0)
	ds_write2_b32 v12, v6, v7 offset1:1
	v_add_u32_e32 v6, 0x4118, v0
	ds_write2_b32 v6, v8, v9 offset1:1
	global_load_dwordx4 v[6:9], v[2:3], off offset:512
	v_add_u32_e32 v12, 0x8200, v0
	s_waitcnt vmcnt(0) lgkmcnt(0)
	ds_write2_b32 v12, v6, v7 offset1:1
	v_add_u32_e32 v6, 0x8208, v0
	ds_write2_b32 v6, v8, v9 offset1:1
	global_load_dwordx4 v[6:9], v[2:3], off offset:528
	v_add_u32_e32 v12, 0x8210, v0
	s_waitcnt vmcnt(0) lgkmcnt(0)
	ds_write2_b32 v12, v6, v7 offset1:1
	v_add_u32_e32 v6, 0x8218, v0
	ds_write2_b32 v6, v8, v9 offset1:1
	global_load_dwordx4 v[6:9], v[2:3], off offset:768
	v_add_u32_e32 v12, 0xc300, v0
	s_waitcnt vmcnt(0) lgkmcnt(0)
	ds_write2_b32 v12, v6, v7 offset1:1
	v_add_u32_e32 v6, 0xc308, v0
	ds_write2_b32 v6, v8, v9 offset1:1
	global_load_dwordx4 v[6:9], v[2:3], off offset:784
	v_add_u32_e32 v12, 0xc310, v0
	v_add_u32_e32 v0, 0xc318, v0
	s_waitcnt vmcnt(0) lgkmcnt(0)
	ds_write2_b32 v0, v8, v9 offset1:1
	v_lshlrev_b32_e32 v0, 8, v4
	ds_write2_b32 v12, v6, v7 offset1:1
	v_sub_u32_e32 v7, v11, v0
	v_lshlrev_b32_e32 v0, 1, v5
	v_mul_u32_u24_e32 v8, 0x104, v5
	v_lshl_add_u64 v[2:3], s[6:7], 0, v[0:1]
	v_add_u32_e32 v5, s8, v4
	s_movk_i32 s6, 0xb00
	v_cmp_gt_u32_e32 vcc, s6, v5
	v_bfe_u32 v6, v10, 3, 7
	v_add_u32_e32 v7, v7, v8
	s_waitcnt lgkmcnt(0)
	s_barrier
	s_and_saveexec_b64 s[6:7], vcc
	s_cbranch_execz .LBB0_1773
	v_add_u32_e32 v10, 0x400, v7
	ds_read2_b32 v[8:9], v10 offset0:134 offset1:199
	ds_read2_b32 v[12:13], v7 offset1:65
	v_lshlrev_b32_e32 v0, 1, v5
	s_movk_i32 s9, 0x1f00
	v_and_or_b32 v0, v0, s9, v6
	s_waitcnt lgkmcnt(1)
	v_cvt_pk_bf16_f32 v11, v8, v9
	ds_read2_b32 v[8:9], v10 offset0:4 offset1:69
	v_lshlrev_b32_e32 v0, 11, v0
	s_waitcnt lgkmcnt(0)
	v_cvt_pk_bf16_f32 v10, v8, v9
	ds_read2_b32 v[8:9], v7 offset0:130 offset1:195
	s_waitcnt lgkmcnt(0)
	v_cvt_pk_bf16_f32 v9, v8, v9
	v_cvt_pk_bf16_f32 v8, v12, v13
	v_lshl_add_u64 v[12:13], v[2:3], 0, v[0:1]
	v_add_co_u32_e32 v12, vcc, 0x40000, v12
	s_nop 1
	v_addc_co_u32_e32 v13, vcc, 0, v13, vcc
	global_store_dwordx4 v[12:13], v[8:11], off

.LBB0_1781:
	s_andn2_b64 vcc, exec, s[6:7]
	s_cbranch_vccnz .LBB0_1483
	v_mov_b32_e32 v0, s64
	v_mov_b32_e32 v2, s65
	v_readlane_b32 s8, v254, 59
	v_readfirstlane_b32 s6, v0
	v_readfirstlane_b32 s7, v2
	v_mov_b32_e32 v8, v247
	v_mov_b32_e32 v2, s6
	v_mov_b32_e32 v3, s7
	global_load_dwordx2 v[2:3], v[2:3], off offset:56
	s_waitcnt vmcnt(0) lgkmcnt(0)
	v_mov_b32_e32 v0, v3
	s_nop 0
	v_readfirstlane_b32 s6, v2
	v_readfirstlane_b32 s7, v0
	s_add_u32 s12, s6, s8
	v_readlane_b32 s6, v255, 2
	s_addc_u32 s13, s7, s6
	s_mul_hi_i32 s6, s4, 0x2e8ba2e9
	s_lshr_b32 s7, s6, 31
	s_ashr_i32 s10, s6, 1
	s_add_i32 s10, s10, s7
	s_mul_i32 s6, s10, 0xfffff500
	s_add_i32 s8, s52, s6
	v_ashrrev_i32_e32 v9, 3, v8
	v_lshlrev_b32_e32 v0, 3, v8
	s_lshl_b32 s6, s10, 6
	v_and_b32_e32 v10, 56, v0
	v_add_u32_e32 v0, s6, v9
	v_mov_b64_e32 v[2:3], s[12:13]
	s_movk_i32 s7, 0x2c00
	v_mad_i64_i32 v[2:3], s[12:13], v0, s7, v[2:3]
	v_lshlrev_b32_e32 v0, 2, v10
	v_lshl_add_u64 v[2:3], v[2:3], 0, v[0:1]
	s_ashr_i32 s9, s8, 31
	s_movk_i32 s7, 0x104
	v_lshl_add_u64 v[6:7], s[8:9], 2, v[2:3]
	v_mul_lo_u32 v2, v9, s7
	v_add_u32_e32 v11, 16, v2
	global_load_dwordx4 v[2:5], v[6:7], off
	v_add_u32_e32 v0, v11, v0
	v_add_u32_e32 v12, 0x4100, v0
	s_ashr_i32 s7, s6, 31
	s_lshl_b64 s[6:7], s[6:7], 1
	s_add_u32 s6, s0, s6
	s_addc_u32 s7, s1, s7
	s_mulk_i32 s10, 0xb00
	s_waitcnt vmcnt(0) lgkmcnt(0)
	ds_write2_b32 v0, v2, v3 offset1:1
	ds_write2_b32 v0, v4, v5 offset0:2 offset1:3
	global_load_dwordx4 v[2:5], v[6:7], off offset:16
	s_waitcnt vmcnt(0) lgkmcnt(0)
	ds_write2_b32 v0, v2, v3 offset0:4 offset1:5
	ds_write2_b32 v0, v4, v5 offset0:6 offset1:7
	global_load_dwordx4 v[2:5], v[6:7], off offset:256
	s_waitcnt vmcnt(0) lgkmcnt(0)
	ds_write2_b32 v12, v2, v3 offset1:1
	v_add_u32_e32 v2, 0x4108, v0
	ds_write2_b32 v2, v4, v5 offset1:1
	global_load_dwordx4 v[2:5], v[6:7], off offset:272
	v_add_u32_e32 v12, 0x4110, v0
	s_waitcnt vmcnt(0) lgkmcnt(0)
	ds_write2_b32 v12, v2, v3 offset1:1
	v_add_u32_e32 v2, 0x4118, v0
	ds_write2_b32 v2, v4, v5 offset1:1
	global_load_dwordx4 v[2:5], v[6:7], off offset:512
	v_add_u32_e32 v12, 0x8200, v0
	s_waitcnt vmcnt(0) lgkmcnt(0)
	ds_write2_b32 v12, v2, v3 offset1:1
	v_add_u32_e32 v2, 0x8208, v0
	ds_write2_b32 v2, v4, v5 offset1:1
	global_load_dwordx4 v[2:5], v[6:7], off offset:528
	v_add_u32_e32 v12, 0x8210, v0
	s_waitcnt vmcnt(0) lgkmcnt(0)
	ds_write2_b32 v12, v2, v3 offset1:1
	v_add_u32_e32 v2, 0x8218, v0
	ds_write2_b32 v2, v4, v5 offset1:1
	global_load_dwordx4 v[2:5], v[6:7], off offset:768
	v_add_u32_e32 v12, 0xc300, v0
	s_waitcnt vmcnt(0) lgkmcnt(0)
	ds_write2_b32 v12, v2, v3 offset1:1
	v_add_u32_e32 v2, 0xc308, v0
	ds_write2_b32 v2, v4, v5 offset1:1
	global_load_dwordx4 v[2:5], v[6:7], off offset:784
	v_add_u32_e32 v12, 0xc310, v0
	v_add_u32_e32 v0, 0xc318, v0
	v_mul_u32_u24_e32 v7, 0x104, v10
	s_waitcnt vmcnt(0) lgkmcnt(0)
	ds_write2_b32 v0, v4, v5 offset1:1
	v_lshlrev_b32_e32 v0, 8, v9
	v_sub_u32_e32 v6, v11, v0
	v_lshlrev_b32_e32 v0, 1, v10
	ds_write2_b32 v12, v2, v3 offset1:1
	v_lshl_add_u64 v[2:3], s[6:7], 0, v[0:1]
	v_subrev_u32_e32 v0, s10, v9
	v_add_u32_e32 v4, s52, v0
	s_movk_i32 s10, 0xb00
	v_cmp_gt_u32_e32 vcc, s10, v4
	v_bfe_u32 v5, v8, 3, 7
	v_add_u32_e32 v6, v6, v7
	s_waitcnt lgkmcnt(0)
	s_barrier
	s_and_saveexec_b64 s[6:7], vcc
	s_cbranch_execz .LBB0_1784
	v_add_u32_e32 v7, 0x400, v6
	ds_read2_b32 v[8:9], v7 offset0:134 offset1:199
	ds_read2_b32 v[12:13], v6 offset1:65
	v_lshlrev_b32_e32 v0, 1, v4
	s_movk_i32 s8, 0x1f00
	v_and_or_b32 v0, v0, s8, v5
	s_waitcnt lgkmcnt(1)
	v_cvt_pk_bf16_f32 v11, v8, v9
	ds_read2_b32 v[8:9], v7 offset0:4 offset1:69
	v_lshlrev_b32_e32 v0, 11, v0
	s_waitcnt lgkmcnt(0)
	v_cvt_pk_bf16_f32 v10, v8, v9
	ds_read2_b32 v[8:9], v6 offset0:130 offset1:195
	s_waitcnt lgkmcnt(0)
	v_cvt_pk_bf16_f32 v9, v8, v9
	v_cvt_pk_bf16_f32 v8, v12, v13
	v_lshl_add_u64 v[12:13], v[2:3], 0, v[0:1]
	global_store_dwordx4 v[12:13], v[8:11], off

.LBB0_1792:
	s_and_b64 vcc, exec, s[6:7]
	s_cbranch_vccz .LBB0_2359
	s_and_b64 vcc, exec, s[38:39]
	s_cbranch_vccnz .LBB0_2046
	v_mov_b32_e32 v0, s64
	v_mov_b32_e32 v2, s65
	s_nop 0
	v_readfirstlane_b32 s0, v0
	v_readfirstlane_b32 s1, v2
	v_mov_b32_e32 v0, s88
	v_mov_b32_e32 v2, s0
	v_mov_b32_e32 v3, s1
	global_load_dwordx2 v[2:3], v[2:3], off offset:248
	s_waitcnt vmcnt(0) lgkmcnt(0)
	s_nop 0
	v_readfirstlane_b32 s4, v0
	v_readfirstlane_b32 s0, v2
	s_cmp_lt_i32 s4, 48
	v_readfirstlane_b32 s1, v3
	s_cbranch_scc1 .LBB0_2046
	s_sub_i32 s4, s4, 48
	s_cmpk_gt_u32 s4, 0x3cf
	s_cbranch_scc1 .LBB0_2046
	s_add_u32 s5, s0, 0x1080000
	s_addc_u32 s20, s1, 0
	s_add_u32 s21, s0, 0xb00000
	v_readlane_b32 s6, v254, 21
	s_addc_u32 s33, s1, 0
	s_lshl_b32 s34, s4, 8
	s_lshl_b32 s35, s6, 8
	s_lshl_b32 s44, s4, 4
	s_lshl_b32 s45, s6, 4
	s_branch .LBB0_1799

.LBB0_1799:
	s_cmpk_gt_i32 s4, 0xaf
	s_mov_b64 s[6:7], -1
	s_cbranch_scc0 .LBB0_2036
	s_cmpk_gt_u32 s4, 0x15f
	s_cbranch_scc0 .LBB0_2025
	s_cmpk_gt_u32 s4, 0x20f
	s_cbranch_scc0 .LBB0_2015
	v_mov_b32_e32 v0, s64
	v_mov_b32_e32 v2, s65
	v_readlane_b32 s8, v254, 63
	v_readfirstlane_b32 s6, v0
	v_readfirstlane_b32 s7, v2
	v_mov_b32_e32 v6, 0
	v_mov_b32_e32 v2, s6
	v_mov_b32_e32 v3, s7
	global_load_dwordx2 v[2:3], v[2:3], off offset:88
	v_mov_b32_e32 v7, 0
	v_mov_b32_e32 v8, 0
	v_mov_b32_e32 v9, 0
	v_mov_b32_e32 v10, 0
	v_mov_b32_e32 v11, 0
	v_mov_b32_e32 v12, 0
	v_mov_b32_e32 v13, 0
	s_waitcnt vmcnt(0) lgkmcnt(0)
	v_mov_b32_e32 v0, v2
	s_nop 0
	v_readfirstlane_b32 s6, v0
	v_readfirstlane_b32 s7, v3
	s_add_u32 s6, s6, s8
	v_readlane_b32 s8, v254, 61
	s_addc_u32 s7, s7, s8
	s_add_i32 s8, s4, 0xfdf0
	s_bfe_u32 s9, s8, 0xe0002
	s_mulk_i32 s9, 0x4925
	s_lshr_b32 s9, s9, 17
	s_mul_i32 s10, s9, 28
	v_mov_b32_e32 v0, v247
	s_sub_i32 s8, s8, s10
	s_lshl_b32 s10, s8, 2
	v_ashrrev_i32_e32 v36, 3, v0
	v_lshlrev_b32_e32 v0, 3, v0
	s_lshl_b32 s11, s9, 6
	s_and_b32 s12, s10, 0xfffc
	v_and_b32_e32 v37, 56, v0
	v_add_u32_e32 v0, s11, v36
	v_mov_b64_e32 v[2:3], s[6:7]
	s_movk_i32 s6, 0x6c20
	v_add_u32_e32 v19, 8, v37
	v_mad_i64_i32 v[2:3], s[6:7], v0, s6, v[2:3]
	v_lshlrev_b32_e32 v0, 2, v37
	s_lshl_b32 s10, s12, 6
	v_lshl_add_u64 v[34:35], v[2:3], 0, v[0:1]
	v_or_b32_e32 v0, s10, v19
	s_movk_i32 s6, 0x1b09
	v_cmp_gt_u32_e32 vcc, s6, v0
	v_mov_b32_e32 v2, 0
	s_and_saveexec_b64 s[6:7], vcc
	s_cbranch_execz .LBB0_1804
	s_lshl_b32 s18, s10, 2
	v_lshl_add_u64 v[4:5], v[34:35], 0, s[18:19]
	global_load_dwordx4 v[6:9], v[4:5], off
	global_load_dwordx4 v[10:13], v[4:5], off offset:16
.LBB0_1804:
	s_or_b64 exec, exec, s[6:7]
	s_or_b32 s50, s12, 1
	s_lshl_b32 s51, s50, 6
	s_and_b32 s8, 0xffff, s8
	s_cmp_gt_u32 s8, 26
	s_cselect_b64 s[6:7], -1, 0
	s_cmp_lt_u32 s8, 27
	v_add_u32_e32 v0, s51, v19
	s_movk_i32 s13, 0x1b09
	s_cselect_b64 s[8:9], -1, 0
	v_cmp_gt_u32_e32 vcc, s13, v0
	s_and_b64 s[14:15], s[8:9], vcc
	v_mov_b32_e32 v3, 0
	v_mov_b32_e32 v4, 0
	v_mov_b32_e32 v5, 0
	v_mov_b32_e32 v14, 0
	v_mov_b32_e32 v15, 0
	v_mov_b32_e32 v16, 0
	v_mov_b32_e32 v17, 0
	s_and_saveexec_b64 s[8:9], s[14:15]
	s_cbranch_execz .LBB0_1806
	s_lshl_b32 s18, s51, 2
	v_lshl_add_u64 v[14:15], v[34:35], 0, s[18:19]
	global_load_dwordx4 v[2:5], v[14:15], off
	s_nop 0
	global_load_dwordx4 v[14:17], v[14:15], off offset:16
.LBB0_1806:
	s_or_b64 exec, exec, s[8:9]
	s_or_b32 s48, s12, 2
	s_lshl_b32 s49, s48, 6
	v_or_b32_e32 v0, s49, v19
	s_movk_i32 s8, 0x1b09
	v_cmp_gt_u32_e32 vcc, s8, v0
	s_xor_b64 s[6:7], s[6:7], -1
	s_and_b64 s[8:9], s[6:7], vcc
	v_mov_b32_e32 v18, 0
	v_mov_b32_e32 v22, 0
	v_mov_b32_e32 v23, 0
	v_mov_b32_e32 v24, 0
	v_mov_b32_e32 v25, 0
	v_mov_b32_e32 v26, 0
	v_mov_b32_e32 v27, 0
	v_mov_b32_e32 v28, 0
	v_mov_b32_e32 v29, 0
	s_and_saveexec_b64 s[6:7], s[8:9]
	s_cbranch_execz .LBB0_1808
	s_lshl_b32 s18, s49, 2
	v_lshl_add_u64 v[20:21], v[34:35], 0, s[18:19]
	global_load_dwordx4 v[22:25], v[20:21], off
	global_load_dwordx4 v[26:29], v[20:21], off offset:16
.LBB0_1808:
	s_or_b64 exec, exec, s[6:7]
	s_or_b32 s46, s12, 3
	s_lshl_b32 s47, s46, 6
	s_cmpk_lt_u32 s46, 0x6d
	v_add_u32_e32 v0, s47, v19
	s_movk_i32 s8, 0x1b09
	s_cselect_b64 s[6:7], -1, 0
	v_cmp_gt_u32_e32 vcc, s8, v0
	s_and_b64 s[8:9], s[6:7], vcc
	v_mov_b32_e32 v19, 0
	v_mov_b32_e32 v20, 0
	v_mov_b32_e32 v21, 0
	v_mov_b32_e32 v30, 0
	v_mov_b32_e32 v31, 0
	v_mov_b32_e32 v32, 0
	v_mov_b32_e32 v33, 0
	s_and_saveexec_b64 s[6:7], s[8:9]
	s_cbranch_execz .LBB0_1810
	s_lshl_b32 s18, s47, 2
	v_lshl_add_u64 v[30:31], v[34:35], 0, s[18:19]
	global_load_dwordx4 v[18:21], v[30:31], off
	s_nop 0
	global_load_dwordx4 v[30:33], v[30:31], off offset:16

.LBB0_2015:
	s_and_b64 vcc, exec, s[6:7]
	s_cbranch_vccz .LBB0_2045
	v_mov_b32_e32 v0, s64
	v_mov_b32_e32 v2, s65
	v_readlane_b32 s8, v254, 60
	v_readfirstlane_b32 s6, v0
	v_readfirstlane_b32 s7, v2
	s_nop 0
	v_mov_b32_e32 v2, s6
	v_mov_b32_e32 v3, s7
	global_load_dwordx2 v[2:3], v[2:3], off offset:72
	s_waitcnt vmcnt(0) lgkmcnt(0)
	v_mov_b32_e32 v0, v3
	s_nop 0
	v_readfirstlane_b32 s6, v2
	v_readfirstlane_b32 s7, v0
	s_add_u32 s10, s6, s8
	v_readlane_b32 s6, v254, 58
	s_addc_u32 s11, s7, s6
	v_mov_b32_e32 v0, v247
	s_and_b32 s6, s44, 0x3fc0
	s_addk_i32 s6, 0xea00
	v_ashrrev_i32_e32 v4, 3, v0
	v_add_u32_e32 v2, s6, v4
	v_lshlrev_b32_e32 v0, 3, v0
	v_ashrrev_i32_e32 v3, 31, v2
	v_and_b32_e32 v5, 56, v0
	v_lshlrev_b64 v[2:3], 12, v[2:3]
	s_and_b32 s8, s34, 0x300
	v_lshl_add_u64 v[2:3], s[10:11], 0, v[2:3]
	v_lshlrev_b32_e32 v0, 2, v5
	v_lshl_add_u64 v[2:3], v[2:3], 0, v[0:1]
	s_lshl_b32 s18, s8, 2
	s_movk_i32 s7, 0x104
	v_lshl_add_u64 v[2:3], v[2:3], 0, s[18:19]
	v_mul_lo_u32 v6, v4, s7
	v_add_u32_e32 v10, 16, v6
	global_load_dwordx4 v[6:9], v[2:3], off
	v_add_u32_e32 v0, v10, v0
	v_add_u32_e32 v11, 0x4100, v0
	s_mov_b32 s7, s19
	s_lshl_b64 s[6:7], s[6:7], 1
	s_add_u32 s6, s21, s6
	s_addc_u32 s7, s33, s7
	s_waitcnt vmcnt(0) lgkmcnt(0)
	ds_write2_b32 v0, v6, v7 offset1:1
	ds_write2_b32 v0, v8, v9 offset0:2 offset1:3
	global_load_dwordx4 v[6:9], v[2:3], off offset:16
	s_waitcnt vmcnt(0) lgkmcnt(0)
	ds_write2_b32 v0, v6, v7 offset0:4 offset1:5
	ds_write2_b32 v0, v8, v9 offset0:6 offset1:7
	global_load_dwordx4 v[6:9], v[2:3], off offset:256
	s_waitcnt vmcnt(0) lgkmcnt(0)
	ds_write2_b32 v11, v6, v7 offset1:1
	v_add_u32_e32 v6, 0x4108, v0
	ds_write2_b32 v6, v8, v9 offset1:1
	global_load_dwordx4 v[6:9], v[2:3], off offset:272
	v_add_u32_e32 v11, 0x4110, v0
	s_waitcnt vmcnt(0) lgkmcnt(0)
	ds_write2_b32 v11, v6, v7 offset1:1
	v_add_u32_e32 v6, 0x4118, v0
	ds_write2_b32 v6, v8, v9 offset1:1
	global_load_dwordx4 v[6:9], v[2:3], off offset:512
	v_add_u32_e32 v11, 0x8200, v0
	s_waitcnt vmcnt(0) lgkmcnt(0)
	ds_write2_b32 v11, v6, v7 offset1:1
	v_add_u32_e32 v6, 0x8208, v0
	ds_write2_b32 v6, v8, v9 offset1:1
	global_load_dwordx4 v[6:9], v[2:3], off offset:528
	v_add_u32_e32 v11, 0x8210, v0
	s_waitcnt vmcnt(0) lgkmcnt(0)
	ds_write2_b32 v11, v6, v7 offset1:1
	v_add_u32_e32 v6, 0x8218, v0
	ds_write2_b32 v6, v8, v9 offset1:1
	global_load_dwordx4 v[6:9], v[2:3], off offset:768
	v_add_u32_e32 v11, 0xc300, v0
	s_waitcnt vmcnt(0) lgkmcnt(0)
	ds_write2_b32 v11, v6, v7 offset1:1
	v_add_u32_e32 v6, 0xc308, v0
	ds_write2_b32 v6, v8, v9 offset1:1
	global_load_dwordx4 v[6:9], v[2:3], off offset:784
	v_add_u32_e32 v11, 0xc310, v0
	v_add_u32_e32 v0, 0xc318, v0
	s_waitcnt vmcnt(0) lgkmcnt(0)
	ds_write2_b32 v0, v8, v9 offset1:1
	v_lshlrev_b32_e32 v0, 8, v4
	ds_write2_b32 v11, v6, v7 offset1:1
	v_sub_u32_e32 v6, v10, v0
	v_lshlrev_b32_e32 v0, 1, v5
	v_mul_u32_u24_e32 v7, 0x104, v5
	v_lshl_add_u64 v[2:3], s[6:7], 0, v[0:1]
	v_add_u32_e32 v5, s8, v4
	s_movk_i32 s6, 0x400
	v_cmp_gt_u32_e32 vcc, s6, v5
	v_add_u32_e32 v6, v6, v7
	s_waitcnt lgkmcnt(0)
	s_barrier
	s_and_saveexec_b64 s[6:7], vcc
	s_cbranch_execz .LBB0_2018
	v_add_u32_e32 v0, 0x400, v6
	ds_read2_b32 v[8:9], v0 offset0:134 offset1:199
	ds_read2_b32 v[12:13], v6 offset1:65
	s_movk_i32 s9, 0x1600
	s_waitcnt lgkmcnt(1)
	v_cvt_pk_bf16_f32 v11, v8, v9
	ds_read2_b32 v[8:9], v0 offset0:4 offset1:69
	v_mul_lo_u32 v0, v5, s9
	s_waitcnt lgkmcnt(0)
	v_cvt_pk_bf16_f32 v10, v8, v9
	ds_read2_b32 v[8:9], v6 offset0:130 offset1:195
	s_waitcnt lgkmcnt(0)
	v_cvt_pk_bf16_f32 v9, v8, v9
	v_cvt_pk_bf16_f32 v8, v12, v13
	v_lshl_add_u64 v[12:13], v[2:3], 0, v[0:1]
	global_store_dwordx4 v[12:13], v[8:11], off

.LBB0_2026:
	v_mov_b32_e32 v0, s64
	v_mov_b32_e32 v2, s65
	v_readlane_b32 s8, v254, 60
	v_readfirstlane_b32 s6, v0
	v_readfirstlane_b32 s7, v2
	v_mov_b32_e32 v10, v247
	v_mov_b32_e32 v2, s6
	v_mov_b32_e32 v3, s7
	global_load_dwordx2 v[2:3], v[2:3], off offset:64
	s_waitcnt vmcnt(0) lgkmcnt(0)
	v_mov_b32_e32 v0, v3
	s_nop 0
	v_readfirstlane_b32 s6, v2
	v_readfirstlane_b32 s7, v0
	s_add_u32 s6, s6, s8
	v_readlane_b32 s8, v254, 58
	s_addc_u32 s7, s7, s8
	s_add_i32 s8, s4, 0x50
	s_and_b32 s9, s8, 0xff
	s_mulk_i32 s9, 0x75
	s_lshr_b32 s10, s9, 8
	s_sub_i32 s10, s8, s10
	s_bfe_u32 s10, s10, 0x70001
	s_bfe_u32 s9, s9, 0x80008
	s_add_i32 s10, s10, s9
	s_bfe_u32 s9, s10, 0x50003
	s_mul_i32 s10, s9, 11
	s_sub_i32 s8, s8, s10
	v_ashrrev_i32_e32 v4, 3, v10
	v_lshlrev_b32_e32 v0, 3, v10
	s_lshl_b32 s8, s8, 2
	v_and_b32_e32 v5, 56, v0
	v_lshl_add_u32 v0, s9, 6, v4
	v_mov_b64_e32 v[2:3], s[6:7]
	s_movk_i32 s6, 0x2c00
	s_and_b32 s10, s8, 0xfc
	v_mad_i64_i32 v[2:3], s[6:7], v0, s6, v[2:3]
	v_lshlrev_b32_e32 v0, 2, v5
	v_lshl_add_u64 v[2:3], v[2:3], 0, v[0:1]
	s_lshl_b32 s18, s10, 8
	s_movk_i32 s6, 0x104
	v_lshl_add_u64 v[2:3], v[2:3], 0, s[18:19]
	v_mul_lo_u32 v6, v4, s6
	v_add_u32_e32 v11, 16, v6
	global_load_dwordx4 v[6:9], v[2:3], off
	v_add_u32_e32 v0, v11, v0
	v_add_u32_e32 v12, 0x4100, v0
	s_lshl_b32 s8, s10, 6
	s_lshl_b32 s6, s9, 7
	s_add_u32 s6, s0, s6
	s_addc_u32 s7, s1, 0
	s_waitcnt vmcnt(0) lgkmcnt(0)
	ds_write2_b32 v0, v6, v7 offset1:1
	ds_write2_b32 v0, v8, v9 offset0:2 offset1:3
	global_load_dwordx4 v[6:9], v[2:3], off offset:16
	s_waitcnt vmcnt(0) lgkmcnt(0)
	ds_write2_b32 v0, v6, v7 offset0:4 offset1:5
	ds_write2_b32 v0, v8, v9 offset0:6 offset1:7
	global_load_dwordx4 v[6:9], v[2:3], off offset:256
	s_waitcnt vmcnt(0) lgkmcnt(0)
	ds_write2_b32 v12, v6, v7 offset1:1
	v_add_u32_e32 v6, 0x4108, v0
	ds_write2_b32 v6, v8, v9 offset1:1
	global_load_dwordx4 v[6:9], v[2:3], off offset:272
	v_add_u32_e32 v12, 0x4110, v0
	s_waitcnt vmcnt(0) lgkmcnt(0)
	ds_write2_b32 v12, v6, v7 offset1:1
	v_add_u32_e32 v6, 0x4118, v0
	ds_write2_b32 v6, v8, v9 offset1:1
	global_load_dwordx4 v[6:9], v[2:3], off offset:512
	v_add_u32_e32 v12, 0x8200, v0
	s_waitcnt vmcnt(0) lgkmcnt(0)
	ds_write2_b32 v12, v6, v7 offset1:1
	v_add_u32_e32 v6, 0x8208, v0
	ds_write2_b32 v6, v8, v9 offset1:1
	global_load_dwordx4 v[6:9], v[2:3], off offset:528
	v_add_u32_e32 v12, 0x8210, v0
	s_waitcnt vmcnt(0) lgkmcnt(0)
	ds_write2_b32 v12, v6, v7 offset1:1
	v_add_u32_e32 v6, 0x8218, v0
	ds_write2_b32 v6, v8, v9 offset1:1
	global_load_dwordx4 v[6:9], v[2:3], off offset:768
	v_add_u32_e32 v12, 0xc300, v0
	s_waitcnt vmcnt(0) lgkmcnt(0)
	ds_write2_b32 v12, v6, v7 offset1:1
	v_add_u32_e32 v6, 0xc308, v0
	ds_write2_b32 v6, v8, v9 offset1:1
	global_load_dwordx4 v[6:9], v[2:3], off offset:784
	v_add_u32_e32 v12, 0xc310, v0
	v_add_u32_e32 v0, 0xc318, v0
	s_waitcnt vmcnt(0) lgkmcnt(0)
	ds_write2_b32 v0, v8, v9 offset1:1
	v_lshlrev_b32_e32 v0, 8, v4
	ds_write2_b32 v12, v6, v7 offset1:1
	v_sub_u32_e32 v7, v11, v0
	v_lshlrev_b32_e32 v0, 1, v5
	v_mul_u32_u24_e32 v8, 0x104, v5
	v_lshl_add_u64 v[2:3], s[6:7], 0, v[0:1]
	v_add_u32_e32 v5, s8, v4
	s_movk_i32 s6, 0xb00
	v_cmp_gt_u32_e32 vcc, s6, v5
	v_bfe_u32 v6, v10, 3, 7
	v_add_u32_e32 v7, v7, v8
	s_waitcnt lgkmcnt(0)
	s_barrier
	s_and_saveexec_b64 s[6:7], vcc
	s_cbranch_execz .LBB0_2028
	v_add_u32_e32 v10, 0x400, v7
	ds_read2_b32 v[8:9], v10 offset0:134 offset1:199
	ds_read2_b32 v[12:13], v7 offset1:65
	v_lshlrev_b32_e32 v0, 1, v5
	s_movk_i32 s9, 0x1f00
	v_and_or_b32 v0, v0, s9, v6
	s_waitcnt lgkmcnt(1)
	v_cvt_pk_bf16_f32 v11, v8, v9
	ds_read2_b32 v[8:9], v10 offset0:4 offset1:69
	v_lshlrev_b32_e32 v0, 11, v0
	s_waitcnt lgkmcnt(0)
	v_cvt_pk_bf16_f32 v10, v8, v9
	ds_read2_b32 v[8:9], v7 offset0:130 offset1:195
	s_waitcnt lgkmcnt(0)
	v_cvt_pk_bf16_f32 v9, v8, v9
	v_cvt_pk_bf16_f32 v8, v12, v13
	v_lshl_add_u64 v[12:13], v[2:3], 0, v[0:1]
	v_add_co_u32_e32 v12, vcc, 0x40000, v12
	s_nop 1
	v_addc_co_u32_e32 v13, vcc, 0, v13, vcc
	global_store_dwordx4 v[12:13], v[8:11], off

.LBB0_2036:
	s_andn2_b64 vcc, exec, s[6:7]
	s_cbranch_vccnz .LBB0_1798
	v_mov_b32_e32 v0, s64
	v_mov_b32_e32 v2, s65
	v_readlane_b32 s8, v254, 60
	v_readfirstlane_b32 s6, v0
	v_readfirstlane_b32 s7, v2
	v_mov_b32_e32 v8, v247
	v_mov_b32_e32 v2, s6
	v_mov_b32_e32 v3, s7
	global_load_dwordx2 v[2:3], v[2:3], off offset:56
	s_waitcnt vmcnt(0) lgkmcnt(0)
	v_mov_b32_e32 v0, v3
	s_nop 0
	v_readfirstlane_b32 s6, v2
	v_readfirstlane_b32 s7, v0
	s_add_u32 s12, s6, s8
	v_readlane_b32 s6, v254, 58
	s_addc_u32 s13, s7, s6
	s_mul_hi_i32 s6, s4, 0x2e8ba2e9
	s_lshr_b32 s7, s6, 31
	s_ashr_i32 s10, s6, 1
	s_add_i32 s10, s10, s7
	s_mul_i32 s6, s10, 0xfffff500
	s_add_i32 s8, s34, s6
	v_ashrrev_i32_e32 v9, 3, v8
	v_lshlrev_b32_e32 v0, 3, v8
	s_lshl_b32 s6, s10, 6
	v_and_b32_e32 v10, 56, v0
	v_add_u32_e32 v0, s6, v9
	v_mov_b64_e32 v[2:3], s[12:13]
	s_movk_i32 s7, 0x2c00
	v_mad_i64_i32 v[2:3], s[12:13], v0, s7, v[2:3]
	v_lshlrev_b32_e32 v0, 2, v10
	v_lshl_add_u64 v[2:3], v[2:3], 0, v[0:1]
	s_ashr_i32 s9, s8, 31
	s_movk_i32 s7, 0x104
	v_lshl_add_u64 v[6:7], s[8:9], 2, v[2:3]
	v_mul_lo_u32 v2, v9, s7
	v_add_u32_e32 v11, 16, v2
	global_load_dwordx4 v[2:5], v[6:7], off
	v_add_u32_e32 v0, v11, v0
	v_add_u32_e32 v12, 0x4100, v0
	s_ashr_i32 s7, s6, 31
	s_lshl_b64 s[6:7], s[6:7], 1
	s_add_u32 s6, s0, s6
	s_addc_u32 s7, s1, s7
	s_mulk_i32 s10, 0xb00
	s_waitcnt vmcnt(0) lgkmcnt(0)
	ds_write2_b32 v0, v2, v3 offset1:1
	ds_write2_b32 v0, v4, v5 offset0:2 offset1:3
	global_load_dwordx4 v[2:5], v[6:7], off offset:16
	s_waitcnt vmcnt(0) lgkmcnt(0)
	ds_write2_b32 v0, v2, v3 offset0:4 offset1:5
	ds_write2_b32 v0, v4, v5 offset0:6 offset1:7
	global_load_dwordx4 v[2:5], v[6:7], off offset:256
	s_waitcnt vmcnt(0) lgkmcnt(0)
	ds_write2_b32 v12, v2, v3 offset1:1
	v_add_u32_e32 v2, 0x4108, v0
	ds_write2_b32 v2, v4, v5 offset1:1
	global_load_dwordx4 v[2:5], v[6:7], off offset:272
	v_add_u32_e32 v12, 0x4110, v0
	s_waitcnt vmcnt(0) lgkmcnt(0)
	ds_write2_b32 v12, v2, v3 offset1:1
	v_add_u32_e32 v2, 0x4118, v0
	ds_write2_b32 v2, v4, v5 offset1:1
	global_load_dwordx4 v[2:5], v[6:7], off offset:512
	v_add_u32_e32 v12, 0x8200, v0
	s_waitcnt vmcnt(0) lgkmcnt(0)
	ds_write2_b32 v12, v2, v3 offset1:1
	v_add_u32_e32 v2, 0x8208, v0
	ds_write2_b32 v2, v4, v5 offset1:1
	global_load_dwordx4 v[2:5], v[6:7], off offset:528
	v_add_u32_e32 v12, 0x8210, v0
	s_waitcnt vmcnt(0) lgkmcnt(0)
	ds_write2_b32 v12, v2, v3 offset1:1
	v_add_u32_e32 v2, 0x8218, v0
	ds_write2_b32 v2, v4, v5 offset1:1
	global_load_dwordx4 v[2:5], v[6:7], off offset:768
	v_add_u32_e32 v12, 0xc300, v0
	s_waitcnt vmcnt(0) lgkmcnt(0)
	ds_write2_b32 v12, v2, v3 offset1:1
	v_add_u32_e32 v2, 0xc308, v0
	ds_write2_b32 v2, v4, v5 offset1:1
	global_load_dwordx4 v[2:5], v[6:7], off offset:784
	v_add_u32_e32 v12, 0xc310, v0
	v_add_u32_e32 v0, 0xc318, v0
	v_mul_u32_u24_e32 v7, 0x104, v10
	s_waitcnt vmcnt(0) lgkmcnt(0)
	ds_write2_b32 v0, v4, v5 offset1:1
	v_lshlrev_b32_e32 v0, 8, v9
	v_sub_u32_e32 v6, v11, v0
	v_lshlrev_b32_e32 v0, 1, v10
	ds_write2_b32 v12, v2, v3 offset1:1
	v_lshl_add_u64 v[2:3], s[6:7], 0, v[0:1]
	v_subrev_u32_e32 v0, s10, v9
	v_add_u32_e32 v4, s34, v0
	s_movk_i32 s10, 0xb00
	v_cmp_gt_u32_e32 vcc, s10, v4
	v_bfe_u32 v5, v8, 3, 7
	v_add_u32_e32 v6, v6, v7
	s_waitcnt lgkmcnt(0)
	s_barrier
	s_and_saveexec_b64 s[6:7], vcc
	s_cbranch_execz .LBB0_2039
	v_add_u32_e32 v7, 0x400, v6
	ds_read2_b32 v[8:9], v7 offset0:134 offset1:199
	ds_read2_b32 v[12:13], v6 offset1:65
	v_lshlrev_b32_e32 v0, 1, v4
	s_movk_i32 s8, 0x1f00
	v_and_or_b32 v0, v0, s8, v5
	s_waitcnt lgkmcnt(1)
	v_cvt_pk_bf16_f32 v11, v8, v9
	ds_read2_b32 v[8:9], v7 offset0:4 offset1:69
	v_lshlrev_b32_e32 v0, 11, v0
	s_waitcnt lgkmcnt(0)
	v_cvt_pk_bf16_f32 v10, v8, v9
	ds_read2_b32 v[8:9], v6 offset0:130 offset1:195
	s_waitcnt lgkmcnt(0)
	v_cvt_pk_bf16_f32 v9, v8, v9
	v_cvt_pk_bf16_f32 v8, v12, v13
	v_lshl_add_u64 v[12:13], v[2:3], 0, v[0:1]
	global_store_dwordx4 v[12:13], v[8:11], off

.LBB0_2046:
	v_readlane_b32 s0, v255, 0
	v_readlane_b32 s4, v255, 8
	v_readlane_b32 s1, v255, 1
	v_readlane_b32 s5, v255, 9
	s_and_b64 s[0:1], s[0:1], s[4:5]
	s_andn2_b64 vcc, exec, s[0:1]
	s_cbranch_vccnz .LBB0_2359
	v_mov_b32_e32 v0, s64
	v_mov_b32_e32 v2, s65
	s_nop 0
	v_readfirstlane_b32 s0, v0
	v_readfirstlane_b32 s1, v2
	v_mov_b32_e32 v0, s88
	v_mov_b32_e32 v2, s0
	v_mov_b32_e32 v3, s1
	global_load_dwordx2 v[2:3], v[2:3], off offset:248
	s_waitcnt vmcnt(0) lgkmcnt(0)
	s_nop 0
	v_readfirstlane_b32 s4, v0
	v_readfirstlane_b32 s0, v2
	s_cmp_lt_i32 s4, 48
	v_readfirstlane_b32 s1, v3
	s_cbranch_scc1 .LBB0_2359
	s_addk_i32 s4, 0x3a0
	s_cmpk_gt_i32 s4, 0x65f
	s_cbranch_scc1 .LBB0_2359
	s_add_u32 s5, s0, 0x2d80000
	s_addc_u32 s20, s1, 0
	s_add_u32 s21, s0, 0x2280000
	s_addc_u32 s33, s1, 0
	s_add_u32 s34, s0, 0x2080000
	s_addc_u32 s35, s1, 0
	s_add_u32 s44, s0, 0x1e80000
	s_addc_u32 s45, s1, 0
	s_add_u32 s46, s0, 0x1080000
	s_addc_u32 s47, s1, 0
	s_add_u32 s48, s0, 0xb00000
	v_readlane_b32 s6, v254, 21
	s_addc_u32 s49, s1, 0
	s_lshl_b32 s50, s4, 8
	s_lshl_b32 s51, s6, 8
	s_lshl_b32 s52, s4, 4
	s_lshl_b32 s53, s6, 4
	s_branch .LBB0_2052

.LBB0_2052:
	s_cmpk_gt_i32 s4, 0xaf
	s_mov_b64 s[6:7], -1
	s_cbranch_scc0 .LBB0_2349
	s_cmpk_gt_u32 s4, 0x15f
	s_cbranch_scc0 .LBB0_2338
	s_cmpk_gt_u32 s4, 0x20f
	s_cbranch_scc0 .LBB0_2327
	s_cmpk_gt_u32 s4, 0x3cf
	s_cbranch_scc0 .LBB0_2112
	s_cmpk_gt_u32 s4, 0x40f
	s_cbranch_scc0 .LBB0_2101
	s_cmpk_gt_u32 s4, 0x44f
	s_cbranch_scc0 .LBB0_2090
	s_cmpk_gt_u32 s4, 0x4ff
	s_cbranch_scc0 .LBB0_2079
	s_cmpk_gt_u32 s4, 0x5af
	s_cbranch_scc0 .LBB0_2069
	v_mov_b32_e32 v0, s64
	v_mov_b32_e32 v2, s65
	v_readlane_b32 s8, v254, 59
	v_readfirstlane_b32 s6, v0
	v_readfirstlane_b32 s7, v2
	s_nop 0
	v_mov_b32_e32 v2, s6
	v_mov_b32_e32 v3, s7
	global_load_dwordx2 v[2:3], v[2:3], off offset:224
	s_waitcnt vmcnt(0) lgkmcnt(0)
	v_mov_b32_e32 v0, v3
	s_nop 0
	v_readfirstlane_b32 s6, v2
	v_readfirstlane_b32 s7, v0
	s_add_u32 s10, s6, s8
	v_readlane_b32 s6, v255, 2
	s_addc_u32 s11, s7, s6
	v_mov_b32_e32 v0, v247
	s_and_b32 s6, s52, 0xffffffc0
	s_addk_i32 s6, 0xa500
	v_ashrrev_i32_e32 v4, 3, v0
	v_add_u32_e32 v2, s6, v4
	v_lshlrev_b32_e32 v0, 3, v0
	v_ashrrev_i32_e32 v3, 31, v2
	v_and_b32_e32 v5, 56, v0
	v_lshlrev_b64 v[2:3], 12, v[2:3]
	s_and_b32 s8, s50, 0x300
	v_lshl_add_u64 v[2:3], s[10:11], 0, v[2:3]
	v_lshlrev_b32_e32 v0, 2, v5
	v_lshl_add_u64 v[2:3], v[2:3], 0, v[0:1]
	s_lshl_b32 s18, s8, 2
	s_movk_i32 s7, 0x104
	v_lshl_add_u64 v[2:3], v[2:3], 0, s[18:19]
	v_mul_lo_u32 v6, v4, s7
	v_add_u32_e32 v10, 16, v6
	global_load_dwordx4 v[6:9], v[2:3], off
	v_add_u32_e32 v0, v10, v0
	v_add_u32_e32 v11, 0x4100, v0
	s_mov_b32 s7, s19
	s_lshl_b64 s[6:7], s[6:7], 1
	s_add_u32 s6, s5, s6
	s_addc_u32 s7, s20, s7
	s_waitcnt vmcnt(0) lgkmcnt(0)
	ds_write2_b32 v0, v6, v7 offset1:1
	ds_write2_b32 v0, v8, v9 offset0:2 offset1:3
	global_load_dwordx4 v[6:9], v[2:3], off offset:16
	s_waitcnt vmcnt(0) lgkmcnt(0)
	ds_write2_b32 v0, v6, v7 offset0:4 offset1:5
	ds_write2_b32 v0, v8, v9 offset0:6 offset1:7
	global_load_dwordx4 v[6:9], v[2:3], off offset:256
	s_waitcnt vmcnt(0) lgkmcnt(0)
	ds_write2_b32 v11, v6, v7 offset1:1
	v_add_u32_e32 v6, 0x4108, v0
	ds_write2_b32 v6, v8, v9 offset1:1
	global_load_dwordx4 v[6:9], v[2:3], off offset:272
	v_add_u32_e32 v11, 0x4110, v0
	s_waitcnt vmcnt(0) lgkmcnt(0)
	ds_write2_b32 v11, v6, v7 offset1:1
	v_add_u32_e32 v6, 0x4118, v0
	ds_write2_b32 v6, v8, v9 offset1:1
	global_load_dwordx4 v[6:9], v[2:3], off offset:512
	v_add_u32_e32 v11, 0x8200, v0
	s_waitcnt vmcnt(0) lgkmcnt(0)
	ds_write2_b32 v11, v6, v7 offset1:1
	v_add_u32_e32 v6, 0x8208, v0
	ds_write2_b32 v6, v8, v9 offset1:1
	global_load_dwordx4 v[6:9], v[2:3], off offset:528
	v_add_u32_e32 v11, 0x8210, v0
	s_waitcnt vmcnt(0) lgkmcnt(0)
	ds_write2_b32 v11, v6, v7 offset1:1
	v_add_u32_e32 v6, 0x8218, v0
	ds_write2_b32 v6, v8, v9 offset1:1
	global_load_dwordx4 v[6:9], v[2:3], off offset:768
	v_add_u32_e32 v11, 0xc300, v0
	s_waitcnt vmcnt(0) lgkmcnt(0)
	ds_write2_b32 v11, v6, v7 offset1:1
	v_add_u32_e32 v6, 0xc308, v0
	ds_write2_b32 v6, v8, v9 offset1:1
	global_load_dwordx4 v[6:9], v[2:3], off offset:784
	v_add_u32_e32 v11, 0xc310, v0
	v_add_u32_e32 v0, 0xc318, v0
	s_waitcnt vmcnt(0) lgkmcnt(0)
	ds_write2_b32 v0, v8, v9 offset1:1
	v_lshlrev_b32_e32 v0, 8, v4
	ds_write2_b32 v11, v6, v7 offset1:1
	v_sub_u32_e32 v6, v10, v0
	v_lshlrev_b32_e32 v0, 1, v5
	v_mul_u32_u24_e32 v7, 0x104, v5
	v_lshl_add_u64 v[2:3], s[6:7], 0, v[0:1]
	v_add_u32_e32 v5, s8, v4
	s_movk_i32 s6, 0x400
	v_cmp_gt_u32_e32 vcc, s6, v5
	v_add_u32_e32 v6, v6, v7
	s_waitcnt lgkmcnt(0)
	s_barrier
	s_and_saveexec_b64 s[6:7], vcc
	s_cbranch_execz .LBB0_2062
	v_add_u32_e32 v0, 0x400, v6
	ds_read2_b32 v[8:9], v0 offset0:134 offset1:199
	ds_read2_b32 v[12:13], v6 offset1:65
	s_movk_i32 s9, 0x1600
	s_waitcnt lgkmcnt(1)
	v_cvt_pk_bf16_f32 v11, v8, v9
	ds_read2_b32 v[8:9], v0 offset0:4 offset1:69
	v_mul_lo_u32 v0, v5, s9
	s_waitcnt lgkmcnt(0)
	v_cvt_pk_bf16_f32 v10, v8, v9
	ds_read2_b32 v[8:9], v6 offset0:130 offset1:195
	s_waitcnt lgkmcnt(0)
	v_cvt_pk_bf16_f32 v9, v8, v9
	v_cvt_pk_bf16_f32 v8, v12, v13
	v_lshl_add_u64 v[12:13], v[2:3], 0, v[0:1]
	global_store_dwordx4 v[12:13], v[8:11], off

.LBB0_2090:
	s_andn2_b64 vcc, exec, s[6:7]
	s_cbranch_vccnz .LBB0_2100
	v_mov_b32_e32 v0, s64
	v_mov_b32_e32 v2, s65
	v_readlane_b32 s8, v255, 3
	v_readfirstlane_b32 s6, v0
	v_readfirstlane_b32 s7, v2
	v_readlane_b32 s9, v255, 4
	v_mov_b32_e32 v2, s6
	v_mov_b32_e32 v3, s7
	global_load_dwordx2 v[2:3], v[2:3], off offset:192
	s_waitcnt vmcnt(0) lgkmcnt(0)
	v_mov_b32_e32 v0, v3
	s_nop 0
	v_readfirstlane_b32 s6, v2
	v_readfirstlane_b32 s7, v0
	s_add_u32 s10, s6, s8
	s_addc_u32 s11, s7, s9
	v_mov_b32_e32 v0, v247
	s_and_b32 s6, s52, 0x7fc0
	s_addk_i32 s6, 0xbf00
	v_ashrrev_i32_e32 v4, 3, v0
	v_add_u32_e32 v2, s6, v4
	v_lshlrev_b32_e32 v0, 3, v0
	v_ashrrev_i32_e32 v3, 31, v2
	v_and_b32_e32 v5, 56, v0
	v_lshlrev_b64 v[2:3], 12, v[2:3]
	s_and_b32 s8, s50, 0x300
	v_lshl_add_u64 v[2:3], s[10:11], 0, v[2:3]
	v_lshlrev_b32_e32 v0, 2, v5
	v_lshl_add_u64 v[2:3], v[2:3], 0, v[0:1]
	s_lshl_b32 s18, s8, 2
	s_movk_i32 s7, 0x104
	v_lshl_add_u64 v[2:3], v[2:3], 0, s[18:19]
	v_mul_lo_u32 v6, v4, s7
	v_add_u32_e32 v10, 16, v6
	global_load_dwordx4 v[6:9], v[2:3], off
	v_add_u32_e32 v0, v10, v0
	v_add_u32_e32 v11, 0x4100, v0
	s_mov_b32 s7, s19
	s_lshl_b64 s[6:7], s[6:7], 1
	s_add_u32 s6, s34, s6
	s_addc_u32 s7, s35, s7
	s_waitcnt vmcnt(0) lgkmcnt(0)
	ds_write2_b32 v0, v6, v7 offset1:1
	ds_write2_b32 v0, v8, v9 offset0:2 offset1:3
	global_load_dwordx4 v[6:9], v[2:3], off offset:16
	s_waitcnt vmcnt(0) lgkmcnt(0)
	ds_write2_b32 v0, v6, v7 offset0:4 offset1:5
	ds_write2_b32 v0, v8, v9 offset0:6 offset1:7
	global_load_dwordx4 v[6:9], v[2:3], off offset:256
	s_waitcnt vmcnt(0) lgkmcnt(0)
	ds_write2_b32 v11, v6, v7 offset1:1
	v_add_u32_e32 v6, 0x4108, v0
	ds_write2_b32 v6, v8, v9 offset1:1
	global_load_dwordx4 v[6:9], v[2:3], off offset:272
	v_add_u32_e32 v11, 0x4110, v0
	s_waitcnt vmcnt(0) lgkmcnt(0)
	ds_write2_b32 v11, v6, v7 offset1:1
	v_add_u32_e32 v6, 0x4118, v0
	ds_write2_b32 v6, v8, v9 offset1:1
	global_load_dwordx4 v[6:9], v[2:3], off offset:512
	v_add_u32_e32 v11, 0x8200, v0
	s_waitcnt vmcnt(0) lgkmcnt(0)
	ds_write2_b32 v11, v6, v7 offset1:1
	v_add_u32_e32 v6, 0x8208, v0
	ds_write2_b32 v6, v8, v9 offset1:1
	global_load_dwordx4 v[6:9], v[2:3], off offset:528
	v_add_u32_e32 v11, 0x8210, v0
	s_waitcnt vmcnt(0) lgkmcnt(0)
	ds_write2_b32 v11, v6, v7 offset1:1
	v_add_u32_e32 v6, 0x8218, v0
	ds_write2_b32 v6, v8, v9 offset1:1
	global_load_dwordx4 v[6:9], v[2:3], off offset:768
	v_add_u32_e32 v11, 0xc300, v0
	s_waitcnt vmcnt(0) lgkmcnt(0)
	ds_write2_b32 v11, v6, v7 offset1:1
	v_add_u32_e32 v6, 0xc308, v0
	ds_write2_b32 v6, v8, v9 offset1:1
	global_load_dwordx4 v[6:9], v[2:3], off offset:784
	v_add_u32_e32 v11, 0xc310, v0
	v_add_u32_e32 v0, 0xc318, v0
	s_waitcnt vmcnt(0) lgkmcnt(0)
	ds_write2_b32 v0, v8, v9 offset1:1
	v_lshlrev_b32_e32 v0, 8, v4
	ds_write2_b32 v11, v6, v7 offset1:1
	v_sub_u32_e32 v6, v10, v0
	v_lshlrev_b32_e32 v0, 1, v5
	v_mul_u32_u24_e32 v7, 0x104, v5
	v_lshl_add_u64 v[2:3], s[6:7], 0, v[0:1]
	v_add_u32_e32 v5, s8, v4
	s_movk_i32 s6, 0x400
	v_cmp_gt_u32_e32 vcc, s6, v5
	v_add_u32_e32 v6, v6, v7
	s_waitcnt lgkmcnt(0)
	s_barrier
	s_and_saveexec_b64 s[6:7], vcc
	s_cbranch_execz .LBB0_2093
	v_add_u32_e32 v0, 0x400, v6
	ds_read2_b32 v[8:9], v0 offset0:134 offset1:199
	ds_read2_b32 v[12:13], v6 offset1:65
	s_waitcnt lgkmcnt(1)
	v_cvt_pk_bf16_f32 v11, v8, v9
	ds_read2_b32 v[8:9], v0 offset0:4 offset1:69
	v_lshlrev_b32_e32 v0, 11, v5
	s_waitcnt lgkmcnt(0)
	v_cvt_pk_bf16_f32 v10, v8, v9
	ds_read2_b32 v[8:9], v6 offset0:130 offset1:195
	s_waitcnt lgkmcnt(0)
	v_cvt_pk_bf16_f32 v9, v8, v9
	v_cvt_pk_bf16_f32 v8, v12, v13
	v_lshl_add_u64 v[12:13], v[2:3], 0, v[0:1]
	global_store_dwordx4 v[12:13], v[8:11], off

.LBB0_2101:
	s_andn2_b64 vcc, exec, s[6:7]
	s_cbranch_vccnz .LBB0_2111
	s_add_i32 s6, s4, 0xfffffc30
	v_mov_b32_e32 v0, s64
	v_mov_b32_e32 v2, s65
	s_lshr_b32 s10, s6, 4
	s_mov_b32 s11, s19
	v_readfirstlane_b32 s6, v0
	v_readfirstlane_b32 s7, v2
	s_nop 0
	v_mov_b32_e32 v2, s6
	v_mov_b32_e32 v3, s7
	global_load_dwordx2 v[2:3], v[2:3], off offset:184
	v_readlane_b32 s6, v254, 51
	s_add_i32 s18, s10, s6
	s_lshl_b64 s[6:7], s[18:19], 20
	s_waitcnt vmcnt(0) lgkmcnt(0)
	v_mov_b32_e32 v0, v3
	s_nop 0
	v_readfirstlane_b32 s8, v2
	v_readfirstlane_b32 s9, v0
	s_add_u32 s6, s8, s6
	s_addc_u32 s7, s9, s7
	s_and_b32 s8, s50, 0x300
	s_lshl_b64 s[10:11], s[10:11], 9
	s_add_u32 s9, s44, s10
	v_mov_b32_e32 v0, v247
	s_addc_u32 s10, s45, s11
	s_and_b32 s11, s52, 0xc0
	v_ashrrev_i32_e32 v4, 3, v0
	v_add_u32_e32 v2, s11, v4
	v_lshlrev_b32_e32 v0, 3, v0
	v_ashrrev_i32_e32 v3, 31, v2
	v_and_b32_e32 v5, 56, v0
	v_lshlrev_b64 v[2:3], 12, v[2:3]
	v_lshl_add_u64 v[2:3], s[6:7], 0, v[2:3]
	v_lshlrev_b32_e32 v0, 2, v5
	v_lshl_add_u64 v[2:3], v[2:3], 0, v[0:1]
	s_lshl_b32 s18, s8, 2
	s_movk_i32 s6, 0x104
	v_lshl_add_u64 v[2:3], v[2:3], 0, s[18:19]
	v_mul_lo_u32 v6, v4, s6
	v_add_u32_e32 v10, 16, v6
	global_load_dwordx4 v[6:9], v[2:3], off
	v_add_u32_e32 v0, v10, v0
	v_add_u32_e32 v11, 0x4100, v0
	s_lshl_b32 s6, s11, 1
	s_add_u32 s6, s9, s6
	s_addc_u32 s7, s10, 0
	s_waitcnt vmcnt(0) lgkmcnt(0)
	ds_write2_b32 v0, v6, v7 offset1:1
	ds_write2_b32 v0, v8, v9 offset0:2 offset1:3
	global_load_dwordx4 v[6:9], v[2:3], off offset:16
	s_waitcnt vmcnt(0) lgkmcnt(0)
	ds_write2_b32 v0, v6, v7 offset0:4 offset1:5
	ds_write2_b32 v0, v8, v9 offset0:6 offset1:7
	global_load_dwordx4 v[6:9], v[2:3], off offset:256
	s_waitcnt vmcnt(0) lgkmcnt(0)
	ds_write2_b32 v11, v6, v7 offset1:1
	v_add_u32_e32 v6, 0x4108, v0
	ds_write2_b32 v6, v8, v9 offset1:1
	global_load_dwordx4 v[6:9], v[2:3], off offset:272
	v_add_u32_e32 v11, 0x4110, v0
	s_waitcnt vmcnt(0) lgkmcnt(0)
	ds_write2_b32 v11, v6, v7 offset1:1
	v_add_u32_e32 v6, 0x4118, v0
	ds_write2_b32 v6, v8, v9 offset1:1
	global_load_dwordx4 v[6:9], v[2:3], off offset:512
	v_add_u32_e32 v11, 0x8200, v0
	s_waitcnt vmcnt(0) lgkmcnt(0)
	ds_write2_b32 v11, v6, v7 offset1:1
	v_add_u32_e32 v6, 0x8208, v0
	ds_write2_b32 v6, v8, v9 offset1:1
	global_load_dwordx4 v[6:9], v[2:3], off offset:528
	v_add_u32_e32 v11, 0x8210, v0
	s_waitcnt vmcnt(0) lgkmcnt(0)
	ds_write2_b32 v11, v6, v7 offset1:1
	v_add_u32_e32 v6, 0x8218, v0
	ds_write2_b32 v6, v8, v9 offset1:1
	global_load_dwordx4 v[6:9], v[2:3], off offset:768
	v_add_u32_e32 v11, 0xc300, v0
	s_waitcnt vmcnt(0) lgkmcnt(0)
	ds_write2_b32 v11, v6, v7 offset1:1
	v_add_u32_e32 v6, 0xc308, v0
	ds_write2_b32 v6, v8, v9 offset1:1
	global_load_dwordx4 v[6:9], v[2:3], off offset:784
	v_add_u32_e32 v11, 0xc310, v0
	v_add_u32_e32 v0, 0xc318, v0
	s_waitcnt vmcnt(0) lgkmcnt(0)
	ds_write2_b32 v0, v8, v9 offset1:1
	v_lshlrev_b32_e32 v0, 8, v4
	ds_write2_b32 v11, v6, v7 offset1:1
	v_sub_u32_e32 v6, v10, v0
	v_lshlrev_b32_e32 v0, 1, v5
	v_mul_u32_u24_e32 v7, 0x104, v5
	v_lshl_add_u64 v[2:3], s[6:7], 0, v[0:1]
	v_add_u32_e32 v5, s8, v4
	s_movk_i32 s6, 0x400
	v_cmp_gt_u32_e32 vcc, s6, v5
	v_add_u32_e32 v6, v6, v7
	s_waitcnt lgkmcnt(0)
	s_barrier
	s_and_saveexec_b64 s[6:7], vcc
	s_cbranch_execz .LBB0_2104
	v_add_u32_e32 v0, 0x400, v6
	ds_read2_b32 v[8:9], v0 offset0:134 offset1:199
	ds_read2_b32 v[12:13], v6 offset1:65
	s_waitcnt lgkmcnt(1)
	v_cvt_pk_bf16_f32 v11, v8, v9
	ds_read2_b32 v[8:9], v0 offset0:4 offset1:69
	v_lshlrev_b32_e32 v0, 11, v5
	s_waitcnt lgkmcnt(0)
	v_cvt_pk_bf16_f32 v10, v8, v9
	ds_read2_b32 v[8:9], v6 offset0:130 offset1:195
	s_waitcnt lgkmcnt(0)
	v_cvt_pk_bf16_f32 v9, v8, v9
	v_cvt_pk_bf16_f32 v8, v12, v13
	v_lshl_add_u64 v[12:13], v[2:3], 0, v[0:1]
	global_store_dwordx4 v[12:13], v[8:11], off

.LBB0_2115:
	s_or_b64 exec, exec, s[6:7]
	s_or_b32 s58, s12, 1
	s_lshl_b32 s59, s58, 6
	s_and_b32 s8, 0xffff, s8
	s_cmp_gt_u32 s8, 26
	s_cselect_b64 s[6:7], -1, 0
	s_cmp_lt_u32 s8, 27
	v_add_u32_e32 v0, s59, v19
	s_movk_i32 s13, 0x1b09
	s_cselect_b64 s[8:9], -1, 0
	v_cmp_gt_u32_e32 vcc, s13, v0
	s_and_b64 s[14:15], s[8:9], vcc
	v_mov_b32_e32 v3, 0
	v_mov_b32_e32 v4, 0
	v_mov_b32_e32 v5, 0
	v_mov_b32_e32 v14, 0
	v_mov_b32_e32 v15, 0
	v_mov_b32_e32 v16, 0
	v_mov_b32_e32 v17, 0
	s_and_saveexec_b64 s[8:9], s[14:15]
	s_cbranch_execz .LBB0_2117
	s_lshl_b32 s18, s59, 2
	v_lshl_add_u64 v[14:15], v[34:35], 0, s[18:19]
	global_load_dwordx4 v[2:5], v[14:15], off
	s_nop 0
	global_load_dwordx4 v[14:17], v[14:15], off offset:16
.LBB0_2117:
	s_or_b64 exec, exec, s[8:9]
	s_or_b32 s56, s12, 2
	s_lshl_b32 s57, s56, 6
	v_or_b32_e32 v0, s57, v19
	s_movk_i32 s8, 0x1b09
	v_cmp_gt_u32_e32 vcc, s8, v0
	s_xor_b64 s[6:7], s[6:7], -1
	s_and_b64 s[8:9], s[6:7], vcc
	v_mov_b32_e32 v18, 0
	v_mov_b32_e32 v22, 0
	v_mov_b32_e32 v23, 0
	v_mov_b32_e32 v24, 0
	v_mov_b32_e32 v25, 0
	v_mov_b32_e32 v26, 0
	v_mov_b32_e32 v27, 0
	v_mov_b32_e32 v28, 0
	v_mov_b32_e32 v29, 0
	s_and_saveexec_b64 s[6:7], s[8:9]
	s_cbranch_execz .LBB0_2119
	s_lshl_b32 s18, s57, 2
	v_lshl_add_u64 v[20:21], v[34:35], 0, s[18:19]
	global_load_dwordx4 v[22:25], v[20:21], off
	global_load_dwordx4 v[26:29], v[20:21], off offset:16
.LBB0_2119:
	s_or_b64 exec, exec, s[6:7]
	s_or_b32 s54, s12, 3
	s_lshl_b32 s55, s54, 6
	s_cmpk_lt_u32 s54, 0x6d
	v_add_u32_e32 v0, s55, v19
	s_movk_i32 s8, 0x1b09
	s_cselect_b64 s[6:7], -1, 0
	v_cmp_gt_u32_e32 vcc, s8, v0
	s_and_b64 s[8:9], s[6:7], vcc
	v_mov_b32_e32 v19, 0
	v_mov_b32_e32 v20, 0
	v_mov_b32_e32 v21, 0
	v_mov_b32_e32 v30, 0
	v_mov_b32_e32 v31, 0
	v_mov_b32_e32 v32, 0
	v_mov_b32_e32 v33, 0
	s_and_saveexec_b64 s[6:7], s[8:9]
	s_cbranch_execz .LBB0_2121
	s_lshl_b32 s18, s55, 2
	v_lshl_add_u64 v[30:31], v[34:35], 0, s[18:19]
	global_load_dwordx4 v[18:21], v[30:31], off
	s_nop 0
	global_load_dwordx4 v[30:33], v[30:31], off offset:16

.LBB0_2327:
	s_andn2_b64 vcc, exec, s[6:7]
	s_cbranch_vccnz .LBB0_2337
	v_mov_b32_e32 v0, s64
	v_mov_b32_e32 v2, s65
	v_readlane_b32 s8, v254, 59
	v_readfirstlane_b32 s6, v0
	v_readfirstlane_b32 s7, v2
	s_nop 0
	v_mov_b32_e32 v2, s6
	v_mov_b32_e32 v3, s7
	global_load_dwordx2 v[2:3], v[2:3], off offset:72
	s_waitcnt vmcnt(0) lgkmcnt(0)
	v_mov_b32_e32 v0, v3
	s_nop 0
	v_readfirstlane_b32 s6, v2
	v_readfirstlane_b32 s7, v0
	s_add_u32 s10, s6, s8
	v_readlane_b32 s6, v255, 2
	s_addc_u32 s11, s7, s6
	v_mov_b32_e32 v0, v247
	s_and_b32 s6, s52, 0x3fc0
	s_addk_i32 s6, 0xea00
	v_ashrrev_i32_e32 v4, 3, v0
	v_add_u32_e32 v2, s6, v4
	v_lshlrev_b32_e32 v0, 3, v0
	v_ashrrev_i32_e32 v3, 31, v2
	v_and_b32_e32 v5, 56, v0
	v_lshlrev_b64 v[2:3], 12, v[2:3]
	s_and_b32 s8, s50, 0x300
	v_lshl_add_u64 v[2:3], s[10:11], 0, v[2:3]
	v_lshlrev_b32_e32 v0, 2, v5
	v_lshl_add_u64 v[2:3], v[2:3], 0, v[0:1]
	s_lshl_b32 s18, s8, 2
	s_movk_i32 s7, 0x104
	v_lshl_add_u64 v[2:3], v[2:3], 0, s[18:19]
	v_mul_lo_u32 v6, v4, s7
	v_add_u32_e32 v10, 16, v6
	global_load_dwordx4 v[6:9], v[2:3], off
	v_add_u32_e32 v0, v10, v0
	v_add_u32_e32 v11, 0x4100, v0
	s_mov_b32 s7, s19
	s_lshl_b64 s[6:7], s[6:7], 1
	s_add_u32 s6, s48, s6
	s_addc_u32 s7, s49, s7
	s_waitcnt vmcnt(0) lgkmcnt(0)
	ds_write2_b32 v0, v6, v7 offset1:1
	ds_write2_b32 v0, v8, v9 offset0:2 offset1:3
	global_load_dwordx4 v[6:9], v[2:3], off offset:16
	s_waitcnt vmcnt(0) lgkmcnt(0)
	ds_write2_b32 v0, v6, v7 offset0:4 offset1:5
	ds_write2_b32 v0, v8, v9 offset0:6 offset1:7
	global_load_dwordx4 v[6:9], v[2:3], off offset:256
	s_waitcnt vmcnt(0) lgkmcnt(0)
	ds_write2_b32 v11, v6, v7 offset1:1
	v_add_u32_e32 v6, 0x4108, v0
	ds_write2_b32 v6, v8, v9 offset1:1
	global_load_dwordx4 v[6:9], v[2:3], off offset:272
	v_add_u32_e32 v11, 0x4110, v0
	s_waitcnt vmcnt(0) lgkmcnt(0)
	ds_write2_b32 v11, v6, v7 offset1:1
	v_add_u32_e32 v6, 0x4118, v0
	ds_write2_b32 v6, v8, v9 offset1:1
	global_load_dwordx4 v[6:9], v[2:3], off offset:512
	v_add_u32_e32 v11, 0x8200, v0
	s_waitcnt vmcnt(0) lgkmcnt(0)
	ds_write2_b32 v11, v6, v7 offset1:1
	v_add_u32_e32 v6, 0x8208, v0
	ds_write2_b32 v6, v8, v9 offset1:1
	global_load_dwordx4 v[6:9], v[2:3], off offset:528
	v_add_u32_e32 v11, 0x8210, v0
	s_waitcnt vmcnt(0) lgkmcnt(0)
	ds_write2_b32 v11, v6, v7 offset1:1
	v_add_u32_e32 v6, 0x8218, v0
	ds_write2_b32 v6, v8, v9 offset1:1
	global_load_dwordx4 v[6:9], v[2:3], off offset:768
	v_add_u32_e32 v11, 0xc300, v0
	s_waitcnt vmcnt(0) lgkmcnt(0)
	ds_write2_b32 v11, v6, v7 offset1:1
	v_add_u32_e32 v6, 0xc308, v0
	ds_write2_b32 v6, v8, v9 offset1:1
	global_load_dwordx4 v[6:9], v[2:3], off offset:784
	v_add_u32_e32 v11, 0xc310, v0
	v_add_u32_e32 v0, 0xc318, v0
	s_waitcnt vmcnt(0) lgkmcnt(0)
	ds_write2_b32 v0, v8, v9 offset1:1
	v_lshlrev_b32_e32 v0, 8, v4
	ds_write2_b32 v11, v6, v7 offset1:1
	v_sub_u32_e32 v6, v10, v0
	v_lshlrev_b32_e32 v0, 1, v5
	v_mul_u32_u24_e32 v7, 0x104, v5
	v_lshl_add_u64 v[2:3], s[6:7], 0, v[0:1]
	v_add_u32_e32 v5, s8, v4
	s_movk_i32 s6, 0x400
	v_cmp_gt_u32_e32 vcc, s6, v5
	v_add_u32_e32 v6, v6, v7
	s_waitcnt lgkmcnt(0)
	s_barrier
	s_and_saveexec_b64 s[6:7], vcc
	s_cbranch_execz .LBB0_2330
	v_add_u32_e32 v0, 0x400, v6
	ds_read2_b32 v[8:9], v0 offset0:134 offset1:199
	ds_read2_b32 v[12:13], v6 offset1:65
	s_movk_i32 s9, 0x1600
	s_waitcnt lgkmcnt(1)
	v_cvt_pk_bf16_f32 v11, v8, v9
	ds_read2_b32 v[8:9], v0 offset0:4 offset1:69
	v_mul_lo_u32 v0, v5, s9
	s_waitcnt lgkmcnt(0)
	v_cvt_pk_bf16_f32 v10, v8, v9
	ds_read2_b32 v[8:9], v6 offset0:130 offset1:195
	s_waitcnt lgkmcnt(0)
	v_cvt_pk_bf16_f32 v9, v8, v9
	v_cvt_pk_bf16_f32 v8, v12, v13
	v_lshl_add_u64 v[12:13], v[2:3], 0, v[0:1]
	global_store_dwordx4 v[12:13], v[8:11], off

.LBB0_2338:
	s_andn2_b64 vcc, exec, s[6:7]
	s_cbranch_vccnz .LBB0_2348
	v_mov_b32_e32 v0, s64
	v_mov_b32_e32 v2, s65
	v_readlane_b32 s8, v254, 59
	v_readfirstlane_b32 s6, v0
	v_readfirstlane_b32 s7, v2
	v_mov_b32_e32 v10, v247
	v_mov_b32_e32 v2, s6
	v_mov_b32_e32 v3, s7
	global_load_dwordx2 v[2:3], v[2:3], off offset:64
	s_waitcnt vmcnt(0) lgkmcnt(0)
	v_mov_b32_e32 v0, v2
	s_nop 0
	v_readfirstlane_b32 s6, v0
	v_readfirstlane_b32 s7, v3
	s_add_u32 s6, s6, s8
	v_readlane_b32 s8, v255, 2
	s_addc_u32 s7, s7, s8
	s_add_i32 s8, s4, 0x50
	s_and_b32 s9, s8, 0xff
	s_mulk_i32 s9, 0x75
	s_lshr_b32 s10, s9, 8
	s_sub_i32 s10, s8, s10
	s_bfe_u32 s10, s10, 0x70001
	s_bfe_u32 s9, s9, 0x80008
	s_add_i32 s10, s10, s9
	s_bfe_u32 s9, s10, 0x50003
	s_mul_i32 s10, s9, 11
	s_sub_i32 s8, s8, s10
	v_ashrrev_i32_e32 v4, 3, v10
	v_lshlrev_b32_e32 v0, 3, v10
	s_lshl_b32 s8, s8, 2
	v_and_b32_e32 v5, 56, v0
	v_lshl_add_u32 v0, s9, 6, v4
	v_mov_b64_e32 v[2:3], s[6:7]
	s_movk_i32 s6, 0x2c00
	s_and_b32 s10, s8, 0xfc
	v_mad_i64_i32 v[2:3], s[6:7], v0, s6, v[2:3]
	v_lshlrev_b32_e32 v0, 2, v5
	v_lshl_add_u64 v[2:3], v[2:3], 0, v[0:1]
	s_lshl_b32 s18, s10, 8
	s_movk_i32 s6, 0x104
	v_lshl_add_u64 v[2:3], v[2:3], 0, s[18:19]
	v_mul_lo_u32 v6, v4, s6
	v_add_u32_e32 v11, 16, v6
	global_load_dwordx4 v[6:9], v[2:3], off
	v_add_u32_e32 v0, v11, v0
	v_add_u32_e32 v12, 0x4100, v0
	s_lshl_b32 s8, s10, 6
	s_lshl_b32 s6, s9, 7
	s_add_u32 s6, s0, s6
	s_addc_u32 s7, s1, 0
	s_waitcnt vmcnt(0) lgkmcnt(0)
	ds_write2_b32 v0, v6, v7 offset1:1
	ds_write2_b32 v0, v8, v9 offset0:2 offset1:3
	global_load_dwordx4 v[6:9], v[2:3], off offset:16
	s_waitcnt vmcnt(0) lgkmcnt(0)
	ds_write2_b32 v0, v6, v7 offset0:4 offset1:5
	ds_write2_b32 v0, v8, v9 offset0:6 offset1:7
	global_load_dwordx4 v[6:9], v[2:3], off offset:256
	s_waitcnt vmcnt(0) lgkmcnt(0)
	ds_write2_b32 v12, v6, v7 offset1:1
	v_add_u32_e32 v6, 0x4108, v0
	ds_write2_b32 v6, v8, v9 offset1:1
	global_load_dwordx4 v[6:9], v[2:3], off offset:272
	v_add_u32_e32 v12, 0x4110, v0
	s_waitcnt vmcnt(0) lgkmcnt(0)
	ds_write2_b32 v12, v6, v7 offset1:1
	v_add_u32_e32 v6, 0x4118, v0
	ds_write2_b32 v6, v8, v9 offset1:1
	global_load_dwordx4 v[6:9], v[2:3], off offset:512
	v_add_u32_e32 v12, 0x8200, v0
	s_waitcnt vmcnt(0) lgkmcnt(0)
	ds_write2_b32 v12, v6, v7 offset1:1
	v_add_u32_e32 v6, 0x8208, v0
	ds_write2_b32 v6, v8, v9 offset1:1
	global_load_dwordx4 v[6:9], v[2:3], off offset:528
	v_add_u32_e32 v12, 0x8210, v0
	s_waitcnt vmcnt(0) lgkmcnt(0)
	ds_write2_b32 v12, v6, v7 offset1:1
	v_add_u32_e32 v6, 0x8218, v0
	ds_write2_b32 v6, v8, v9 offset1:1
	global_load_dwordx4 v[6:9], v[2:3], off offset:768
	v_add_u32_e32 v12, 0xc300, v0
	s_waitcnt vmcnt(0) lgkmcnt(0)
	ds_write2_b32 v12, v6, v7 offset1:1
	v_add_u32_e32 v6, 0xc308, v0
	ds_write2_b32 v6, v8, v9 offset1:1
	global_load_dwordx4 v[6:9], v[2:3], off offset:784
	v_add_u32_e32 v12, 0xc310, v0
	v_add_u32_e32 v0, 0xc318, v0
	s_waitcnt vmcnt(0) lgkmcnt(0)
	ds_write2_b32 v0, v8, v9 offset1:1
	v_lshlrev_b32_e32 v0, 8, v4
	ds_write2_b32 v12, v6, v7 offset1:1
	v_sub_u32_e32 v7, v11, v0
	v_lshlrev_b32_e32 v0, 1, v5
	v_mul_u32_u24_e32 v8, 0x104, v5
	v_lshl_add_u64 v[2:3], s[6:7], 0, v[0:1]
	v_add_u32_e32 v5, s8, v4
	s_movk_i32 s6, 0xb00
	v_cmp_gt_u32_e32 vcc, s6, v5
	v_bfe_u32 v6, v10, 3, 7
	v_add_u32_e32 v7, v7, v8
	s_waitcnt lgkmcnt(0)
	s_barrier
	s_and_saveexec_b64 s[6:7], vcc
	s_cbranch_execz .LBB0_2341
	v_add_u32_e32 v10, 0x400, v7
	ds_read2_b32 v[8:9], v10 offset0:134 offset1:199
	ds_read2_b32 v[12:13], v7 offset1:65
	v_lshlrev_b32_e32 v0, 1, v5
	s_movk_i32 s9, 0x1f00
	v_and_or_b32 v0, v0, s9, v6
	s_waitcnt lgkmcnt(1)
	v_cvt_pk_bf16_f32 v11, v8, v9
	ds_read2_b32 v[8:9], v10 offset0:4 offset1:69
	v_lshlrev_b32_e32 v0, 11, v0
	s_waitcnt lgkmcnt(0)
	v_cvt_pk_bf16_f32 v10, v8, v9
	ds_read2_b32 v[8:9], v7 offset0:130 offset1:195
	s_waitcnt lgkmcnt(0)
	v_cvt_pk_bf16_f32 v9, v8, v9
	v_cvt_pk_bf16_f32 v8, v12, v13
	v_lshl_add_u64 v[12:13], v[2:3], 0, v[0:1]
	v_add_co_u32_e32 v12, vcc, 0x40000, v12
	s_nop 1
	v_addc_co_u32_e32 v13, vcc, 0, v13, vcc
	global_store_dwordx4 v[12:13], v[8:11], off

.LBB0_2349:
	s_andn2_b64 vcc, exec, s[6:7]
	s_cbranch_vccnz .LBB0_2051
	v_mov_b32_e32 v0, s64
	v_mov_b32_e32 v2, s65
	v_readlane_b32 s8, v254, 59
	v_readfirstlane_b32 s6, v0
	v_readfirstlane_b32 s7, v2
	v_mov_b32_e32 v8, v247
	v_mov_b32_e32 v2, s6
	v_mov_b32_e32 v3, s7
	global_load_dwordx2 v[2:3], v[2:3], off offset:56
	s_waitcnt vmcnt(0) lgkmcnt(0)
	v_mov_b32_e32 v0, v3
	s_nop 0
	v_readfirstlane_b32 s6, v2
	v_readfirstlane_b32 s7, v0
	s_add_u32 s12, s6, s8
	v_readlane_b32 s6, v255, 2
	s_addc_u32 s13, s7, s6
	s_mul_hi_i32 s6, s4, 0x2e8ba2e9
	s_lshr_b32 s7, s6, 31
	s_ashr_i32 s10, s6, 1
	s_add_i32 s10, s10, s7
	s_mul_i32 s6, s10, 0xfffff500
	s_add_i32 s8, s50, s6
	v_ashrrev_i32_e32 v9, 3, v8
	v_lshlrev_b32_e32 v0, 3, v8
	s_lshl_b32 s6, s10, 6
	v_and_b32_e32 v10, 56, v0
	v_add_u32_e32 v0, s6, v9
	v_mov_b64_e32 v[2:3], s[12:13]
	s_movk_i32 s7, 0x2c00
	v_mad_i64_i32 v[2:3], s[12:13], v0, s7, v[2:3]
	v_lshlrev_b32_e32 v0, 2, v10
	v_lshl_add_u64 v[2:3], v[2:3], 0, v[0:1]
	s_ashr_i32 s9, s8, 31
	s_movk_i32 s7, 0x104
	v_lshl_add_u64 v[6:7], s[8:9], 2, v[2:3]
	v_mul_lo_u32 v2, v9, s7
	v_add_u32_e32 v11, 16, v2
	global_load_dwordx4 v[2:5], v[6:7], off
	v_add_u32_e32 v0, v11, v0
	v_add_u32_e32 v12, 0x4100, v0
	s_ashr_i32 s7, s6, 31
	s_lshl_b64 s[6:7], s[6:7], 1
	s_add_u32 s6, s0, s6
	s_addc_u32 s7, s1, s7
	s_mulk_i32 s10, 0xb00
	s_waitcnt vmcnt(0) lgkmcnt(0)
	ds_write2_b32 v0, v2, v3 offset1:1
	ds_write2_b32 v0, v4, v5 offset0:2 offset1:3
	global_load_dwordx4 v[2:5], v[6:7], off offset:16
	s_waitcnt vmcnt(0) lgkmcnt(0)
	ds_write2_b32 v0, v2, v3 offset0:4 offset1:5
	ds_write2_b32 v0, v4, v5 offset0:6 offset1:7
	global_load_dwordx4 v[2:5], v[6:7], off offset:256
	s_waitcnt vmcnt(0) lgkmcnt(0)
	ds_write2_b32 v12, v2, v3 offset1:1
	v_add_u32_e32 v2, 0x4108, v0
	ds_write2_b32 v2, v4, v5 offset1:1
	global_load_dwordx4 v[2:5], v[6:7], off offset:272
	v_add_u32_e32 v12, 0x4110, v0
	s_waitcnt vmcnt(0) lgkmcnt(0)
	ds_write2_b32 v12, v2, v3 offset1:1
	v_add_u32_e32 v2, 0x4118, v0
	ds_write2_b32 v2, v4, v5 offset1:1
	global_load_dwordx4 v[2:5], v[6:7], off offset:512
	v_add_u32_e32 v12, 0x8200, v0
	s_waitcnt vmcnt(0) lgkmcnt(0)
	ds_write2_b32 v12, v2, v3 offset1:1
	v_add_u32_e32 v2, 0x8208, v0
	ds_write2_b32 v2, v4, v5 offset1:1
	global_load_dwordx4 v[2:5], v[6:7], off offset:528
	v_add_u32_e32 v12, 0x8210, v0
	s_waitcnt vmcnt(0) lgkmcnt(0)
	ds_write2_b32 v12, v2, v3 offset1:1
	v_add_u32_e32 v2, 0x8218, v0
	ds_write2_b32 v2, v4, v5 offset1:1
	global_load_dwordx4 v[2:5], v[6:7], off offset:768
	v_add_u32_e32 v12, 0xc300, v0
	s_waitcnt vmcnt(0) lgkmcnt(0)
	ds_write2_b32 v12, v2, v3 offset1:1
	v_add_u32_e32 v2, 0xc308, v0
	ds_write2_b32 v2, v4, v5 offset1:1
	global_load_dwordx4 v[2:5], v[6:7], off offset:784
	v_add_u32_e32 v12, 0xc310, v0
	v_add_u32_e32 v0, 0xc318, v0
	v_mul_u32_u24_e32 v7, 0x104, v10
	s_waitcnt vmcnt(0) lgkmcnt(0)
	ds_write2_b32 v0, v4, v5 offset1:1
	v_lshlrev_b32_e32 v0, 8, v9
	v_sub_u32_e32 v6, v11, v0
	v_lshlrev_b32_e32 v0, 1, v10
	ds_write2_b32 v12, v2, v3 offset1:1
	v_lshl_add_u64 v[2:3], s[6:7], 0, v[0:1]
	v_subrev_u32_e32 v0, s10, v9
	v_add_u32_e32 v4, s50, v0
	s_movk_i32 s10, 0xb00
	v_cmp_gt_u32_e32 vcc, s10, v4
	v_bfe_u32 v5, v8, 3, 7
	v_add_u32_e32 v6, v6, v7
	s_waitcnt lgkmcnt(0)
	s_barrier
	s_and_saveexec_b64 s[6:7], vcc
	s_cbranch_execz .LBB0_2352
	v_add_u32_e32 v7, 0x400, v6
	ds_read2_b32 v[8:9], v7 offset0:134 offset1:199
	ds_read2_b32 v[12:13], v6 offset1:65
	v_lshlrev_b32_e32 v0, 1, v4
	s_movk_i32 s8, 0x1f00
	v_and_or_b32 v0, v0, s8, v5
	s_waitcnt lgkmcnt(1)
	v_cvt_pk_bf16_f32 v11, v8, v9
	ds_read2_b32 v[8:9], v7 offset0:4 offset1:69
	v_lshlrev_b32_e32 v0, 11, v0
	s_waitcnt lgkmcnt(0)
	v_cvt_pk_bf16_f32 v10, v8, v9
	ds_read2_b32 v[8:9], v6 offset0:130 offset1:195
	s_waitcnt lgkmcnt(0)
	v_cvt_pk_bf16_f32 v9, v8, v9
	v_cvt_pk_bf16_f32 v8, v12, v13
	v_lshl_add_u64 v[12:13], v[2:3], 0, v[0:1]
	global_store_dwordx4 v[12:13], v[8:11], off

.LBB0_2364:
	v_readlane_b32 s4, v253, 9
	v_readlane_b32 s5, v253, 10
	v_readlane_b32 s1, v253, 6
	s_or_b64 s[14:15], s[14:15], exec
	v_mov_b64_e32 v[2:3], s[4:5]
	v_readlane_b32 s4, v253, 11
	v_readlane_b32 s5, v253, 12
	s_waitcnt lgkmcnt(0)
	global_load_dword v0, v[2:3], off sc1
	s_or_b64 s[12:13], s[12:13], exec
	v_mov_b64_e32 v[2:3], s[4:5]
	v_readlane_b32 s4, v253, 13
	v_readlane_b32 s5, v253, 14
	global_load_dword v2, v[2:3], off sc1
	s_waitcnt vmcnt(0) lgkmcnt(0)
	v_add_u32_e32 v6, v2, v0
	v_mov_b64_e32 v[4:5], s[4:5]
	v_readlane_b32 s4, v253, 15
	v_readlane_b32 s5, v253, 16
	global_load_dword v3, v[4:5], off sc1
	s_waitcnt vmcnt(0) lgkmcnt(0)
	v_add_u32_e32 v6, v6, v3
	v_mov_b64_e32 v[4:5], s[4:5]
	global_load_dword v4, v[4:5], off sc1
	v_readlane_b32 s4, v253, 17
	v_readlane_b32 s5, v253, 18
	s_waitcnt vmcnt(0) lgkmcnt(0)
	v_add_u32_e32 v8, v6, v4
	v_mov_b64_e32 v[6:7], s[4:5]
	v_readlane_b32 s4, v253, 19
	v_readlane_b32 s5, v253, 20
	global_load_dword v5, v[6:7], off sc1
	s_waitcnt vmcnt(0) lgkmcnt(0)
	v_add_u32_e32 v8, v8, v5
	v_mov_b64_e32 v[6:7], s[4:5]
	global_load_dword v6, v[6:7], off sc1
	v_readlane_b32 s4, v253, 21
	v_readlane_b32 s5, v253, 22
	s_waitcnt vmcnt(0) lgkmcnt(0)
	v_add_u32_e32 v10, v8, v6
	v_mov_b64_e32 v[8:9], s[4:5]
	v_readlane_b32 s4, v253, 23
	v_readlane_b32 s5, v253, 24
	global_load_dword v7, v[8:9], off sc1
	s_waitcnt vmcnt(0) lgkmcnt(0)
	v_add_u32_e32 v10, v10, v7
	v_mov_b64_e32 v[8:9], s[4:5]
	global_load_dword v8, v[8:9], off sc1
	v_readlane_b32 s4, v253, 25
	v_readlane_b32 s5, v253, 26
	s_waitcnt vmcnt(0) lgkmcnt(0)
	v_add_u32_e32 v12, v10, v8
	v_mov_b64_e32 v[10:11], s[4:5]
	v_readlane_b32 s4, v253, 27
	v_readlane_b32 s5, v253, 28
	global_load_dword v9, v[10:11], off sc1
	s_waitcnt vmcnt(0) lgkmcnt(0)
	v_add_u32_e32 v12, v12, v9
	v_mov_b64_e32 v[10:11], s[4:5]
	global_load_dword v10, v[10:11], off sc1
	v_readlane_b32 s4, v253, 29
	v_readlane_b32 s5, v253, 30
	s_waitcnt vmcnt(0) lgkmcnt(0)
	v_add_u32_e32 v14, v12, v10
	v_mov_b64_e32 v[12:13], s[4:5]
	v_readlane_b32 s4, v253, 31
	v_readlane_b32 s5, v253, 32
	global_load_dword v11, v[12:13], off sc1
	s_waitcnt vmcnt(0) lgkmcnt(0)
	v_add_u32_e32 v14, v14, v11
	v_mov_b64_e32 v[12:13], s[4:5]
	global_load_dword v12, v[12:13], off sc1
	v_readlane_b32 s4, v253, 33
	v_readlane_b32 s5, v253, 34
	s_waitcnt vmcnt(0) lgkmcnt(0)
	v_add_u32_e32 v16, v14, v12
	v_mov_b64_e32 v[14:15], s[4:5]
	v_readlane_b32 s4, v253, 35
	v_readlane_b32 s5, v253, 36
	global_load_dword v13, v[14:15], off sc1
	s_waitcnt vmcnt(0) lgkmcnt(0)
	v_add_u32_e32 v16, v16, v13
	v_mov_b64_e32 v[14:15], s[4:5]
	global_load_dword v14, v[14:15], off sc1
	v_readlane_b32 s4, v253, 37
	v_readlane_b32 s5, v253, 38
	s_waitcnt vmcnt(0) lgkmcnt(0)
	v_add_u32_e32 v18, v16, v14
	v_mov_b64_e32 v[16:17], s[4:5]
	v_readlane_b32 s4, v253, 39
	v_readlane_b32 s5, v253, 40
	global_load_dword v15, v[16:17], off sc1
	s_waitcnt vmcnt(0) lgkmcnt(0)
	v_add_u32_e32 v18, v18, v15
	v_mov_b64_e32 v[16:17], s[4:5]
	global_load_dword v16, v[16:17], off sc1
	s_waitcnt vmcnt(0) lgkmcnt(0)
	v_add_u32_e32 v17, v18, v16
	v_cmp_ne_u32_e32 vcc, s1, v17
	s_and_saveexec_b64 s[22:23], vcc
	s_cbranch_execz .LBB0_2363
	s_and_b32 s1, s0, 0xff
	s_mov_b64 s[24:25], -1
	s_cmp_eq_u32 s1, 0
	s_mov_b64 s[28:29], -1
	s_mov_b64 s[26:27], -1
	s_sleep 1
	s_cbranch_scc1 .LBB0_2367
	s_and_saveexec_b64 s[30:31], s[28:29]
	s_cbranch_execz .LBB0_2362
	s_branch .LBB0_2370
.LBB0_2367:
	v_readlane_b32 s4, v253, 7
	v_readlane_b32 s5, v253, 8
	s_mov_b64 s[28:29], 0
	s_nop 0
	v_mov_b64_e32 v[18:19], s[4:5]
	global_load_dword v17, v[18:19], off sc1
	s_waitcnt vmcnt(0) lgkmcnt(0)
	v_cmp_eq_u32_e32 vcc, 0, v17
	s_and_saveexec_b64 s[30:31], vcc
	s_cmp_lt_u32 s0, 0x40001
	s_cselect_b64 s[4:5], -1, 0
	s_xor_b64 s[26:27], exec, -1
	s_and_b64 s[28:29], s[4:5], exec
	s_or_b64 exec, exec, s[30:31]
	s_and_saveexec_b64 s[30:31], s[28:29]
	s_cbranch_execz .LBB0_2362

.LBB0_2371:
	s_or_b64 exec, exec, s[8:9]
	s_xor_b64 s[0:1], s[10:11], -1
	s_and_saveexec_b64 s[4:5], s[0:1]
	s_xor_b64 s[8:9], exec, s[4:5]
	s_cbranch_execz .LBB0_2373
	v_readlane_b32 s0, v253, 7
	v_readlane_b32 s1, v253, 8
	s_nop 1
	v_mov_b64_e32 v[18:19], s[0:1]
	global_atomic_add v[18:19], v166, off

.LBB0_2374:
	v_readlane_b32 s0, v254, 9
	v_readlane_b32 s1, v254, 10
	v_cvt_f32_u32_e32 v3, v2
	v_rcp_iflag_f32_e32 v3, v3
	v_mov_b64_e32 v[4:5], s[0:1]
	global_atomic_add v4, v[4:5], v166, off sc0
	v_sub_u32_e32 v5, 0, v2
	v_mul_f32_e32 v3, 0x4f7ffffe, v3
	v_cvt_u32_f32_e32 v3, v3
	v_mul_lo_u32 v5, v5, v3
	v_mul_hi_u32 v5, v3, v5
	v_add_u32_e32 v3, v3, v5
	s_waitcnt vmcnt(0) lgkmcnt(0)
	v_mul_hi_u32 v3, v4, v3
	v_mul_lo_u32 v5, v3, v2
	v_sub_u32_e32 v5, v4, v5
	v_cmp_ge_u32_e32 vcc, v5, v2
	v_add_u32_e32 v6, 1, v3
	s_nop 0
	v_cndmask_b32_e32 v3, v3, v6, vcc
	v_sub_u32_e32 v6, v5, v2
	v_cndmask_b32_e32 v5, v5, v6, vcc
	v_cmp_ge_u32_e32 vcc, v5, v2
	v_add_u32_e32 v5, 1, v3
	v_add_u32_e32 v6, 1, v4
	v_cndmask_b32_e32 v3, v3, v5, vcc
	v_mad_u64_u32 v[4:5], s[0:1], v2, v3, v[2:3]
	v_cmp_ne_u32_e32 vcc, v6, v4
	s_and_saveexec_b64 s[0:1], vcc
	s_xor_b64 s[8:9], exec, s[0:1]
	s_cbranch_execz .LBB0_2387
	v_readlane_b32 s0, v254, 11
	v_readlane_b32 s1, v254, 12
	s_nop 1
	v_mov_b64_e32 v[4:5], s[0:1]
	global_load_dword v0, v[4:5], off sc1
	s_waitcnt vmcnt(0) lgkmcnt(0)
	v_cmp_eq_u32_e32 vcc, v0, v3
	s_and_saveexec_b64 s[10:11], vcc
	s_cbranch_execz .LBB0_2386
	s_mov_b32 s0, 1
	s_mov_b64 s[12:13], 0
	s_branch .LBB0_2378

.LBB0_2378:
	s_and_b32 s1, s0, 0xff
	s_mov_b64 s[24:25], -1
	s_cmp_lg_u32 s1, 0
	s_mov_b64 s[26:27], -1
	s_sleep 1
	s_cbranch_scc1 .LBB0_2382
	v_readlane_b32 s4, v253, 7
	v_readlane_b32 s5, v253, 8
	s_mov_b64 s[26:27], 0
	s_mov_b64 s[28:29], -1
	v_mov_b64_e32 v[4:5], s[4:5]
	global_load_dword v0, v[4:5], off sc1
	s_waitcnt vmcnt(0) lgkmcnt(0)
	v_cmp_eq_u32_e32 vcc, 0, v0
	s_and_saveexec_b64 s[30:31], vcc
	s_cmp_lt_u32 s0, 0x40001
	s_cselect_b64 s[4:5], -1, 0
	s_xor_b64 s[28:29], exec, -1
	s_and_b64 s[26:27], s[4:5], exec
	s_or_b64 exec, exec, s[30:31]
.LBB0_2382:
	s_andn2_b64 s[4:5], s[22:23], exec
	s_and_b64 s[20:21], s[28:29], exec
	s_or_b64 s[22:23], s[4:5], s[20:21]
	s_and_saveexec_b64 s[28:29], s[26:27]
	s_cbranch_execz .LBB0_2377
	v_readlane_b32 s4, v254, 11
	v_readlane_b32 s5, v254, 12
	s_add_i32 s0, s0, 1
	s_or_b64 s[22:23], s[22:23], exec
	v_mov_b64_e32 v[4:5], s[4:5]
	global_load_dword v0, v[4:5], off sc1
	s_waitcnt vmcnt(0) lgkmcnt(0)
	v_cmp_ne_u32_e32 vcc, v0, v3
	s_orn2_b64 s[24:25], vcc, exec
	s_branch .LBB0_2377
.LBB0_2384:
	s_or_b64 exec, exec, s[12:13]
	s_xor_b64 s[0:1], s[14:15], -1
	s_and_saveexec_b64 s[4:5], s[0:1]
	s_xor_b64 s[4:5], exec, s[4:5]
	s_cbranch_execz .LBB0_2386
	v_readlane_b32 s0, v253, 7
	v_readlane_b32 s1, v253, 8
	s_nop 1
	v_mov_b64_e32 v[2:3], s[0:1]
	global_atomic_add v[2:3], v166, off

.LBB0_2388:
	v_readlane_b32 s0, v254, 13
	v_readlane_b32 s1, v254, 14
	buffer_wbl2 sc1
	s_waitcnt vmcnt(0)
	v_sub_u32_e32 v4, 0, v0
	v_mov_b64_e32 v[2:3], s[0:1]
	global_atomic_add v2, v[2:3], v166, off sc0
	v_cvt_f32_u32_e32 v3, v0
	s_mov_b64 s[10:11], -1
	v_rcp_iflag_f32_e32 v3, v3
	s_nop 0
	v_mul_f32_e32 v3, 0x4f7ffffe, v3
	v_cvt_u32_f32_e32 v3, v3
	v_mul_lo_u32 v4, v4, v3
	v_mul_hi_u32 v4, v3, v4
	v_add_u32_e32 v3, v3, v4
	s_waitcnt vmcnt(0) lgkmcnt(0)
	v_mul_hi_u32 v3, v2, v3
	v_mul_lo_u32 v4, v3, v0
	v_sub_u32_e32 v4, v2, v4
	v_cmp_ge_u32_e32 vcc, v4, v0
	v_add_u32_e32 v5, 1, v3
	s_nop 0
	v_cndmask_b32_e32 v3, v3, v5, vcc
	v_sub_u32_e32 v5, v4, v0
	v_cndmask_b32_e32 v4, v4, v5, vcc
	v_cmp_ge_u32_e32 vcc, v4, v0
	v_add_u32_e32 v4, 1, v3
	v_add_u32_e32 v5, 1, v2
	v_cndmask_b32_e32 v4, v3, v4, vcc
	v_mad_u64_u32 v[2:3], s[0:1], v0, v4, v[0:1]
	v_readlane_b32 s0, v254, 15
	v_readlane_b32 s1, v254, 16
	v_cmp_ne_u32_e32 vcc, v5, v2
	s_nop 0
	v_mov_b64_e32 v[2:3], s[0:1]
	s_and_saveexec_b64 s[8:9], vcc
	s_cbranch_execz .LBB0_2401
	v_readlane_b32 s0, v254, 15
	v_readlane_b32 s1, v254, 16
	s_mov_b64 s[12:13], 0
	s_nop 0
	v_mov_b64_e32 v[2:3], s[0:1]
	global_load_dword v0, v[2:3], off sc1
	s_waitcnt vmcnt(0) lgkmcnt(0)
	v_cmp_eq_u32_e32 vcc, v0, v4
	s_and_saveexec_b64 s[10:11], vcc
	s_cbranch_execz .LBB0_2400
	s_mov_b32 s0, 1
	s_branch .LBB0_2392

.LBB0_2394:
	v_readlane_b32 s4, v253, 7
	v_readlane_b32 s5, v253, 8
	s_mov_b64 s[26:27], 0
	s_mov_b64 s[24:25], -1
	v_mov_b64_e32 v[2:3], s[4:5]
	global_load_dword v0, v[2:3], off sc1
	s_waitcnt vmcnt(0) lgkmcnt(0)
	v_cmp_eq_u32_e32 vcc, 0, v0
	s_and_saveexec_b64 s[28:29], vcc
	s_cmp_lt_u32 s0, 0x40001
	s_cselect_b64 s[4:5], -1, 0
	s_xor_b64 s[24:25], exec, -1
	s_and_b64 s[26:27], s[4:5], exec
	s_or_b64 exec, exec, s[28:29]
	s_and_saveexec_b64 s[28:29], s[26:27]
	s_cbranch_execz .LBB0_2391
.LBB0_2397:
	v_readlane_b32 s4, v254, 15
	v_readlane_b32 s5, v254, 16
	s_add_i32 s0, s0, 1
	s_or_b64 s[24:25], s[24:25], exec
	v_mov_b64_e32 v[2:3], s[4:5]
	global_load_dword v0, v[2:3], off sc1
	s_waitcnt vmcnt(0) lgkmcnt(0)
	v_cmp_ne_u32_e32 vcc, v0, v4
	s_orn2_b64 s[22:23], vcc, exec
	s_branch .LBB0_2391

.LBB0_2402:
	global_atomic_add v[2:3], v166, off
	s_getpc_b64 s[98:99]

.LBB0_2403:
	v_mov_b32_e32 v0, s64
	v_mov_b32_e32 v1, s65
	v_mov_b32_e32 v2, s64
	v_readfirstlane_b32 s0, v0
	v_readfirstlane_b32 s1, v1
	v_mov_b32_e32 v3, s65
	v_mov_b32_e32 v0, s0
	v_mov_b32_e32 v1, s1
	global_load_dwordx2 v[0:1], v[0:1], off offset:248
	s_waitcnt vmcnt(0) lgkmcnt(0)
	v_mov_b32_e32 v4, s64
	v_readfirstlane_b32 s0, v2
	v_readfirstlane_b32 s1, v3
	v_mov_b32_e32 v5, s65
	v_mov_b32_e32 v2, s0
	v_mov_b32_e32 v3, s1
	global_load_dwordx2 v[2:3], v[2:3], off offset:232
	s_waitcnt vmcnt(0) lgkmcnt(0)
	s_nop 0
	v_readfirstlane_b32 s0, v4
	v_readfirstlane_b32 s1, v5
	v_readfirstlane_b32 s8, v2
	v_mov_b32_e32 v4, s0
	v_mov_b32_e32 v5, s1
	global_load_dwordx2 v[6:7], v[4:5], off offset:240
	v_mov_b32_e32 v5, v247
	v_mov_b32_e32 v4, s88
	v_readfirstlane_b32 s0, v0
	v_readfirstlane_b32 s1, v1
	v_readfirstlane_b32 s9, v3
	s_waitcnt vmcnt(0) lgkmcnt(0)
	v_mov_b32_e32 v0, v7
	s_nop 0
	v_readfirstlane_b32 s4, v4
	v_ashrrev_i32_e32 v4, 6, v247
	s_lshl_b32 s6, s4, 3
	v_add_u32_e32 v8, s6, v4
	s_movk_i32 s4, 0x4000
	v_readfirstlane_b32 s2, v6
	v_readfirstlane_b32 s3, v0
	v_cmp_gt_i32_e32 vcc, s4, v8
	s_and_saveexec_b64 s[4:5], vcc
	s_cbranch_execz .LBB0_2406
	v_lshlrev_b32_e32 v0, 4, v5
	v_and_b32_e32 v0, 0x3f0, v0
	v_mov_b32_e32 v1, 0
	v_lshl_add_u64 v[2:3], s[8:9], 0, v[0:1]
	v_xor_b32_e32 v0, 1, v219
	v_cmp_lt_i32_e32 vcc, v0, v220
	s_ashr_i32 s7, s6, 31
	v_mov_b32_e32 v15, 0x358637bd
	v_cndmask_b32_e32 v0, v219, v0, vcc
	v_lshlrev_b32_e32 v9, 2, v0
	v_xor_b32_e32 v0, 2, v219
	v_cmp_lt_i32_e32 vcc, v0, v220
	s_nop 1
	v_cndmask_b32_e32 v0, v219, v0, vcc
	v_lshlrev_b32_e32 v10, 2, v0
	v_xor_b32_e32 v0, 4, v219
	v_cmp_lt_i32_e32 vcc, v0, v220
	s_nop 1
	v_cndmask_b32_e32 v0, v219, v0, vcc
	v_lshlrev_b32_e32 v11, 2, v0
	v_xor_b32_e32 v0, 8, v219
	v_cmp_lt_i32_e32 vcc, v0, v220
	s_nop 1
	v_cndmask_b32_e32 v0, v219, v0, vcc
	v_cmp_lt_i32_e32 vcc, v222, v220
	v_lshlrev_b32_e32 v12, 2, v0
	s_nop 0
	v_cndmask_b32_e32 v0, v219, v222, vcc
	v_cmp_lt_i32_e32 vcc, v221, v220
	v_lshlrev_b32_e32 v13, 2, v0
	s_nop 0
	v_cndmask_b32_e32 v0, v219, v221, vcc
	v_lshlrev_b32_e32 v14, 2, v0
	v_and_b32_e32 v0, 63, v5
	v_ashrrev_i32_e32 v5, 31, v4
	v_lshl_add_u64 v[4:5], v[4:5], 0, s[6:7]
	v_lshlrev_b64 v[6:7], 12, v[4:5]
	v_lshlrev_b32_e32 v0, 4, v0
	v_lshl_add_u64 v[4:5], s[0:1], 0, v[6:7]
	v_lshl_add_u64 v[6:7], s[2:3], 0, v[6:7]
	s_mov_b64 s[0:1], 0
	s_mov_b32 s2, 0x800000
	s_movk_i32 s3, 0x3fff
.LBB0_2405:
	v_lshl_add_u64 v[16:17], v[4:5], 0, v[0:1]
	v_add_co_u32_e32 v36, vcc, 0x3300000, v16
	v_add_u32_e32 v8, s78, v8
	s_nop 0
	v_addc_co_u32_e32 v37, vcc, 0, v17, vcc
	global_load_dwordx4 v[16:19], v[36:37], off
	global_load_dwordx4 v[20:23], v[36:37], off offset:1024
	global_load_dwordx4 v[24:27], v[36:37], off offset:2048
	global_load_dwordx4 v[28:31], v[36:37], off offset:3072
	global_load_dwordx4 v[32:35], v[2:3], off
	v_lshl_add_u64 v[36:37], v[6:7], 0, v[0:1]
	v_lshl_add_u64 v[4:5], v[4:5], 0, s[80:81]
	v_lshl_add_u64 v[6:7], v[6:7], 0, s[80:81]
	s_waitcnt vmcnt(0) lgkmcnt(0)
	v_mov_b32_e32 v40, v17
	v_mov_b32_e32 v41, v21
	v_mov_b32_e32 v38, v16
	v_mov_b32_e32 v39, v20
	v_mov_b32_e32 v48, v25
	v_mov_b32_e32 v49, v29
	v_pk_mul_f32 v[40:41], v[40:41], v[40:41]
	v_mov_b32_e32 v42, v18
	v_mov_b32_e32 v43, v22
	v_mov_b32_e32 v46, v24
	v_mov_b32_e32 v47, v28
	v_pk_mul_f32 v[48:49], v[48:49], v[48:49]
	v_pk_fma_f32 v[38:39], v[38:39], v[38:39], v[40:41]
	v_mov_b32_e32 v44, v19
	v_mov_b32_e32 v45, v23
	v_mov_b32_e32 v50, v26
	v_mov_b32_e32 v51, v30
	v_pk_fma_f32 v[40:41], v[46:47], v[46:47], v[48:49]
	v_pk_fma_f32 v[38:39], v[42:43], v[42:43], v[38:39]
	v_mov_b32_e32 v52, v27
	v_mov_b32_e32 v53, v31
	v_pk_fma_f32 v[40:41], v[50:51], v[50:51], v[40:41]
	v_pk_fma_f32 v[38:39], v[44:45], v[44:45], v[38:39]
	v_pk_fma_f32 v[40:41], v[52:53], v[52:53], v[40:41]
	v_add_f32_e32 v38, v38, v39
	v_add_f32_e32 v38, v38, v40
	v_add_f32_e32 v38, v38, v41
	ds_bpermute_b32 v39, v9, v38
	s_waitcnt lgkmcnt(0)
	v_add_f32_e32 v38, v38, v39
	ds_bpermute_b32 v39, v10, v38
	s_waitcnt lgkmcnt(0)
	v_add_f32_e32 v38, v38, v39
	ds_bpermute_b32 v39, v11, v38
	s_waitcnt lgkmcnt(0)
	v_add_f32_e32 v38, v38, v39
	ds_bpermute_b32 v39, v12, v38
	s_waitcnt lgkmcnt(0)
	v_add_f32_e32 v38, v38, v39
	ds_bpermute_b32 v39, v13, v38
	s_waitcnt lgkmcnt(0)
	v_add_f32_e32 v38, v38, v39
	ds_bpermute_b32 v39, v14, v38
	s_waitcnt lgkmcnt(0)
	v_add_f32_e32 v38, v38, v39
	v_fmamk_f32 v38, v38, 0x3a800000, v15
	v_mul_f32_e32 v39, 0x4b800000, v38
	v_cmp_gt_f32_e32 vcc, s2, v38
	s_nop 1
	v_cndmask_b32_e32 v38, v38, v39, vcc
	v_rsq_f32_e32 v38, v38
	s_nop 0
	v_mul_f32_e32 v39, 0x45800000, v38
	v_cndmask_b32_e32 v38, v38, v39, vcc
	v_pk_mul_f32 v[16:17], v[16:17], v[38:39] op_sel_hi:[1,0]
	v_pk_mul_f32 v[18:19], v[18:19], v[38:39] op_sel_hi:[1,0]
	v_pk_mul_f32 v[16:17], v[32:33], v[16:17]
	v_pk_mul_f32 v[18:19], v[34:35], v[18:19]
	global_store_dwordx4 v[36:37], v[16:19], off
	global_load_dwordx4 v[16:19], v[2:3], off offset:1024
	v_pk_mul_f32 v[20:21], v[20:21], v[38:39] op_sel_hi:[1,0]
	v_pk_mul_f32 v[22:23], v[22:23], v[38:39] op_sel_hi:[1,0]
	v_cmp_lt_i32_e32 vcc, s3, v8
	s_or_b64 s[0:1], vcc, s[0:1]
	s_waitcnt vmcnt(0) lgkmcnt(0)
	v_pk_mul_f32 v[16:17], v[16:17], v[20:21]
	v_pk_mul_f32 v[18:19], v[18:19], v[22:23]
	global_store_dwordx4 v[36:37], v[16:19], off offset:1024
	global_load_dwordx4 v[16:19], v[2:3], off offset:2048
	v_pk_mul_f32 v[20:21], v[24:25], v[38:39] op_sel_hi:[1,0]
	v_pk_mul_f32 v[22:23], v[26:27], v[38:39] op_sel_hi:[1,0]
	s_waitcnt vmcnt(0) lgkmcnt(0)
	v_pk_mul_f32 v[16:17], v[20:21], v[16:17]
	v_pk_mul_f32 v[18:19], v[22:23], v[18:19]
	global_store_dwordx4 v[36:37], v[16:19], off offset:2048
	global_load_dwordx4 v[16:19], v[2:3], off offset:3072
	v_pk_mul_f32 v[20:21], v[28:29], v[38:39] op_sel_hi:[1,0]
	v_pk_mul_f32 v[22:23], v[30:31], v[38:39] op_sel_hi:[1,0]
	s_waitcnt vmcnt(0) lgkmcnt(0)
	v_pk_mul_f32 v[16:17], v[20:21], v[16:17]
	v_pk_mul_f32 v[18:19], v[22:23], v[18:19]
	global_store_dwordx4 v[36:37], v[16:19], off offset:3072
	s_andn2_b64 exec, exec, s[0:1]
	s_cbranch_execnz .LBB0_2405
